# unit-end ALIGN barrier of the leading half-workgroup moved behind its first four epilogue stores (it guards nothing they need), so the leading half packs/stores while the trailing half finishes its la
# speedup vs baseline: 1.0053x; 1.0023x over previous
; #define PG8_STAGE(bufoff, gbase, voff) do { _Pragma("unroll") for (int _i = 0; _i < 2; ++_i) \
;         __builtin_amdgcn_global_load_lds((const unsigned*)((const char*)(gbase) + (voff)[_i]), (LAS unsigned*)(lds + (bufoff) + ldsw + _i * 8192), 16, 0, 0); } while (0)
; #define PG8_LDA(dst, b, h) do { _Pragma("unroll") for (int m = 0; m < 4; ++m) _Pragma("unroll") for (int k = 0; k < 2; ++k) dst[m][k] = *(const LAS bf16x8*)(lds + PG8_SA(b, h) + aoff + m * 2048 + k * 1024); } while (0)
; #define PG8_LDB(dst, b, h) do { _Pragma("unroll") for (int n = 0; n < 2; ++n) _Pragma("unroll") for (int k = 0; k < 2; ++k) dst[n][k] = *(const LAS bf16x8*)(lds + PG8_SB(b, h) + boff + n * 2048 + k * 1024); } while (0)
; #define PG8_MMA(ai, bj, At, Bt) do { __builtin_amdgcn_s_setprio(1); _Pragma("unroll") for (int m = 0; m < 4; ++m) _Pragma("unroll") for (int n = 0; n < 2; ++n) _Pragma("unroll") for (int k = 0; k < 2; ++k) \
;         acc[ai][bj][m][n] = __builtin_amdgcn_mfma_f32_16x16x32_bf16(Bt[n][k], At[m][k], acc[ai][bj][m][n], 0, 0, 0); __builtin_amdgcn_s_setprio(0); } while (0)
; #define PG8_WAIT_V(n) asm volatile("s_waitcnt vmcnt(" #n ")" ::: "memory")
; #define PG8_WAIT_L(n) asm volatile("s_waitcnt lgkmcnt(" #n ")" ::: "memory")
; #define PG8_BAR __builtin_amdgcn_s_barrier()
; #define PG8_SCHED __builtin_amdgcn_sched_barrier(0)
; template <class Epi, class Map>
; __device__ __forceinline__ void gemm_phase(LAS unsigned char* lds, const Gemm g, const Sched<Map>& S, const Epi& E) {
;     ...
;         const bool has_next = S.next(ui + 1, nxt);
;         const char* nA = has_next ? (const char*)g.A + nxt.aoff : cA; const char* nB = has_next ? (const char*)g.Bt + nxt.boff : cB;
; #pragma unroll 1
;         for (int t = 0; t < nt; t += 2) {
;             const bool last = (t == nt - 2);
;             const char* a1 = cA + (size_t)(t + 1) * kstep;
;             const char* a2 = last ? nA : cA + (size_t)(t + 2) * kstep; const char* b2 = last ? nB : cB + (size_t)(t + 2) * kstep;
;             const char* a3 = a2 + kstep; const char* b3 = b2 + kstep;
;             PG8_LDB(B0, 0, 0); PG8_LDB(B1, 0, 1); PG8_SCHED; PG8_LDA(At, 0, 0); PG8_STAGE(PG8_SA(1, 1), a1 + hstepA, voffA);
;             PG8_WAIT_V(8); PG8_WAIT_L(0); PG8_BAR; PG8_MMA(0, 0, At, B0); PG8_MMA(0, 1, At, B1); PG8_BAR; PG8_SCHED;
.LBB0_222:
	s_add_u32 s34, s16, s54
	s_addc_u32 s35, s17, 0
	s_and_b64 s[36:37], s[40:41], exec
	s_cselect_b32 s56, s35, s43
	s_cselect_b32 s57, s34, s42
	s_add_u32 s36, s3, s53
	s_addc_u32 s37, s4, 0
	s_and_b64 s[48:49], s[40:41], exec
	s_cselect_b32 s58, s37, s47
	s_cselect_b32 s59, s36, s46
	s_add_u32 s48, s42, 0x80
	s_addc_u32 s49, s43, 0
	s_add_u32 s65, s46, 0x100
	v_mov_b32_e32 v0, 0
	v_lshl_add_u64 v[128:129], s[48:49], 0, v[158:159]
	v_lshl_add_u64 v[130:131], s[48:49], 0, v[160:161]
	s_addc_u32 s66, s47, 0
	s_mov_b32 s67, -2
	s_mov_b64 s[46:47], 0
	v_mov_b32_e32 v1, v0
	v_mov_b32_e32 v2, v0
	v_mov_b32_e32 v3, v0
	v_mov_b32_e32 v4, v0
	v_mov_b32_e32 v5, v0
	v_mov_b32_e32 v6, v0
	v_mov_b32_e32 v7, v0
	s_waitcnt vmcnt(0)
	v_mov_b32_e32 v16, v0
	v_mov_b32_e32 v17, v0
	v_mov_b32_e32 v18, v0
	v_mov_b32_e32 v19, v0
	v_mov_b32_e32 v20, v0
	v_mov_b32_e32 v21, v0
	v_mov_b32_e32 v22, v0
	v_mov_b32_e32 v23, v0
	v_mov_b32_e32 v32, v0
	v_mov_b32_e32 v33, v0
	v_mov_b32_e32 v34, v0
	v_mov_b32_e32 v35, v0
	v_mov_b32_e32 v36, v0
	v_mov_b32_e32 v37, v0
	v_mov_b32_e32 v38, v0
	v_mov_b32_e32 v39, v0
	v_mov_b32_e32 v48, v0
	v_mov_b32_e32 v49, v0
	v_mov_b32_e32 v50, v0
	v_mov_b32_e32 v51, v0
	v_mov_b32_e32 v52, v0
	v_mov_b32_e32 v53, v0
	v_mov_b32_e32 v54, v0
	v_mov_b32_e32 v55, v0
	v_mov_b32_e32 v8, v0
	v_mov_b32_e32 v9, v0
	v_mov_b32_e32 v10, v0
	v_mov_b32_e32 v11, v0
	v_mov_b32_e32 v12, v0
	v_mov_b32_e32 v13, v0
	v_mov_b32_e32 v14, v0
	v_mov_b32_e32 v15, v0
	v_mov_b32_e32 v24, v0
	v_mov_b32_e32 v25, v0
	v_mov_b32_e32 v26, v0
	v_mov_b32_e32 v27, v0
	v_mov_b32_e32 v28, v0
	v_mov_b32_e32 v29, v0
	v_mov_b32_e32 v30, v0
	v_mov_b32_e32 v31, v0
	v_mov_b32_e32 v40, v0
	v_mov_b32_e32 v41, v0
	v_mov_b32_e32 v42, v0
	v_mov_b32_e32 v43, v0
	v_mov_b32_e32 v44, v0
	v_mov_b32_e32 v45, v0
	v_mov_b32_e32 v46, v0
	v_mov_b32_e32 v47, v0
	v_mov_b32_e32 v56, v0
	v_mov_b32_e32 v57, v0
	v_mov_b32_e32 v58, v0
	v_mov_b32_e32 v59, v0
	v_mov_b32_e32 v60, v0
	v_mov_b32_e32 v61, v0
	v_mov_b32_e32 v62, v0
	v_mov_b32_e32 v63, v0
	v_mov_b32_e32 v64, v0
	v_mov_b32_e32 v65, v0
	v_mov_b32_e32 v66, v0
	v_mov_b32_e32 v67, v0
	v_mov_b32_e32 v68, v0
	v_mov_b32_e32 v69, v0
	v_mov_b32_e32 v70, v0
	v_mov_b32_e32 v71, v0
	v_mov_b32_e32 v80, v0
	v_mov_b32_e32 v81, v0
	v_mov_b32_e32 v82, v0
	v_mov_b32_e32 v83, v0
	v_mov_b32_e32 v84, v0
	v_mov_b32_e32 v85, v0
	v_mov_b32_e32 v86, v0
	v_mov_b32_e32 v87, v0
	v_mov_b32_e32 v96, v0
	v_mov_b32_e32 v97, v0
	v_mov_b32_e32 v98, v0
	v_mov_b32_e32 v99, v0
	v_mov_b32_e32 v100, v0
	v_mov_b32_e32 v101, v0
	v_mov_b32_e32 v102, v0
	v_mov_b32_e32 v103, v0
	v_mov_b32_e32 v112, v0
	v_mov_b32_e32 v113, v0
	v_mov_b32_e32 v114, v0
	v_mov_b32_e32 v115, v0
	v_mov_b32_e32 v116, v0
	v_mov_b32_e32 v117, v0
	v_mov_b32_e32 v118, v0
	v_mov_b32_e32 v119, v0
	v_mov_b32_e32 v72, v0
	v_mov_b32_e32 v73, v0
	v_mov_b32_e32 v74, v0
	v_mov_b32_e32 v75, v0
	v_mov_b32_e32 v76, v0
	v_mov_b32_e32 v77, v0
	v_mov_b32_e32 v78, v0
	v_mov_b32_e32 v79, v0
	v_mov_b32_e32 v88, v0
	v_mov_b32_e32 v89, v0
	v_mov_b32_e32 v90, v0
	v_mov_b32_e32 v91, v0
	v_mov_b32_e32 v92, v0
	v_mov_b32_e32 v93, v0
	v_mov_b32_e32 v94, v0
	v_mov_b32_e32 v95, v0
	v_mov_b32_e32 v104, v0
	v_mov_b32_e32 v105, v0
	v_mov_b32_e32 v106, v0
	v_mov_b32_e32 v107, v0
	v_mov_b32_e32 v108, v0
	v_mov_b32_e32 v109, v0
	v_mov_b32_e32 v110, v0
	v_mov_b32_e32 v111, v0
	v_mov_b32_e32 v120, v0
	v_mov_b32_e32 v121, v0
	v_mov_b32_e32 v122, v0
	v_mov_b32_e32 v123, v0
	v_mov_b32_e32 v124, v0
	v_mov_b32_e32 v125, v0
	v_mov_b32_e32 v126, v0
	v_mov_b32_e32 v127, v0
.LBB0_223:
	s_add_u32 s48, s42, s46
	s_addc_u32 s49, s43, s47
	s_add_u32 s48, s48, 0x100
	s_addc_u32 s49, s49, 0
	s_add_u32 s62, s65, s46
	s_addc_u32 s63, s66, s47
	s_add_i32 s68, 0, 0x10000
	s_cmpk_eq_i32 s46, 0xf00
	s_cselect_b32 s51, s56, s49
	s_cselect_b32 s50, s57, s48
	v_add_u32_e32 v136, s68, v170
	s_cselect_b32 s49, s58, s63
	s_cselect_b32 s48, s59, s62
	s_add_i32 s62, 0, 0x14000
	ds_read_b128 v[132:135], v136
	ds_read_b128 v[162:165], v136 offset:1024
	ds_read_b128 v[172:175], v136 offset:2048
	ds_read_b128 v[176:179], v136 offset:3072
	v_add_u32_e32 v136, s62, v170
	ds_read_b128 v[192:195], v136
	ds_read_b128 v[196:199], v136 offset:1024
	ds_read_b128 v[200:203], v136 offset:2048
	ds_read_b128 v[204:207], v136 offset:3072
	v_lshl_add_u64 v[136:137], v[130:131], 0, s[46:47]
	s_add_i32 m0, s6, 0xc000
	ds_read_b128 v[208:211], v171
	ds_read_b128 v[212:215], v171 offset:1024
	ds_read_b128 v[216:219], v171 offset:2048
	ds_read_b128 v[220:223], v171 offset:3072
	ds_read_b128 v[224:227], v171 offset:4096
	ds_read_b128 v[228:231], v171 offset:5120
	ds_read_b128 v[232:235], v171 offset:6144
	ds_read_b128 v[236:239], v171 offset:7168
	global_load_lds_dwordx4 v[136:137], off
	v_lshl_add_u64 v[136:137], v[128:129], 0, s[46:47]
	s_add_i32 m0, s6, 0xe000
	s_nop 0
	global_load_lds_dwordx4 v[136:137], off
	s_waitcnt vmcnt(8)
	s_waitcnt lgkmcnt(0)
	s_barrier
; #define PG8_STAGE(bufoff, gbase, voff) do { _Pragma("unroll") for (int _i = 0; _i < 2; ++_i) \
;         __builtin_amdgcn_global_load_lds((const unsigned*)((const char*)(gbase) + (voff)[_i]), (LAS unsigned*)(lds + (bufoff) + ldsw + _i * 8192), 16, 0, 0); } while (0)
; #define PG8_LDA(dst, b, h) do { _Pragma("unroll") for (int m = 0; m < 4; ++m) _Pragma("unroll") for (int k = 0; k < 2; ++k) dst[m][k] = *(const LAS bf16x8*)(lds + PG8_SA(b, h) + aoff + m * 2048 + k * 1024); } while (0)
; #define PG8_LDB(dst, b, h) do { _Pragma("unroll") for (int n = 0; n < 2; ++n) _Pragma("unroll") for (int k = 0; k < 2; ++k) dst[n][k] = *(const LAS bf16x8*)(lds + PG8_SB(b, h) + boff + n * 2048 + k * 1024); } while (0)
; #define PG8_MMA(ai, bj, At, Bt) do { __builtin_amdgcn_s_setprio(1); _Pragma("unroll") for (int m = 0; m < 4; ++m) _Pragma("unroll") for (int n = 0; n < 2; ++n) _Pragma("unroll") for (int k = 0; k < 2; ++k) \
;         acc[ai][bj][m][n] = __builtin_amdgcn_mfma_f32_16x16x32_bf16(Bt[n][k], At[m][k], acc[ai][bj][m][n], 0, 0, 0); __builtin_amdgcn_s_setprio(0); } while (0)
; #define PG8_WAIT_V(n) asm volatile("s_waitcnt vmcnt(" #n ")" ::: "memory")
; #define PG8_WAIT_L(n) asm volatile("s_waitcnt lgkmcnt(" #n ")" ::: "memory")
; #define PG8_BAR __builtin_amdgcn_s_barrier()
; #define PG8_SCHED __builtin_amdgcn_sched_barrier(0)
; template <class Epi, class Map>
; __device__ __forceinline__ void gemm_phase(LAS unsigned char* lds, const Gemm g, const Sched<Map>& S, const Epi& E) {
;     ...
;             PG8_WAIT_V(8); PG8_WAIT_L(0); PG8_BAR; PG8_MMA(0, 0, At, B0); PG8_MMA(0, 1, At, B1); PG8_BAR; PG8_SCHED;
;             PG8_LDA(At, 0, 1); PG8_STAGE(PG8_SB(0, 0), b2, voffB); PG8_STAGE(PG8_SB(0, 1), b2 + hstepB, voffB); PG8_STAGE(PG8_SA(0, 0), a2, voffA);
;             PG8_WAIT_V(8); PG8_WAIT_L(0); PG8_BAR; PG8_MMA(1, 0, At, B0); PG8_MMA(1, 1, At, B1); PG8_BAR; PG8_SCHED;
;             PG8_LDB(B0, 1, 0); PG8_LDB(B1, 1, 1); PG8_SCHED; PG8_LDA(At, 1, 0); PG8_STAGE(PG8_SA(0, 1), a2 + hstepA, voffA);
;             PG8_WAIT_V(8); PG8_WAIT_L(0); PG8_BAR; PG8_MMA(0, 0, At, B0); PG8_MMA(0, 1, At, B1); PG8_BAR; PG8_SCHED;
	s_waitcnt lgkmcnt(0)
	v_mfma_f32_16x16x32_bf16 v[124:127], v[132:135], v[208:211], v[124:127]
	v_mfma_f32_16x16x32_bf16 v[120:123], v[172:175], v[208:211], v[120:123]
	v_mfma_f32_16x16x32_bf16 v[108:111], v[132:135], v[216:219], v[108:111]
	v_mfma_f32_16x16x32_bf16 v[104:107], v[172:175], v[216:219], v[104:107]
	v_mfma_f32_16x16x32_bf16 v[92:95], v[132:135], v[224:227], v[92:95]
	v_mfma_f32_16x16x32_bf16 v[88:91], v[172:175], v[224:227], v[88:91]
	v_mfma_f32_16x16x32_bf16 v[76:79], v[132:135], v[232:235], v[76:79]
	v_mfma_f32_16x16x32_bf16 v[72:75], v[172:175], v[232:235], v[72:75]
	v_mfma_f32_16x16x32_bf16 v[124:127], v[162:165], v[212:215], v[124:127]
	v_mfma_f32_16x16x32_bf16 v[120:123], v[176:179], v[212:215], v[120:123]
	v_mfma_f32_16x16x32_bf16 v[108:111], v[162:165], v[220:223], v[108:111]
	v_mfma_f32_16x16x32_bf16 v[104:107], v[176:179], v[220:223], v[104:107]
	v_mfma_f32_16x16x32_bf16 v[92:95], v[162:165], v[228:231], v[92:95]
	v_mfma_f32_16x16x32_bf16 v[88:91], v[176:179], v[228:231], v[88:91]
	v_mfma_f32_16x16x32_bf16 v[76:79], v[162:165], v[236:239], v[76:79]
	v_mfma_f32_16x16x32_bf16 v[72:75], v[176:179], v[236:239], v[72:75]
	v_mfma_f32_16x16x32_bf16 v[116:119], v[192:195], v[208:211], v[116:119]
	v_mfma_f32_16x16x32_bf16 v[112:115], v[200:203], v[208:211], v[112:115]
	v_mfma_f32_16x16x32_bf16 v[100:103], v[192:195], v[216:219], v[100:103]
	v_mfma_f32_16x16x32_bf16 v[96:99], v[200:203], v[216:219], v[96:99]
	v_mfma_f32_16x16x32_bf16 v[84:87], v[192:195], v[224:227], v[84:87]
	v_mfma_f32_16x16x32_bf16 v[80:83], v[200:203], v[224:227], v[80:83]
	v_mfma_f32_16x16x32_bf16 v[68:71], v[192:195], v[232:235], v[68:71]
	v_mfma_f32_16x16x32_bf16 v[64:67], v[200:203], v[232:235], v[64:67]
	v_mfma_f32_16x16x32_bf16 v[116:119], v[196:199], v[212:215], v[116:119]
	v_mfma_f32_16x16x32_bf16 v[112:115], v[204:207], v[212:215], v[112:115]
	v_mfma_f32_16x16x32_bf16 v[100:103], v[196:199], v[220:223], v[100:103]
	v_mfma_f32_16x16x32_bf16 v[96:99], v[204:207], v[220:223], v[96:99]
	v_mfma_f32_16x16x32_bf16 v[84:87], v[196:199], v[228:231], v[84:87]
	v_mfma_f32_16x16x32_bf16 v[80:83], v[204:207], v[228:231], v[80:83]
	v_mfma_f32_16x16x32_bf16 v[68:71], v[196:199], v[236:239], v[68:71]
	v_mfma_f32_16x16x32_bf16 v[64:67], v[204:207], v[236:239], v[64:67]
	s_barrier
	s_add_i32 s63, s68, s5
	v_lshl_add_u64 v[136:137], s[48:49], 0, v[144:145]
	s_mov_b32 m0, s63
	ds_read_b128 v[208:211], v171 offset:16384
	ds_read_b128 v[212:215], v171 offset:17408
	ds_read_b128 v[216:219], v171 offset:18432
	ds_read_b128 v[220:223], v171 offset:19456
	ds_read_b128 v[224:227], v171 offset:20480
	ds_read_b128 v[228:231], v171 offset:21504
	ds_read_b128 v[232:235], v171 offset:22528
	ds_read_b128 v[236:239], v171 offset:23552
	global_load_lds_dwordx4 v[136:137], off
	s_add_i32 m0, s63, 0x2000
	s_add_u32 s68, s48, 0x80000
	v_lshl_add_u64 v[166:167], s[48:49], 0, v[142:143]
	s_addc_u32 s69, s49, 0
	s_add_i32 s62, s62, s5
	global_load_lds_dwordx4 v[166:167], off
	v_lshl_add_u64 v[180:181], s[68:69], 0, v[144:145]
	s_mov_b32 m0, s62
	v_lshl_add_u64 v[240:241], s[50:51], 0, v[140:141]
	global_load_lds_dwordx4 v[180:181], off
	v_lshl_add_u64 v[180:181], s[68:69], 0, v[142:143]
	s_add_i32 m0, s62, 0x2000
	s_nop 0
	global_load_lds_dwordx4 v[180:181], off
	v_lshl_add_u64 v[180:181], s[50:51], 0, v[138:139]
	s_mov_b32 m0, s6
	s_nop 0
	global_load_lds_dwordx4 v[180:181], off
	s_mov_b32 m0, s7
	s_nop 0
	global_load_lds_dwordx4 v[240:241], off
	s_waitcnt vmcnt(8)
	s_waitcnt lgkmcnt(0)
	s_barrier
	s_waitcnt lgkmcnt(0)
	v_mfma_f32_16x16x32_bf16 v[60:63], v[132:135], v[208:211], v[60:63]
	v_mfma_f32_16x16x32_bf16 v[56:59], v[172:175], v[208:211], v[56:59]
	v_mfma_f32_16x16x32_bf16 v[44:47], v[132:135], v[216:219], v[44:47]
	v_mfma_f32_16x16x32_bf16 v[40:43], v[172:175], v[216:219], v[40:43]
	v_mfma_f32_16x16x32_bf16 v[28:31], v[132:135], v[224:227], v[28:31]
	v_mfma_f32_16x16x32_bf16 v[24:27], v[172:175], v[224:227], v[24:27]
	v_mfma_f32_16x16x32_bf16 v[12:15], v[132:135], v[232:235], v[12:15]
	v_mfma_f32_16x16x32_bf16 v[8:11], v[172:175], v[232:235], v[8:11]
	v_mfma_f32_16x16x32_bf16 v[60:63], v[162:165], v[212:215], v[60:63]
	v_mfma_f32_16x16x32_bf16 v[56:59], v[176:179], v[212:215], v[56:59]
	v_mfma_f32_16x16x32_bf16 v[44:47], v[162:165], v[220:223], v[44:47]
	v_mfma_f32_16x16x32_bf16 v[40:43], v[176:179], v[220:223], v[40:43]
	v_mfma_f32_16x16x32_bf16 v[28:31], v[162:165], v[228:231], v[28:31]
	v_mfma_f32_16x16x32_bf16 v[24:27], v[176:179], v[228:231], v[24:27]
	v_mfma_f32_16x16x32_bf16 v[12:15], v[162:165], v[236:239], v[12:15]
	v_mfma_f32_16x16x32_bf16 v[8:11], v[176:179], v[236:239], v[8:11]
	v_mfma_f32_16x16x32_bf16 v[52:55], v[192:195], v[208:211], v[52:55]
	v_mfma_f32_16x16x32_bf16 v[48:51], v[200:203], v[208:211], v[48:51]
	v_mfma_f32_16x16x32_bf16 v[36:39], v[192:195], v[216:219], v[36:39]
	v_mfma_f32_16x16x32_bf16 v[32:35], v[200:203], v[216:219], v[32:35]
	v_mfma_f32_16x16x32_bf16 v[20:23], v[192:195], v[224:227], v[20:23]
	v_mfma_f32_16x16x32_bf16 v[16:19], v[200:203], v[224:227], v[16:19]
	v_mfma_f32_16x16x32_bf16 v[4:7], v[192:195], v[232:235], v[4:7]
	v_mfma_f32_16x16x32_bf16 v[0:3], v[200:203], v[232:235], v[0:3]
	v_mfma_f32_16x16x32_bf16 v[52:55], v[196:199], v[212:215], v[52:55]
	v_mfma_f32_16x16x32_bf16 v[48:51], v[204:207], v[212:215], v[48:51]
	v_mfma_f32_16x16x32_bf16 v[36:39], v[196:199], v[220:223], v[36:39]
	v_mfma_f32_16x16x32_bf16 v[32:35], v[204:207], v[220:223], v[32:35]
	v_mfma_f32_16x16x32_bf16 v[20:23], v[196:199], v[228:231], v[20:23]
	v_mfma_f32_16x16x32_bf16 v[16:19], v[204:207], v[228:231], v[16:19]
	v_mfma_f32_16x16x32_bf16 v[4:7], v[196:199], v[236:239], v[4:7]
	v_mfma_f32_16x16x32_bf16 v[0:3], v[204:207], v[236:239], v[0:3]
	s_barrier
; #define PG8_STAGE(bufoff, gbase, voff) do { _Pragma("unroll") for (int _i = 0; _i < 2; ++_i) \
;         __builtin_amdgcn_global_load_lds((const unsigned*)((const char*)(gbase) + (voff)[_i]), (LAS unsigned*)(lds + (bufoff) + ldsw + _i * 8192), 16, 0, 0); } while (0)
; #define PG8_LDA(dst, b, h) do { _Pragma("unroll") for (int m = 0; m < 4; ++m) _Pragma("unroll") for (int k = 0; k < 2; ++k) dst[m][k] = *(const LAS bf16x8*)(lds + PG8_SA(b, h) + aoff + m * 2048 + k * 1024); } while (0)
; #define PG8_LDB(dst, b, h) do { _Pragma("unroll") for (int n = 0; n < 2; ++n) _Pragma("unroll") for (int k = 0; k < 2; ++k) dst[n][k] = *(const LAS bf16x8*)(lds + PG8_SB(b, h) + boff + n * 2048 + k * 1024); } while (0)
; #define PG8_MMA(ai, bj, At, Bt) do { __builtin_amdgcn_s_setprio(1); _Pragma("unroll") for (int m = 0; m < 4; ++m) _Pragma("unroll") for (int n = 0; n < 2; ++n) _Pragma("unroll") for (int k = 0; k < 2; ++k) \
;         acc[ai][bj][m][n] = __builtin_amdgcn_mfma_f32_16x16x32_bf16(Bt[n][k], At[m][k], acc[ai][bj][m][n], 0, 0, 0); __builtin_amdgcn_s_setprio(0); } while (0)
; #define PG8_WAIT_V(n) asm volatile("s_waitcnt vmcnt(" #n ")" ::: "memory")
; #define PG8_WAIT_L(n) asm volatile("s_waitcnt lgkmcnt(" #n ")" ::: "memory")
; #define PG8_BAR __builtin_amdgcn_s_barrier()
; #define PG8_SCHED __builtin_amdgcn_sched_barrier(0)
; template <class Epi, class Map>
; __device__ __forceinline__ void gemm_phase(LAS unsigned char* lds, const Gemm g, const Sched<Map>& S, const Epi& E) {
;     ...
;             PG8_LDB(B0, 1, 0); PG8_LDB(B1, 1, 1); PG8_SCHED; PG8_LDA(At, 1, 0); PG8_STAGE(PG8_SA(0, 1), a2 + hstepA, voffA);
;             PG8_WAIT_V(8); PG8_WAIT_L(0); PG8_BAR; PG8_MMA(0, 0, At, B0); PG8_MMA(0, 1, At, B1); PG8_BAR; PG8_SCHED;
;             PG8_LDA(At, 1, 1); PG8_STAGE(PG8_SB(1, 0), b3, voffB); PG8_STAGE(PG8_SB(1, 1), b3 + hstepB, voffB); PG8_STAGE(PG8_SA(1, 0), a3, voffA);
;             PG8_WAIT_V(8); PG8_WAIT_L(0); PG8_BAR; PG8_MMA(1, 0, At, B0); PG8_MMA(1, 1, At, B1); PG8_BAR; PG8_SCHED;
;         }
	s_add_i32 s62, 0, 0x18000
	s_add_i32 s63, 0, 0x1c000
	v_add_u32_e32 v176, s62, v170
	v_add_u32_e32 v204, s63, v170
	ds_read_b128 v[132:135], v176
	ds_read_b128 v[162:165], v176 offset:1024
	ds_read_b128 v[172:175], v176 offset:2048
	ds_read_b128 v[176:179], v176 offset:3072
	ds_read_b128 v[192:195], v204
	ds_read_b128 v[196:199], v204 offset:1024
	ds_read_b128 v[200:203], v204 offset:2048
	ds_read_b128 v[204:207], v204 offset:3072
	s_add_u32 s50, s50, s20
	s_addc_u32 s51, s51, 0
	s_mov_b32 m0, s8
	v_lshl_add_u64 v[242:243], s[50:51], 0, v[138:139]
	ds_read_b128 v[208:211], v171 offset:32768
	ds_read_b128 v[212:215], v171 offset:33792
	ds_read_b128 v[216:219], v171 offset:34816
	ds_read_b128 v[220:223], v171 offset:35840
	ds_read_b128 v[224:227], v171 offset:36864
	ds_read_b128 v[228:231], v171 offset:37888
	ds_read_b128 v[232:235], v171 offset:38912
	ds_read_b128 v[236:239], v171 offset:39936
	global_load_lds_dwordx4 v[242:243], off
	v_lshl_add_u64 v[242:243], s[50:51], 0, v[140:141]
	s_mov_b32 m0, s9
	s_nop 0
	global_load_lds_dwordx4 v[242:243], off
	s_waitcnt vmcnt(8)
	s_waitcnt lgkmcnt(0)
	s_barrier
	s_waitcnt lgkmcnt(0)
	v_mfma_f32_16x16x32_bf16 v[124:127], v[132:135], v[208:211], v[124:127]
	v_mfma_f32_16x16x32_bf16 v[120:123], v[172:175], v[208:211], v[120:123]
	v_mfma_f32_16x16x32_bf16 v[108:111], v[132:135], v[216:219], v[108:111]
	v_mfma_f32_16x16x32_bf16 v[104:107], v[172:175], v[216:219], v[104:107]
	v_mfma_f32_16x16x32_bf16 v[92:95], v[132:135], v[224:227], v[92:95]
	v_mfma_f32_16x16x32_bf16 v[88:91], v[172:175], v[224:227], v[88:91]
	v_mfma_f32_16x16x32_bf16 v[76:79], v[132:135], v[232:235], v[76:79]
	v_mfma_f32_16x16x32_bf16 v[72:75], v[172:175], v[232:235], v[72:75]
	v_mfma_f32_16x16x32_bf16 v[124:127], v[162:165], v[212:215], v[124:127]
	v_mfma_f32_16x16x32_bf16 v[120:123], v[176:179], v[212:215], v[120:123]
	v_mfma_f32_16x16x32_bf16 v[108:111], v[162:165], v[220:223], v[108:111]
	v_mfma_f32_16x16x32_bf16 v[104:107], v[176:179], v[220:223], v[104:107]
	v_mfma_f32_16x16x32_bf16 v[92:95], v[162:165], v[228:231], v[92:95]
	v_mfma_f32_16x16x32_bf16 v[88:91], v[176:179], v[228:231], v[88:91]
	v_mfma_f32_16x16x32_bf16 v[76:79], v[162:165], v[236:239], v[76:79]
	v_mfma_f32_16x16x32_bf16 v[72:75], v[176:179], v[236:239], v[72:75]
	v_mfma_f32_16x16x32_bf16 v[116:119], v[192:195], v[208:211], v[116:119]
	v_mfma_f32_16x16x32_bf16 v[112:115], v[200:203], v[208:211], v[112:115]
	v_mfma_f32_16x16x32_bf16 v[100:103], v[192:195], v[216:219], v[100:103]
	v_mfma_f32_16x16x32_bf16 v[96:99], v[200:203], v[216:219], v[96:99]
	v_mfma_f32_16x16x32_bf16 v[84:87], v[192:195], v[224:227], v[84:87]
	v_mfma_f32_16x16x32_bf16 v[80:83], v[200:203], v[224:227], v[80:83]
	v_mfma_f32_16x16x32_bf16 v[68:71], v[192:195], v[232:235], v[68:71]
	v_mfma_f32_16x16x32_bf16 v[64:67], v[200:203], v[232:235], v[64:67]
	v_mfma_f32_16x16x32_bf16 v[116:119], v[196:199], v[212:215], v[116:119]
	v_mfma_f32_16x16x32_bf16 v[112:115], v[204:207], v[212:215], v[112:115]
	v_mfma_f32_16x16x32_bf16 v[100:103], v[196:199], v[220:223], v[100:103]
	v_mfma_f32_16x16x32_bf16 v[96:99], v[204:207], v[220:223], v[96:99]
	v_mfma_f32_16x16x32_bf16 v[84:87], v[196:199], v[228:231], v[84:87]
	v_mfma_f32_16x16x32_bf16 v[80:83], v[204:207], v[228:231], v[80:83]
	v_mfma_f32_16x16x32_bf16 v[68:71], v[196:199], v[236:239], v[68:71]
	v_mfma_f32_16x16x32_bf16 v[64:67], v[204:207], v[236:239], v[64:67]
	s_barrier
	s_add_i32 s50, s62, s5
	v_lshl_add_u64 v[136:137], v[136:137], 0, s[82:83]
	s_mov_b32 m0, s50
	ds_read_b128 v[208:211], v171 offset:49152
	ds_read_b128 v[212:215], v171 offset:50176
	ds_read_b128 v[216:219], v171 offset:51200
	ds_read_b128 v[220:223], v171 offset:52224
	ds_read_b128 v[224:227], v171 offset:53248
	ds_read_b128 v[228:231], v171 offset:54272
	ds_read_b128 v[232:235], v171 offset:55296
	ds_read_b128 v[236:239], v171 offset:56320
	global_load_lds_dwordx4 v[136:137], off
	s_add_i32 m0, s50, 0x2000
	s_add_u32 s48, s48, 0x80080
	v_lshl_add_u64 v[136:137], v[166:167], 0, s[82:83]
	s_addc_u32 s49, s49, 0
	s_add_i32 s50, s63, s5
	global_load_lds_dwordx4 v[136:137], off
	v_lshl_add_u64 v[136:137], s[48:49], 0, v[144:145]
	s_mov_b32 m0, s50
	s_nop 0
	global_load_lds_dwordx4 v[136:137], off
	v_lshl_add_u64 v[136:137], s[48:49], 0, v[142:143]
	s_add_i32 m0, s50, 0x2000
	s_nop 0
	global_load_lds_dwordx4 v[136:137], off
	v_lshl_add_u64 v[136:137], v[180:181], 0, s[82:83]
	s_mov_b32 m0, s14
	s_nop 0
	global_load_lds_dwordx4 v[136:137], off
	v_lshl_add_u64 v[136:137], v[240:241], 0, s[82:83]
	s_mov_b32 m0, s15
	s_nop 0
	global_load_lds_dwordx4 v[136:137], off
	s_waitcnt vmcnt(8)
	s_waitcnt lgkmcnt(0)
	s_barrier
	s_waitcnt lgkmcnt(0)
	v_mfma_f32_16x16x32_bf16 v[60:63], v[132:135], v[208:211], v[60:63]
	v_mfma_f32_16x16x32_bf16 v[56:59], v[172:175], v[208:211], v[56:59]
	v_mfma_f32_16x16x32_bf16 v[44:47], v[132:135], v[216:219], v[44:47]
	v_mfma_f32_16x16x32_bf16 v[40:43], v[172:175], v[216:219], v[40:43]
	v_mfma_f32_16x16x32_bf16 v[28:31], v[132:135], v[224:227], v[28:31]
	v_mfma_f32_16x16x32_bf16 v[24:27], v[172:175], v[224:227], v[24:27]
	v_mfma_f32_16x16x32_bf16 v[12:15], v[132:135], v[232:235], v[12:15]
	v_mfma_f32_16x16x32_bf16 v[8:11], v[172:175], v[232:235], v[8:11]
	v_mfma_f32_16x16x32_bf16 v[60:63], v[162:165], v[212:215], v[60:63]
	v_mfma_f32_16x16x32_bf16 v[56:59], v[176:179], v[212:215], v[56:59]
	v_mfma_f32_16x16x32_bf16 v[44:47], v[162:165], v[220:223], v[44:47]
	v_mfma_f32_16x16x32_bf16 v[40:43], v[176:179], v[220:223], v[40:43]
	v_mfma_f32_16x16x32_bf16 v[28:31], v[162:165], v[228:231], v[28:31]
	v_mfma_f32_16x16x32_bf16 v[24:27], v[176:179], v[228:231], v[24:27]
	v_mfma_f32_16x16x32_bf16 v[12:15], v[162:165], v[236:239], v[12:15]
	v_mfma_f32_16x16x32_bf16 v[8:11], v[176:179], v[236:239], v[8:11]
	v_mfma_f32_16x16x32_bf16 v[52:55], v[192:195], v[208:211], v[52:55]
	v_mfma_f32_16x16x32_bf16 v[48:51], v[200:203], v[208:211], v[48:51]
	v_mfma_f32_16x16x32_bf16 v[36:39], v[192:195], v[216:219], v[36:39]
	v_mfma_f32_16x16x32_bf16 v[32:35], v[200:203], v[216:219], v[32:35]
	v_mfma_f32_16x16x32_bf16 v[20:23], v[192:195], v[224:227], v[20:23]
	v_mfma_f32_16x16x32_bf16 v[16:19], v[200:203], v[224:227], v[16:19]
	v_mfma_f32_16x16x32_bf16 v[4:7], v[192:195], v[232:235], v[4:7]
	v_mfma_f32_16x16x32_bf16 v[0:3], v[200:203], v[232:235], v[0:3]
	v_mfma_f32_16x16x32_bf16 v[52:55], v[196:199], v[212:215], v[52:55]
	v_mfma_f32_16x16x32_bf16 v[48:51], v[204:207], v[212:215], v[48:51]
	v_mfma_f32_16x16x32_bf16 v[36:39], v[196:199], v[220:223], v[36:39]
	v_mfma_f32_16x16x32_bf16 v[32:35], v[204:207], v[220:223], v[32:35]
	v_mfma_f32_16x16x32_bf16 v[20:23], v[196:199], v[228:231], v[20:23]
	v_mfma_f32_16x16x32_bf16 v[16:19], v[204:207], v[228:231], v[16:19]
	v_mfma_f32_16x16x32_bf16 v[4:7], v[196:199], v[236:239], v[4:7]
	v_mfma_f32_16x16x32_bf16 v[0:3], v[204:207], v[236:239], v[0:3]
	s_barrier
	s_add_i32 s67, s67, 2
	s_add_u32 s46, s46, 0x100
	s_addc_u32 s47, s47, 0
	s_cmp_gt_u32 s67, 29
	s_cbranch_scc0 .LBB0_223
	s_and_b64 vcc, exec, s[28:29]
	s_cbranch_vccz .LBB0_226
; #define PG8_BAR __builtin_amdgcn_s_barrier()
; template <class Epi, class Map>
; __device__ __forceinline__ void gemm_phase(LAS unsigned char* lds, const Gemm g, const Sched<Map>& S, const Epi& E) {
;     ...
;         if (wr == 0) PG8_BAR;
;     __device__ __forceinline__ void operator()(const Acc& acc, const Unit& u, int wr, int wc, int fr, int fq) const {
;     ...
; #pragma unroll
;         for (int ai = 0; ai < 2; ++ai)
; #pragma unroll
;             for (int m = 0; m < 4; ++m) {
;                 const int row_in = ai * HALF + wr * 64 + m * 16 + fr, c = u.pm * BM + row_in;
;                 const int tok = ((c & ((1 << lL) - 1)) << ld) + (c >> lL);
;                 f32x4 t0 = (f32x4){1.f, 0.f, 1.f, 0.f}, t1 = t0;
;                 if (wc == 0) { const f32x4* cp = csa + ((size_t)tok * 16 + 4 * fq) / 2; t0 = cp[0]; t1 = cp[1]; }
;                 bf16_t* rowp = O + u.coff + (size_t)row_in * D + wc * 32 + ((fq & 1) ? 16 + 4 * (fq - 1) : 4 * fq);
.LBB0_226:
	v_mov_b32_e32 v165, v169
	v_mov_b32_e32 v128, v168
	v_cndmask_b32_e64 v130, 0, 1, s[30:31]
	v_lshlrev_b32_e32 v162, 2, v165
	v_add_u32_e32 v164, s13, v128
	s_lshl_b32 s46, s45, 8
	v_ashrrev_i32_e32 v163, 31, v162
	v_mov_b32_e32 v129, 0
	v_mov_b32_e32 v128, 1.0
	v_cmp_ne_u32_e64 s[42:43], 1, v130
	s_andn2_b64 vcc, exec, s[30:31]
	v_mov_b32_e32 v130, 1.0
	v_mov_b32_e32 v131, 0
	v_mov_b32_e32 v132, 1.0
	v_mov_b32_e32 v133, 0
	v_mov_b32_e32 v134, 1.0
	v_mov_b32_e32 v135, 0
	v_mov_b32_e32 v136, 1.0
	v_mov_b32_e32 v137, 0
	s_cbranch_vccnz .LBB0_228
	v_add_u32_e32 v196, s46, v164
	v_lshlrev_b32_e32 v197, s1, v196
	v_and_b32_e32 v197, 0x3fff, v197
	v_ashrrev_i32_e32 v196, s10, v196
	v_add_u32_e32 v196, v197, v196
	v_ashrrev_i32_e32 v197, 31, v196
	v_lshl_add_u64 v[196:197], v[196:197], 4, v[162:163]
	v_lshl_add_u64 v[196:197], v[196:197], 3, s[18:19]
	global_load_dwordx4 v[192:195], v[196:197], off offset:16
	s_nop 0
	global_load_dwordx4 v[196:199], v[196:197], off
	v_add_u32_e32 v204, 16, v164
	v_add_u32_e32 v204, s46, v204
	v_lshlrev_b32_e32 v205, s1, v204
	v_and_b32_e32 v205, 0x3fff, v205
	v_ashrrev_i32_e32 v204, s10, v204
	v_add_u32_e32 v204, v205, v204
	v_ashrrev_i32_e32 v205, 31, v204
	v_lshl_add_u64 v[204:205], v[204:205], 4, v[162:163]
	v_lshl_add_u64 v[204:205], v[204:205], 3, s[18:19]
	global_load_dwordx4 v[200:203], v[204:205], off offset:16
	s_nop 0
	global_load_dwordx4 v[204:207], v[204:205], off
	v_add_u32_e32 v212, 32, v164
	v_add_u32_e32 v212, s46, v212
	v_lshlrev_b32_e32 v213, s1, v212
	v_and_b32_e32 v213, 0x3fff, v213
	v_ashrrev_i32_e32 v212, s10, v212
	v_add_u32_e32 v212, v213, v212
	v_ashrrev_i32_e32 v213, 31, v212
	v_lshl_add_u64 v[212:213], v[212:213], 4, v[162:163]
	v_lshl_add_u64 v[212:213], v[212:213], 3, s[18:19]
	global_load_dwordx4 v[208:211], v[212:213], off offset:16
	s_nop 0
	global_load_dwordx4 v[212:215], v[212:213], off
	v_add_u32_e32 v220, 48, v164
	v_add_u32_e32 v220, s46, v220
	v_lshlrev_b32_e32 v221, s1, v220
	v_and_b32_e32 v221, 0x3fff, v221
	v_ashrrev_i32_e32 v220, s10, v220
	v_add_u32_e32 v220, v221, v220
	v_ashrrev_i32_e32 v221, 31, v220
	v_lshl_add_u64 v[220:221], v[220:221], 4, v[162:163]
	v_lshl_add_u64 v[220:221], v[220:221], 3, s[18:19]
	global_load_dwordx4 v[216:219], v[220:221], off offset:16
	s_nop 0
	global_load_dwordx4 v[220:223], v[220:221], off
	v_add_u32_e32 v228, 0x80, v164
	v_add_u32_e32 v228, s46, v228
	v_lshlrev_b32_e32 v229, s1, v228
	v_and_b32_e32 v229, 0x3fff, v229
	v_ashrrev_i32_e32 v228, s10, v228
	v_add_u32_e32 v228, v229, v228
	v_ashrrev_i32_e32 v229, 31, v228
	v_lshl_add_u64 v[228:229], v[228:229], 4, v[162:163]
	v_lshl_add_u64 v[228:229], v[228:229], 3, s[18:19]
	global_load_dwordx4 v[224:227], v[228:229], off offset:16
	s_nop 0
	global_load_dwordx4 v[228:231], v[228:229], off
	v_add_u32_e32 v236, 0x90, v164
	v_add_u32_e32 v236, s46, v236
	v_lshlrev_b32_e32 v237, s1, v236
	v_and_b32_e32 v237, 0x3fff, v237
	v_ashrrev_i32_e32 v236, s10, v236
	v_add_u32_e32 v236, v237, v236
	v_ashrrev_i32_e32 v237, 31, v236
	v_lshl_add_u64 v[236:237], v[236:237], 4, v[162:163]
	v_lshl_add_u64 v[236:237], v[236:237], 3, s[18:19]
	global_load_dwordx4 v[232:235], v[236:237], off offset:16
	s_nop 0
	global_load_dwordx4 v[236:239], v[236:237], off
	s_waitcnt vmcnt(10)
	v_mov_b32_e32 v130, v192
	v_mov_b32_e32 v131, v193
	v_mov_b32_e32 v132, v194
	v_mov_b32_e32 v133, v195
	v_mov_b32_e32 v134, v196
	v_mov_b32_e32 v135, v197
	v_mov_b32_e32 v136, v198
	v_mov_b32_e32 v137, v199
	v_add_u32_e32 v196, 0xa0, v164
	v_add_u32_e32 v196, s46, v196
	v_lshlrev_b32_e32 v197, s1, v196
	v_and_b32_e32 v197, 0x3fff, v197
	v_ashrrev_i32_e32 v196, s10, v196
	v_add_u32_e32 v196, v197, v196
	v_ashrrev_i32_e32 v197, 31, v196
	v_lshl_add_u64 v[196:197], v[196:197], 4, v[162:163]
	v_lshl_add_u64 v[196:197], v[196:197], 3, s[18:19]
	global_load_dwordx4 v[192:195], v[196:197], off offset:16
	s_nop 0
	global_load_dwordx4 v[196:199], v[196:197], off

; __device__ __forceinline__ unsigned cvt_pk_bf16(float lo, float hi) { unsigned r; asm volatile("v_cvt_pk_bf16_f32 %0, %1, %2" : "=v"(r) : "v"(lo), "v"(hi)); return r; }
; #define PG8_BAR __builtin_amdgcn_s_barrier()
; template <class Epi, class Map>
; __device__ __forceinline__ void gemm_phase(LAS unsigned char* lds, const Gemm g, const Sched<Map>& S, const Epi& E) {
;     ...
;         if (wr == 0) PG8_BAR;
;     __device__ __forceinline__ void operator()(const Acc& acc, const Unit& u, int wr, int wc, int fr, int fq) const {
;     ...
; #pragma unroll
;                 for (int bj = 0; bj < 2; ++bj) {
;                     const f32x4 x1 = acc[ai][bj][m][0], x2 = acc[ai][bj][m][1];
;                     float o1[4], o2[4];
;                     const float cc[4] = {t0[0], t0[2], t1[0], t1[2]}, ss[4] = {t0[1], t0[3], t1[1], t1[3]};
; #pragma unroll
;                     for (int j = 0; j < 4; ++j) { o1[j] = x1[j] * cc[j] - x2[j] * ss[j]; o2[j] = x2[j] * cc[j] + x1[j] * ss[j]; }
;                     const unsigned lo0 = cvt_pk_bf16(o1[0], o1[1]), lo1 = cvt_pk_bf16(o1[2], o1[3]), hi0 = cvt_pk_bf16(o2[0], o2[1]), hi1 = cvt_pk_bf16(o2[2], o2[3]);
;                     const auto s0 = __builtin_amdgcn_permlane16_swap(lo0, hi0, false, false), s1 = __builtin_amdgcn_permlane16_swap(lo1, hi1, false, false);
;                     *(u32x4*)(rowp + bj * HALF) = (u32x4){s0[0], s1[0], s0[1], s1[1]};
;                 }
.LBB0_230:
	v_mov_b32_e32 v118, v108
	v_mov_b32_e32 v119, v104
	v_pk_mul_f32 v[118:119], v[118:119], v[112:113]
	v_ashrrev_i32_e32 v117, 31, v116
	v_sub_f32_e32 v120, v118, v119
	v_mov_b32_e32 v118, v104
	v_mov_b32_e32 v119, v108
	v_pk_mul_f32 v[118:119], v[118:119], v[112:113]
	v_mov_b32_e32 v104, v109
	v_mov_b32_e32 v108, v105
	v_add_f32_e32 v121, v119, v118
	v_pk_mul_f32 v[118:119], v[104:105], v[114:115]
	v_pk_mul_f32 v[104:105], v[108:109], v[114:115]
	v_sub_f32_e32 v118, v118, v119
	v_add_f32_e32 v108, v105, v104
	v_mov_b32_e32 v104, v110
	v_mov_b32_e32 v105, v106
	v_pk_mul_f32 v[104:105], v[104:105], v[128:129]
	v_lshlrev_b64 v[116:117], 12, v[116:117]
	v_sub_f32_e32 v109, v104, v105
	v_mov_b32_e32 v104, v106
	v_mov_b32_e32 v105, v110
	v_pk_mul_f32 v[104:105], v[104:105], v[128:129]
	v_mov_b32_e32 v106, v111
	v_add_f32_e32 v119, v105, v104
	v_pk_mul_f32 v[104:105], v[106:107], v[130:131]
	v_mov_b32_e32 v110, v107
	v_sub_f32_e32 v106, v104, v105
	v_pk_mul_f32 v[104:105], v[110:111], v[130:131]
	v_lshl_add_u64 v[116:117], s[44:45], 0, v[116:117]
	v_add_f32_e32 v107, v105, v104
	v_lshl_add_u64 v[116:117], v[116:117], 0, s[60:61]
	v_cvt_pk_bf16_f32 v104, v120, v118
	v_cvt_pk_bf16_f32 v105, v109, v106
	v_cvt_pk_bf16_f32 v106, v121, v108
	v_cvt_pk_bf16_f32 v107, v119, v107
	v_lshl_add_u64 v[116:117], v[166:167], 1, v[116:117]
	v_permlane16_swap_b32_e32 v104, v106
	v_permlane16_swap_b32_e32 v105, v107
	global_store_dwordx4 v[116:117], v[104:107], off
	s_and_b64 vcc, exec, s[42:43]
	s_nop 0
	v_mov_b32_e32 v104, v100
	v_mov_b32_e32 v105, v96
	v_pk_mul_f32 v[104:105], v[104:105], v[112:113]
	s_nop 0
	v_sub_f32_e32 v106, v104, v105
	v_mov_b32_e32 v104, v96
	v_mov_b32_e32 v105, v100
	v_pk_mul_f32 v[104:105], v[104:105], v[112:113]
	v_mov_b32_e32 v96, v101
	v_mov_b32_e32 v100, v97
	v_add_f32_e32 v107, v105, v104
	v_pk_mul_f32 v[104:105], v[96:97], v[114:115]
	v_pk_mul_f32 v[96:97], v[100:101], v[114:115]
	v_sub_f32_e32 v104, v104, v105
	v_add_f32_e32 v100, v97, v96
	v_mov_b32_e32 v96, v102
	v_mov_b32_e32 v97, v98
	v_pk_mul_f32 v[96:97], v[96:97], v[128:129]
	s_nop 0
	v_sub_f32_e32 v101, v96, v97
	v_mov_b32_e32 v96, v98
	v_mov_b32_e32 v97, v102
	v_pk_mul_f32 v[96:97], v[96:97], v[128:129]
	v_mov_b32_e32 v98, v103
	v_add_f32_e32 v105, v97, v96
	v_pk_mul_f32 v[96:97], v[98:99], v[130:131]
	v_mov_b32_e32 v102, v99
	v_sub_f32_e32 v98, v96, v97
	v_pk_mul_f32 v[96:97], v[102:103], v[130:131]
	v_mov_b32_e32 v102, 1.0
	v_add_f32_e32 v99, v97, v96
	v_cvt_pk_bf16_f32 v96, v106, v104
	v_cvt_pk_bf16_f32 v97, v101, v98
	v_cvt_pk_bf16_f32 v98, v107, v100
	v_cvt_pk_bf16_f32 v99, v105, v99
	v_add_u32_e32 v106, 32, v164
	v_permlane16_swap_b32_e32 v96, v98
	v_permlane16_swap_b32_e32 v97, v99
	global_store_dwordx4 v[116:117], v[96:99], off offset:256
	s_cmp_lg_u64 s[28:29], 0
	s_cbranch_scc0 .Llate_align_0
	s_barrier
.Llate_align_0:
	v_mov_b32_e32 v100, 1.0
	v_mov_b32_e32 v101, 0
	v_mov_b32_e32 v97, 0
	v_mov_b32_e32 v96, 1.0
	v_mov_b32_e32 v98, 1.0
	v_mov_b32_e32 v99, 0
	v_mov_b32_e32 v103, 0
	v_mov_b32_e32 v104, 1.0
	v_mov_b32_e32 v105, 0
	s_cbranch_vccnz .LBB0_232
	s_waitcnt vmcnt(14)
	v_mov_b32_e32 v98, v208
	v_mov_b32_e32 v99, v209
	v_mov_b32_e32 v100, v210
	v_mov_b32_e32 v101, v211
	v_mov_b32_e32 v102, v212
	v_mov_b32_e32 v103, v213
	v_mov_b32_e32 v104, v214
	v_mov_b32_e32 v105, v215

; #define PG8_STAGE(bufoff, gbase, voff) do { _Pragma("unroll") for (int _i = 0; _i < 2; ++_i) \
;         __builtin_amdgcn_global_load_lds((const unsigned*)((const char*)(gbase) + (voff)[_i]), (LAS unsigned*)(lds + (bufoff) + ldsw + _i * 8192), 16, 0, 0); } while (0)
; #define PG8_LDA(dst, b, h) do { _Pragma("unroll") for (int m = 0; m < 4; ++m) _Pragma("unroll") for (int k = 0; k < 2; ++k) dst[m][k] = *(const LAS bf16x8*)(lds + PG8_SA(b, h) + aoff + m * 2048 + k * 1024); } while (0)
; #define PG8_LDB(dst, b, h) do { _Pragma("unroll") for (int n = 0; n < 2; ++n) _Pragma("unroll") for (int k = 0; k < 2; ++k) dst[n][k] = *(const LAS bf16x8*)(lds + PG8_SB(b, h) + boff + n * 2048 + k * 1024); } while (0)
; #define PG8_MMA(ai, bj, At, Bt) do { __builtin_amdgcn_s_setprio(1); _Pragma("unroll") for (int m = 0; m < 4; ++m) _Pragma("unroll") for (int n = 0; n < 2; ++n) _Pragma("unroll") for (int k = 0; k < 2; ++k) \
;         acc[ai][bj][m][n] = __builtin_amdgcn_mfma_f32_16x16x32_bf16(Bt[n][k], At[m][k], acc[ai][bj][m][n], 0, 0, 0); __builtin_amdgcn_s_setprio(0); } while (0)
; #define PG8_WAIT_V(n) asm volatile("s_waitcnt vmcnt(" #n ")" ::: "memory")
; #define PG8_WAIT_L(n) asm volatile("s_waitcnt lgkmcnt(" #n ")" ::: "memory")
; #define PG8_BAR __builtin_amdgcn_s_barrier()
; #define PG8_SCHED __builtin_amdgcn_sched_barrier(0)
; template <class Epi, class Map>
; __device__ __forceinline__ void gemm_phase(LAS unsigned char* lds, const Gemm g, const Sched<Map>& S, const Epi& E) {
;     ...
;         const bool has_next = S.next(ui + 1, nxt);
;         const char* nA = has_next ? (const char*)g.A + nxt.aoff : cA; const char* nB = has_next ? (const char*)g.Bt + nxt.boff : cB;
; #pragma unroll 1
;         for (int t = 0; t < nt; t += 2) {
;             const bool last = (t == nt - 2);
;             const char* a1 = cA + (size_t)(t + 1) * kstep;
;             const char* a2 = last ? nA : cA + (size_t)(t + 2) * kstep; const char* b2 = last ? nB : cB + (size_t)(t + 2) * kstep;
;             const char* a3 = a2 + kstep; const char* b3 = b2 + kstep;
;             PG8_LDB(B0, 0, 0); PG8_LDB(B1, 0, 1); PG8_SCHED; PG8_LDA(At, 0, 0); PG8_STAGE(PG8_SA(1, 1), a1 + hstepA, voffA);
;             PG8_WAIT_V(8); PG8_WAIT_L(0); PG8_BAR; PG8_MMA(0, 0, At, B0); PG8_MMA(0, 1, At, B1); PG8_BAR; PG8_SCHED;
.LBB0_260:
	s_add_u32 s28, s2, s43
	s_addc_u32 s29, s3, 0
	s_and_b64 s[30:31], s[40:41], exec
	s_cselect_b32 s25, s29, s35
	s_cselect_b32 s46, s28, s34
	s_add_u32 s30, s16, s44
	s_addc_u32 s31, s17, 0
	s_and_b64 s[48:49], s[40:41], exec
	s_cselect_b32 s47, s31, s37
	s_cselect_b32 s48, s30, s36
	s_add_u32 s34, s34, 0x80080
	s_addc_u32 s35, s35, 0
	s_add_u32 s49, s36, 0x100
	v_mov_b32_e32 v0, 0
	s_addc_u32 s50, s37, 0
	s_mov_b32 s51, -2
	v_mov_b32_e32 v1, v0
	v_mov_b32_e32 v2, v0
	v_mov_b32_e32 v3, v0
	v_mov_b32_e32 v4, v0
	v_mov_b32_e32 v5, v0
	v_mov_b32_e32 v6, v0
	v_mov_b32_e32 v7, v0
	v_mov_b32_e32 v8, v0
	v_mov_b32_e32 v9, v0
	v_mov_b32_e32 v10, v0
	v_mov_b32_e32 v11, v0
	v_mov_b32_e32 v16, v0
	v_mov_b32_e32 v17, v0
	v_mov_b32_e32 v18, v0
	v_mov_b32_e32 v19, v0
	v_mov_b32_e32 v24, v0
	v_mov_b32_e32 v25, v0
	v_mov_b32_e32 v26, v0
	v_mov_b32_e32 v27, v0
	v_mov_b32_e32 v32, v0
	v_mov_b32_e32 v33, v0
	v_mov_b32_e32 v34, v0
	v_mov_b32_e32 v35, v0
	v_mov_b32_e32 v40, v0
	v_mov_b32_e32 v41, v0
	v_mov_b32_e32 v42, v0
	v_mov_b32_e32 v43, v0
	v_mov_b32_e32 v48, v0
	v_mov_b32_e32 v49, v0
	v_mov_b32_e32 v50, v0
	v_mov_b32_e32 v51, v0
	v_mov_b32_e32 v12, v0
	v_mov_b32_e32 v13, v0
	v_mov_b32_e32 v14, v0
	v_mov_b32_e32 v15, v0
	v_mov_b32_e32 v20, v0
	v_mov_b32_e32 v21, v0
	v_mov_b32_e32 v22, v0
	v_mov_b32_e32 v23, v0
	v_mov_b32_e32 v28, v0
	v_mov_b32_e32 v29, v0
	v_mov_b32_e32 v30, v0
	v_mov_b32_e32 v31, v0
	v_mov_b32_e32 v36, v0
	v_mov_b32_e32 v37, v0
	v_mov_b32_e32 v38, v0
	v_mov_b32_e32 v39, v0
	v_mov_b32_e32 v44, v0
	v_mov_b32_e32 v45, v0
	v_mov_b32_e32 v46, v0
	v_mov_b32_e32 v47, v0
	v_mov_b32_e32 v52, v0
	v_mov_b32_e32 v53, v0
	v_mov_b32_e32 v54, v0
	v_mov_b32_e32 v55, v0
	v_mov_b32_e32 v56, v0
	v_mov_b32_e32 v57, v0
	v_mov_b32_e32 v58, v0
	v_mov_b32_e32 v59, v0
	v_mov_b32_e32 v60, v0
	v_mov_b32_e32 v61, v0
	v_mov_b32_e32 v62, v0
	v_mov_b32_e32 v63, v0
	v_mov_b32_e32 v64, v0
	v_mov_b32_e32 v65, v0
	v_mov_b32_e32 v66, v0
	v_mov_b32_e32 v67, v0
	v_mov_b32_e32 v68, v0
	v_mov_b32_e32 v69, v0
	v_mov_b32_e32 v70, v0
	v_mov_b32_e32 v71, v0
	v_mov_b32_e32 v72, v0
	v_mov_b32_e32 v73, v0
	v_mov_b32_e32 v74, v0
	v_mov_b32_e32 v75, v0
	v_mov_b32_e32 v80, v0
	v_mov_b32_e32 v81, v0
	v_mov_b32_e32 v82, v0
	v_mov_b32_e32 v83, v0
	v_mov_b32_e32 v88, v0
	v_mov_b32_e32 v89, v0
	v_mov_b32_e32 v90, v0
	v_mov_b32_e32 v91, v0
	v_mov_b32_e32 v96, v0
	v_mov_b32_e32 v97, v0
	v_mov_b32_e32 v98, v0
	v_mov_b32_e32 v99, v0
	v_mov_b32_e32 v104, v0
	v_mov_b32_e32 v105, v0
	v_mov_b32_e32 v106, v0
	v_mov_b32_e32 v107, v0
	v_mov_b32_e32 v112, v0
	v_mov_b32_e32 v113, v0
	v_mov_b32_e32 v114, v0
	v_mov_b32_e32 v115, v0
	v_mov_b32_e32 v76, v0
	v_mov_b32_e32 v77, v0
	v_mov_b32_e32 v78, v0
	v_mov_b32_e32 v79, v0
	v_mov_b32_e32 v84, v0
	v_mov_b32_e32 v85, v0
	v_mov_b32_e32 v86, v0
	v_mov_b32_e32 v87, v0
	v_mov_b32_e32 v92, v0
	v_mov_b32_e32 v93, v0
	v_mov_b32_e32 v94, v0
	v_mov_b32_e32 v95, v0
	v_mov_b32_e32 v100, v0
	v_mov_b32_e32 v101, v0
	v_mov_b32_e32 v102, v0
	v_mov_b32_e32 v103, v0
	v_mov_b32_e32 v108, v0
	v_mov_b32_e32 v109, v0
	v_mov_b32_e32 v110, v0
	v_mov_b32_e32 v111, v0
	v_mov_b32_e32 v116, v0
	v_mov_b32_e32 v117, v0
	v_mov_b32_e32 v118, v0
	v_mov_b32_e32 v119, v0
	v_mov_b32_e32 v120, v0
	v_mov_b32_e32 v121, v0
	v_mov_b32_e32 v122, v0
	v_mov_b32_e32 v123, v0
	v_mov_b32_e32 v124, v0
	v_mov_b32_e32 v125, v0
	v_mov_b32_e32 v126, v0
	v_mov_b32_e32 v127, v0
.LBB0_261:
	s_add_u32 s36, s34, 0xfff80080
	s_addc_u32 s37, s35, -1
	s_add_i32 s54, 0, 0x10000
	s_cmp_eq_u32 s51, 28
	s_cselect_b32 s37, s25, s37
	s_cselect_b32 s36, s46, s36
	v_add_u32_e32 v138, s54, v142
	s_cselect_b32 s53, s47, s50
	s_cselect_b32 s52, s48, s49
	s_add_i32 s55, 0, 0x14000
	ds_read_b128 v[158:161], v138
	ds_read_b128 v[162:165], v138 offset:1024
	ds_read_b128 v[166:169], v138 offset:2048
	ds_read_b128 v[170:173], v138 offset:3072
	v_add_u32_e32 v138, s55, v142
	ds_read_b128 v[174:177], v138
	ds_read_b128 v[178:181], v138 offset:1024
	ds_read_b128 v[192:195], v138 offset:2048
	ds_read_b128 v[196:199], v138 offset:3072
	v_lshl_add_u64 v[138:139], s[34:35], 0, v[134:135]
	s_add_i32 m0, s7, 0xc000
	ds_read_b128 v[200:203], v143
	ds_read_b128 v[204:207], v143 offset:1024
	ds_read_b128 v[208:211], v143 offset:2048
	ds_read_b128 v[212:215], v143 offset:3072
	ds_read_b128 v[216:219], v143 offset:4096
	ds_read_b128 v[220:223], v143 offset:5120
	ds_read_b128 v[224:227], v143 offset:6144
	ds_read_b128 v[228:231], v143 offset:7168
	global_load_lds_dwordx4 v[138:139], off
	v_lshl_add_u64 v[138:139], s[34:35], 0, v[136:137]
	s_add_i32 m0, s7, 0xe000
	s_nop 0
	global_load_lds_dwordx4 v[138:139], off
	s_waitcnt vmcnt(8)
	s_waitcnt lgkmcnt(0)
	s_barrier
; #define PG8_STAGE(bufoff, gbase, voff) do { _Pragma("unroll") for (int _i = 0; _i < 2; ++_i) \
;         __builtin_amdgcn_global_load_lds((const unsigned*)((const char*)(gbase) + (voff)[_i]), (LAS unsigned*)(lds + (bufoff) + ldsw + _i * 8192), 16, 0, 0); } while (0)
; #define PG8_LDA(dst, b, h) do { _Pragma("unroll") for (int m = 0; m < 4; ++m) _Pragma("unroll") for (int k = 0; k < 2; ++k) dst[m][k] = *(const LAS bf16x8*)(lds + PG8_SA(b, h) + aoff + m * 2048 + k * 1024); } while (0)
; #define PG8_LDB(dst, b, h) do { _Pragma("unroll") for (int n = 0; n < 2; ++n) _Pragma("unroll") for (int k = 0; k < 2; ++k) dst[n][k] = *(const LAS bf16x8*)(lds + PG8_SB(b, h) + boff + n * 2048 + k * 1024); } while (0)
; #define PG8_MMA(ai, bj, At, Bt) do { __builtin_amdgcn_s_setprio(1); _Pragma("unroll") for (int m = 0; m < 4; ++m) _Pragma("unroll") for (int n = 0; n < 2; ++n) _Pragma("unroll") for (int k = 0; k < 2; ++k) \
;         acc[ai][bj][m][n] = __builtin_amdgcn_mfma_f32_16x16x32_bf16(Bt[n][k], At[m][k], acc[ai][bj][m][n], 0, 0, 0); __builtin_amdgcn_s_setprio(0); } while (0)
; #define PG8_WAIT_V(n) asm volatile("s_waitcnt vmcnt(" #n ")" ::: "memory")
; #define PG8_WAIT_L(n) asm volatile("s_waitcnt lgkmcnt(" #n ")" ::: "memory")
; #define PG8_BAR __builtin_amdgcn_s_barrier()
; #define PG8_SCHED __builtin_amdgcn_sched_barrier(0)
; template <class Epi, class Map>
; __device__ __forceinline__ void gemm_phase(LAS unsigned char* lds, const Gemm g, const Sched<Map>& S, const Epi& E) {
;     ...
;             PG8_WAIT_V(8); PG8_WAIT_L(0); PG8_BAR; PG8_MMA(0, 0, At, B0); PG8_MMA(0, 1, At, B1); PG8_BAR; PG8_SCHED;
;             PG8_LDA(At, 0, 1); PG8_STAGE(PG8_SB(0, 0), b2, voffB); PG8_STAGE(PG8_SB(0, 1), b2 + hstepB, voffB); PG8_STAGE(PG8_SA(0, 0), a2, voffA);
;             PG8_WAIT_V(8); PG8_WAIT_L(0); PG8_BAR; PG8_MMA(1, 0, At, B0); PG8_MMA(1, 1, At, B1); PG8_BAR; PG8_SCHED;
;             PG8_LDB(B0, 1, 0); PG8_LDB(B1, 1, 1); PG8_SCHED; PG8_LDA(At, 1, 0); PG8_STAGE(PG8_SA(0, 1), a2 + hstepA, voffA);
;             PG8_WAIT_V(8); PG8_WAIT_L(0); PG8_BAR; PG8_MMA(0, 0, At, B0); PG8_MMA(0, 1, At, B1); PG8_BAR; PG8_SCHED;
	s_waitcnt lgkmcnt(0)
	v_mfma_f32_16x16x32_bf16 v[124:127], v[158:161], v[200:203], v[124:127]
	v_mfma_f32_16x16x32_bf16 v[120:123], v[166:169], v[200:203], v[120:123]
	v_mfma_f32_16x16x32_bf16 v[116:119], v[158:161], v[208:211], v[116:119]
	v_mfma_f32_16x16x32_bf16 v[108:111], v[166:169], v[208:211], v[108:111]
	v_mfma_f32_16x16x32_bf16 v[100:103], v[158:161], v[216:219], v[100:103]
	v_mfma_f32_16x16x32_bf16 v[92:95], v[166:169], v[216:219], v[92:95]
	v_mfma_f32_16x16x32_bf16 v[84:87], v[158:161], v[224:227], v[84:87]
	v_mfma_f32_16x16x32_bf16 v[76:79], v[166:169], v[224:227], v[76:79]
	v_mfma_f32_16x16x32_bf16 v[124:127], v[162:165], v[204:207], v[124:127]
	v_mfma_f32_16x16x32_bf16 v[120:123], v[170:173], v[204:207], v[120:123]
	v_mfma_f32_16x16x32_bf16 v[116:119], v[162:165], v[212:215], v[116:119]
	v_mfma_f32_16x16x32_bf16 v[108:111], v[170:173], v[212:215], v[108:111]
	v_mfma_f32_16x16x32_bf16 v[100:103], v[162:165], v[220:223], v[100:103]
	v_mfma_f32_16x16x32_bf16 v[92:95], v[170:173], v[220:223], v[92:95]
	v_mfma_f32_16x16x32_bf16 v[84:87], v[162:165], v[228:231], v[84:87]
	v_mfma_f32_16x16x32_bf16 v[76:79], v[170:173], v[228:231], v[76:79]
	v_mfma_f32_16x16x32_bf16 v[112:115], v[174:177], v[200:203], v[112:115]
	v_mfma_f32_16x16x32_bf16 v[104:107], v[192:195], v[200:203], v[104:107]
	v_mfma_f32_16x16x32_bf16 v[96:99], v[174:177], v[208:211], v[96:99]
	v_mfma_f32_16x16x32_bf16 v[88:91], v[192:195], v[208:211], v[88:91]
	v_mfma_f32_16x16x32_bf16 v[80:83], v[174:177], v[216:219], v[80:83]
	v_mfma_f32_16x16x32_bf16 v[72:75], v[192:195], v[216:219], v[72:75]
	v_mfma_f32_16x16x32_bf16 v[68:71], v[174:177], v[224:227], v[68:71]
	v_mfma_f32_16x16x32_bf16 v[64:67], v[192:195], v[224:227], v[64:67]
	v_mfma_f32_16x16x32_bf16 v[112:115], v[178:181], v[204:207], v[112:115]
	v_mfma_f32_16x16x32_bf16 v[104:107], v[196:199], v[204:207], v[104:107]
	v_mfma_f32_16x16x32_bf16 v[96:99], v[178:181], v[212:215], v[96:99]
	v_mfma_f32_16x16x32_bf16 v[88:91], v[196:199], v[212:215], v[88:91]
	v_mfma_f32_16x16x32_bf16 v[80:83], v[178:181], v[220:223], v[80:83]
	v_mfma_f32_16x16x32_bf16 v[72:75], v[196:199], v[220:223], v[72:75]
	v_mfma_f32_16x16x32_bf16 v[68:71], v[178:181], v[228:231], v[68:71]
	v_mfma_f32_16x16x32_bf16 v[64:67], v[196:199], v[228:231], v[64:67]
	s_barrier
	s_add_i32 s54, s54, s6
	v_lshl_add_u64 v[138:139], s[52:53], 0, v[144:145]
	s_mov_b32 m0, s54
	ds_read_b128 v[200:203], v143 offset:16384
	ds_read_b128 v[204:207], v143 offset:17408
	ds_read_b128 v[208:211], v143 offset:18432
	ds_read_b128 v[212:215], v143 offset:19456
	ds_read_b128 v[216:219], v143 offset:20480
	ds_read_b128 v[220:223], v143 offset:21504
	ds_read_b128 v[224:227], v143 offset:22528
	ds_read_b128 v[228:231], v143 offset:23552
	global_load_lds_dwordx4 v[138:139], off
	s_add_i32 m0, s54, 0x2000
	v_lshl_add_u64 v[232:233], s[52:53], 0, v[128:129]
	s_add_u32 s52, s52, s5
	s_addc_u32 s53, s53, 0
	s_add_i32 s54, s55, s6
	global_load_lds_dwordx4 v[232:233], off
	v_lshl_add_u64 v[234:235], s[52:53], 0, v[144:145]
	s_mov_b32 m0, s54
	v_lshl_add_u64 v[236:237], s[52:53], 0, v[128:129]
	global_load_lds_dwordx4 v[234:235], off
	s_add_i32 m0, s54, 0x2000
	v_lshl_add_u64 v[238:239], s[36:37], 0, v[132:133]
	global_load_lds_dwordx4 v[236:237], off
	s_mov_b32 m0, s7
	v_lshl_add_u64 v[240:241], s[36:37], 0, v[130:131]
	global_load_lds_dwordx4 v[238:239], off
	s_mov_b32 m0, s8
	s_nop 0
	global_load_lds_dwordx4 v[240:241], off
	s_waitcnt vmcnt(8)
	s_waitcnt lgkmcnt(0)
	s_barrier
	s_waitcnt lgkmcnt(0)
	v_mfma_f32_16x16x32_bf16 v[60:63], v[158:161], v[200:203], v[60:63]
	v_mfma_f32_16x16x32_bf16 v[56:59], v[166:169], v[200:203], v[56:59]
	v_mfma_f32_16x16x32_bf16 v[52:55], v[158:161], v[208:211], v[52:55]
	v_mfma_f32_16x16x32_bf16 v[44:47], v[166:169], v[208:211], v[44:47]
	v_mfma_f32_16x16x32_bf16 v[36:39], v[158:161], v[216:219], v[36:39]
	v_mfma_f32_16x16x32_bf16 v[28:31], v[166:169], v[216:219], v[28:31]
	v_mfma_f32_16x16x32_bf16 v[20:23], v[158:161], v[224:227], v[20:23]
	v_mfma_f32_16x16x32_bf16 v[12:15], v[166:169], v[224:227], v[12:15]
	v_mfma_f32_16x16x32_bf16 v[60:63], v[162:165], v[204:207], v[60:63]
	v_mfma_f32_16x16x32_bf16 v[56:59], v[170:173], v[204:207], v[56:59]
	v_mfma_f32_16x16x32_bf16 v[52:55], v[162:165], v[212:215], v[52:55]
	v_mfma_f32_16x16x32_bf16 v[44:47], v[170:173], v[212:215], v[44:47]
	v_mfma_f32_16x16x32_bf16 v[36:39], v[162:165], v[220:223], v[36:39]
	v_mfma_f32_16x16x32_bf16 v[28:31], v[170:173], v[220:223], v[28:31]
	v_mfma_f32_16x16x32_bf16 v[20:23], v[162:165], v[228:231], v[20:23]
	v_mfma_f32_16x16x32_bf16 v[12:15], v[170:173], v[228:231], v[12:15]
	v_mfma_f32_16x16x32_bf16 v[48:51], v[174:177], v[200:203], v[48:51]
	v_mfma_f32_16x16x32_bf16 v[40:43], v[192:195], v[200:203], v[40:43]
	v_mfma_f32_16x16x32_bf16 v[32:35], v[174:177], v[208:211], v[32:35]
	v_mfma_f32_16x16x32_bf16 v[24:27], v[192:195], v[208:211], v[24:27]
	v_mfma_f32_16x16x32_bf16 v[16:19], v[174:177], v[216:219], v[16:19]
	v_mfma_f32_16x16x32_bf16 v[8:11], v[192:195], v[216:219], v[8:11]
	v_mfma_f32_16x16x32_bf16 v[4:7], v[174:177], v[224:227], v[4:7]
	v_mfma_f32_16x16x32_bf16 v[0:3], v[192:195], v[224:227], v[0:3]
	v_mfma_f32_16x16x32_bf16 v[48:51], v[178:181], v[204:207], v[48:51]
	v_mfma_f32_16x16x32_bf16 v[40:43], v[196:199], v[204:207], v[40:43]
	v_mfma_f32_16x16x32_bf16 v[32:35], v[178:181], v[212:215], v[32:35]
	v_mfma_f32_16x16x32_bf16 v[24:27], v[196:199], v[212:215], v[24:27]
	v_mfma_f32_16x16x32_bf16 v[16:19], v[178:181], v[220:223], v[16:19]
	v_mfma_f32_16x16x32_bf16 v[8:11], v[196:199], v[220:223], v[8:11]
	v_mfma_f32_16x16x32_bf16 v[4:7], v[178:181], v[228:231], v[4:7]
	v_mfma_f32_16x16x32_bf16 v[0:3], v[196:199], v[228:231], v[0:3]
	s_barrier
; #define PG8_STAGE(bufoff, gbase, voff) do { _Pragma("unroll") for (int _i = 0; _i < 2; ++_i) \
;         __builtin_amdgcn_global_load_lds((const unsigned*)((const char*)(gbase) + (voff)[_i]), (LAS unsigned*)(lds + (bufoff) + ldsw + _i * 8192), 16, 0, 0); } while (0)
; #define PG8_LDA(dst, b, h) do { _Pragma("unroll") for (int m = 0; m < 4; ++m) _Pragma("unroll") for (int k = 0; k < 2; ++k) dst[m][k] = *(const LAS bf16x8*)(lds + PG8_SA(b, h) + aoff + m * 2048 + k * 1024); } while (0)
; #define PG8_LDB(dst, b, h) do { _Pragma("unroll") for (int n = 0; n < 2; ++n) _Pragma("unroll") for (int k = 0; k < 2; ++k) dst[n][k] = *(const LAS bf16x8*)(lds + PG8_SB(b, h) + boff + n * 2048 + k * 1024); } while (0)
; #define PG8_MMA(ai, bj, At, Bt) do { __builtin_amdgcn_s_setprio(1); _Pragma("unroll") for (int m = 0; m < 4; ++m) _Pragma("unroll") for (int n = 0; n < 2; ++n) _Pragma("unroll") for (int k = 0; k < 2; ++k) \
;         acc[ai][bj][m][n] = __builtin_amdgcn_mfma_f32_16x16x32_bf16(Bt[n][k], At[m][k], acc[ai][bj][m][n], 0, 0, 0); __builtin_amdgcn_s_setprio(0); } while (0)
; #define PG8_WAIT_V(n) asm volatile("s_waitcnt vmcnt(" #n ")" ::: "memory")
; #define PG8_WAIT_L(n) asm volatile("s_waitcnt lgkmcnt(" #n ")" ::: "memory")
; #define PG8_BAR __builtin_amdgcn_s_barrier()
; #define PG8_SCHED __builtin_amdgcn_sched_barrier(0)
; template <class Epi, class Map>
; __device__ __forceinline__ void gemm_phase(LAS unsigned char* lds, const Gemm g, const Sched<Map>& S, const Epi& E) {
;     ...
;             PG8_LDB(B0, 1, 0); PG8_LDB(B1, 1, 1); PG8_SCHED; PG8_LDA(At, 1, 0); PG8_STAGE(PG8_SA(0, 1), a2 + hstepA, voffA);
;             PG8_WAIT_V(8); PG8_WAIT_L(0); PG8_BAR; PG8_MMA(0, 0, At, B0); PG8_MMA(0, 1, At, B1); PG8_BAR; PG8_SCHED;
;             PG8_LDA(At, 1, 1); PG8_STAGE(PG8_SB(1, 0), b3, voffB); PG8_STAGE(PG8_SB(1, 1), b3 + hstepB, voffB); PG8_STAGE(PG8_SA(1, 0), a3, voffA);
;             PG8_WAIT_V(8); PG8_WAIT_L(0); PG8_BAR; PG8_MMA(1, 0, At, B0); PG8_MMA(1, 1, At, B1); PG8_BAR; PG8_SCHED;
	s_add_i32 s52, 0, 0x18000
	s_add_i32 s53, 0, 0x1c000
	v_add_u32_e32 v170, s52, v142
	v_add_u32_e32 v196, s53, v142
	ds_read_b128 v[158:161], v170
	ds_read_b128 v[162:165], v170 offset:1024
	ds_read_b128 v[166:169], v170 offset:2048
	ds_read_b128 v[170:173], v170 offset:3072
	ds_read_b128 v[174:177], v196
	ds_read_b128 v[178:181], v196 offset:1024
	ds_read_b128 v[192:195], v196 offset:2048
	ds_read_b128 v[196:199], v196 offset:3072
	s_add_u32 s36, s36, 0x80000
	s_addc_u32 s37, s37, 0
	s_mov_b32 m0, s9
	v_lshl_add_u64 v[242:243], s[36:37], 0, v[132:133]
	ds_read_b128 v[200:203], v143 offset:32768
	ds_read_b128 v[204:207], v143 offset:33792
	ds_read_b128 v[208:211], v143 offset:34816
	ds_read_b128 v[212:215], v143 offset:35840
	ds_read_b128 v[216:219], v143 offset:36864
	ds_read_b128 v[220:223], v143 offset:37888
	ds_read_b128 v[224:227], v143 offset:38912
	ds_read_b128 v[228:231], v143 offset:39936
	global_load_lds_dwordx4 v[242:243], off
	v_lshl_add_u64 v[242:243], s[36:37], 0, v[130:131]
	s_mov_b32 m0, s10
	s_nop 0
	global_load_lds_dwordx4 v[242:243], off
	s_waitcnt vmcnt(8)
	s_waitcnt lgkmcnt(0)
	s_barrier
	s_waitcnt lgkmcnt(0)
	v_mfma_f32_16x16x32_bf16 v[124:127], v[158:161], v[200:203], v[124:127]
	v_mfma_f32_16x16x32_bf16 v[120:123], v[166:169], v[200:203], v[120:123]
	v_mfma_f32_16x16x32_bf16 v[116:119], v[158:161], v[208:211], v[116:119]
	v_mfma_f32_16x16x32_bf16 v[108:111], v[166:169], v[208:211], v[108:111]
	v_mfma_f32_16x16x32_bf16 v[100:103], v[158:161], v[216:219], v[100:103]
	v_mfma_f32_16x16x32_bf16 v[92:95], v[166:169], v[216:219], v[92:95]
	v_mfma_f32_16x16x32_bf16 v[84:87], v[158:161], v[224:227], v[84:87]
	v_mfma_f32_16x16x32_bf16 v[76:79], v[166:169], v[224:227], v[76:79]
	v_mfma_f32_16x16x32_bf16 v[124:127], v[162:165], v[204:207], v[124:127]
	v_mfma_f32_16x16x32_bf16 v[120:123], v[170:173], v[204:207], v[120:123]
	v_mfma_f32_16x16x32_bf16 v[116:119], v[162:165], v[212:215], v[116:119]
	v_mfma_f32_16x16x32_bf16 v[108:111], v[170:173], v[212:215], v[108:111]
	v_mfma_f32_16x16x32_bf16 v[100:103], v[162:165], v[220:223], v[100:103]
	v_mfma_f32_16x16x32_bf16 v[92:95], v[170:173], v[220:223], v[92:95]
	v_mfma_f32_16x16x32_bf16 v[84:87], v[162:165], v[228:231], v[84:87]
	v_mfma_f32_16x16x32_bf16 v[76:79], v[170:173], v[228:231], v[76:79]
	v_mfma_f32_16x16x32_bf16 v[112:115], v[174:177], v[200:203], v[112:115]
	v_mfma_f32_16x16x32_bf16 v[104:107], v[192:195], v[200:203], v[104:107]
	v_mfma_f32_16x16x32_bf16 v[96:99], v[174:177], v[208:211], v[96:99]
	v_mfma_f32_16x16x32_bf16 v[88:91], v[192:195], v[208:211], v[88:91]
	v_mfma_f32_16x16x32_bf16 v[80:83], v[174:177], v[216:219], v[80:83]
	v_mfma_f32_16x16x32_bf16 v[72:75], v[192:195], v[216:219], v[72:75]
	v_mfma_f32_16x16x32_bf16 v[68:71], v[174:177], v[224:227], v[68:71]
	v_mfma_f32_16x16x32_bf16 v[64:67], v[192:195], v[224:227], v[64:67]
	v_mfma_f32_16x16x32_bf16 v[112:115], v[178:181], v[204:207], v[112:115]
	v_mfma_f32_16x16x32_bf16 v[104:107], v[196:199], v[204:207], v[104:107]
	v_mfma_f32_16x16x32_bf16 v[96:99], v[178:181], v[212:215], v[96:99]
	v_mfma_f32_16x16x32_bf16 v[88:91], v[196:199], v[212:215], v[88:91]
	v_mfma_f32_16x16x32_bf16 v[80:83], v[178:181], v[220:223], v[80:83]
	v_mfma_f32_16x16x32_bf16 v[72:75], v[196:199], v[220:223], v[72:75]
	v_mfma_f32_16x16x32_bf16 v[68:71], v[178:181], v[228:231], v[68:71]
	v_mfma_f32_16x16x32_bf16 v[64:67], v[196:199], v[228:231], v[64:67]
	s_barrier
	s_add_i32 s36, s52, s6
	v_lshl_add_u64 v[138:139], v[138:139], 0, s[82:83]
	s_mov_b32 m0, s36
	ds_read_b128 v[200:203], v143 offset:49152
	ds_read_b128 v[204:207], v143 offset:50176
	ds_read_b128 v[208:211], v143 offset:51200
	ds_read_b128 v[212:215], v143 offset:52224
	ds_read_b128 v[216:219], v143 offset:53248
	ds_read_b128 v[220:223], v143 offset:54272
	ds_read_b128 v[224:227], v143 offset:55296
	ds_read_b128 v[228:231], v143 offset:56320
	global_load_lds_dwordx4 v[138:139], off
	v_lshl_add_u64 v[138:139], v[232:233], 0, s[82:83]
	s_add_i32 m0, s36, 0x2000
	s_add_i32 s36, s53, s6
	global_load_lds_dwordx4 v[138:139], off
	v_lshl_add_u64 v[138:139], v[234:235], 0, s[82:83]
	s_mov_b32 m0, s36
	s_nop 0
	global_load_lds_dwordx4 v[138:139], off
	v_lshl_add_u64 v[138:139], v[236:237], 0, s[82:83]
	s_add_i32 m0, s36, 0x2000
	s_nop 0
	global_load_lds_dwordx4 v[138:139], off
	v_lshl_add_u64 v[138:139], v[238:239], 0, s[82:83]
	s_mov_b32 m0, s15
	s_nop 0
	global_load_lds_dwordx4 v[138:139], off
	v_lshl_add_u64 v[138:139], v[240:241], 0, s[82:83]
	s_mov_b32 m0, s33
	s_nop 0
	global_load_lds_dwordx4 v[138:139], off
	s_waitcnt vmcnt(8)
	s_waitcnt lgkmcnt(0)
	s_barrier
; __device__ __forceinline__ unsigned cvt_pk_bf16(float lo, float hi) { unsigned r; asm volatile("v_cvt_pk_bf16_f32 %0, %1, %2" : "=v"(r) : "v"(lo), "v"(hi)); return r; }
; __device__ __forceinline__ float silu_f(float v) { return v / (1.0f + __expf(-v)); }
; #define PG8_MMA(ai, bj, At, Bt) do { __builtin_amdgcn_s_setprio(1); _Pragma("unroll") for (int m = 0; m < 4; ++m) _Pragma("unroll") for (int n = 0; n < 2; ++n) _Pragma("unroll") for (int k = 0; k < 2; ++k) \
;         acc[ai][bj][m][n] = __builtin_amdgcn_mfma_f32_16x16x32_bf16(Bt[n][k], At[m][k], acc[ai][bj][m][n], 0, 0, 0); __builtin_amdgcn_s_setprio(0); } while (0)
; #define PG8_WAIT_V(n) asm volatile("s_waitcnt vmcnt(" #n ")" ::: "memory")
; #define PG8_WAIT_L(n) asm volatile("s_waitcnt lgkmcnt(" #n ")" ::: "memory")
; #define PG8_BAR __builtin_amdgcn_s_barrier()
; template <class Epi, class Map>
; __device__ __forceinline__ void gemm_phase(LAS unsigned char* lds, const Gemm g, const Sched<Map>& S, const Epi& E) {
;     ...
;             PG8_WAIT_V(8); PG8_WAIT_L(0); PG8_BAR; PG8_MMA(1, 0, At, B0); PG8_MMA(1, 1, At, B1); PG8_BAR; PG8_SCHED;
;         }
;         if (wr == 0) PG8_BAR;
;         E(acc, cur, wr, wc, fr, fq);
;         if (!has_next) break;
;     __device__ __forceinline__ void operator()(const Acc& acc, const Unit& u, int wr, int wc, int fr, int fq) const {
;         asm volatile("" : "+v"(fr), "+v"(fq));
;         bf16_t* base = O + u.coff + (size_t)(wr * 64 + fr) * ldc + wc * 32 + 8 * fq;
; #pragma unroll
;         for (int ai = 0; ai < 2; ++ai)
; #pragma unroll
;             for (int m = 0; m < 4; ++m) { bf16_t* rowp = base + (size_t)(ai * HALF + m * 16) * ldc;
; #pragma unroll
;                 for (int bj = 0; bj < 2; ++bj) { f32x4 v0 = acc[ai][bj][m][0], v1 = acc[ai][bj][m][1];
;                     if (ACT == 1) {
; #pragma unroll
;                         for (int j = 0; j < 4; ++j) { v0[j] = silu_f(v0[j]); v1[j] = silu_f(v1[j]); } }
;                     if (ACT == 2) {
; #pragma unroll
;                         for (int j = 0; j < 4; ++j) { const float a = fmaxf(v0[j], 0.f), b = fmaxf(v1[j], 0.f); v0[j] = a * a; v1[j] = b * b; } }
;                     u32x4 w; w.x = cvt_pk_bf16(v0[0], v0[1]); w.y = cvt_pk_bf16(v0[2], v0[3]); w.z = cvt_pk_bf16(v1[0], v1[1]); w.w = cvt_pk_bf16(v1[2], v1[3]);
;                     *(u32x4*)(rowp + bj * HALF) = w; } }
	s_waitcnt lgkmcnt(0)
	v_mfma_f32_16x16x32_bf16 v[60:63], v[158:161], v[200:203], v[60:63]
	v_mfma_f32_16x16x32_bf16 v[56:59], v[166:169], v[200:203], v[56:59]
	v_mfma_f32_16x16x32_bf16 v[52:55], v[158:161], v[208:211], v[52:55]
	v_mfma_f32_16x16x32_bf16 v[44:47], v[166:169], v[208:211], v[44:47]
	v_mfma_f32_16x16x32_bf16 v[36:39], v[158:161], v[216:219], v[36:39]
	v_mfma_f32_16x16x32_bf16 v[28:31], v[166:169], v[216:219], v[28:31]
	v_mfma_f32_16x16x32_bf16 v[20:23], v[158:161], v[224:227], v[20:23]
	v_mfma_f32_16x16x32_bf16 v[12:15], v[166:169], v[224:227], v[12:15]
	v_mfma_f32_16x16x32_bf16 v[60:63], v[162:165], v[204:207], v[60:63]
	v_mfma_f32_16x16x32_bf16 v[56:59], v[170:173], v[204:207], v[56:59]
	v_mfma_f32_16x16x32_bf16 v[52:55], v[162:165], v[212:215], v[52:55]
	v_mfma_f32_16x16x32_bf16 v[44:47], v[170:173], v[212:215], v[44:47]
	v_mfma_f32_16x16x32_bf16 v[36:39], v[162:165], v[220:223], v[36:39]
	v_mfma_f32_16x16x32_bf16 v[28:31], v[170:173], v[220:223], v[28:31]
	v_mfma_f32_16x16x32_bf16 v[20:23], v[162:165], v[228:231], v[20:23]
	v_mfma_f32_16x16x32_bf16 v[12:15], v[170:173], v[228:231], v[12:15]
	v_mfma_f32_16x16x32_bf16 v[48:51], v[174:177], v[200:203], v[48:51]
	v_mfma_f32_16x16x32_bf16 v[40:43], v[192:195], v[200:203], v[40:43]
	v_mfma_f32_16x16x32_bf16 v[32:35], v[174:177], v[208:211], v[32:35]
	v_mfma_f32_16x16x32_bf16 v[24:27], v[192:195], v[208:211], v[24:27]
	v_mfma_f32_16x16x32_bf16 v[16:19], v[174:177], v[216:219], v[16:19]
	v_mfma_f32_16x16x32_bf16 v[8:11], v[192:195], v[216:219], v[8:11]
	v_mfma_f32_16x16x32_bf16 v[4:7], v[174:177], v[224:227], v[4:7]
	v_mfma_f32_16x16x32_bf16 v[0:3], v[192:195], v[224:227], v[0:3]
	v_mfma_f32_16x16x32_bf16 v[48:51], v[178:181], v[204:207], v[48:51]
	v_mfma_f32_16x16x32_bf16 v[40:43], v[196:199], v[204:207], v[40:43]
	v_mfma_f32_16x16x32_bf16 v[32:35], v[178:181], v[212:215], v[32:35]
	v_mfma_f32_16x16x32_bf16 v[24:27], v[196:199], v[212:215], v[24:27]
	v_mfma_f32_16x16x32_bf16 v[16:19], v[178:181], v[220:223], v[16:19]
	v_mfma_f32_16x16x32_bf16 v[8:11], v[196:199], v[220:223], v[8:11]
	v_mfma_f32_16x16x32_bf16 v[4:7], v[178:181], v[228:231], v[4:7]
	v_mfma_f32_16x16x32_bf16 v[0:3], v[196:199], v[228:231], v[0:3]
	s_barrier
	s_add_i32 s51, s51, 2
	s_add_u32 s34, s34, 0x100
	s_addc_u32 s35, s35, 0
	s_add_u32 s49, s49, 0x100
	s_addc_u32 s50, s50, 0
	s_cmp_gt_u32 s51, 29
	s_cbranch_scc0 .LBB0_261
	s_and_b64 vcc, exec, s[20:21]
	s_cbranch_vccz .LBB0_264
.LBB0_264:
	v_mov_b32_e32 v138, v140
	v_mov_b32_e32 v158, v141
	s_lshl_b64 s[34:35], s[60:61], 1
	v_add_u32_e32 v138, s14, v138
	s_add_u32 s34, s12, s34
	v_ashrrev_i32_e32 v139, 31, v138
	s_addc_u32 s35, s13, s35
	v_lshlrev_b64 v[138:139], 15, v[138:139]
	v_lshl_add_u64 v[138:139], s[34:35], 0, v[138:139]
	s_mov_b32 s25, s61
	v_lshlrev_b32_e32 v158, 3, v158
	v_lshl_add_u64 v[138:139], v[138:139], 0, s[24:25]
	v_ashrrev_i32_e32 v159, 31, v158
	v_lshl_add_u64 v[138:139], v[158:159], 1, v[138:139]
	s_mov_b32 s25, 0x80000
	v_cvt_pk_bf16_f32 v124, v124, v125
	v_cvt_pk_bf16_f32 v125, v126, v127
	v_cvt_pk_bf16_f32 v126, v120, v121
	v_cvt_pk_bf16_f32 v127, v122, v123
	global_store_dwordx4 v[138:139], v[124:127], off
	v_cvt_pk_bf16_f32 v112, v112, v113
	v_cvt_pk_bf16_f32 v113, v114, v115
	v_cvt_pk_bf16_f32 v114, v104, v105
	v_cvt_pk_bf16_f32 v115, v106, v107
	global_store_dwordx4 v[138:139], v[112:115], off offset:256
	v_cvt_pk_bf16_f32 v104, v116, v117
	v_cvt_pk_bf16_f32 v105, v118, v119
	v_cvt_pk_bf16_f32 v106, v108, v109
	v_add_co_u32_e32 v108, vcc, s25, v138
	v_cvt_pk_bf16_f32 v107, v110, v111
	s_mov_b32 s25, 0x180000
	s_nop 0
	v_addc_co_u32_e32 v109, vcc, 0, v139, vcc
	global_store_dwordx4 v[108:109], v[104:107], off
	v_cvt_pk_bf16_f32 v96, v96, v97
	v_cvt_pk_bf16_f32 v97, v98, v99
	v_cvt_pk_bf16_f32 v98, v88, v89
	v_cvt_pk_bf16_f32 v99, v90, v91
	global_store_dwordx4 v[108:109], v[96:99], off offset:256
	s_cmp_lg_u64 s[20:21], 0
	s_cbranch_scc0 .Llate_align_1
	s_barrier
.Llate_align_1:
	v_cvt_pk_bf16_f32 v88, v100, v101
	v_cvt_pk_bf16_f32 v89, v102, v103
	v_cvt_pk_bf16_f32 v90, v92, v93
	v_add_co_u32_e32 v92, vcc, s72, v138
	v_cvt_pk_bf16_f32 v91, v94, v95
	s_mov_b64 s[34:35], -1
	s_nop 0
	v_addc_co_u32_e32 v93, vcc, 0, v139, vcc
	global_store_dwordx4 v[92:93], v[88:91], off
	v_cvt_pk_bf16_f32 v80, v80, v81
	v_cvt_pk_bf16_f32 v81, v82, v83
	v_cvt_pk_bf16_f32 v82, v72, v73
	v_cvt_pk_bf16_f32 v83, v74, v75
	global_store_dwordx4 v[92:93], v[80:83], off offset:256
	v_cvt_pk_bf16_f32 v72, v84, v85
	v_cvt_pk_bf16_f32 v73, v86, v87
	v_cvt_pk_bf16_f32 v74, v76, v77
	v_add_co_u32_e32 v76, vcc, s25, v138
	s_mov_b32 s25, 0x400000
	s_nop 0
	v_addc_co_u32_e32 v77, vcc, 0, v139, vcc
	v_cvt_pk_bf16_f32 v75, v78, v79
	global_store_dwordx4 v[76:77], v[72:75], off
	v_cvt_pk_bf16_f32 v68, v68, v69
	v_cvt_pk_bf16_f32 v69, v70, v71
	v_cvt_pk_bf16_f32 v70, v64, v65
	v_cvt_pk_bf16_f32 v71, v66, v67
	global_store_dwordx4 v[76:77], v[68:71], off offset:256
	v_cvt_pk_bf16_f32 v60, v60, v61
	v_cvt_pk_bf16_f32 v61, v62, v63
	v_cvt_pk_bf16_f32 v62, v56, v57
	v_add_co_u32_e32 v56, vcc, s25, v138
	s_mov_b32 s25, 0x480000
	s_nop 0
	v_addc_co_u32_e32 v57, vcc, 0, v139, vcc
	v_cvt_pk_bf16_f32 v63, v58, v59
	global_store_dwordx4 v[56:57], v[60:63], off
	v_cvt_pk_bf16_f32 v48, v48, v49
	v_cvt_pk_bf16_f32 v49, v50, v51
	v_cvt_pk_bf16_f32 v50, v40, v41
	v_cvt_pk_bf16_f32 v51, v42, v43
	global_store_dwordx4 v[56:57], v[48:51], off offset:256
	v_cvt_pk_bf16_f32 v40, v52, v53
	v_cvt_pk_bf16_f32 v41, v54, v55
	v_cvt_pk_bf16_f32 v42, v44, v45
	v_add_co_u32_e32 v44, vcc, s25, v138
	s_mov_b32 s25, 0x500000
	s_nop 0
	v_addc_co_u32_e32 v45, vcc, 0, v139, vcc
	v_cvt_pk_bf16_f32 v43, v46, v47
	global_store_dwordx4 v[44:45], v[40:43], off
	v_cvt_pk_bf16_f32 v32, v32, v33
	v_cvt_pk_bf16_f32 v33, v34, v35
	v_cvt_pk_bf16_f32 v34, v24, v25
	v_cvt_pk_bf16_f32 v35, v26, v27
	global_store_dwordx4 v[44:45], v[32:35], off offset:256
	v_cvt_pk_bf16_f32 v24, v36, v37
	v_cvt_pk_bf16_f32 v25, v38, v39
	v_cvt_pk_bf16_f32 v26, v28, v29
	v_add_co_u32_e32 v28, vcc, s25, v138
	s_mov_b32 s25, 0x580000
	s_nop 0
	v_addc_co_u32_e32 v29, vcc, 0, v139, vcc
	v_cvt_pk_bf16_f32 v27, v30, v31
	global_store_dwordx4 v[28:29], v[24:27], off
	v_cvt_pk_bf16_f32 v16, v16, v17
	v_cvt_pk_bf16_f32 v17, v18, v19
	v_cvt_pk_bf16_f32 v18, v8, v9
	v_cvt_pk_bf16_f32 v19, v10, v11
	global_store_dwordx4 v[28:29], v[16:19], off offset:256
	v_cvt_pk_bf16_f32 v8, v20, v21
	v_cvt_pk_bf16_f32 v9, v22, v23
	v_cvt_pk_bf16_f32 v10, v12, v13
	v_add_co_u32_e32 v12, vcc, s25, v138
	v_cvt_pk_bf16_f32 v11, v14, v15
	s_nop 1
	v_addc_co_u32_e32 v13, vcc, 0, v139, vcc
	s_andn2_b64 vcc, exec, s[40:41]
	global_store_dwordx4 v[12:13], v[8:11], off
	v_cvt_pk_bf16_f32 v4, v4, v5
	v_cvt_pk_bf16_f32 v5, v6, v7
	v_cvt_pk_bf16_f32 v6, v0, v1
	v_cvt_pk_bf16_f32 v7, v2, v3
	global_store_dwordx4 v[12:13], v[4:7], off offset:256
	s_cbranch_vccnz .LBB0_253
	s_andn2_b64 vcc, exec, s[18:19]
	s_cbranch_vccnz .LBB0_252
	s_barrier
	s_branch .LBB0_252

; #define PG8_STAGE(bufoff, gbase, voff) do { _Pragma("unroll") for (int _i = 0; _i < 2; ++_i) \
;         __builtin_amdgcn_global_load_lds((const unsigned*)((const char*)(gbase) + (voff)[_i]), (LAS unsigned*)(lds + (bufoff) + ldsw + _i * 8192), 16, 0, 0); } while (0)
; #define PG8_LDA(dst, b, h) do { _Pragma("unroll") for (int m = 0; m < 4; ++m) _Pragma("unroll") for (int k = 0; k < 2; ++k) dst[m][k] = *(const LAS bf16x8*)(lds + PG8_SA(b, h) + aoff + m * 2048 + k * 1024); } while (0)
; #define PG8_LDB(dst, b, h) do { _Pragma("unroll") for (int n = 0; n < 2; ++n) _Pragma("unroll") for (int k = 0; k < 2; ++k) dst[n][k] = *(const LAS bf16x8*)(lds + PG8_SB(b, h) + boff + n * 2048 + k * 1024); } while (0)
; #define PG8_MMA(ai, bj, At, Bt) do { __builtin_amdgcn_s_setprio(1); _Pragma("unroll") for (int m = 0; m < 4; ++m) _Pragma("unroll") for (int n = 0; n < 2; ++n) _Pragma("unroll") for (int k = 0; k < 2; ++k) \
;         acc[ai][bj][m][n] = __builtin_amdgcn_mfma_f32_16x16x32_bf16(Bt[n][k], At[m][k], acc[ai][bj][m][n], 0, 0, 0); __builtin_amdgcn_s_setprio(0); } while (0)
; #define PG8_WAIT_V(n) asm volatile("s_waitcnt vmcnt(" #n ")" ::: "memory")
; #define PG8_WAIT_L(n) asm volatile("s_waitcnt lgkmcnt(" #n ")" ::: "memory")
; #define PG8_BAR __builtin_amdgcn_s_barrier()
; #define PG8_SCHED __builtin_amdgcn_sched_barrier(0)
; template <class Epi, class Map>
; __device__ __forceinline__ void gemm_phase(LAS unsigned char* lds, const Gemm g, const Sched<Map>& S, const Epi& E) {
;     ...
;         const bool has_next = S.next(ui + 1, nxt);
;         const char* nA = has_next ? (const char*)g.A + nxt.aoff : cA; const char* nB = has_next ? (const char*)g.Bt + nxt.boff : cB;
; #pragma unroll 1
;         for (int t = 0; t < nt; t += 2) {
;             const bool last = (t == nt - 2);
;             const char* a1 = cA + (size_t)(t + 1) * kstep;
;             const char* a2 = last ? nA : cA + (size_t)(t + 2) * kstep; const char* b2 = last ? nB : cB + (size_t)(t + 2) * kstep;
;             const char* a3 = a2 + kstep; const char* b3 = b2 + kstep;
;             PG8_LDB(B0, 0, 0); PG8_LDB(B1, 0, 1); PG8_SCHED; PG8_LDA(At, 0, 0); PG8_STAGE(PG8_SA(1, 1), a1 + hstepA, voffA);
;             PG8_WAIT_V(8); PG8_WAIT_L(0); PG8_BAR; PG8_MMA(0, 0, At, B0); PG8_MMA(0, 1, At, B1); PG8_BAR; PG8_SCHED;
.LBB0_404:
	v_readlane_b32 s20, v245, 21
	v_readlane_b32 s21, v245, 22
	s_add_u32 s20, s20, s33
	s_addc_u32 s21, s21, 0
	s_and_b64 s[24:25], s[38:39], exec
	v_readlane_b32 s5, v247, 56
	s_cselect_b32 s40, s21, s29
	s_cselect_b32 s41, s20, s28
	s_add_u32 s24, s5, s15
	v_readlane_b32 s5, v247, 57
	s_addc_u32 s25, s5, 0
	s_and_b64 s[34:35], s[38:39], exec
	s_cselect_b32 s42, s25, s31
	s_cselect_b32 s43, s24, s30
	s_add_u32 s28, s28, 0x80080
	s_addc_u32 s29, s29, 0
	s_add_u32 s44, s30, 0x100
	v_mov_b32_e32 v0, 0
	s_addc_u32 s45, s31, 0
	s_mov_b32 s46, -2
	v_mov_b32_e32 v1, v0
	v_mov_b32_e32 v2, v0
	v_mov_b32_e32 v3, v0
	v_mov_b32_e32 v4, v0
	v_mov_b32_e32 v5, v0
	v_mov_b32_e32 v6, v0
	v_mov_b32_e32 v7, v0
	v_mov_b32_e32 v12, v0
	v_mov_b32_e32 v13, v0
	v_mov_b32_e32 v14, v0
	v_mov_b32_e32 v15, v0
	v_mov_b32_e32 v16, v0
	v_mov_b32_e32 v17, v0
	v_mov_b32_e32 v18, v0
	v_mov_b32_e32 v19, v0
	v_mov_b32_e32 v32, v0
	v_mov_b32_e32 v33, v0
	v_mov_b32_e32 v34, v0
	v_mov_b32_e32 v35, v0
	v_mov_b32_e32 v36, v0
	v_mov_b32_e32 v37, v0
	v_mov_b32_e32 v38, v0
	v_mov_b32_e32 v39, v0
	v_mov_b32_e32 v40, v0
	v_mov_b32_e32 v41, v0
	v_mov_b32_e32 v42, v0
	v_mov_b32_e32 v43, v0
	v_mov_b32_e32 v44, v0
	v_mov_b32_e32 v45, v0
	v_mov_b32_e32 v46, v0
	v_mov_b32_e32 v47, v0
	v_mov_b32_e32 v8, v0
	v_mov_b32_e32 v9, v0
	v_mov_b32_e32 v10, v0
	v_mov_b32_e32 v11, v0
	v_mov_b32_e32 v20, v0
	v_mov_b32_e32 v21, v0
	v_mov_b32_e32 v22, v0
	v_mov_b32_e32 v23, v0
	v_mov_b32_e32 v24, v0
	v_mov_b32_e32 v25, v0
	v_mov_b32_e32 v26, v0
	v_mov_b32_e32 v27, v0
	v_mov_b32_e32 v28, v0
	v_mov_b32_e32 v29, v0
	v_mov_b32_e32 v30, v0
	v_mov_b32_e32 v31, v0
	v_mov_b32_e32 v48, v0
	v_mov_b32_e32 v49, v0
	v_mov_b32_e32 v50, v0
	v_mov_b32_e32 v51, v0
	v_mov_b32_e32 v52, v0
	v_mov_b32_e32 v53, v0
	v_mov_b32_e32 v54, v0
	v_mov_b32_e32 v55, v0
	v_mov_b32_e32 v56, v0
	v_mov_b32_e32 v57, v0
	v_mov_b32_e32 v58, v0
	v_mov_b32_e32 v59, v0
	v_mov_b32_e32 v60, v0
	v_mov_b32_e32 v61, v0
	v_mov_b32_e32 v62, v0
	v_mov_b32_e32 v63, v0
	v_mov_b32_e32 v76, v0
	v_mov_b32_e32 v77, v0
	v_mov_b32_e32 v78, v0
	v_mov_b32_e32 v79, v0
	v_mov_b32_e32 v80, v0
	v_mov_b32_e32 v81, v0
	v_mov_b32_e32 v82, v0
	v_mov_b32_e32 v83, v0
	v_mov_b32_e32 v84, v0
	v_mov_b32_e32 v85, v0
	v_mov_b32_e32 v86, v0
	v_mov_b32_e32 v87, v0
	v_mov_b32_e32 v88, v0
	v_mov_b32_e32 v89, v0
	v_mov_b32_e32 v90, v0
	v_mov_b32_e32 v91, v0
	v_mov_b32_e32 v112, v0
	v_mov_b32_e32 v113, v0
	v_mov_b32_e32 v114, v0
	v_mov_b32_e32 v115, v0
	v_mov_b32_e32 v116, v0
	v_mov_b32_e32 v117, v0
	v_mov_b32_e32 v118, v0
	v_mov_b32_e32 v119, v0
	v_mov_b32_e32 v120, v0
	v_mov_b32_e32 v121, v0
	v_mov_b32_e32 v122, v0
	v_mov_b32_e32 v123, v0
	v_mov_b32_e32 v124, v0
	v_mov_b32_e32 v125, v0
	v_mov_b32_e32 v126, v0
	v_mov_b32_e32 v127, v0
	v_mov_b32_e32 v92, v0
	v_mov_b32_e32 v93, v0
	v_mov_b32_e32 v94, v0
	v_mov_b32_e32 v95, v0
	v_mov_b32_e32 v96, v0
	v_mov_b32_e32 v97, v0
	v_mov_b32_e32 v98, v0
	v_mov_b32_e32 v99, v0
	v_mov_b32_e32 v100, v0
	v_mov_b32_e32 v101, v0
	v_mov_b32_e32 v102, v0
	v_mov_b32_e32 v103, v0
	v_mov_b32_e32 v104, v0
	v_mov_b32_e32 v105, v0
	v_mov_b32_e32 v106, v0
	v_mov_b32_e32 v107, v0
	v_mov_b32_e32 v128, v0
	v_mov_b32_e32 v129, v0
	v_mov_b32_e32 v130, v0
	v_mov_b32_e32 v131, v0
	v_mov_b32_e32 v132, v0
	v_mov_b32_e32 v133, v0
	v_mov_b32_e32 v134, v0
	v_mov_b32_e32 v135, v0
	v_mov_b32_e32 v136, v0
	v_mov_b32_e32 v137, v0
	v_mov_b32_e32 v138, v0
	v_mov_b32_e32 v139, v0
	v_mov_b32_e32 v140, v0
	v_mov_b32_e32 v141, v0
	v_mov_b32_e32 v142, v0
	v_mov_b32_e32 v143, v0
.LBB0_405:
	s_add_u32 s30, s28, 0xfff80080
	s_addc_u32 s31, s29, -1
	s_add_i32 s47, 0, 0x10000
	s_cmp_eq_u32 s46, 28
	s_cselect_b32 s35, s40, s31
	s_cselect_b32 s34, s41, s30
	s_cselect_b32 s31, s42, s45
	s_cselect_b32 s30, s43, s44
	s_add_i32 s50, 0, 0x14000
	v_add_u32_e32 v108, s47, v173
	v_add_u32_e32 v170, s50, v173
	ds_read_b128 v[64:67], v108
	ds_read_b128 v[68:71], v108 offset:1024
	ds_read_b128 v[72:75], v108 offset:2048
	ds_read_b128 v[108:111], v108 offset:3072
	ds_read_b128 v[166:169], v170
	ds_read_b128 v[176:179], v170 offset:1024
	ds_read_b128 v[192:195], v170 offset:2048
	ds_read_b128 v[196:199], v170 offset:3072
	v_lshl_add_u64 v[170:171], s[28:29], 0, v[162:163]
	s_add_i32 m0, s1, 0xc000
	ds_read_b128 v[200:203], v174
	ds_read_b128 v[204:207], v174 offset:1024
	ds_read_b128 v[208:211], v174 offset:2048
	ds_read_b128 v[212:215], v174 offset:3072
	ds_read_b128 v[216:219], v174 offset:4096
	ds_read_b128 v[220:223], v174 offset:5120
	ds_read_b128 v[224:227], v174 offset:6144
	ds_read_b128 v[228:231], v174 offset:7168
	global_load_lds_dwordx4 v[170:171], off
	v_lshl_add_u64 v[170:171], s[28:29], 0, v[164:165]
	s_add_i32 m0, s1, 0xe000
	s_nop 0
	global_load_lds_dwordx4 v[170:171], off
	s_waitcnt vmcnt(8)
	s_waitcnt lgkmcnt(0)
	s_barrier
; #define PG8_STAGE(bufoff, gbase, voff) do { _Pragma("unroll") for (int _i = 0; _i < 2; ++_i) \
;         __builtin_amdgcn_global_load_lds((const unsigned*)((const char*)(gbase) + (voff)[_i]), (LAS unsigned*)(lds + (bufoff) + ldsw + _i * 8192), 16, 0, 0); } while (0)
; #define PG8_LDA(dst, b, h) do { _Pragma("unroll") for (int m = 0; m < 4; ++m) _Pragma("unroll") for (int k = 0; k < 2; ++k) dst[m][k] = *(const LAS bf16x8*)(lds + PG8_SA(b, h) + aoff + m * 2048 + k * 1024); } while (0)
; #define PG8_LDB(dst, b, h) do { _Pragma("unroll") for (int n = 0; n < 2; ++n) _Pragma("unroll") for (int k = 0; k < 2; ++k) dst[n][k] = *(const LAS bf16x8*)(lds + PG8_SB(b, h) + boff + n * 2048 + k * 1024); } while (0)
; #define PG8_MMA(ai, bj, At, Bt) do { __builtin_amdgcn_s_setprio(1); _Pragma("unroll") for (int m = 0; m < 4; ++m) _Pragma("unroll") for (int n = 0; n < 2; ++n) _Pragma("unroll") for (int k = 0; k < 2; ++k) \
;         acc[ai][bj][m][n] = __builtin_amdgcn_mfma_f32_16x16x32_bf16(Bt[n][k], At[m][k], acc[ai][bj][m][n], 0, 0, 0); __builtin_amdgcn_s_setprio(0); } while (0)
; #define PG8_WAIT_V(n) asm volatile("s_waitcnt vmcnt(" #n ")" ::: "memory")
; #define PG8_WAIT_L(n) asm volatile("s_waitcnt lgkmcnt(" #n ")" ::: "memory")
; #define PG8_BAR __builtin_amdgcn_s_barrier()
; #define PG8_SCHED __builtin_amdgcn_sched_barrier(0)
; template <class Epi, class Map>
; __device__ __forceinline__ void gemm_phase(LAS unsigned char* lds, const Gemm g, const Sched<Map>& S, const Epi& E) {
;     ...
;             PG8_WAIT_V(8); PG8_WAIT_L(0); PG8_BAR; PG8_MMA(0, 0, At, B0); PG8_MMA(0, 1, At, B1); PG8_BAR; PG8_SCHED;
;             PG8_LDA(At, 0, 1); PG8_STAGE(PG8_SB(0, 0), b2, voffB); PG8_STAGE(PG8_SB(0, 1), b2 + hstepB, voffB); PG8_STAGE(PG8_SA(0, 0), a2, voffA);
;             PG8_WAIT_V(8); PG8_WAIT_L(0); PG8_BAR; PG8_MMA(1, 0, At, B0); PG8_MMA(1, 1, At, B1); PG8_BAR; PG8_SCHED;
;             PG8_LDB(B0, 1, 0); PG8_LDB(B1, 1, 1); PG8_SCHED; PG8_LDA(At, 1, 0); PG8_STAGE(PG8_SA(0, 1), a2 + hstepA, voffA);
;             PG8_WAIT_V(8); PG8_WAIT_L(0); PG8_BAR; PG8_MMA(0, 0, At, B0); PG8_MMA(0, 1, At, B1); PG8_BAR; PG8_SCHED;
	s_waitcnt lgkmcnt(0)
	v_mfma_f32_16x16x32_bf16 v[140:143], v[64:67], v[200:203], v[140:143]
	v_mfma_f32_16x16x32_bf16 v[136:139], v[72:75], v[200:203], v[136:139]
	v_mfma_f32_16x16x32_bf16 v[132:135], v[64:67], v[208:211], v[132:135]
	v_mfma_f32_16x16x32_bf16 v[128:131], v[72:75], v[208:211], v[128:131]
	v_mfma_f32_16x16x32_bf16 v[104:107], v[64:67], v[216:219], v[104:107]
	v_mfma_f32_16x16x32_bf16 v[100:103], v[72:75], v[216:219], v[100:103]
	v_mfma_f32_16x16x32_bf16 v[96:99], v[64:67], v[224:227], v[96:99]
	v_mfma_f32_16x16x32_bf16 v[92:95], v[72:75], v[224:227], v[92:95]
	v_mfma_f32_16x16x32_bf16 v[140:143], v[68:71], v[204:207], v[140:143]
	v_mfma_f32_16x16x32_bf16 v[136:139], v[108:111], v[204:207], v[136:139]
	v_mfma_f32_16x16x32_bf16 v[132:135], v[68:71], v[212:215], v[132:135]
	v_mfma_f32_16x16x32_bf16 v[128:131], v[108:111], v[212:215], v[128:131]
	v_mfma_f32_16x16x32_bf16 v[104:107], v[68:71], v[220:223], v[104:107]
	v_mfma_f32_16x16x32_bf16 v[100:103], v[108:111], v[220:223], v[100:103]
	v_mfma_f32_16x16x32_bf16 v[96:99], v[68:71], v[228:231], v[96:99]
	v_mfma_f32_16x16x32_bf16 v[92:95], v[108:111], v[228:231], v[92:95]
	v_mfma_f32_16x16x32_bf16 v[124:127], v[166:169], v[200:203], v[124:127]
	v_mfma_f32_16x16x32_bf16 v[120:123], v[192:195], v[200:203], v[120:123]
	v_mfma_f32_16x16x32_bf16 v[116:119], v[166:169], v[208:211], v[116:119]
	v_mfma_f32_16x16x32_bf16 v[112:115], v[192:195], v[208:211], v[112:115]
	v_mfma_f32_16x16x32_bf16 v[88:91], v[166:169], v[216:219], v[88:91]
	v_mfma_f32_16x16x32_bf16 v[84:87], v[192:195], v[216:219], v[84:87]
	v_mfma_f32_16x16x32_bf16 v[80:83], v[166:169], v[224:227], v[80:83]
	v_mfma_f32_16x16x32_bf16 v[76:79], v[192:195], v[224:227], v[76:79]
	v_mfma_f32_16x16x32_bf16 v[124:127], v[176:179], v[204:207], v[124:127]
	v_mfma_f32_16x16x32_bf16 v[120:123], v[196:199], v[204:207], v[120:123]
	v_mfma_f32_16x16x32_bf16 v[116:119], v[176:179], v[212:215], v[116:119]
	v_mfma_f32_16x16x32_bf16 v[112:115], v[196:199], v[212:215], v[112:115]
	v_mfma_f32_16x16x32_bf16 v[88:91], v[176:179], v[220:223], v[88:91]
	v_mfma_f32_16x16x32_bf16 v[84:87], v[196:199], v[220:223], v[84:87]
	v_mfma_f32_16x16x32_bf16 v[80:83], v[176:179], v[228:231], v[80:83]
	v_mfma_f32_16x16x32_bf16 v[76:79], v[196:199], v[228:231], v[76:79]
	s_barrier
	s_add_i32 s47, s47, s0
	v_lshl_add_u64 v[170:171], s[30:31], 0, v[144:145]
	s_mov_b32 m0, s47
	ds_read_b128 v[200:203], v174 offset:16384
	ds_read_b128 v[204:207], v174 offset:17408
	ds_read_b128 v[208:211], v174 offset:18432
	ds_read_b128 v[212:215], v174 offset:19456
	ds_read_b128 v[216:219], v174 offset:20480
	ds_read_b128 v[220:223], v174 offset:21504
	ds_read_b128 v[224:227], v174 offset:22528
	ds_read_b128 v[228:231], v174 offset:23552
	global_load_lds_dwordx4 v[170:171], off
	s_add_i32 m0, s47, 0x2000
	s_add_u32 s48, s30, 0x80000
	v_lshl_add_u64 v[180:181], s[30:31], 0, v[160:161]
	s_addc_u32 s49, s31, 0
	s_add_i32 s47, s50, s0
	global_load_lds_dwordx4 v[180:181], off
	v_lshl_add_u64 v[232:233], s[48:49], 0, v[144:145]
	s_mov_b32 m0, s47
	v_lshl_add_u64 v[234:235], s[34:35], 0, v[160:161]
	global_load_lds_dwordx4 v[232:233], off
	v_lshl_add_u64 v[232:233], s[48:49], 0, v[160:161]
	s_add_i32 m0, s47, 0x2000
	s_nop 0
	global_load_lds_dwordx4 v[232:233], off
	v_lshl_add_u64 v[232:233], s[34:35], 0, v[144:145]
	s_mov_b32 m0, s1
	s_nop 0
	global_load_lds_dwordx4 v[232:233], off
	s_mov_b32 m0, s2
	s_nop 0
	global_load_lds_dwordx4 v[234:235], off
	s_waitcnt vmcnt(8)
	s_waitcnt lgkmcnt(0)
	s_barrier
	s_waitcnt lgkmcnt(0)
	v_mfma_f32_16x16x32_bf16 v[60:63], v[64:67], v[200:203], v[60:63]
	v_mfma_f32_16x16x32_bf16 v[56:59], v[72:75], v[200:203], v[56:59]
	v_mfma_f32_16x16x32_bf16 v[52:55], v[64:67], v[208:211], v[52:55]
	v_mfma_f32_16x16x32_bf16 v[48:51], v[72:75], v[208:211], v[48:51]
	v_mfma_f32_16x16x32_bf16 v[28:31], v[64:67], v[216:219], v[28:31]
	v_mfma_f32_16x16x32_bf16 v[24:27], v[72:75], v[216:219], v[24:27]
	v_mfma_f32_16x16x32_bf16 v[20:23], v[64:67], v[224:227], v[20:23]
	v_mfma_f32_16x16x32_bf16 v[8:11], v[72:75], v[224:227], v[8:11]
	v_mfma_f32_16x16x32_bf16 v[60:63], v[68:71], v[204:207], v[60:63]
	v_mfma_f32_16x16x32_bf16 v[56:59], v[108:111], v[204:207], v[56:59]
	v_mfma_f32_16x16x32_bf16 v[52:55], v[68:71], v[212:215], v[52:55]
	v_mfma_f32_16x16x32_bf16 v[48:51], v[108:111], v[212:215], v[48:51]
	v_mfma_f32_16x16x32_bf16 v[28:31], v[68:71], v[220:223], v[28:31]
	v_mfma_f32_16x16x32_bf16 v[24:27], v[108:111], v[220:223], v[24:27]
	v_mfma_f32_16x16x32_bf16 v[20:23], v[68:71], v[228:231], v[20:23]
	v_mfma_f32_16x16x32_bf16 v[8:11], v[108:111], v[228:231], v[8:11]
	v_mfma_f32_16x16x32_bf16 v[44:47], v[166:169], v[200:203], v[44:47]
	v_mfma_f32_16x16x32_bf16 v[40:43], v[192:195], v[200:203], v[40:43]
	v_mfma_f32_16x16x32_bf16 v[36:39], v[166:169], v[208:211], v[36:39]
	v_mfma_f32_16x16x32_bf16 v[32:35], v[192:195], v[208:211], v[32:35]
	v_mfma_f32_16x16x32_bf16 v[16:19], v[166:169], v[216:219], v[16:19]
	v_mfma_f32_16x16x32_bf16 v[12:15], v[192:195], v[216:219], v[12:15]
	v_mfma_f32_16x16x32_bf16 v[4:7], v[166:169], v[224:227], v[4:7]
	v_mfma_f32_16x16x32_bf16 v[0:3], v[192:195], v[224:227], v[0:3]
	v_mfma_f32_16x16x32_bf16 v[44:47], v[176:179], v[204:207], v[44:47]
	v_mfma_f32_16x16x32_bf16 v[40:43], v[196:199], v[204:207], v[40:43]
	v_mfma_f32_16x16x32_bf16 v[36:39], v[176:179], v[212:215], v[36:39]
	v_mfma_f32_16x16x32_bf16 v[32:35], v[196:199], v[212:215], v[32:35]
	v_mfma_f32_16x16x32_bf16 v[16:19], v[176:179], v[220:223], v[16:19]
	v_mfma_f32_16x16x32_bf16 v[12:15], v[196:199], v[220:223], v[12:15]
	v_mfma_f32_16x16x32_bf16 v[4:7], v[176:179], v[228:231], v[4:7]
	v_mfma_f32_16x16x32_bf16 v[0:3], v[196:199], v[228:231], v[0:3]
	s_barrier
; #define PG8_STAGE(bufoff, gbase, voff) do { _Pragma("unroll") for (int _i = 0; _i < 2; ++_i) \
;         __builtin_amdgcn_global_load_lds((const unsigned*)((const char*)(gbase) + (voff)[_i]), (LAS unsigned*)(lds + (bufoff) + ldsw + _i * 8192), 16, 0, 0); } while (0)
; #define PG8_LDA(dst, b, h) do { _Pragma("unroll") for (int m = 0; m < 4; ++m) _Pragma("unroll") for (int k = 0; k < 2; ++k) dst[m][k] = *(const LAS bf16x8*)(lds + PG8_SA(b, h) + aoff + m * 2048 + k * 1024); } while (0)
; #define PG8_LDB(dst, b, h) do { _Pragma("unroll") for (int n = 0; n < 2; ++n) _Pragma("unroll") for (int k = 0; k < 2; ++k) dst[n][k] = *(const LAS bf16x8*)(lds + PG8_SB(b, h) + boff + n * 2048 + k * 1024); } while (0)
; #define PG8_MMA(ai, bj, At, Bt) do { __builtin_amdgcn_s_setprio(1); _Pragma("unroll") for (int m = 0; m < 4; ++m) _Pragma("unroll") for (int n = 0; n < 2; ++n) _Pragma("unroll") for (int k = 0; k < 2; ++k) \
;         acc[ai][bj][m][n] = __builtin_amdgcn_mfma_f32_16x16x32_bf16(Bt[n][k], At[m][k], acc[ai][bj][m][n], 0, 0, 0); __builtin_amdgcn_s_setprio(0); } while (0)
; #define PG8_WAIT_V(n) asm volatile("s_waitcnt vmcnt(" #n ")" ::: "memory")
; #define PG8_WAIT_L(n) asm volatile("s_waitcnt lgkmcnt(" #n ")" ::: "memory")
; #define PG8_BAR __builtin_amdgcn_s_barrier()
; #define PG8_SCHED __builtin_amdgcn_sched_barrier(0)
; template <class Epi, class Map>
; __device__ __forceinline__ void gemm_phase(LAS unsigned char* lds, const Gemm g, const Sched<Map>& S, const Epi& E) {
;     ...
;             PG8_LDB(B0, 1, 0); PG8_LDB(B1, 1, 1); PG8_SCHED; PG8_LDA(At, 1, 0); PG8_STAGE(PG8_SA(0, 1), a2 + hstepA, voffA);
;             PG8_WAIT_V(8); PG8_WAIT_L(0); PG8_BAR; PG8_MMA(0, 0, At, B0); PG8_MMA(0, 1, At, B1); PG8_BAR; PG8_SCHED;
;             PG8_LDA(At, 1, 1); PG8_STAGE(PG8_SB(1, 0), b3, voffB); PG8_STAGE(PG8_SB(1, 1), b3 + hstepB, voffB); PG8_STAGE(PG8_SA(1, 0), a3, voffA);
;             PG8_WAIT_V(8); PG8_WAIT_L(0); PG8_BAR; PG8_MMA(1, 0, At, B0); PG8_MMA(1, 1, At, B1); PG8_BAR; PG8_SCHED;
	s_add_i32 s47, 0, 0x18000
	s_add_i32 s48, 0, 0x1c000
	v_add_u32_e32 v108, s47, v173
	v_add_u32_e32 v175, s48, v173
	ds_read_b128 v[64:67], v108
	ds_read_b128 v[68:71], v108 offset:1024
	ds_read_b128 v[72:75], v108 offset:2048
	ds_read_b128 v[108:111], v108 offset:3072
	ds_read_b128 v[166:169], v175
	ds_read_b128 v[176:179], v175 offset:1024
	ds_read_b128 v[192:195], v175 offset:2048
	ds_read_b128 v[196:199], v175 offset:3072
	s_add_u32 s34, s34, 0x80000
	s_addc_u32 s35, s35, 0
	s_mov_b32 m0, s3
	v_lshl_add_u64 v[236:237], s[34:35], 0, v[144:145]
	ds_read_b128 v[200:203], v174 offset:32768
	ds_read_b128 v[204:207], v174 offset:33792
	ds_read_b128 v[208:211], v174 offset:34816
	ds_read_b128 v[212:215], v174 offset:35840
	ds_read_b128 v[216:219], v174 offset:36864
	ds_read_b128 v[220:223], v174 offset:37888
	ds_read_b128 v[224:227], v174 offset:38912
	ds_read_b128 v[228:231], v174 offset:39936
	global_load_lds_dwordx4 v[236:237], off
	v_lshl_add_u64 v[236:237], s[34:35], 0, v[160:161]
	s_mov_b32 m0, s4
	s_nop 0
	global_load_lds_dwordx4 v[236:237], off
	s_waitcnt vmcnt(8)
	s_waitcnt lgkmcnt(0)
	s_barrier
	s_waitcnt lgkmcnt(0)
	v_mfma_f32_16x16x32_bf16 v[140:143], v[64:67], v[200:203], v[140:143]
	v_mfma_f32_16x16x32_bf16 v[136:139], v[72:75], v[200:203], v[136:139]
	v_mfma_f32_16x16x32_bf16 v[132:135], v[64:67], v[208:211], v[132:135]
	v_mfma_f32_16x16x32_bf16 v[128:131], v[72:75], v[208:211], v[128:131]
	v_mfma_f32_16x16x32_bf16 v[104:107], v[64:67], v[216:219], v[104:107]
	v_mfma_f32_16x16x32_bf16 v[100:103], v[72:75], v[216:219], v[100:103]
	v_mfma_f32_16x16x32_bf16 v[96:99], v[64:67], v[224:227], v[96:99]
	v_mfma_f32_16x16x32_bf16 v[92:95], v[72:75], v[224:227], v[92:95]
	v_mfma_f32_16x16x32_bf16 v[140:143], v[68:71], v[204:207], v[140:143]
	v_mfma_f32_16x16x32_bf16 v[136:139], v[108:111], v[204:207], v[136:139]
	v_mfma_f32_16x16x32_bf16 v[132:135], v[68:71], v[212:215], v[132:135]
	v_mfma_f32_16x16x32_bf16 v[128:131], v[108:111], v[212:215], v[128:131]
	v_mfma_f32_16x16x32_bf16 v[104:107], v[68:71], v[220:223], v[104:107]
	v_mfma_f32_16x16x32_bf16 v[100:103], v[108:111], v[220:223], v[100:103]
	v_mfma_f32_16x16x32_bf16 v[96:99], v[68:71], v[228:231], v[96:99]
	v_mfma_f32_16x16x32_bf16 v[92:95], v[108:111], v[228:231], v[92:95]
	v_mfma_f32_16x16x32_bf16 v[124:127], v[166:169], v[200:203], v[124:127]
	v_mfma_f32_16x16x32_bf16 v[120:123], v[192:195], v[200:203], v[120:123]
	v_mfma_f32_16x16x32_bf16 v[116:119], v[166:169], v[208:211], v[116:119]
	v_mfma_f32_16x16x32_bf16 v[112:115], v[192:195], v[208:211], v[112:115]
	v_mfma_f32_16x16x32_bf16 v[88:91], v[166:169], v[216:219], v[88:91]
	v_mfma_f32_16x16x32_bf16 v[84:87], v[192:195], v[216:219], v[84:87]
	v_mfma_f32_16x16x32_bf16 v[80:83], v[166:169], v[224:227], v[80:83]
	v_mfma_f32_16x16x32_bf16 v[76:79], v[192:195], v[224:227], v[76:79]
	v_mfma_f32_16x16x32_bf16 v[124:127], v[176:179], v[204:207], v[124:127]
	v_mfma_f32_16x16x32_bf16 v[120:123], v[196:199], v[204:207], v[120:123]
	v_mfma_f32_16x16x32_bf16 v[116:119], v[176:179], v[212:215], v[116:119]
	v_mfma_f32_16x16x32_bf16 v[112:115], v[196:199], v[212:215], v[112:115]
	v_mfma_f32_16x16x32_bf16 v[88:91], v[176:179], v[220:223], v[88:91]
	v_mfma_f32_16x16x32_bf16 v[84:87], v[196:199], v[220:223], v[84:87]
	v_mfma_f32_16x16x32_bf16 v[80:83], v[176:179], v[228:231], v[80:83]
	v_mfma_f32_16x16x32_bf16 v[76:79], v[196:199], v[228:231], v[76:79]
	s_barrier
	s_add_i32 s34, s47, s0
	v_lshl_add_u64 v[170:171], v[170:171], 0, s[82:83]
	s_mov_b32 m0, s34
	ds_read_b128 v[200:203], v174 offset:49152
	ds_read_b128 v[204:207], v174 offset:50176
	ds_read_b128 v[208:211], v174 offset:51200
	ds_read_b128 v[212:215], v174 offset:52224
	ds_read_b128 v[216:219], v174 offset:53248
	ds_read_b128 v[220:223], v174 offset:54272
	ds_read_b128 v[224:227], v174 offset:55296
	ds_read_b128 v[228:231], v174 offset:56320
	global_load_lds_dwordx4 v[170:171], off
	s_add_i32 m0, s34, 0x2000
	s_add_u32 s30, s30, 0x80080
	v_lshl_add_u64 v[170:171], v[180:181], 0, s[82:83]
	s_addc_u32 s31, s31, 0
	s_add_i32 s34, s48, s0
	global_load_lds_dwordx4 v[170:171], off
	v_lshl_add_u64 v[170:171], s[30:31], 0, v[144:145]
	s_mov_b32 m0, s34
	s_nop 0
	global_load_lds_dwordx4 v[170:171], off
	v_lshl_add_u64 v[170:171], s[30:31], 0, v[160:161]
	s_add_i32 m0, s34, 0x2000
	s_nop 0
	global_load_lds_dwordx4 v[170:171], off
	v_lshl_add_u64 v[170:171], v[232:233], 0, s[82:83]
	s_mov_b32 m0, s10
	s_nop 0
	global_load_lds_dwordx4 v[170:171], off
	v_lshl_add_u64 v[170:171], v[234:235], 0, s[82:83]
	s_mov_b32 m0, s11
	s_nop 0
	global_load_lds_dwordx4 v[170:171], off
	s_waitcnt vmcnt(8)
	s_waitcnt lgkmcnt(0)
	s_barrier
; #define PG8_MMA(ai, bj, At, Bt) do { __builtin_amdgcn_s_setprio(1); _Pragma("unroll") for (int m = 0; m < 4; ++m) _Pragma("unroll") for (int n = 0; n < 2; ++n) _Pragma("unroll") for (int k = 0; k < 2; ++k) \
;         acc[ai][bj][m][n] = __builtin_amdgcn_mfma_f32_16x16x32_bf16(Bt[n][k], At[m][k], acc[ai][bj][m][n], 0, 0, 0); __builtin_amdgcn_s_setprio(0); } while (0)
; #define PG8_WAIT_V(n) asm volatile("s_waitcnt vmcnt(" #n ")" ::: "memory")
; #define PG8_WAIT_L(n) asm volatile("s_waitcnt lgkmcnt(" #n ")" ::: "memory")
; #define PG8_BAR __builtin_amdgcn_s_barrier()
; #define PG8_SCHED __builtin_amdgcn_sched_barrier(0)
; template <class Epi, class Map>
; __device__ __forceinline__ void gemm_phase(LAS unsigned char* lds, const Gemm g, const Sched<Map>& S, const Epi& E) {
;     ...
;             PG8_WAIT_V(8); PG8_WAIT_L(0); PG8_BAR; PG8_MMA(1, 0, At, B0); PG8_MMA(1, 1, At, B1); PG8_BAR; PG8_SCHED;
;         }
;         if (wr == 0) PG8_BAR;
;     __device__ __forceinline__ void operator()(const Acc& acc, const Unit& u, int wr, int wc, int fr, int fq) const {
;         asm volatile("" : "+v"(fr), "+v"(fq));
;         const int row0 = u.pm * BM + wr * 64 + fr, col0 = u.pn * BM + wc * 32 + 4 * fq;
;         const float* gp = gate + (size_t)(u.pm >> 6) * gate_bstride + col0;
;         f32x4 gv[2][2];
; #pragma unroll
;         for (int bj = 0; bj < 2; ++bj)
; #pragma unroll
;             for (int n = 0; n < 2; ++n) gv[bj][n] = *(const f32x4*)(gp + bj * HALF + n * 16);
; #pragma unroll
;         for (int aim = 0; aim < 4; ++aim) { const int ai = aim >> 1, m0 = (aim & 1) * 2;
;             f32x4 bs[2][2][2];
; #pragma unroll
;             for (int mm = 0; mm < 2; ++mm) { const size_t off = (size_t)(row0 + ai * HALF + (m0 + mm) * 16) * D + col0;
; #pragma unroll
;                 for (int bj = 0; bj < 2; ++bj)
; #pragma unroll
;                     for (int n = 0; n < 2; ++n) bs[mm][bj][n] = *(const f32x4*)(base + off + bj * HALF + n * 16); }
; #pragma unroll
;             for (int mm = 0; mm < 2; ++mm) { const size_t off = (size_t)(row0 + ai * HALF + (m0 + mm) * 16) * D + col0;
; #pragma unroll
;                 for (int bj = 0; bj < 2; ++bj)
; #pragma unroll
;                     for (int n = 0; n < 2; ++n) *(f32x4*)(out + off + bj * HALF + n * 16) = bs[mm][bj][n] + gv[bj][n] * acc[ai][bj][m0 + mm][n]; }
;             asm volatile("" ::: "memory"); }
	s_waitcnt lgkmcnt(0)
	v_mfma_f32_16x16x32_bf16 v[60:63], v[64:67], v[200:203], v[60:63]
	v_mfma_f32_16x16x32_bf16 v[56:59], v[72:75], v[200:203], v[56:59]
	v_mfma_f32_16x16x32_bf16 v[52:55], v[64:67], v[208:211], v[52:55]
	v_mfma_f32_16x16x32_bf16 v[48:51], v[72:75], v[208:211], v[48:51]
	v_mfma_f32_16x16x32_bf16 v[28:31], v[64:67], v[216:219], v[28:31]
	v_mfma_f32_16x16x32_bf16 v[24:27], v[72:75], v[216:219], v[24:27]
	v_mfma_f32_16x16x32_bf16 v[20:23], v[64:67], v[224:227], v[20:23]
	v_mfma_f32_16x16x32_bf16 v[8:11], v[72:75], v[224:227], v[8:11]
	v_mfma_f32_16x16x32_bf16 v[60:63], v[68:71], v[204:207], v[60:63]
	v_mfma_f32_16x16x32_bf16 v[56:59], v[108:111], v[204:207], v[56:59]
	v_mfma_f32_16x16x32_bf16 v[52:55], v[68:71], v[212:215], v[52:55]
	v_mfma_f32_16x16x32_bf16 v[48:51], v[108:111], v[212:215], v[48:51]
	v_mfma_f32_16x16x32_bf16 v[28:31], v[68:71], v[220:223], v[28:31]
	v_mfma_f32_16x16x32_bf16 v[24:27], v[108:111], v[220:223], v[24:27]
	v_mfma_f32_16x16x32_bf16 v[20:23], v[68:71], v[228:231], v[20:23]
	v_mfma_f32_16x16x32_bf16 v[8:11], v[108:111], v[228:231], v[8:11]
	v_mfma_f32_16x16x32_bf16 v[44:47], v[166:169], v[200:203], v[44:47]
	v_mfma_f32_16x16x32_bf16 v[40:43], v[192:195], v[200:203], v[40:43]
	v_mfma_f32_16x16x32_bf16 v[36:39], v[166:169], v[208:211], v[36:39]
	v_mfma_f32_16x16x32_bf16 v[32:35], v[192:195], v[208:211], v[32:35]
	v_mfma_f32_16x16x32_bf16 v[16:19], v[166:169], v[216:219], v[16:19]
	v_mfma_f32_16x16x32_bf16 v[12:15], v[192:195], v[216:219], v[12:15]
	v_mfma_f32_16x16x32_bf16 v[4:7], v[166:169], v[224:227], v[4:7]
	v_mfma_f32_16x16x32_bf16 v[0:3], v[192:195], v[224:227], v[0:3]
	v_mfma_f32_16x16x32_bf16 v[44:47], v[176:179], v[204:207], v[44:47]
	v_mfma_f32_16x16x32_bf16 v[40:43], v[196:199], v[204:207], v[40:43]
	v_mfma_f32_16x16x32_bf16 v[36:39], v[176:179], v[212:215], v[36:39]
	v_mfma_f32_16x16x32_bf16 v[32:35], v[196:199], v[212:215], v[32:35]
	v_mfma_f32_16x16x32_bf16 v[16:19], v[176:179], v[220:223], v[16:19]
	v_mfma_f32_16x16x32_bf16 v[12:15], v[196:199], v[220:223], v[12:15]
	v_mfma_f32_16x16x32_bf16 v[4:7], v[176:179], v[228:231], v[4:7]
	v_mfma_f32_16x16x32_bf16 v[0:3], v[196:199], v[228:231], v[0:3]
	s_barrier
	s_add_i32 s46, s46, 2
	s_add_u32 s28, s28, 0x100
	s_addc_u32 s29, s29, 0
	s_add_u32 s44, s44, 0x100
	s_addc_u32 s45, s45, 0
	s_cmp_gt_u32 s46, 29
	s_cbranch_scc0 .LBB0_405
	s_and_b64 vcc, exec, s[18:19]
	s_cbranch_vccz .LBB0_408
.LBB0_408:
	v_mov_b32_e32 v64, v172
	v_mov_b32_e32 v168, v159
	s_lshl_b32 s28, s37, 8
	s_or_b32 s28, s28, s9
	v_lshl_add_u32 v64, v64, 2, s28
	s_ashr_i32 s28, s36, 6
	s_mul_hi_i32 s29, s28, 0xc000
	s_mul_i32 s28, s28, 0xc000
	s_add_u32 s28, s6, s28
	v_ashrrev_i32_e32 v65, 31, v64
	s_addc_u32 s29, s7, s29
	v_lshlrev_b64 v[166:167], 2, v[64:65]
	v_lshl_add_u64 v[64:65], s[28:29], 0, v[166:167]
	s_lshl_b32 s28, s36, 8
	s_add_i32 s28, s28, s8
	v_add_u32_e32 v170, s28, v168
	v_readlane_b32 s28, v245, 51
	v_readlane_b32 s29, v245, 52
	v_ashrrev_i32_e32 v171, 31, v170
	v_lshlrev_b64 v[170:171], 13, v[170:171]
	v_lshl_add_u64 v[168:169], s[28:29], 0, v[166:167]
	v_lshl_add_u64 v[180:181], v[168:169], 0, v[170:171]
	s_mov_b64 s[30:31], 0x20000
	global_load_dwordx4 v[108:111], v[64:65], off
	global_load_dwordx4 v[72:75], v[64:65], off offset:64
	global_load_dwordx4 v[68:71], v[64:65], off offset:512
	s_nop 0
	global_load_dwordx4 v[64:67], v[64:65], off offset:576
	s_nop 0
	global_load_dwordx4 v[176:179], v[180:181], off
	global_load_dwordx4 v[192:195], v[180:181], off offset:64
	global_load_dwordx4 v[196:199], v[180:181], off offset:512
	global_load_dwordx4 v[200:203], v[180:181], off offset:576
	v_lshl_add_u64 v[180:181], v[170:171], 0, s[30:31]
	v_lshl_add_u64 v[216:217], v[168:169], 0, v[180:181]
	global_load_dwordx4 v[204:207], v[216:217], off
	global_load_dwordx4 v[208:211], v[216:217], off offset:64
	global_load_dwordx4 v[212:215], v[216:217], off offset:512
	s_nop 0
	global_load_dwordx4 v[216:219], v[216:217], off offset:576
	s_mov_b64 s[30:31], 0x40000
	s_andn2_b64 vcc, exec, s[38:39]
	s_waitcnt vmcnt(0)
	v_pk_fma_f32 v[140:141], v[140:141], v[108:109], v[176:177]
	v_lshl_add_u64 v[176:177], s[28:29], 0, v[170:171]
	v_lshl_add_u64 v[176:177], v[176:177], 0, v[166:167]
	v_pk_fma_f32 v[126:127], v[126:127], v[70:71], v[198:199]
	v_pk_fma_f32 v[124:125], v[124:125], v[68:69], v[196:197]
	global_store_dwordx4 v[176:177], v[124:127], off offset:512
	v_pk_fma_f32 v[122:123], v[122:123], v[66:67], v[202:203]
	v_pk_fma_f32 v[120:121], v[120:121], v[64:65], v[200:201]
	v_lshl_add_u64 v[124:125], s[28:29], 0, v[180:181]
	global_store_dwordx4 v[176:177], v[120:123], off offset:576
	v_lshl_add_u64 v[124:125], v[124:125], 0, v[166:167]
	v_pk_fma_f32 v[142:143], v[142:143], v[110:111], v[178:179]
	v_pk_fma_f32 v[122:123], v[134:135], v[110:111], v[206:207]
	v_pk_fma_f32 v[120:121], v[132:133], v[108:109], v[204:205]
	v_pk_fma_f32 v[138:139], v[138:139], v[74:75], v[194:195]
	v_pk_fma_f32 v[136:137], v[136:137], v[72:73], v[192:193]
	global_store_dwordx4 v[124:125], v[120:123], off
	v_pk_fma_f32 v[118:119], v[118:119], v[70:71], v[214:215]
	v_pk_fma_f32 v[116:117], v[116:117], v[68:69], v[212:213]
	v_pk_fma_f32 v[122:123], v[130:131], v[74:75], v[210:211]
	v_pk_fma_f32 v[120:121], v[128:129], v[72:73], v[208:209]
	v_pk_fma_f32 v[114:115], v[114:115], v[66:67], v[218:219]
	v_pk_fma_f32 v[112:113], v[112:113], v[64:65], v[216:217]
	global_store_dwordx4 v[176:177], v[140:143], off
	s_cmp_lg_u64 s[18:19], 0
	s_cbranch_scc0 .Llate_align_2
	s_barrier
;     __device__ __forceinline__ void operator()(const Acc& acc, const Unit& u, int wr, int wc, int fr, int fq) const {
;     ...
;         for (int aim = 0; aim < 4; ++aim) { const int ai = aim >> 1, m0 = (aim & 1) * 2;
;             f32x4 bs[2][2][2];
; #pragma unroll
;             for (int mm = 0; mm < 2; ++mm) { const size_t off = (size_t)(row0 + ai * HALF + (m0 + mm) * 16) * D + col0;
; #pragma unroll
;                 for (int bj = 0; bj < 2; ++bj)
; #pragma unroll
;                     for (int n = 0; n < 2; ++n) bs[mm][bj][n] = *(const f32x4*)(base + off + bj * HALF + n * 16); }
; #pragma unroll
;             for (int mm = 0; mm < 2; ++mm) { const size_t off = (size_t)(row0 + ai * HALF + (m0 + mm) * 16) * D + col0;
; #pragma unroll
;                 for (int bj = 0; bj < 2; ++bj)
; #pragma unroll
;                     for (int n = 0; n < 2; ++n) *(f32x4*)(out + off + bj * HALF + n * 16) = bs[mm][bj][n] + gv[bj][n] * acc[ai][bj][m0 + mm][n]; }
;             asm volatile("" ::: "memory"); }
.Llate_align_2:
	global_store_dwordx4 v[176:177], v[136:139], off offset:64
	global_store_dwordx4 v[124:125], v[120:123], off offset:64
	global_store_dwordx4 v[124:125], v[116:119], off offset:512
	global_store_dwordx4 v[124:125], v[112:115], off offset:576
	v_lshl_add_u64 v[176:177], v[170:171], 0, s[30:31]
	v_lshl_add_u64 v[124:125], v[168:169], 0, v[176:177]
	s_mov_b64 s[30:31], 0x60000
	global_load_dwordx4 v[112:115], v[124:125], off
	global_load_dwordx4 v[116:119], v[124:125], off offset:64
	global_load_dwordx4 v[120:123], v[124:125], off offset:512
	s_nop 0
	global_load_dwordx4 v[124:127], v[124:125], off offset:576
	v_lshl_add_u64 v[178:179], v[170:171], 0, s[30:31]
	v_lshl_add_u64 v[140:141], v[168:169], 0, v[178:179]
	global_load_dwordx4 v[128:131], v[140:141], off
	global_load_dwordx4 v[132:135], v[140:141], off offset:64
	global_load_dwordx4 v[136:139], v[140:141], off offset:512
	s_nop 0
	global_load_dwordx4 v[140:143], v[140:141], off offset:576
	s_mov_b64 s[30:31], 0x100000
	s_waitcnt vmcnt(7)
	v_pk_fma_f32 v[104:105], v[104:105], v[108:109], v[112:113]
	v_lshl_add_u64 v[112:113], s[28:29], 0, v[176:177]
	v_lshl_add_u64 v[112:113], v[112:113], 0, v[166:167]
	s_waitcnt vmcnt(5)
	v_pk_fma_f32 v[90:91], v[90:91], v[70:71], v[122:123]
	v_pk_fma_f32 v[88:89], v[88:89], v[68:69], v[120:121]
	global_store_dwordx4 v[112:113], v[88:91], off offset:512
	s_waitcnt vmcnt(5)
	v_pk_fma_f32 v[86:87], v[86:87], v[66:67], v[126:127]
	v_pk_fma_f32 v[84:85], v[84:85], v[64:65], v[124:125]
	v_lshl_add_u64 v[88:89], s[28:29], 0, v[178:179]
	global_store_dwordx4 v[112:113], v[84:87], off offset:576
	v_lshl_add_u64 v[88:89], v[88:89], 0, v[166:167]
	v_pk_fma_f32 v[106:107], v[106:107], v[110:111], v[114:115]
	s_waitcnt vmcnt(5)
	v_pk_fma_f32 v[86:87], v[98:99], v[110:111], v[130:131]
	v_pk_fma_f32 v[84:85], v[96:97], v[108:109], v[128:129]
	v_pk_fma_f32 v[102:103], v[102:103], v[74:75], v[118:119]
	v_pk_fma_f32 v[100:101], v[100:101], v[72:73], v[116:117]
	global_store_dwordx4 v[88:89], v[84:87], off
	s_waitcnt vmcnt(4)
	v_pk_fma_f32 v[82:83], v[82:83], v[70:71], v[138:139]
	v_pk_fma_f32 v[80:81], v[80:81], v[68:69], v[136:137]
	v_pk_fma_f32 v[86:87], v[94:95], v[74:75], v[134:135]
	v_pk_fma_f32 v[84:85], v[92:93], v[72:73], v[132:133]
	s_waitcnt vmcnt(3)
	v_pk_fma_f32 v[78:79], v[78:79], v[66:67], v[142:143]
	v_pk_fma_f32 v[76:77], v[76:77], v[64:65], v[140:141]
	global_store_dwordx4 v[112:113], v[104:107], off
	global_store_dwordx4 v[112:113], v[100:103], off offset:64
	global_store_dwordx4 v[88:89], v[84:87], off offset:64
	global_store_dwordx4 v[88:89], v[80:83], off offset:512
	global_store_dwordx4 v[88:89], v[76:79], off offset:576
	v_lshl_add_u64 v[112:113], v[170:171], 0, s[30:31]
	v_lshl_add_u64 v[88:89], v[168:169], 0, v[112:113]
	s_mov_b64 s[30:31], 0x120000
	global_load_dwordx4 v[76:79], v[88:89], off
	global_load_dwordx4 v[80:83], v[88:89], off offset:64
	global_load_dwordx4 v[84:87], v[88:89], off offset:512
	s_nop 0
	global_load_dwordx4 v[88:91], v[88:89], off offset:576
	v_lshl_add_u64 v[114:115], v[170:171], 0, s[30:31]
	v_lshl_add_u64 v[104:105], v[168:169], 0, v[114:115]
	global_load_dwordx4 v[92:95], v[104:105], off
	global_load_dwordx4 v[96:99], v[104:105], off offset:64
	global_load_dwordx4 v[100:103], v[104:105], off offset:512
	s_nop 0
	global_load_dwordx4 v[104:107], v[104:105], off offset:576
	s_mov_b64 s[30:31], 0x140000
	s_waitcnt vmcnt(7)
	v_pk_fma_f32 v[60:61], v[60:61], v[108:109], v[76:77]
	v_lshl_add_u64 v[76:77], s[28:29], 0, v[112:113]
	v_lshl_add_u64 v[76:77], v[76:77], 0, v[166:167]
	s_waitcnt vmcnt(5)
	v_pk_fma_f32 v[46:47], v[46:47], v[70:71], v[86:87]
	v_pk_fma_f32 v[44:45], v[44:45], v[68:69], v[84:85]
	global_store_dwordx4 v[76:77], v[44:47], off offset:512
	s_waitcnt vmcnt(5)
; #define PG8_BAR __builtin_amdgcn_s_barrier()
; template <class Epi, class Map>
; __device__ __forceinline__ void gemm_phase(LAS unsigned char* lds, const Gemm g, const Sched<Map>& S, const Epi& E) {
;     ...
;         if (!has_next) break;
; #pragma unroll
;         for (int a = 0; a < 2; ++a)
; #pragma unroll
;             for (int b = 0; b < 2; ++b)
; #pragma unroll
;                 for (int m = 0; m < 4; ++m)
; #pragma unroll
;                     for (int n = 0; n < 2; ++n) acc[a][b][m][n] = (f32x4){0.f, 0.f, 0.f, 0.f};
;         cur = nxt; cA = nA; cB = nB; ++ui;
;         if (wr == 1) PG8_BAR;
;     __device__ __forceinline__ void operator()(const Acc& acc, const Unit& u, int wr, int wc, int fr, int fq) const {
;     ...
;         for (int aim = 0; aim < 4; ++aim) { const int ai = aim >> 1, m0 = (aim & 1) * 2;
;             f32x4 bs[2][2][2];
; #pragma unroll
;             for (int mm = 0; mm < 2; ++mm) { const size_t off = (size_t)(row0 + ai * HALF + (m0 + mm) * 16) * D + col0;
; #pragma unroll
;                 for (int bj = 0; bj < 2; ++bj)
; #pragma unroll
;                     for (int n = 0; n < 2; ++n) bs[mm][bj][n] = *(const f32x4*)(base + off + bj * HALF + n * 16); }
; #pragma unroll
;             for (int mm = 0; mm < 2; ++mm) { const size_t off = (size_t)(row0 + ai * HALF + (m0 + mm) * 16) * D + col0;
; #pragma unroll
;                 for (int bj = 0; bj < 2; ++bj)
; #pragma unroll
;                     for (int n = 0; n < 2; ++n) *(f32x4*)(out + off + bj * HALF + n * 16) = bs[mm][bj][n] + gv[bj][n] * acc[ai][bj][m0 + mm][n]; }
;             asm volatile("" ::: "memory"); }
	v_pk_fma_f32 v[42:43], v[42:43], v[66:67], v[90:91]
	v_pk_fma_f32 v[40:41], v[40:41], v[64:65], v[88:89]
	v_lshl_add_u64 v[44:45], s[28:29], 0, v[114:115]
	global_store_dwordx4 v[76:77], v[40:43], off offset:576
	v_lshl_add_u64 v[44:45], v[44:45], 0, v[166:167]
	v_pk_fma_f32 v[62:63], v[62:63], v[110:111], v[78:79]
	s_waitcnt vmcnt(5)
	v_pk_fma_f32 v[42:43], v[54:55], v[110:111], v[94:95]
	v_pk_fma_f32 v[40:41], v[52:53], v[108:109], v[92:93]
	v_pk_fma_f32 v[58:59], v[58:59], v[74:75], v[82:83]
	v_pk_fma_f32 v[56:57], v[56:57], v[72:73], v[80:81]
	global_store_dwordx4 v[44:45], v[40:43], off
	s_waitcnt vmcnt(4)
	v_pk_fma_f32 v[38:39], v[38:39], v[70:71], v[102:103]
	v_pk_fma_f32 v[36:37], v[36:37], v[68:69], v[100:101]
	v_pk_fma_f32 v[42:43], v[50:51], v[74:75], v[98:99]
	v_pk_fma_f32 v[40:41], v[48:49], v[72:73], v[96:97]
	s_waitcnt vmcnt(3)
	v_pk_fma_f32 v[34:35], v[34:35], v[66:67], v[106:107]
	v_pk_fma_f32 v[32:33], v[32:33], v[64:65], v[104:105]
	global_store_dwordx4 v[76:77], v[60:63], off
	global_store_dwordx4 v[76:77], v[56:59], off offset:64
	global_store_dwordx4 v[44:45], v[40:43], off offset:64
	global_store_dwordx4 v[44:45], v[36:39], off offset:512
	global_store_dwordx4 v[44:45], v[32:35], off offset:576
	v_lshl_add_u64 v[76:77], v[170:171], 0, s[30:31]
	s_mov_b64 s[30:31], 0x160000
	v_lshl_add_u64 v[44:45], v[168:169], 0, v[76:77]
	v_lshl_add_u64 v[78:79], v[170:171], 0, s[30:31]
	global_load_dwordx4 v[32:35], v[44:45], off
	global_load_dwordx4 v[36:39], v[44:45], off offset:64
	global_load_dwordx4 v[40:43], v[44:45], off offset:512
	s_nop 0
	global_load_dwordx4 v[44:47], v[44:45], off offset:576
	v_lshl_add_u64 v[60:61], v[168:169], 0, v[78:79]
	global_load_dwordx4 v[48:51], v[60:61], off
	global_load_dwordx4 v[52:55], v[60:61], off offset:64
	global_load_dwordx4 v[56:59], v[60:61], off offset:512
	s_nop 0
	global_load_dwordx4 v[60:63], v[60:61], off offset:576
	s_waitcnt vmcnt(7)
	v_pk_fma_f32 v[28:29], v[28:29], v[108:109], v[32:33]
	v_lshl_add_u64 v[32:33], s[28:29], 0, v[76:77]
	v_lshl_add_u64 v[32:33], v[32:33], 0, v[166:167]
	s_waitcnt vmcnt(5)
	v_pk_fma_f32 v[18:19], v[18:19], v[70:71], v[42:43]
	v_pk_fma_f32 v[16:17], v[16:17], v[68:69], v[40:41]
	global_store_dwordx4 v[32:33], v[16:19], off offset:512
	s_waitcnt vmcnt(5)
	v_pk_fma_f32 v[14:15], v[14:15], v[66:67], v[46:47]
	v_pk_fma_f32 v[12:13], v[12:13], v[64:65], v[44:45]
	v_lshl_add_u64 v[16:17], s[28:29], 0, v[78:79]
	v_pk_fma_f32 v[30:31], v[30:31], v[110:111], v[34:35]
	v_pk_fma_f32 v[26:27], v[26:27], v[74:75], v[38:39]
	v_pk_fma_f32 v[24:25], v[24:25], v[72:73], v[36:37]
	global_store_dwordx4 v[32:33], v[12:15], off offset:576
	v_lshl_add_u64 v[16:17], v[16:17], 0, v[166:167]
	s_waitcnt vmcnt(4)
	v_pk_fma_f32 v[10:11], v[10:11], v[74:75], v[54:55]
	v_pk_fma_f32 v[14:15], v[22:23], v[110:111], v[50:51]
	v_pk_fma_f32 v[12:13], v[20:21], v[108:109], v[48:49]
	v_pk_fma_f32 v[8:9], v[8:9], v[72:73], v[52:53]
	s_waitcnt vmcnt(3)
	v_pk_fma_f32 v[6:7], v[6:7], v[70:71], v[58:59]
	v_pk_fma_f32 v[4:5], v[4:5], v[68:69], v[56:57]
	s_waitcnt vmcnt(2)
	v_pk_fma_f32 v[2:3], v[2:3], v[66:67], v[62:63]
	v_pk_fma_f32 v[0:1], v[0:1], v[64:65], v[60:61]
	global_store_dwordx4 v[32:33], v[28:31], off
	global_store_dwordx4 v[32:33], v[24:27], off offset:64
	global_store_dwordx4 v[16:17], v[12:15], off
	global_store_dwordx4 v[16:17], v[8:11], off offset:64
	global_store_dwordx4 v[16:17], v[4:7], off offset:512
	global_store_dwordx4 v[16:17], v[0:3], off offset:576
	s_mov_b64 s[28:29], -1
	s_cbranch_vccnz .LBB0_397
	s_andn2_b64 vcc, exec, s[16:17]
	s_cbranch_vccnz .LBB0_396
	s_barrier
	s_branch .LBB0_396

; #define PG8_STAGE(bufoff, gbase, voff) do { _Pragma("unroll") for (int _i = 0; _i < 2; ++_i) \
;         __builtin_amdgcn_global_load_lds((const unsigned*)((const char*)(gbase) + (voff)[_i]), (LAS unsigned*)(lds + (bufoff) + ldsw + _i * 8192), 16, 0, 0); } while (0)
; #define PG8_LDA(dst, b, h) do { _Pragma("unroll") for (int m = 0; m < 4; ++m) _Pragma("unroll") for (int k = 0; k < 2; ++k) dst[m][k] = *(const LAS bf16x8*)(lds + PG8_SA(b, h) + aoff + m * 2048 + k * 1024); } while (0)
; #define PG8_LDB(dst, b, h) do { _Pragma("unroll") for (int n = 0; n < 2; ++n) _Pragma("unroll") for (int k = 0; k < 2; ++k) dst[n][k] = *(const LAS bf16x8*)(lds + PG8_SB(b, h) + boff + n * 2048 + k * 1024); } while (0)
; #define PG8_MMA(ai, bj, At, Bt) do { __builtin_amdgcn_s_setprio(1); _Pragma("unroll") for (int m = 0; m < 4; ++m) _Pragma("unroll") for (int n = 0; n < 2; ++n) _Pragma("unroll") for (int k = 0; k < 2; ++k) \
;         acc[ai][bj][m][n] = __builtin_amdgcn_mfma_f32_16x16x32_bf16(Bt[n][k], At[m][k], acc[ai][bj][m][n], 0, 0, 0); __builtin_amdgcn_s_setprio(0); } while (0)
; #define PG8_WAIT_V(n) asm volatile("s_waitcnt vmcnt(" #n ")" ::: "memory")
; #define PG8_WAIT_L(n) asm volatile("s_waitcnt lgkmcnt(" #n ")" ::: "memory")
; #define PG8_BAR __builtin_amdgcn_s_barrier()
; #define PG8_SCHED __builtin_amdgcn_sched_barrier(0)
; template <class Epi, class Map>
; __device__ __forceinline__ void gemm_phase(LAS unsigned char* lds, const Gemm g, const Sched<Map>& S, const Epi& E) {
;     ...
;         const bool has_next = S.next(ui + 1, nxt);
;         const char* nA = has_next ? (const char*)g.A + nxt.aoff : cA; const char* nB = has_next ? (const char*)g.Bt + nxt.boff : cB;
; #pragma unroll 1
;         for (int t = 0; t < nt; t += 2) {
;             const bool last = (t == nt - 2);
;             const char* a1 = cA + (size_t)(t + 1) * kstep;
;             const char* a2 = last ? nA : cA + (size_t)(t + 2) * kstep; const char* b2 = last ? nB : cB + (size_t)(t + 2) * kstep;
;             const char* a3 = a2 + kstep; const char* b3 = b2 + kstep;
;             PG8_LDB(B0, 0, 0); PG8_LDB(B1, 0, 1); PG8_SCHED; PG8_LDA(At, 0, 0); PG8_STAGE(PG8_SA(1, 1), a1 + hstepA, voffA);
;             PG8_WAIT_V(8); PG8_WAIT_L(0); PG8_BAR; PG8_MMA(0, 0, At, B0); PG8_MMA(0, 1, At, B1); PG8_BAR; PG8_SCHED;
.LBB0_551:
	s_add_u32 s54, s78, s6
	s_addc_u32 s55, s79, 0
	s_and_b64 s[8:9], s[40:41], exec
	s_cselect_b32 s3, s55, s25
	s_cselect_b32 s8, s54, s24
	s_add_u32 s58, s4, s1
	s_addc_u32 s59, s5, 0
	s_and_b64 s[10:11], s[40:41], exec
	s_cselect_b32 s9, s59, s29
	s_cselect_b32 s10, s58, s28
	s_add_u32 s24, s24, 0x80080
	s_addc_u32 s25, s25, 0
	s_add_u32 s11, s28, 0x100
	v_mov_b32_e32 v4, 0
	s_addc_u32 s12, s29, 0
	s_mov_b32 s13, -2
	v_mov_b32_e32 v5, v4
	v_mov_b32_e32 v6, v4
	v_mov_b32_e32 v7, v4
	v_mov_b32_e32 v8, v4
	v_mov_b32_e32 v9, v4
	v_mov_b32_e32 v10, v4
	v_mov_b32_e32 v11, v4
	v_mov_b32_e32 v20, v4
	v_mov_b32_e32 v21, v4
	v_mov_b32_e32 v22, v4
	v_mov_b32_e32 v23, v4
	v_mov_b32_e32 v24, v4
	v_mov_b32_e32 v25, v4
	v_mov_b32_e32 v26, v4
	v_mov_b32_e32 v27, v4
	v_mov_b32_e32 v36, v4
	v_mov_b32_e32 v37, v4
	v_mov_b32_e32 v38, v4
	v_mov_b32_e32 v39, v4
	v_mov_b32_e32 v40, v4
	v_mov_b32_e32 v41, v4
	v_mov_b32_e32 v42, v4
	v_mov_b32_e32 v43, v4
	v_mov_b32_e32 v52, v4
	v_mov_b32_e32 v53, v4
	v_mov_b32_e32 v54, v4
	v_mov_b32_e32 v55, v4
	v_mov_b32_e32 v56, v4
	v_mov_b32_e32 v57, v4
	v_mov_b32_e32 v58, v4
	v_mov_b32_e32 v59, v4
	v_mov_b32_e32 v0, v4
	v_mov_b32_e32 v1, v4
	v_mov_b32_e32 v2, v4
	v_mov_b32_e32 v3, v4
	v_mov_b32_e32 v12, v4
	v_mov_b32_e32 v13, v4
	v_mov_b32_e32 v14, v4
	v_mov_b32_e32 v15, v4
	v_mov_b32_e32 v16, v4
	v_mov_b32_e32 v17, v4
	v_mov_b32_e32 v18, v4
	v_mov_b32_e32 v19, v4
	v_mov_b32_e32 v28, v4
	v_mov_b32_e32 v29, v4
	v_mov_b32_e32 v30, v4
	v_mov_b32_e32 v31, v4
	v_mov_b32_e32 v32, v4
	v_mov_b32_e32 v33, v4
	v_mov_b32_e32 v34, v4
	v_mov_b32_e32 v35, v4
	v_mov_b32_e32 v44, v4
	v_mov_b32_e32 v45, v4
	v_mov_b32_e32 v46, v4
	v_mov_b32_e32 v47, v4
	v_mov_b32_e32 v48, v4
	v_mov_b32_e32 v49, v4
	v_mov_b32_e32 v50, v4
	v_mov_b32_e32 v51, v4
	v_mov_b32_e32 v60, v4
	v_mov_b32_e32 v61, v4
	v_mov_b32_e32 v62, v4
	v_mov_b32_e32 v63, v4
	v_mov_b32_e32 v68, v4
	v_mov_b32_e32 v69, v4
	v_mov_b32_e32 v70, v4
	v_mov_b32_e32 v71, v4
	v_mov_b32_e32 v72, v4
	v_mov_b32_e32 v73, v4
	v_mov_b32_e32 v74, v4
	v_mov_b32_e32 v75, v4
	v_mov_b32_e32 v84, v4
	v_mov_b32_e32 v85, v4
	v_mov_b32_e32 v86, v4
	v_mov_b32_e32 v87, v4
	v_mov_b32_e32 v88, v4
	v_mov_b32_e32 v89, v4
	v_mov_b32_e32 v90, v4
	v_mov_b32_e32 v91, v4
	v_mov_b32_e32 v100, v4
	v_mov_b32_e32 v101, v4
	v_mov_b32_e32 v102, v4
	v_mov_b32_e32 v103, v4
	v_mov_b32_e32 v104, v4
	v_mov_b32_e32 v105, v4
	v_mov_b32_e32 v106, v4
	v_mov_b32_e32 v107, v4
	v_mov_b32_e32 v112, v4
	v_mov_b32_e32 v113, v4
	v_mov_b32_e32 v114, v4
	v_mov_b32_e32 v115, v4
	v_mov_b32_e32 v120, v4
	v_mov_b32_e32 v121, v4
	v_mov_b32_e32 v122, v4
	v_mov_b32_e32 v123, v4
	v_mov_b32_e32 v64, v4
	v_mov_b32_e32 v65, v4
	v_mov_b32_e32 v66, v4
	v_mov_b32_e32 v67, v4
	v_mov_b32_e32 v76, v4
	v_mov_b32_e32 v77, v4
	v_mov_b32_e32 v78, v4
	v_mov_b32_e32 v79, v4
	v_mov_b32_e32 v80, v4
	v_mov_b32_e32 v81, v4
	v_mov_b32_e32 v82, v4
	v_mov_b32_e32 v83, v4
	v_mov_b32_e32 v92, v4
	v_mov_b32_e32 v93, v4
	v_mov_b32_e32 v94, v4
	v_mov_b32_e32 v95, v4
	v_mov_b32_e32 v96, v4
	v_mov_b32_e32 v97, v4
	v_mov_b32_e32 v98, v4
	v_mov_b32_e32 v99, v4
	v_mov_b32_e32 v108, v4
	v_mov_b32_e32 v109, v4
	v_mov_b32_e32 v110, v4
	v_mov_b32_e32 v111, v4
	v_mov_b32_e32 v116, v4
	v_mov_b32_e32 v117, v4
	v_mov_b32_e32 v118, v4
	v_mov_b32_e32 v119, v4
	v_mov_b32_e32 v124, v4
	v_mov_b32_e32 v125, v4
	v_mov_b32_e32 v126, v4
	v_mov_b32_e32 v127, v4
.LBB0_552:
	s_add_u32 s14, s24, 0xfff80080
	s_addc_u32 s15, s25, -1
	s_add_i32 s19, 0, 0x10000
	s_cmp_eq_u32 s13, 28
	s_cselect_b32 s31, s3, s15
	s_cselect_b32 s30, s8, s14
	v_add_u32_e32 v142, s19, v168
	s_cselect_b32 s29, s9, s12
	s_cselect_b32 s28, s10, s11
	s_add_i32 s21, 0, 0x14000
	ds_read_b128 v[128:131], v142
	ds_read_b128 v[160:163], v142 offset:1024
	ds_read_b128 v[170:173], v142 offset:2048
	ds_read_b128 v[174:177], v142 offset:3072
	v_add_u32_e32 v142, s21, v168
	ds_read_b128 v[178:181], v142
	ds_read_b128 v[192:195], v142 offset:1024
	ds_read_b128 v[196:199], v142 offset:2048
	ds_read_b128 v[200:203], v142 offset:3072
	v_lshl_add_u64 v[142:143], s[24:25], 0, v[138:139]
	s_add_i32 m0, s35, 0xc000
	ds_read_b128 v[204:207], v169
	ds_read_b128 v[208:211], v169 offset:1024
	ds_read_b128 v[212:215], v169 offset:2048
	ds_read_b128 v[216:219], v169 offset:3072
	ds_read_b128 v[220:223], v169 offset:4096
	ds_read_b128 v[224:227], v169 offset:5120
	ds_read_b128 v[228:231], v169 offset:6144
	ds_read_b128 v[232:235], v169 offset:7168
	global_load_lds_dwordx4 v[142:143], off
	v_lshl_add_u64 v[142:143], s[24:25], 0, v[140:141]
	s_add_i32 m0, s35, 0xe000
	s_nop 0
	global_load_lds_dwordx4 v[142:143], off
	s_waitcnt vmcnt(8)
	s_waitcnt lgkmcnt(0)
	s_barrier
; #define PG8_STAGE(bufoff, gbase, voff) do { _Pragma("unroll") for (int _i = 0; _i < 2; ++_i) \
;         __builtin_amdgcn_global_load_lds((const unsigned*)((const char*)(gbase) + (voff)[_i]), (LAS unsigned*)(lds + (bufoff) + ldsw + _i * 8192), 16, 0, 0); } while (0)
; #define PG8_LDA(dst, b, h) do { _Pragma("unroll") for (int m = 0; m < 4; ++m) _Pragma("unroll") for (int k = 0; k < 2; ++k) dst[m][k] = *(const LAS bf16x8*)(lds + PG8_SA(b, h) + aoff + m * 2048 + k * 1024); } while (0)
; #define PG8_LDB(dst, b, h) do { _Pragma("unroll") for (int n = 0; n < 2; ++n) _Pragma("unroll") for (int k = 0; k < 2; ++k) dst[n][k] = *(const LAS bf16x8*)(lds + PG8_SB(b, h) + boff + n * 2048 + k * 1024); } while (0)
; #define PG8_MMA(ai, bj, At, Bt) do { __builtin_amdgcn_s_setprio(1); _Pragma("unroll") for (int m = 0; m < 4; ++m) _Pragma("unroll") for (int n = 0; n < 2; ++n) _Pragma("unroll") for (int k = 0; k < 2; ++k) \
;         acc[ai][bj][m][n] = __builtin_amdgcn_mfma_f32_16x16x32_bf16(Bt[n][k], At[m][k], acc[ai][bj][m][n], 0, 0, 0); __builtin_amdgcn_s_setprio(0); } while (0)
; #define PG8_WAIT_V(n) asm volatile("s_waitcnt vmcnt(" #n ")" ::: "memory")
; #define PG8_WAIT_L(n) asm volatile("s_waitcnt lgkmcnt(" #n ")" ::: "memory")
; #define PG8_BAR __builtin_amdgcn_s_barrier()
; #define PG8_SCHED __builtin_amdgcn_sched_barrier(0)
; template <class Epi, class Map>
; __device__ __forceinline__ void gemm_phase(LAS unsigned char* lds, const Gemm g, const Sched<Map>& S, const Epi& E) {
;     ...
;             PG8_WAIT_V(8); PG8_WAIT_L(0); PG8_BAR; PG8_MMA(0, 0, At, B0); PG8_MMA(0, 1, At, B1); PG8_BAR; PG8_SCHED;
;             PG8_LDA(At, 0, 1); PG8_STAGE(PG8_SB(0, 0), b2, voffB); PG8_STAGE(PG8_SB(0, 1), b2 + hstepB, voffB); PG8_STAGE(PG8_SA(0, 0), a2, voffA);
;             PG8_WAIT_V(8); PG8_WAIT_L(0); PG8_BAR; PG8_MMA(1, 0, At, B0); PG8_MMA(1, 1, At, B1); PG8_BAR; PG8_SCHED;
;             PG8_LDB(B0, 1, 0); PG8_LDB(B1, 1, 1); PG8_SCHED; PG8_LDA(At, 1, 0); PG8_STAGE(PG8_SA(0, 1), a2 + hstepA, voffA);
;             PG8_WAIT_V(8); PG8_WAIT_L(0); PG8_BAR; PG8_MMA(0, 0, At, B0); PG8_MMA(0, 1, At, B1); PG8_BAR; PG8_SCHED;
	s_waitcnt lgkmcnt(0)
	v_mfma_f32_16x16x32_bf16 v[124:127], v[128:131], v[204:207], v[124:127]
	v_mfma_f32_16x16x32_bf16 v[116:119], v[170:173], v[204:207], v[116:119]
	v_mfma_f32_16x16x32_bf16 v[108:111], v[128:131], v[212:215], v[108:111]
	v_mfma_f32_16x16x32_bf16 v[96:99], v[170:173], v[212:215], v[96:99]
	v_mfma_f32_16x16x32_bf16 v[92:95], v[128:131], v[220:223], v[92:95]
	v_mfma_f32_16x16x32_bf16 v[80:83], v[170:173], v[220:223], v[80:83]
	v_mfma_f32_16x16x32_bf16 v[76:79], v[128:131], v[228:231], v[76:79]
	v_mfma_f32_16x16x32_bf16 v[64:67], v[170:173], v[228:231], v[64:67]
	v_mfma_f32_16x16x32_bf16 v[124:127], v[160:163], v[208:211], v[124:127]
	v_mfma_f32_16x16x32_bf16 v[116:119], v[174:177], v[208:211], v[116:119]
	v_mfma_f32_16x16x32_bf16 v[108:111], v[160:163], v[216:219], v[108:111]
	v_mfma_f32_16x16x32_bf16 v[96:99], v[174:177], v[216:219], v[96:99]
	v_mfma_f32_16x16x32_bf16 v[92:95], v[160:163], v[224:227], v[92:95]
	v_mfma_f32_16x16x32_bf16 v[80:83], v[174:177], v[224:227], v[80:83]
	v_mfma_f32_16x16x32_bf16 v[76:79], v[160:163], v[232:235], v[76:79]
	v_mfma_f32_16x16x32_bf16 v[64:67], v[174:177], v[232:235], v[64:67]
	v_mfma_f32_16x16x32_bf16 v[120:123], v[178:181], v[204:207], v[120:123]
	v_mfma_f32_16x16x32_bf16 v[112:115], v[196:199], v[204:207], v[112:115]
	v_mfma_f32_16x16x32_bf16 v[104:107], v[178:181], v[212:215], v[104:107]
	v_mfma_f32_16x16x32_bf16 v[100:103], v[196:199], v[212:215], v[100:103]
	v_mfma_f32_16x16x32_bf16 v[88:91], v[178:181], v[220:223], v[88:91]
	v_mfma_f32_16x16x32_bf16 v[84:87], v[196:199], v[220:223], v[84:87]
	v_mfma_f32_16x16x32_bf16 v[72:75], v[178:181], v[228:231], v[72:75]
	v_mfma_f32_16x16x32_bf16 v[68:71], v[196:199], v[228:231], v[68:71]
	v_mfma_f32_16x16x32_bf16 v[120:123], v[192:195], v[208:211], v[120:123]
	v_mfma_f32_16x16x32_bf16 v[112:115], v[200:203], v[208:211], v[112:115]
	v_mfma_f32_16x16x32_bf16 v[104:107], v[192:195], v[216:219], v[104:107]
	v_mfma_f32_16x16x32_bf16 v[100:103], v[200:203], v[216:219], v[100:103]
	v_mfma_f32_16x16x32_bf16 v[88:91], v[192:195], v[224:227], v[88:91]
	v_mfma_f32_16x16x32_bf16 v[84:87], v[200:203], v[224:227], v[84:87]
	v_mfma_f32_16x16x32_bf16 v[72:75], v[192:195], v[232:235], v[72:75]
	v_mfma_f32_16x16x32_bf16 v[68:71], v[200:203], v[232:235], v[68:71]
	s_barrier
	s_add_i32 s14, s19, s34
	v_lshl_add_u64 v[142:143], s[28:29], 0, v[144:145]
	s_mov_b32 m0, s14
	ds_read_b128 v[204:207], v169 offset:16384
	ds_read_b128 v[208:211], v169 offset:17408
	ds_read_b128 v[212:215], v169 offset:18432
	ds_read_b128 v[216:219], v169 offset:19456
	ds_read_b128 v[220:223], v169 offset:20480
	ds_read_b128 v[224:227], v169 offset:21504
	ds_read_b128 v[228:231], v169 offset:22528
	ds_read_b128 v[232:235], v169 offset:23552
	global_load_lds_dwordx4 v[142:143], off
	s_add_i32 m0, s14, 0x2000
	s_add_u32 s14, s28, 0x80000
	v_lshl_add_u64 v[164:165], s[28:29], 0, v[136:137]
	s_addc_u32 s15, s29, 0
	s_add_i32 s19, s21, s34
	global_load_lds_dwordx4 v[164:165], off
	v_lshl_add_u64 v[236:237], s[14:15], 0, v[144:145]
	s_mov_b32 m0, s19
	v_lshl_add_u64 v[238:239], s[30:31], 0, v[134:135]
	global_load_lds_dwordx4 v[236:237], off
	v_lshl_add_u64 v[236:237], s[14:15], 0, v[136:137]
	s_add_i32 m0, s19, 0x2000
	s_nop 0
	global_load_lds_dwordx4 v[236:237], off
	v_lshl_add_u64 v[236:237], s[30:31], 0, v[132:133]
	s_mov_b32 m0, s35
	s_nop 0
	global_load_lds_dwordx4 v[236:237], off
	s_mov_b32 m0, s84
	s_nop 0
	global_load_lds_dwordx4 v[238:239], off
	s_waitcnt vmcnt(8)
	s_waitcnt lgkmcnt(0)
	s_barrier
	s_waitcnt lgkmcnt(0)
	v_mfma_f32_16x16x32_bf16 v[60:63], v[128:131], v[204:207], v[60:63]
	v_mfma_f32_16x16x32_bf16 v[48:51], v[170:173], v[204:207], v[48:51]
	v_mfma_f32_16x16x32_bf16 v[44:47], v[128:131], v[212:215], v[44:47]
	v_mfma_f32_16x16x32_bf16 v[32:35], v[170:173], v[212:215], v[32:35]
	v_mfma_f32_16x16x32_bf16 v[28:31], v[128:131], v[220:223], v[28:31]
	v_mfma_f32_16x16x32_bf16 v[16:19], v[170:173], v[220:223], v[16:19]
	v_mfma_f32_16x16x32_bf16 v[12:15], v[128:131], v[228:231], v[12:15]
	v_mfma_f32_16x16x32_bf16 v[0:3], v[170:173], v[228:231], v[0:3]
	v_mfma_f32_16x16x32_bf16 v[60:63], v[160:163], v[208:211], v[60:63]
	v_mfma_f32_16x16x32_bf16 v[48:51], v[174:177], v[208:211], v[48:51]
	v_mfma_f32_16x16x32_bf16 v[44:47], v[160:163], v[216:219], v[44:47]
	v_mfma_f32_16x16x32_bf16 v[32:35], v[174:177], v[216:219], v[32:35]
	v_mfma_f32_16x16x32_bf16 v[28:31], v[160:163], v[224:227], v[28:31]
	v_mfma_f32_16x16x32_bf16 v[16:19], v[174:177], v[224:227], v[16:19]
	v_mfma_f32_16x16x32_bf16 v[12:15], v[160:163], v[232:235], v[12:15]
	v_mfma_f32_16x16x32_bf16 v[0:3], v[174:177], v[232:235], v[0:3]
	v_mfma_f32_16x16x32_bf16 v[56:59], v[178:181], v[204:207], v[56:59]
	v_mfma_f32_16x16x32_bf16 v[52:55], v[196:199], v[204:207], v[52:55]
	v_mfma_f32_16x16x32_bf16 v[40:43], v[178:181], v[212:215], v[40:43]
	v_mfma_f32_16x16x32_bf16 v[36:39], v[196:199], v[212:215], v[36:39]
	v_mfma_f32_16x16x32_bf16 v[24:27], v[178:181], v[220:223], v[24:27]
	v_mfma_f32_16x16x32_bf16 v[20:23], v[196:199], v[220:223], v[20:23]
	v_mfma_f32_16x16x32_bf16 v[8:11], v[178:181], v[228:231], v[8:11]
	v_mfma_f32_16x16x32_bf16 v[4:7], v[196:199], v[228:231], v[4:7]
	v_mfma_f32_16x16x32_bf16 v[56:59], v[192:195], v[208:211], v[56:59]
	v_mfma_f32_16x16x32_bf16 v[52:55], v[200:203], v[208:211], v[52:55]
	v_mfma_f32_16x16x32_bf16 v[40:43], v[192:195], v[216:219], v[40:43]
	v_mfma_f32_16x16x32_bf16 v[36:39], v[200:203], v[216:219], v[36:39]
	v_mfma_f32_16x16x32_bf16 v[24:27], v[192:195], v[224:227], v[24:27]
	v_mfma_f32_16x16x32_bf16 v[20:23], v[200:203], v[224:227], v[20:23]
	v_mfma_f32_16x16x32_bf16 v[8:11], v[192:195], v[232:235], v[8:11]
	v_mfma_f32_16x16x32_bf16 v[4:7], v[200:203], v[232:235], v[4:7]
	s_barrier
; #define PG8_STAGE(bufoff, gbase, voff) do { _Pragma("unroll") for (int _i = 0; _i < 2; ++_i) \
;         __builtin_amdgcn_global_load_lds((const unsigned*)((const char*)(gbase) + (voff)[_i]), (LAS unsigned*)(lds + (bufoff) + ldsw + _i * 8192), 16, 0, 0); } while (0)
; #define PG8_LDA(dst, b, h) do { _Pragma("unroll") for (int m = 0; m < 4; ++m) _Pragma("unroll") for (int k = 0; k < 2; ++k) dst[m][k] = *(const LAS bf16x8*)(lds + PG8_SA(b, h) + aoff + m * 2048 + k * 1024); } while (0)
; #define PG8_LDB(dst, b, h) do { _Pragma("unroll") for (int n = 0; n < 2; ++n) _Pragma("unroll") for (int k = 0; k < 2; ++k) dst[n][k] = *(const LAS bf16x8*)(lds + PG8_SB(b, h) + boff + n * 2048 + k * 1024); } while (0)
; #define PG8_MMA(ai, bj, At, Bt) do { __builtin_amdgcn_s_setprio(1); _Pragma("unroll") for (int m = 0; m < 4; ++m) _Pragma("unroll") for (int n = 0; n < 2; ++n) _Pragma("unroll") for (int k = 0; k < 2; ++k) \
;         acc[ai][bj][m][n] = __builtin_amdgcn_mfma_f32_16x16x32_bf16(Bt[n][k], At[m][k], acc[ai][bj][m][n], 0, 0, 0); __builtin_amdgcn_s_setprio(0); } while (0)
; #define PG8_WAIT_V(n) asm volatile("s_waitcnt vmcnt(" #n ")" ::: "memory")
; #define PG8_WAIT_L(n) asm volatile("s_waitcnt lgkmcnt(" #n ")" ::: "memory")
; #define PG8_BAR __builtin_amdgcn_s_barrier()
; #define PG8_SCHED __builtin_amdgcn_sched_barrier(0)
; template <class Epi, class Map>
; __device__ __forceinline__ void gemm_phase(LAS unsigned char* lds, const Gemm g, const Sched<Map>& S, const Epi& E) {
;     ...
;             PG8_LDB(B0, 1, 0); PG8_LDB(B1, 1, 1); PG8_SCHED; PG8_LDA(At, 1, 0); PG8_STAGE(PG8_SA(0, 1), a2 + hstepA, voffA);
;             PG8_WAIT_V(8); PG8_WAIT_L(0); PG8_BAR; PG8_MMA(0, 0, At, B0); PG8_MMA(0, 1, At, B1); PG8_BAR; PG8_SCHED;
;             PG8_LDA(At, 1, 1); PG8_STAGE(PG8_SB(1, 0), b3, voffB); PG8_STAGE(PG8_SB(1, 1), b3 + hstepB, voffB); PG8_STAGE(PG8_SA(1, 0), a3, voffA);
;             PG8_WAIT_V(8); PG8_WAIT_L(0); PG8_BAR; PG8_MMA(1, 0, At, B0); PG8_MMA(1, 1, At, B1); PG8_BAR; PG8_SCHED;
	s_add_i32 s19, 0, 0x18000
	s_add_i32 s21, 0, 0x1c000
	v_add_u32_e32 v174, s19, v168
	v_add_u32_e32 v200, s21, v168
	ds_read_b128 v[128:131], v174
	ds_read_b128 v[160:163], v174 offset:1024
	ds_read_b128 v[170:173], v174 offset:2048
	ds_read_b128 v[174:177], v174 offset:3072
	ds_read_b128 v[178:181], v200
	ds_read_b128 v[192:195], v200 offset:1024
	ds_read_b128 v[196:199], v200 offset:2048
	ds_read_b128 v[200:203], v200 offset:3072
	s_add_u32 s14, s30, 0x80000
	s_addc_u32 s15, s31, 0
	s_mov_b32 m0, s85
	v_lshl_add_u64 v[240:241], s[14:15], 0, v[132:133]
	ds_read_b128 v[204:207], v169 offset:32768
	ds_read_b128 v[208:211], v169 offset:33792
	ds_read_b128 v[212:215], v169 offset:34816
	ds_read_b128 v[216:219], v169 offset:35840
	ds_read_b128 v[220:223], v169 offset:36864
	ds_read_b128 v[224:227], v169 offset:37888
	ds_read_b128 v[228:231], v169 offset:38912
	ds_read_b128 v[232:235], v169 offset:39936
	global_load_lds_dwordx4 v[240:241], off
	v_lshl_add_u64 v[240:241], s[14:15], 0, v[134:135]
	s_mov_b32 m0, s90
	s_nop 0
	global_load_lds_dwordx4 v[240:241], off
	s_waitcnt vmcnt(8)
	s_waitcnt lgkmcnt(0)
	s_barrier
	s_waitcnt lgkmcnt(0)
	v_mfma_f32_16x16x32_bf16 v[124:127], v[128:131], v[204:207], v[124:127]
	v_mfma_f32_16x16x32_bf16 v[116:119], v[170:173], v[204:207], v[116:119]
	v_mfma_f32_16x16x32_bf16 v[108:111], v[128:131], v[212:215], v[108:111]
	v_mfma_f32_16x16x32_bf16 v[96:99], v[170:173], v[212:215], v[96:99]
	v_mfma_f32_16x16x32_bf16 v[92:95], v[128:131], v[220:223], v[92:95]
	v_mfma_f32_16x16x32_bf16 v[80:83], v[170:173], v[220:223], v[80:83]
	v_mfma_f32_16x16x32_bf16 v[76:79], v[128:131], v[228:231], v[76:79]
	v_mfma_f32_16x16x32_bf16 v[64:67], v[170:173], v[228:231], v[64:67]
	v_mfma_f32_16x16x32_bf16 v[124:127], v[160:163], v[208:211], v[124:127]
	v_mfma_f32_16x16x32_bf16 v[116:119], v[174:177], v[208:211], v[116:119]
	v_mfma_f32_16x16x32_bf16 v[108:111], v[160:163], v[216:219], v[108:111]
	v_mfma_f32_16x16x32_bf16 v[96:99], v[174:177], v[216:219], v[96:99]
	v_mfma_f32_16x16x32_bf16 v[92:95], v[160:163], v[224:227], v[92:95]
	v_mfma_f32_16x16x32_bf16 v[80:83], v[174:177], v[224:227], v[80:83]
	v_mfma_f32_16x16x32_bf16 v[76:79], v[160:163], v[232:235], v[76:79]
	v_mfma_f32_16x16x32_bf16 v[64:67], v[174:177], v[232:235], v[64:67]
	v_mfma_f32_16x16x32_bf16 v[120:123], v[178:181], v[204:207], v[120:123]
	v_mfma_f32_16x16x32_bf16 v[112:115], v[196:199], v[204:207], v[112:115]
	v_mfma_f32_16x16x32_bf16 v[104:107], v[178:181], v[212:215], v[104:107]
	v_mfma_f32_16x16x32_bf16 v[100:103], v[196:199], v[212:215], v[100:103]
	v_mfma_f32_16x16x32_bf16 v[88:91], v[178:181], v[220:223], v[88:91]
	v_mfma_f32_16x16x32_bf16 v[84:87], v[196:199], v[220:223], v[84:87]
	v_mfma_f32_16x16x32_bf16 v[72:75], v[178:181], v[228:231], v[72:75]
	v_mfma_f32_16x16x32_bf16 v[68:71], v[196:199], v[228:231], v[68:71]
	v_mfma_f32_16x16x32_bf16 v[120:123], v[192:195], v[208:211], v[120:123]
	v_mfma_f32_16x16x32_bf16 v[112:115], v[200:203], v[208:211], v[112:115]
	v_mfma_f32_16x16x32_bf16 v[104:107], v[192:195], v[216:219], v[104:107]
	v_mfma_f32_16x16x32_bf16 v[100:103], v[200:203], v[216:219], v[100:103]
	v_mfma_f32_16x16x32_bf16 v[88:91], v[192:195], v[224:227], v[88:91]
	v_mfma_f32_16x16x32_bf16 v[84:87], v[200:203], v[224:227], v[84:87]
	v_mfma_f32_16x16x32_bf16 v[72:75], v[192:195], v[232:235], v[72:75]
	v_mfma_f32_16x16x32_bf16 v[68:71], v[200:203], v[232:235], v[68:71]
	s_barrier
	s_add_i32 s14, s19, s34
	v_lshl_add_u64 v[142:143], v[142:143], 0, s[82:83]
	s_mov_b32 m0, s14
	ds_read_b128 v[204:207], v169 offset:49152
	ds_read_b128 v[208:211], v169 offset:50176
	ds_read_b128 v[212:215], v169 offset:51200
	ds_read_b128 v[216:219], v169 offset:52224
	ds_read_b128 v[220:223], v169 offset:53248
	ds_read_b128 v[224:227], v169 offset:54272
	ds_read_b128 v[228:231], v169 offset:55296
	ds_read_b128 v[232:235], v169 offset:56320
	global_load_lds_dwordx4 v[142:143], off
	s_add_i32 m0, s14, 0x2000
	s_add_u32 s14, s28, 0x80080
	v_lshl_add_u64 v[142:143], v[164:165], 0, s[82:83]
	s_addc_u32 s15, s29, 0
	s_add_i32 s19, s21, s34
	global_load_lds_dwordx4 v[142:143], off
	v_lshl_add_u64 v[142:143], s[14:15], 0, v[144:145]
	s_mov_b32 m0, s19
	s_nop 0
	global_load_lds_dwordx4 v[142:143], off
	v_lshl_add_u64 v[142:143], s[14:15], 0, v[136:137]
	s_add_i32 m0, s19, 0x2000
	s_nop 0
	global_load_lds_dwordx4 v[142:143], off
	v_lshl_add_u64 v[142:143], v[236:237], 0, s[82:83]
	s_mov_b32 m0, s97
	s_nop 0
	global_load_lds_dwordx4 v[142:143], off
	v_lshl_add_u64 v[142:143], v[238:239], 0, s[82:83]
	s_mov_b32 m0, s56
	s_nop 0
	global_load_lds_dwordx4 v[142:143], off
	s_waitcnt vmcnt(8)
	s_waitcnt lgkmcnt(0)
	s_barrier
; #define PG8_MMA(ai, bj, At, Bt) do { __builtin_amdgcn_s_setprio(1); _Pragma("unroll") for (int m = 0; m < 4; ++m) _Pragma("unroll") for (int n = 0; n < 2; ++n) _Pragma("unroll") for (int k = 0; k < 2; ++k) \
;         acc[ai][bj][m][n] = __builtin_amdgcn_mfma_f32_16x16x32_bf16(Bt[n][k], At[m][k], acc[ai][bj][m][n], 0, 0, 0); __builtin_amdgcn_s_setprio(0); } while (0)
; #define PG8_WAIT_V(n) asm volatile("s_waitcnt vmcnt(" #n ")" ::: "memory")
; #define PG8_WAIT_L(n) asm volatile("s_waitcnt lgkmcnt(" #n ")" ::: "memory")
; #define PG8_BAR __builtin_amdgcn_s_barrier()
; #define PG8_SCHED __builtin_amdgcn_sched_barrier(0)
; template <class Epi, class Map>
; __device__ __forceinline__ void gemm_phase(LAS unsigned char* lds, const Gemm g, const Sched<Map>& S, const Epi& E) {
;     ...
;             PG8_WAIT_V(8); PG8_WAIT_L(0); PG8_BAR; PG8_MMA(1, 0, At, B0); PG8_MMA(1, 1, At, B1); PG8_BAR; PG8_SCHED;
;         }
;         if (wr == 0) PG8_BAR;
;     __device__ __forceinline__ void operator()(const Acc& acc, const Unit& u, int wr, int wc, int fr, int fq) const {
;     ...
;         const float lg = l2g[u.pn];
; #pragma unroll
;         for (int ai = 0; ai < 2; ++ai)
; #pragma unroll
;             for (int m = 0; m < 4; ++m) {
;                 const int row_in = ai * HALF + wr * 64 + m * 16 + fr, s = u.pm * BM + row_in;
;                 const float rs = mode == 0 ? exp2f((float)(row_in + 1) * lg) : 0.0625f;
;                 const f32x4* cp = cs + ((size_t)s * 128 + wc * 32 + 8 * fq) / 2;
;                 f32x4 t[4];
; #pragma unroll
;                 for (int i = 0; i < 4; ++i) t[i] = cp[i];
	s_waitcnt lgkmcnt(0)
	v_mfma_f32_16x16x32_bf16 v[60:63], v[128:131], v[204:207], v[60:63]
	v_mfma_f32_16x16x32_bf16 v[48:51], v[170:173], v[204:207], v[48:51]
	v_mfma_f32_16x16x32_bf16 v[44:47], v[128:131], v[212:215], v[44:47]
	v_mfma_f32_16x16x32_bf16 v[32:35], v[170:173], v[212:215], v[32:35]
	v_mfma_f32_16x16x32_bf16 v[28:31], v[128:131], v[220:223], v[28:31]
	v_mfma_f32_16x16x32_bf16 v[16:19], v[170:173], v[220:223], v[16:19]
	v_mfma_f32_16x16x32_bf16 v[12:15], v[128:131], v[228:231], v[12:15]
	v_mfma_f32_16x16x32_bf16 v[0:3], v[170:173], v[228:231], v[0:3]
	v_mfma_f32_16x16x32_bf16 v[60:63], v[160:163], v[208:211], v[60:63]
	v_mfma_f32_16x16x32_bf16 v[48:51], v[174:177], v[208:211], v[48:51]
	v_mfma_f32_16x16x32_bf16 v[44:47], v[160:163], v[216:219], v[44:47]
	v_mfma_f32_16x16x32_bf16 v[32:35], v[174:177], v[216:219], v[32:35]
	v_mfma_f32_16x16x32_bf16 v[28:31], v[160:163], v[224:227], v[28:31]
	v_mfma_f32_16x16x32_bf16 v[16:19], v[174:177], v[224:227], v[16:19]
	v_mfma_f32_16x16x32_bf16 v[12:15], v[160:163], v[232:235], v[12:15]
	v_mfma_f32_16x16x32_bf16 v[0:3], v[174:177], v[232:235], v[0:3]
	v_mfma_f32_16x16x32_bf16 v[56:59], v[178:181], v[204:207], v[56:59]
	v_mfma_f32_16x16x32_bf16 v[52:55], v[196:199], v[204:207], v[52:55]
	v_mfma_f32_16x16x32_bf16 v[40:43], v[178:181], v[212:215], v[40:43]
	v_mfma_f32_16x16x32_bf16 v[36:39], v[196:199], v[212:215], v[36:39]
	v_mfma_f32_16x16x32_bf16 v[24:27], v[178:181], v[220:223], v[24:27]
	v_mfma_f32_16x16x32_bf16 v[20:23], v[196:199], v[220:223], v[20:23]
	v_mfma_f32_16x16x32_bf16 v[8:11], v[178:181], v[228:231], v[8:11]
	v_mfma_f32_16x16x32_bf16 v[4:7], v[196:199], v[228:231], v[4:7]
	v_mfma_f32_16x16x32_bf16 v[56:59], v[192:195], v[208:211], v[56:59]
	v_mfma_f32_16x16x32_bf16 v[52:55], v[200:203], v[208:211], v[52:55]
	v_mfma_f32_16x16x32_bf16 v[40:43], v[192:195], v[216:219], v[40:43]
	v_mfma_f32_16x16x32_bf16 v[36:39], v[200:203], v[216:219], v[36:39]
	v_mfma_f32_16x16x32_bf16 v[24:27], v[192:195], v[224:227], v[24:27]
	v_mfma_f32_16x16x32_bf16 v[20:23], v[200:203], v[224:227], v[20:23]
	v_mfma_f32_16x16x32_bf16 v[8:11], v[192:195], v[232:235], v[8:11]
	v_mfma_f32_16x16x32_bf16 v[4:7], v[200:203], v[232:235], v[4:7]
	s_barrier
	s_add_i32 s13, s13, 2
	s_add_u32 s24, s24, 0x100
	s_addc_u32 s25, s25, 0
	s_add_u32 s11, s11, 0x100
	s_addc_u32 s12, s12, 0
	s_cmp_gt_u32 s13, 29
	s_cbranch_scc0 .LBB0_552
	s_and_b64 vcc, exec, s[52:53]
	s_cbranch_vccz .LBB0_555
.LBB0_555:
	s_ashr_i32 s21, s20, 31
	s_lshl_b64 s[8:9], s[20:21], 2
	v_readlane_b32 s10, v248, 2
	v_readlane_b32 s11, v248, 3
	s_add_u32 s8, s10, s8
	v_mov_b32_e32 v128, v166
	v_mov_b32_e32 v129, v167
	s_addc_u32 s9, s11, s9
	global_load_dword v170, v145, s[8:9]
	v_lshlrev_b32_e32 v162, 3, v129
	v_add_u32_e32 v142, s96, v128
	v_add_u32_e32 v128, s50, v162
	v_ashrrev_i32_e32 v129, 31, v128
	v_lshlrev_b64 v[160:161], 9, v[128:129]
	v_add_u32_e32 v129, 1, v142
	v_cvt_f32_i32_e32 v129, v129
	s_lshl_b32 s20, s2, 8
	v_add_u32_e32 v128, s20, v142
	v_ashrrev_i32_e32 v163, 31, v162
	v_lshl_add_u64 v[164:165], v[162:163], 0, s[50:51]
	s_mov_b32 s19, s61
	s_lshl_b64 s[86:87], s[18:19], 1
	s_add_u32 s36, s94, s86
	s_addc_u32 s37, s95, s87
	s_waitcnt vmcnt(0)
	v_mul_f32_e32 v130, v170, v129
	v_cmp_gt_f32_e32 vcc, s75, v130
	s_nop 1
	v_cndmask_b32_e32 v131, 0, v190, vcc
	v_fmac_f32_e32 v131, v170, v129
	v_exp_f32_e32 v129, v131
	v_cndmask_b32_e32 v130, 0, v189, vcc
	s_andn2_b64 vcc, exec, s[46:47]
	v_ldexp_f32 v143, v129, v130
	v_ashrrev_i32_e32 v129, 31, v128
	v_lshlrev_b64 v[128:129], 7, v[128:129]
	v_lshl_add_u64 v[128:129], v[128:129], 0, v[164:165]
	v_lshl_add_u64 v[172:173], v[128:129], 3, s[16:17]
	global_load_dwordx4 v[128:131], v[172:173], off offset:48
	global_load_dwordx4 v[174:177], v[172:173], off offset:32
	global_load_dwordx4 v[178:181], v[172:173], off offset:16
	global_load_dwordx4 v[192:195], v[172:173], off
	v_add_u32_e32 v228, 16, v142
	v_add_u32_e32 v228, s20, v228
	v_ashrrev_i32_e32 v229, 31, v228
	v_lshlrev_b64 v[228:229], 7, v[228:229]
	v_lshl_add_u64 v[228:229], v[228:229], 0, v[164:165]
	v_lshl_add_u64 v[228:229], v[228:229], 3, s[16:17]
	global_load_dwordx4 v[212:215], v[228:229], off offset:48
	global_load_dwordx4 v[216:219], v[228:229], off offset:32
	global_load_dwordx4 v[220:223], v[228:229], off offset:16
	global_load_dwordx4 v[224:227], v[228:229], off
	v_mov_b32_e32 v172, v124
	v_mov_b32_e32 v173, v120
	v_cndmask_b32_e64 v143, v191, v143, s[44:45]
	s_waitcnt vmcnt(4)
; __device__ __forceinline__ unsigned cvt_pk_bf16(float lo, float hi) { unsigned r; asm volatile("v_cvt_pk_bf16_f32 %0, %1, %2" : "=v"(r) : "v"(lo), "v"(hi)); return r; }
;     __device__ __forceinline__ void operator()(const Acc& acc, const Unit& u, int wr, int wc, int fr, int fq) const {
;     ...
;                 float o1[8], o2[8];
; #pragma unroll
;                 for (int n = 0; n < 2; ++n)
; #pragma unroll
;                     for (int j = 0; j < 4; ++j) { const int e = n * 4 + j; const float co = t[e >> 1][(e & 1) * 2], si = t[e >> 1][(e & 1) * 2 + 1];
;                         const float x1 = acc[ai][0][m][n][j], x2 = acc[ai][1][m][n][j];
;                         o1[e] = (x1 * co - x2 * si) * rs; o2[e] = (x2 * co + x1 * si) * rs; }
;                 bf16_t* rowp = O + u.coff + (size_t)row_in * ldc + wc * 32 + 8 * fq;
;                 u32x4 w; w.x = cvt_pk_bf16(o1[0], o1[1]); w.y = cvt_pk_bf16(o1[2], o1[3]); w.z = cvt_pk_bf16(o1[4], o1[5]); w.w = cvt_pk_bf16(o1[6], o1[7]);
;                 *(u32x4*)rowp = w;
;                 w.x = cvt_pk_bf16(o2[0], o2[1]); w.y = cvt_pk_bf16(o2[2], o2[3]); w.z = cvt_pk_bf16(o2[4], o2[5]); w.w = cvt_pk_bf16(o2[6], o2[7]);
;                 *(u32x4*)(rowp + HALF) = w;
;                 if (mode == 1) {
;                     const float z = exp2f((float)(255 - row_in) * lg);
;                     bf16_t* kz = KZ + u.coff + (size_t)(wc * 32 + 8 * fq) * 256 + row_in;
; #pragma unroll
;                     for (int e = 0; e < 8; e += 2) { const unsigned p1 = cvt_pk_bf16(o1[e] * z, o1[e + 1] * z), p2 = cvt_pk_bf16(o2[e] * z, o2[e + 1] * z);
;                         kz[(size_t)e * 256] = (bf16_t)(p1 & 0xffffu); kz[(size_t)(e + 1) * 256] = (bf16_t)(p1 >> 16);
;                         kz[(size_t)(e + HALF) * 256] = (bf16_t)(p2 & 0xffffu); kz[(size_t)(e + 1 + HALF) * 256] = (bf16_t)(p2 >> 16); }
	v_pk_mul_f32 v[172:173], v[172:173], v[192:193]
	s_nop 0
	v_sub_f32_e32 v171, v172, v173
	v_mov_b32_e32 v172, v120
	v_mov_b32_e32 v173, v124
	v_pk_mul_f32 v[172:173], v[172:173], v[192:193]
	v_mov_b32_e32 v124, v121
	v_add_f32_e32 v120, v173, v172
	v_mul_f32_e32 v172, v120, v143
	v_mov_b32_e32 v120, v125
	v_pk_mul_f32 v[192:193], v[120:121], v[194:195]
	v_pk_mul_f32 v[124:125], v[124:125], v[194:195]
	v_sub_f32_e32 v120, v192, v193
	v_add_f32_e32 v121, v125, v124
	v_mov_b32_e32 v124, v126
	v_mov_b32_e32 v125, v122
	v_mov_b32_e32 v192, v122
	v_mov_b32_e32 v193, v126
	v_pk_mul_f32 v[124:125], v[124:125], v[178:179]
	v_pk_mul_f32 v[178:179], v[192:193], v[178:179]
	v_sub_f32_e32 v124, v124, v125
	v_add_f32_e32 v122, v179, v178
	v_mul_f32_e32 v125, v122, v143
	v_mov_b32_e32 v122, v127
	v_mov_b32_e32 v126, v123
	v_pk_mul_f32 v[178:179], v[122:123], v[180:181]
	v_pk_mul_f32 v[126:127], v[126:127], v[180:181]
	v_sub_f32_e32 v122, v178, v179
	v_add_f32_e32 v123, v127, v126
	v_mov_b32_e32 v126, v116
	v_mov_b32_e32 v127, v112
	v_mov_b32_e32 v178, v112
	v_mov_b32_e32 v179, v116
	v_pk_mul_f32 v[126:127], v[126:127], v[174:175]
	v_pk_mul_f32 v[174:175], v[178:179], v[174:175]
	v_sub_f32_e32 v126, v126, v127
	v_add_f32_e32 v112, v175, v174
	v_mul_f32_e32 v127, v143, v112
	v_mov_b32_e32 v112, v117
	v_mov_b32_e32 v116, v113
	v_pk_mul_f32 v[174:175], v[112:113], v[176:177]
	v_pk_mul_f32 v[116:117], v[116:117], v[176:177]
	v_sub_f32_e32 v112, v174, v175
	v_add_f32_e32 v113, v117, v116
	v_mov_b32_e32 v116, v118
	v_mov_b32_e32 v117, v114
	v_mov_b32_e32 v174, v114
	v_mov_b32_e32 v175, v118
	v_pk_mul_f32 v[116:117], v[116:117], v[128:129]
	v_pk_mul_f32 v[128:129], v[174:175], v[128:129]
	v_sub_f32_e32 v116, v116, v117
	v_add_f32_e32 v114, v129, v128
	v_mul_f32_e32 v117, v143, v114
	v_mov_b32_e32 v114, v119
	v_mov_b32_e32 v118, v115
	v_pk_mul_f32 v[128:129], v[114:115], v[130:131]
	v_pk_mul_f32 v[118:119], v[118:119], v[130:131]
	v_sub_f32_e32 v114, v128, v129
	v_add_f32_e32 v115, v119, v118
	v_mul_f32_e32 v171, v171, v143
	v_mul_f32_e32 v120, v120, v143
	v_mul_f32_e32 v121, v121, v143
	v_mul_f32_e32 v124, v124, v143
	v_mul_f32_e32 v122, v122, v143
	v_mul_f32_e32 v123, v123, v143
	v_mul_f32_e32 v126, v143, v126
	v_mul_f32_e32 v112, v143, v112
	v_mul_f32_e32 v113, v143, v113
	v_mul_f32_e32 v116, v143, v116
	v_mul_f32_e32 v114, v143, v114
	v_mul_f32_e32 v115, v143, v115
	v_ashrrev_i32_e32 v143, 31, v142
	v_lshlrev_b64 v[118:119], s38, v[142:143]
	v_lshl_add_u64 v[118:119], v[118:119], 1, s[36:37]
	v_lshl_add_u64 v[118:119], v[118:119], 0, s[60:61]
	v_lshl_add_u64 v[118:119], v[162:163], 1, v[118:119]
	v_cvt_pk_bf16_f32 v128, v171, v120
	v_cvt_pk_bf16_f32 v129, v124, v122
	v_cvt_pk_bf16_f32 v130, v126, v112
	v_cvt_pk_bf16_f32 v131, v116, v114
	global_store_dwordx4 v[118:119], v[128:131], off
	s_nop 1
	v_cvt_pk_bf16_f32 v128, v172, v121
	v_cvt_pk_bf16_f32 v129, v125, v123
	v_cvt_pk_bf16_f32 v130, v127, v113
	v_cvt_pk_bf16_f32 v131, v117, v115
	global_store_dwordx4 v[118:119], v[128:131], off offset:256
	v_cndmask_b32_e64 v118, 0, 1, s[46:47]
	v_cmp_ne_u32_e64 s[42:43], 1, v118
	s_cbranch_vccnz .LBB0_557
	v_sub_u32_e32 v118, 0xff, v142
	v_cvt_f32_i32_e32 v118, v118
	s_add_u32 s2, s76, s86
	s_addc_u32 s3, s64, s87
	v_mul_f32_e32 v119, v170, v118
	v_cmp_gt_f32_e32 vcc, s75, v119
	s_nop 1
	v_cndmask_b32_e32 v119, 0, v190, vcc
	v_fmac_f32_e32 v119, v170, v118
	v_exp_f32_e32 v128, v119
	v_cndmask_b32_e32 v129, 0, v189, vcc
	v_lshl_add_u64 v[118:119], s[2:3], 0, v[160:161]
	v_lshl_add_u64 v[118:119], v[142:143], 1, v[118:119]
	v_ldexp_f32 v128, v128, v129
	v_mul_f32_e32 v129, v128, v171
	v_mul_f32_e32 v120, v128, v120
	v_cvt_pk_bf16_f32 v120, v129, v120
	v_mul_f32_e32 v129, v128, v172
	v_mul_f32_e32 v121, v128, v121
	v_cvt_pk_bf16_f32 v129, v129, v121
	global_store_short v[118:119], v120, off
	global_store_short_d16_hi v[118:119], v120, off offset:512
	v_add_co_u32_e32 v120, vcc, s33, v118
	v_mul_f32_e32 v122, v128, v122
	s_nop 0
	v_addc_co_u32_e32 v121, vcc, 0, v119, vcc
	global_store_short v[120:121], v129, off
	global_store_short_d16_hi v[120:121], v129, off offset:512
	v_mul_f32_e32 v124, v128, v124
	v_cvt_pk_bf16_f32 v122, v124, v122
	v_mul_f32_e32 v123, v128, v123
	v_mul_f32_e32 v124, v128, v125
	v_cvt_pk_bf16_f32 v123, v124, v123
	global_store_short v[118:119], v122, off offset:1024
	global_store_short_d16_hi v[118:119], v122, off offset:1536
	global_store_short v[120:121], v123, off offset:1024
	global_store_short_d16_hi v[120:121], v123, off offset:1536
	v_mul_f32_e32 v122, v128, v126
	v_mul_f32_e32 v112, v128, v112
	v_mul_f32_e32 v113, v128, v113
	v_cvt_pk_bf16_f32 v112, v122, v112
	v_mul_f32_e32 v122, v128, v127
	v_cvt_pk_bf16_f32 v113, v122, v113
	global_store_short v[118:119], v112, off offset:2048
	global_store_short_d16_hi v[118:119], v112, off offset:2560
	global_store_short v[120:121], v113, off offset:2048
	global_store_short_d16_hi v[120:121], v113, off offset:2560
	v_mul_f32_e32 v112, v128, v116
	v_mul_f32_e32 v113, v128, v114
	v_cvt_pk_bf16_f32 v112, v112, v113
	v_mul_f32_e32 v113, v128, v117
	v_mul_f32_e32 v114, v128, v115
	v_cvt_pk_bf16_f32 v113, v113, v114
	global_store_short v[118:119], v112, off offset:3072
	global_store_short_d16_hi v[118:119], v112, off offset:3584
	global_store_short v[120:121], v113, off offset:3072
	global_store_short_d16_hi v[120:121], v113, off offset:3584
	s_waitcnt vmcnt(18)
	s_branch .Lrq_copy_1

; __device__ __forceinline__ unsigned cvt_pk_bf16(float lo, float hi) { unsigned r; asm volatile("v_cvt_pk_bf16_f32 %0, %1, %2" : "=v"(r) : "v"(lo), "v"(hi)); return r; }
;     __device__ __forceinline__ void operator()(const Acc& acc, const Unit& u, int wr, int wc, int fr, int fq) const {
;     ...
;                 const int row_in = ai * HALF + wr * 64 + m * 16 + fr, s = u.pm * BM + row_in;
;                 const float rs = mode == 0 ? exp2f((float)(row_in + 1) * lg) : 0.0625f;
;                 const f32x4* cp = cs + ((size_t)s * 128 + wc * 32 + 8 * fq) / 2;
;                 f32x4 t[4];
; #pragma unroll
;                 for (int i = 0; i < 4; ++i) t[i] = cp[i];
;                 float o1[8], o2[8];
; #pragma unroll
;                 for (int n = 0; n < 2; ++n)
; #pragma unroll
;                     for (int j = 0; j < 4; ++j) { const int e = n * 4 + j; const float co = t[e >> 1][(e & 1) * 2], si = t[e >> 1][(e & 1) * 2 + 1];
;                         const float x1 = acc[ai][0][m][n][j], x2 = acc[ai][1][m][n][j];
;                         o1[e] = (x1 * co - x2 * si) * rs; o2[e] = (x2 * co + x1 * si) * rs; }
;                 bf16_t* rowp = O + u.coff + (size_t)row_in * ldc + wc * 32 + 8 * fq;
;                 u32x4 w; w.x = cvt_pk_bf16(o1[0], o1[1]); w.y = cvt_pk_bf16(o1[2], o1[3]); w.z = cvt_pk_bf16(o1[4], o1[5]); w.w = cvt_pk_bf16(o1[6], o1[7]);
;                 *(u32x4*)rowp = w;
;                 w.x = cvt_pk_bf16(o2[0], o2[1]); w.y = cvt_pk_bf16(o2[2], o2[3]); w.z = cvt_pk_bf16(o2[4], o2[5]); w.w = cvt_pk_bf16(o2[6], o2[7]);
;                 *(u32x4*)(rowp + HALF) = w;
;                 if (mode == 1) {
;                     const float z = exp2f((float)(255 - row_in) * lg);
;                     bf16_t* kz = KZ + u.coff + (size_t)(wc * 32 + 8 * fq) * 256 + row_in;
; #pragma unroll
;                     for (int e = 0; e < 8; e += 2) { const unsigned p1 = cvt_pk_bf16(o1[e] * z, o1[e + 1] * z), p2 = cvt_pk_bf16(o2[e] * z, o2[e + 1] * z);
;                         kz[(size_t)e * 256] = (bf16_t)(p1 & 0xffffu); kz[(size_t)(e + 1) * 256] = (bf16_t)(p1 >> 16);
;                         kz[(size_t)(e + HALF) * 256] = (bf16_t)(p2 & 0xffffu); kz[(size_t)(e + 1 + HALF) * 256] = (bf16_t)(p2 >> 16); }
.Lrq_copy_1:
	v_add_u32_e32 v113, 17, v142
	v_cvt_f32_i32_e32 v113, v113
	v_add_u32_e32 v116, 16, v142
	v_add_u32_e32 v112, s20, v116
	v_mov_b32_e32 v172, v104
	v_mul_f32_e32 v114, v170, v113
	v_cmp_gt_f32_e32 vcc, s75, v114
	v_mov_b32_e32 v173, v108
	s_nop 0
	v_cndmask_b32_e32 v114, 0, v190, vcc
	v_fmac_f32_e32 v114, v170, v113
	v_exp_f32_e32 v113, v114
	v_cndmask_b32_e32 v114, 0, v189, vcc
	s_and_b64 vcc, exec, s[42:43]
	v_ldexp_f32 v117, v113, v114
	v_ashrrev_i32_e32 v113, 31, v112
	v_lshlrev_b64 v[112:113], 7, v[112:113]
	v_lshl_add_u64 v[112:113], v[112:113], 0, v[164:165]
	v_lshl_add_u64 v[118:119], v[112:113], 3, s[16:17]
	v_mov_b32_e32 v112, v212
	v_mov_b32_e32 v113, v213
	v_mov_b32_e32 v114, v214
	v_mov_b32_e32 v115, v215
	v_mov_b32_e32 v120, v216
	v_mov_b32_e32 v121, v217
	v_mov_b32_e32 v122, v218
	v_mov_b32_e32 v123, v219
	v_mov_b32_e32 v124, v220
	v_mov_b32_e32 v125, v221
	v_mov_b32_e32 v126, v222
	v_mov_b32_e32 v127, v223
	v_mov_b32_e32 v128, v224
	v_mov_b32_e32 v129, v225
	v_mov_b32_e32 v130, v226
	v_mov_b32_e32 v131, v227
	v_add_u32_e32 v228, 32, v142
	v_add_u32_e32 v228, s20, v228
	v_ashrrev_i32_e32 v229, 31, v228
	v_lshlrev_b64 v[228:229], 7, v[228:229]
	v_lshl_add_u64 v[228:229], v[228:229], 0, v[164:165]
	v_lshl_add_u64 v[228:229], v[228:229], 3, s[16:17]
	global_load_dwordx4 v[196:199], v[228:229], off offset:48
	global_load_dwordx4 v[200:203], v[228:229], off offset:32
	global_load_dwordx4 v[204:207], v[228:229], off offset:16
	global_load_dwordx4 v[208:211], v[228:229], off
	v_mov_b32_e32 v118, v108
	v_mov_b32_e32 v119, v104
	v_cndmask_b32_e64 v117, v191, v117, s[44:45]
	v_mov_b32_e32 v108, v105
	v_pk_mul_f32 v[118:119], v[118:119], v[128:129]
	v_pk_mul_f32 v[128:129], v[172:173], v[128:129]
	v_sub_f32_e32 v118, v118, v119
	v_add_f32_e32 v104, v129, v128
	v_mul_f32_e32 v119, v117, v104
	v_mov_b32_e32 v104, v109
	v_pk_mul_f32 v[128:129], v[104:105], v[130:131]
	v_pk_mul_f32 v[108:109], v[108:109], v[130:131]
	v_sub_f32_e32 v104, v128, v129
	v_add_f32_e32 v105, v109, v108
	v_mov_b32_e32 v108, v110
	v_mov_b32_e32 v109, v106
	v_mov_b32_e32 v128, v106
	v_mov_b32_e32 v129, v110
	v_pk_mul_f32 v[108:109], v[108:109], v[124:125]
	v_pk_mul_f32 v[124:125], v[128:129], v[124:125]
	v_sub_f32_e32 v108, v108, v109
	v_add_f32_e32 v106, v125, v124
	v_mul_f32_e32 v109, v117, v106
	v_mov_b32_e32 v106, v111
	v_mov_b32_e32 v110, v107
	v_pk_mul_f32 v[124:125], v[106:107], v[126:127]
	v_pk_mul_f32 v[110:111], v[110:111], v[126:127]
	v_sub_f32_e32 v106, v124, v125
	v_add_f32_e32 v107, v111, v110
	v_mov_b32_e32 v110, v96
	v_mov_b32_e32 v111, v100
	v_mov_b32_e32 v124, v100
	v_mov_b32_e32 v125, v96
	v_pk_mul_f32 v[110:111], v[110:111], v[120:121]
	v_pk_mul_f32 v[120:121], v[124:125], v[120:121]
	v_mov_b32_e32 v100, v97
	v_add_f32_e32 v96, v121, v120
	v_pk_mul_f32 v[120:121], v[100:101], v[122:123]
	v_sub_f32_e32 v110, v110, v111
	v_mul_f32_e32 v111, v117, v96
	v_sub_f32_e32 v96, v120, v121
	v_mul_f32_e32 v100, v117, v96
	v_mov_b32_e32 v96, v101
	v_mov_b32_e32 v120, v98
	v_mov_b32_e32 v121, v102
	v_pk_mul_f32 v[96:97], v[96:97], v[122:123]
	v_pk_mul_f32 v[120:121], v[120:121], v[112:113]
	v_add_f32_e32 v96, v97, v96
	v_sub_f32_e32 v97, v120, v121
	v_mov_b32_e32 v120, v102
	v_mov_b32_e32 v121, v98
	v_pk_mul_f32 v[112:113], v[120:121], v[112:113]
	v_mov_b32_e32 v102, v99
	v_add_f32_e32 v98, v113, v112
	v_pk_mul_f32 v[112:113], v[102:103], v[114:115]
	v_mul_f32_e32 v101, v117, v98
	v_sub_f32_e32 v98, v112, v113
	v_mul_f32_e32 v102, v117, v98
	v_mov_b32_e32 v98, v103
	v_pk_mul_f32 v[98:99], v[98:99], v[114:115]
	v_mul_f32_e32 v118, v117, v118
	v_add_f32_e32 v98, v99, v98
	v_mul_f32_e32 v104, v117, v104
	v_mul_f32_e32 v105, v117, v105
	v_mul_f32_e32 v108, v117, v108
	v_mul_f32_e32 v106, v117, v106
	v_mul_f32_e32 v107, v117, v107
	v_mul_f32_e32 v110, v117, v110
	v_mul_f32_e32 v96, v117, v96
	v_mul_f32_e32 v97, v117, v97
	v_mul_f32_e32 v98, v117, v98
	v_ashrrev_i32_e32 v117, 31, v116
	v_lshlrev_b64 v[112:113], s38, v[116:117]
	v_lshl_add_u64 v[112:113], v[112:113], 1, s[36:37]
	v_lshl_add_u64 v[112:113], v[112:113], 0, s[60:61]
	v_lshl_add_u64 v[116:117], v[162:163], 1, v[112:113]
	v_cvt_pk_bf16_f32 v112, v118, v104
	v_cvt_pk_bf16_f32 v113, v108, v106
	v_cvt_pk_bf16_f32 v114, v110, v100
	v_cvt_pk_bf16_f32 v115, v97, v102
	global_store_dwordx4 v[116:117], v[112:115], off
	s_nop 1
	v_cvt_pk_bf16_f32 v112, v119, v105
	v_cvt_pk_bf16_f32 v113, v109, v107
	v_cvt_pk_bf16_f32 v114, v111, v96
	v_cvt_pk_bf16_f32 v115, v101, v98
	global_store_dwordx4 v[116:117], v[112:115], off offset:256
	s_cmp_lg_u64 s[52:53], 0
	s_cbranch_scc0 .Llate_align_3
	s_barrier
.Llate_align_3:
	s_cbranch_vccnz .LBB0_559
	v_sub_u32_e32 v99, 0xef, v142
	v_cvt_f32_i32_e32 v99, v99
	s_add_u32 s2, s76, s86
	s_addc_u32 s3, s64, s87
	v_lshl_add_u64 v[112:113], s[2:3], 0, v[160:161]
	v_mul_f32_e32 v103, v170, v99
	v_cmp_gt_f32_e32 vcc, s75, v103
	v_lshl_add_u64 v[112:113], v[142:143], 1, v[112:113]
	s_nop 0
	v_cndmask_b32_e32 v103, 0, v190, vcc
	v_fmac_f32_e32 v103, v170, v99
	v_exp_f32_e32 v99, v103
	v_cndmask_b32_e32 v103, 0, v189, vcc
	v_ldexp_f32 v99, v99, v103
	v_mul_f32_e32 v103, v99, v118
	v_mul_f32_e32 v104, v99, v104
	v_cvt_pk_bf16_f32 v103, v103, v104
	v_mul_f32_e32 v104, v99, v119
	v_mul_f32_e32 v105, v99, v105
	v_cvt_pk_bf16_f32 v114, v104, v105
	v_add_co_u32_e32 v104, vcc, s33, v112
	global_store_short v[112:113], v103, off offset:32
	global_store_short_d16_hi v[112:113], v103, off offset:544
	v_addc_co_u32_e32 v105, vcc, 0, v113, vcc
	v_mul_f32_e32 v103, v99, v108
	v_mul_f32_e32 v106, v99, v106
	global_store_short v[104:105], v114, off offset:32
	global_store_short_d16_hi v[104:105], v114, off offset:544
	v_cvt_pk_bf16_f32 v103, v103, v106
	v_mul_f32_e32 v106, v99, v109
	v_mul_f32_e32 v107, v99, v107
	v_cvt_pk_bf16_f32 v106, v106, v107
	global_store_short v[112:113], v103, off offset:1056
	global_store_short_d16_hi v[112:113], v103, off offset:1568
	global_store_short v[104:105], v106, off offset:1056
	global_store_short_d16_hi v[104:105], v106, off offset:1568
	v_mul_f32_e32 v103, v99, v110
	v_mul_f32_e32 v100, v99, v100
	v_mul_f32_e32 v96, v99, v96
	v_cvt_pk_bf16_f32 v100, v103, v100
	v_mul_f32_e32 v103, v99, v111
	v_cvt_pk_bf16_f32 v96, v103, v96
	global_store_short v[112:113], v100, off offset:2080
	global_store_short_d16_hi v[112:113], v100, off offset:2592
	global_store_short v[104:105], v96, off offset:2080
	global_store_short_d16_hi v[104:105], v96, off offset:2592
	v_mul_f32_e32 v96, v99, v97
	v_mul_f32_e32 v97, v99, v102
	v_cvt_pk_bf16_f32 v96, v96, v97
	v_mul_f32_e32 v97, v99, v101
	v_mul_f32_e32 v98, v99, v98
	v_cvt_pk_bf16_f32 v97, v97, v98
	global_store_short v[112:113], v96, off offset:3104
	global_store_short_d16_hi v[112:113], v96, off offset:3616
	global_store_short v[104:105], v97, off offset:3104
	global_store_short_d16_hi v[104:105], v97, off offset:3616
	s_waitcnt vmcnt(18)
	s_branch .Lrq_copy_2

; #define PG8_STAGE(bufoff, gbase, voff) do { _Pragma("unroll") for (int _i = 0; _i < 2; ++_i) \
;         __builtin_amdgcn_global_load_lds((const unsigned*)((const char*)(gbase) + (voff)[_i]), (LAS unsigned*)(lds + (bufoff) + ldsw + _i * 8192), 16, 0, 0); } while (0)
; #define PG8_LDA(dst, b, h) do { _Pragma("unroll") for (int m = 0; m < 4; ++m) _Pragma("unroll") for (int k = 0; k < 2; ++k) dst[m][k] = *(const LAS bf16x8*)(lds + PG8_SA(b, h) + aoff + m * 2048 + k * 1024); } while (0)
; #define PG8_LDB(dst, b, h) do { _Pragma("unroll") for (int n = 0; n < 2; ++n) _Pragma("unroll") for (int k = 0; k < 2; ++k) dst[n][k] = *(const LAS bf16x8*)(lds + PG8_SB(b, h) + boff + n * 2048 + k * 1024); } while (0)
; #define PG8_MMA(ai, bj, At, Bt) do { __builtin_amdgcn_s_setprio(1); _Pragma("unroll") for (int m = 0; m < 4; ++m) _Pragma("unroll") for (int n = 0; n < 2; ++n) _Pragma("unroll") for (int k = 0; k < 2; ++k) \
;         acc[ai][bj][m][n] = __builtin_amdgcn_mfma_f32_16x16x32_bf16(Bt[n][k], At[m][k], acc[ai][bj][m][n], 0, 0, 0); __builtin_amdgcn_s_setprio(0); } while (0)
; template <class Epi, class Map>
; __device__ __forceinline__ void gemm_phase(LAS unsigned char* lds, const Gemm g, const Sched<Map>& S, const Epi& E) {
;     ...
;         const bool has_next = S.next(ui + 1, nxt);
;         const char* nA = has_next ? (const char*)g.A + nxt.aoff : cA; const char* nB = has_next ? (const char*)g.Bt + nxt.boff : cB;
; #pragma unroll 1
;         for (int t = 0; t < nt; t += 2) {
;             const bool last = (t == nt - 2);
;             const char* a1 = cA + (size_t)(t + 1) * kstep;
;             const char* a2 = last ? nA : cA + (size_t)(t + 2) * kstep; const char* b2 = last ? nB : cB + (size_t)(t + 2) * kstep;
;             const char* a3 = a2 + kstep; const char* b3 = b2 + kstep;
;             PG8_LDB(B0, 0, 0); PG8_LDB(B1, 0, 1); PG8_SCHED; PG8_LDA(At, 0, 0); PG8_STAGE(PG8_SA(1, 1), a1 + hstepA, voffA);
;             PG8_WAIT_V(8); PG8_WAIT_L(0); PG8_BAR; PG8_MMA(0, 0, At, B0); PG8_MMA(0, 1, At, B1); PG8_BAR; PG8_SCHED;
;     ...
; #pragma unroll
;         for (int a = 0; a < 2; ++a)
; #pragma unroll
;             for (int b = 0; b < 2; ++b)
; #pragma unroll
;                 for (int m = 0; m < 4; ++m)
; #pragma unroll
;                     for (int n = 0; n < 2; ++n) acc[a][b][m][n] = (f32x4){0.f, 0.f, 0.f, 0.f};
;         cur = nxt; cA = nA; cB = nB; ++ui;
.LBB0_586:
	v_readlane_b32 s12, v246, 9
	s_add_u32 s24, s12, s10
	v_readlane_b32 s12, v246, 10
	s_addc_u32 s25, s12, 0
	s_and_b64 s[12:13], s[42:43], exec
	s_cselect_b32 s12, s25, s31
	s_cselect_b32 s13, s24, s30
	s_add_u32 s28, s78, s9
	s_addc_u32 s29, s79, 0
	s_and_b64 s[14:15], s[42:43], exec
	s_cselect_b32 s14, s29, s35
	s_cselect_b32 s15, s28, s34
	s_add_u32 s30, s30, 0x80080
	s_addc_u32 s31, s31, 0
	s_add_u32 s21, s34, 0x100
	v_mov_b32_e32 v0, 0
	s_addc_u32 s33, s35, 0
	s_mov_b32 s38, -2
	v_mov_b32_e32 v1, v0
	v_mov_b32_e32 v2, v0
	v_mov_b32_e32 v3, v0
	v_mov_b32_e32 v4, v0
	v_mov_b32_e32 v5, v0
	v_mov_b32_e32 v6, v0
	v_mov_b32_e32 v7, v0
	v_mov_b32_e32 v8, v0
	v_mov_b32_e32 v9, v0
	v_mov_b32_e32 v10, v0
	v_mov_b32_e32 v11, v0
	v_mov_b32_e32 v16, v0
	v_mov_b32_e32 v17, v0
	v_mov_b32_e32 v18, v0
	v_mov_b32_e32 v19, v0
	v_mov_b32_e32 v24, v0
	v_mov_b32_e32 v25, v0
	v_mov_b32_e32 v26, v0
	v_mov_b32_e32 v27, v0
	v_mov_b32_e32 v32, v0
	v_mov_b32_e32 v33, v0
	v_mov_b32_e32 v34, v0
	v_mov_b32_e32 v35, v0
	v_mov_b32_e32 v40, v0
	v_mov_b32_e32 v41, v0
	v_mov_b32_e32 v42, v0
	v_mov_b32_e32 v43, v0
	v_mov_b32_e32 v48, v0
	v_mov_b32_e32 v49, v0
	v_mov_b32_e32 v50, v0
	v_mov_b32_e32 v51, v0
	v_mov_b32_e32 v12, v0
	v_mov_b32_e32 v13, v0
	v_mov_b32_e32 v14, v0
	v_mov_b32_e32 v15, v0
	v_mov_b32_e32 v20, v0
	v_mov_b32_e32 v21, v0
	v_mov_b32_e32 v22, v0
	v_mov_b32_e32 v23, v0
	v_mov_b32_e32 v28, v0
	v_mov_b32_e32 v29, v0
	v_mov_b32_e32 v30, v0
	v_mov_b32_e32 v31, v0
	v_mov_b32_e32 v36, v0
	v_mov_b32_e32 v37, v0
	v_mov_b32_e32 v38, v0
	v_mov_b32_e32 v39, v0
	v_mov_b32_e32 v44, v0
	v_mov_b32_e32 v45, v0
	v_mov_b32_e32 v46, v0
	v_mov_b32_e32 v47, v0
	v_mov_b32_e32 v52, v0
	v_mov_b32_e32 v53, v0
	v_mov_b32_e32 v54, v0
	v_mov_b32_e32 v55, v0
	v_mov_b32_e32 v56, v0
	v_mov_b32_e32 v57, v0
	v_mov_b32_e32 v58, v0
	v_mov_b32_e32 v59, v0
	v_mov_b32_e32 v60, v0
	v_mov_b32_e32 v61, v0
	v_mov_b32_e32 v62, v0
	v_mov_b32_e32 v63, v0
	v_mov_b32_e32 v64, v0
	v_mov_b32_e32 v65, v0
	v_mov_b32_e32 v66, v0
	v_mov_b32_e32 v67, v0
	v_mov_b32_e32 v68, v0
	v_mov_b32_e32 v69, v0
	v_mov_b32_e32 v70, v0
	v_mov_b32_e32 v71, v0
	v_mov_b32_e32 v72, v0
	v_mov_b32_e32 v73, v0
	v_mov_b32_e32 v74, v0
	v_mov_b32_e32 v75, v0
	v_mov_b32_e32 v80, v0
	v_mov_b32_e32 v81, v0
	v_mov_b32_e32 v82, v0
	v_mov_b32_e32 v83, v0
	v_mov_b32_e32 v88, v0
	v_mov_b32_e32 v89, v0
	v_mov_b32_e32 v90, v0
	v_mov_b32_e32 v91, v0
	v_mov_b32_e32 v96, v0
	v_mov_b32_e32 v97, v0
	v_mov_b32_e32 v98, v0
	v_mov_b32_e32 v99, v0
	v_mov_b32_e32 v104, v0
	v_mov_b32_e32 v105, v0
	v_mov_b32_e32 v106, v0
	v_mov_b32_e32 v107, v0
	v_mov_b32_e32 v112, v0
	v_mov_b32_e32 v113, v0
	v_mov_b32_e32 v114, v0
	v_mov_b32_e32 v115, v0
	v_mov_b32_e32 v76, v0
	v_mov_b32_e32 v77, v0
	v_mov_b32_e32 v78, v0
	v_mov_b32_e32 v79, v0
	v_mov_b32_e32 v84, v0
	v_mov_b32_e32 v85, v0
	v_mov_b32_e32 v86, v0
	v_mov_b32_e32 v87, v0
	v_mov_b32_e32 v92, v0
	v_mov_b32_e32 v93, v0
	v_mov_b32_e32 v94, v0
	v_mov_b32_e32 v95, v0
	v_mov_b32_e32 v100, v0
	v_mov_b32_e32 v101, v0
	v_mov_b32_e32 v102, v0
	v_mov_b32_e32 v103, v0
	v_mov_b32_e32 v108, v0
	v_mov_b32_e32 v109, v0
	v_mov_b32_e32 v110, v0
	v_mov_b32_e32 v111, v0
	v_mov_b32_e32 v116, v0
	v_mov_b32_e32 v117, v0
	v_mov_b32_e32 v118, v0
	v_mov_b32_e32 v119, v0
	v_mov_b32_e32 v120, v0
	v_mov_b32_e32 v121, v0
	v_mov_b32_e32 v122, v0
	v_mov_b32_e32 v123, v0
	v_mov_b32_e32 v124, v0
	v_mov_b32_e32 v125, v0
	v_mov_b32_e32 v126, v0
	v_mov_b32_e32 v127, v0
.LBB0_587:
	s_add_u32 s34, s30, 0xfff80080
	s_addc_u32 s35, s31, -1
	s_add_i32 s39, 0, 0x10000
	s_cmp_eq_u32 s38, 28
	s_cselect_b32 s37, s12, s35
	s_cselect_b32 s36, s13, s34
	v_add_u32_e32 v138, s39, v142
	s_cselect_b32 s35, s14, s33
	s_cselect_b32 s34, s15, s21
	s_add_i32 s46, 0, 0x14000
	ds_read_b128 v[160:163], v138
	ds_read_b128 v[164:167], v138 offset:1024
	ds_read_b128 v[168:171], v138 offset:2048
	ds_read_b128 v[172:175], v138 offset:3072
	v_add_u32_e32 v138, s46, v142
	ds_read_b128 v[176:179], v138
	ds_read_b128 v[192:195], v138 offset:1024
	ds_read_b128 v[196:199], v138 offset:2048
	ds_read_b128 v[200:203], v138 offset:3072
	v_lshl_add_u64 v[138:139], s[30:31], 0, v[134:135]
	s_add_i32 m0, s1, 0xc000
	ds_read_b128 v[204:207], v143
	ds_read_b128 v[208:211], v143 offset:1024
	ds_read_b128 v[212:215], v143 offset:2048
	ds_read_b128 v[216:219], v143 offset:3072
	ds_read_b128 v[220:223], v143 offset:4096
	ds_read_b128 v[224:227], v143 offset:5120
	ds_read_b128 v[228:231], v143 offset:6144
	ds_read_b128 v[232:235], v143 offset:7168
	global_load_lds_dwordx4 v[138:139], off
	v_lshl_add_u64 v[138:139], s[30:31], 0, v[136:137]
	s_add_i32 m0, s1, 0xe000
	s_nop 0
	global_load_lds_dwordx4 v[138:139], off
	s_waitcnt vmcnt(8)
	s_waitcnt lgkmcnt(0)
	s_barrier
; #define PG8_STAGE(bufoff, gbase, voff) do { _Pragma("unroll") for (int _i = 0; _i < 2; ++_i) \
;         __builtin_amdgcn_global_load_lds((const unsigned*)((const char*)(gbase) + (voff)[_i]), (LAS unsigned*)(lds + (bufoff) + ldsw + _i * 8192), 16, 0, 0); } while (0)
; #define PG8_LDA(dst, b, h) do { _Pragma("unroll") for (int m = 0; m < 4; ++m) _Pragma("unroll") for (int k = 0; k < 2; ++k) dst[m][k] = *(const LAS bf16x8*)(lds + PG8_SA(b, h) + aoff + m * 2048 + k * 1024); } while (0)
; #define PG8_LDB(dst, b, h) do { _Pragma("unroll") for (int n = 0; n < 2; ++n) _Pragma("unroll") for (int k = 0; k < 2; ++k) dst[n][k] = *(const LAS bf16x8*)(lds + PG8_SB(b, h) + boff + n * 2048 + k * 1024); } while (0)
; #define PG8_MMA(ai, bj, At, Bt) do { __builtin_amdgcn_s_setprio(1); _Pragma("unroll") for (int m = 0; m < 4; ++m) _Pragma("unroll") for (int n = 0; n < 2; ++n) _Pragma("unroll") for (int k = 0; k < 2; ++k) \
;         acc[ai][bj][m][n] = __builtin_amdgcn_mfma_f32_16x16x32_bf16(Bt[n][k], At[m][k], acc[ai][bj][m][n], 0, 0, 0); __builtin_amdgcn_s_setprio(0); } while (0)
; #define PG8_WAIT_V(n) asm volatile("s_waitcnt vmcnt(" #n ")" ::: "memory")
; #define PG8_WAIT_L(n) asm volatile("s_waitcnt lgkmcnt(" #n ")" ::: "memory")
; #define PG8_BAR __builtin_amdgcn_s_barrier()
; #define PG8_SCHED __builtin_amdgcn_sched_barrier(0)
; template <class Epi, class Map>
; __device__ __forceinline__ void gemm_phase(LAS unsigned char* lds, const Gemm g, const Sched<Map>& S, const Epi& E) {
;     ...
;             PG8_WAIT_V(8); PG8_WAIT_L(0); PG8_BAR; PG8_MMA(0, 0, At, B0); PG8_MMA(0, 1, At, B1); PG8_BAR; PG8_SCHED;
;             PG8_LDA(At, 0, 1); PG8_STAGE(PG8_SB(0, 0), b2, voffB); PG8_STAGE(PG8_SB(0, 1), b2 + hstepB, voffB); PG8_STAGE(PG8_SA(0, 0), a2, voffA);
;             PG8_WAIT_V(8); PG8_WAIT_L(0); PG8_BAR; PG8_MMA(1, 0, At, B0); PG8_MMA(1, 1, At, B1); PG8_BAR; PG8_SCHED;
;             PG8_LDB(B0, 1, 0); PG8_LDB(B1, 1, 1); PG8_SCHED; PG8_LDA(At, 1, 0); PG8_STAGE(PG8_SA(0, 1), a2 + hstepA, voffA);
	s_waitcnt lgkmcnt(0)
	v_mfma_f32_16x16x32_bf16 v[124:127], v[160:163], v[204:207], v[124:127]
	v_mfma_f32_16x16x32_bf16 v[120:123], v[168:171], v[204:207], v[120:123]
	v_mfma_f32_16x16x32_bf16 v[116:119], v[160:163], v[212:215], v[116:119]
	v_mfma_f32_16x16x32_bf16 v[108:111], v[168:171], v[212:215], v[108:111]
	v_mfma_f32_16x16x32_bf16 v[100:103], v[160:163], v[220:223], v[100:103]
	v_mfma_f32_16x16x32_bf16 v[92:95], v[168:171], v[220:223], v[92:95]
	v_mfma_f32_16x16x32_bf16 v[84:87], v[160:163], v[228:231], v[84:87]
	v_mfma_f32_16x16x32_bf16 v[76:79], v[168:171], v[228:231], v[76:79]
	v_mfma_f32_16x16x32_bf16 v[124:127], v[164:167], v[208:211], v[124:127]
	v_mfma_f32_16x16x32_bf16 v[120:123], v[172:175], v[208:211], v[120:123]
	v_mfma_f32_16x16x32_bf16 v[116:119], v[164:167], v[216:219], v[116:119]
	v_mfma_f32_16x16x32_bf16 v[108:111], v[172:175], v[216:219], v[108:111]
	v_mfma_f32_16x16x32_bf16 v[100:103], v[164:167], v[224:227], v[100:103]
	v_mfma_f32_16x16x32_bf16 v[92:95], v[172:175], v[224:227], v[92:95]
	v_mfma_f32_16x16x32_bf16 v[84:87], v[164:167], v[232:235], v[84:87]
	v_mfma_f32_16x16x32_bf16 v[76:79], v[172:175], v[232:235], v[76:79]
	v_mfma_f32_16x16x32_bf16 v[112:115], v[176:179], v[204:207], v[112:115]
	v_mfma_f32_16x16x32_bf16 v[104:107], v[196:199], v[204:207], v[104:107]
	v_mfma_f32_16x16x32_bf16 v[96:99], v[176:179], v[212:215], v[96:99]
	v_mfma_f32_16x16x32_bf16 v[88:91], v[196:199], v[212:215], v[88:91]
	v_mfma_f32_16x16x32_bf16 v[80:83], v[176:179], v[220:223], v[80:83]
	v_mfma_f32_16x16x32_bf16 v[72:75], v[196:199], v[220:223], v[72:75]
	v_mfma_f32_16x16x32_bf16 v[68:71], v[176:179], v[228:231], v[68:71]
	v_mfma_f32_16x16x32_bf16 v[64:67], v[196:199], v[228:231], v[64:67]
	v_mfma_f32_16x16x32_bf16 v[112:115], v[192:195], v[208:211], v[112:115]
	v_mfma_f32_16x16x32_bf16 v[104:107], v[200:203], v[208:211], v[104:107]
	v_mfma_f32_16x16x32_bf16 v[96:99], v[192:195], v[216:219], v[96:99]
	v_mfma_f32_16x16x32_bf16 v[88:91], v[200:203], v[216:219], v[88:91]
	v_mfma_f32_16x16x32_bf16 v[80:83], v[192:195], v[224:227], v[80:83]
	v_mfma_f32_16x16x32_bf16 v[72:75], v[200:203], v[224:227], v[72:75]
	v_mfma_f32_16x16x32_bf16 v[68:71], v[192:195], v[232:235], v[68:71]
	v_mfma_f32_16x16x32_bf16 v[64:67], v[200:203], v[232:235], v[64:67]
	s_barrier
	s_add_i32 s39, s39, s0
	v_lshl_add_u64 v[138:139], s[34:35], 0, v[144:145]
	s_mov_b32 m0, s39
	ds_read_b128 v[204:207], v143 offset:16384
	ds_read_b128 v[208:211], v143 offset:17408
	ds_read_b128 v[212:215], v143 offset:18432
	ds_read_b128 v[216:219], v143 offset:19456
	ds_read_b128 v[220:223], v143 offset:20480
	ds_read_b128 v[224:227], v143 offset:21504
	ds_read_b128 v[228:231], v143 offset:22528
	ds_read_b128 v[232:235], v143 offset:23552
	global_load_lds_dwordx4 v[138:139], off
	s_add_i32 m0, s39, 0x2000
	s_add_u32 s44, s34, 0x80000
	v_lshl_add_u64 v[180:181], s[34:35], 0, v[128:129]
	s_addc_u32 s45, s35, 0
	s_add_i32 s39, s46, s0
	global_load_lds_dwordx4 v[180:181], off
	v_lshl_add_u64 v[236:237], s[44:45], 0, v[144:145]
	s_mov_b32 m0, s39
	v_lshl_add_u64 v[238:239], s[36:37], 0, v[130:131]
	global_load_lds_dwordx4 v[236:237], off
	v_lshl_add_u64 v[236:237], s[44:45], 0, v[128:129]
	s_add_i32 m0, s39, 0x2000
	s_nop 0
	global_load_lds_dwordx4 v[236:237], off
	v_lshl_add_u64 v[236:237], s[36:37], 0, v[132:133]
	s_mov_b32 m0, s1
	s_nop 0
	global_load_lds_dwordx4 v[236:237], off
	s_mov_b32 m0, s2
	s_nop 0
	global_load_lds_dwordx4 v[238:239], off
	s_waitcnt vmcnt(8)
	s_waitcnt lgkmcnt(0)
	s_barrier
	s_waitcnt lgkmcnt(0)
	v_mfma_f32_16x16x32_bf16 v[60:63], v[160:163], v[204:207], v[60:63]
	v_mfma_f32_16x16x32_bf16 v[56:59], v[168:171], v[204:207], v[56:59]
	v_mfma_f32_16x16x32_bf16 v[52:55], v[160:163], v[212:215], v[52:55]
	v_mfma_f32_16x16x32_bf16 v[44:47], v[168:171], v[212:215], v[44:47]
	v_mfma_f32_16x16x32_bf16 v[36:39], v[160:163], v[220:223], v[36:39]
	v_mfma_f32_16x16x32_bf16 v[28:31], v[168:171], v[220:223], v[28:31]
	v_mfma_f32_16x16x32_bf16 v[20:23], v[160:163], v[228:231], v[20:23]
	v_mfma_f32_16x16x32_bf16 v[12:15], v[168:171], v[228:231], v[12:15]
	v_mfma_f32_16x16x32_bf16 v[60:63], v[164:167], v[208:211], v[60:63]
	v_mfma_f32_16x16x32_bf16 v[56:59], v[172:175], v[208:211], v[56:59]
	v_mfma_f32_16x16x32_bf16 v[52:55], v[164:167], v[216:219], v[52:55]
	v_mfma_f32_16x16x32_bf16 v[44:47], v[172:175], v[216:219], v[44:47]
	v_mfma_f32_16x16x32_bf16 v[36:39], v[164:167], v[224:227], v[36:39]
	v_mfma_f32_16x16x32_bf16 v[28:31], v[172:175], v[224:227], v[28:31]
	v_mfma_f32_16x16x32_bf16 v[20:23], v[164:167], v[232:235], v[20:23]
	v_mfma_f32_16x16x32_bf16 v[12:15], v[172:175], v[232:235], v[12:15]
	v_mfma_f32_16x16x32_bf16 v[48:51], v[176:179], v[204:207], v[48:51]
	v_mfma_f32_16x16x32_bf16 v[40:43], v[196:199], v[204:207], v[40:43]
	v_mfma_f32_16x16x32_bf16 v[32:35], v[176:179], v[212:215], v[32:35]
	v_mfma_f32_16x16x32_bf16 v[24:27], v[196:199], v[212:215], v[24:27]
	v_mfma_f32_16x16x32_bf16 v[16:19], v[176:179], v[220:223], v[16:19]
	v_mfma_f32_16x16x32_bf16 v[8:11], v[196:199], v[220:223], v[8:11]
	v_mfma_f32_16x16x32_bf16 v[4:7], v[176:179], v[228:231], v[4:7]
	v_mfma_f32_16x16x32_bf16 v[0:3], v[196:199], v[228:231], v[0:3]
	v_mfma_f32_16x16x32_bf16 v[48:51], v[192:195], v[208:211], v[48:51]
	v_mfma_f32_16x16x32_bf16 v[40:43], v[200:203], v[208:211], v[40:43]
	v_mfma_f32_16x16x32_bf16 v[32:35], v[192:195], v[216:219], v[32:35]
	v_mfma_f32_16x16x32_bf16 v[24:27], v[200:203], v[216:219], v[24:27]
	v_mfma_f32_16x16x32_bf16 v[16:19], v[192:195], v[224:227], v[16:19]
	v_mfma_f32_16x16x32_bf16 v[8:11], v[200:203], v[224:227], v[8:11]
	v_mfma_f32_16x16x32_bf16 v[4:7], v[192:195], v[232:235], v[4:7]
	v_mfma_f32_16x16x32_bf16 v[0:3], v[200:203], v[232:235], v[0:3]
	s_barrier
; #define PG8_STAGE(bufoff, gbase, voff) do { _Pragma("unroll") for (int _i = 0; _i < 2; ++_i) \
;         __builtin_amdgcn_global_load_lds((const unsigned*)((const char*)(gbase) + (voff)[_i]), (LAS unsigned*)(lds + (bufoff) + ldsw + _i * 8192), 16, 0, 0); } while (0)
; #define PG8_LDA(dst, b, h) do { _Pragma("unroll") for (int m = 0; m < 4; ++m) _Pragma("unroll") for (int k = 0; k < 2; ++k) dst[m][k] = *(const LAS bf16x8*)(lds + PG8_SA(b, h) + aoff + m * 2048 + k * 1024); } while (0)
; #define PG8_LDB(dst, b, h) do { _Pragma("unroll") for (int n = 0; n < 2; ++n) _Pragma("unroll") for (int k = 0; k < 2; ++k) dst[n][k] = *(const LAS bf16x8*)(lds + PG8_SB(b, h) + boff + n * 2048 + k * 1024); } while (0)
; #define PG8_MMA(ai, bj, At, Bt) do { __builtin_amdgcn_s_setprio(1); _Pragma("unroll") for (int m = 0; m < 4; ++m) _Pragma("unroll") for (int n = 0; n < 2; ++n) _Pragma("unroll") for (int k = 0; k < 2; ++k) \
;         acc[ai][bj][m][n] = __builtin_amdgcn_mfma_f32_16x16x32_bf16(Bt[n][k], At[m][k], acc[ai][bj][m][n], 0, 0, 0); __builtin_amdgcn_s_setprio(0); } while (0)
; #define PG8_WAIT_V(n) asm volatile("s_waitcnt vmcnt(" #n ")" ::: "memory")
; #define PG8_WAIT_L(n) asm volatile("s_waitcnt lgkmcnt(" #n ")" ::: "memory")
; #define PG8_BAR __builtin_amdgcn_s_barrier()
; #define PG8_SCHED __builtin_amdgcn_sched_barrier(0)
; template <class Epi, class Map>
; __device__ __forceinline__ void gemm_phase(LAS unsigned char* lds, const Gemm g, const Sched<Map>& S, const Epi& E) {
;     ...
;             PG8_LDB(B0, 1, 0); PG8_LDB(B1, 1, 1); PG8_SCHED; PG8_LDA(At, 1, 0); PG8_STAGE(PG8_SA(0, 1), a2 + hstepA, voffA);
;             PG8_WAIT_V(8); PG8_WAIT_L(0); PG8_BAR; PG8_MMA(0, 0, At, B0); PG8_MMA(0, 1, At, B1); PG8_BAR; PG8_SCHED;
;             PG8_LDA(At, 1, 1); PG8_STAGE(PG8_SB(1, 0), b3, voffB); PG8_STAGE(PG8_SB(1, 1), b3 + hstepB, voffB); PG8_STAGE(PG8_SA(1, 0), a3, voffA);
	s_add_i32 s39, 0, 0x18000
	s_add_i32 s44, 0, 0x1c000
	v_add_u32_e32 v172, s39, v142
	v_add_u32_e32 v200, s44, v142
	ds_read_b128 v[160:163], v172
	ds_read_b128 v[164:167], v172 offset:1024
	ds_read_b128 v[168:171], v172 offset:2048
	ds_read_b128 v[172:175], v172 offset:3072
	ds_read_b128 v[176:179], v200
	ds_read_b128 v[192:195], v200 offset:1024
	ds_read_b128 v[196:199], v200 offset:2048
	ds_read_b128 v[200:203], v200 offset:3072
	s_add_u32 s36, s36, 0x80000
	s_addc_u32 s37, s37, 0
	s_mov_b32 m0, s3
	v_lshl_add_u64 v[240:241], s[36:37], 0, v[132:133]
	ds_read_b128 v[204:207], v143 offset:32768
	ds_read_b128 v[208:211], v143 offset:33792
	ds_read_b128 v[212:215], v143 offset:34816
	ds_read_b128 v[216:219], v143 offset:35840
	ds_read_b128 v[220:223], v143 offset:36864
	ds_read_b128 v[224:227], v143 offset:37888
	ds_read_b128 v[228:231], v143 offset:38912
	ds_read_b128 v[232:235], v143 offset:39936
	global_load_lds_dwordx4 v[240:241], off
	v_lshl_add_u64 v[240:241], s[36:37], 0, v[130:131]
	s_mov_b32 m0, s4
	s_nop 0
	global_load_lds_dwordx4 v[240:241], off
	s_waitcnt vmcnt(8)
	s_waitcnt lgkmcnt(0)
	s_barrier
	s_waitcnt lgkmcnt(0)
	v_mfma_f32_16x16x32_bf16 v[124:127], v[160:163], v[204:207], v[124:127]
	v_mfma_f32_16x16x32_bf16 v[120:123], v[168:171], v[204:207], v[120:123]
	v_mfma_f32_16x16x32_bf16 v[116:119], v[160:163], v[212:215], v[116:119]
	v_mfma_f32_16x16x32_bf16 v[108:111], v[168:171], v[212:215], v[108:111]
	v_mfma_f32_16x16x32_bf16 v[100:103], v[160:163], v[220:223], v[100:103]
	v_mfma_f32_16x16x32_bf16 v[92:95], v[168:171], v[220:223], v[92:95]
	v_mfma_f32_16x16x32_bf16 v[84:87], v[160:163], v[228:231], v[84:87]
	v_mfma_f32_16x16x32_bf16 v[76:79], v[168:171], v[228:231], v[76:79]
	v_mfma_f32_16x16x32_bf16 v[124:127], v[164:167], v[208:211], v[124:127]
	v_mfma_f32_16x16x32_bf16 v[120:123], v[172:175], v[208:211], v[120:123]
	v_mfma_f32_16x16x32_bf16 v[116:119], v[164:167], v[216:219], v[116:119]
	v_mfma_f32_16x16x32_bf16 v[108:111], v[172:175], v[216:219], v[108:111]
	v_mfma_f32_16x16x32_bf16 v[100:103], v[164:167], v[224:227], v[100:103]
	v_mfma_f32_16x16x32_bf16 v[92:95], v[172:175], v[224:227], v[92:95]
	v_mfma_f32_16x16x32_bf16 v[84:87], v[164:167], v[232:235], v[84:87]
	v_mfma_f32_16x16x32_bf16 v[76:79], v[172:175], v[232:235], v[76:79]
	v_mfma_f32_16x16x32_bf16 v[112:115], v[176:179], v[204:207], v[112:115]
	v_mfma_f32_16x16x32_bf16 v[104:107], v[196:199], v[204:207], v[104:107]
	v_mfma_f32_16x16x32_bf16 v[96:99], v[176:179], v[212:215], v[96:99]
	v_mfma_f32_16x16x32_bf16 v[88:91], v[196:199], v[212:215], v[88:91]
	v_mfma_f32_16x16x32_bf16 v[80:83], v[176:179], v[220:223], v[80:83]
	v_mfma_f32_16x16x32_bf16 v[72:75], v[196:199], v[220:223], v[72:75]
	v_mfma_f32_16x16x32_bf16 v[68:71], v[176:179], v[228:231], v[68:71]
	v_mfma_f32_16x16x32_bf16 v[64:67], v[196:199], v[228:231], v[64:67]
	v_mfma_f32_16x16x32_bf16 v[112:115], v[192:195], v[208:211], v[112:115]
	v_mfma_f32_16x16x32_bf16 v[104:107], v[200:203], v[208:211], v[104:107]
	v_mfma_f32_16x16x32_bf16 v[96:99], v[192:195], v[216:219], v[96:99]
	v_mfma_f32_16x16x32_bf16 v[88:91], v[200:203], v[216:219], v[88:91]
	v_mfma_f32_16x16x32_bf16 v[80:83], v[192:195], v[224:227], v[80:83]
	v_mfma_f32_16x16x32_bf16 v[72:75], v[200:203], v[224:227], v[72:75]
	v_mfma_f32_16x16x32_bf16 v[68:71], v[192:195], v[232:235], v[68:71]
	v_mfma_f32_16x16x32_bf16 v[64:67], v[200:203], v[232:235], v[64:67]
	s_barrier
	s_add_i32 s36, s39, s0
	v_lshl_add_u64 v[138:139], v[138:139], 0, s[82:83]
	s_mov_b32 m0, s36
	ds_read_b128 v[204:207], v143 offset:49152
	ds_read_b128 v[208:211], v143 offset:50176
	ds_read_b128 v[212:215], v143 offset:51200
	ds_read_b128 v[216:219], v143 offset:52224
	ds_read_b128 v[220:223], v143 offset:53248
	ds_read_b128 v[224:227], v143 offset:54272
	ds_read_b128 v[228:231], v143 offset:55296
	ds_read_b128 v[232:235], v143 offset:56320
	global_load_lds_dwordx4 v[138:139], off
	s_add_i32 m0, s36, 0x2000
	s_add_u32 s34, s34, 0x80080
	v_lshl_add_u64 v[138:139], v[180:181], 0, s[82:83]
	s_addc_u32 s35, s35, 0
	s_add_i32 s36, s44, s0
	global_load_lds_dwordx4 v[138:139], off
	v_lshl_add_u64 v[138:139], s[34:35], 0, v[144:145]
	s_mov_b32 m0, s36
	s_nop 0
	global_load_lds_dwordx4 v[138:139], off
	v_lshl_add_u64 v[138:139], s[34:35], 0, v[128:129]
	s_add_i32 m0, s36, 0x2000
	s_nop 0
	global_load_lds_dwordx4 v[138:139], off
	v_lshl_add_u64 v[138:139], v[236:237], 0, s[82:83]
	s_mov_b32 m0, s6
	s_nop 0
	global_load_lds_dwordx4 v[138:139], off
	v_lshl_add_u64 v[138:139], v[238:239], 0, s[82:83]
	s_mov_b32 m0, s7
	s_nop 0
	global_load_lds_dwordx4 v[138:139], off
	s_waitcnt vmcnt(8)
	s_waitcnt lgkmcnt(0)
	s_barrier
; __device__ __forceinline__ unsigned cvt_pk_bf16(float lo, float hi) { unsigned r; asm volatile("v_cvt_pk_bf16_f32 %0, %1, %2" : "=v"(r) : "v"(lo), "v"(hi)); return r; }
; __device__ __forceinline__ float silu_f(float v) { return v / (1.0f + __expf(-v)); }
; #define PG8_WAIT_V(n) asm volatile("s_waitcnt vmcnt(" #n ")" ::: "memory")
; #define PG8_WAIT_L(n) asm volatile("s_waitcnt lgkmcnt(" #n ")" ::: "memory")
; #define PG8_BAR __builtin_amdgcn_s_barrier()
; #define PG8_SCHED __builtin_amdgcn_sched_barrier(0)
; template <class Epi, class Map>
; __device__ __forceinline__ void gemm_phase(LAS unsigned char* lds, const Gemm g, const Sched<Map>& S, const Epi& E) {
;     ...
;             PG8_WAIT_V(8); PG8_WAIT_L(0); PG8_BAR; PG8_MMA(1, 0, At, B0); PG8_MMA(1, 1, At, B1); PG8_BAR; PG8_SCHED;
;         }
;         if (wr == 0) PG8_BAR;
;         E(acc, cur, wr, wc, fr, fq);
;         if (!has_next) break;
; #pragma unroll
;         for (int a = 0; a < 2; ++a)
; #pragma unroll
;             for (int b = 0; b < 2; ++b)
; #pragma unroll
;                 for (int m = 0; m < 4; ++m)
; #pragma unroll
;                     for (int n = 0; n < 2; ++n) acc[a][b][m][n] = (f32x4){0.f, 0.f, 0.f, 0.f};
;         cur = nxt; cA = nA; cB = nB; ++ui;
;         if (wr == 1) PG8_BAR;
;     __device__ __forceinline__ void operator()(const Acc& acc, const Unit& u, int wr, int wc, int fr, int fq) const {
;     ...
;         bf16_t* base = O + u.coff + (size_t)(wr * 64 + fr) * ldc + wc * 32 + 8 * fq;
; #pragma unroll
;         for (int ai = 0; ai < 2; ++ai)
; #pragma unroll
;             for (int m = 0; m < 4; ++m) { bf16_t* rowp = base + (size_t)(ai * HALF + m * 16) * ldc;
; #pragma unroll
;                 for (int bj = 0; bj < 2; ++bj) { f32x4 v0 = acc[ai][bj][m][0], v1 = acc[ai][bj][m][1];
;                     if (ACT == 1) {
; #pragma unroll
;                         for (int j = 0; j < 4; ++j) { v0[j] = silu_f(v0[j]); v1[j] = silu_f(v1[j]); } }
;                     if (ACT == 2) {
; #pragma unroll
;                         for (int j = 0; j < 4; ++j) { const float a = fmaxf(v0[j], 0.f), b = fmaxf(v1[j], 0.f); v0[j] = a * a; v1[j] = b * b; } }
;                     u32x4 w; w.x = cvt_pk_bf16(v0[0], v0[1]); w.y = cvt_pk_bf16(v0[2], v0[3]); w.z = cvt_pk_bf16(v1[0], v1[1]); w.w = cvt_pk_bf16(v1[2], v1[3]);
;                     *(u32x4*)(rowp + bj * HALF) = w; } }
	s_waitcnt lgkmcnt(0)
	v_mfma_f32_16x16x32_bf16 v[60:63], v[160:163], v[204:207], v[60:63]
	v_mfma_f32_16x16x32_bf16 v[56:59], v[168:171], v[204:207], v[56:59]
	v_mfma_f32_16x16x32_bf16 v[52:55], v[160:163], v[212:215], v[52:55]
	v_mfma_f32_16x16x32_bf16 v[44:47], v[168:171], v[212:215], v[44:47]
	v_mfma_f32_16x16x32_bf16 v[36:39], v[160:163], v[220:223], v[36:39]
	v_mfma_f32_16x16x32_bf16 v[28:31], v[168:171], v[220:223], v[28:31]
	v_mfma_f32_16x16x32_bf16 v[20:23], v[160:163], v[228:231], v[20:23]
	v_mfma_f32_16x16x32_bf16 v[12:15], v[168:171], v[228:231], v[12:15]
	v_mfma_f32_16x16x32_bf16 v[60:63], v[164:167], v[208:211], v[60:63]
	v_mfma_f32_16x16x32_bf16 v[56:59], v[172:175], v[208:211], v[56:59]
	v_mfma_f32_16x16x32_bf16 v[52:55], v[164:167], v[216:219], v[52:55]
	v_mfma_f32_16x16x32_bf16 v[44:47], v[172:175], v[216:219], v[44:47]
	v_mfma_f32_16x16x32_bf16 v[36:39], v[164:167], v[224:227], v[36:39]
	v_mfma_f32_16x16x32_bf16 v[28:31], v[172:175], v[224:227], v[28:31]
	v_mfma_f32_16x16x32_bf16 v[20:23], v[164:167], v[232:235], v[20:23]
	v_mfma_f32_16x16x32_bf16 v[12:15], v[172:175], v[232:235], v[12:15]
	v_mfma_f32_16x16x32_bf16 v[48:51], v[176:179], v[204:207], v[48:51]
	v_mfma_f32_16x16x32_bf16 v[40:43], v[196:199], v[204:207], v[40:43]
	v_mfma_f32_16x16x32_bf16 v[32:35], v[176:179], v[212:215], v[32:35]
	v_mfma_f32_16x16x32_bf16 v[24:27], v[196:199], v[212:215], v[24:27]
	v_mfma_f32_16x16x32_bf16 v[16:19], v[176:179], v[220:223], v[16:19]
	v_mfma_f32_16x16x32_bf16 v[8:11], v[196:199], v[220:223], v[8:11]
	v_mfma_f32_16x16x32_bf16 v[4:7], v[176:179], v[228:231], v[4:7]
	v_mfma_f32_16x16x32_bf16 v[0:3], v[196:199], v[228:231], v[0:3]
	v_mfma_f32_16x16x32_bf16 v[48:51], v[192:195], v[208:211], v[48:51]
	v_mfma_f32_16x16x32_bf16 v[40:43], v[200:203], v[208:211], v[40:43]
	v_mfma_f32_16x16x32_bf16 v[32:35], v[192:195], v[216:219], v[32:35]
	v_mfma_f32_16x16x32_bf16 v[24:27], v[200:203], v[216:219], v[24:27]
	v_mfma_f32_16x16x32_bf16 v[16:19], v[192:195], v[224:227], v[16:19]
	v_mfma_f32_16x16x32_bf16 v[8:11], v[200:203], v[224:227], v[8:11]
	v_mfma_f32_16x16x32_bf16 v[4:7], v[192:195], v[232:235], v[4:7]
	v_mfma_f32_16x16x32_bf16 v[0:3], v[200:203], v[232:235], v[0:3]
	s_barrier
	s_add_i32 s38, s38, 2
	s_add_u32 s30, s30, 0x100
	s_addc_u32 s31, s31, 0
	s_add_u32 s21, s21, 0x100
	s_addc_u32 s33, s33, 0
	s_cmp_gt_u32 s38, 29
	s_cbranch_scc0 .LBB0_587
	s_and_b64 vcc, exec, s[18:19]
	s_cbranch_vccz .LBB0_590
.LBB0_590:
	v_mov_b32_e32 v160, v141
	v_mov_b32_e32 v138, v140
	s_lshl_b64 s[12:13], s[60:61], 1
	v_readlane_b32 s14, v246, 43
	v_add_u32_e32 v138, s5, v138
	s_add_u32 s12, s14, s12
	v_readlane_b32 s14, v246, 44
	v_ashrrev_i32_e32 v139, 31, v138
	s_addc_u32 s13, s14, s13
	v_lshlrev_b64 v[138:139], 10, v[138:139]
	v_lshl_add_u64 v[138:139], s[12:13], 0, v[138:139]
	s_mov_b32 s21, s61
	v_lshlrev_b32_e32 v160, 3, v160
	v_lshl_add_u64 v[138:139], v[138:139], 0, s[20:21]
	v_ashrrev_i32_e32 v161, 31, v160
	v_lshl_add_u64 v[138:139], v[160:161], 1, v[138:139]
	s_movk_i32 s12, 0x4000
	v_cvt_pk_bf16_f32 v124, v124, v125
	v_cvt_pk_bf16_f32 v125, v126, v127
	v_cvt_pk_bf16_f32 v126, v120, v121
	v_cvt_pk_bf16_f32 v127, v122, v123
	global_store_dwordx4 v[138:139], v[124:127], off
	v_cvt_pk_bf16_f32 v112, v112, v113
	v_cvt_pk_bf16_f32 v113, v114, v115
	v_cvt_pk_bf16_f32 v114, v104, v105
	v_cvt_pk_bf16_f32 v115, v106, v107
	global_store_dwordx4 v[138:139], v[112:115], off offset:256
	v_cvt_pk_bf16_f32 v104, v116, v117
	v_cvt_pk_bf16_f32 v105, v118, v119
	v_cvt_pk_bf16_f32 v106, v108, v109
	v_add_co_u32_e32 v108, vcc, s12, v138
	s_mov_b32 s12, 0x8000
	s_nop 0
	v_addc_co_u32_e32 v109, vcc, 0, v139, vcc
	v_cvt_pk_bf16_f32 v107, v110, v111
	global_store_dwordx4 v[108:109], v[104:107], off
	v_cvt_pk_bf16_f32 v96, v96, v97
	v_cvt_pk_bf16_f32 v97, v98, v99
	v_cvt_pk_bf16_f32 v98, v88, v89
	v_cvt_pk_bf16_f32 v99, v90, v91
	global_store_dwordx4 v[108:109], v[96:99], off offset:256
	s_cmp_lg_u64 s[18:19], 0
	s_cbranch_scc0 .Llate_align_4
	s_barrier
.Llate_align_4:
	v_cvt_pk_bf16_f32 v88, v100, v101
	v_cvt_pk_bf16_f32 v89, v102, v103
	v_cvt_pk_bf16_f32 v90, v92, v93
	v_add_co_u32_e32 v92, vcc, s12, v138
	s_mov_b32 s12, 0xc000
	s_nop 0
	v_addc_co_u32_e32 v93, vcc, 0, v139, vcc
	v_cvt_pk_bf16_f32 v91, v94, v95
	global_store_dwordx4 v[92:93], v[88:91], off
	v_cvt_pk_bf16_f32 v80, v80, v81
	v_cvt_pk_bf16_f32 v81, v82, v83
	v_cvt_pk_bf16_f32 v82, v72, v73
	v_cvt_pk_bf16_f32 v83, v74, v75
	global_store_dwordx4 v[92:93], v[80:83], off offset:256
	v_cvt_pk_bf16_f32 v72, v84, v85
	v_cvt_pk_bf16_f32 v73, v86, v87
	v_cvt_pk_bf16_f32 v74, v76, v77
	v_add_co_u32_e32 v76, vcc, s12, v138
	s_mov_b32 s12, 0x20000
	s_nop 0
	v_addc_co_u32_e32 v77, vcc, 0, v139, vcc
	v_cvt_pk_bf16_f32 v75, v78, v79
	global_store_dwordx4 v[76:77], v[72:75], off
	v_cvt_pk_bf16_f32 v68, v68, v69
	v_cvt_pk_bf16_f32 v69, v70, v71
	v_cvt_pk_bf16_f32 v70, v64, v65
	v_cvt_pk_bf16_f32 v71, v66, v67
	global_store_dwordx4 v[76:77], v[68:71], off offset:256
	v_cvt_pk_bf16_f32 v60, v60, v61
	v_cvt_pk_bf16_f32 v61, v62, v63
	v_cvt_pk_bf16_f32 v62, v56, v57
	v_add_co_u32_e32 v56, vcc, s12, v138
	s_mov_b32 s12, 0x24000
	s_nop 0
	v_addc_co_u32_e32 v57, vcc, 0, v139, vcc
	v_cvt_pk_bf16_f32 v63, v58, v59
	global_store_dwordx4 v[56:57], v[60:63], off
	v_cvt_pk_bf16_f32 v48, v48, v49
	v_cvt_pk_bf16_f32 v49, v50, v51
	v_cvt_pk_bf16_f32 v50, v40, v41
	v_cvt_pk_bf16_f32 v51, v42, v43
	global_store_dwordx4 v[56:57], v[48:51], off offset:256
	v_cvt_pk_bf16_f32 v40, v52, v53
	v_cvt_pk_bf16_f32 v41, v54, v55
	v_cvt_pk_bf16_f32 v42, v44, v45
	v_add_co_u32_e32 v44, vcc, s12, v138
	s_mov_b32 s12, 0x28000
	s_nop 0
	v_addc_co_u32_e32 v45, vcc, 0, v139, vcc
	v_cvt_pk_bf16_f32 v43, v46, v47
	global_store_dwordx4 v[44:45], v[40:43], off
	v_cvt_pk_bf16_f32 v32, v32, v33
	v_cvt_pk_bf16_f32 v33, v34, v35
	v_cvt_pk_bf16_f32 v34, v24, v25
	v_cvt_pk_bf16_f32 v35, v26, v27
	global_store_dwordx4 v[44:45], v[32:35], off offset:256
	v_cvt_pk_bf16_f32 v24, v36, v37
	v_cvt_pk_bf16_f32 v25, v38, v39
	v_cvt_pk_bf16_f32 v26, v28, v29
	v_add_co_u32_e32 v28, vcc, s12, v138
	s_mov_b32 s12, 0x2c000
	s_nop 0
	v_addc_co_u32_e32 v29, vcc, 0, v139, vcc
	v_cvt_pk_bf16_f32 v27, v30, v31
	global_store_dwordx4 v[28:29], v[24:27], off
	v_cvt_pk_bf16_f32 v16, v16, v17
	v_cvt_pk_bf16_f32 v17, v18, v19
	v_cvt_pk_bf16_f32 v18, v8, v9
	v_cvt_pk_bf16_f32 v19, v10, v11
	global_store_dwordx4 v[28:29], v[16:19], off offset:256
	v_cvt_pk_bf16_f32 v8, v20, v21
	v_cvt_pk_bf16_f32 v9, v22, v23
	v_cvt_pk_bf16_f32 v10, v12, v13
	v_add_co_u32_e32 v12, vcc, s12, v138
	s_mov_b64 s[30:31], -1
	s_nop 0
	v_addc_co_u32_e32 v13, vcc, 0, v139, vcc
	s_andn2_b64 vcc, exec, s[42:43]
	v_cvt_pk_bf16_f32 v11, v14, v15
	global_store_dwordx4 v[12:13], v[8:11], off
	v_cvt_pk_bf16_f32 v4, v4, v5
	v_cvt_pk_bf16_f32 v5, v6, v7
	v_cvt_pk_bf16_f32 v6, v0, v1
	v_cvt_pk_bf16_f32 v7, v2, v3
	global_store_dwordx4 v[12:13], v[4:7], off offset:256
	s_cbranch_vccnz .LBB0_579
	s_andn2_b64 vcc, exec, s[16:17]
	s_cbranch_vccnz .LBB0_578
	s_barrier
	s_branch .LBB0_578

; #define PG8_STAGE(bufoff, gbase, voff) do { _Pragma("unroll") for (int _i = 0; _i < 2; ++_i) \
;         __builtin_amdgcn_global_load_lds((const unsigned*)((const char*)(gbase) + (voff)[_i]), (LAS unsigned*)(lds + (bufoff) + ldsw + _i * 8192), 16, 0, 0); } while (0)
; #define PG8_LDA(dst, b, h) do { _Pragma("unroll") for (int m = 0; m < 4; ++m) _Pragma("unroll") for (int k = 0; k < 2; ++k) dst[m][k] = *(const LAS bf16x8*)(lds + PG8_SA(b, h) + aoff + m * 2048 + k * 1024); } while (0)
; #define PG8_LDB(dst, b, h) do { _Pragma("unroll") for (int n = 0; n < 2; ++n) _Pragma("unroll") for (int k = 0; k < 2; ++k) dst[n][k] = *(const LAS bf16x8*)(lds + PG8_SB(b, h) + boff + n * 2048 + k * 1024); } while (0)
; #define PG8_MMA(ai, bj, At, Bt) do { __builtin_amdgcn_s_setprio(1); _Pragma("unroll") for (int m = 0; m < 4; ++m) _Pragma("unroll") for (int n = 0; n < 2; ++n) _Pragma("unroll") for (int k = 0; k < 2; ++k) \
;         acc[ai][bj][m][n] = __builtin_amdgcn_mfma_f32_16x16x32_bf16(Bt[n][k], At[m][k], acc[ai][bj][m][n], 0, 0, 0); __builtin_amdgcn_s_setprio(0); } while (0)
; template <class Epi, class Map>
; __device__ __forceinline__ void gemm_phase(LAS unsigned char* lds, const Gemm g, const Sched<Map>& S, const Epi& E) {
;     ...
;         const bool has_next = S.next(ui + 1, nxt);
;         const char* nA = has_next ? (const char*)g.A + nxt.aoff : cA; const char* nB = has_next ? (const char*)g.Bt + nxt.boff : cB;
; #pragma unroll 1
;         for (int t = 0; t < nt; t += 2) {
;             const bool last = (t == nt - 2);
;             const char* a1 = cA + (size_t)(t + 1) * kstep;
;             const char* a2 = last ? nA : cA + (size_t)(t + 2) * kstep; const char* b2 = last ? nB : cB + (size_t)(t + 2) * kstep;
;             const char* a3 = a2 + kstep; const char* b3 = b2 + kstep;
;             PG8_LDB(B0, 0, 0); PG8_LDB(B1, 0, 1); PG8_SCHED; PG8_LDA(At, 0, 0); PG8_STAGE(PG8_SA(1, 1), a1 + hstepA, voffA);
;             PG8_WAIT_V(8); PG8_WAIT_L(0); PG8_BAR; PG8_MMA(0, 0, At, B0); PG8_MMA(0, 1, At, B1); PG8_BAR; PG8_SCHED;
;     ...
; #pragma unroll
;         for (int a = 0; a < 2; ++a)
; #pragma unroll
;             for (int b = 0; b < 2; ++b)
; #pragma unroll
;                 for (int m = 0; m < 4; ++m)
; #pragma unroll
;                     for (int n = 0; n < 2; ++n) acc[a][b][m][n] = (f32x4){0.f, 0.f, 0.f, 0.f};
;         cur = nxt; cA = nA; cB = nB; ++ui;
.LBB0_658:
	v_readlane_b32 s20, v245, 30
	v_readlane_b32 s21, v245, 31
	s_add_u32 s20, s20, s13
	s_addc_u32 s21, s21, 0
	s_and_b64 s[24:25], s[42:43], exec
	v_readlane_b32 s24, v246, 17
	s_cselect_b32 s15, s21, s31
	s_cselect_b32 s33, s20, s30
	v_readlane_b32 s25, v246, 18
	s_add_u32 s24, s24, s12
	s_addc_u32 s25, s25, 0
	s_and_b64 s[34:35], s[42:43], exec
	v_mov_b32_e32 v0, 0
	s_cselect_b32 s38, s25, s29
	s_cselect_b32 s39, s24, s28
	s_mov_b64 s[44:45], 0
	s_mov_b64 s[34:35], -1
	s_mov_b64 s[36:37], 0
	v_mov_b32_e32 v1, v0
	v_mov_b32_e32 v2, v0
	v_mov_b32_e32 v3, v0
	v_mov_b32_e32 v4, v0
	v_mov_b32_e32 v5, v0
	v_mov_b32_e32 v6, v0
	v_mov_b32_e32 v7, v0
	v_mov_b32_e32 v8, v0
	v_mov_b32_e32 v9, v0
	v_mov_b32_e32 v10, v0
	v_mov_b32_e32 v11, v0
	v_mov_b32_e32 v12, v0
	v_mov_b32_e32 v13, v0
	v_mov_b32_e32 v14, v0
	v_mov_b32_e32 v15, v0
	v_mov_b32_e32 v16, v0
	v_mov_b32_e32 v17, v0
	v_mov_b32_e32 v18, v0
	v_mov_b32_e32 v19, v0
	v_mov_b32_e32 v20, v0
	v_mov_b32_e32 v21, v0
	v_mov_b32_e32 v22, v0
	v_mov_b32_e32 v23, v0
	v_mov_b32_e32 v24, v0
	v_mov_b32_e32 v25, v0
	v_mov_b32_e32 v26, v0
	v_mov_b32_e32 v27, v0
	v_mov_b32_e32 v28, v0
	v_mov_b32_e32 v29, v0
	v_mov_b32_e32 v30, v0
	v_mov_b32_e32 v31, v0
	v_mov_b32_e32 v64, v0
	v_mov_b32_e32 v65, v0
	v_mov_b32_e32 v66, v0
	v_mov_b32_e32 v67, v0
	v_mov_b32_e32 v68, v0
	v_mov_b32_e32 v69, v0
	v_mov_b32_e32 v70, v0
	v_mov_b32_e32 v71, v0
	v_mov_b32_e32 v72, v0
	v_mov_b32_e32 v73, v0
	v_mov_b32_e32 v74, v0
	v_mov_b32_e32 v75, v0
	v_mov_b32_e32 v76, v0
	v_mov_b32_e32 v77, v0
	v_mov_b32_e32 v78, v0
	v_mov_b32_e32 v79, v0
	v_mov_b32_e32 v80, v0
	v_mov_b32_e32 v81, v0
	v_mov_b32_e32 v82, v0
	v_mov_b32_e32 v83, v0
	v_mov_b32_e32 v84, v0
	v_mov_b32_e32 v85, v0
	v_mov_b32_e32 v86, v0
	v_mov_b32_e32 v87, v0
	v_mov_b32_e32 v88, v0
	v_mov_b32_e32 v89, v0
	v_mov_b32_e32 v90, v0
	v_mov_b32_e32 v91, v0
	v_mov_b32_e32 v92, v0
	v_mov_b32_e32 v93, v0
	v_mov_b32_e32 v94, v0
	v_mov_b32_e32 v95, v0
	v_mov_b32_e32 v32, v0
	v_mov_b32_e32 v33, v0
	v_mov_b32_e32 v34, v0
	v_mov_b32_e32 v35, v0
	v_mov_b32_e32 v36, v0
	v_mov_b32_e32 v37, v0
	v_mov_b32_e32 v38, v0
	v_mov_b32_e32 v39, v0
	v_mov_b32_e32 v40, v0
	v_mov_b32_e32 v41, v0
	v_mov_b32_e32 v42, v0
	v_mov_b32_e32 v43, v0
	v_mov_b32_e32 v44, v0
	v_mov_b32_e32 v45, v0
	v_mov_b32_e32 v46, v0
	v_mov_b32_e32 v47, v0
	v_mov_b32_e32 v48, v0
	v_mov_b32_e32 v49, v0
	v_mov_b32_e32 v50, v0
	v_mov_b32_e32 v51, v0
	v_mov_b32_e32 v52, v0
	v_mov_b32_e32 v53, v0
	v_mov_b32_e32 v54, v0
	v_mov_b32_e32 v55, v0
	v_mov_b32_e32 v56, v0
	v_mov_b32_e32 v57, v0
	v_mov_b32_e32 v58, v0
	v_mov_b32_e32 v59, v0
	v_mov_b32_e32 v60, v0
	v_mov_b32_e32 v61, v0
	v_mov_b32_e32 v62, v0
	v_mov_b32_e32 v63, v0
	v_mov_b32_e32 v96, v0
	v_mov_b32_e32 v97, v0
	v_mov_b32_e32 v98, v0
	v_mov_b32_e32 v99, v0
	v_mov_b32_e32 v100, v0
	v_mov_b32_e32 v101, v0
	v_mov_b32_e32 v102, v0
	v_mov_b32_e32 v103, v0
	v_mov_b32_e32 v104, v0
	v_mov_b32_e32 v105, v0
	v_mov_b32_e32 v106, v0
	v_mov_b32_e32 v107, v0
	v_mov_b32_e32 v108, v0
	v_mov_b32_e32 v109, v0
	v_mov_b32_e32 v110, v0
	v_mov_b32_e32 v111, v0
	v_mov_b32_e32 v112, v0
	v_mov_b32_e32 v113, v0
	v_mov_b32_e32 v114, v0
	v_mov_b32_e32 v115, v0
	v_mov_b32_e32 v116, v0
	v_mov_b32_e32 v117, v0
	v_mov_b32_e32 v118, v0
	v_mov_b32_e32 v119, v0
	v_mov_b32_e32 v120, v0
	v_mov_b32_e32 v121, v0
	v_mov_b32_e32 v122, v0
	v_mov_b32_e32 v123, v0
	v_mov_b32_e32 v124, v0
	v_mov_b32_e32 v125, v0
	v_mov_b32_e32 v126, v0
	v_mov_b32_e32 v127, v0
.LBB0_659:
	s_add_u32 s50, s30, s44
	s_addc_u32 s51, s31, s45
	s_add_u32 s48, s50, 0x100
	s_addc_u32 s49, s51, 0
	s_and_b64 s[46:47], s[36:37], exec
	s_cselect_b32 s47, s15, s49
	s_cselect_b32 s46, s33, s48
	s_add_u32 s44, s28, s44
	s_addc_u32 s45, s29, s45
	s_add_u32 s44, s44, 0x100
	s_addc_u32 s45, s45, 0
	s_add_i32 s62, 0, 0x10000
	s_and_b64 s[36:37], s[36:37], exec
	s_cselect_b32 s49, s38, s45
	s_cselect_b32 s48, s39, s44
	s_add_i32 s37, 0, 0x14000
	s_add_u32 s52, s50, 0x20080
	s_addc_u32 s53, s51, 0
	s_add_i32 s66, s62, s0
	s_add_i32 m0, s1, 0xc000
	s_add_i32 s63, s1, 0xe000
	s_add_i32 s58, s66, 0x2000
	v_add_u32_e32 v142, s62, v140
	s_add_u32 s50, s48, 0x10000
	ds_read_b128 v[134:137], v142
	ds_read_b128 v[160:163], v142 offset:1024
	ds_read_b128 v[164:167], v142 offset:2048
	ds_read_b128 v[168:171], v142 offset:3072
	v_add_u32_e32 v142, s37, v140
	s_addc_u32 s51, s49, 0
	s_add_i32 s65, s37, s0
	ds_read_b128 v[172:175], v142
	ds_read_b128 v[176:179], v142 offset:1024
	ds_read_b128 v[192:195], v142 offset:2048
	ds_read_b128 v[196:199], v142 offset:3072
	s_add_i32 s59, s65, 0x2000
	s_add_i32 s57, 0, 0x18000
	s_add_i32 s56, 0, 0x1c000
	s_add_u32 s44, s46, 0x20000
	s_addc_u32 s45, s47, 0
	s_add_i32 s55, s57, s0
	s_add_i32 s54, s55, 0x2000
	s_add_u32 s36, s48, 0x10080
	s_addc_u32 s37, s49, 0
	s_add_i32 s68, s56, s0
	s_add_i32 s67, s68, 0x2000
	v_lshl_add_u64 v[142:143], s[52:53], 0, v[132:133]
	ds_read_b128 v[200:203], v141
	ds_read_b128 v[204:207], v141 offset:1024
	ds_read_b128 v[208:211], v141 offset:2048
	ds_read_b128 v[212:215], v141 offset:3072
	ds_read_b128 v[216:219], v141 offset:4096
	ds_read_b128 v[220:223], v141 offset:5120
	ds_read_b128 v[224:227], v141 offset:6144
	ds_read_b128 v[228:231], v141 offset:7168
	global_load_lds_dwordx4 v[142:143], off
	v_lshl_add_u64 v[142:143], s[52:53], 0, v[130:131]
	s_mov_b32 m0, s63
	s_nop 0
	global_load_lds_dwordx4 v[142:143], off
	s_waitcnt vmcnt(8)
	s_waitcnt lgkmcnt(0)
	s_barrier
; #define PG8_STAGE(bufoff, gbase, voff) do { _Pragma("unroll") for (int _i = 0; _i < 2; ++_i) \
;         __builtin_amdgcn_global_load_lds((const unsigned*)((const char*)(gbase) + (voff)[_i]), (LAS unsigned*)(lds + (bufoff) + ldsw + _i * 8192), 16, 0, 0); } while (0)
; #define PG8_LDA(dst, b, h) do { _Pragma("unroll") for (int m = 0; m < 4; ++m) _Pragma("unroll") for (int k = 0; k < 2; ++k) dst[m][k] = *(const LAS bf16x8*)(lds + PG8_SA(b, h) + aoff + m * 2048 + k * 1024); } while (0)
; #define PG8_LDB(dst, b, h) do { _Pragma("unroll") for (int n = 0; n < 2; ++n) _Pragma("unroll") for (int k = 0; k < 2; ++k) dst[n][k] = *(const LAS bf16x8*)(lds + PG8_SB(b, h) + boff + n * 2048 + k * 1024); } while (0)
; #define PG8_MMA(ai, bj, At, Bt) do { __builtin_amdgcn_s_setprio(1); _Pragma("unroll") for (int m = 0; m < 4; ++m) _Pragma("unroll") for (int n = 0; n < 2; ++n) _Pragma("unroll") for (int k = 0; k < 2; ++k) \
;         acc[ai][bj][m][n] = __builtin_amdgcn_mfma_f32_16x16x32_bf16(Bt[n][k], At[m][k], acc[ai][bj][m][n], 0, 0, 0); __builtin_amdgcn_s_setprio(0); } while (0)
; #define PG8_WAIT_V(n) asm volatile("s_waitcnt vmcnt(" #n ")" ::: "memory")
; #define PG8_WAIT_L(n) asm volatile("s_waitcnt lgkmcnt(" #n ")" ::: "memory")
; #define PG8_BAR __builtin_amdgcn_s_barrier()
; #define PG8_SCHED __builtin_amdgcn_sched_barrier(0)
; template <class Epi, class Map>
; __device__ __forceinline__ void gemm_phase(LAS unsigned char* lds, const Gemm g, const Sched<Map>& S, const Epi& E) {
;     ...
;             PG8_WAIT_V(8); PG8_WAIT_L(0); PG8_BAR; PG8_MMA(0, 0, At, B0); PG8_MMA(0, 1, At, B1); PG8_BAR; PG8_SCHED;
;             PG8_LDA(At, 0, 1); PG8_STAGE(PG8_SB(0, 0), b2, voffB); PG8_STAGE(PG8_SB(0, 1), b2 + hstepB, voffB); PG8_STAGE(PG8_SA(0, 0), a2, voffA);
;             PG8_WAIT_V(8); PG8_WAIT_L(0); PG8_BAR; PG8_MMA(1, 0, At, B0); PG8_MMA(1, 1, At, B1); PG8_BAR; PG8_SCHED;
;             PG8_LDB(B0, 1, 0); PG8_LDB(B1, 1, 1); PG8_SCHED; PG8_LDA(At, 1, 0); PG8_STAGE(PG8_SA(0, 1), a2 + hstepA, voffA);
	s_waitcnt lgkmcnt(0)
	v_mfma_f32_16x16x32_bf16 v[124:127], v[134:137], v[200:203], v[124:127]
	v_mfma_f32_16x16x32_bf16 v[120:123], v[164:167], v[200:203], v[120:123]
	v_mfma_f32_16x16x32_bf16 v[116:119], v[134:137], v[208:211], v[116:119]
	v_mfma_f32_16x16x32_bf16 v[112:115], v[164:167], v[208:211], v[112:115]
	v_mfma_f32_16x16x32_bf16 v[108:111], v[134:137], v[216:219], v[108:111]
	v_mfma_f32_16x16x32_bf16 v[104:107], v[164:167], v[216:219], v[104:107]
	v_mfma_f32_16x16x32_bf16 v[100:103], v[134:137], v[224:227], v[100:103]
	v_mfma_f32_16x16x32_bf16 v[96:99], v[164:167], v[224:227], v[96:99]
	v_mfma_f32_16x16x32_bf16 v[124:127], v[160:163], v[204:207], v[124:127]
	v_mfma_f32_16x16x32_bf16 v[120:123], v[168:171], v[204:207], v[120:123]
	v_mfma_f32_16x16x32_bf16 v[116:119], v[160:163], v[212:215], v[116:119]
	v_mfma_f32_16x16x32_bf16 v[112:115], v[168:171], v[212:215], v[112:115]
	v_mfma_f32_16x16x32_bf16 v[108:111], v[160:163], v[220:223], v[108:111]
	v_mfma_f32_16x16x32_bf16 v[104:107], v[168:171], v[220:223], v[104:107]
	v_mfma_f32_16x16x32_bf16 v[100:103], v[160:163], v[228:231], v[100:103]
	v_mfma_f32_16x16x32_bf16 v[96:99], v[168:171], v[228:231], v[96:99]
	v_mfma_f32_16x16x32_bf16 v[60:63], v[172:175], v[200:203], v[60:63]
	v_mfma_f32_16x16x32_bf16 v[56:59], v[192:195], v[200:203], v[56:59]
	v_mfma_f32_16x16x32_bf16 v[52:55], v[172:175], v[208:211], v[52:55]
	v_mfma_f32_16x16x32_bf16 v[48:51], v[192:195], v[208:211], v[48:51]
	v_mfma_f32_16x16x32_bf16 v[44:47], v[172:175], v[216:219], v[44:47]
	v_mfma_f32_16x16x32_bf16 v[40:43], v[192:195], v[216:219], v[40:43]
	v_mfma_f32_16x16x32_bf16 v[36:39], v[172:175], v[224:227], v[36:39]
	v_mfma_f32_16x16x32_bf16 v[32:35], v[192:195], v[224:227], v[32:35]
	v_mfma_f32_16x16x32_bf16 v[60:63], v[176:179], v[204:207], v[60:63]
	v_mfma_f32_16x16x32_bf16 v[56:59], v[196:199], v[204:207], v[56:59]
	v_mfma_f32_16x16x32_bf16 v[52:55], v[176:179], v[212:215], v[52:55]
	v_mfma_f32_16x16x32_bf16 v[48:51], v[196:199], v[212:215], v[48:51]
	v_mfma_f32_16x16x32_bf16 v[44:47], v[176:179], v[220:223], v[44:47]
	v_mfma_f32_16x16x32_bf16 v[40:43], v[196:199], v[220:223], v[40:43]
	v_mfma_f32_16x16x32_bf16 v[36:39], v[176:179], v[228:231], v[36:39]
	v_mfma_f32_16x16x32_bf16 v[32:35], v[196:199], v[228:231], v[32:35]
	s_barrier
	s_mov_b32 m0, s66
	v_lshl_add_u64 v[142:143], s[48:49], 0, v[144:145]
	ds_read_b128 v[200:203], v141 offset:16384
	ds_read_b128 v[204:207], v141 offset:17408
	ds_read_b128 v[208:211], v141 offset:18432
	ds_read_b128 v[212:215], v141 offset:19456
	ds_read_b128 v[216:219], v141 offset:20480
	ds_read_b128 v[220:223], v141 offset:21504
	ds_read_b128 v[224:227], v141 offset:22528
	ds_read_b128 v[228:231], v141 offset:23552
	global_load_lds_dwordx4 v[142:143], off
	v_lshl_add_u64 v[180:181], s[48:49], 0, v[128:129]
	s_mov_b32 m0, s58
	v_lshl_add_u64 v[232:233], s[50:51], 0, v[144:145]
	global_load_lds_dwordx4 v[180:181], off
	s_mov_b32 m0, s65
	v_lshl_add_u64 v[234:235], s[46:47], 0, v[130:131]
	global_load_lds_dwordx4 v[232:233], off
	v_lshl_add_u64 v[232:233], s[50:51], 0, v[128:129]
	s_mov_b32 m0, s59
	s_nop 0
	global_load_lds_dwordx4 v[232:233], off
	v_lshl_add_u64 v[232:233], s[46:47], 0, v[132:133]
	s_mov_b32 m0, s1
	s_nop 0
	global_load_lds_dwordx4 v[232:233], off
	s_mov_b32 m0, s2
	s_nop 0
	global_load_lds_dwordx4 v[234:235], off
	s_waitcnt vmcnt(8)
	s_waitcnt lgkmcnt(0)
	s_barrier
	s_waitcnt lgkmcnt(0)
	v_mfma_f32_16x16x32_bf16 v[92:95], v[134:137], v[200:203], v[92:95]
	v_mfma_f32_16x16x32_bf16 v[88:91], v[164:167], v[200:203], v[88:91]
	v_mfma_f32_16x16x32_bf16 v[84:87], v[134:137], v[208:211], v[84:87]
	v_mfma_f32_16x16x32_bf16 v[80:83], v[164:167], v[208:211], v[80:83]
	v_mfma_f32_16x16x32_bf16 v[76:79], v[134:137], v[216:219], v[76:79]
	v_mfma_f32_16x16x32_bf16 v[72:75], v[164:167], v[216:219], v[72:75]
	v_mfma_f32_16x16x32_bf16 v[68:71], v[134:137], v[224:227], v[68:71]
	v_mfma_f32_16x16x32_bf16 v[64:67], v[164:167], v[224:227], v[64:67]
	v_mfma_f32_16x16x32_bf16 v[92:95], v[160:163], v[204:207], v[92:95]
	v_mfma_f32_16x16x32_bf16 v[88:91], v[168:171], v[204:207], v[88:91]
	v_mfma_f32_16x16x32_bf16 v[84:87], v[160:163], v[212:215], v[84:87]
	v_mfma_f32_16x16x32_bf16 v[80:83], v[168:171], v[212:215], v[80:83]
	v_mfma_f32_16x16x32_bf16 v[76:79], v[160:163], v[220:223], v[76:79]
	v_mfma_f32_16x16x32_bf16 v[72:75], v[168:171], v[220:223], v[72:75]
	v_mfma_f32_16x16x32_bf16 v[68:71], v[160:163], v[228:231], v[68:71]
	v_mfma_f32_16x16x32_bf16 v[64:67], v[168:171], v[228:231], v[64:67]
	v_mfma_f32_16x16x32_bf16 v[28:31], v[172:175], v[200:203], v[28:31]
	v_mfma_f32_16x16x32_bf16 v[24:27], v[192:195], v[200:203], v[24:27]
	v_mfma_f32_16x16x32_bf16 v[20:23], v[172:175], v[208:211], v[20:23]
	v_mfma_f32_16x16x32_bf16 v[16:19], v[192:195], v[208:211], v[16:19]
	v_mfma_f32_16x16x32_bf16 v[12:15], v[172:175], v[216:219], v[12:15]
	v_mfma_f32_16x16x32_bf16 v[8:11], v[192:195], v[216:219], v[8:11]
	v_mfma_f32_16x16x32_bf16 v[4:7], v[172:175], v[224:227], v[4:7]
	v_mfma_f32_16x16x32_bf16 v[0:3], v[192:195], v[224:227], v[0:3]
	v_mfma_f32_16x16x32_bf16 v[28:31], v[176:179], v[204:207], v[28:31]
	v_mfma_f32_16x16x32_bf16 v[24:27], v[196:199], v[204:207], v[24:27]
	v_mfma_f32_16x16x32_bf16 v[20:23], v[176:179], v[212:215], v[20:23]
	v_mfma_f32_16x16x32_bf16 v[16:19], v[196:199], v[212:215], v[16:19]
	v_mfma_f32_16x16x32_bf16 v[12:15], v[176:179], v[220:223], v[12:15]
	v_mfma_f32_16x16x32_bf16 v[8:11], v[196:199], v[220:223], v[8:11]
	v_mfma_f32_16x16x32_bf16 v[4:7], v[176:179], v[228:231], v[4:7]
	v_mfma_f32_16x16x32_bf16 v[0:3], v[196:199], v[228:231], v[0:3]
	s_barrier
; #define PG8_STAGE(bufoff, gbase, voff) do { _Pragma("unroll") for (int _i = 0; _i < 2; ++_i) \
;         __builtin_amdgcn_global_load_lds((const unsigned*)((const char*)(gbase) + (voff)[_i]), (LAS unsigned*)(lds + (bufoff) + ldsw + _i * 8192), 16, 0, 0); } while (0)
; #define PG8_LDA(dst, b, h) do { _Pragma("unroll") for (int m = 0; m < 4; ++m) _Pragma("unroll") for (int k = 0; k < 2; ++k) dst[m][k] = *(const LAS bf16x8*)(lds + PG8_SA(b, h) + aoff + m * 2048 + k * 1024); } while (0)
; #define PG8_LDB(dst, b, h) do { _Pragma("unroll") for (int n = 0; n < 2; ++n) _Pragma("unroll") for (int k = 0; k < 2; ++k) dst[n][k] = *(const LAS bf16x8*)(lds + PG8_SB(b, h) + boff + n * 2048 + k * 1024); } while (0)
; #define PG8_MMA(ai, bj, At, Bt) do { __builtin_amdgcn_s_setprio(1); _Pragma("unroll") for (int m = 0; m < 4; ++m) _Pragma("unroll") for (int n = 0; n < 2; ++n) _Pragma("unroll") for (int k = 0; k < 2; ++k) \
;         acc[ai][bj][m][n] = __builtin_amdgcn_mfma_f32_16x16x32_bf16(Bt[n][k], At[m][k], acc[ai][bj][m][n], 0, 0, 0); __builtin_amdgcn_s_setprio(0); } while (0)
; #define PG8_WAIT_V(n) asm volatile("s_waitcnt vmcnt(" #n ")" ::: "memory")
; #define PG8_WAIT_L(n) asm volatile("s_waitcnt lgkmcnt(" #n ")" ::: "memory")
; #define PG8_BAR __builtin_amdgcn_s_barrier()
; #define PG8_SCHED __builtin_amdgcn_sched_barrier(0)
; template <class Epi, class Map>
; __device__ __forceinline__ void gemm_phase(LAS unsigned char* lds, const Gemm g, const Sched<Map>& S, const Epi& E) {
;     ...
;             PG8_LDB(B0, 1, 0); PG8_LDB(B1, 1, 1); PG8_SCHED; PG8_LDA(At, 1, 0); PG8_STAGE(PG8_SA(0, 1), a2 + hstepA, voffA);
;             PG8_WAIT_V(8); PG8_WAIT_L(0); PG8_BAR; PG8_MMA(0, 0, At, B0); PG8_MMA(0, 1, At, B1); PG8_BAR; PG8_SCHED;
;             PG8_LDA(At, 1, 1); PG8_STAGE(PG8_SB(1, 0), b3, voffB); PG8_STAGE(PG8_SB(1, 1), b3 + hstepB, voffB); PG8_STAGE(PG8_SA(1, 0), a3, voffA);
;             PG8_WAIT_V(8); PG8_WAIT_L(0); PG8_BAR; PG8_MMA(1, 0, At, B0); PG8_MMA(1, 1, At, B1); PG8_BAR; PG8_SCHED;
;         }
;         if (wr == 0) PG8_BAR;
	v_add_u32_e32 v168, s57, v140
	v_add_u32_e32 v196, s56, v140
	ds_read_b128 v[134:137], v168
	ds_read_b128 v[160:163], v168 offset:1024
	ds_read_b128 v[164:167], v168 offset:2048
	ds_read_b128 v[168:171], v168 offset:3072
	ds_read_b128 v[172:175], v196
	ds_read_b128 v[176:179], v196 offset:1024
	ds_read_b128 v[192:195], v196 offset:2048
	ds_read_b128 v[196:199], v196 offset:3072
	s_mov_b32 m0, s3
	v_lshl_add_u64 v[236:237], s[44:45], 0, v[132:133]
	ds_read_b128 v[200:203], v141 offset:32768
	ds_read_b128 v[204:207], v141 offset:33792
	ds_read_b128 v[208:211], v141 offset:34816
	ds_read_b128 v[212:215], v141 offset:35840
	ds_read_b128 v[216:219], v141 offset:36864
	ds_read_b128 v[220:223], v141 offset:37888
	ds_read_b128 v[224:227], v141 offset:38912
	ds_read_b128 v[228:231], v141 offset:39936
	global_load_lds_dwordx4 v[236:237], off
	v_lshl_add_u64 v[236:237], s[44:45], 0, v[130:131]
	s_mov_b32 m0, s4
	s_nop 0
	global_load_lds_dwordx4 v[236:237], off
	s_waitcnt vmcnt(8)
	s_waitcnt lgkmcnt(0)
	s_barrier
	s_waitcnt lgkmcnt(0)
	v_mfma_f32_16x16x32_bf16 v[124:127], v[134:137], v[200:203], v[124:127]
	v_mfma_f32_16x16x32_bf16 v[120:123], v[164:167], v[200:203], v[120:123]
	v_mfma_f32_16x16x32_bf16 v[116:119], v[134:137], v[208:211], v[116:119]
	v_mfma_f32_16x16x32_bf16 v[112:115], v[164:167], v[208:211], v[112:115]
	v_mfma_f32_16x16x32_bf16 v[108:111], v[134:137], v[216:219], v[108:111]
	v_mfma_f32_16x16x32_bf16 v[104:107], v[164:167], v[216:219], v[104:107]
	v_mfma_f32_16x16x32_bf16 v[100:103], v[134:137], v[224:227], v[100:103]
	v_mfma_f32_16x16x32_bf16 v[96:99], v[164:167], v[224:227], v[96:99]
	v_mfma_f32_16x16x32_bf16 v[124:127], v[160:163], v[204:207], v[124:127]
	v_mfma_f32_16x16x32_bf16 v[120:123], v[168:171], v[204:207], v[120:123]
	v_mfma_f32_16x16x32_bf16 v[116:119], v[160:163], v[212:215], v[116:119]
	v_mfma_f32_16x16x32_bf16 v[112:115], v[168:171], v[212:215], v[112:115]
	v_mfma_f32_16x16x32_bf16 v[108:111], v[160:163], v[220:223], v[108:111]
	v_mfma_f32_16x16x32_bf16 v[104:107], v[168:171], v[220:223], v[104:107]
	v_mfma_f32_16x16x32_bf16 v[100:103], v[160:163], v[228:231], v[100:103]
	v_mfma_f32_16x16x32_bf16 v[96:99], v[168:171], v[228:231], v[96:99]
	v_mfma_f32_16x16x32_bf16 v[60:63], v[172:175], v[200:203], v[60:63]
	v_mfma_f32_16x16x32_bf16 v[56:59], v[192:195], v[200:203], v[56:59]
	v_mfma_f32_16x16x32_bf16 v[52:55], v[172:175], v[208:211], v[52:55]
	v_mfma_f32_16x16x32_bf16 v[48:51], v[192:195], v[208:211], v[48:51]
	v_mfma_f32_16x16x32_bf16 v[44:47], v[172:175], v[216:219], v[44:47]
	v_mfma_f32_16x16x32_bf16 v[40:43], v[192:195], v[216:219], v[40:43]
	v_mfma_f32_16x16x32_bf16 v[36:39], v[172:175], v[224:227], v[36:39]
	v_mfma_f32_16x16x32_bf16 v[32:35], v[192:195], v[224:227], v[32:35]
	v_mfma_f32_16x16x32_bf16 v[60:63], v[176:179], v[204:207], v[60:63]
	v_mfma_f32_16x16x32_bf16 v[56:59], v[196:199], v[204:207], v[56:59]
	v_mfma_f32_16x16x32_bf16 v[52:55], v[176:179], v[212:215], v[52:55]
	v_mfma_f32_16x16x32_bf16 v[48:51], v[196:199], v[212:215], v[48:51]
	v_mfma_f32_16x16x32_bf16 v[44:47], v[176:179], v[220:223], v[44:47]
	v_mfma_f32_16x16x32_bf16 v[40:43], v[196:199], v[220:223], v[40:43]
	v_mfma_f32_16x16x32_bf16 v[36:39], v[176:179], v[228:231], v[36:39]
	v_mfma_f32_16x16x32_bf16 v[32:35], v[196:199], v[228:231], v[32:35]
	s_barrier
	s_mov_b32 m0, s55
	v_lshl_add_u64 v[142:143], v[142:143], 0, s[82:83]
	ds_read_b128 v[200:203], v141 offset:49152
	ds_read_b128 v[204:207], v141 offset:50176
	ds_read_b128 v[208:211], v141 offset:51200
	ds_read_b128 v[212:215], v141 offset:52224
	ds_read_b128 v[216:219], v141 offset:53248
	ds_read_b128 v[220:223], v141 offset:54272
	ds_read_b128 v[224:227], v141 offset:55296
	ds_read_b128 v[228:231], v141 offset:56320
	global_load_lds_dwordx4 v[142:143], off
	v_lshl_add_u64 v[142:143], v[180:181], 0, s[82:83]
	s_mov_b32 m0, s54
	s_nop 0
	global_load_lds_dwordx4 v[142:143], off
	v_lshl_add_u64 v[142:143], s[36:37], 0, v[144:145]
	s_mov_b32 m0, s68
	s_nop 0
	global_load_lds_dwordx4 v[142:143], off
	v_lshl_add_u64 v[142:143], s[36:37], 0, v[128:129]
	s_mov_b32 m0, s67
	s_nop 0
	global_load_lds_dwordx4 v[142:143], off
	v_lshl_add_u64 v[142:143], v[232:233], 0, s[82:83]
	s_mov_b32 m0, s7
	s_nop 0
	global_load_lds_dwordx4 v[142:143], off
	v_lshl_add_u64 v[142:143], v[234:235], 0, s[82:83]
	s_mov_b32 m0, s8
	s_nop 0
	global_load_lds_dwordx4 v[142:143], off
	s_waitcnt vmcnt(8)
	s_waitcnt lgkmcnt(0)
	s_barrier
	s_waitcnt lgkmcnt(0)
	v_mfma_f32_16x16x32_bf16 v[92:95], v[134:137], v[200:203], v[92:95]
	v_mfma_f32_16x16x32_bf16 v[88:91], v[164:167], v[200:203], v[88:91]
	v_mfma_f32_16x16x32_bf16 v[84:87], v[134:137], v[208:211], v[84:87]
	v_mfma_f32_16x16x32_bf16 v[80:83], v[164:167], v[208:211], v[80:83]
	v_mfma_f32_16x16x32_bf16 v[76:79], v[134:137], v[216:219], v[76:79]
	v_mfma_f32_16x16x32_bf16 v[72:75], v[164:167], v[216:219], v[72:75]
	v_mfma_f32_16x16x32_bf16 v[68:71], v[134:137], v[224:227], v[68:71]
	v_mfma_f32_16x16x32_bf16 v[64:67], v[164:167], v[224:227], v[64:67]
	v_mfma_f32_16x16x32_bf16 v[92:95], v[160:163], v[204:207], v[92:95]
	v_mfma_f32_16x16x32_bf16 v[88:91], v[168:171], v[204:207], v[88:91]
	v_mfma_f32_16x16x32_bf16 v[84:87], v[160:163], v[212:215], v[84:87]
	v_mfma_f32_16x16x32_bf16 v[80:83], v[168:171], v[212:215], v[80:83]
	v_mfma_f32_16x16x32_bf16 v[76:79], v[160:163], v[220:223], v[76:79]
	v_mfma_f32_16x16x32_bf16 v[72:75], v[168:171], v[220:223], v[72:75]
	v_mfma_f32_16x16x32_bf16 v[68:71], v[160:163], v[228:231], v[68:71]
	v_mfma_f32_16x16x32_bf16 v[64:67], v[168:171], v[228:231], v[64:67]
	v_mfma_f32_16x16x32_bf16 v[28:31], v[172:175], v[200:203], v[28:31]
	v_mfma_f32_16x16x32_bf16 v[24:27], v[192:195], v[200:203], v[24:27]
	v_mfma_f32_16x16x32_bf16 v[20:23], v[172:175], v[208:211], v[20:23]
	v_mfma_f32_16x16x32_bf16 v[16:19], v[192:195], v[208:211], v[16:19]
	v_mfma_f32_16x16x32_bf16 v[12:15], v[172:175], v[216:219], v[12:15]
	v_mfma_f32_16x16x32_bf16 v[8:11], v[192:195], v[216:219], v[8:11]
	v_mfma_f32_16x16x32_bf16 v[4:7], v[172:175], v[224:227], v[4:7]
	v_mfma_f32_16x16x32_bf16 v[0:3], v[192:195], v[224:227], v[0:3]
	v_mfma_f32_16x16x32_bf16 v[28:31], v[176:179], v[204:207], v[28:31]
	v_mfma_f32_16x16x32_bf16 v[24:27], v[196:199], v[204:207], v[24:27]
	v_mfma_f32_16x16x32_bf16 v[20:23], v[176:179], v[212:215], v[20:23]
	v_mfma_f32_16x16x32_bf16 v[16:19], v[196:199], v[212:215], v[16:19]
	v_mfma_f32_16x16x32_bf16 v[12:15], v[176:179], v[220:223], v[12:15]
	v_mfma_f32_16x16x32_bf16 v[8:11], v[196:199], v[220:223], v[8:11]
	v_mfma_f32_16x16x32_bf16 v[4:7], v[176:179], v[228:231], v[4:7]
	v_mfma_f32_16x16x32_bf16 v[0:3], v[196:199], v[228:231], v[0:3]
	s_barrier
	s_andn2_b64 vcc, exec, s[34:35]
	s_mov_b64 s[36:37], -1
	s_mov_b64 s[34:35], 0
	s_mov_b64 s[44:45], 0x100
	s_cbranch_vccz .LBB0_659
	s_and_b64 vcc, exec, s[18:19]
	s_cbranch_vccz .LBB0_662
;     __device__ __forceinline__ void operator()(const Acc& acc, const Unit& u, int wr, int wc, int fr, int fq) const {
;     ...
;         const float lg = l2g[u.pm >> 6];
; #pragma unroll
;         for (int bj = 0; bj < 2; ++bj) {
;             const int j0 = bj * HALF + wc * 32 + 8 * fq;
;             float f[8];
; #pragma unroll
;             for (int e = 0; e < 8; ++e) f[e] = exp2f(-(float)(j0 + e + 1) * lg);
; #pragma unroll
;             for (int ai = 0; ai < 2; ++ai)
; #pragma unroll
;                 for (int m = 0; m < 4; ++m) {
;                     const int i = ai * HALF + wr * 64 + m * 16 + fr;
;                     float o[8];
; #pragma unroll
;                     for (int n = 0; n < 2; ++n)
; #pragma unroll
;                         for (int j = 0; j < 4; ++j) { const int e = n * 4 + j; o[e] = (i >= j0 + e) ? acc[ai][bj][m][n][j] * f[e] : 0.f; }
.LBB0_662:
	s_ashr_i32 s14, s14, 6
	s_ashr_i32 s15, s14, 31
	s_lshl_b64 s[14:15], s[14:15], 2
	v_readlane_b32 s28, v248, 2
	v_readlane_b32 s29, v248, 3
	s_add_u32 s14, s28, s14
	v_mov_b32_e32 v134, v139
	v_mov_b32_e32 v135, v138
	s_addc_u32 s15, s29, s15
	global_load_dword v142, v145, s[14:15]
	v_lshl_add_u32 v136, v134, 3, s6
	v_add_u32_e32 v134, s5, v135
	v_or_b32_e32 v135, 1, v136
	v_cvt_f32_i32_e32 v135, v135
	v_or_b32_e32 v160, 2, v136
	v_or_b32_e32 v162, 3, v136
	v_or_b32_e32 v164, 4, v136
	v_or_b32_e32 v166, 5, v136
	v_or_b32_e32 v168, 6, v136
	v_or_b32_e32 v170, 7, v136
	s_lshl_b64 s[14:15], s[60:61], 1
	v_readlane_b32 s28, v245, 30
	v_readlane_b32 s29, v245, 31
	s_add_u32 s28, s28, s14
	s_addc_u32 s29, s29, s15
	s_waitcnt vmcnt(0)
	v_mul_f32_e64 v137, v142, -v135
	v_cmp_gt_f32_e32 vcc, s75, v137
	s_nop 1
	v_cndmask_b32_e32 v137, 0, v190, vcc
	v_fma_f32 v135, v142, -v135, v137
	v_exp_f32_e32 v135, v135
	v_cndmask_b32_e32 v137, 0, v189, vcc
	v_ldexp_f32 v143, v135, v137
	v_cvt_f32_i32_e32 v135, v160
	v_mul_f32_e32 v124, v124, v143
	v_mul_f32_e32 v116, v116, v143
	v_mul_f32_e32 v108, v108, v143
	v_mul_f32_e64 v137, v142, -v135
	v_cmp_gt_f32_e32 vcc, s75, v137
	v_mul_f32_e32 v100, v100, v143
	v_mul_f32_e32 v92, v92, v143
	v_cndmask_b32_e32 v137, 0, v190, vcc
	v_fma_f32 v135, v142, -v135, v137
	v_exp_f32_e32 v135, v135
	v_cndmask_b32_e32 v137, 0, v189, vcc
	v_mul_f32_e32 v84, v84, v143
	v_mul_f32_e32 v76, v76, v143
	v_ldexp_f32 v161, v135, v137
	v_cvt_f32_i32_e32 v135, v162
	v_mul_f32_e32 v125, v125, v161
	v_mul_f32_e32 v117, v117, v161
	v_mul_f32_e32 v109, v109, v161
	v_mul_f32_e64 v137, v142, -v135
	v_cmp_gt_f32_e32 vcc, s75, v137
	v_mul_f32_e32 v101, v101, v161
	v_mul_f32_e32 v93, v93, v161
	v_cndmask_b32_e32 v137, 0, v190, vcc
	v_fma_f32 v135, v142, -v135, v137
	v_exp_f32_e32 v135, v135
	v_cndmask_b32_e32 v137, 0, v189, vcc
	v_mul_f32_e32 v85, v85, v161
	v_mul_f32_e32 v77, v77, v161
	v_ldexp_f32 v163, v135, v137
	v_cvt_f32_i32_e32 v135, v164
	v_mul_f32_e32 v126, v126, v163
	v_mul_f32_e32 v118, v118, v163
	v_mul_f32_e32 v110, v110, v163
	v_mul_f32_e64 v137, v142, -v135
	v_cmp_gt_f32_e32 vcc, s75, v137
	v_mul_f32_e32 v102, v102, v163
	v_mul_f32_e32 v94, v94, v163
	v_cndmask_b32_e32 v137, 0, v190, vcc
	v_fma_f32 v135, v142, -v135, v137
	v_exp_f32_e32 v135, v135
	v_cndmask_b32_e32 v137, 0, v189, vcc
	v_mul_f32_e32 v86, v86, v163
	v_mul_f32_e32 v78, v78, v163
	v_ldexp_f32 v165, v135, v137
	v_cvt_f32_i32_e32 v135, v166
	v_mul_f32_e32 v127, v127, v165
	v_mul_f32_e32 v119, v119, v165
	v_mul_f32_e32 v111, v111, v165
	v_mul_f32_e64 v137, v142, -v135
	v_cmp_gt_f32_e32 vcc, s75, v137
	v_mul_f32_e32 v103, v103, v165
	v_mul_f32_e32 v95, v95, v165
	v_cndmask_b32_e32 v137, 0, v190, vcc
	v_fma_f32 v135, v142, -v135, v137
	v_exp_f32_e32 v135, v135
	v_cndmask_b32_e32 v137, 0, v189, vcc
	v_mul_f32_e32 v87, v87, v165
	v_mul_f32_e32 v79, v79, v165
	v_ldexp_f32 v167, v135, v137
	v_cvt_f32_i32_e32 v135, v168
	v_mul_f32_e32 v120, v120, v167
	v_mul_f32_e32 v112, v112, v167
	v_mul_f32_e32 v104, v104, v167
	v_mul_f32_e64 v137, v142, -v135
	v_cmp_gt_f32_e32 vcc, s75, v137
	v_mul_f32_e32 v96, v96, v167
	v_mul_f32_e32 v88, v88, v167
	v_cndmask_b32_e32 v137, 0, v190, vcc
	v_fma_f32 v135, v142, -v135, v137
	v_exp_f32_e32 v135, v135
	v_cndmask_b32_e32 v137, 0, v189, vcc
	v_mul_f32_e32 v80, v80, v167
	v_mul_f32_e32 v72, v72, v167
	v_ldexp_f32 v169, v135, v137
	v_cvt_f32_i32_e32 v135, v170
	v_mul_f32_e32 v121, v121, v169
	v_mul_f32_e32 v113, v113, v169
	v_mul_f32_e32 v105, v105, v169
	v_mul_f32_e64 v137, v142, -v135
	v_cmp_gt_f32_e32 vcc, s75, v137
	v_mul_f32_e32 v97, v97, v169
	v_mul_f32_e32 v89, v89, v169
	v_cndmask_b32_e32 v137, 0, v190, vcc
	v_fma_f32 v135, v142, -v135, v137
	v_exp_f32_e32 v135, v135
	v_cndmask_b32_e32 v137, 0, v189, vcc
	v_mul_f32_e32 v81, v81, v169
	v_mul_f32_e32 v73, v73, v169
	v_ldexp_f32 v171, v135, v137
	v_add_u32_e32 v135, 8, v136
	v_cvt_f32_i32_e32 v135, v135
	v_mul_f32_e32 v122, v122, v171
	v_mul_f32_e32 v114, v114, v171
	v_mul_f32_e32 v106, v106, v171
	v_mul_f32_e64 v137, v142, -v135
	v_cmp_gt_f32_e32 vcc, s75, v137
	v_mul_f32_e32 v98, v98, v171
	v_mul_f32_e32 v90, v90, v171
	v_cndmask_b32_e32 v137, 0, v190, vcc
	v_fma_f32 v135, v142, -v135, v137
	v_cndmask_b32_e32 v137, 0, v189, vcc
	v_cmp_ge_i32_e32 vcc, v134, v136
	v_exp_f32_e32 v135, v135
	v_mul_f32_e32 v82, v82, v171
	v_cndmask_b32_e32 v124, 0, v124, vcc
	v_cmp_gt_i32_e32 vcc, v134, v136
	v_ldexp_f32 v172, v135, v137
	v_ashrrev_i32_e32 v135, 31, v134
	v_cndmask_b32_e32 v125, 0, v125, vcc
	v_cmp_ge_i32_e32 vcc, v134, v160
	v_ashrrev_i32_e32 v137, 31, v136
	v_mul_f32_e32 v123, v123, v172
	v_cndmask_b32_e32 v126, 0, v126, vcc
	v_cmp_ge_i32_e32 vcc, v134, v162
	v_cvt_pk_bf16_f32 v174, v124, v125
	v_lshlrev_b64 v[124:125], 1, v[136:137]
	v_mul_f32_e32 v115, v115, v172
	v_cndmask_b32_e32 v127, 0, v127, vcc
	v_cmp_ge_i32_e32 vcc, v134, v164
	v_cvt_pk_bf16_f32 v175, v126, v127
	v_mul_f32_e32 v107, v107, v172
	v_mul_f32_e32 v99, v99, v172
	v_cndmask_b32_e32 v120, 0, v120, vcc
	v_cmp_ge_i32_e32 vcc, v134, v166
	v_mul_f32_e32 v91, v91, v172
	v_mul_f32_e32 v83, v83, v172
	v_cndmask_b32_e32 v121, 0, v121, vcc
	v_cmp_ge_i32_e32 vcc, v134, v168
	v_cvt_pk_bf16_f32 v176, v120, v121
	v_lshlrev_b64 v[120:121], 10, v[134:135]
	v_lshl_add_u64 v[120:121], s[28:29], 0, v[120:121]
	v_cndmask_b32_e32 v122, 0, v122, vcc
	v_cmp_ge_i32_e32 vcc, v134, v170
	v_mul_f32_e32 v74, v74, v171
	v_mul_f32_e32 v75, v75, v172
	v_cndmask_b32_e32 v123, 0, v123, vcc
	v_cvt_pk_bf16_f32 v177, v122, v123
	v_lshl_add_u64 v[122:123], v[120:121], 0, v[124:125]
	v_add_u32_e32 v120, 16, v134
	v_cmp_ge_i32_e32 vcc, v120, v136
; __device__ __forceinline__ unsigned cvt_pk_bf16(float lo, float hi) { unsigned r; asm volatile("v_cvt_pk_bf16_f32 %0, %1, %2" : "=v"(r) : "v"(lo), "v"(hi)); return r; }
;     __device__ __forceinline__ void operator()(const Acc& acc, const Unit& u, int wr, int wc, int fr, int fq) const {
;     ...
;             for (int ai = 0; ai < 2; ++ai)
; #pragma unroll
;                 for (int m = 0; m < 4; ++m) {
;                     const int i = ai * HALF + wr * 64 + m * 16 + fr;
;                     float o[8];
; #pragma unroll
;                     for (int n = 0; n < 2; ++n)
; #pragma unroll
;                         for (int j = 0; j < 4; ++j) { const int e = n * 4 + j; o[e] = (i >= j0 + e) ? acc[ai][bj][m][n][j] * f[e] : 0.f; }
;                     u32x4 w; w.x = cvt_pk_bf16(o[0], o[1]); w.y = cvt_pk_bf16(o[2], o[3]); w.z = cvt_pk_bf16(o[4], o[5]); w.w = cvt_pk_bf16(o[6], o[7]);
;                     *(u32x4*)(O + u.coff + (size_t)i * 512 + j0) = w;
	v_ashrrev_i32_e32 v121, 31, v120
	global_store_dwordx4 v[122:123], v[174:177], off
	v_cndmask_b32_e32 v116, 0, v116, vcc
	v_cmp_gt_i32_e32 vcc, v120, v136
	v_mul_f32_e32 v68, v68, v143
	v_mul_f32_e32 v69, v69, v161
	v_cndmask_b32_e32 v117, 0, v117, vcc
	v_cmp_ge_i32_e32 vcc, v120, v160
	v_cvt_pk_bf16_f32 v116, v116, v117
	v_mul_f32_e32 v70, v70, v163
	v_mul_f32_e32 v71, v71, v165
	v_cndmask_b32_e32 v118, 0, v118, vcc
	v_cmp_ge_i32_e32 vcc, v120, v162
	v_mul_f32_e32 v64, v64, v167
	v_mul_f32_e32 v65, v65, v169
	v_cndmask_b32_e32 v119, 0, v119, vcc
	v_cmp_ge_i32_e32 vcc, v120, v164
	v_cvt_pk_bf16_f32 v117, v118, v119
	v_mul_f32_e32 v66, v66, v171
	s_nop 0
	v_cndmask_b32_e32 v112, 0, v112, vcc
	v_cmp_ge_i32_e32 vcc, v120, v166
	s_nop 1
	v_cndmask_b32_e32 v113, 0, v113, vcc
	v_cmp_ge_i32_e32 vcc, v120, v168
	v_cvt_pk_bf16_f32 v118, v112, v113
	v_lshlrev_b64 v[112:113], 10, v[120:121]
	v_lshl_add_u64 v[112:113], s[28:29], 0, v[112:113]
	v_cndmask_b32_e32 v114, 0, v114, vcc
	v_cmp_ge_i32_e32 vcc, v120, v170
	s_nop 1
	v_cndmask_b32_e32 v115, 0, v115, vcc
	v_cvt_pk_bf16_f32 v119, v114, v115
	v_lshl_add_u64 v[114:115], v[112:113], 0, v[124:125]
	v_add_u32_e32 v112, 32, v134
	v_cmp_ge_i32_e32 vcc, v112, v136
	v_ashrrev_i32_e32 v113, 31, v112
	global_store_dwordx4 v[114:115], v[116:119], off
	v_cndmask_b32_e32 v108, 0, v108, vcc
	v_cmp_gt_i32_e32 vcc, v112, v136
	s_nop 1
	v_cndmask_b32_e32 v109, 0, v109, vcc
	v_cmp_ge_i32_e32 vcc, v112, v160
	v_cvt_pk_bf16_f32 v108, v108, v109
	s_nop 1
	v_cndmask_b32_e32 v110, 0, v110, vcc
	v_cmp_ge_i32_e32 vcc, v112, v162
	s_nop 1
	v_cndmask_b32_e32 v111, 0, v111, vcc
	v_cmp_ge_i32_e32 vcc, v112, v164
	v_cvt_pk_bf16_f32 v109, v110, v111
	s_nop 1
	v_cndmask_b32_e32 v104, 0, v104, vcc
	v_cmp_ge_i32_e32 vcc, v112, v166
	s_nop 1
	v_cndmask_b32_e32 v105, 0, v105, vcc
	v_cmp_ge_i32_e32 vcc, v112, v168
	v_cvt_pk_bf16_f32 v110, v104, v105
	v_lshlrev_b64 v[104:105], 10, v[112:113]
	v_lshl_add_u64 v[104:105], s[28:29], 0, v[104:105]
	v_cndmask_b32_e32 v106, 0, v106, vcc
	v_cmp_ge_i32_e32 vcc, v112, v170
	s_nop 1
	v_cndmask_b32_e32 v107, 0, v107, vcc
	v_cvt_pk_bf16_f32 v111, v106, v107
	v_lshl_add_u64 v[106:107], v[104:105], 0, v[124:125]
	v_add_u32_e32 v104, 48, v134
	v_cmp_ge_i32_e32 vcc, v104, v136
	v_ashrrev_i32_e32 v105, 31, v104
	global_store_dwordx4 v[106:107], v[108:111], off
	v_cndmask_b32_e32 v100, 0, v100, vcc
	v_cmp_gt_i32_e32 vcc, v104, v136
	s_nop 1
	v_cndmask_b32_e32 v101, 0, v101, vcc
	v_cmp_ge_i32_e32 vcc, v104, v160
	v_cvt_pk_bf16_f32 v100, v100, v101
	s_nop 1
	v_cndmask_b32_e32 v102, 0, v102, vcc
	v_cmp_ge_i32_e32 vcc, v104, v162
	s_nop 1
	v_cndmask_b32_e32 v103, 0, v103, vcc
	v_cmp_ge_i32_e32 vcc, v104, v164
	v_cvt_pk_bf16_f32 v101, v102, v103
	s_nop 1
	v_cndmask_b32_e32 v96, 0, v96, vcc
	v_cmp_ge_i32_e32 vcc, v104, v166
	s_nop 1
	v_cndmask_b32_e32 v97, 0, v97, vcc
	v_cmp_ge_i32_e32 vcc, v104, v168
	v_cvt_pk_bf16_f32 v102, v96, v97
	v_lshlrev_b64 v[96:97], 10, v[104:105]
	v_lshl_add_u64 v[96:97], s[28:29], 0, v[96:97]
	v_cndmask_b32_e32 v98, 0, v98, vcc
	v_cmp_ge_i32_e32 vcc, v104, v170
	s_nop 1
	v_cndmask_b32_e32 v99, 0, v99, vcc
	v_cvt_pk_bf16_f32 v103, v98, v99
	v_lshl_add_u64 v[98:99], v[96:97], 0, v[124:125]
	v_add_u32_e32 v96, 0x80, v134
	v_cmp_ge_i32_e32 vcc, v96, v136
	v_ashrrev_i32_e32 v97, 31, v96
	global_store_dwordx4 v[98:99], v[100:103], off
	s_cmp_lg_u64 s[18:19], 0
	s_cbranch_scc0 .Llate_align_5
	s_barrier
.Llate_align_5:
	v_cndmask_b32_e32 v92, 0, v92, vcc
	v_cmp_gt_i32_e32 vcc, v96, v136
	s_nop 1
	v_cndmask_b32_e32 v93, 0, v93, vcc
	v_cmp_ge_i32_e32 vcc, v96, v160
	v_cvt_pk_bf16_f32 v92, v92, v93
	s_nop 1
	v_cndmask_b32_e32 v94, 0, v94, vcc
	v_cmp_ge_i32_e32 vcc, v96, v162
	s_nop 1
	v_cndmask_b32_e32 v95, 0, v95, vcc
	v_cmp_ge_i32_e32 vcc, v96, v164
	v_cvt_pk_bf16_f32 v93, v94, v95
	s_nop 1
	v_cndmask_b32_e32 v88, 0, v88, vcc
	v_cmp_ge_i32_e32 vcc, v96, v166
	s_nop 1
	v_cndmask_b32_e32 v89, 0, v89, vcc
	v_cmp_ge_i32_e32 vcc, v96, v168
	v_cvt_pk_bf16_f32 v94, v88, v89
	v_lshlrev_b64 v[88:89], 10, v[96:97]
	v_lshl_add_u64 v[88:89], s[28:29], 0, v[88:89]
	v_cndmask_b32_e32 v90, 0, v90, vcc
	v_cmp_ge_i32_e32 vcc, v96, v170
	s_nop 1
	v_cndmask_b32_e32 v91, 0, v91, vcc
	v_cvt_pk_bf16_f32 v95, v90, v91
	v_lshl_add_u64 v[90:91], v[88:89], 0, v[124:125]
	v_add_u32_e32 v88, 0x90, v134
	v_cmp_ge_i32_e32 vcc, v88, v136
	v_ashrrev_i32_e32 v89, 31, v88
	global_store_dwordx4 v[90:91], v[92:95], off
	v_cndmask_b32_e32 v84, 0, v84, vcc
	v_cmp_gt_i32_e32 vcc, v88, v136
	s_nop 1
	v_cndmask_b32_e32 v85, 0, v85, vcc
	v_cmp_ge_i32_e32 vcc, v88, v160
	v_cvt_pk_bf16_f32 v84, v84, v85
	s_nop 1
	v_cndmask_b32_e32 v86, 0, v86, vcc
	v_cmp_ge_i32_e32 vcc, v88, v162
	s_nop 1
	v_cndmask_b32_e32 v87, 0, v87, vcc
	v_cmp_ge_i32_e32 vcc, v88, v164
	v_cvt_pk_bf16_f32 v85, v86, v87
	s_nop 1
	v_cndmask_b32_e32 v80, 0, v80, vcc
	v_cmp_ge_i32_e32 vcc, v88, v166
	s_nop 1
	v_cndmask_b32_e32 v81, 0, v81, vcc
	v_cmp_ge_i32_e32 vcc, v88, v168
	v_cvt_pk_bf16_f32 v86, v80, v81
	v_lshlrev_b64 v[80:81], 10, v[88:89]
	v_lshl_add_u64 v[80:81], s[28:29], 0, v[80:81]
	v_cndmask_b32_e32 v82, 0, v82, vcc
	v_cmp_ge_i32_e32 vcc, v88, v170
	s_nop 1
	v_cndmask_b32_e32 v83, 0, v83, vcc
	v_cvt_pk_bf16_f32 v87, v82, v83
	v_lshl_add_u64 v[82:83], v[80:81], 0, v[124:125]
	v_add_u32_e32 v80, 0xa0, v134
	v_cmp_ge_i32_e32 vcc, v80, v136
	v_ashrrev_i32_e32 v81, 31, v80
	global_store_dwordx4 v[82:83], v[84:87], off
	v_cndmask_b32_e32 v76, 0, v76, vcc
	v_cmp_gt_i32_e32 vcc, v80, v136
	s_nop 1
	v_cndmask_b32_e32 v77, 0, v77, vcc
	v_cmp_ge_i32_e32 vcc, v80, v160
	v_cvt_pk_bf16_f32 v76, v76, v77
	s_nop 1
	v_cndmask_b32_e32 v78, 0, v78, vcc
; __device__ __forceinline__ unsigned cvt_pk_bf16(float lo, float hi) { unsigned r; asm volatile("v_cvt_pk_bf16_f32 %0, %1, %2" : "=v"(r) : "v"(lo), "v"(hi)); return r; }
;     __device__ __forceinline__ void operator()(const Acc& acc, const Unit& u, int wr, int wc, int fr, int fq) const {
;     ...
;         for (int bj = 0; bj < 2; ++bj) {
;             const int j0 = bj * HALF + wc * 32 + 8 * fq;
;             float f[8];
; #pragma unroll
;             for (int e = 0; e < 8; ++e) f[e] = exp2f(-(float)(j0 + e + 1) * lg);
; #pragma unroll
;             for (int ai = 0; ai < 2; ++ai)
; #pragma unroll
;                 for (int m = 0; m < 4; ++m) {
;                     const int i = ai * HALF + wr * 64 + m * 16 + fr;
;                     float o[8];
; #pragma unroll
;                     for (int n = 0; n < 2; ++n)
; #pragma unroll
;                         for (int j = 0; j < 4; ++j) { const int e = n * 4 + j; o[e] = (i >= j0 + e) ? acc[ai][bj][m][n][j] * f[e] : 0.f; }
;                     u32x4 w; w.x = cvt_pk_bf16(o[0], o[1]); w.y = cvt_pk_bf16(o[2], o[3]); w.z = cvt_pk_bf16(o[4], o[5]); w.w = cvt_pk_bf16(o[6], o[7]);
;                     *(u32x4*)(O + u.coff + (size_t)i * 512 + j0) = w;
	v_cmp_ge_i32_e32 vcc, v80, v162
	s_nop 1
	v_cndmask_b32_e32 v79, 0, v79, vcc
	v_cmp_ge_i32_e32 vcc, v80, v164
	v_cvt_pk_bf16_f32 v77, v78, v79
	s_nop 1
	v_cndmask_b32_e32 v72, 0, v72, vcc
	v_cmp_ge_i32_e32 vcc, v80, v166
	s_nop 1
	v_cndmask_b32_e32 v73, 0, v73, vcc
	v_cmp_ge_i32_e32 vcc, v80, v168
	v_cvt_pk_bf16_f32 v78, v72, v73
	v_lshlrev_b64 v[72:73], 10, v[80:81]
	v_lshl_add_u64 v[72:73], s[28:29], 0, v[72:73]
	v_cndmask_b32_e32 v74, 0, v74, vcc
	v_cmp_ge_i32_e32 vcc, v80, v170
	s_nop 1
	v_cndmask_b32_e32 v75, 0, v75, vcc
	v_cvt_pk_bf16_f32 v79, v74, v75
	v_lshl_add_u64 v[74:75], v[72:73], 0, v[124:125]
	v_add_u32_e32 v72, 0xb0, v134
	v_cmp_ge_i32_e32 vcc, v72, v136
	global_store_dwordx4 v[74:75], v[76:79], off
	s_nop 0
	v_cndmask_b32_e32 v68, 0, v68, vcc
	v_cmp_gt_i32_e32 vcc, v72, v136
	s_nop 1
	v_cndmask_b32_e32 v69, 0, v69, vcc
	v_cmp_ge_i32_e32 vcc, v72, v160
	s_nop 1
	v_cndmask_b32_e32 v70, 0, v70, vcc
	v_cmp_ge_i32_e32 vcc, v72, v162
	s_nop 1
	v_cndmask_b32_e32 v71, 0, v71, vcc
	v_cmp_ge_i32_e32 vcc, v72, v164
	s_nop 1
	v_cndmask_b32_e32 v64, 0, v64, vcc
	v_cmp_ge_i32_e32 vcc, v72, v166
	s_nop 1
	v_cndmask_b32_e32 v65, 0, v65, vcc
	v_cmp_ge_i32_e32 vcc, v72, v168
	s_nop 1
	v_cndmask_b32_e32 v73, 0, v66, vcc
	v_mul_f32_e32 v66, v67, v172
	v_cmp_ge_i32_e32 vcc, v72, v170
	s_nop 1
	v_cndmask_b32_e32 v76, 0, v66, vcc
	v_cvt_pk_bf16_f32 v66, v68, v69
	v_cvt_pk_bf16_f32 v67, v70, v71
	v_cvt_pk_bf16_f32 v68, v64, v65
	v_cvt_pk_bf16_f32 v69, v73, v76
	v_ashrrev_i32_e32 v73, 31, v72
	v_lshlrev_b64 v[64:65], 10, v[72:73]
	v_lshl_add_u64 v[64:65], s[28:29], 0, v[64:65]
	v_lshl_add_u64 v[64:65], v[64:65], 0, v[124:125]
	global_store_dwordx4 v[64:65], v[66:69], off
	s_mov_b64 s[28:29], -1
	s_nop 0
	v_add_u32_e32 v67, 0x81, v136
	v_cvt_f32_i32_e32 v67, v67
	v_add_u32_e32 v66, 0x80, v136
	v_mul_f32_e64 v68, v142, -v67
	v_cmp_gt_f32_e32 vcc, s75, v68
	s_nop 1
	v_cndmask_b32_e32 v68, 0, v190, vcc
	v_fma_f32 v67, v142, -v67, v68
	v_exp_f32_e32 v67, v67
	v_cndmask_b32_e32 v68, 0, v189, vcc
	v_ldexp_f32 v67, v67, v68
	v_add_u32_e32 v68, 0x82, v136
	v_cvt_f32_i32_e32 v69, v68
	v_mul_f32_e32 v60, v60, v67
	v_mul_f32_e32 v52, v52, v67
	v_mul_f32_e32 v44, v44, v67
	v_mul_f32_e64 v70, v142, -v69
	v_cmp_gt_f32_e32 vcc, s75, v70
	v_mul_f32_e32 v36, v36, v67
	v_mul_f32_e32 v28, v28, v67
	v_cndmask_b32_e32 v70, 0, v190, vcc
	v_fma_f32 v69, v142, -v69, v70
	v_exp_f32_e32 v69, v69
	v_cndmask_b32_e32 v70, 0, v189, vcc
	v_mul_f32_e32 v20, v20, v67
	v_mul_f32_e32 v12, v12, v67
	v_ldexp_f32 v69, v69, v70
	v_add_u32_e32 v70, 0x83, v136
	v_cvt_f32_i32_e32 v71, v70
	v_mul_f32_e32 v61, v61, v69
	v_mul_f32_e32 v53, v53, v69
	v_mul_f32_e32 v45, v45, v69
	v_mul_f32_e64 v73, v142, -v71
	v_cmp_gt_f32_e32 vcc, s75, v73
	v_mul_f32_e32 v37, v37, v69
	v_mul_f32_e32 v29, v29, v69
	v_cndmask_b32_e32 v73, 0, v190, vcc
	v_fma_f32 v71, v142, -v71, v73
	v_exp_f32_e32 v71, v71
	v_cndmask_b32_e32 v73, 0, v189, vcc
	v_mul_f32_e32 v21, v21, v69
	v_mul_f32_e32 v13, v13, v69
	v_ldexp_f32 v71, v71, v73
	v_add_u32_e32 v73, 0x84, v136
	v_cvt_f32_i32_e32 v76, v73
	v_mul_f32_e32 v62, v62, v71
	v_mul_f32_e32 v54, v54, v71
	v_mul_f32_e32 v46, v46, v71
	v_mul_f32_e64 v77, v142, -v76
	v_cmp_gt_f32_e32 vcc, s75, v77
	v_mul_f32_e32 v38, v38, v71
	v_mul_f32_e32 v30, v30, v71
	v_cndmask_b32_e32 v77, 0, v190, vcc
	v_fma_f32 v76, v142, -v76, v77
	v_exp_f32_e32 v76, v76
	v_cndmask_b32_e32 v77, 0, v189, vcc
	v_mul_f32_e32 v22, v22, v71
	v_mul_f32_e32 v14, v14, v71
	v_ldexp_f32 v76, v76, v77
	v_add_u32_e32 v77, 0x85, v136
	v_cvt_f32_i32_e32 v78, v77
	v_mul_f32_e32 v63, v63, v76
	v_mul_f32_e32 v55, v55, v76
	v_mul_f32_e32 v47, v47, v76
	v_mul_f32_e64 v79, v142, -v78
	v_cmp_gt_f32_e32 vcc, s75, v79
	v_mul_f32_e32 v39, v39, v76
	v_mul_f32_e32 v31, v31, v76
	v_cndmask_b32_e32 v79, 0, v190, vcc
	v_fma_f32 v78, v142, -v78, v79
	v_exp_f32_e32 v78, v78
	v_cndmask_b32_e32 v79, 0, v189, vcc
	v_mul_f32_e32 v23, v23, v76
	v_mul_f32_e32 v15, v15, v76
	v_ldexp_f32 v78, v78, v79
	v_add_u32_e32 v79, 0x86, v136
	v_cvt_f32_i32_e32 v81, v79
	v_mul_f32_e32 v56, v56, v78
	v_mul_f32_e32 v48, v48, v78
	v_mul_f32_e32 v40, v40, v78
	v_mul_f32_e64 v84, v142, -v81
	v_cmp_gt_f32_e32 vcc, s75, v84
	v_mul_f32_e32 v32, v32, v78
	v_mul_f32_e32 v24, v24, v78
	v_cndmask_b32_e32 v84, 0, v190, vcc
	v_fma_f32 v81, v142, -v81, v84
	v_exp_f32_e32 v81, v81
	v_cndmask_b32_e32 v84, 0, v189, vcc
	v_mul_f32_e32 v16, v16, v78
	v_mul_f32_e32 v8, v8, v78
	v_ldexp_f32 v81, v81, v84
	v_add_u32_e32 v84, 0x87, v136
	v_cvt_f32_i32_e32 v85, v84
	v_mul_f32_e32 v4, v4, v67
	v_mul_f32_e32 v5, v5, v69
	v_mul_f32_e32 v6, v6, v71
	v_mul_f32_e64 v86, v142, -v85
	v_cmp_gt_f32_e32 vcc, s75, v86
	v_mul_f32_e32 v7, v7, v76
	v_mul_f32_e32 v0, v0, v78
	v_cndmask_b32_e32 v86, 0, v190, vcc
	v_fma_f32 v85, v142, -v85, v86
	v_exp_f32_e32 v85, v85
	v_cndmask_b32_e32 v86, 0, v189, vcc
	v_ldexp_f32 v85, v85, v86
	v_add_u32_e32 v86, 0x88, v136
	v_cvt_f32_i32_e32 v86, v86
	v_mul_f32_e64 v87, v142, -v86
	v_cmp_gt_f32_e32 vcc, s75, v87
	s_nop 1
	v_cndmask_b32_e32 v87, 0, v190, vcc
	v_fma_f32 v86, v142, -v86, v87
	v_cndmask_b32_e32 v87, 0, v189, vcc
	v_cmp_ge_i32_e32 vcc, v134, v66
	v_exp_f32_e32 v86, v86
	s_nop 0
	v_cndmask_b32_e32 v60, 0, v60, vcc
	v_cmp_gt_i32_e32 vcc, v134, v66
	v_ldexp_f32 v86, v86, v87
	s_nop 0
	v_cndmask_b32_e32 v61, 0, v61, vcc
	v_cmp_ge_i32_e32 vcc, v134, v68
	s_nop 1
	v_cndmask_b32_e32 v62, 0, v62, vcc
	v_cmp_ge_i32_e32 vcc, v134, v70
	s_nop 1
	v_cndmask_b32_e32 v63, 0, v63, vcc
	v_cmp_ge_i32_e32 vcc, v134, v73
	s_nop 1
	v_cndmask_b32_e32 v87, 0, v56, vcc
	v_mul_f32_e32 v56, v57, v81
	v_cmp_ge_i32_e32 vcc, v134, v77
	s_nop 1
	v_cndmask_b32_e32 v89, 0, v56, vcc
; __device__ __forceinline__ unsigned cvt_pk_bf16(float lo, float hi) { unsigned r; asm volatile("v_cvt_pk_bf16_f32 %0, %1, %2" : "=v"(r) : "v"(lo), "v"(hi)); return r; }
; #define PG8_BAR __builtin_amdgcn_s_barrier()
; template <class Epi, class Map>
; __device__ __forceinline__ void gemm_phase(LAS unsigned char* lds, const Gemm g, const Sched<Map>& S, const Epi& E) {
;     ...
;         if (!has_next) break;
; #pragma unroll
;         for (int a = 0; a < 2; ++a)
; #pragma unroll
;             for (int b = 0; b < 2; ++b)
; #pragma unroll
;                 for (int m = 0; m < 4; ++m)
; #pragma unroll
;                     for (int n = 0; n < 2; ++n) acc[a][b][m][n] = (f32x4){0.f, 0.f, 0.f, 0.f};
;         cur = nxt; cA = nA; cB = nB; ++ui;
;         if (wr == 1) PG8_BAR;
;     __device__ __forceinline__ void operator()(const Acc& acc, const Unit& u, int wr, int wc, int fr, int fq) const {
;     ...
;             for (int ai = 0; ai < 2; ++ai)
; #pragma unroll
;                 for (int m = 0; m < 4; ++m) {
;                     const int i = ai * HALF + wr * 64 + m * 16 + fr;
;                     float o[8];
; #pragma unroll
;                     for (int n = 0; n < 2; ++n)
; #pragma unroll
;                         for (int j = 0; j < 4; ++j) { const int e = n * 4 + j; o[e] = (i >= j0 + e) ? acc[ai][bj][m][n][j] * f[e] : 0.f; }
;                     u32x4 w; w.x = cvt_pk_bf16(o[0], o[1]); w.y = cvt_pk_bf16(o[2], o[3]); w.z = cvt_pk_bf16(o[4], o[5]); w.w = cvt_pk_bf16(o[6], o[7]);
;                     *(u32x4*)(O + u.coff + (size_t)i * 512 + j0) = w;
	v_mul_f32_e32 v56, v58, v85
	v_cmp_ge_i32_e32 vcc, v134, v79
	s_nop 1
	v_cndmask_b32_e32 v92, 0, v56, vcc
	v_mul_f32_e32 v56, v59, v86
	v_cmp_ge_i32_e32 vcc, v134, v84
	s_nop 1
	v_cndmask_b32_e32 v59, 0, v56, vcc
	v_cmp_ge_i32_e32 vcc, v120, v66
	v_cvt_pk_bf16_f32 v56, v60, v61
	v_cvt_pk_bf16_f32 v57, v62, v63
	v_cvt_pk_bf16_f32 v58, v87, v89
	v_cvt_pk_bf16_f32 v59, v92, v59
	global_store_dwordx4 v[122:123], v[56:59], off offset:256
	s_nop 0
	v_cndmask_b32_e32 v52, 0, v52, vcc
	v_cmp_gt_i32_e32 vcc, v120, v66
	s_nop 1
	v_cndmask_b32_e32 v53, 0, v53, vcc
	v_cmp_ge_i32_e32 vcc, v120, v68
	s_nop 1
	v_cndmask_b32_e32 v54, 0, v54, vcc
	v_cmp_ge_i32_e32 vcc, v120, v70
	s_nop 1
	v_cndmask_b32_e32 v55, 0, v55, vcc
	v_cmp_ge_i32_e32 vcc, v120, v73
	s_nop 1
	v_cndmask_b32_e32 v56, 0, v48, vcc
	v_mul_f32_e32 v48, v49, v81
	v_cmp_ge_i32_e32 vcc, v120, v77
	s_nop 1
	v_cndmask_b32_e32 v57, 0, v48, vcc
	v_mul_f32_e32 v48, v50, v85
	v_cmp_ge_i32_e32 vcc, v120, v79
	s_nop 1
	v_cndmask_b32_e32 v58, 0, v48, vcc
	v_mul_f32_e32 v48, v51, v86
	v_cmp_ge_i32_e32 vcc, v120, v84
	s_nop 1
	v_cndmask_b32_e32 v51, 0, v48, vcc
	v_cmp_ge_i32_e32 vcc, v112, v66
	v_cvt_pk_bf16_f32 v48, v52, v53
	v_cvt_pk_bf16_f32 v49, v54, v55
	v_cvt_pk_bf16_f32 v50, v56, v57
	v_cvt_pk_bf16_f32 v51, v58, v51
	global_store_dwordx4 v[114:115], v[48:51], off offset:256
	s_nop 0
	v_cndmask_b32_e32 v44, 0, v44, vcc
	v_cmp_gt_i32_e32 vcc, v112, v66
	s_nop 1
	v_cndmask_b32_e32 v45, 0, v45, vcc
	v_cmp_ge_i32_e32 vcc, v112, v68
	s_nop 1
	v_cndmask_b32_e32 v46, 0, v46, vcc
	v_cmp_ge_i32_e32 vcc, v112, v70
	s_nop 1
	v_cndmask_b32_e32 v47, 0, v47, vcc
	v_cmp_ge_i32_e32 vcc, v112, v73
	s_nop 1
	v_cndmask_b32_e32 v48, 0, v40, vcc
	v_mul_f32_e32 v40, v41, v81
	v_cmp_ge_i32_e32 vcc, v112, v77
	s_nop 1
	v_cndmask_b32_e32 v49, 0, v40, vcc
	v_mul_f32_e32 v40, v42, v85
	v_cmp_ge_i32_e32 vcc, v112, v79
	s_nop 1
	v_cndmask_b32_e32 v50, 0, v40, vcc
	v_mul_f32_e32 v40, v43, v86
	v_cmp_ge_i32_e32 vcc, v112, v84
	s_nop 1
	v_cndmask_b32_e32 v43, 0, v40, vcc
	v_cmp_ge_i32_e32 vcc, v104, v66
	v_cvt_pk_bf16_f32 v40, v44, v45
	v_cvt_pk_bf16_f32 v41, v46, v47
	v_cvt_pk_bf16_f32 v42, v48, v49
	v_cvt_pk_bf16_f32 v43, v50, v43
	global_store_dwordx4 v[106:107], v[40:43], off offset:256
	s_nop 0
	v_cndmask_b32_e32 v36, 0, v36, vcc
	v_cmp_gt_i32_e32 vcc, v104, v66
	s_nop 1
	v_cndmask_b32_e32 v37, 0, v37, vcc
	v_cmp_ge_i32_e32 vcc, v104, v68
	s_nop 1
	v_cndmask_b32_e32 v38, 0, v38, vcc
	v_cmp_ge_i32_e32 vcc, v104, v70
	s_nop 1
	v_cndmask_b32_e32 v39, 0, v39, vcc
	v_cmp_ge_i32_e32 vcc, v104, v73
	s_nop 1
	v_cndmask_b32_e32 v40, 0, v32, vcc
	v_mul_f32_e32 v32, v33, v81
	v_cmp_ge_i32_e32 vcc, v104, v77
	s_nop 1
	v_cndmask_b32_e32 v41, 0, v32, vcc
	v_mul_f32_e32 v32, v34, v85
	v_cmp_ge_i32_e32 vcc, v104, v79
	s_nop 1
	v_cndmask_b32_e32 v42, 0, v32, vcc
	v_mul_f32_e32 v32, v35, v86
	v_cmp_ge_i32_e32 vcc, v104, v84
	s_nop 1
	v_cndmask_b32_e32 v35, 0, v32, vcc
	v_cmp_ge_i32_e32 vcc, v96, v66
	v_cvt_pk_bf16_f32 v32, v36, v37
	v_cvt_pk_bf16_f32 v33, v38, v39
	v_cvt_pk_bf16_f32 v34, v40, v41
	v_cvt_pk_bf16_f32 v35, v42, v35
	global_store_dwordx4 v[98:99], v[32:35], off offset:256
	s_nop 0
	v_cndmask_b32_e32 v28, 0, v28, vcc
	v_cmp_gt_i32_e32 vcc, v96, v66
	s_nop 1
	v_cndmask_b32_e32 v29, 0, v29, vcc
	v_cmp_ge_i32_e32 vcc, v96, v68
	s_nop 1
	v_cndmask_b32_e32 v30, 0, v30, vcc
	v_cmp_ge_i32_e32 vcc, v96, v70
	s_nop 1
	v_cndmask_b32_e32 v31, 0, v31, vcc
	v_cmp_ge_i32_e32 vcc, v96, v73
	s_nop 1
	v_cndmask_b32_e32 v32, 0, v24, vcc
	v_mul_f32_e32 v24, v25, v81
	v_cmp_ge_i32_e32 vcc, v96, v77
	s_nop 1
	v_cndmask_b32_e32 v33, 0, v24, vcc
	v_mul_f32_e32 v24, v26, v85
	v_cmp_ge_i32_e32 vcc, v96, v79
	s_nop 1
	v_cndmask_b32_e32 v34, 0, v24, vcc
	v_mul_f32_e32 v24, v27, v86
	v_cmp_ge_i32_e32 vcc, v96, v84
	s_nop 1
	v_cndmask_b32_e32 v27, 0, v24, vcc
	v_cmp_ge_i32_e32 vcc, v88, v66
	v_cvt_pk_bf16_f32 v24, v28, v29
	v_cvt_pk_bf16_f32 v25, v30, v31
	v_cvt_pk_bf16_f32 v26, v32, v33
	v_cvt_pk_bf16_f32 v27, v34, v27
	global_store_dwordx4 v[90:91], v[24:27], off offset:256
	s_nop 0
	v_cndmask_b32_e32 v20, 0, v20, vcc
	v_cmp_gt_i32_e32 vcc, v88, v66
	s_nop 1
	v_cndmask_b32_e32 v21, 0, v21, vcc
	v_cmp_ge_i32_e32 vcc, v88, v68
	s_nop 1
	v_cndmask_b32_e32 v22, 0, v22, vcc
	v_cmp_ge_i32_e32 vcc, v88, v70
	s_nop 1
	v_cndmask_b32_e32 v23, 0, v23, vcc
	v_cmp_ge_i32_e32 vcc, v88, v73
	s_nop 1
	v_cndmask_b32_e32 v24, 0, v16, vcc
	v_mul_f32_e32 v16, v17, v81
	v_cmp_ge_i32_e32 vcc, v88, v77
	s_nop 1
	v_cndmask_b32_e32 v25, 0, v16, vcc
	v_mul_f32_e32 v16, v18, v85
	v_cmp_ge_i32_e32 vcc, v88, v79
	s_nop 1
	v_cndmask_b32_e32 v26, 0, v16, vcc
	v_mul_f32_e32 v16, v19, v86
	v_cmp_ge_i32_e32 vcc, v88, v84
	s_nop 1
	v_cndmask_b32_e32 v19, 0, v16, vcc
	v_cmp_ge_i32_e32 vcc, v80, v66
	v_cvt_pk_bf16_f32 v16, v20, v21
	v_cvt_pk_bf16_f32 v17, v22, v23
	v_cvt_pk_bf16_f32 v18, v24, v25
	v_cvt_pk_bf16_f32 v19, v26, v19
	global_store_dwordx4 v[82:83], v[16:19], off offset:256
	s_nop 0
	v_cndmask_b32_e32 v12, 0, v12, vcc
	v_cmp_gt_i32_e32 vcc, v80, v66
	s_nop 1
	v_cndmask_b32_e32 v13, 0, v13, vcc
	v_cmp_ge_i32_e32 vcc, v80, v68
	s_nop 1
	v_cndmask_b32_e32 v14, 0, v14, vcc
	v_cmp_ge_i32_e32 vcc, v80, v70
	s_nop 1
	v_cndmask_b32_e32 v15, 0, v15, vcc
	v_cmp_ge_i32_e32 vcc, v80, v73
	s_nop 1
	v_cndmask_b32_e32 v16, 0, v8, vcc
	v_mul_f32_e32 v8, v9, v81
	v_cmp_ge_i32_e32 vcc, v80, v77
	s_nop 1
	v_cndmask_b32_e32 v17, 0, v8, vcc
	v_mul_f32_e32 v8, v10, v85
	v_cmp_ge_i32_e32 vcc, v80, v79
	s_nop 1
	v_cndmask_b32_e32 v18, 0, v8, vcc
	v_mul_f32_e32 v8, v11, v86
	v_cmp_ge_i32_e32 vcc, v80, v84
	s_nop 1
	v_cndmask_b32_e32 v11, 0, v8, vcc
	v_cmp_ge_i32_e32 vcc, v72, v66
	v_cvt_pk_bf16_f32 v8, v12, v13
	v_cvt_pk_bf16_f32 v9, v14, v15
	v_cvt_pk_bf16_f32 v10, v16, v17
	v_cvt_pk_bf16_f32 v11, v18, v11
	global_store_dwordx4 v[74:75], v[8:11], off offset:256
	s_nop 0
	v_cndmask_b32_e32 v4, 0, v4, vcc
	v_cmp_gt_i32_e32 vcc, v72, v66
	s_nop 1
	v_cndmask_b32_e32 v5, 0, v5, vcc
	v_cmp_ge_i32_e32 vcc, v72, v68
	s_nop 1
	v_cndmask_b32_e32 v6, 0, v6, vcc
	v_cmp_ge_i32_e32 vcc, v72, v70
	s_nop 1
	v_cndmask_b32_e32 v7, 0, v7, vcc
	v_cmp_ge_i32_e32 vcc, v72, v73
	s_nop 1
	v_cndmask_b32_e32 v8, 0, v0, vcc
	v_mul_f32_e32 v0, v1, v81
	v_cmp_ge_i32_e32 vcc, v72, v77
	s_nop 1
	v_cndmask_b32_e32 v9, 0, v0, vcc
	v_mul_f32_e32 v0, v2, v85
	v_cmp_ge_i32_e32 vcc, v72, v79
	s_nop 1
	v_cndmask_b32_e32 v10, 0, v0, vcc
	v_mul_f32_e32 v0, v3, v86
	v_cmp_ge_i32_e32 vcc, v72, v84
	s_nop 1
	v_cndmask_b32_e32 v3, 0, v0, vcc
	s_andn2_b64 vcc, exec, s[42:43]
	v_cvt_pk_bf16_f32 v0, v4, v5
	v_cvt_pk_bf16_f32 v1, v6, v7
	v_cvt_pk_bf16_f32 v2, v8, v9
	v_cvt_pk_bf16_f32 v3, v10, v3
	global_store_dwordx4 v[64:65], v[0:3], off offset:256
	s_cbranch_vccnz .LBB0_651
	s_andn2_b64 vcc, exec, s[16:17]
	s_cbranch_vccnz .LBB0_650
	s_barrier
	s_branch .LBB0_650

; #define PG8_STAGE(bufoff, gbase, voff) do { _Pragma("unroll") for (int _i = 0; _i < 2; ++_i) \
;         __builtin_amdgcn_global_load_lds((const unsigned*)((const char*)(gbase) + (voff)[_i]), (LAS unsigned*)(lds + (bufoff) + ldsw + _i * 8192), 16, 0, 0); } while (0)
; #define PG8_LDA(dst, b, h) do { _Pragma("unroll") for (int m = 0; m < 4; ++m) _Pragma("unroll") for (int k = 0; k < 2; ++k) dst[m][k] = *(const LAS bf16x8*)(lds + PG8_SA(b, h) + aoff + m * 2048 + k * 1024); } while (0)
; #define PG8_LDB(dst, b, h) do { _Pragma("unroll") for (int n = 0; n < 2; ++n) _Pragma("unroll") for (int k = 0; k < 2; ++k) dst[n][k] = *(const LAS bf16x8*)(lds + PG8_SB(b, h) + boff + n * 2048 + k * 1024); } while (0)
; #define PG8_MMA(ai, bj, At, Bt) do { __builtin_amdgcn_s_setprio(1); _Pragma("unroll") for (int m = 0; m < 4; ++m) _Pragma("unroll") for (int n = 0; n < 2; ++n) _Pragma("unroll") for (int k = 0; k < 2; ++k) \
;         acc[ai][bj][m][n] = __builtin_amdgcn_mfma_f32_16x16x32_bf16(Bt[n][k], At[m][k], acc[ai][bj][m][n], 0, 0, 0); __builtin_amdgcn_s_setprio(0); } while (0)
; template <class Epi, class Map>
; __device__ __forceinline__ void gemm_phase(LAS unsigned char* lds, const Gemm g, const Sched<Map>& S, const Epi& E) {
;     ...
;         const bool has_next = S.next(ui + 1, nxt);
;         const char* nA = has_next ? (const char*)g.A + nxt.aoff : cA; const char* nB = has_next ? (const char*)g.Bt + nxt.boff : cB;
; #pragma unroll 1
;         for (int t = 0; t < nt; t += 2) {
;             const bool last = (t == nt - 2);
;             const char* a1 = cA + (size_t)(t + 1) * kstep;
;             const char* a2 = last ? nA : cA + (size_t)(t + 2) * kstep; const char* b2 = last ? nB : cB + (size_t)(t + 2) * kstep;
;             const char* a3 = a2 + kstep; const char* b3 = b2 + kstep;
;             PG8_LDB(B0, 0, 0); PG8_LDB(B1, 0, 1); PG8_SCHED; PG8_LDA(At, 0, 0); PG8_STAGE(PG8_SA(1, 1), a1 + hstepA, voffA);
;             PG8_WAIT_V(8); PG8_WAIT_L(0); PG8_BAR; PG8_MMA(0, 0, At, B0); PG8_MMA(0, 1, At, B1); PG8_BAR; PG8_SCHED;
;     ...
; #pragma unroll
;         for (int a = 0; a < 2; ++a)
; #pragma unroll
;             for (int b = 0; b < 2; ++b)
; #pragma unroll
;                 for (int m = 0; m < 4; ++m)
; #pragma unroll
;                     for (int n = 0; n < 2; ++n) acc[a][b][m][n] = (f32x4){0.f, 0.f, 0.f, 0.f};
;         cur = nxt; cA = nA; cB = nB; ++ui;
.LBB0_678:
	v_readlane_b32 s12, v246, 43
	s_add_u32 s24, s12, s11
	v_readlane_b32 s12, v246, 44
	s_addc_u32 s25, s12, 0
	s_and_b64 s[12:13], s[42:43], exec
	s_cselect_b32 s12, s25, s35
	s_cselect_b32 s13, s24, s34
	s_add_u32 s28, s76, s10
	s_addc_u32 s29, s64, 0
	s_and_b64 s[14:15], s[42:43], exec
	v_mov_b32_e32 v0, 0
	s_cselect_b32 s14, s29, s31
	s_cselect_b32 s15, s28, s30
	s_mov_b64 s[46:47], 0
	s_mov_b64 s[36:37], -1
	s_mov_b64 s[44:45], 0
	v_mov_b32_e32 v1, v0
	v_mov_b32_e32 v2, v0
	v_mov_b32_e32 v3, v0
	v_mov_b32_e32 v4, v0
	v_mov_b32_e32 v5, v0
	v_mov_b32_e32 v6, v0
	v_mov_b32_e32 v7, v0
	v_mov_b32_e32 v8, v0
	v_mov_b32_e32 v9, v0
	v_mov_b32_e32 v10, v0
	v_mov_b32_e32 v11, v0
	v_mov_b32_e32 v16, v0
	v_mov_b32_e32 v17, v0
	v_mov_b32_e32 v18, v0
	v_mov_b32_e32 v19, v0
	v_mov_b32_e32 v24, v0
	v_mov_b32_e32 v25, v0
	v_mov_b32_e32 v26, v0
	v_mov_b32_e32 v27, v0
	v_mov_b32_e32 v32, v0
	v_mov_b32_e32 v33, v0
	v_mov_b32_e32 v34, v0
	v_mov_b32_e32 v35, v0
	v_mov_b32_e32 v40, v0
	v_mov_b32_e32 v41, v0
	v_mov_b32_e32 v42, v0
	v_mov_b32_e32 v43, v0
	v_mov_b32_e32 v48, v0
	v_mov_b32_e32 v49, v0
	v_mov_b32_e32 v50, v0
	v_mov_b32_e32 v51, v0
	v_mov_b32_e32 v12, v0
	v_mov_b32_e32 v13, v0
	v_mov_b32_e32 v14, v0
	v_mov_b32_e32 v15, v0
	v_mov_b32_e32 v20, v0
	v_mov_b32_e32 v21, v0
	v_mov_b32_e32 v22, v0
	v_mov_b32_e32 v23, v0
	v_mov_b32_e32 v28, v0
	v_mov_b32_e32 v29, v0
	v_mov_b32_e32 v30, v0
	v_mov_b32_e32 v31, v0
	v_mov_b32_e32 v36, v0
	v_mov_b32_e32 v37, v0
	v_mov_b32_e32 v38, v0
	v_mov_b32_e32 v39, v0
	v_mov_b32_e32 v44, v0
	v_mov_b32_e32 v45, v0
	v_mov_b32_e32 v46, v0
	v_mov_b32_e32 v47, v0
	v_mov_b32_e32 v52, v0
	v_mov_b32_e32 v53, v0
	v_mov_b32_e32 v54, v0
	v_mov_b32_e32 v55, v0
	v_mov_b32_e32 v56, v0
	v_mov_b32_e32 v57, v0
	v_mov_b32_e32 v58, v0
	v_mov_b32_e32 v59, v0
	v_mov_b32_e32 v60, v0
	v_mov_b32_e32 v61, v0
	v_mov_b32_e32 v62, v0
	v_mov_b32_e32 v63, v0
	v_mov_b32_e32 v64, v0
	v_mov_b32_e32 v65, v0
	v_mov_b32_e32 v66, v0
	v_mov_b32_e32 v67, v0
	v_mov_b32_e32 v68, v0
	v_mov_b32_e32 v69, v0
	v_mov_b32_e32 v70, v0
	v_mov_b32_e32 v71, v0
	v_mov_b32_e32 v72, v0
	v_mov_b32_e32 v73, v0
	v_mov_b32_e32 v74, v0
	v_mov_b32_e32 v75, v0
	v_mov_b32_e32 v80, v0
	v_mov_b32_e32 v81, v0
	v_mov_b32_e32 v82, v0
	v_mov_b32_e32 v83, v0
	v_mov_b32_e32 v88, v0
	v_mov_b32_e32 v89, v0
	v_mov_b32_e32 v90, v0
	v_mov_b32_e32 v91, v0
	v_mov_b32_e32 v96, v0
	v_mov_b32_e32 v97, v0
	v_mov_b32_e32 v98, v0
	v_mov_b32_e32 v99, v0
	v_mov_b32_e32 v104, v0
	v_mov_b32_e32 v105, v0
	v_mov_b32_e32 v106, v0
	v_mov_b32_e32 v107, v0
	v_mov_b32_e32 v112, v0
	v_mov_b32_e32 v113, v0
	v_mov_b32_e32 v114, v0
	v_mov_b32_e32 v115, v0
	v_mov_b32_e32 v76, v0
	v_mov_b32_e32 v77, v0
	v_mov_b32_e32 v78, v0
	v_mov_b32_e32 v79, v0
	v_mov_b32_e32 v84, v0
	v_mov_b32_e32 v85, v0
	v_mov_b32_e32 v86, v0
	v_mov_b32_e32 v87, v0
	v_mov_b32_e32 v92, v0
	v_mov_b32_e32 v93, v0
	v_mov_b32_e32 v94, v0
	v_mov_b32_e32 v95, v0
	v_mov_b32_e32 v100, v0
	v_mov_b32_e32 v101, v0
	v_mov_b32_e32 v102, v0
	v_mov_b32_e32 v103, v0
	v_mov_b32_e32 v108, v0
	v_mov_b32_e32 v109, v0
	v_mov_b32_e32 v110, v0
	v_mov_b32_e32 v111, v0
	v_mov_b32_e32 v116, v0
	v_mov_b32_e32 v117, v0
	v_mov_b32_e32 v118, v0
	v_mov_b32_e32 v119, v0
	v_mov_b32_e32 v120, v0
	v_mov_b32_e32 v121, v0
	v_mov_b32_e32 v122, v0
	v_mov_b32_e32 v123, v0
	v_mov_b32_e32 v124, v0
	v_mov_b32_e32 v125, v0
	v_mov_b32_e32 v126, v0
	v_mov_b32_e32 v127, v0
.LBB0_679:
	s_add_u32 s21, s34, s46
	s_addc_u32 s33, s35, s47
	s_add_u32 s48, s21, 0x100
	s_addc_u32 s49, s33, 0
	s_and_b64 s[38:39], s[44:45], exec
	s_cselect_b32 s49, s12, s49
	s_cselect_b32 s48, s13, s48
	s_add_u32 s38, s30, s46
	s_addc_u32 s39, s31, s47
	s_add_u32 s46, s38, 0x100
	s_addc_u32 s47, s39, 0
	s_add_i32 s62, 0, 0x10000
	s_and_b64 s[38:39], s[44:45], exec
	s_cselect_b32 s51, s14, s47
	s_cselect_b32 s50, s15, s46
	s_add_i32 s45, 0, 0x14000
	s_add_u32 s54, s21, 0x20080
	s_addc_u32 s55, s33, 0
	s_add_i32 s59, s62, s0
	s_add_i32 m0, s1, 0xc000
	s_add_i32 s63, s1, 0xe000
	s_add_i32 s56, s59, 0x2000
	v_add_u32_e32 v134, s62, v138
	s_add_u32 s52, s50, 0x10000
	ds_read_b128 v[140:143], v134
	ds_read_b128 v[160:163], v134 offset:1024
	ds_read_b128 v[164:167], v134 offset:2048
	ds_read_b128 v[168:171], v134 offset:3072
	v_add_u32_e32 v134, s45, v138
	s_addc_u32 s53, s51, 0
	s_add_i32 s58, s45, s0
	ds_read_b128 v[172:175], v134
	ds_read_b128 v[176:179], v134 offset:1024
	ds_read_b128 v[192:195], v134 offset:2048
	ds_read_b128 v[196:199], v134 offset:3072
	s_add_i32 s57, s58, 0x2000
	s_add_i32 s39, 0, 0x18000
	s_add_i32 s38, 0, 0x1c000
	s_add_u32 s46, s48, 0x20000
	s_addc_u32 s47, s49, 0
	s_add_i32 s33, s39, s0
	s_add_i32 s21, s33, 0x2000
	s_add_u32 s44, s50, 0x10080
	s_addc_u32 s45, s51, 0
	s_add_i32 s66, s38, s0
	s_add_i32 s65, s66, 0x2000
	v_lshl_add_u64 v[134:135], s[54:55], 0, v[132:133]
	ds_read_b128 v[200:203], v139
	ds_read_b128 v[204:207], v139 offset:1024
	ds_read_b128 v[208:211], v139 offset:2048
	ds_read_b128 v[212:215], v139 offset:3072
	ds_read_b128 v[216:219], v139 offset:4096
	ds_read_b128 v[220:223], v139 offset:5120
	ds_read_b128 v[224:227], v139 offset:6144
	ds_read_b128 v[228:231], v139 offset:7168
	global_load_lds_dwordx4 v[134:135], off
	v_lshl_add_u64 v[134:135], s[54:55], 0, v[130:131]
	s_mov_b32 m0, s63
	s_nop 0
	global_load_lds_dwordx4 v[134:135], off
	s_waitcnt vmcnt(8)
	s_waitcnt lgkmcnt(0)
	s_barrier
; #define PG8_STAGE(bufoff, gbase, voff) do { _Pragma("unroll") for (int _i = 0; _i < 2; ++_i) \
;         __builtin_amdgcn_global_load_lds((const unsigned*)((const char*)(gbase) + (voff)[_i]), (LAS unsigned*)(lds + (bufoff) + ldsw + _i * 8192), 16, 0, 0); } while (0)
; #define PG8_LDA(dst, b, h) do { _Pragma("unroll") for (int m = 0; m < 4; ++m) _Pragma("unroll") for (int k = 0; k < 2; ++k) dst[m][k] = *(const LAS bf16x8*)(lds + PG8_SA(b, h) + aoff + m * 2048 + k * 1024); } while (0)
; #define PG8_LDB(dst, b, h) do { _Pragma("unroll") for (int n = 0; n < 2; ++n) _Pragma("unroll") for (int k = 0; k < 2; ++k) dst[n][k] = *(const LAS bf16x8*)(lds + PG8_SB(b, h) + boff + n * 2048 + k * 1024); } while (0)
; #define PG8_MMA(ai, bj, At, Bt) do { __builtin_amdgcn_s_setprio(1); _Pragma("unroll") for (int m = 0; m < 4; ++m) _Pragma("unroll") for (int n = 0; n < 2; ++n) _Pragma("unroll") for (int k = 0; k < 2; ++k) \
;         acc[ai][bj][m][n] = __builtin_amdgcn_mfma_f32_16x16x32_bf16(Bt[n][k], At[m][k], acc[ai][bj][m][n], 0, 0, 0); __builtin_amdgcn_s_setprio(0); } while (0)
; #define PG8_WAIT_V(n) asm volatile("s_waitcnt vmcnt(" #n ")" ::: "memory")
; #define PG8_WAIT_L(n) asm volatile("s_waitcnt lgkmcnt(" #n ")" ::: "memory")
; #define PG8_BAR __builtin_amdgcn_s_barrier()
; #define PG8_SCHED __builtin_amdgcn_sched_barrier(0)
; template <class Epi, class Map>
; __device__ __forceinline__ void gemm_phase(LAS unsigned char* lds, const Gemm g, const Sched<Map>& S, const Epi& E) {
;     ...
;             PG8_WAIT_V(8); PG8_WAIT_L(0); PG8_BAR; PG8_MMA(0, 0, At, B0); PG8_MMA(0, 1, At, B1); PG8_BAR; PG8_SCHED;
;             PG8_LDA(At, 0, 1); PG8_STAGE(PG8_SB(0, 0), b2, voffB); PG8_STAGE(PG8_SB(0, 1), b2 + hstepB, voffB); PG8_STAGE(PG8_SA(0, 0), a2, voffA);
;             PG8_WAIT_V(8); PG8_WAIT_L(0); PG8_BAR; PG8_MMA(1, 0, At, B0); PG8_MMA(1, 1, At, B1); PG8_BAR; PG8_SCHED;
;             PG8_LDB(B0, 1, 0); PG8_LDB(B1, 1, 1); PG8_SCHED; PG8_LDA(At, 1, 0); PG8_STAGE(PG8_SA(0, 1), a2 + hstepA, voffA);
	s_waitcnt lgkmcnt(0)
	v_mfma_f32_16x16x32_bf16 v[124:127], v[140:143], v[200:203], v[124:127]
	v_mfma_f32_16x16x32_bf16 v[120:123], v[164:167], v[200:203], v[120:123]
	v_mfma_f32_16x16x32_bf16 v[116:119], v[140:143], v[208:211], v[116:119]
	v_mfma_f32_16x16x32_bf16 v[108:111], v[164:167], v[208:211], v[108:111]
	v_mfma_f32_16x16x32_bf16 v[100:103], v[140:143], v[216:219], v[100:103]
	v_mfma_f32_16x16x32_bf16 v[92:95], v[164:167], v[216:219], v[92:95]
	v_mfma_f32_16x16x32_bf16 v[84:87], v[140:143], v[224:227], v[84:87]
	v_mfma_f32_16x16x32_bf16 v[76:79], v[164:167], v[224:227], v[76:79]
	v_mfma_f32_16x16x32_bf16 v[124:127], v[160:163], v[204:207], v[124:127]
	v_mfma_f32_16x16x32_bf16 v[120:123], v[168:171], v[204:207], v[120:123]
	v_mfma_f32_16x16x32_bf16 v[116:119], v[160:163], v[212:215], v[116:119]
	v_mfma_f32_16x16x32_bf16 v[108:111], v[168:171], v[212:215], v[108:111]
	v_mfma_f32_16x16x32_bf16 v[100:103], v[160:163], v[220:223], v[100:103]
	v_mfma_f32_16x16x32_bf16 v[92:95], v[168:171], v[220:223], v[92:95]
	v_mfma_f32_16x16x32_bf16 v[84:87], v[160:163], v[228:231], v[84:87]
	v_mfma_f32_16x16x32_bf16 v[76:79], v[168:171], v[228:231], v[76:79]
	v_mfma_f32_16x16x32_bf16 v[112:115], v[172:175], v[200:203], v[112:115]
	v_mfma_f32_16x16x32_bf16 v[104:107], v[192:195], v[200:203], v[104:107]
	v_mfma_f32_16x16x32_bf16 v[96:99], v[172:175], v[208:211], v[96:99]
	v_mfma_f32_16x16x32_bf16 v[88:91], v[192:195], v[208:211], v[88:91]
	v_mfma_f32_16x16x32_bf16 v[80:83], v[172:175], v[216:219], v[80:83]
	v_mfma_f32_16x16x32_bf16 v[72:75], v[192:195], v[216:219], v[72:75]
	v_mfma_f32_16x16x32_bf16 v[68:71], v[172:175], v[224:227], v[68:71]
	v_mfma_f32_16x16x32_bf16 v[64:67], v[192:195], v[224:227], v[64:67]
	v_mfma_f32_16x16x32_bf16 v[112:115], v[176:179], v[204:207], v[112:115]
	v_mfma_f32_16x16x32_bf16 v[104:107], v[196:199], v[204:207], v[104:107]
	v_mfma_f32_16x16x32_bf16 v[96:99], v[176:179], v[212:215], v[96:99]
	v_mfma_f32_16x16x32_bf16 v[88:91], v[196:199], v[212:215], v[88:91]
	v_mfma_f32_16x16x32_bf16 v[80:83], v[176:179], v[220:223], v[80:83]
	v_mfma_f32_16x16x32_bf16 v[72:75], v[196:199], v[220:223], v[72:75]
	v_mfma_f32_16x16x32_bf16 v[68:71], v[176:179], v[228:231], v[68:71]
	v_mfma_f32_16x16x32_bf16 v[64:67], v[196:199], v[228:231], v[64:67]
	s_barrier
	s_mov_b32 m0, s59
	v_lshl_add_u64 v[134:135], s[50:51], 0, v[144:145]
	ds_read_b128 v[200:203], v139 offset:16384
	ds_read_b128 v[204:207], v139 offset:17408
	ds_read_b128 v[208:211], v139 offset:18432
	ds_read_b128 v[212:215], v139 offset:19456
	ds_read_b128 v[216:219], v139 offset:20480
	ds_read_b128 v[220:223], v139 offset:21504
	ds_read_b128 v[224:227], v139 offset:22528
	ds_read_b128 v[228:231], v139 offset:23552
	global_load_lds_dwordx4 v[134:135], off
	v_lshl_add_u64 v[180:181], s[50:51], 0, v[128:129]
	s_mov_b32 m0, s56
	v_lshl_add_u64 v[232:233], s[52:53], 0, v[144:145]
	global_load_lds_dwordx4 v[180:181], off
	s_mov_b32 m0, s58
	v_lshl_add_u64 v[234:235], s[48:49], 0, v[130:131]
	global_load_lds_dwordx4 v[232:233], off
	v_lshl_add_u64 v[232:233], s[52:53], 0, v[128:129]
	s_mov_b32 m0, s57
	s_nop 0
	global_load_lds_dwordx4 v[232:233], off
	v_lshl_add_u64 v[232:233], s[48:49], 0, v[132:133]
	s_mov_b32 m0, s1
	s_nop 0
	global_load_lds_dwordx4 v[232:233], off
	s_mov_b32 m0, s2
	s_nop 0
	global_load_lds_dwordx4 v[234:235], off
	s_waitcnt vmcnt(8)
	s_waitcnt lgkmcnt(0)
	s_barrier
	s_waitcnt lgkmcnt(0)
	v_mfma_f32_16x16x32_bf16 v[60:63], v[140:143], v[200:203], v[60:63]
	v_mfma_f32_16x16x32_bf16 v[56:59], v[164:167], v[200:203], v[56:59]
	v_mfma_f32_16x16x32_bf16 v[52:55], v[140:143], v[208:211], v[52:55]
	v_mfma_f32_16x16x32_bf16 v[44:47], v[164:167], v[208:211], v[44:47]
	v_mfma_f32_16x16x32_bf16 v[36:39], v[140:143], v[216:219], v[36:39]
	v_mfma_f32_16x16x32_bf16 v[28:31], v[164:167], v[216:219], v[28:31]
	v_mfma_f32_16x16x32_bf16 v[20:23], v[140:143], v[224:227], v[20:23]
	v_mfma_f32_16x16x32_bf16 v[12:15], v[164:167], v[224:227], v[12:15]
	v_mfma_f32_16x16x32_bf16 v[60:63], v[160:163], v[204:207], v[60:63]
	v_mfma_f32_16x16x32_bf16 v[56:59], v[168:171], v[204:207], v[56:59]
	v_mfma_f32_16x16x32_bf16 v[52:55], v[160:163], v[212:215], v[52:55]
	v_mfma_f32_16x16x32_bf16 v[44:47], v[168:171], v[212:215], v[44:47]
	v_mfma_f32_16x16x32_bf16 v[36:39], v[160:163], v[220:223], v[36:39]
	v_mfma_f32_16x16x32_bf16 v[28:31], v[168:171], v[220:223], v[28:31]
	v_mfma_f32_16x16x32_bf16 v[20:23], v[160:163], v[228:231], v[20:23]
	v_mfma_f32_16x16x32_bf16 v[12:15], v[168:171], v[228:231], v[12:15]
	v_mfma_f32_16x16x32_bf16 v[48:51], v[172:175], v[200:203], v[48:51]
	v_mfma_f32_16x16x32_bf16 v[40:43], v[192:195], v[200:203], v[40:43]
	v_mfma_f32_16x16x32_bf16 v[32:35], v[172:175], v[208:211], v[32:35]
	v_mfma_f32_16x16x32_bf16 v[24:27], v[192:195], v[208:211], v[24:27]
	v_mfma_f32_16x16x32_bf16 v[16:19], v[172:175], v[216:219], v[16:19]
	v_mfma_f32_16x16x32_bf16 v[8:11], v[192:195], v[216:219], v[8:11]
	v_mfma_f32_16x16x32_bf16 v[4:7], v[172:175], v[224:227], v[4:7]
	v_mfma_f32_16x16x32_bf16 v[0:3], v[192:195], v[224:227], v[0:3]
	v_mfma_f32_16x16x32_bf16 v[48:51], v[176:179], v[204:207], v[48:51]
	v_mfma_f32_16x16x32_bf16 v[40:43], v[196:199], v[204:207], v[40:43]
	v_mfma_f32_16x16x32_bf16 v[32:35], v[176:179], v[212:215], v[32:35]
	v_mfma_f32_16x16x32_bf16 v[24:27], v[196:199], v[212:215], v[24:27]
	v_mfma_f32_16x16x32_bf16 v[16:19], v[176:179], v[220:223], v[16:19]
	v_mfma_f32_16x16x32_bf16 v[8:11], v[196:199], v[220:223], v[8:11]
	v_mfma_f32_16x16x32_bf16 v[4:7], v[176:179], v[228:231], v[4:7]
	v_mfma_f32_16x16x32_bf16 v[0:3], v[196:199], v[228:231], v[0:3]
	s_barrier
; #define PG8_STAGE(bufoff, gbase, voff) do { _Pragma("unroll") for (int _i = 0; _i < 2; ++_i) \
;         __builtin_amdgcn_global_load_lds((const unsigned*)((const char*)(gbase) + (voff)[_i]), (LAS unsigned*)(lds + (bufoff) + ldsw + _i * 8192), 16, 0, 0); } while (0)
; #define PG8_LDA(dst, b, h) do { _Pragma("unroll") for (int m = 0; m < 4; ++m) _Pragma("unroll") for (int k = 0; k < 2; ++k) dst[m][k] = *(const LAS bf16x8*)(lds + PG8_SA(b, h) + aoff + m * 2048 + k * 1024); } while (0)
; #define PG8_LDB(dst, b, h) do { _Pragma("unroll") for (int n = 0; n < 2; ++n) _Pragma("unroll") for (int k = 0; k < 2; ++k) dst[n][k] = *(const LAS bf16x8*)(lds + PG8_SB(b, h) + boff + n * 2048 + k * 1024); } while (0)
; #define PG8_MMA(ai, bj, At, Bt) do { __builtin_amdgcn_s_setprio(1); _Pragma("unroll") for (int m = 0; m < 4; ++m) _Pragma("unroll") for (int n = 0; n < 2; ++n) _Pragma("unroll") for (int k = 0; k < 2; ++k) \
;         acc[ai][bj][m][n] = __builtin_amdgcn_mfma_f32_16x16x32_bf16(Bt[n][k], At[m][k], acc[ai][bj][m][n], 0, 0, 0); __builtin_amdgcn_s_setprio(0); } while (0)
; #define PG8_WAIT_V(n) asm volatile("s_waitcnt vmcnt(" #n ")" ::: "memory")
; #define PG8_WAIT_L(n) asm volatile("s_waitcnt lgkmcnt(" #n ")" ::: "memory")
; #define PG8_BAR __builtin_amdgcn_s_barrier()
; #define PG8_SCHED __builtin_amdgcn_sched_barrier(0)
; template <class Epi, class Map>
; __device__ __forceinline__ void gemm_phase(LAS unsigned char* lds, const Gemm g, const Sched<Map>& S, const Epi& E) {
;     ...
;             PG8_LDB(B0, 1, 0); PG8_LDB(B1, 1, 1); PG8_SCHED; PG8_LDA(At, 1, 0); PG8_STAGE(PG8_SA(0, 1), a2 + hstepA, voffA);
;             PG8_WAIT_V(8); PG8_WAIT_L(0); PG8_BAR; PG8_MMA(0, 0, At, B0); PG8_MMA(0, 1, At, B1); PG8_BAR; PG8_SCHED;
;             PG8_LDA(At, 1, 1); PG8_STAGE(PG8_SB(1, 0), b3, voffB); PG8_STAGE(PG8_SB(1, 1), b3 + hstepB, voffB); PG8_STAGE(PG8_SA(1, 0), a3, voffA);
;             PG8_WAIT_V(8); PG8_WAIT_L(0); PG8_BAR; PG8_MMA(1, 0, At, B0); PG8_MMA(1, 1, At, B1); PG8_BAR; PG8_SCHED;
;         }
;         if (wr == 0) PG8_BAR;
	v_add_u32_e32 v168, s39, v138
	v_add_u32_e32 v196, s38, v138
	ds_read_b128 v[140:143], v168
	ds_read_b128 v[160:163], v168 offset:1024
	ds_read_b128 v[164:167], v168 offset:2048
	ds_read_b128 v[168:171], v168 offset:3072
	ds_read_b128 v[172:175], v196
	ds_read_b128 v[176:179], v196 offset:1024
	ds_read_b128 v[192:195], v196 offset:2048
	ds_read_b128 v[196:199], v196 offset:3072
	s_mov_b32 m0, s3
	v_lshl_add_u64 v[236:237], s[46:47], 0, v[132:133]
	ds_read_b128 v[200:203], v139 offset:32768
	ds_read_b128 v[204:207], v139 offset:33792
	ds_read_b128 v[208:211], v139 offset:34816
	ds_read_b128 v[212:215], v139 offset:35840
	ds_read_b128 v[216:219], v139 offset:36864
	ds_read_b128 v[220:223], v139 offset:37888
	ds_read_b128 v[224:227], v139 offset:38912
	ds_read_b128 v[228:231], v139 offset:39936
	global_load_lds_dwordx4 v[236:237], off
	v_lshl_add_u64 v[236:237], s[46:47], 0, v[130:131]
	s_mov_b32 m0, s4
	s_nop 0
	global_load_lds_dwordx4 v[236:237], off
	s_waitcnt vmcnt(8)
	s_waitcnt lgkmcnt(0)
	s_barrier
	s_waitcnt lgkmcnt(0)
	v_mfma_f32_16x16x32_bf16 v[124:127], v[140:143], v[200:203], v[124:127]
	v_mfma_f32_16x16x32_bf16 v[120:123], v[164:167], v[200:203], v[120:123]
	v_mfma_f32_16x16x32_bf16 v[116:119], v[140:143], v[208:211], v[116:119]
	v_mfma_f32_16x16x32_bf16 v[108:111], v[164:167], v[208:211], v[108:111]
	v_mfma_f32_16x16x32_bf16 v[100:103], v[140:143], v[216:219], v[100:103]
	v_mfma_f32_16x16x32_bf16 v[92:95], v[164:167], v[216:219], v[92:95]
	v_mfma_f32_16x16x32_bf16 v[84:87], v[140:143], v[224:227], v[84:87]
	v_mfma_f32_16x16x32_bf16 v[76:79], v[164:167], v[224:227], v[76:79]
	v_mfma_f32_16x16x32_bf16 v[124:127], v[160:163], v[204:207], v[124:127]
	v_mfma_f32_16x16x32_bf16 v[120:123], v[168:171], v[204:207], v[120:123]
	v_mfma_f32_16x16x32_bf16 v[116:119], v[160:163], v[212:215], v[116:119]
	v_mfma_f32_16x16x32_bf16 v[108:111], v[168:171], v[212:215], v[108:111]
	v_mfma_f32_16x16x32_bf16 v[100:103], v[160:163], v[220:223], v[100:103]
	v_mfma_f32_16x16x32_bf16 v[92:95], v[168:171], v[220:223], v[92:95]
	v_mfma_f32_16x16x32_bf16 v[84:87], v[160:163], v[228:231], v[84:87]
	v_mfma_f32_16x16x32_bf16 v[76:79], v[168:171], v[228:231], v[76:79]
	v_mfma_f32_16x16x32_bf16 v[112:115], v[172:175], v[200:203], v[112:115]
	v_mfma_f32_16x16x32_bf16 v[104:107], v[192:195], v[200:203], v[104:107]
	v_mfma_f32_16x16x32_bf16 v[96:99], v[172:175], v[208:211], v[96:99]
	v_mfma_f32_16x16x32_bf16 v[88:91], v[192:195], v[208:211], v[88:91]
	v_mfma_f32_16x16x32_bf16 v[80:83], v[172:175], v[216:219], v[80:83]
	v_mfma_f32_16x16x32_bf16 v[72:75], v[192:195], v[216:219], v[72:75]
	v_mfma_f32_16x16x32_bf16 v[68:71], v[172:175], v[224:227], v[68:71]
	v_mfma_f32_16x16x32_bf16 v[64:67], v[192:195], v[224:227], v[64:67]
	v_mfma_f32_16x16x32_bf16 v[112:115], v[176:179], v[204:207], v[112:115]
	v_mfma_f32_16x16x32_bf16 v[104:107], v[196:199], v[204:207], v[104:107]
	v_mfma_f32_16x16x32_bf16 v[96:99], v[176:179], v[212:215], v[96:99]
	v_mfma_f32_16x16x32_bf16 v[88:91], v[196:199], v[212:215], v[88:91]
	v_mfma_f32_16x16x32_bf16 v[80:83], v[176:179], v[220:223], v[80:83]
	v_mfma_f32_16x16x32_bf16 v[72:75], v[196:199], v[220:223], v[72:75]
	v_mfma_f32_16x16x32_bf16 v[68:71], v[176:179], v[228:231], v[68:71]
	v_mfma_f32_16x16x32_bf16 v[64:67], v[196:199], v[228:231], v[64:67]
	s_barrier
	s_mov_b32 m0, s33
	v_lshl_add_u64 v[134:135], v[134:135], 0, s[82:83]
	ds_read_b128 v[200:203], v139 offset:49152
	ds_read_b128 v[204:207], v139 offset:50176
	ds_read_b128 v[208:211], v139 offset:51200
	ds_read_b128 v[212:215], v139 offset:52224
	ds_read_b128 v[216:219], v139 offset:53248
	ds_read_b128 v[220:223], v139 offset:54272
	ds_read_b128 v[224:227], v139 offset:55296
	ds_read_b128 v[228:231], v139 offset:56320
	global_load_lds_dwordx4 v[134:135], off
	v_lshl_add_u64 v[134:135], v[180:181], 0, s[82:83]
	s_mov_b32 m0, s21
	s_nop 0
	global_load_lds_dwordx4 v[134:135], off
	v_lshl_add_u64 v[134:135], s[44:45], 0, v[144:145]
	s_mov_b32 m0, s66
	s_nop 0
	global_load_lds_dwordx4 v[134:135], off
	v_lshl_add_u64 v[134:135], s[44:45], 0, v[128:129]
	s_mov_b32 m0, s65
	s_nop 0
	global_load_lds_dwordx4 v[134:135], off
	v_lshl_add_u64 v[134:135], v[232:233], 0, s[82:83]
	s_mov_b32 m0, s6
	s_nop 0
	global_load_lds_dwordx4 v[134:135], off
	v_lshl_add_u64 v[134:135], v[234:235], 0, s[82:83]
	s_mov_b32 m0, s7
	s_nop 0
	global_load_lds_dwordx4 v[134:135], off
	s_waitcnt vmcnt(8)
	s_waitcnt lgkmcnt(0)
	s_barrier
	s_waitcnt lgkmcnt(0)
	v_mfma_f32_16x16x32_bf16 v[60:63], v[140:143], v[200:203], v[60:63]
	v_mfma_f32_16x16x32_bf16 v[56:59], v[164:167], v[200:203], v[56:59]
	v_mfma_f32_16x16x32_bf16 v[52:55], v[140:143], v[208:211], v[52:55]
	v_mfma_f32_16x16x32_bf16 v[44:47], v[164:167], v[208:211], v[44:47]
	v_mfma_f32_16x16x32_bf16 v[36:39], v[140:143], v[216:219], v[36:39]
	v_mfma_f32_16x16x32_bf16 v[28:31], v[164:167], v[216:219], v[28:31]
	v_mfma_f32_16x16x32_bf16 v[20:23], v[140:143], v[224:227], v[20:23]
	v_mfma_f32_16x16x32_bf16 v[12:15], v[164:167], v[224:227], v[12:15]
	v_mfma_f32_16x16x32_bf16 v[60:63], v[160:163], v[204:207], v[60:63]
	v_mfma_f32_16x16x32_bf16 v[56:59], v[168:171], v[204:207], v[56:59]
	v_mfma_f32_16x16x32_bf16 v[52:55], v[160:163], v[212:215], v[52:55]
	v_mfma_f32_16x16x32_bf16 v[44:47], v[168:171], v[212:215], v[44:47]
	v_mfma_f32_16x16x32_bf16 v[36:39], v[160:163], v[220:223], v[36:39]
	v_mfma_f32_16x16x32_bf16 v[28:31], v[168:171], v[220:223], v[28:31]
	v_mfma_f32_16x16x32_bf16 v[20:23], v[160:163], v[228:231], v[20:23]
	v_mfma_f32_16x16x32_bf16 v[12:15], v[168:171], v[228:231], v[12:15]
	v_mfma_f32_16x16x32_bf16 v[48:51], v[172:175], v[200:203], v[48:51]
	v_mfma_f32_16x16x32_bf16 v[40:43], v[192:195], v[200:203], v[40:43]
	v_mfma_f32_16x16x32_bf16 v[32:35], v[172:175], v[208:211], v[32:35]
	v_mfma_f32_16x16x32_bf16 v[24:27], v[192:195], v[208:211], v[24:27]
	v_mfma_f32_16x16x32_bf16 v[16:19], v[172:175], v[216:219], v[16:19]
	v_mfma_f32_16x16x32_bf16 v[8:11], v[192:195], v[216:219], v[8:11]
	v_mfma_f32_16x16x32_bf16 v[4:7], v[172:175], v[224:227], v[4:7]
	v_mfma_f32_16x16x32_bf16 v[0:3], v[192:195], v[224:227], v[0:3]
	v_mfma_f32_16x16x32_bf16 v[48:51], v[176:179], v[204:207], v[48:51]
	v_mfma_f32_16x16x32_bf16 v[40:43], v[196:199], v[204:207], v[40:43]
	v_mfma_f32_16x16x32_bf16 v[32:35], v[176:179], v[212:215], v[32:35]
	v_mfma_f32_16x16x32_bf16 v[24:27], v[196:199], v[212:215], v[24:27]
	v_mfma_f32_16x16x32_bf16 v[16:19], v[176:179], v[220:223], v[16:19]
	v_mfma_f32_16x16x32_bf16 v[8:11], v[196:199], v[220:223], v[8:11]
	v_mfma_f32_16x16x32_bf16 v[4:7], v[176:179], v[228:231], v[4:7]
	v_mfma_f32_16x16x32_bf16 v[0:3], v[196:199], v[228:231], v[0:3]
	s_barrier
	s_andn2_b64 vcc, exec, s[36:37]
	s_mov_b64 s[44:45], -1
	s_mov_b64 s[36:37], 0
	s_mov_b64 s[46:47], 0x100
	s_cbranch_vccz .LBB0_679
	s_and_b64 vcc, exec, s[18:19]
	s_cbranch_vccz .LBB0_682
; __device__ __forceinline__ unsigned cvt_pk_bf16(float lo, float hi) { unsigned r; asm volatile("v_cvt_pk_bf16_f32 %0, %1, %2" : "=v"(r) : "v"(lo), "v"(hi)); return r; }
; __device__ __forceinline__ float silu_f(float v) { return v / (1.0f + __expf(-v)); }
; #define PG8_BAR __builtin_amdgcn_s_barrier()
; template <class Epi, class Map>
; __device__ __forceinline__ void gemm_phase(LAS unsigned char* lds, const Gemm g, const Sched<Map>& S, const Epi& E) {
;     ...
;         if (wr == 0) PG8_BAR;
;         E(acc, cur, wr, wc, fr, fq);
;         if (!has_next) break;
; #pragma unroll
;         for (int a = 0; a < 2; ++a)
; #pragma unroll
;             for (int b = 0; b < 2; ++b)
; #pragma unroll
;                 for (int m = 0; m < 4; ++m)
; #pragma unroll
;                     for (int n = 0; n < 2; ++n) acc[a][b][m][n] = (f32x4){0.f, 0.f, 0.f, 0.f};
;         cur = nxt; cA = nA; cB = nB; ++ui;
;         if (wr == 1) PG8_BAR;
;     __device__ __forceinline__ void operator()(const Acc& acc, const Unit& u, int wr, int wc, int fr, int fq) const {
;     ...
;         bf16_t* base = O + u.coff + (size_t)(wr * 64 + fr) * ldc + wc * 32 + 8 * fq;
; #pragma unroll
;         for (int ai = 0; ai < 2; ++ai)
; #pragma unroll
;             for (int m = 0; m < 4; ++m) { bf16_t* rowp = base + (size_t)(ai * HALF + m * 16) * ldc;
; #pragma unroll
;                 for (int bj = 0; bj < 2; ++bj) { f32x4 v0 = acc[ai][bj][m][0], v1 = acc[ai][bj][m][1];
;                     if (ACT == 1) {
; #pragma unroll
;                         for (int j = 0; j < 4; ++j) { v0[j] = silu_f(v0[j]); v1[j] = silu_f(v1[j]); } }
;                     if (ACT == 2) {
; #pragma unroll
;                         for (int j = 0; j < 4; ++j) { const float a = fmaxf(v0[j], 0.f), b = fmaxf(v1[j], 0.f); v0[j] = a * a; v1[j] = b * b; } }
;                     u32x4 w; w.x = cvt_pk_bf16(v0[0], v0[1]); w.y = cvt_pk_bf16(v0[2], v0[3]); w.z = cvt_pk_bf16(v1[0], v1[1]); w.w = cvt_pk_bf16(v1[2], v1[3]);
;                     *(u32x4*)(rowp + bj * HALF) = w; } }
.LBB0_682:
	v_mov_b32_e32 v134, v136
	v_mov_b32_e32 v140, v137
	s_lshl_b64 s[12:13], s[60:61], 1
	v_readlane_b32 s14, v246, 43
	v_add_u32_e32 v134, s5, v134
	s_add_u32 s12, s14, s12
	v_readlane_b32 s14, v246, 44
	v_ashrrev_i32_e32 v135, 31, v134
	s_addc_u32 s13, s14, s13
	v_lshlrev_b64 v[134:135], 10, v[134:135]
	v_lshl_add_u64 v[134:135], s[12:13], 0, v[134:135]
	s_mov_b32 s21, s61
	v_lshlrev_b32_e32 v140, 3, v140
	v_lshl_add_u64 v[134:135], v[134:135], 0, s[20:21]
	v_ashrrev_i32_e32 v141, 31, v140
	v_lshl_add_u64 v[134:135], v[140:141], 1, v[134:135]
	s_movk_i32 s12, 0x4000
	v_cvt_pk_bf16_f32 v124, v124, v125
	v_cvt_pk_bf16_f32 v125, v126, v127
	v_cvt_pk_bf16_f32 v126, v120, v121
	v_cvt_pk_bf16_f32 v127, v122, v123
	global_store_dwordx4 v[134:135], v[124:127], off
	v_cvt_pk_bf16_f32 v112, v112, v113
	v_cvt_pk_bf16_f32 v113, v114, v115
	v_cvt_pk_bf16_f32 v114, v104, v105
	v_cvt_pk_bf16_f32 v115, v106, v107
	global_store_dwordx4 v[134:135], v[112:115], off offset:256
	v_cvt_pk_bf16_f32 v104, v116, v117
	v_cvt_pk_bf16_f32 v105, v118, v119
	v_cvt_pk_bf16_f32 v106, v108, v109
	v_add_co_u32_e32 v108, vcc, s12, v134
	s_mov_b32 s12, 0x8000
	s_nop 0
	v_addc_co_u32_e32 v109, vcc, 0, v135, vcc
	v_cvt_pk_bf16_f32 v107, v110, v111
	global_store_dwordx4 v[108:109], v[104:107], off
	v_cvt_pk_bf16_f32 v96, v96, v97
	v_cvt_pk_bf16_f32 v97, v98, v99
	v_cvt_pk_bf16_f32 v98, v88, v89
	v_cvt_pk_bf16_f32 v99, v90, v91
	global_store_dwordx4 v[108:109], v[96:99], off offset:256
	s_cmp_lg_u64 s[18:19], 0
	s_cbranch_scc0 .Llate_align_6
	s_barrier
.Llate_align_6:
	v_cvt_pk_bf16_f32 v88, v100, v101
	v_cvt_pk_bf16_f32 v89, v102, v103
	v_cvt_pk_bf16_f32 v90, v92, v93
	v_add_co_u32_e32 v92, vcc, s12, v134
	s_mov_b32 s12, 0xc000
	s_nop 0
	v_addc_co_u32_e32 v93, vcc, 0, v135, vcc
	v_cvt_pk_bf16_f32 v91, v94, v95
	global_store_dwordx4 v[92:93], v[88:91], off
	v_cvt_pk_bf16_f32 v80, v80, v81
	v_cvt_pk_bf16_f32 v81, v82, v83
	v_cvt_pk_bf16_f32 v82, v72, v73
	v_cvt_pk_bf16_f32 v83, v74, v75
	global_store_dwordx4 v[92:93], v[80:83], off offset:256
	v_cvt_pk_bf16_f32 v72, v84, v85
	v_cvt_pk_bf16_f32 v73, v86, v87
	v_cvt_pk_bf16_f32 v74, v76, v77
	v_add_co_u32_e32 v76, vcc, s12, v134
	s_mov_b32 s12, 0x20000
	s_nop 0
	v_addc_co_u32_e32 v77, vcc, 0, v135, vcc
	v_cvt_pk_bf16_f32 v75, v78, v79
	global_store_dwordx4 v[76:77], v[72:75], off
	v_cvt_pk_bf16_f32 v68, v68, v69
	v_cvt_pk_bf16_f32 v69, v70, v71
	v_cvt_pk_bf16_f32 v70, v64, v65
	v_cvt_pk_bf16_f32 v71, v66, v67
	global_store_dwordx4 v[76:77], v[68:71], off offset:256
	v_cvt_pk_bf16_f32 v60, v60, v61
	v_cvt_pk_bf16_f32 v61, v62, v63
	v_cvt_pk_bf16_f32 v62, v56, v57
	v_add_co_u32_e32 v56, vcc, s12, v134
	s_mov_b32 s12, 0x24000
	s_nop 0
	v_addc_co_u32_e32 v57, vcc, 0, v135, vcc
	v_cvt_pk_bf16_f32 v63, v58, v59
	global_store_dwordx4 v[56:57], v[60:63], off
	v_cvt_pk_bf16_f32 v48, v48, v49
	v_cvt_pk_bf16_f32 v49, v50, v51
	v_cvt_pk_bf16_f32 v50, v40, v41
	v_cvt_pk_bf16_f32 v51, v42, v43
	global_store_dwordx4 v[56:57], v[48:51], off offset:256
	v_cvt_pk_bf16_f32 v40, v52, v53
	v_cvt_pk_bf16_f32 v41, v54, v55
	v_cvt_pk_bf16_f32 v42, v44, v45
	v_add_co_u32_e32 v44, vcc, s12, v134
	s_mov_b32 s12, 0x28000
	s_nop 0
	v_addc_co_u32_e32 v45, vcc, 0, v135, vcc
	v_cvt_pk_bf16_f32 v43, v46, v47
	global_store_dwordx4 v[44:45], v[40:43], off
	v_cvt_pk_bf16_f32 v32, v32, v33
	v_cvt_pk_bf16_f32 v33, v34, v35
	v_cvt_pk_bf16_f32 v34, v24, v25
	v_cvt_pk_bf16_f32 v35, v26, v27
	global_store_dwordx4 v[44:45], v[32:35], off offset:256
	v_cvt_pk_bf16_f32 v24, v36, v37
	v_cvt_pk_bf16_f32 v25, v38, v39
	v_cvt_pk_bf16_f32 v26, v28, v29
	v_add_co_u32_e32 v28, vcc, s12, v134
	s_mov_b32 s12, 0x2c000
	s_nop 0
	v_addc_co_u32_e32 v29, vcc, 0, v135, vcc
	v_cvt_pk_bf16_f32 v27, v30, v31
	global_store_dwordx4 v[28:29], v[24:27], off
	v_cvt_pk_bf16_f32 v16, v16, v17
	v_cvt_pk_bf16_f32 v17, v18, v19
	v_cvt_pk_bf16_f32 v18, v8, v9
	v_cvt_pk_bf16_f32 v19, v10, v11
	global_store_dwordx4 v[28:29], v[16:19], off offset:256
	v_cvt_pk_bf16_f32 v8, v20, v21
	v_cvt_pk_bf16_f32 v9, v22, v23
	v_cvt_pk_bf16_f32 v10, v12, v13
	v_add_co_u32_e32 v12, vcc, s12, v134
	s_mov_b64 s[30:31], -1
	s_nop 0
	v_addc_co_u32_e32 v13, vcc, 0, v135, vcc
	s_andn2_b64 vcc, exec, s[42:43]
	v_cvt_pk_bf16_f32 v11, v14, v15
	global_store_dwordx4 v[12:13], v[8:11], off
	v_cvt_pk_bf16_f32 v4, v4, v5
	v_cvt_pk_bf16_f32 v5, v6, v7
	v_cvt_pk_bf16_f32 v6, v0, v1
	v_cvt_pk_bf16_f32 v7, v2, v3
	global_store_dwordx4 v[12:13], v[4:7], off offset:256
	s_cbranch_vccnz .LBB0_671
	s_andn2_b64 vcc, exec, s[16:17]
	s_cbranch_vccnz .LBB0_670
	s_barrier
	s_branch .LBB0_670

; #define PG8_STAGE(bufoff, gbase, voff) do { _Pragma("unroll") for (int _i = 0; _i < 2; ++_i) \
;         __builtin_amdgcn_global_load_lds((const unsigned*)((const char*)(gbase) + (voff)[_i]), (LAS unsigned*)(lds + (bufoff) + ldsw + _i * 8192), 16, 0, 0); } while (0)
; #define PG8_LDA(dst, b, h) do { _Pragma("unroll") for (int m = 0; m < 4; ++m) _Pragma("unroll") for (int k = 0; k < 2; ++k) dst[m][k] = *(const LAS bf16x8*)(lds + PG8_SA(b, h) + aoff + m * 2048 + k * 1024); } while (0)
; #define PG8_LDB(dst, b, h) do { _Pragma("unroll") for (int n = 0; n < 2; ++n) _Pragma("unroll") for (int k = 0; k < 2; ++k) dst[n][k] = *(const LAS bf16x8*)(lds + PG8_SB(b, h) + boff + n * 2048 + k * 1024); } while (0)
; #define PG8_MMA(ai, bj, At, Bt) do { __builtin_amdgcn_s_setprio(1); _Pragma("unroll") for (int m = 0; m < 4; ++m) _Pragma("unroll") for (int n = 0; n < 2; ++n) _Pragma("unroll") for (int k = 0; k < 2; ++k) \
;         acc[ai][bj][m][n] = __builtin_amdgcn_mfma_f32_16x16x32_bf16(Bt[n][k], At[m][k], acc[ai][bj][m][n], 0, 0, 0); __builtin_amdgcn_s_setprio(0); } while (0)
; template <class Epi, class Map>
; __device__ __forceinline__ void gemm_phase(LAS unsigned char* lds, const Gemm g, const Sched<Map>& S, const Epi& E) {
;     ...
;         const bool has_next = S.next(ui + 1, nxt);
;         const char* nA = has_next ? (const char*)g.A + nxt.aoff : cA; const char* nB = has_next ? (const char*)g.Bt + nxt.boff : cB;
; #pragma unroll 1
;         for (int t = 0; t < nt; t += 2) {
;             const bool last = (t == nt - 2);
;             const char* a1 = cA + (size_t)(t + 1) * kstep;
;             const char* a2 = last ? nA : cA + (size_t)(t + 2) * kstep; const char* b2 = last ? nB : cB + (size_t)(t + 2) * kstep;
;             const char* a3 = a2 + kstep; const char* b3 = b2 + kstep;
;             PG8_LDB(B0, 0, 0); PG8_LDB(B1, 0, 1); PG8_SCHED; PG8_LDA(At, 0, 0); PG8_STAGE(PG8_SA(1, 1), a1 + hstepA, voffA);
;             PG8_WAIT_V(8); PG8_WAIT_L(0); PG8_BAR; PG8_MMA(0, 0, At, B0); PG8_MMA(0, 1, At, B1); PG8_BAR; PG8_SCHED;
;     ...
; #pragma unroll
;         for (int a = 0; a < 2; ++a)
; #pragma unroll
;             for (int b = 0; b < 2; ++b)
; #pragma unroll
;                 for (int m = 0; m < 4; ++m)
; #pragma unroll
;                     for (int n = 0; n < 2; ++n) acc[a][b][m][n] = (f32x4){0.f, 0.f, 0.f, 0.f};
;         cur = nxt; cA = nA; cB = nB; ++ui;
.LBB0_807:
	v_readlane_b32 s28, v245, 30
	v_readlane_b32 s29, v245, 31
	s_add_u32 s28, s28, s11
	s_addc_u32 s29, s29, 0
	s_and_b64 s[30:31], s[42:43], exec
	v_readlane_b32 s30, v246, 43
	s_cselect_b32 s21, s29, s35
	s_cselect_b32 s25, s28, s34
	s_add_u32 s30, s30, s12
	v_readlane_b32 s31, v246, 44
	s_addc_u32 s31, s31, 0
	s_and_b64 s[38:39], s[42:43], exec
	s_cselect_b32 s33, s31, s37
	s_cselect_b32 s38, s30, s36
	s_add_u32 s34, s34, 0x20080
	s_addc_u32 s35, s35, 0
	s_add_u32 s39, s36, 0x100
	v_mov_b32_e32 v0, 0
	s_addc_u32 s46, s37, 0
	s_mov_b32 s47, -2
	v_mov_b32_e32 v1, v0
	v_mov_b32_e32 v2, v0
	v_mov_b32_e32 v3, v0
	v_mov_b32_e32 v4, v0
	v_mov_b32_e32 v5, v0
	v_mov_b32_e32 v6, v0
	v_mov_b32_e32 v7, v0
	v_mov_b32_e32 v8, v0
	v_mov_b32_e32 v9, v0
	v_mov_b32_e32 v10, v0
	v_mov_b32_e32 v11, v0
	v_mov_b32_e32 v12, v0
	v_mov_b32_e32 v13, v0
	v_mov_b32_e32 v14, v0
	v_mov_b32_e32 v15, v0
	v_mov_b32_e32 v16, v0
	v_mov_b32_e32 v17, v0
	v_mov_b32_e32 v18, v0
	v_mov_b32_e32 v19, v0
	v_mov_b32_e32 v20, v0
	v_mov_b32_e32 v21, v0
	v_mov_b32_e32 v22, v0
	v_mov_b32_e32 v23, v0
	v_mov_b32_e32 v24, v0
	v_mov_b32_e32 v25, v0
	v_mov_b32_e32 v26, v0
	v_mov_b32_e32 v27, v0
	v_mov_b32_e32 v28, v0
	v_mov_b32_e32 v29, v0
	v_mov_b32_e32 v30, v0
	v_mov_b32_e32 v31, v0
	v_mov_b32_e32 v32, v0
	v_mov_b32_e32 v33, v0
	v_mov_b32_e32 v34, v0
	v_mov_b32_e32 v35, v0
	v_mov_b32_e32 v36, v0
	v_mov_b32_e32 v37, v0
	v_mov_b32_e32 v38, v0
	v_mov_b32_e32 v39, v0
	v_mov_b32_e32 v40, v0
	v_mov_b32_e32 v41, v0
	v_mov_b32_e32 v42, v0
	v_mov_b32_e32 v43, v0
	v_mov_b32_e32 v44, v0
	v_mov_b32_e32 v45, v0
	v_mov_b32_e32 v46, v0
	v_mov_b32_e32 v47, v0
	v_mov_b32_e32 v48, v0
	v_mov_b32_e32 v49, v0
	v_mov_b32_e32 v50, v0
	v_mov_b32_e32 v51, v0
	v_mov_b32_e32 v52, v0
	v_mov_b32_e32 v53, v0
	v_mov_b32_e32 v54, v0
	v_mov_b32_e32 v55, v0
	v_mov_b32_e32 v56, v0
	v_mov_b32_e32 v57, v0
	v_mov_b32_e32 v58, v0
	v_mov_b32_e32 v59, v0
	v_mov_b32_e32 v60, v0
	v_mov_b32_e32 v61, v0
	v_mov_b32_e32 v62, v0
	v_mov_b32_e32 v63, v0
	v_mov_b32_e32 v64, v0
	v_mov_b32_e32 v65, v0
	v_mov_b32_e32 v66, v0
	v_mov_b32_e32 v67, v0
	v_mov_b32_e32 v68, v0
	v_mov_b32_e32 v69, v0
	v_mov_b32_e32 v70, v0
	v_mov_b32_e32 v71, v0
	v_mov_b32_e32 v72, v0
	v_mov_b32_e32 v73, v0
	v_mov_b32_e32 v74, v0
	v_mov_b32_e32 v75, v0
	v_mov_b32_e32 v76, v0
	v_mov_b32_e32 v77, v0
	v_mov_b32_e32 v78, v0
	v_mov_b32_e32 v79, v0
	v_mov_b32_e32 v80, v0
	v_mov_b32_e32 v81, v0
	v_mov_b32_e32 v82, v0
	v_mov_b32_e32 v83, v0
	v_mov_b32_e32 v84, v0
	v_mov_b32_e32 v85, v0
	v_mov_b32_e32 v86, v0
	v_mov_b32_e32 v87, v0
	v_mov_b32_e32 v88, v0
	v_mov_b32_e32 v89, v0
	v_mov_b32_e32 v90, v0
	v_mov_b32_e32 v91, v0
	v_mov_b32_e32 v92, v0
	v_mov_b32_e32 v93, v0
	v_mov_b32_e32 v94, v0
	v_mov_b32_e32 v95, v0
	v_mov_b32_e32 v96, v0
	v_mov_b32_e32 v97, v0
	v_mov_b32_e32 v98, v0
	v_mov_b32_e32 v99, v0
	v_mov_b32_e32 v100, v0
	v_mov_b32_e32 v101, v0
	v_mov_b32_e32 v102, v0
	v_mov_b32_e32 v103, v0
	v_mov_b32_e32 v104, v0
	v_mov_b32_e32 v105, v0
	v_mov_b32_e32 v106, v0
	v_mov_b32_e32 v107, v0
	v_mov_b32_e32 v108, v0
	v_mov_b32_e32 v109, v0
	v_mov_b32_e32 v110, v0
	v_mov_b32_e32 v111, v0
	v_mov_b32_e32 v112, v0
	v_mov_b32_e32 v113, v0
	v_mov_b32_e32 v114, v0
	v_mov_b32_e32 v115, v0
	v_mov_b32_e32 v116, v0
	v_mov_b32_e32 v117, v0
	v_mov_b32_e32 v118, v0
	v_mov_b32_e32 v119, v0
	v_mov_b32_e32 v120, v0
	v_mov_b32_e32 v121, v0
	v_mov_b32_e32 v122, v0
	v_mov_b32_e32 v123, v0
	v_mov_b32_e32 v124, v0
	v_mov_b32_e32 v125, v0
	v_mov_b32_e32 v126, v0
	v_mov_b32_e32 v127, v0
.LBB0_808:
	s_add_u32 s36, s34, 0xfffe0080
	s_addc_u32 s37, s35, -1
	s_add_i32 s48, 0, 0x10000
	s_cmp_eq_u32 s47, 4
	s_cselect_b32 s45, s21, s37
	s_cselect_b32 s44, s25, s36
	v_add_u32_e32 v161, s48, v159
	s_cselect_b32 s37, s33, s46
	s_cselect_b32 s36, s38, s39
	s_add_i32 s50, 0, 0x14000
	ds_read_b128 v[138:141], v161
	ds_read_b128 v[162:165], v161 offset:1024
	ds_read_b128 v[166:169], v161 offset:2048
	ds_read_b128 v[170:173], v161 offset:3072
	v_add_u32_e32 v161, s50, v159
	ds_read_b128 v[174:177], v161
	ds_read_b128 v[178:181], v161 offset:1024
	ds_read_b128 v[192:195], v161 offset:2048
	ds_read_b128 v[196:199], v161 offset:3072
	v_lshl_add_u64 v[232:233], s[34:35], 0, v[134:135]
	s_add_i32 m0, s1, 0xc000
	ds_read_b128 v[200:203], v160
	ds_read_b128 v[204:207], v160 offset:1024
	ds_read_b128 v[208:211], v160 offset:2048
	ds_read_b128 v[212:215], v160 offset:3072
	ds_read_b128 v[216:219], v160 offset:4096
	ds_read_b128 v[220:223], v160 offset:5120
	ds_read_b128 v[224:227], v160 offset:6144
	ds_read_b128 v[228:231], v160 offset:7168
	global_load_lds_dwordx4 v[232:233], off
	v_lshl_add_u64 v[232:233], s[34:35], 0, v[136:137]
	s_add_i32 m0, s1, 0xe000
	s_nop 0
	global_load_lds_dwordx4 v[232:233], off
	s_waitcnt vmcnt(8)
	s_waitcnt lgkmcnt(0)
	s_barrier
; #define PG8_STAGE(bufoff, gbase, voff) do { _Pragma("unroll") for (int _i = 0; _i < 2; ++_i) \
;         __builtin_amdgcn_global_load_lds((const unsigned*)((const char*)(gbase) + (voff)[_i]), (LAS unsigned*)(lds + (bufoff) + ldsw + _i * 8192), 16, 0, 0); } while (0)
; #define PG8_LDA(dst, b, h) do { _Pragma("unroll") for (int m = 0; m < 4; ++m) _Pragma("unroll") for (int k = 0; k < 2; ++k) dst[m][k] = *(const LAS bf16x8*)(lds + PG8_SA(b, h) + aoff + m * 2048 + k * 1024); } while (0)
; #define PG8_LDB(dst, b, h) do { _Pragma("unroll") for (int n = 0; n < 2; ++n) _Pragma("unroll") for (int k = 0; k < 2; ++k) dst[n][k] = *(const LAS bf16x8*)(lds + PG8_SB(b, h) + boff + n * 2048 + k * 1024); } while (0)
; #define PG8_MMA(ai, bj, At, Bt) do { __builtin_amdgcn_s_setprio(1); _Pragma("unroll") for (int m = 0; m < 4; ++m) _Pragma("unroll") for (int n = 0; n < 2; ++n) _Pragma("unroll") for (int k = 0; k < 2; ++k) \
;         acc[ai][bj][m][n] = __builtin_amdgcn_mfma_f32_16x16x32_bf16(Bt[n][k], At[m][k], acc[ai][bj][m][n], 0, 0, 0); __builtin_amdgcn_s_setprio(0); } while (0)
; #define PG8_WAIT_V(n) asm volatile("s_waitcnt vmcnt(" #n ")" ::: "memory")
; #define PG8_WAIT_L(n) asm volatile("s_waitcnt lgkmcnt(" #n ")" ::: "memory")
; #define PG8_BAR __builtin_amdgcn_s_barrier()
; #define PG8_SCHED __builtin_amdgcn_sched_barrier(0)
; template <class Epi, class Map>
; __device__ __forceinline__ void gemm_phase(LAS unsigned char* lds, const Gemm g, const Sched<Map>& S, const Epi& E) {
;     ...
;             PG8_WAIT_V(8); PG8_WAIT_L(0); PG8_BAR; PG8_MMA(0, 0, At, B0); PG8_MMA(0, 1, At, B1); PG8_BAR; PG8_SCHED;
;             PG8_LDA(At, 0, 1); PG8_STAGE(PG8_SB(0, 0), b2, voffB); PG8_STAGE(PG8_SB(0, 1), b2 + hstepB, voffB); PG8_STAGE(PG8_SA(0, 0), a2, voffA);
;             PG8_WAIT_V(8); PG8_WAIT_L(0); PG8_BAR; PG8_MMA(1, 0, At, B0); PG8_MMA(1, 1, At, B1); PG8_BAR; PG8_SCHED;
;             PG8_LDB(B0, 1, 0); PG8_LDB(B1, 1, 1); PG8_SCHED; PG8_LDA(At, 1, 0); PG8_STAGE(PG8_SA(0, 1), a2 + hstepA, voffA);
	s_waitcnt lgkmcnt(0)
	v_mfma_f32_16x16x32_bf16 v[124:127], v[138:141], v[200:203], v[124:127]
	v_mfma_f32_16x16x32_bf16 v[120:123], v[166:169], v[200:203], v[120:123]
	v_mfma_f32_16x16x32_bf16 v[116:119], v[138:141], v[208:211], v[116:119]
	v_mfma_f32_16x16x32_bf16 v[112:115], v[166:169], v[208:211], v[112:115]
	v_mfma_f32_16x16x32_bf16 v[108:111], v[138:141], v[216:219], v[108:111]
	v_mfma_f32_16x16x32_bf16 v[104:107], v[166:169], v[216:219], v[104:107]
	v_mfma_f32_16x16x32_bf16 v[100:103], v[138:141], v[224:227], v[100:103]
	v_mfma_f32_16x16x32_bf16 v[96:99], v[166:169], v[224:227], v[96:99]
	v_mfma_f32_16x16x32_bf16 v[124:127], v[162:165], v[204:207], v[124:127]
	v_mfma_f32_16x16x32_bf16 v[120:123], v[170:173], v[204:207], v[120:123]
	v_mfma_f32_16x16x32_bf16 v[116:119], v[162:165], v[212:215], v[116:119]
	v_mfma_f32_16x16x32_bf16 v[112:115], v[170:173], v[212:215], v[112:115]
	v_mfma_f32_16x16x32_bf16 v[108:111], v[162:165], v[220:223], v[108:111]
	v_mfma_f32_16x16x32_bf16 v[104:107], v[170:173], v[220:223], v[104:107]
	v_mfma_f32_16x16x32_bf16 v[100:103], v[162:165], v[228:231], v[100:103]
	v_mfma_f32_16x16x32_bf16 v[96:99], v[170:173], v[228:231], v[96:99]
	v_mfma_f32_16x16x32_bf16 v[92:95], v[174:177], v[200:203], v[92:95]
	v_mfma_f32_16x16x32_bf16 v[88:91], v[192:195], v[200:203], v[88:91]
	v_mfma_f32_16x16x32_bf16 v[84:87], v[174:177], v[208:211], v[84:87]
	v_mfma_f32_16x16x32_bf16 v[80:83], v[192:195], v[208:211], v[80:83]
	v_mfma_f32_16x16x32_bf16 v[76:79], v[174:177], v[216:219], v[76:79]
	v_mfma_f32_16x16x32_bf16 v[72:75], v[192:195], v[216:219], v[72:75]
	v_mfma_f32_16x16x32_bf16 v[68:71], v[174:177], v[224:227], v[68:71]
	v_mfma_f32_16x16x32_bf16 v[64:67], v[192:195], v[224:227], v[64:67]
	v_mfma_f32_16x16x32_bf16 v[92:95], v[178:181], v[204:207], v[92:95]
	v_mfma_f32_16x16x32_bf16 v[88:91], v[196:199], v[204:207], v[88:91]
	v_mfma_f32_16x16x32_bf16 v[84:87], v[178:181], v[212:215], v[84:87]
	v_mfma_f32_16x16x32_bf16 v[80:83], v[196:199], v[212:215], v[80:83]
	v_mfma_f32_16x16x32_bf16 v[76:79], v[178:181], v[220:223], v[76:79]
	v_mfma_f32_16x16x32_bf16 v[72:75], v[196:199], v[220:223], v[72:75]
	v_mfma_f32_16x16x32_bf16 v[68:71], v[178:181], v[228:231], v[68:71]
	v_mfma_f32_16x16x32_bf16 v[64:67], v[196:199], v[228:231], v[64:67]
	s_barrier
	s_add_i32 s48, s48, s0
	v_lshl_add_u64 v[232:233], s[36:37], 0, v[144:145]
	s_mov_b32 m0, s48
	ds_read_b128 v[200:203], v160 offset:16384
	ds_read_b128 v[204:207], v160 offset:17408
	ds_read_b128 v[208:211], v160 offset:18432
	ds_read_b128 v[212:215], v160 offset:19456
	ds_read_b128 v[216:219], v160 offset:20480
	ds_read_b128 v[220:223], v160 offset:21504
	ds_read_b128 v[224:227], v160 offset:22528
	ds_read_b128 v[228:231], v160 offset:23552
	global_load_lds_dwordx4 v[232:233], off
	s_add_i32 m0, s48, 0x2000
	s_add_u32 s48, s36, 0x20000
	v_lshl_add_u64 v[234:235], s[36:37], 0, v[128:129]
	s_addc_u32 s49, s37, 0
	s_add_i32 s50, s50, s0
	global_load_lds_dwordx4 v[234:235], off
	v_lshl_add_u64 v[236:237], s[48:49], 0, v[144:145]
	s_mov_b32 m0, s50
	v_lshl_add_u64 v[238:239], s[44:45], 0, v[130:131]
	global_load_lds_dwordx4 v[236:237], off
	v_lshl_add_u64 v[236:237], s[48:49], 0, v[128:129]
	s_add_i32 m0, s50, 0x2000
	s_nop 0
	global_load_lds_dwordx4 v[236:237], off
	v_lshl_add_u64 v[236:237], s[44:45], 0, v[132:133]
	s_mov_b32 m0, s1
	s_nop 0
	global_load_lds_dwordx4 v[236:237], off
	s_mov_b32 m0, s2
	s_nop 0
	global_load_lds_dwordx4 v[238:239], off
	s_waitcnt vmcnt(8)
	s_waitcnt lgkmcnt(0)
	s_barrier
	s_waitcnt lgkmcnt(0)
	v_mfma_f32_16x16x32_bf16 v[60:63], v[138:141], v[200:203], v[60:63]
	v_mfma_f32_16x16x32_bf16 v[56:59], v[166:169], v[200:203], v[56:59]
	v_mfma_f32_16x16x32_bf16 v[52:55], v[138:141], v[208:211], v[52:55]
	v_mfma_f32_16x16x32_bf16 v[48:51], v[166:169], v[208:211], v[48:51]
	v_mfma_f32_16x16x32_bf16 v[44:47], v[138:141], v[216:219], v[44:47]
	v_mfma_f32_16x16x32_bf16 v[40:43], v[166:169], v[216:219], v[40:43]
	v_mfma_f32_16x16x32_bf16 v[36:39], v[138:141], v[224:227], v[36:39]
	v_mfma_f32_16x16x32_bf16 v[32:35], v[166:169], v[224:227], v[32:35]
	v_mfma_f32_16x16x32_bf16 v[60:63], v[162:165], v[204:207], v[60:63]
	v_mfma_f32_16x16x32_bf16 v[56:59], v[170:173], v[204:207], v[56:59]
	v_mfma_f32_16x16x32_bf16 v[52:55], v[162:165], v[212:215], v[52:55]
	v_mfma_f32_16x16x32_bf16 v[48:51], v[170:173], v[212:215], v[48:51]
	v_mfma_f32_16x16x32_bf16 v[44:47], v[162:165], v[220:223], v[44:47]
	v_mfma_f32_16x16x32_bf16 v[40:43], v[170:173], v[220:223], v[40:43]
	v_mfma_f32_16x16x32_bf16 v[36:39], v[162:165], v[228:231], v[36:39]
	v_mfma_f32_16x16x32_bf16 v[32:35], v[170:173], v[228:231], v[32:35]
	v_mfma_f32_16x16x32_bf16 v[28:31], v[174:177], v[200:203], v[28:31]
	v_mfma_f32_16x16x32_bf16 v[24:27], v[192:195], v[200:203], v[24:27]
	v_mfma_f32_16x16x32_bf16 v[20:23], v[174:177], v[208:211], v[20:23]
	v_mfma_f32_16x16x32_bf16 v[16:19], v[192:195], v[208:211], v[16:19]
	v_mfma_f32_16x16x32_bf16 v[12:15], v[174:177], v[216:219], v[12:15]
	v_mfma_f32_16x16x32_bf16 v[8:11], v[192:195], v[216:219], v[8:11]
	v_mfma_f32_16x16x32_bf16 v[4:7], v[174:177], v[224:227], v[4:7]
	v_mfma_f32_16x16x32_bf16 v[0:3], v[192:195], v[224:227], v[0:3]
	v_mfma_f32_16x16x32_bf16 v[28:31], v[178:181], v[204:207], v[28:31]
	v_mfma_f32_16x16x32_bf16 v[24:27], v[196:199], v[204:207], v[24:27]
	v_mfma_f32_16x16x32_bf16 v[20:23], v[178:181], v[212:215], v[20:23]
	v_mfma_f32_16x16x32_bf16 v[16:19], v[196:199], v[212:215], v[16:19]
	v_mfma_f32_16x16x32_bf16 v[12:15], v[178:181], v[220:223], v[12:15]
	v_mfma_f32_16x16x32_bf16 v[8:11], v[196:199], v[220:223], v[8:11]
	v_mfma_f32_16x16x32_bf16 v[4:7], v[178:181], v[228:231], v[4:7]
	v_mfma_f32_16x16x32_bf16 v[0:3], v[196:199], v[228:231], v[0:3]
	s_barrier
; #define PG8_STAGE(bufoff, gbase, voff) do { _Pragma("unroll") for (int _i = 0; _i < 2; ++_i) \
;         __builtin_amdgcn_global_load_lds((const unsigned*)((const char*)(gbase) + (voff)[_i]), (LAS unsigned*)(lds + (bufoff) + ldsw + _i * 8192), 16, 0, 0); } while (0)
; #define PG8_LDA(dst, b, h) do { _Pragma("unroll") for (int m = 0; m < 4; ++m) _Pragma("unroll") for (int k = 0; k < 2; ++k) dst[m][k] = *(const LAS bf16x8*)(lds + PG8_SA(b, h) + aoff + m * 2048 + k * 1024); } while (0)
; #define PG8_LDB(dst, b, h) do { _Pragma("unroll") for (int n = 0; n < 2; ++n) _Pragma("unroll") for (int k = 0; k < 2; ++k) dst[n][k] = *(const LAS bf16x8*)(lds + PG8_SB(b, h) + boff + n * 2048 + k * 1024); } while (0)
; #define PG8_MMA(ai, bj, At, Bt) do { __builtin_amdgcn_s_setprio(1); _Pragma("unroll") for (int m = 0; m < 4; ++m) _Pragma("unroll") for (int n = 0; n < 2; ++n) _Pragma("unroll") for (int k = 0; k < 2; ++k) \
;         acc[ai][bj][m][n] = __builtin_amdgcn_mfma_f32_16x16x32_bf16(Bt[n][k], At[m][k], acc[ai][bj][m][n], 0, 0, 0); __builtin_amdgcn_s_setprio(0); } while (0)
; #define PG8_WAIT_V(n) asm volatile("s_waitcnt vmcnt(" #n ")" ::: "memory")
; #define PG8_WAIT_L(n) asm volatile("s_waitcnt lgkmcnt(" #n ")" ::: "memory")
; #define PG8_BAR __builtin_amdgcn_s_barrier()
; #define PG8_SCHED __builtin_amdgcn_sched_barrier(0)
; template <class Epi, class Map>
; __device__ __forceinline__ void gemm_phase(LAS unsigned char* lds, const Gemm g, const Sched<Map>& S, const Epi& E) {
;     ...
;             PG8_LDB(B0, 1, 0); PG8_LDB(B1, 1, 1); PG8_SCHED; PG8_LDA(At, 1, 0); PG8_STAGE(PG8_SA(0, 1), a2 + hstepA, voffA);
;             PG8_WAIT_V(8); PG8_WAIT_L(0); PG8_BAR; PG8_MMA(0, 0, At, B0); PG8_MMA(0, 1, At, B1); PG8_BAR; PG8_SCHED;
;             PG8_LDA(At, 1, 1); PG8_STAGE(PG8_SB(1, 0), b3, voffB); PG8_STAGE(PG8_SB(1, 1), b3 + hstepB, voffB); PG8_STAGE(PG8_SA(1, 0), a3, voffA);
	s_add_i32 s48, 0, 0x18000
	v_add_u32_e32 v161, s48, v159
	s_add_i32 s49, 0, 0x1c000
	ds_read_b128 v[138:141], v161
	ds_read_b128 v[162:165], v161 offset:1024
	ds_read_b128 v[166:169], v161 offset:2048
	ds_read_b128 v[170:173], v161 offset:3072
	v_add_u32_e32 v161, s49, v159
	ds_read_b128 v[174:177], v161
	ds_read_b128 v[178:181], v161 offset:1024
	ds_read_b128 v[192:195], v161 offset:2048
	ds_read_b128 v[196:199], v161 offset:3072
	s_add_u32 s44, s44, 0x20000
	s_addc_u32 s45, s45, 0
	s_mov_b32 m0, s3
	v_lshl_add_u64 v[240:241], s[44:45], 0, v[132:133]
	ds_read_b128 v[200:203], v160 offset:32768
	ds_read_b128 v[204:207], v160 offset:33792
	ds_read_b128 v[208:211], v160 offset:34816
	ds_read_b128 v[212:215], v160 offset:35840
	ds_read_b128 v[216:219], v160 offset:36864
	ds_read_b128 v[220:223], v160 offset:37888
	ds_read_b128 v[224:227], v160 offset:38912
	ds_read_b128 v[228:231], v160 offset:39936
	global_load_lds_dwordx4 v[240:241], off
	v_lshl_add_u64 v[240:241], s[44:45], 0, v[130:131]
	s_mov_b32 m0, s4
	s_nop 0
	global_load_lds_dwordx4 v[240:241], off
	s_waitcnt vmcnt(8)
	s_waitcnt lgkmcnt(0)
	s_barrier
	s_waitcnt lgkmcnt(0)
	v_mfma_f32_16x16x32_bf16 v[124:127], v[138:141], v[200:203], v[124:127]
	v_mfma_f32_16x16x32_bf16 v[120:123], v[166:169], v[200:203], v[120:123]
	v_mfma_f32_16x16x32_bf16 v[116:119], v[138:141], v[208:211], v[116:119]
	v_mfma_f32_16x16x32_bf16 v[112:115], v[166:169], v[208:211], v[112:115]
	v_mfma_f32_16x16x32_bf16 v[108:111], v[138:141], v[216:219], v[108:111]
	v_mfma_f32_16x16x32_bf16 v[104:107], v[166:169], v[216:219], v[104:107]
	v_mfma_f32_16x16x32_bf16 v[100:103], v[138:141], v[224:227], v[100:103]
	v_mfma_f32_16x16x32_bf16 v[96:99], v[166:169], v[224:227], v[96:99]
	v_mfma_f32_16x16x32_bf16 v[124:127], v[162:165], v[204:207], v[124:127]
	v_mfma_f32_16x16x32_bf16 v[120:123], v[170:173], v[204:207], v[120:123]
	v_mfma_f32_16x16x32_bf16 v[116:119], v[162:165], v[212:215], v[116:119]
	v_mfma_f32_16x16x32_bf16 v[112:115], v[170:173], v[212:215], v[112:115]
	v_mfma_f32_16x16x32_bf16 v[108:111], v[162:165], v[220:223], v[108:111]
	v_mfma_f32_16x16x32_bf16 v[104:107], v[170:173], v[220:223], v[104:107]
	v_mfma_f32_16x16x32_bf16 v[100:103], v[162:165], v[228:231], v[100:103]
	v_mfma_f32_16x16x32_bf16 v[96:99], v[170:173], v[228:231], v[96:99]
	v_mfma_f32_16x16x32_bf16 v[92:95], v[174:177], v[200:203], v[92:95]
	v_mfma_f32_16x16x32_bf16 v[88:91], v[192:195], v[200:203], v[88:91]
	v_mfma_f32_16x16x32_bf16 v[84:87], v[174:177], v[208:211], v[84:87]
	v_mfma_f32_16x16x32_bf16 v[80:83], v[192:195], v[208:211], v[80:83]
	v_mfma_f32_16x16x32_bf16 v[76:79], v[174:177], v[216:219], v[76:79]
	v_mfma_f32_16x16x32_bf16 v[72:75], v[192:195], v[216:219], v[72:75]
	v_mfma_f32_16x16x32_bf16 v[68:71], v[174:177], v[224:227], v[68:71]
	v_mfma_f32_16x16x32_bf16 v[64:67], v[192:195], v[224:227], v[64:67]
	v_mfma_f32_16x16x32_bf16 v[92:95], v[178:181], v[204:207], v[92:95]
	v_mfma_f32_16x16x32_bf16 v[88:91], v[196:199], v[204:207], v[88:91]
	v_mfma_f32_16x16x32_bf16 v[84:87], v[178:181], v[212:215], v[84:87]
	v_mfma_f32_16x16x32_bf16 v[80:83], v[196:199], v[212:215], v[80:83]
	v_mfma_f32_16x16x32_bf16 v[76:79], v[178:181], v[220:223], v[76:79]
	v_mfma_f32_16x16x32_bf16 v[72:75], v[196:199], v[220:223], v[72:75]
	v_mfma_f32_16x16x32_bf16 v[68:71], v[178:181], v[228:231], v[68:71]
	v_mfma_f32_16x16x32_bf16 v[64:67], v[196:199], v[228:231], v[64:67]
	s_barrier
	s_add_i32 s44, s48, s0
	v_lshl_add_u64 v[232:233], v[232:233], 0, s[82:83]
	s_mov_b32 m0, s44
	ds_read_b128 v[200:203], v160 offset:49152
	ds_read_b128 v[204:207], v160 offset:50176
	ds_read_b128 v[208:211], v160 offset:51200
	ds_read_b128 v[212:215], v160 offset:52224
	ds_read_b128 v[216:219], v160 offset:53248
	ds_read_b128 v[220:223], v160 offset:54272
	ds_read_b128 v[224:227], v160 offset:55296
	ds_read_b128 v[228:231], v160 offset:56320
	global_load_lds_dwordx4 v[232:233], off
	s_add_i32 m0, s44, 0x2000
	s_add_u32 s36, s36, 0x20080
	v_lshl_add_u64 v[232:233], v[234:235], 0, s[82:83]
	s_addc_u32 s37, s37, 0
	s_add_i32 s44, s49, s0
	global_load_lds_dwordx4 v[232:233], off
	v_lshl_add_u64 v[232:233], s[36:37], 0, v[144:145]
	s_mov_b32 m0, s44
	s_nop 0
	global_load_lds_dwordx4 v[232:233], off
	v_lshl_add_u64 v[232:233], s[36:37], 0, v[128:129]
	s_add_i32 m0, s44, 0x2000
	s_nop 0
	global_load_lds_dwordx4 v[232:233], off
	v_lshl_add_u64 v[232:233], v[236:237], 0, s[82:83]
	s_mov_b32 m0, s6
	s_nop 0
	global_load_lds_dwordx4 v[232:233], off
	v_lshl_add_u64 v[232:233], v[238:239], 0, s[82:83]
	s_mov_b32 m0, s7
	s_nop 0
	global_load_lds_dwordx4 v[232:233], off
	s_waitcnt vmcnt(8)
	s_waitcnt lgkmcnt(0)
	s_barrier
; __device__ __forceinline__ unsigned cvt_pk_bf16(float lo, float hi) { unsigned r; asm volatile("v_cvt_pk_bf16_f32 %0, %1, %2" : "=v"(r) : "v"(lo), "v"(hi)); return r; }
; #define PG8_MMA(ai, bj, At, Bt) do { __builtin_amdgcn_s_setprio(1); _Pragma("unroll") for (int m = 0; m < 4; ++m) _Pragma("unroll") for (int n = 0; n < 2; ++n) _Pragma("unroll") for (int k = 0; k < 2; ++k) \
;         acc[ai][bj][m][n] = __builtin_amdgcn_mfma_f32_16x16x32_bf16(Bt[n][k], At[m][k], acc[ai][bj][m][n], 0, 0, 0); __builtin_amdgcn_s_setprio(0); } while (0)
; #define PG8_WAIT_V(n) asm volatile("s_waitcnt vmcnt(" #n ")" ::: "memory")
; #define PG8_WAIT_L(n) asm volatile("s_waitcnt lgkmcnt(" #n ")" ::: "memory")
; #define PG8_BAR __builtin_amdgcn_s_barrier()
; #define PG8_SCHED __builtin_amdgcn_sched_barrier(0)
; template <class Epi, class Map>
; __device__ __forceinline__ void gemm_phase(LAS unsigned char* lds, const Gemm g, const Sched<Map>& S, const Epi& E) {
;     ...
;             PG8_WAIT_V(8); PG8_WAIT_L(0); PG8_BAR; PG8_MMA(1, 0, At, B0); PG8_MMA(1, 1, At, B1); PG8_BAR; PG8_SCHED;
;         }
;         if (wr == 0) PG8_BAR;
;     __device__ __forceinline__ void operator()(const Acc& acc, const Unit& u, int wr, int wc, int fr, int fq) const {
;     ...
;         const int h = u.pm >> 6, nchunk = u.pm & 63, et = u.pn;
; #pragma unroll
;         for (int ai = 0; ai < 2; ++ai) {
;             float S1[4], S2[4];
; #pragma unroll
;             for (int m = 0; m < 4; ++m) {
;                 const int row_in = ai * HALF + wr * 64 + m * 16 + fr;
;                 float s1 = 0.f, s2 = 0.f;
; #pragma unroll
;                 for (int bj = 0; bj < 2; ++bj) {
;                     const f32x4 v0 = acc[ai][bj][m][0], v1 = acc[ai][bj][m][1];
; #pragma unroll
;                     for (int j = 0; j < 4; ++j) { s1 += v0[j] + v1[j]; s2 += v0[j] * v0[j] + v1[j] * v1[j]; }
;                     u32x4 w; w.x = cvt_pk_bf16(v0[0], v0[1]); w.y = cvt_pk_bf16(v0[2], v0[3]); w.z = cvt_pk_bf16(v1[0], v1[1]); w.w = cvt_pk_bf16(v1[2], v1[3]);
;                     *(u32x4*)(O + u.coff + (size_t)row_in * RV + bj * HALF + wc * 32 + 8 * fq) = w;
;                 }
;                 s1 += __shfl_xor(s1, 16); s1 += __shfl_xor(s1, 32); s2 += __shfl_xor(s2, 16); s2 += __shfl_xor(s2, 32);
;                 S1[m] = s1; S2[m] = s2;
	s_waitcnt lgkmcnt(0)
	v_mfma_f32_16x16x32_bf16 v[60:63], v[138:141], v[200:203], v[60:63]
	v_mfma_f32_16x16x32_bf16 v[56:59], v[166:169], v[200:203], v[56:59]
	v_mfma_f32_16x16x32_bf16 v[52:55], v[138:141], v[208:211], v[52:55]
	v_mfma_f32_16x16x32_bf16 v[48:51], v[166:169], v[208:211], v[48:51]
	v_mfma_f32_16x16x32_bf16 v[44:47], v[138:141], v[216:219], v[44:47]
	v_mfma_f32_16x16x32_bf16 v[40:43], v[166:169], v[216:219], v[40:43]
	v_mfma_f32_16x16x32_bf16 v[36:39], v[138:141], v[224:227], v[36:39]
	v_mfma_f32_16x16x32_bf16 v[32:35], v[166:169], v[224:227], v[32:35]
	v_mfma_f32_16x16x32_bf16 v[60:63], v[162:165], v[204:207], v[60:63]
	v_mfma_f32_16x16x32_bf16 v[56:59], v[170:173], v[204:207], v[56:59]
	v_mfma_f32_16x16x32_bf16 v[52:55], v[162:165], v[212:215], v[52:55]
	v_mfma_f32_16x16x32_bf16 v[48:51], v[170:173], v[212:215], v[48:51]
	v_mfma_f32_16x16x32_bf16 v[44:47], v[162:165], v[220:223], v[44:47]
	v_mfma_f32_16x16x32_bf16 v[40:43], v[170:173], v[220:223], v[40:43]
	v_mfma_f32_16x16x32_bf16 v[36:39], v[162:165], v[228:231], v[36:39]
	v_mfma_f32_16x16x32_bf16 v[32:35], v[170:173], v[228:231], v[32:35]
	v_mfma_f32_16x16x32_bf16 v[28:31], v[174:177], v[200:203], v[28:31]
	v_mfma_f32_16x16x32_bf16 v[24:27], v[192:195], v[200:203], v[24:27]
	v_mfma_f32_16x16x32_bf16 v[20:23], v[174:177], v[208:211], v[20:23]
	v_mfma_f32_16x16x32_bf16 v[16:19], v[192:195], v[208:211], v[16:19]
	v_mfma_f32_16x16x32_bf16 v[12:15], v[174:177], v[216:219], v[12:15]
	v_mfma_f32_16x16x32_bf16 v[8:11], v[192:195], v[216:219], v[8:11]
	v_mfma_f32_16x16x32_bf16 v[4:7], v[174:177], v[224:227], v[4:7]
	v_mfma_f32_16x16x32_bf16 v[0:3], v[192:195], v[224:227], v[0:3]
	v_mfma_f32_16x16x32_bf16 v[28:31], v[178:181], v[204:207], v[28:31]
	v_mfma_f32_16x16x32_bf16 v[24:27], v[196:199], v[204:207], v[24:27]
	v_mfma_f32_16x16x32_bf16 v[20:23], v[178:181], v[212:215], v[20:23]
	v_mfma_f32_16x16x32_bf16 v[16:19], v[196:199], v[212:215], v[16:19]
	v_mfma_f32_16x16x32_bf16 v[12:15], v[178:181], v[220:223], v[12:15]
	v_mfma_f32_16x16x32_bf16 v[8:11], v[196:199], v[220:223], v[8:11]
	v_mfma_f32_16x16x32_bf16 v[4:7], v[178:181], v[228:231], v[4:7]
	v_mfma_f32_16x16x32_bf16 v[0:3], v[196:199], v[228:231], v[0:3]
	s_barrier
	s_add_i32 s47, s47, 2
	s_add_u32 s34, s34, 0x100
	s_addc_u32 s35, s35, 0
	s_add_u32 s39, s39, 0x100
	s_addc_u32 s46, s46, 0
	s_cmp_gt_u32 s47, 5
	s_cbranch_scc0 .LBB0_808
	s_and_b64 vcc, exec, s[18:19]
	s_cbranch_vccz .LBB0_811
.LBB0_811:
	v_mov_b32_e32 v138, v143
	v_mov_b32_e32 v139, v142
	s_ashr_i32 s34, s15, 6
	s_lshl_b32 s15, s15, 8
	v_add_u32_e32 v140, s5, v139
	v_lshlrev_b32_e32 v162, 3, v138
	v_cmp_eq_u32_e32 vcc, 0, v138
	v_cmp_eq_u32_e64 s[44:45], 1, v138
	v_cmp_eq_u32_e64 s[46:47], 2, v138
	v_lshlrev_b32_e32 v138, 4, v138
	s_and_b32 s15, s15, 0x3f00
	s_ashr_i32 s35, s34, 31
	s_lshl_b32 s50, s14, 2
	v_add3_u32 v138, v138, s15, v140
	s_ashr_i32 s51, s50, 31
	s_lshl_b64 s[34:35], s[34:35], 6
	v_pk_add_f32 v[168:169], v[124:125], v[120:121]
	s_lshl_b64 s[14:15], s[60:61], 1
	v_readlane_b32 s36, v246, 17
	v_ashrrev_i32_e32 v141, 31, v140
	v_add_f32_e32 v139, 0, v168
	v_readlane_b32 s37, v246, 18
	s_add_u32 s36, s36, s14
	v_lshlrev_b64 v[164:165], 13, v[140:141]
	v_add_f32_e32 v139, v169, v139
	v_pk_mul_f32 v[168:169], v[122:123], v[122:123]
	v_pk_mul_f32 v[170:171], v[120:121], v[120:121]
	s_addc_u32 s37, s37, s15
	v_ashrrev_i32_e32 v163, 31, v162
	v_pk_add_f32 v[166:167], v[126:127], v[122:123]
	v_pk_fma_f32 v[168:169], v[126:127], v[126:127], v[168:169]
	v_pk_fma_f32 v[170:171], v[124:125], v[124:125], v[170:171]
	v_cvt_pk_bf16_f32 v124, v124, v125
	v_cvt_pk_bf16_f32 v125, v126, v127
	v_cvt_pk_bf16_f32 v126, v120, v121
	v_lshl_add_u64 v[120:121], s[36:37], 0, v[164:165]
	s_mov_b32 s21, s61
	v_add_f32_e32 v139, v166, v139
	v_cvt_pk_bf16_f32 v127, v122, v123
	v_lshl_add_u64 v[122:123], v[120:121], 0, s[20:21]
	v_lshlrev_b64 v[120:121], 1, v[162:163]
	v_add_f32_e32 v139, v167, v139
	v_lshl_add_u64 v[166:167], v[122:123], 0, v[120:121]
	global_store_dwordx4 v[166:167], v[124:127], off
	v_pk_add_f32 v[122:123], v[92:93], v[88:89]
	v_cvt_pk_bf16_f32 v162, v92, v93
	v_cvt_pk_bf16_f32 v163, v94, v95
	v_cvt_pk_bf16_f32 v164, v88, v89
	v_cvt_pk_bf16_f32 v165, v90, v91
	s_nop 0
	v_pk_mul_f32 v[124:125], v[92:93], v[92:93]
	v_add_f32_e32 v122, v139, v122
	v_pk_fma_f32 v[124:125], v[88:89], v[88:89], v[124:125]
	v_and_b32_e32 v89, 64, v183
	v_xor_b32_e32 v88, 16, v183
	v_add_u32_e32 v89, 64, v89
	v_cmp_lt_i32_e64 s[48:49], v88, v89
	v_add_f32_e32 v122, v123, v122
	v_add_f32_e32 v123, v170, v171
	v_cndmask_b32_e64 v88, v183, v88, s[48:49]
	v_add_f32_e32 v123, v168, v123
	v_lshlrev_b32_e32 v93, 2, v88
	v_xor_b32_e32 v88, 32, v183
	v_add_f32_e32 v123, v169, v123
	v_cmp_lt_i32_e64 s[48:49], v88, v89
	v_add_f32_e32 v126, v123, v124
	v_pk_add_f32 v[124:125], v[124:125], v[126:127] op_sel_hi:[1,0]
	v_cndmask_b32_e64 v88, v183, v88, s[48:49]
	v_lshlrev_b32_e32 v92, 2, v88
	v_add_u32_e32 v88, 16, v140
	v_mov_b32_e32 v126, v94
	v_mov_b32_e32 v127, v90
	v_mul_f32_e32 v124, v94, v94
	global_store_dwordx4 v[166:167], v[162:165], off offset:256
	v_ashrrev_i32_e32 v89, 31, v88
	v_pk_fma_f32 v[126:127], v[126:127], v[126:127], v[124:125] op_sel_hi:[1,1,0]
	v_pk_add_f32 v[164:165], v[116:117], v[112:113]
	v_lshlrev_b64 v[88:89], 13, v[88:89]
	v_add_f32_e32 v124, 0, v164
	v_pk_add_f32 v[162:163], v[118:119], v[114:115]
	v_add_f32_e32 v124, v165, v124
	v_lshl_add_u64 v[88:89], s[36:37], 0, v[88:89]
	v_add_f32_e32 v124, v162, v124
	v_lshl_add_u64 v[88:89], v[88:89], 0, s[20:21]
	v_pk_mul_f32 v[166:167], v[112:113], v[112:113]
	v_add_f32_e32 v124, v163, v124
	v_lshl_add_u64 v[162:163], v[88:89], 0, v[120:121]
	v_pk_add_f32 v[88:89], v[84:85], v[80:81]
	v_pk_mul_f32 v[164:165], v[114:115], v[114:115]
	v_pk_fma_f32 v[166:167], v[116:117], v[116:117], v[166:167]
	v_add_f32_e32 v88, v124, v88
	v_pk_fma_f32 v[164:165], v[118:119], v[118:119], v[164:165]
	v_add_f32_e32 v88, v89, v88
	v_add_f32_e32 v89, v166, v167
	v_cvt_pk_bf16_f32 v116, v116, v117
	v_cvt_pk_bf16_f32 v117, v118, v119
	v_cvt_pk_bf16_f32 v118, v112, v113
	v_pk_mul_f32 v[112:113], v[84:85], v[84:85]
	v_add_f32_e32 v89, v164, v89
	v_pk_fma_f32 v[112:113], v[80:81], v[80:81], v[112:113]
	v_add_f32_e32 v89, v165, v89
	v_cvt_pk_bf16_f32 v119, v114, v115
	v_add_f32_e32 v114, v89, v112
	global_store_dwordx4 v[162:163], v[116:119], off
	v_mul_f32_e32 v89, v83, v83
	v_mul_f32_e32 v123, v91, v91
	v_pk_add_f32 v[116:117], v[112:113], v[114:115] op_sel_hi:[1,0]
	v_mov_b32_e32 v112, v86
	v_mov_b32_e32 v113, v82
	v_mul_f32_e32 v114, v86, v86
	v_pk_fma_f32 v[118:119], v[112:113], v[112:113], v[114:115] op_sel_hi:[1,1,0]
	v_cvt_pk_bf16_f32 v112, v84, v85
	v_cvt_pk_bf16_f32 v113, v86, v87
	v_cvt_pk_bf16_f32 v114, v80, v81
	v_cvt_pk_bf16_f32 v115, v82, v83
	global_store_dwordx4 v[162:163], v[112:115], off offset:256
	s_cmp_lg_u64 s[18:19], 0
	s_cbranch_scc0 .Llate_align_7
	s_barrier
; __device__ __forceinline__ unsigned cvt_pk_bf16(float lo, float hi) { unsigned r; asm volatile("v_cvt_pk_bf16_f32 %0, %1, %2" : "=v"(r) : "v"(lo), "v"(hi)); return r; }
;     __device__ __forceinline__ void operator()(const Acc& acc, const Unit& u, int wr, int wc, int fr, int fq) const {
;     ...
;             for (int m = 0; m < 4; ++m) {
;                 const int row_in = ai * HALF + wr * 64 + m * 16 + fr;
;                 float s1 = 0.f, s2 = 0.f;
; #pragma unroll
;                 for (int bj = 0; bj < 2; ++bj) {
;                     const f32x4 v0 = acc[ai][bj][m][0], v1 = acc[ai][bj][m][1];
; #pragma unroll
;                     for (int j = 0; j < 4; ++j) { s1 += v0[j] + v1[j]; s2 += v0[j] * v0[j] + v1[j] * v1[j]; }
;                     u32x4 w; w.x = cvt_pk_bf16(v0[0], v0[1]); w.y = cvt_pk_bf16(v0[2], v0[3]); w.z = cvt_pk_bf16(v1[0], v1[1]); w.w = cvt_pk_bf16(v1[2], v1[3]);
;                     *(u32x4*)(O + u.coff + (size_t)row_in * RV + bj * HALF + wc * 32 + 8 * fq) = w;
;                 }
;                 s1 += __shfl_xor(s1, 16); s1 += __shfl_xor(s1, 32); s2 += __shfl_xor(s2, 16); s2 += __shfl_xor(s2, 32);
;                 S1[m] = s1; S2[m] = s2;
;             }
;             const float t1 = fq == 0 ? S1[0] : fq == 1 ? S1[1] : fq == 2 ? S1[2] : S1[3], t2 = fq == 0 ? S2[0] : fq == 1 ? S2[1] : fq == 2 ? S2[2] : S2[3];
.Llate_align_7:
	v_pk_add_f32 v[84:85], v[110:111], v[106:107]
	v_add_u32_e32 v80, 32, v140
	v_pk_add_f32 v[112:113], v[108:109], v[104:105]
	v_pk_mul_f32 v[114:115], v[104:105], v[104:105]
	v_add_f32_e32 v112, 0, v112
	v_add_f32_e32 v116, v113, v112
	v_add_f32_e32 v84, v84, v116
	v_add_f32_e32 v116, v85, v84
	v_pk_add_f32 v[84:85], v[76:77], v[72:73]
	v_ashrrev_i32_e32 v81, 31, v80
	v_pk_mul_f32 v[112:113], v[106:107], v[106:107]
	v_pk_fma_f32 v[114:115], v[108:109], v[108:109], v[114:115]
	v_add_f32_e32 v84, v116, v84
	v_lshlrev_b64 v[80:81], 13, v[80:81]
	v_pk_fma_f32 v[112:113], v[110:111], v[110:111], v[112:113]
	v_add_f32_e32 v84, v85, v84
	v_add_f32_e32 v85, v114, v115
	v_cvt_pk_bf16_f32 v108, v108, v109
	v_cvt_pk_bf16_f32 v109, v110, v111
	v_cvt_pk_bf16_f32 v110, v104, v105
	v_lshl_add_u64 v[80:81], s[36:37], 0, v[80:81]
	v_pk_mul_f32 v[104:105], v[76:77], v[76:77]
	v_add_f32_e32 v85, v112, v85
	v_lshl_add_u64 v[80:81], v[80:81], 0, s[20:21]
	v_pk_fma_f32 v[104:105], v[72:73], v[72:73], v[104:105]
	v_add_f32_e32 v85, v113, v85
	v_cvt_pk_bf16_f32 v111, v106, v107
	v_lshl_add_u64 v[80:81], v[80:81], 0, v[120:121]
	v_add_f32_e32 v106, v85, v104
	global_store_dwordx4 v[80:81], v[108:111], off
	v_mov_b32_e32 v118, v87
	v_mov_b32_e32 v116, v83
	v_pk_add_f32 v[108:109], v[104:105], v[106:107] op_sel_hi:[1,0]
	v_mov_b32_e32 v104, v78
	v_mov_b32_e32 v105, v74
	v_mul_f32_e32 v106, v78, v78
	v_pk_fma_f32 v[110:111], v[104:105], v[104:105], v[106:107] op_sel_hi:[1,1,0]
	v_cvt_pk_bf16_f32 v104, v76, v77
	v_cvt_pk_bf16_f32 v105, v78, v79
	v_cvt_pk_bf16_f32 v106, v72, v73
	v_cvt_pk_bf16_f32 v107, v74, v75
	global_store_dwordx4 v[80:81], v[104:107], off offset:256
	v_pk_add_f32 v[80:81], v[100:101], v[96:97]
	v_pk_add_f32 v[76:77], v[102:103], v[98:99]
	v_add_f32_e32 v80, 0, v80
	v_add_f32_e32 v106, v81, v80
	v_add_f32_e32 v76, v76, v106
	v_pk_mul_f32 v[104:105], v[96:97], v[96:97]
	v_add_f32_e32 v106, v77, v76
	v_pk_add_f32 v[76:77], v[68:69], v[64:65]
	v_pk_mul_f32 v[80:81], v[98:99], v[98:99]
	v_pk_fma_f32 v[104:105], v[100:101], v[100:101], v[104:105]
	v_add_f32_e32 v76, v106, v76
	v_add_u32_e32 v72, 48, v140
	v_pk_fma_f32 v[80:81], v[102:103], v[102:103], v[80:81]
	v_add_f32_e32 v76, v77, v76
	v_add_f32_e32 v77, v104, v105
	v_ashrrev_i32_e32 v73, 31, v72
	v_cvt_pk_bf16_f32 v100, v100, v101
	v_cvt_pk_bf16_f32 v101, v102, v103
	v_cvt_pk_bf16_f32 v102, v96, v97
	v_pk_mul_f32 v[96:97], v[68:69], v[68:69]
	v_add_f32_e32 v77, v80, v77
	v_lshlrev_b64 v[72:73], 13, v[72:73]
	v_pk_fma_f32 v[96:97], v[64:65], v[64:65], v[96:97]
	v_add_f32_e32 v77, v81, v77
	v_lshl_add_u64 v[72:73], s[36:37], 0, v[72:73]
	v_add_f32_e32 v80, v77, v96
	v_lshl_add_u64 v[72:73], v[72:73], 0, s[20:21]
	v_pk_add_f32 v[80:81], v[96:97], v[80:81] op_sel_hi:[1,0]
	v_lshl_add_u64 v[72:73], v[72:73], 0, v[120:121]
	v_mov_b32_e32 v96, v70
	v_mov_b32_e32 v97, v66
	v_mul_f32_e32 v80, v70, v70
	v_pk_add_f32 v[82:83], v[86:87], v[82:83]
	v_pk_mul_f32 v[86:87], v[86:87], v[86:87]
	v_cvt_pk_bf16_f32 v103, v98, v99
	global_store_dwordx4 v[72:73], v[100:103], off
	v_mov_b32_e32 v83, v87
	v_pk_add_f32 v[82:83], v[82:83], v[88:89]
	v_pk_fma_f32 v[100:101], v[96:97], v[96:97], v[80:81] op_sel_hi:[1,1,0]
	v_cvt_pk_bf16_f32 v96, v68, v69
	v_cvt_pk_bf16_f32 v97, v70, v71
	v_cvt_pk_bf16_f32 v98, v64, v65
	v_cvt_pk_bf16_f32 v99, v66, v67
	global_store_dwordx4 v[72:73], v[96:99], off offset:256
	v_pk_add_f32 v[68:69], v[94:95], v[90:91]
	v_pk_mul_f32 v[72:73], v[94:95], v[94:95]
	v_mul_f32_e32 v85, v75, v75
	v_mov_b32_e32 v69, v73
	v_pk_add_f32 v[72:73], v[118:119], v[116:117]
	v_mov_b32_e32 v110, v79
	v_pk_add_f32 v[72:73], v[82:83], v[72:73]
	ds_bpermute_b32 v82, v93, v72
	ds_bpermute_b32 v83, v93, v73
	v_mov_b32_e32 v108, v75
	v_pk_add_f32 v[74:75], v[78:79], v[74:75]
	v_pk_mul_f32 v[78:79], v[78:79], v[78:79]
	v_mul_f32_e32 v77, v67, v67
	s_waitcnt lgkmcnt(0)
	v_pk_add_f32 v[72:73], v[72:73], v[82:83]
	ds_bpermute_b32 v82, v92, v72
	ds_bpermute_b32 v83, v92, v73
	v_mov_b32_e32 v75, v79
	v_pk_add_f32 v[74:75], v[74:75], v[84:85]
	v_mov_b32_e32 v100, v71
	v_mov_b32_e32 v80, v67
	s_waitcnt lgkmcnt(0)
	v_pk_add_f32 v[72:73], v[72:73], v[82:83]
	v_pk_add_f32 v[82:83], v[110:111], v[108:109]
	v_pk_add_f32 v[66:67], v[70:71], v[66:67]
	v_pk_add_f32 v[74:75], v[74:75], v[82:83]
	ds_bpermute_b32 v78, v93, v74
	ds_bpermute_b32 v79, v93, v75
	v_pk_mul_f32 v[70:71], v[70:71], v[70:71]
	v_mov_b32_e32 v126, v95
	v_mov_b32_e32 v67, v71
	v_pk_add_f32 v[66:67], v[66:67], v[76:77]
	s_waitcnt lgkmcnt(0)
	v_pk_add_f32 v[74:75], v[74:75], v[78:79]
	ds_bpermute_b32 v78, v92, v74
	ds_bpermute_b32 v79, v92, v75
	v_mov_b32_e32 v124, v91
	v_pk_add_f32 v[64:65], v[126:127], v[124:125]
	v_pk_add_f32 v[68:69], v[68:69], v[122:123]
	v_ashrrev_i32_e32 v139, 31, v138
	s_waitcnt lgkmcnt(0)
	v_pk_add_f32 v[74:75], v[74:75], v[78:79]
	v_pk_add_f32 v[78:79], v[100:101], v[80:81]
	v_pk_add_f32 v[64:65], v[68:69], v[64:65]
	v_pk_add_f32 v[66:67], v[66:67], v[78:79]
	ds_bpermute_b32 v70, v93, v66
	ds_bpermute_b32 v71, v93, v67
	ds_bpermute_b32 v68, v93, v64
	ds_bpermute_b32 v69, v93, v65
	v_readlane_b32 s14, v248, 11
	v_readlane_b32 s15, v248, 12
	s_waitcnt lgkmcnt(0)
	v_pk_add_f32 v[66:67], v[66:67], v[70:71]
	ds_bpermute_b32 v70, v92, v66
	ds_bpermute_b32 v71, v92, v67
	v_pk_add_f32 v[64:65], v[64:65], v[68:69]
	ds_bpermute_b32 v68, v92, v64
	ds_bpermute_b32 v69, v92, v65
	s_lshl_b64 s[48:49], s[50:51], 3
	s_waitcnt lgkmcnt(0)
; __device__ __forceinline__ unsigned cvt_pk_bf16(float lo, float hi) { unsigned r; asm volatile("v_cvt_pk_bf16_f32 %0, %1, %2" : "=v"(r) : "v"(lo), "v"(hi)); return r; }
;     __device__ __forceinline__ void operator()(const Acc& acc, const Unit& u, int wr, int wc, int fr, int fq) const {
;     ...
;         for (int ai = 0; ai < 2; ++ai) {
;             float S1[4], S2[4];
; #pragma unroll
;             for (int m = 0; m < 4; ++m) {
;                 const int row_in = ai * HALF + wr * 64 + m * 16 + fr;
;                 float s1 = 0.f, s2 = 0.f;
; #pragma unroll
;                 for (int bj = 0; bj < 2; ++bj) {
;                     const f32x4 v0 = acc[ai][bj][m][0], v1 = acc[ai][bj][m][1];
; #pragma unroll
;                     for (int j = 0; j < 4; ++j) { s1 += v0[j] + v1[j]; s2 += v0[j] * v0[j] + v1[j] * v1[j]; }
;                     u32x4 w; w.x = cvt_pk_bf16(v0[0], v0[1]); w.y = cvt_pk_bf16(v0[2], v0[3]); w.z = cvt_pk_bf16(v1[0], v1[1]); w.w = cvt_pk_bf16(v1[2], v1[3]);
;                     *(u32x4*)(O + u.coff + (size_t)row_in * RV + bj * HALF + wc * 32 + 8 * fq) = w;
;                 }
;                 s1 += __shfl_xor(s1, 16); s1 += __shfl_xor(s1, 32); s2 += __shfl_xor(s2, 16); s2 += __shfl_xor(s2, 32);
;                 S1[m] = s1; S2[m] = s2;
;             }
;             const float t1 = fq == 0 ? S1[0] : fq == 1 ? S1[1] : fq == 2 ? S1[2] : S1[3], t2 = fq == 0 ? S2[0] : fq == 1 ? S2[1] : fq == 2 ? S2[2] : S2[3];
;             const int row_st = ai * HALF + wr * 64 + fq * 16 + fr;
;             stats[((size_t)(nchunk * 256 + row_st) * 8 + h) * 8 + et * 4 + wc] = (f32x2){t1, t2};
	v_pk_add_f32 v[66:67], v[66:67], v[70:71]
	s_mov_b32 s25, s61
	v_cndmask_b32_e64 v67, v67, v75, s[46:47]
	v_cndmask_b32_e64 v66, v66, v74, s[46:47]
	v_pk_add_f32 v[64:65], v[64:65], v[68:69]
	v_cndmask_b32_e64 v66, v66, v72, s[44:45]
	v_cndmask_b32_e64 v67, v67, v73, s[44:45]
	v_cndmask_b32_e32 v65, v67, v65, vcc
	v_cndmask_b32_e32 v64, v66, v64, vcc
	v_lshlrev_b64 v[66:67], 9, v[138:139]
	v_lshl_add_u64 v[66:67], s[14:15], 0, v[66:67]
	v_lshl_add_u64 v[66:67], v[66:67], 0, s[34:35]
	v_lshl_add_u64 v[66:67], v[66:67], 0, s[48:49]
	v_lshl_add_u64 v[66:67], v[66:67], 0, s[24:25]
	global_store_dwordx2 v[66:67], v[64:65], off
	v_add_u32_e32 v64, 0x80, v140
	v_pk_add_f32 v[68:69], v[60:61], v[56:57]
	v_ashrrev_i32_e32 v65, 31, v64
	v_add_f32_e32 v68, 0, v68
	v_lshlrev_b64 v[64:65], 13, v[64:65]
	v_add_f32_e32 v72, v69, v68
	v_pk_mul_f32 v[68:69], v[58:59], v[58:59]
	v_pk_mul_f32 v[70:71], v[56:57], v[56:57]
	v_pk_add_f32 v[66:67], v[62:63], v[58:59]
	v_pk_fma_f32 v[68:69], v[62:63], v[62:63], v[68:69]
	v_pk_fma_f32 v[70:71], v[60:61], v[60:61], v[70:71]
	v_cvt_pk_bf16_f32 v60, v60, v61
	v_cvt_pk_bf16_f32 v61, v62, v63
	v_cvt_pk_bf16_f32 v62, v56, v57
	v_lshl_add_u64 v[56:57], s[36:37], 0, v[64:65]
	v_add_f32_e32 v66, v66, v72
	v_lshl_add_u64 v[56:57], v[56:57], 0, s[20:21]
	v_add_f32_e32 v72, v67, v66
	v_lshl_add_u64 v[66:67], v[56:57], 0, v[120:121]
	v_pk_add_f32 v[56:57], v[28:29], v[24:25]
	v_cvt_pk_bf16_f32 v63, v58, v59
	v_pk_mul_f32 v[58:59], v[28:29], v[28:29]
	v_add_f32_e32 v56, v72, v56
	v_add_f32_e32 v56, v57, v56
	v_add_f32_e32 v57, v70, v71
	v_add_f32_e32 v57, v68, v57
	v_pk_fma_f32 v[58:59], v[24:25], v[24:25], v[58:59]
	v_add_f32_e32 v57, v69, v57
	global_store_dwordx4 v[66:67], v[60:63], off
	s_nop 1
	v_add_f32_e32 v60, v57, v58
	v_pk_add_f32 v[58:59], v[58:59], v[60:61] op_sel_hi:[1,0]
	v_cvt_pk_bf16_f32 v62, v28, v29
	v_cvt_pk_bf16_f32 v63, v30, v31
	v_cvt_pk_bf16_f32 v64, v24, v25
	v_add_u32_e32 v24, 0x90, v140
	v_mov_b32_e32 v60, v30
	v_mov_b32_e32 v61, v26
	v_mul_f32_e32 v58, v30, v30
	v_cvt_pk_bf16_f32 v65, v26, v27
	global_store_dwordx4 v[66:67], v[62:65], off offset:256
	v_ashrrev_i32_e32 v25, 31, v24
	v_pk_fma_f32 v[60:61], v[60:61], v[60:61], v[58:59] op_sel_hi:[1,1,0]
	v_pk_add_f32 v[62:63], v[52:53], v[48:49]
	v_lshlrev_b64 v[24:25], 13, v[24:25]
	v_add_f32_e32 v58, 0, v62
	v_pk_add_f32 v[28:29], v[54:55], v[50:51]
	v_add_f32_e32 v58, v63, v58
	v_lshl_add_u64 v[24:25], s[36:37], 0, v[24:25]
	v_add_f32_e32 v28, v28, v58
	v_lshl_add_u64 v[24:25], v[24:25], 0, s[20:21]
	v_pk_mul_f32 v[64:65], v[48:49], v[48:49]
	v_add_f32_e32 v58, v29, v28
	v_lshl_add_u64 v[28:29], v[24:25], 0, v[120:121]
	v_pk_add_f32 v[24:25], v[20:21], v[16:17]
	v_pk_mul_f32 v[62:63], v[50:51], v[50:51]
	v_pk_fma_f32 v[64:65], v[52:53], v[52:53], v[64:65]
	v_add_f32_e32 v24, v58, v24
	v_pk_fma_f32 v[62:63], v[54:55], v[54:55], v[62:63]
	v_add_f32_e32 v24, v25, v24
	v_add_f32_e32 v25, v64, v65
	v_cvt_pk_bf16_f32 v52, v52, v53
	v_cvt_pk_bf16_f32 v53, v54, v55
	v_cvt_pk_bf16_f32 v54, v48, v49
	v_pk_mul_f32 v[48:49], v[20:21], v[20:21]
	v_add_f32_e32 v25, v62, v25
	v_pk_fma_f32 v[48:49], v[16:17], v[16:17], v[48:49]
	v_add_f32_e32 v25, v63, v25
	v_cvt_pk_bf16_f32 v55, v50, v51
	v_add_f32_e32 v50, v25, v48
	global_store_dwordx4 v[28:29], v[52:55], off
	v_mul_f32_e32 v25, v19, v19
	v_mul_f32_e32 v57, v27, v27
	v_pk_add_f32 v[52:53], v[48:49], v[50:51] op_sel_hi:[1,0]
	v_mov_b32_e32 v48, v22
	v_mov_b32_e32 v49, v18
	v_mul_f32_e32 v50, v22, v22
	v_pk_fma_f32 v[54:55], v[48:49], v[48:49], v[50:51] op_sel_hi:[1,1,0]
	v_cvt_pk_bf16_f32 v48, v20, v21
	v_cvt_pk_bf16_f32 v49, v22, v23
	v_cvt_pk_bf16_f32 v50, v16, v17
	v_cvt_pk_bf16_f32 v51, v18, v19
	global_store_dwordx4 v[28:29], v[48:51], off offset:256
	v_pk_add_f32 v[28:29], v[44:45], v[40:41]
	v_pk_add_f32 v[20:21], v[46:47], v[42:43]
	v_add_f32_e32 v28, 0, v28
	v_add_f32_e32 v50, v29, v28
	v_add_f32_e32 v20, v20, v50
	v_pk_mul_f32 v[48:49], v[40:41], v[40:41]
	v_add_f32_e32 v50, v21, v20
	v_pk_add_f32 v[20:21], v[12:13], v[8:9]
	v_pk_mul_f32 v[28:29], v[42:43], v[42:43]
	v_pk_fma_f32 v[48:49], v[44:45], v[44:45], v[48:49]
	v_add_f32_e32 v20, v50, v20
	v_add_u32_e32 v16, 0xa0, v140
	v_pk_fma_f32 v[28:29], v[46:47], v[46:47], v[28:29]
	v_add_f32_e32 v20, v21, v20
	v_add_f32_e32 v21, v48, v49
	v_ashrrev_i32_e32 v17, 31, v16
	v_cvt_pk_bf16_f32 v44, v44, v45
	v_cvt_pk_bf16_f32 v45, v46, v47
	v_cvt_pk_bf16_f32 v46, v40, v41
	v_pk_mul_f32 v[40:41], v[12:13], v[12:13]
	v_add_f32_e32 v21, v28, v21
	v_lshlrev_b64 v[16:17], 13, v[16:17]
	v_pk_fma_f32 v[40:41], v[8:9], v[8:9], v[40:41]
	v_add_f32_e32 v21, v29, v21
	v_lshl_add_u64 v[16:17], s[36:37], 0, v[16:17]
	v_add_f32_e32 v28, v21, v40
	v_lshl_add_u64 v[16:17], v[16:17], 0, s[20:21]
	v_pk_add_f32 v[28:29], v[40:41], v[28:29] op_sel_hi:[1,0]
; __device__ __forceinline__ unsigned cvt_pk_bf16(float lo, float hi) { unsigned r; asm volatile("v_cvt_pk_bf16_f32 %0, %1, %2" : "=v"(r) : "v"(lo), "v"(hi)); return r; }
; #define PG8_BAR __builtin_amdgcn_s_barrier()
; template <class Epi, class Map>
; __device__ __forceinline__ void gemm_phase(LAS unsigned char* lds, const Gemm g, const Sched<Map>& S, const Epi& E) {
;     ...
;         if (!has_next) break;
; #pragma unroll
;         for (int a = 0; a < 2; ++a)
; #pragma unroll
;             for (int b = 0; b < 2; ++b)
; #pragma unroll
;                 for (int m = 0; m < 4; ++m)
; #pragma unroll
;                     for (int n = 0; n < 2; ++n) acc[a][b][m][n] = (f32x4){0.f, 0.f, 0.f, 0.f};
;         cur = nxt; cA = nA; cB = nB; ++ui;
;         if (wr == 1) PG8_BAR;
;     __device__ __forceinline__ void operator()(const Acc& acc, const Unit& u, int wr, int wc, int fr, int fq) const {
;     ...
;             for (int m = 0; m < 4; ++m) {
;                 const int row_in = ai * HALF + wr * 64 + m * 16 + fr;
;                 float s1 = 0.f, s2 = 0.f;
; #pragma unroll
;                 for (int bj = 0; bj < 2; ++bj) {
;                     const f32x4 v0 = acc[ai][bj][m][0], v1 = acc[ai][bj][m][1];
; #pragma unroll
;                     for (int j = 0; j < 4; ++j) { s1 += v0[j] + v1[j]; s2 += v0[j] * v0[j] + v1[j] * v1[j]; }
;                     u32x4 w; w.x = cvt_pk_bf16(v0[0], v0[1]); w.y = cvt_pk_bf16(v0[2], v0[3]); w.z = cvt_pk_bf16(v1[0], v1[1]); w.w = cvt_pk_bf16(v1[2], v1[3]);
;                     *(u32x4*)(O + u.coff + (size_t)row_in * RV + bj * HALF + wc * 32 + 8 * fq) = w;
;                 }
;                 s1 += __shfl_xor(s1, 16); s1 += __shfl_xor(s1, 32); s2 += __shfl_xor(s2, 16); s2 += __shfl_xor(s2, 32);
;                 S1[m] = s1; S2[m] = s2;
;             }
;             const float t1 = fq == 0 ? S1[0] : fq == 1 ? S1[1] : fq == 2 ? S1[2] : S1[3], t2 = fq == 0 ? S2[0] : fq == 1 ? S2[1] : fq == 2 ? S2[2] : S2[3];
;             const int row_st = ai * HALF + wr * 64 + fq * 16 + fr;
;             stats[((size_t)(nchunk * 256 + row_st) * 8 + h) * 8 + et * 4 + wc] = (f32x2){t1, t2};
	v_lshl_add_u64 v[16:17], v[16:17], 0, v[120:121]
	v_mov_b32_e32 v40, v14
	v_mov_b32_e32 v41, v10
	v_mul_f32_e32 v28, v14, v14
	v_cvt_pk_bf16_f32 v47, v42, v43
	global_store_dwordx4 v[16:17], v[44:47], off
	v_mov_b32_e32 v54, v23
	v_mov_b32_e32 v52, v19
	v_pk_fma_f32 v[44:45], v[40:41], v[40:41], v[28:29] op_sel_hi:[1,1,0]
	v_cvt_pk_bf16_f32 v40, v12, v13
	v_cvt_pk_bf16_f32 v41, v14, v15
	v_cvt_pk_bf16_f32 v42, v8, v9
	v_cvt_pk_bf16_f32 v43, v10, v11
	global_store_dwordx4 v[16:17], v[40:43], off offset:256
	v_pk_add_f32 v[16:17], v[36:37], v[32:33]
	v_pk_add_f32 v[12:13], v[38:39], v[34:35]
	v_add_f32_e32 v16, 0, v16
	v_add_f32_e32 v28, v17, v16
	v_add_f32_e32 v12, v12, v28
	v_pk_mul_f32 v[40:41], v[32:33], v[32:33]
	v_add_f32_e32 v28, v13, v12
	v_pk_add_f32 v[12:13], v[4:5], v[0:1]
	v_pk_mul_f32 v[16:17], v[34:35], v[34:35]
	v_pk_fma_f32 v[40:41], v[36:37], v[36:37], v[40:41]
	v_add_f32_e32 v12, v28, v12
	v_add_u32_e32 v8, 0xb0, v140
	v_pk_fma_f32 v[16:17], v[38:39], v[38:39], v[16:17]
	v_add_f32_e32 v12, v13, v12
	v_add_f32_e32 v13, v40, v41
	v_ashrrev_i32_e32 v9, 31, v8
	v_cvt_pk_bf16_f32 v36, v36, v37
	v_cvt_pk_bf16_f32 v37, v38, v39
	v_cvt_pk_bf16_f32 v38, v32, v33
	v_pk_mul_f32 v[32:33], v[4:5], v[4:5]
	v_add_f32_e32 v13, v16, v13
	v_lshlrev_b64 v[8:9], 13, v[8:9]
	v_pk_fma_f32 v[32:33], v[0:1], v[0:1], v[32:33]
	v_add_f32_e32 v13, v17, v13
	v_lshl_add_u64 v[8:9], s[36:37], 0, v[8:9]
	v_add_f32_e32 v16, v13, v32
	v_lshl_add_u64 v[8:9], v[8:9], 0, s[20:21]
	v_pk_add_f32 v[16:17], v[32:33], v[16:17] op_sel_hi:[1,0]
	v_lshl_add_u64 v[8:9], v[8:9], 0, v[120:121]
	v_mov_b32_e32 v32, v6
	v_mov_b32_e32 v33, v2
	v_mul_f32_e32 v16, v6, v6
	v_pk_add_f32 v[18:19], v[22:23], v[18:19]
	v_pk_mul_f32 v[22:23], v[22:23], v[22:23]
	v_cvt_pk_bf16_f32 v39, v34, v35
	global_store_dwordx4 v[8:9], v[36:39], off
	v_mov_b32_e32 v19, v23
	v_pk_add_f32 v[18:19], v[18:19], v[24:25]
	v_pk_fma_f32 v[36:37], v[32:33], v[32:33], v[16:17] op_sel_hi:[1,1,0]
	v_cvt_pk_bf16_f32 v32, v4, v5
	v_cvt_pk_bf16_f32 v33, v6, v7
	v_cvt_pk_bf16_f32 v34, v0, v1
	v_cvt_pk_bf16_f32 v35, v2, v3
	global_store_dwordx4 v[8:9], v[32:35], off offset:256
	v_pk_add_f32 v[4:5], v[30:31], v[26:27]
	v_pk_mul_f32 v[8:9], v[30:31], v[30:31]
	v_mul_f32_e32 v21, v11, v11
	v_mov_b32_e32 v5, v9
	v_pk_add_f32 v[8:9], v[54:55], v[52:53]
	v_mov_b32_e32 v44, v15
	v_pk_add_f32 v[8:9], v[18:19], v[8:9]
	ds_bpermute_b32 v18, v93, v8
	ds_bpermute_b32 v19, v93, v9
	v_mov_b32_e32 v28, v11
	v_pk_add_f32 v[10:11], v[14:15], v[10:11]
	v_pk_mul_f32 v[14:15], v[14:15], v[14:15]
	v_mul_f32_e32 v13, v3, v3
	s_waitcnt lgkmcnt(0)
	v_pk_add_f32 v[8:9], v[8:9], v[18:19]
	ds_bpermute_b32 v18, v92, v8
	ds_bpermute_b32 v19, v92, v9
	v_mov_b32_e32 v11, v15
	v_pk_add_f32 v[10:11], v[10:11], v[20:21]
	v_mov_b32_e32 v36, v7
	v_mov_b32_e32 v16, v3
	s_waitcnt lgkmcnt(0)
	v_pk_add_f32 v[8:9], v[8:9], v[18:19]
	v_pk_add_f32 v[18:19], v[44:45], v[28:29]
	v_pk_add_f32 v[2:3], v[6:7], v[2:3]
	v_pk_add_f32 v[10:11], v[10:11], v[18:19]
	ds_bpermute_b32 v14, v93, v10
	ds_bpermute_b32 v15, v93, v11
	v_pk_mul_f32 v[6:7], v[6:7], v[6:7]
	v_mov_b32_e32 v60, v31
	v_mov_b32_e32 v3, v7
	v_pk_add_f32 v[2:3], v[2:3], v[12:13]
	s_waitcnt lgkmcnt(0)
	v_pk_add_f32 v[10:11], v[10:11], v[14:15]
	ds_bpermute_b32 v14, v92, v10
	ds_bpermute_b32 v15, v92, v11
	v_mov_b32_e32 v58, v27
	v_pk_add_f32 v[0:1], v[60:61], v[58:59]
	v_pk_add_f32 v[4:5], v[4:5], v[56:57]
	s_waitcnt lgkmcnt(0)
	v_pk_add_f32 v[10:11], v[10:11], v[14:15]
	v_pk_add_f32 v[14:15], v[36:37], v[16:17]
	v_pk_add_f32 v[0:1], v[4:5], v[0:1]
	v_pk_add_f32 v[2:3], v[2:3], v[14:15]
	ds_bpermute_b32 v6, v93, v2
	ds_bpermute_b32 v7, v93, v3
	ds_bpermute_b32 v4, v93, v0
	ds_bpermute_b32 v5, v93, v1
	s_waitcnt lgkmcnt(0)
	v_pk_add_f32 v[2:3], v[2:3], v[6:7]
	ds_bpermute_b32 v6, v92, v2
	ds_bpermute_b32 v7, v92, v3
	v_pk_add_f32 v[0:1], v[0:1], v[4:5]
	ds_bpermute_b32 v4, v92, v0
	ds_bpermute_b32 v5, v92, v1
	s_waitcnt lgkmcnt(0)
	v_pk_add_f32 v[2:3], v[2:3], v[6:7]
	s_nop 0
	v_cndmask_b32_e64 v2, v2, v10, s[46:47]
	v_cndmask_b32_e64 v3, v3, v11, s[46:47]
	v_pk_add_f32 v[0:1], v[0:1], v[4:5]
	v_cndmask_b32_e64 v2, v2, v8, s[44:45]
	v_cndmask_b32_e64 v3, v3, v9, s[44:45]
	v_cndmask_b32_e32 v0, v2, v0, vcc
	v_add_u32_e32 v2, 0x80, v138
	v_cndmask_b32_e32 v1, v3, v1, vcc
	v_ashrrev_i32_e32 v3, 31, v2
	v_lshlrev_b64 v[2:3], 9, v[2:3]
	v_lshl_add_u64 v[2:3], s[14:15], 0, v[2:3]
	v_lshl_add_u64 v[2:3], v[2:3], 0, s[34:35]
	v_lshl_add_u64 v[2:3], v[2:3], 0, s[48:49]
	v_lshl_add_u64 v[2:3], v[2:3], 0, s[24:25]
	s_mov_b64 s[34:35], -1
	s_andn2_b64 vcc, exec, s[42:43]
	global_store_dwordx2 v[2:3], v[0:1], off
	s_cbranch_vccnz .LBB0_800
	s_andn2_b64 vcc, exec, s[16:17]
	s_cbranch_vccnz .LBB0_799
	s_barrier
	s_branch .LBB0_799

; #define PG8_STAGE(bufoff, gbase, voff) do { _Pragma("unroll") for (int _i = 0; _i < 2; ++_i) \
;         __builtin_amdgcn_global_load_lds((const unsigned*)((const char*)(gbase) + (voff)[_i]), (LAS unsigned*)(lds + (bufoff) + ldsw + _i * 8192), 16, 0, 0); } while (0)
; #define PG8_LDA(dst, b, h) do { _Pragma("unroll") for (int m = 0; m < 4; ++m) _Pragma("unroll") for (int k = 0; k < 2; ++k) dst[m][k] = *(const LAS bf16x8*)(lds + PG8_SA(b, h) + aoff + m * 2048 + k * 1024); } while (0)
; #define PG8_LDB(dst, b, h) do { _Pragma("unroll") for (int n = 0; n < 2; ++n) _Pragma("unroll") for (int k = 0; k < 2; ++k) dst[n][k] = *(const LAS bf16x8*)(lds + PG8_SB(b, h) + boff + n * 2048 + k * 1024); } while (0)
; #define PG8_MMA(ai, bj, At, Bt) do { __builtin_amdgcn_s_setprio(1); _Pragma("unroll") for (int m = 0; m < 4; ++m) _Pragma("unroll") for (int n = 0; n < 2; ++n) _Pragma("unroll") for (int k = 0; k < 2; ++k) \
;         acc[ai][bj][m][n] = __builtin_amdgcn_mfma_f32_16x16x32_bf16(Bt[n][k], At[m][k], acc[ai][bj][m][n], 0, 0, 0); __builtin_amdgcn_s_setprio(0); } while (0)
; #define PG8_WAIT_V(n) asm volatile("s_waitcnt vmcnt(" #n ")" ::: "memory")
; #define PG8_WAIT_L(n) asm volatile("s_waitcnt lgkmcnt(" #n ")" ::: "memory")
; #define PG8_BAR __builtin_amdgcn_s_barrier()
; template <class Epi, class Map>
; __device__ __forceinline__ void gemm_phase(LAS unsigned char* lds, const Gemm g, const Sched<Map>& S, const Epi& E) {
;     ...
;         for (int t = 0; t < nt; t += 2) {
;             const bool last = (t == nt - 2);
;             const char* a1 = cA + (size_t)(t + 1) * kstep;
;             const char* a2 = last ? nA : cA + (size_t)(t + 2) * kstep; const char* b2 = last ? nB : cB + (size_t)(t + 2) * kstep;
;             const char* a3 = a2 + kstep; const char* b3 = b2 + kstep;
;             PG8_LDB(B0, 0, 0); PG8_LDB(B1, 0, 1); PG8_SCHED; PG8_LDA(At, 0, 0); PG8_STAGE(PG8_SA(1, 1), a1 + hstepA, voffA);
;             PG8_WAIT_V(8); PG8_WAIT_L(0); PG8_BAR; PG8_MMA(0, 0, At, B0); PG8_MMA(0, 1, At, B1); PG8_BAR; PG8_SCHED;
;     ...
; #pragma unroll
;         for (int a = 0; a < 2; ++a)
; #pragma unroll
;             for (int b = 0; b < 2; ++b)
; #pragma unroll
;                 for (int m = 0; m < 4; ++m)
; #pragma unroll
;                     for (int n = 0; n < 2; ++n) acc[a][b][m][n] = (f32x4){0.f, 0.f, 0.f, 0.f};
;         cur = nxt; cA = nA; cB = nB; ++ui;
.LBB0_879:
	s_add_u32 s16, s78, s54
	s_addc_u32 s17, s79, 0
	s_and_b64 s[2:3], s[40:41], exec
	v_readlane_b32 s4, v246, 58
	s_cselect_b32 s2, s17, s19
	s_cselect_b32 s3, s16, s18
	s_add_u32 s46, s4, s53
	v_readlane_b32 s4, v246, 59
	s_addc_u32 s47, s4, 0
	s_and_b64 s[4:5], s[40:41], exec
	s_cselect_b32 s4, s47, s21
	s_cselect_b32 s5, s46, s20
	s_add_u32 s18, s18, 0x80080
	s_addc_u32 s19, s19, 0
	s_add_u32 s6, s20, 0x100
	v_mov_b32_e32 v0, 0
	s_addc_u32 s7, s21, 0
	s_mov_b32 s8, -2
	v_mov_b32_e32 v1, v0
	v_mov_b32_e32 v2, v0
	v_mov_b32_e32 v3, v0
	v_mov_b32_e32 v4, v0
	v_mov_b32_e32 v5, v0
	v_mov_b32_e32 v6, v0
	v_mov_b32_e32 v7, v0
	v_mov_b32_e32 v16, v0
	v_mov_b32_e32 v17, v0
	v_mov_b32_e32 v18, v0
	v_mov_b32_e32 v19, v0
	v_mov_b32_e32 v20, v0
	v_mov_b32_e32 v21, v0
	v_mov_b32_e32 v22, v0
	v_mov_b32_e32 v23, v0
	v_mov_b32_e32 v32, v0
	v_mov_b32_e32 v33, v0
	v_mov_b32_e32 v34, v0
	v_mov_b32_e32 v35, v0
	v_mov_b32_e32 v36, v0
	v_mov_b32_e32 v37, v0
	v_mov_b32_e32 v38, v0
	v_mov_b32_e32 v39, v0
	v_mov_b32_e32 v48, v0
	v_mov_b32_e32 v49, v0
	v_mov_b32_e32 v50, v0
	v_mov_b32_e32 v51, v0
	v_mov_b32_e32 v52, v0
	v_mov_b32_e32 v53, v0
	v_mov_b32_e32 v54, v0
	v_mov_b32_e32 v55, v0
	v_mov_b32_e32 v8, v0
	v_mov_b32_e32 v9, v0
	v_mov_b32_e32 v10, v0
	v_mov_b32_e32 v11, v0
	v_mov_b32_e32 v12, v0
	v_mov_b32_e32 v13, v0
	v_mov_b32_e32 v14, v0
	v_mov_b32_e32 v15, v0
	v_mov_b32_e32 v24, v0
	v_mov_b32_e32 v25, v0
	v_mov_b32_e32 v26, v0
	v_mov_b32_e32 v27, v0
	v_mov_b32_e32 v28, v0
	v_mov_b32_e32 v29, v0
	v_mov_b32_e32 v30, v0
	v_mov_b32_e32 v31, v0
	v_mov_b32_e32 v40, v0
	v_mov_b32_e32 v41, v0
	v_mov_b32_e32 v42, v0
	v_mov_b32_e32 v43, v0
	v_mov_b32_e32 v44, v0
	v_mov_b32_e32 v45, v0
	v_mov_b32_e32 v46, v0
	v_mov_b32_e32 v47, v0
	v_mov_b32_e32 v56, v0
	v_mov_b32_e32 v57, v0
	v_mov_b32_e32 v58, v0
	v_mov_b32_e32 v59, v0
	v_mov_b32_e32 v60, v0
	v_mov_b32_e32 v61, v0
	v_mov_b32_e32 v62, v0
	v_mov_b32_e32 v63, v0
	v_mov_b32_e32 v64, v0
	v_mov_b32_e32 v65, v0
	v_mov_b32_e32 v66, v0
	v_mov_b32_e32 v67, v0
	v_mov_b32_e32 v68, v0
	v_mov_b32_e32 v69, v0
	v_mov_b32_e32 v70, v0
	v_mov_b32_e32 v71, v0
	v_mov_b32_e32 v80, v0
	v_mov_b32_e32 v81, v0
	v_mov_b32_e32 v82, v0
	v_mov_b32_e32 v83, v0
	v_mov_b32_e32 v84, v0
	v_mov_b32_e32 v85, v0
	v_mov_b32_e32 v86, v0
	v_mov_b32_e32 v87, v0
	v_mov_b32_e32 v96, v0
	v_mov_b32_e32 v97, v0
	v_mov_b32_e32 v98, v0
	v_mov_b32_e32 v99, v0
	v_mov_b32_e32 v100, v0
	v_mov_b32_e32 v101, v0
	v_mov_b32_e32 v102, v0
	v_mov_b32_e32 v103, v0
	v_mov_b32_e32 v112, v0
	v_mov_b32_e32 v113, v0
	v_mov_b32_e32 v114, v0
	v_mov_b32_e32 v115, v0
	v_mov_b32_e32 v116, v0
	v_mov_b32_e32 v117, v0
	v_mov_b32_e32 v118, v0
	v_mov_b32_e32 v119, v0
	v_mov_b32_e32 v72, v0
	v_mov_b32_e32 v73, v0
	v_mov_b32_e32 v74, v0
	v_mov_b32_e32 v75, v0
	v_mov_b32_e32 v76, v0
	v_mov_b32_e32 v77, v0
	v_mov_b32_e32 v78, v0
	v_mov_b32_e32 v79, v0
	v_mov_b32_e32 v88, v0
	v_mov_b32_e32 v89, v0
	v_mov_b32_e32 v90, v0
	v_mov_b32_e32 v91, v0
	v_mov_b32_e32 v92, v0
	v_mov_b32_e32 v93, v0
	v_mov_b32_e32 v94, v0
	v_mov_b32_e32 v95, v0
	v_mov_b32_e32 v104, v0
	v_mov_b32_e32 v105, v0
	v_mov_b32_e32 v106, v0
	v_mov_b32_e32 v107, v0
	v_mov_b32_e32 v108, v0
	v_mov_b32_e32 v109, v0
	v_mov_b32_e32 v110, v0
	v_mov_b32_e32 v111, v0
	v_mov_b32_e32 v120, v0
	v_mov_b32_e32 v121, v0
	v_mov_b32_e32 v122, v0
	v_mov_b32_e32 v123, v0
	v_mov_b32_e32 v128, v0
	v_mov_b32_e32 v129, v0
	v_mov_b32_e32 v130, v0
	v_mov_b32_e32 v131, v0
.LBB0_880:
	s_add_u32 s9, s18, 0xfff80080
	s_addc_u32 s10, s19, -1
	s_add_i32 s11, 0, 0x10000
	s_cmp_eq_u32 s8, 28
	s_cselect_b32 s25, s2, s10
	s_cselect_b32 s24, s3, s9
	s_cselect_b32 s21, s4, s7
	s_cselect_b32 s20, s5, s6
	s_add_i32 s9, 0, 0x14000
	v_add_u32_e32 v166, s11, v173
	v_add_u32_e32 v170, s9, v173
	ds_read_b128 v[124:127], v166
	ds_read_b128 v[132:135], v166 offset:1024
	ds_read_b128 v[162:165], v166 offset:2048
	ds_read_b128 v[166:169], v166 offset:3072
	ds_read_b128 v[176:179], v170
	ds_read_b128 v[192:195], v170 offset:1024
	ds_read_b128 v[196:199], v170 offset:2048
	ds_read_b128 v[200:203], v170 offset:3072
	v_lshl_add_u64 v[170:171], s[18:19], 0, v[142:143]
	s_add_i32 m0, s29, 0xc000
	ds_read_b128 v[204:207], v174
	ds_read_b128 v[208:211], v174 offset:1024
	ds_read_b128 v[212:215], v174 offset:2048
	ds_read_b128 v[216:219], v174 offset:3072
	ds_read_b128 v[220:223], v174 offset:4096
	ds_read_b128 v[224:227], v174 offset:5120
	ds_read_b128 v[228:231], v174 offset:6144
	ds_read_b128 v[232:235], v174 offset:7168
	global_load_lds_dwordx4 v[170:171], off
	v_lshl_add_u64 v[170:171], s[18:19], 0, v[160:161]
	s_add_i32 m0, s29, 0xe000
	s_nop 0
	global_load_lds_dwordx4 v[170:171], off
	s_waitcnt vmcnt(8)
	s_waitcnt lgkmcnt(0)
	s_barrier
; #define PG8_STAGE(bufoff, gbase, voff) do { _Pragma("unroll") for (int _i = 0; _i < 2; ++_i) \
;         __builtin_amdgcn_global_load_lds((const unsigned*)((const char*)(gbase) + (voff)[_i]), (LAS unsigned*)(lds + (bufoff) + ldsw + _i * 8192), 16, 0, 0); } while (0)
; #define PG8_LDA(dst, b, h) do { _Pragma("unroll") for (int m = 0; m < 4; ++m) _Pragma("unroll") for (int k = 0; k < 2; ++k) dst[m][k] = *(const LAS bf16x8*)(lds + PG8_SA(b, h) + aoff + m * 2048 + k * 1024); } while (0)
; #define PG8_LDB(dst, b, h) do { _Pragma("unroll") for (int n = 0; n < 2; ++n) _Pragma("unroll") for (int k = 0; k < 2; ++k) dst[n][k] = *(const LAS bf16x8*)(lds + PG8_SB(b, h) + boff + n * 2048 + k * 1024); } while (0)
; #define PG8_MMA(ai, bj, At, Bt) do { __builtin_amdgcn_s_setprio(1); _Pragma("unroll") for (int m = 0; m < 4; ++m) _Pragma("unroll") for (int n = 0; n < 2; ++n) _Pragma("unroll") for (int k = 0; k < 2; ++k) \
;         acc[ai][bj][m][n] = __builtin_amdgcn_mfma_f32_16x16x32_bf16(Bt[n][k], At[m][k], acc[ai][bj][m][n], 0, 0, 0); __builtin_amdgcn_s_setprio(0); } while (0)
; #define PG8_WAIT_V(n) asm volatile("s_waitcnt vmcnt(" #n ")" ::: "memory")
; #define PG8_WAIT_L(n) asm volatile("s_waitcnt lgkmcnt(" #n ")" ::: "memory")
; #define PG8_BAR __builtin_amdgcn_s_barrier()
; #define PG8_SCHED __builtin_amdgcn_sched_barrier(0)
; template <class Epi, class Map>
; __device__ __forceinline__ void gemm_phase(LAS unsigned char* lds, const Gemm g, const Sched<Map>& S, const Epi& E) {
;     ...
;             PG8_WAIT_V(8); PG8_WAIT_L(0); PG8_BAR; PG8_MMA(0, 0, At, B0); PG8_MMA(0, 1, At, B1); PG8_BAR; PG8_SCHED;
;             PG8_LDA(At, 0, 1); PG8_STAGE(PG8_SB(0, 0), b2, voffB); PG8_STAGE(PG8_SB(0, 1), b2 + hstepB, voffB); PG8_STAGE(PG8_SA(0, 0), a2, voffA);
;             PG8_WAIT_V(8); PG8_WAIT_L(0); PG8_BAR; PG8_MMA(1, 0, At, B0); PG8_MMA(1, 1, At, B1); PG8_BAR; PG8_SCHED;
;             PG8_LDB(B0, 1, 0); PG8_LDB(B1, 1, 1); PG8_SCHED; PG8_LDA(At, 1, 0); PG8_STAGE(PG8_SA(0, 1), a2 + hstepA, voffA);
;             PG8_WAIT_V(8); PG8_WAIT_L(0); PG8_BAR; PG8_MMA(0, 0, At, B0); PG8_MMA(0, 1, At, B1); PG8_BAR; PG8_SCHED;
;             PG8_LDA(At, 1, 1); PG8_STAGE(PG8_SB(1, 0), b3, voffB); PG8_STAGE(PG8_SB(1, 1), b3 + hstepB, voffB); PG8_STAGE(PG8_SA(1, 0), a3, voffA);
	s_waitcnt lgkmcnt(0)
	v_mfma_f32_16x16x32_bf16 v[128:131], v[124:127], v[204:207], v[128:131]
	v_mfma_f32_16x16x32_bf16 v[120:123], v[162:165], v[204:207], v[120:123]
	v_mfma_f32_16x16x32_bf16 v[108:111], v[124:127], v[212:215], v[108:111]
	v_mfma_f32_16x16x32_bf16 v[104:107], v[162:165], v[212:215], v[104:107]
	v_mfma_f32_16x16x32_bf16 v[92:95], v[124:127], v[220:223], v[92:95]
	v_mfma_f32_16x16x32_bf16 v[88:91], v[162:165], v[220:223], v[88:91]
	v_mfma_f32_16x16x32_bf16 v[76:79], v[124:127], v[228:231], v[76:79]
	v_mfma_f32_16x16x32_bf16 v[72:75], v[162:165], v[228:231], v[72:75]
	v_mfma_f32_16x16x32_bf16 v[128:131], v[132:135], v[208:211], v[128:131]
	v_mfma_f32_16x16x32_bf16 v[120:123], v[166:169], v[208:211], v[120:123]
	v_mfma_f32_16x16x32_bf16 v[108:111], v[132:135], v[216:219], v[108:111]
	v_mfma_f32_16x16x32_bf16 v[104:107], v[166:169], v[216:219], v[104:107]
	v_mfma_f32_16x16x32_bf16 v[92:95], v[132:135], v[224:227], v[92:95]
	v_mfma_f32_16x16x32_bf16 v[88:91], v[166:169], v[224:227], v[88:91]
	v_mfma_f32_16x16x32_bf16 v[76:79], v[132:135], v[232:235], v[76:79]
	v_mfma_f32_16x16x32_bf16 v[72:75], v[166:169], v[232:235], v[72:75]
	v_mfma_f32_16x16x32_bf16 v[116:119], v[176:179], v[204:207], v[116:119]
	v_mfma_f32_16x16x32_bf16 v[112:115], v[196:199], v[204:207], v[112:115]
	v_mfma_f32_16x16x32_bf16 v[100:103], v[176:179], v[212:215], v[100:103]
	v_mfma_f32_16x16x32_bf16 v[96:99], v[196:199], v[212:215], v[96:99]
	v_mfma_f32_16x16x32_bf16 v[84:87], v[176:179], v[220:223], v[84:87]
	v_mfma_f32_16x16x32_bf16 v[80:83], v[196:199], v[220:223], v[80:83]
	v_mfma_f32_16x16x32_bf16 v[68:71], v[176:179], v[228:231], v[68:71]
	v_mfma_f32_16x16x32_bf16 v[64:67], v[196:199], v[228:231], v[64:67]
	v_mfma_f32_16x16x32_bf16 v[116:119], v[192:195], v[208:211], v[116:119]
	v_mfma_f32_16x16x32_bf16 v[112:115], v[200:203], v[208:211], v[112:115]
	v_mfma_f32_16x16x32_bf16 v[100:103], v[192:195], v[216:219], v[100:103]
	v_mfma_f32_16x16x32_bf16 v[96:99], v[200:203], v[216:219], v[96:99]
	v_mfma_f32_16x16x32_bf16 v[84:87], v[192:195], v[224:227], v[84:87]
	v_mfma_f32_16x16x32_bf16 v[80:83], v[200:203], v[224:227], v[80:83]
	v_mfma_f32_16x16x32_bf16 v[68:71], v[192:195], v[232:235], v[68:71]
	v_mfma_f32_16x16x32_bf16 v[64:67], v[200:203], v[232:235], v[64:67]
	s_barrier
	s_add_i32 s10, s11, s28
	v_lshl_add_u64 v[170:171], s[20:21], 0, v[144:145]
	s_mov_b32 m0, s10
	ds_read_b128 v[204:207], v174 offset:16384
	ds_read_b128 v[208:211], v174 offset:17408
	ds_read_b128 v[212:215], v174 offset:18432
	ds_read_b128 v[216:219], v174 offset:19456
	ds_read_b128 v[220:223], v174 offset:20480
	ds_read_b128 v[224:227], v174 offset:21504
	ds_read_b128 v[228:231], v174 offset:22528
	ds_read_b128 v[232:235], v174 offset:23552
	global_load_lds_dwordx4 v[170:171], off
	s_add_i32 m0, s10, 0x2000
	s_add_u32 s10, s20, 0x80000
	v_lshl_add_u64 v[180:181], s[20:21], 0, v[136:137]
	s_addc_u32 s11, s21, 0
	s_add_i32 s9, s9, s28
	global_load_lds_dwordx4 v[180:181], off
	v_lshl_add_u64 v[236:237], s[10:11], 0, v[144:145]
	s_mov_b32 m0, s9
	v_lshl_add_u64 v[238:239], s[24:25], 0, v[138:139]
	global_load_lds_dwordx4 v[236:237], off
	v_lshl_add_u64 v[236:237], s[10:11], 0, v[136:137]
	s_add_i32 m0, s9, 0x2000
	s_nop 0
	global_load_lds_dwordx4 v[236:237], off
	v_lshl_add_u64 v[236:237], s[24:25], 0, v[140:141]
	s_mov_b32 m0, s29
	s_nop 0
	global_load_lds_dwordx4 v[236:237], off
	s_mov_b32 m0, s30
	s_nop 0
	global_load_lds_dwordx4 v[238:239], off
	s_waitcnt vmcnt(8)
	s_waitcnt lgkmcnt(0)
	s_barrier
	s_waitcnt lgkmcnt(0)
	v_mfma_f32_16x16x32_bf16 v[60:63], v[124:127], v[204:207], v[60:63]
	v_mfma_f32_16x16x32_bf16 v[56:59], v[162:165], v[204:207], v[56:59]
	v_mfma_f32_16x16x32_bf16 v[44:47], v[124:127], v[212:215], v[44:47]
	v_mfma_f32_16x16x32_bf16 v[40:43], v[162:165], v[212:215], v[40:43]
	v_mfma_f32_16x16x32_bf16 v[28:31], v[124:127], v[220:223], v[28:31]
	v_mfma_f32_16x16x32_bf16 v[24:27], v[162:165], v[220:223], v[24:27]
	v_mfma_f32_16x16x32_bf16 v[12:15], v[124:127], v[228:231], v[12:15]
	v_mfma_f32_16x16x32_bf16 v[8:11], v[162:165], v[228:231], v[8:11]
	v_mfma_f32_16x16x32_bf16 v[60:63], v[132:135], v[208:211], v[60:63]
	v_mfma_f32_16x16x32_bf16 v[56:59], v[166:169], v[208:211], v[56:59]
	v_mfma_f32_16x16x32_bf16 v[44:47], v[132:135], v[216:219], v[44:47]
	v_mfma_f32_16x16x32_bf16 v[40:43], v[166:169], v[216:219], v[40:43]
	v_mfma_f32_16x16x32_bf16 v[28:31], v[132:135], v[224:227], v[28:31]
	v_mfma_f32_16x16x32_bf16 v[24:27], v[166:169], v[224:227], v[24:27]
	v_mfma_f32_16x16x32_bf16 v[12:15], v[132:135], v[232:235], v[12:15]
	v_mfma_f32_16x16x32_bf16 v[8:11], v[166:169], v[232:235], v[8:11]
	v_mfma_f32_16x16x32_bf16 v[52:55], v[176:179], v[204:207], v[52:55]
	v_mfma_f32_16x16x32_bf16 v[48:51], v[196:199], v[204:207], v[48:51]
	v_mfma_f32_16x16x32_bf16 v[36:39], v[176:179], v[212:215], v[36:39]
	v_mfma_f32_16x16x32_bf16 v[32:35], v[196:199], v[212:215], v[32:35]
	v_mfma_f32_16x16x32_bf16 v[20:23], v[176:179], v[220:223], v[20:23]
	v_mfma_f32_16x16x32_bf16 v[16:19], v[196:199], v[220:223], v[16:19]
	v_mfma_f32_16x16x32_bf16 v[4:7], v[176:179], v[228:231], v[4:7]
	v_mfma_f32_16x16x32_bf16 v[0:3], v[196:199], v[228:231], v[0:3]
	v_mfma_f32_16x16x32_bf16 v[52:55], v[192:195], v[208:211], v[52:55]
	v_mfma_f32_16x16x32_bf16 v[48:51], v[200:203], v[208:211], v[48:51]
	v_mfma_f32_16x16x32_bf16 v[36:39], v[192:195], v[216:219], v[36:39]
	v_mfma_f32_16x16x32_bf16 v[32:35], v[200:203], v[216:219], v[32:35]
	v_mfma_f32_16x16x32_bf16 v[20:23], v[192:195], v[224:227], v[20:23]
	v_mfma_f32_16x16x32_bf16 v[16:19], v[200:203], v[224:227], v[16:19]
	v_mfma_f32_16x16x32_bf16 v[4:7], v[192:195], v[232:235], v[4:7]
	v_mfma_f32_16x16x32_bf16 v[0:3], v[200:203], v[232:235], v[0:3]
	s_barrier
; #define PG8_STAGE(bufoff, gbase, voff) do { _Pragma("unroll") for (int _i = 0; _i < 2; ++_i) \
;         __builtin_amdgcn_global_load_lds((const unsigned*)((const char*)(gbase) + (voff)[_i]), (LAS unsigned*)(lds + (bufoff) + ldsw + _i * 8192), 16, 0, 0); } while (0)
; #define PG8_LDA(dst, b, h) do { _Pragma("unroll") for (int m = 0; m < 4; ++m) _Pragma("unroll") for (int k = 0; k < 2; ++k) dst[m][k] = *(const LAS bf16x8*)(lds + PG8_SA(b, h) + aoff + m * 2048 + k * 1024); } while (0)
; #define PG8_LDB(dst, b, h) do { _Pragma("unroll") for (int n = 0; n < 2; ++n) _Pragma("unroll") for (int k = 0; k < 2; ++k) dst[n][k] = *(const LAS bf16x8*)(lds + PG8_SB(b, h) + boff + n * 2048 + k * 1024); } while (0)
; #define PG8_MMA(ai, bj, At, Bt) do { __builtin_amdgcn_s_setprio(1); _Pragma("unroll") for (int m = 0; m < 4; ++m) _Pragma("unroll") for (int n = 0; n < 2; ++n) _Pragma("unroll") for (int k = 0; k < 2; ++k) \
;         acc[ai][bj][m][n] = __builtin_amdgcn_mfma_f32_16x16x32_bf16(Bt[n][k], At[m][k], acc[ai][bj][m][n], 0, 0, 0); __builtin_amdgcn_s_setprio(0); } while (0)
; #define PG8_WAIT_V(n) asm volatile("s_waitcnt vmcnt(" #n ")" ::: "memory")
; #define PG8_WAIT_L(n) asm volatile("s_waitcnt lgkmcnt(" #n ")" ::: "memory")
; #define PG8_BAR __builtin_amdgcn_s_barrier()
; #define PG8_SCHED __builtin_amdgcn_sched_barrier(0)
; template <class Epi, class Map>
; __device__ __forceinline__ void gemm_phase(LAS unsigned char* lds, const Gemm g, const Sched<Map>& S, const Epi& E) {
;     ...
;             PG8_WAIT_V(8); PG8_WAIT_L(0); PG8_BAR; PG8_MMA(1, 0, At, B0); PG8_MMA(1, 1, At, B1); PG8_BAR; PG8_SCHED;
;             PG8_LDB(B0, 1, 0); PG8_LDB(B1, 1, 1); PG8_SCHED; PG8_LDA(At, 1, 0); PG8_STAGE(PG8_SA(0, 1), a2 + hstepA, voffA);
;             PG8_WAIT_V(8); PG8_WAIT_L(0); PG8_BAR; PG8_MMA(0, 0, At, B0); PG8_MMA(0, 1, At, B1); PG8_BAR; PG8_SCHED;
;             PG8_LDA(At, 1, 1); PG8_STAGE(PG8_SB(1, 0), b3, voffB); PG8_STAGE(PG8_SB(1, 1), b3 + hstepB, voffB); PG8_STAGE(PG8_SA(1, 0), a3, voffA);
;             PG8_WAIT_V(8); PG8_WAIT_L(0); PG8_BAR; PG8_MMA(1, 0, At, B0); PG8_MMA(1, 1, At, B1); PG8_BAR; PG8_SCHED;
	s_add_i32 s9, 0, 0x18000
	s_add_i32 s12, 0, 0x1c000
	v_add_u32_e32 v166, s9, v173
	v_add_u32_e32 v175, s12, v173
	ds_read_b128 v[124:127], v166
	ds_read_b128 v[132:135], v166 offset:1024
	ds_read_b128 v[162:165], v166 offset:2048
	ds_read_b128 v[166:169], v166 offset:3072
	ds_read_b128 v[176:179], v175
	ds_read_b128 v[192:195], v175 offset:1024
	ds_read_b128 v[196:199], v175 offset:2048
	ds_read_b128 v[200:203], v175 offset:3072
	s_add_u32 s10, s24, 0x80000
	s_addc_u32 s11, s25, 0
	s_mov_b32 m0, s31
	v_lshl_add_u64 v[240:241], s[10:11], 0, v[140:141]
	ds_read_b128 v[204:207], v174 offset:32768
	ds_read_b128 v[208:211], v174 offset:33792
	ds_read_b128 v[212:215], v174 offset:34816
	ds_read_b128 v[216:219], v174 offset:35840
	ds_read_b128 v[220:223], v174 offset:36864
	ds_read_b128 v[224:227], v174 offset:37888
	ds_read_b128 v[228:231], v174 offset:38912
	ds_read_b128 v[232:235], v174 offset:39936
	global_load_lds_dwordx4 v[240:241], off
	v_lshl_add_u64 v[240:241], s[10:11], 0, v[138:139]
	s_mov_b32 m0, s34
	s_nop 0
	global_load_lds_dwordx4 v[240:241], off
	s_waitcnt vmcnt(8)
	s_waitcnt lgkmcnt(0)
	s_barrier
	s_waitcnt lgkmcnt(0)
	v_mfma_f32_16x16x32_bf16 v[128:131], v[124:127], v[204:207], v[128:131]
	v_mfma_f32_16x16x32_bf16 v[120:123], v[162:165], v[204:207], v[120:123]
	v_mfma_f32_16x16x32_bf16 v[108:111], v[124:127], v[212:215], v[108:111]
	v_mfma_f32_16x16x32_bf16 v[104:107], v[162:165], v[212:215], v[104:107]
	v_mfma_f32_16x16x32_bf16 v[92:95], v[124:127], v[220:223], v[92:95]
	v_mfma_f32_16x16x32_bf16 v[88:91], v[162:165], v[220:223], v[88:91]
	v_mfma_f32_16x16x32_bf16 v[76:79], v[124:127], v[228:231], v[76:79]
	v_mfma_f32_16x16x32_bf16 v[72:75], v[162:165], v[228:231], v[72:75]
	v_mfma_f32_16x16x32_bf16 v[128:131], v[132:135], v[208:211], v[128:131]
	v_mfma_f32_16x16x32_bf16 v[120:123], v[166:169], v[208:211], v[120:123]
	v_mfma_f32_16x16x32_bf16 v[108:111], v[132:135], v[216:219], v[108:111]
	v_mfma_f32_16x16x32_bf16 v[104:107], v[166:169], v[216:219], v[104:107]
	v_mfma_f32_16x16x32_bf16 v[92:95], v[132:135], v[224:227], v[92:95]
	v_mfma_f32_16x16x32_bf16 v[88:91], v[166:169], v[224:227], v[88:91]
	v_mfma_f32_16x16x32_bf16 v[76:79], v[132:135], v[232:235], v[76:79]
	v_mfma_f32_16x16x32_bf16 v[72:75], v[166:169], v[232:235], v[72:75]
	v_mfma_f32_16x16x32_bf16 v[116:119], v[176:179], v[204:207], v[116:119]
	v_mfma_f32_16x16x32_bf16 v[112:115], v[196:199], v[204:207], v[112:115]
	v_mfma_f32_16x16x32_bf16 v[100:103], v[176:179], v[212:215], v[100:103]
	v_mfma_f32_16x16x32_bf16 v[96:99], v[196:199], v[212:215], v[96:99]
	v_mfma_f32_16x16x32_bf16 v[84:87], v[176:179], v[220:223], v[84:87]
	v_mfma_f32_16x16x32_bf16 v[80:83], v[196:199], v[220:223], v[80:83]
	v_mfma_f32_16x16x32_bf16 v[68:71], v[176:179], v[228:231], v[68:71]
	v_mfma_f32_16x16x32_bf16 v[64:67], v[196:199], v[228:231], v[64:67]
	v_mfma_f32_16x16x32_bf16 v[116:119], v[192:195], v[208:211], v[116:119]
	v_mfma_f32_16x16x32_bf16 v[112:115], v[200:203], v[208:211], v[112:115]
	v_mfma_f32_16x16x32_bf16 v[100:103], v[192:195], v[216:219], v[100:103]
	v_mfma_f32_16x16x32_bf16 v[96:99], v[200:203], v[216:219], v[96:99]
	v_mfma_f32_16x16x32_bf16 v[84:87], v[192:195], v[224:227], v[84:87]
	v_mfma_f32_16x16x32_bf16 v[80:83], v[200:203], v[224:227], v[80:83]
	v_mfma_f32_16x16x32_bf16 v[68:71], v[192:195], v[232:235], v[68:71]
	v_mfma_f32_16x16x32_bf16 v[64:67], v[200:203], v[232:235], v[64:67]
	s_barrier
	s_add_i32 s9, s9, s28
	v_lshl_add_u64 v[170:171], v[170:171], 0, s[82:83]
	s_mov_b32 m0, s9
	ds_read_b128 v[204:207], v174 offset:49152
	ds_read_b128 v[208:211], v174 offset:50176
	ds_read_b128 v[212:215], v174 offset:51200
	ds_read_b128 v[216:219], v174 offset:52224
	ds_read_b128 v[220:223], v174 offset:53248
	ds_read_b128 v[224:227], v174 offset:54272
	ds_read_b128 v[228:231], v174 offset:55296
	ds_read_b128 v[232:235], v174 offset:56320
	global_load_lds_dwordx4 v[170:171], off
	s_add_i32 m0, s9, 0x2000
	s_add_u32 s10, s20, 0x80080
	v_lshl_add_u64 v[170:171], v[180:181], 0, s[82:83]
	s_addc_u32 s11, s21, 0
	s_add_i32 s9, s12, s28
	global_load_lds_dwordx4 v[170:171], off
	v_lshl_add_u64 v[170:171], s[10:11], 0, v[144:145]
	s_mov_b32 m0, s9
	s_nop 0
	global_load_lds_dwordx4 v[170:171], off
	v_lshl_add_u64 v[170:171], s[10:11], 0, v[136:137]
	s_add_i32 m0, s9, 0x2000
	s_nop 0
	global_load_lds_dwordx4 v[170:171], off
	v_lshl_add_u64 v[170:171], v[236:237], 0, s[82:83]
	s_mov_b32 m0, s36
	s_nop 0
	global_load_lds_dwordx4 v[170:171], off
	v_lshl_add_u64 v[170:171], v[238:239], 0, s[82:83]
	s_mov_b32 m0, s37
	s_nop 0
	global_load_lds_dwordx4 v[170:171], off
	s_waitcnt vmcnt(8)
	s_waitcnt lgkmcnt(0)
	s_barrier
; #define PG8_STAGE(bufoff, gbase, voff) do { _Pragma("unroll") for (int _i = 0; _i < 2; ++_i) \
;         __builtin_amdgcn_global_load_lds((const unsigned*)((const char*)(gbase) + (voff)[_i]), (LAS unsigned*)(lds + (bufoff) + ldsw + _i * 8192), 16, 0, 0); } while (0)
; #define PG8_LDA(dst, b, h) do { _Pragma("unroll") for (int m = 0; m < 4; ++m) _Pragma("unroll") for (int k = 0; k < 2; ++k) dst[m][k] = *(const LAS bf16x8*)(lds + PG8_SA(b, h) + aoff + m * 2048 + k * 1024); } while (0)
; #define PG8_MMA(ai, bj, At, Bt) do { __builtin_amdgcn_s_setprio(1); _Pragma("unroll") for (int m = 0; m < 4; ++m) _Pragma("unroll") for (int n = 0; n < 2; ++n) _Pragma("unroll") for (int k = 0; k < 2; ++k) \
;         acc[ai][bj][m][n] = __builtin_amdgcn_mfma_f32_16x16x32_bf16(Bt[n][k], At[m][k], acc[ai][bj][m][n], 0, 0, 0); __builtin_amdgcn_s_setprio(0); } while (0)
; #define PG8_WAIT_V(n) asm volatile("s_waitcnt vmcnt(" #n ")" ::: "memory")
; #define PG8_WAIT_L(n) asm volatile("s_waitcnt lgkmcnt(" #n ")" ::: "memory")
; #define PG8_BAR __builtin_amdgcn_s_barrier()
; #define PG8_SCHED __builtin_amdgcn_sched_barrier(0)
; template <class Epi, class Map>
; __device__ __forceinline__ void gemm_phase(LAS unsigned char* lds, const Gemm g, const Sched<Map>& S, const Epi& E) {
;     ...
;             PG8_WAIT_V(8); PG8_WAIT_L(0); PG8_BAR; PG8_MMA(0, 0, At, B0); PG8_MMA(0, 1, At, B1); PG8_BAR; PG8_SCHED;
;             PG8_LDA(At, 1, 1); PG8_STAGE(PG8_SB(1, 0), b3, voffB); PG8_STAGE(PG8_SB(1, 1), b3 + hstepB, voffB); PG8_STAGE(PG8_SA(1, 0), a3, voffA);
;             PG8_WAIT_V(8); PG8_WAIT_L(0); PG8_BAR; PG8_MMA(1, 0, At, B0); PG8_MMA(1, 1, At, B1); PG8_BAR; PG8_SCHED;
;         }
;         if (wr == 0) PG8_BAR;
;         E(acc, cur, wr, wc, fr, fq);
;     __device__ __forceinline__ void operator()(const Acc& acc, const Unit& u, int wr, int wc, int fr, int fq) const {
;     ...
;         const int h = u.pn >> 1;
; #pragma unroll
;         for (int ai = 0; ai < 2; ++ai)
; #pragma unroll
;             for (int m = 0; m < 4; ++m) {
;                 const int row_in = ai * HALF + wr * 64 + m * 16 + fr, s = u.pm * BM + row_in;
;                 const f32x4 tq = ((const f32x4*)(stats + ((size_t)s * 8 + h) * 8))[fq];
;                 const size_t off = (size_t)s * RV + u.pn * BM + wc * 32 + 8 * fq;
;                 const u32x4 o0 = *(const u32x4*)(O + off), o1 = *(const u32x4*)(O + off + HALF);
	s_waitcnt lgkmcnt(0)
	v_mfma_f32_16x16x32_bf16 v[60:63], v[124:127], v[204:207], v[60:63]
	v_mfma_f32_16x16x32_bf16 v[56:59], v[162:165], v[204:207], v[56:59]
	v_mfma_f32_16x16x32_bf16 v[44:47], v[124:127], v[212:215], v[44:47]
	v_mfma_f32_16x16x32_bf16 v[40:43], v[162:165], v[212:215], v[40:43]
	v_mfma_f32_16x16x32_bf16 v[28:31], v[124:127], v[220:223], v[28:31]
	v_mfma_f32_16x16x32_bf16 v[24:27], v[162:165], v[220:223], v[24:27]
	v_mfma_f32_16x16x32_bf16 v[12:15], v[124:127], v[228:231], v[12:15]
	v_mfma_f32_16x16x32_bf16 v[8:11], v[162:165], v[228:231], v[8:11]
	v_mfma_f32_16x16x32_bf16 v[60:63], v[132:135], v[208:211], v[60:63]
	v_mfma_f32_16x16x32_bf16 v[56:59], v[166:169], v[208:211], v[56:59]
	v_mfma_f32_16x16x32_bf16 v[44:47], v[132:135], v[216:219], v[44:47]
	v_mfma_f32_16x16x32_bf16 v[40:43], v[166:169], v[216:219], v[40:43]
	v_mfma_f32_16x16x32_bf16 v[28:31], v[132:135], v[224:227], v[28:31]
	v_mfma_f32_16x16x32_bf16 v[24:27], v[166:169], v[224:227], v[24:27]
	v_mfma_f32_16x16x32_bf16 v[12:15], v[132:135], v[232:235], v[12:15]
	v_mfma_f32_16x16x32_bf16 v[8:11], v[166:169], v[232:235], v[8:11]
	v_mfma_f32_16x16x32_bf16 v[52:55], v[176:179], v[204:207], v[52:55]
	v_mfma_f32_16x16x32_bf16 v[48:51], v[196:199], v[204:207], v[48:51]
	v_mfma_f32_16x16x32_bf16 v[36:39], v[176:179], v[212:215], v[36:39]
	v_mfma_f32_16x16x32_bf16 v[32:35], v[196:199], v[212:215], v[32:35]
	v_mfma_f32_16x16x32_bf16 v[20:23], v[176:179], v[220:223], v[20:23]
	v_mfma_f32_16x16x32_bf16 v[16:19], v[196:199], v[220:223], v[16:19]
	v_mfma_f32_16x16x32_bf16 v[4:7], v[176:179], v[228:231], v[4:7]
	v_mfma_f32_16x16x32_bf16 v[0:3], v[196:199], v[228:231], v[0:3]
	v_mfma_f32_16x16x32_bf16 v[52:55], v[192:195], v[208:211], v[52:55]
	v_mfma_f32_16x16x32_bf16 v[48:51], v[200:203], v[208:211], v[48:51]
	v_mfma_f32_16x16x32_bf16 v[36:39], v[192:195], v[216:219], v[36:39]
	v_mfma_f32_16x16x32_bf16 v[32:35], v[200:203], v[216:219], v[32:35]
	v_mfma_f32_16x16x32_bf16 v[20:23], v[192:195], v[224:227], v[20:23]
	v_mfma_f32_16x16x32_bf16 v[16:19], v[200:203], v[224:227], v[16:19]
	v_mfma_f32_16x16x32_bf16 v[4:7], v[192:195], v[232:235], v[4:7]
	v_mfma_f32_16x16x32_bf16 v[0:3], v[200:203], v[232:235], v[0:3]
	s_barrier
	s_add_i32 s8, s8, 2
	s_add_u32 s18, s18, 0x100
	s_addc_u32 s19, s19, 0
	s_add_u32 s6, s6, 0x100
	s_addc_u32 s7, s7, 0
	s_cmp_gt_u32 s8, 29
	s_cbranch_scc0 .LBB0_880
	s_and_b64 vcc, exec, s[44:45]
	s_cbranch_vccz .LBB0_883
.LBB0_883:
	s_lshl_b32 s1, s1, 8
	v_mov_b32_e32 v125, v159
	v_mov_b32_e32 v124, v172
	s_ashr_i32 s2, s0, 1
	s_add_i32 s1, s1, s35
	s_lshl_b32 s0, s0, 8
	s_ashr_i32 s3, s2, 31
	v_add_u32_e32 v162, s1, v125
	s_ashr_i32 s1, s0, 31
	v_lshlrev_b32_e32 v126, 3, v124
	s_lshl_b64 s[48:49], s[2:3], 6
	v_ashrrev_i32_e32 v127, 31, v126
	s_or_b64 s[0:1], s[0:1], s[60:61]
	v_ashrrev_i32_e32 v163, 31, v162
	v_readlane_b32 s2, v248, 11
	v_lshl_add_u64 v[164:165], s[0:1], 0, v[126:127]
	v_lshlrev_b64 v[126:127], 9, v[162:163]
	v_readlane_b32 s3, v248, 12
	v_ashrrev_i32_e32 v125, 31, v124
	v_lshlrev_b64 v[166:167], 4, v[124:125]
	v_lshl_add_u64 v[126:127], s[2:3], 0, v[126:127]
	v_lshl_add_u64 v[126:127], v[126:127], 0, s[48:49]
	v_lshl_add_u64 v[124:125], v[126:127], 0, v[166:167]
	global_load_dwordx4 v[176:179], v[124:125], off
	v_lshlrev_b64 v[124:125], 12, v[162:163]
	v_lshl_add_u64 v[124:125], v[164:165], 0, v[124:125]
	v_readlane_b32 s4, v246, 17
	v_lshlrev_b64 v[170:171], 1, v[124:125]
	v_readlane_b32 s5, v246, 18
	s_mov_b32 s8, 0x3b000000
	v_readlane_b32 s6, v245, 8
	v_lshl_add_u64 v[124:125], s[4:5], 0, v[170:171]
	global_load_dwordx4 v[132:135], v[124:125], off
	s_nop 0
	global_load_dwordx4 v[124:127], v[124:125], off offset:256
	v_add_u32_e32 v216, 16, v162
	v_ashrrev_i32_e32 v217, 31, v216
	v_lshlrev_b64 v[218:219], 9, v[216:217]
	v_lshl_add_u64 v[218:219], s[2:3], 0, v[218:219]
	v_lshl_add_u64 v[218:219], v[218:219], 0, s[48:49]
	v_lshl_add_u64 v[218:219], v[218:219], 0, v[166:167]
	global_load_dwordx4 v[204:207], v[218:219], off
	v_lshlrev_b64 v[216:217], 12, v[216:217]
	v_lshl_add_u64 v[216:217], v[216:217], 0, v[164:165]
	v_lshlrev_b64 v[216:217], 1, v[216:217]
	v_lshl_add_u64 v[216:217], s[4:5], 0, v[216:217]
	global_load_dwordx4 v[208:211], v[216:217], off
	global_load_dwordx4 v[212:215], v[216:217], off offset:256
	v_readlane_b32 s7, v245, 9
	s_mov_b64 s[18:19], -1
	s_waitcnt vmcnt(3)
; __device__ __forceinline__ unsigned cvt_pk_bf16(float lo, float hi) { unsigned r; asm volatile("v_cvt_pk_bf16_f32 %0, %1, %2" : "=v"(r) : "v"(lo), "v"(hi)); return r; }
; __device__ __forceinline__ float bf_lo(unsigned w) { return __uint_as_float(w << 16); }
; __device__ __forceinline__ float bf_hi(unsigned w) { return __uint_as_float(w & 0xffff0000u); }
; __device__ __forceinline__ float silu_f(float v) { return v / (1.0f + __expf(-v)); }
;     __device__ __forceinline__ void operator()(const Acc& acc, const Unit& u, int wr, int wc, int fr, int fq) const {
;     ...
;                 const int row_in = ai * HALF + wr * 64 + m * 16 + fr, s = u.pm * BM + row_in;
;                 const f32x4 tq = ((const f32x4*)(stats + ((size_t)s * 8 + h) * 8))[fq];
;                 const size_t off = (size_t)s * RV + u.pn * BM + wc * 32 + 8 * fq;
;                 const u32x4 o0 = *(const u32x4*)(O + off), o1 = *(const u32x4*)(O + off + HALF);
;                 float s1 = tq[0] + tq[2], s2 = tq[1] + tq[3];
;                 { const auto r1 = __builtin_amdgcn_permlane16_swap(__float_as_uint(s1), __float_as_uint(s1), false, false); s1 = __uint_as_float(r1[0]) + __uint_as_float(r1[1]);
;                   const auto r2 = __builtin_amdgcn_permlane16_swap(__float_as_uint(s2), __float_as_uint(s2), false, false); s2 = __uint_as_float(r2[0]) + __uint_as_float(r2[1]);
;                   const auto r3 = __builtin_amdgcn_permlane32_swap(__float_as_uint(s1), __float_as_uint(s1), false, false); s1 = __uint_as_float(r3[0]) + __uint_as_float(r3[1]);
;                   const auto r4 = __builtin_amdgcn_permlane32_swap(__float_as_uint(s2), __float_as_uint(s2), false, false); s2 = __uint_as_float(r4[0]) + __uint_as_float(r4[1]); }
;                 const float mu = s1 * (1.0f / 512.0f), var = fmaxf(s2 * (1.0f / 512.0f) - mu * mu, 0.f), rstd = rsqrtf(var + EPS);
; #pragma unroll
;                 for (int bj = 0; bj < 2; ++bj) { const u32x4 ov = bj == 0 ? o0 : o1; const unsigned ow[4] = {ov.x, ov.y, ov.z, ov.w}; unsigned r[4];
; #pragma unroll
;                     for (int p = 0; p < 4; ++p) { const f32x4 v = acc[ai][bj][m][p >> 1]; const float g0 = silu_f(v[(p & 1) * 2]), g1 = silu_f(v[(p & 1) * 2 + 1]);
;                         r[p] = cvt_pk_bf16(g0 * ((bf_lo(ow[p]) - mu) * rstd), g1 * ((bf_hi(ow[p]) - mu) * rstd)); }
	v_add_f32_e32 v163, v176, v178
	v_mov_b32_e32 v169, v163
	v_add_f32_e32 v168, v177, v179
	s_nop 0
	v_permlane16_swap_b32_e32 v163, v169
	v_add_f32_e32 v169, v163, v169
	v_mov_b32_e32 v163, v168
	s_nop 1
	v_permlane16_swap_b32_e32 v168, v163
	v_add_f32_e32 v168, v168, v163
	v_mov_b32_e32 v177, v169
	v_mov_b32_e32 v176, v168
	s_nop 0
	v_permlane32_swap_b32_e32 v169, v177
	v_permlane32_swap_b32_e32 v168, v176
	v_pk_add_f32 v[168:169], v[168:169], v[176:177]
	s_nop 0
	v_pk_mul_f32 v[168:169], v[168:169], s[8:9] op_sel_hi:[1,0]
	s_nop 0
	v_fma_f32 v163, -v169, v169, v168
	v_max_f32_e32 v163, 0, v163
	v_add_f32_e32 v163, 0x358637bd, v163
	v_cmp_gt_f32_e32 vcc, s73, v163
	v_mul_f32_e32 v168, 0x4b800000, v163
	s_nop 0
	v_cndmask_b32_e32 v163, v163, v168, vcc
	v_rsq_f32_e32 v163, v163
	s_nop 0
	v_mul_f32_e32 v168, 0x45800000, v163
	v_cndmask_b32_e32 v163, v163, v168, vcc
	v_mul_f32_e32 v168, 0xbfb8aa3b, v128
	v_exp_f32_e32 v168, v168
	s_nop 0
	v_add_f32_e32 v168, 1.0, v168
	v_div_scale_f32 v175, s[0:1], v168, v168, v128
	v_rcp_f32_e32 v176, v175
	s_nop 0
	v_fma_f32 v177, -v175, v176, 1.0
	v_fmac_f32_e32 v176, v177, v176
	v_div_scale_f32 v177, vcc, v128, v168, v128
	v_mul_f32_e32 v178, v177, v176
	v_fma_f32 v179, -v175, v178, v177
	v_fmac_f32_e32 v178, v179, v176
	v_fma_f32 v175, -v175, v178, v177
	v_div_fmas_f32 v175, v175, v176, v178
	v_div_fixup_f32 v128, v175, v168, v128
	v_mul_f32_e32 v168, 0xbfb8aa3b, v129
	v_exp_f32_e32 v168, v168
	s_nop 0
	v_add_f32_e32 v168, 1.0, v168
	v_div_scale_f32 v175, s[0:1], v168, v168, v129
	v_rcp_f32_e32 v176, v175
	s_nop 0
	v_fma_f32 v177, -v175, v176, 1.0
	v_fmac_f32_e32 v176, v177, v176
	v_div_scale_f32 v177, vcc, v129, v168, v129
	v_mul_f32_e32 v178, v177, v176
	v_fma_f32 v179, -v175, v178, v177
	v_fmac_f32_e32 v178, v179, v176
	v_fma_f32 v175, -v175, v178, v177
	v_div_fmas_f32 v175, v175, v176, v178
	v_div_fixup_f32 v129, v175, v168, v129
	v_lshlrev_b32_e32 v168, 16, v132
	v_and_b32_e32 v132, 0xffff0000, v132
	v_sub_f32_e32 v168, v168, v169
	v_sub_f32_e32 v132, v132, v169
	v_mul_f32_e32 v168, v168, v163
	v_mul_f32_e32 v132, v132, v163
	v_mul_f32_e32 v128, v128, v168
	v_mul_f32_e32 v129, v129, v132
	v_cvt_pk_bf16_f32 v128, v128, v129
	v_mul_f32_e32 v129, 0xbfb8aa3b, v130
	v_exp_f32_e32 v129, v129
	s_nop 0
	v_add_f32_e32 v129, 1.0, v129
	v_div_scale_f32 v132, s[0:1], v129, v129, v130
	v_rcp_f32_e32 v168, v132
	s_nop 0
	v_fma_f32 v175, -v132, v168, 1.0
	v_fmac_f32_e32 v168, v175, v168
	v_div_scale_f32 v175, vcc, v130, v129, v130
	v_mul_f32_e32 v176, v175, v168
	v_fma_f32 v177, -v132, v176, v175
	v_fmac_f32_e32 v176, v177, v168
	v_fma_f32 v132, -v132, v176, v175
	v_div_fmas_f32 v132, v132, v168, v176
	v_div_fixup_f32 v129, v132, v129, v130
	v_mul_f32_e32 v130, 0xbfb8aa3b, v131
	v_exp_f32_e32 v130, v130
	s_nop 0
	v_add_f32_e32 v130, 1.0, v130
	v_div_scale_f32 v132, s[0:1], v130, v130, v131
	v_rcp_f32_e32 v168, v132
	s_nop 0
	v_fma_f32 v175, -v132, v168, 1.0
	v_fmac_f32_e32 v168, v175, v168
	v_div_scale_f32 v175, vcc, v131, v130, v131
	v_mul_f32_e32 v176, v175, v168
	v_fma_f32 v177, -v132, v176, v175
	v_fmac_f32_e32 v176, v177, v168
	v_fma_f32 v132, -v132, v176, v175
	v_div_fmas_f32 v132, v132, v168, v176
	v_div_fixup_f32 v130, v132, v130, v131
	v_lshlrev_b32_e32 v131, 16, v133
	v_sub_f32_e32 v131, v131, v169
	v_mul_f32_e32 v131, v131, v163
	v_mul_f32_e32 v129, v129, v131
	v_and_b32_e32 v131, 0xffff0000, v133
	v_sub_f32_e32 v131, v131, v169
	v_mul_f32_e32 v131, v131, v163
	v_mul_f32_e32 v130, v130, v131
	v_cvt_pk_bf16_f32 v129, v129, v130
	v_mul_f32_e32 v130, 0xbfb8aa3b, v120
	v_exp_f32_e32 v130, v130
	s_nop 0
	v_add_f32_e32 v130, 1.0, v130
	v_div_scale_f32 v131, s[0:1], v130, v130, v120
	v_rcp_f32_e32 v132, v131
	s_nop 0
	v_fma_f32 v133, -v131, v132, 1.0
	v_fmac_f32_e32 v132, v133, v132
	v_div_scale_f32 v133, vcc, v120, v130, v120
	v_mul_f32_e32 v168, v133, v132
	v_fma_f32 v175, -v131, v168, v133
	v_fmac_f32_e32 v168, v175, v132
	v_fma_f32 v131, -v131, v168, v133
	v_div_fmas_f32 v131, v131, v132, v168
	v_div_fixup_f32 v120, v131, v130, v120
	v_mul_f32_e32 v130, 0xbfb8aa3b, v121
	v_exp_f32_e32 v130, v130
	s_nop 0
	v_add_f32_e32 v130, 1.0, v130
	v_div_scale_f32 v131, s[0:1], v130, v130, v121
	v_rcp_f32_e32 v132, v131
	s_nop 0
	v_fma_f32 v133, -v131, v132, 1.0
	v_fmac_f32_e32 v132, v133, v132
	v_div_scale_f32 v133, vcc, v121, v130, v121
	v_mul_f32_e32 v168, v133, v132
	v_fma_f32 v175, -v131, v168, v133
	v_fmac_f32_e32 v168, v175, v132
	v_fma_f32 v131, -v131, v168, v133
	v_div_fmas_f32 v131, v131, v132, v168
	v_div_fixup_f32 v121, v131, v130, v121
	v_lshlrev_b32_e32 v130, 16, v134
	v_sub_f32_e32 v130, v130, v169
	v_mul_f32_e32 v130, v130, v163
	v_mul_f32_e32 v120, v120, v130
	v_and_b32_e32 v130, 0xffff0000, v134
	v_sub_f32_e32 v130, v130, v169
	v_mul_f32_e32 v130, v130, v163
	v_mul_f32_e32 v121, v121, v130
	v_cvt_pk_bf16_f32 v130, v120, v121
	v_mul_f32_e32 v120, 0xbfb8aa3b, v122
	v_exp_f32_e32 v120, v120
	s_nop 0
	v_add_f32_e32 v120, 1.0, v120
	v_div_scale_f32 v121, s[0:1], v120, v120, v122
	v_rcp_f32_e32 v131, v121
	s_nop 0
	v_fma_f32 v132, -v121, v131, 1.0
	v_fmac_f32_e32 v131, v132, v131
	v_div_scale_f32 v132, vcc, v122, v120, v122
	v_mul_f32_e32 v133, v132, v131
	v_fma_f32 v134, -v121, v133, v132
	v_fmac_f32_e32 v133, v134, v131
	v_fma_f32 v121, -v121, v133, v132
	v_div_fmas_f32 v121, v121, v131, v133
	v_div_fixup_f32 v120, v121, v120, v122
	v_mul_f32_e32 v121, 0xbfb8aa3b, v123
	v_exp_f32_e32 v121, v121
	s_nop 0
	v_add_f32_e32 v121, 1.0, v121
	v_div_scale_f32 v122, s[0:1], v121, v121, v123
	v_rcp_f32_e32 v131, v122
	s_nop 0
	v_fma_f32 v132, -v122, v131, 1.0
	v_fmac_f32_e32 v131, v132, v131
; __device__ __forceinline__ unsigned cvt_pk_bf16(float lo, float hi) { unsigned r; asm volatile("v_cvt_pk_bf16_f32 %0, %1, %2" : "=v"(r) : "v"(lo), "v"(hi)); return r; }
; __device__ __forceinline__ float bf_lo(unsigned w) { return __uint_as_float(w << 16); }
; __device__ __forceinline__ float bf_hi(unsigned w) { return __uint_as_float(w & 0xffff0000u); }
; __device__ __forceinline__ float silu_f(float v) { return v / (1.0f + __expf(-v)); }
;     __device__ __forceinline__ void operator()(const Acc& acc, const Unit& u, int wr, int wc, int fr, int fq) const {
;     ...
;                 for (int bj = 0; bj < 2; ++bj) { const u32x4 ov = bj == 0 ? o0 : o1; const unsigned ow[4] = {ov.x, ov.y, ov.z, ov.w}; unsigned r[4];
; #pragma unroll
;                     for (int p = 0; p < 4; ++p) { const f32x4 v = acc[ai][bj][m][p >> 1]; const float g0 = silu_f(v[(p & 1) * 2]), g1 = silu_f(v[(p & 1) * 2 + 1]);
;                         r[p] = cvt_pk_bf16(g0 * ((bf_lo(ow[p]) - mu) * rstd), g1 * ((bf_hi(ow[p]) - mu) * rstd)); }
;                     *(u32x4*)(U + off + bj * HALF) = (u32x4){r[0], r[1], r[2], r[3]}; }
	v_div_scale_f32 v132, vcc, v123, v121, v123
	v_mul_f32_e32 v133, v132, v131
	v_fma_f32 v134, -v122, v133, v132
	v_fmac_f32_e32 v133, v134, v131
	v_fma_f32 v122, -v122, v133, v132
	v_div_fmas_f32 v122, v122, v131, v133
	v_div_fixup_f32 v121, v122, v121, v123
	v_lshlrev_b32_e32 v122, 16, v135
	v_sub_f32_e32 v122, v122, v169
	v_mul_f32_e32 v122, v122, v163
	v_mul_f32_e32 v120, v120, v122
	v_and_b32_e32 v122, 0xffff0000, v135
	v_sub_f32_e32 v122, v122, v169
	v_mul_f32_e32 v122, v122, v163
	v_mul_f32_e32 v121, v121, v122
	v_mul_f32_e32 v122, 0xbfb8aa3b, v116
	v_exp_f32_e32 v122, v122
	v_cvt_pk_bf16_f32 v131, v120, v121
	v_lshl_add_u64 v[120:121], s[6:7], 0, v[170:171]
	global_store_dwordx4 v[120:121], v[128:131], off
	v_add_f32_e32 v122, 1.0, v122
	v_div_scale_f32 v123, s[0:1], v122, v122, v116
	v_rcp_f32_e32 v128, v123
	s_nop 0
	v_fma_f32 v129, -v123, v128, 1.0
	v_fmac_f32_e32 v128, v129, v128
	v_div_scale_f32 v129, vcc, v116, v122, v116
	v_mul_f32_e32 v130, v129, v128
	v_fma_f32 v131, -v123, v130, v129
	v_fmac_f32_e32 v130, v131, v128
	v_fma_f32 v123, -v123, v130, v129
	v_div_fmas_f32 v123, v123, v128, v130
	v_div_fixup_f32 v116, v123, v122, v116
	v_mul_f32_e32 v122, 0xbfb8aa3b, v117
	v_exp_f32_e32 v122, v122
	s_nop 0
	v_add_f32_e32 v122, 1.0, v122
	v_div_scale_f32 v123, s[0:1], v122, v122, v117
	v_rcp_f32_e32 v128, v123
	s_nop 0
	v_fma_f32 v129, -v123, v128, 1.0
	v_fmac_f32_e32 v128, v129, v128
	v_div_scale_f32 v129, vcc, v117, v122, v117
	v_mul_f32_e32 v130, v129, v128
	v_fma_f32 v131, -v123, v130, v129
	v_fmac_f32_e32 v130, v131, v128
	v_fma_f32 v123, -v123, v130, v129
	v_div_fmas_f32 v123, v123, v128, v130
	v_div_fixup_f32 v117, v123, v122, v117
	v_lshlrev_b32_e32 v122, 16, v124
	v_sub_f32_e32 v122, v122, v169
	v_mul_f32_e32 v122, v122, v163
	v_mul_f32_e32 v116, v116, v122
	v_and_b32_e32 v122, 0xffff0000, v124
	v_sub_f32_e32 v122, v122, v169
	v_mul_f32_e32 v122, v122, v163
	v_mul_f32_e32 v117, v117, v122
	v_cvt_pk_bf16_f32 v116, v116, v117
	v_mul_f32_e32 v117, 0xbfb8aa3b, v118
	v_exp_f32_e32 v117, v117
	s_nop 0
	v_add_f32_e32 v117, 1.0, v117
	v_div_scale_f32 v122, s[0:1], v117, v117, v118
	v_rcp_f32_e32 v123, v122
	s_nop 0
	v_fma_f32 v124, -v122, v123, 1.0
	v_fmac_f32_e32 v123, v124, v123
	v_div_scale_f32 v124, vcc, v118, v117, v118
	v_mul_f32_e32 v128, v124, v123
	v_fma_f32 v129, -v122, v128, v124
	v_fmac_f32_e32 v128, v129, v123
	v_fma_f32 v122, -v122, v128, v124
	v_div_fmas_f32 v122, v122, v123, v128
	v_div_fixup_f32 v117, v122, v117, v118
	v_mul_f32_e32 v118, 0xbfb8aa3b, v119
	v_exp_f32_e32 v118, v118
	s_nop 0
	v_add_f32_e32 v118, 1.0, v118
	v_div_scale_f32 v122, s[0:1], v118, v118, v119
	v_rcp_f32_e32 v123, v122
	s_nop 0
	v_fma_f32 v124, -v122, v123, 1.0
	v_fmac_f32_e32 v123, v124, v123
	v_div_scale_f32 v124, vcc, v119, v118, v119
	v_mul_f32_e32 v128, v124, v123
	v_fma_f32 v129, -v122, v128, v124
	v_fmac_f32_e32 v128, v129, v123
	v_fma_f32 v122, -v122, v128, v124
	v_div_fmas_f32 v122, v122, v123, v128
	v_div_fixup_f32 v118, v122, v118, v119
	v_lshlrev_b32_e32 v119, 16, v125
	v_sub_f32_e32 v119, v119, v169
	v_mul_f32_e32 v119, v119, v163
	v_mul_f32_e32 v117, v117, v119
	v_and_b32_e32 v119, 0xffff0000, v125
	v_sub_f32_e32 v119, v119, v169
	v_mul_f32_e32 v119, v119, v163
	v_mul_f32_e32 v118, v118, v119
	v_cvt_pk_bf16_f32 v117, v117, v118
	v_mul_f32_e32 v118, 0xbfb8aa3b, v112
	v_exp_f32_e32 v118, v118
	s_nop 0
	v_add_f32_e32 v118, 1.0, v118
	v_div_scale_f32 v119, s[0:1], v118, v118, v112
	v_rcp_f32_e32 v122, v119
	s_nop 0
	v_fma_f32 v123, -v119, v122, 1.0
	v_fmac_f32_e32 v122, v123, v122
	v_div_scale_f32 v123, vcc, v112, v118, v112
	v_mul_f32_e32 v124, v123, v122
	v_fma_f32 v125, -v119, v124, v123
	v_fmac_f32_e32 v124, v125, v122
	v_fma_f32 v119, -v119, v124, v123
	v_div_fmas_f32 v119, v119, v122, v124
	v_div_fixup_f32 v112, v119, v118, v112
	v_mul_f32_e32 v118, 0xbfb8aa3b, v113
	v_exp_f32_e32 v118, v118
	s_nop 0
	v_add_f32_e32 v118, 1.0, v118
	v_div_scale_f32 v119, s[0:1], v118, v118, v113
	v_rcp_f32_e32 v122, v119
	s_nop 0
	v_fma_f32 v123, -v119, v122, 1.0
	v_fmac_f32_e32 v122, v123, v122
	v_div_scale_f32 v123, vcc, v113, v118, v113
	v_mul_f32_e32 v124, v123, v122
	v_fma_f32 v125, -v119, v124, v123
	v_fmac_f32_e32 v124, v125, v122
	v_fma_f32 v119, -v119, v124, v123
	v_div_fmas_f32 v119, v119, v122, v124
	v_div_fixup_f32 v113, v119, v118, v113
	v_lshlrev_b32_e32 v118, 16, v126
	v_sub_f32_e32 v118, v118, v169
	v_mul_f32_e32 v118, v118, v163
	v_mul_f32_e32 v112, v112, v118
	v_and_b32_e32 v118, 0xffff0000, v126
	v_sub_f32_e32 v118, v118, v169
	v_mul_f32_e32 v118, v118, v163
	v_mul_f32_e32 v113, v113, v118
	v_cvt_pk_bf16_f32 v118, v112, v113
	v_mul_f32_e32 v112, 0xbfb8aa3b, v114
	v_exp_f32_e32 v112, v112
	s_nop 0
	v_add_f32_e32 v112, 1.0, v112
	v_div_scale_f32 v113, s[0:1], v112, v112, v114
	v_rcp_f32_e32 v119, v113
	s_nop 0
	v_fma_f32 v122, -v113, v119, 1.0
	v_fmac_f32_e32 v119, v122, v119
	v_div_scale_f32 v122, vcc, v114, v112, v114
	v_mul_f32_e32 v123, v122, v119
	v_fma_f32 v124, -v113, v123, v122
	v_fmac_f32_e32 v123, v124, v119
	v_fma_f32 v113, -v113, v123, v122
	v_div_fmas_f32 v113, v113, v119, v123
	v_div_fixup_f32 v112, v113, v112, v114
	v_mul_f32_e32 v113, 0xbfb8aa3b, v115
	v_exp_f32_e32 v113, v113
	s_nop 0
	v_add_f32_e32 v113, 1.0, v113
	v_div_scale_f32 v114, s[0:1], v113, v113, v115
	v_rcp_f32_e32 v119, v114
	s_nop 0
	v_fma_f32 v122, -v114, v119, 1.0
	v_fmac_f32_e32 v119, v122, v119
	v_div_scale_f32 v122, vcc, v115, v113, v115
	v_mul_f32_e32 v123, v122, v119
	v_fma_f32 v124, -v114, v123, v122
	v_fmac_f32_e32 v123, v124, v119
	v_fma_f32 v114, -v114, v123, v122
	v_div_fmas_f32 v114, v114, v119, v123
	v_div_fixup_f32 v113, v114, v113, v115
	v_lshlrev_b32_e32 v114, 16, v127
	v_sub_f32_e32 v114, v114, v169
	v_mul_f32_e32 v114, v114, v163
	v_mul_f32_e32 v112, v112, v114
	v_and_b32_e32 v114, 0xffff0000, v127
	v_sub_f32_e32 v114, v114, v169
	v_mul_f32_e32 v114, v114, v163
	v_mul_f32_e32 v113, v113, v114
	v_cvt_pk_bf16_f32 v119, v112, v113
	v_add_u32_e32 v112, 16, v162
	v_ashrrev_i32_e32 v113, 31, v112
	v_lshlrev_b64 v[114:115], 9, v[112:113]
	v_lshl_add_u64 v[114:115], s[2:3], 0, v[114:115]
	v_lshl_add_u64 v[114:115], v[114:115], 0, s[48:49]
	global_store_dwordx4 v[120:121], v[116:119], off offset:256
	v_lshl_add_u64 v[114:115], v[114:115], 0, v[166:167]
	v_lshlrev_b64 v[112:113], 12, v[112:113]
	v_lshl_add_u64 v[112:113], v[112:113], 0, v[164:165]
	v_lshlrev_b64 v[122:123], 1, v[112:113]
	v_lshl_add_u64 v[112:113], s[4:5], 0, v[122:123]
	s_waitcnt vmcnt(2)
; __device__ __forceinline__ unsigned cvt_pk_bf16(float lo, float hi) { unsigned r; asm volatile("v_cvt_pk_bf16_f32 %0, %1, %2" : "=v"(r) : "v"(lo), "v"(hi)); return r; }
; __device__ __forceinline__ float bf_lo(unsigned w) { return __uint_as_float(w << 16); }
; __device__ __forceinline__ float bf_hi(unsigned w) { return __uint_as_float(w & 0xffff0000u); }
; __device__ __forceinline__ float silu_f(float v) { return v / (1.0f + __expf(-v)); }
;     __device__ __forceinline__ void operator()(const Acc& acc, const Unit& u, int wr, int wc, int fr, int fq) const {
;     ...
;             for (int m = 0; m < 4; ++m) {
;                 const int row_in = ai * HALF + wr * 64 + m * 16 + fr, s = u.pm * BM + row_in;
;                 const f32x4 tq = ((const f32x4*)(stats + ((size_t)s * 8 + h) * 8))[fq];
;                 const size_t off = (size_t)s * RV + u.pn * BM + wc * 32 + 8 * fq;
;                 const u32x4 o0 = *(const u32x4*)(O + off), o1 = *(const u32x4*)(O + off + HALF);
;                 float s1 = tq[0] + tq[2], s2 = tq[1] + tq[3];
;                 { const auto r1 = __builtin_amdgcn_permlane16_swap(__float_as_uint(s1), __float_as_uint(s1), false, false); s1 = __uint_as_float(r1[0]) + __uint_as_float(r1[1]);
;                   const auto r2 = __builtin_amdgcn_permlane16_swap(__float_as_uint(s2), __float_as_uint(s2), false, false); s2 = __uint_as_float(r2[0]) + __uint_as_float(r2[1]);
;                   const auto r3 = __builtin_amdgcn_permlane32_swap(__float_as_uint(s1), __float_as_uint(s1), false, false); s1 = __uint_as_float(r3[0]) + __uint_as_float(r3[1]);
;                   const auto r4 = __builtin_amdgcn_permlane32_swap(__float_as_uint(s2), __float_as_uint(s2), false, false); s2 = __uint_as_float(r4[0]) + __uint_as_float(r4[1]); }
;                 const float mu = s1 * (1.0f / 512.0f), var = fmaxf(s2 * (1.0f / 512.0f) - mu * mu, 0.f), rstd = rsqrtf(var + EPS);
; #pragma unroll
;                 for (int bj = 0; bj < 2; ++bj) { const u32x4 ov = bj == 0 ? o0 : o1; const unsigned ow[4] = {ov.x, ov.y, ov.z, ov.w}; unsigned r[4];
; #pragma unroll
;                     for (int p = 0; p < 4; ++p) { const f32x4 v = acc[ai][bj][m][p >> 1]; const float g0 = silu_f(v[(p & 1) * 2]), g1 = silu_f(v[(p & 1) * 2 + 1]);
;                         r[p] = cvt_pk_bf16(g0 * ((bf_lo(ow[p]) - mu) * rstd), g1 * ((bf_hi(ow[p]) - mu) * rstd)); }
	v_mov_b32_e32 v124, v204
	v_mov_b32_e32 v125, v205
	v_mov_b32_e32 v126, v206
	v_mov_b32_e32 v127, v207
	v_mov_b32_e32 v116, v208
	v_mov_b32_e32 v117, v209
	v_mov_b32_e32 v118, v210
	v_mov_b32_e32 v119, v211
	v_mov_b32_e32 v112, v212
	v_mov_b32_e32 v113, v213
	v_mov_b32_e32 v114, v214
	v_mov_b32_e32 v115, v215
	v_add_u32_e32 v216, 32, v162
	v_ashrrev_i32_e32 v217, 31, v216
	v_lshlrev_b64 v[218:219], 9, v[216:217]
	v_lshl_add_u64 v[218:219], s[2:3], 0, v[218:219]
	v_lshl_add_u64 v[218:219], v[218:219], 0, s[48:49]
	v_lshl_add_u64 v[218:219], v[218:219], 0, v[166:167]
	global_load_dwordx4 v[192:195], v[218:219], off
	v_lshlrev_b64 v[216:217], 12, v[216:217]
	v_lshl_add_u64 v[216:217], v[216:217], 0, v[164:165]
	v_lshlrev_b64 v[216:217], 1, v[216:217]
	v_lshl_add_u64 v[216:217], s[4:5], 0, v[216:217]
	global_load_dwordx4 v[196:199], v[216:217], off
	global_load_dwordx4 v[200:203], v[216:217], off offset:256
	v_add_f32_e32 v120, v124, v126
	v_mov_b32_e32 v121, v120
	v_add_f32_e32 v124, v125, v127
	s_nop 0
	v_permlane16_swap_b32_e32 v120, v121
	v_add_f32_e32 v121, v120, v121
	v_mov_b32_e32 v120, v124
	s_nop 1
	v_permlane16_swap_b32_e32 v124, v120
	v_add_f32_e32 v120, v124, v120
	v_mov_b32_e32 v125, v121
	v_mov_b32_e32 v124, v120
	s_nop 0
	v_permlane32_swap_b32_e32 v121, v125
	v_permlane32_swap_b32_e32 v120, v124
	v_pk_add_f32 v[120:121], v[120:121], v[124:125]
	s_nop 0
	v_pk_mul_f32 v[120:121], v[120:121], s[8:9] op_sel_hi:[1,0]
	s_nop 0
	v_fma_f32 v120, -v121, v121, v120
	v_max_f32_e32 v120, 0, v120
	v_add_f32_e32 v120, 0x358637bd, v120
	v_cmp_gt_f32_e32 vcc, s73, v120
	v_mul_f32_e32 v124, 0x4b800000, v120
	s_nop 0
	v_cndmask_b32_e32 v120, v120, v124, vcc
	v_rsq_f32_e32 v120, v120
	s_nop 0
	v_mul_f32_e32 v124, 0x45800000, v120
	v_cndmask_b32_e32 v120, v120, v124, vcc
	v_mul_f32_e32 v124, 0xbfb8aa3b, v108
	v_exp_f32_e32 v124, v124
	s_nop 0
	v_add_f32_e32 v124, 1.0, v124
	v_div_scale_f32 v125, s[0:1], v124, v124, v108
	v_rcp_f32_e32 v126, v125
	s_nop 0
	v_fma_f32 v127, -v125, v126, 1.0
	v_fmac_f32_e32 v126, v127, v126
	v_div_scale_f32 v127, vcc, v108, v124, v108
	v_mul_f32_e32 v128, v127, v126
	v_fma_f32 v129, -v125, v128, v127
	v_fmac_f32_e32 v128, v129, v126
	v_fma_f32 v125, -v125, v128, v127
	v_div_fmas_f32 v125, v125, v126, v128
	v_div_fixup_f32 v108, v125, v124, v108
	v_mul_f32_e32 v124, 0xbfb8aa3b, v109
	v_exp_f32_e32 v124, v124
	s_nop 0
	v_add_f32_e32 v124, 1.0, v124
	v_div_scale_f32 v125, s[0:1], v124, v124, v109
	v_rcp_f32_e32 v126, v125
	s_nop 0
	v_fma_f32 v127, -v125, v126, 1.0
	v_fmac_f32_e32 v126, v127, v126
	v_div_scale_f32 v127, vcc, v109, v124, v109
	v_mul_f32_e32 v128, v127, v126
	v_fma_f32 v129, -v125, v128, v127
	v_fmac_f32_e32 v128, v129, v126
	v_fma_f32 v125, -v125, v128, v127
	v_div_fmas_f32 v125, v125, v126, v128
	v_div_fixup_f32 v109, v125, v124, v109
	v_lshlrev_b32_e32 v124, 16, v116
	v_and_b32_e32 v116, 0xffff0000, v116
	v_sub_f32_e32 v124, v124, v121
	v_sub_f32_e32 v116, v116, v121
	v_mul_f32_e32 v124, v124, v120
	v_mul_f32_e32 v116, v116, v120
	v_mul_f32_e32 v108, v108, v124
	v_mul_f32_e32 v109, v109, v116
	v_cvt_pk_bf16_f32 v108, v108, v109
	v_mul_f32_e32 v109, 0xbfb8aa3b, v110
	v_exp_f32_e32 v109, v109
	s_nop 0
	v_add_f32_e32 v109, 1.0, v109
	v_div_scale_f32 v116, s[0:1], v109, v109, v110
	v_rcp_f32_e32 v124, v116
	s_nop 0
	v_fma_f32 v125, -v116, v124, 1.0
	v_fmac_f32_e32 v124, v125, v124
	v_div_scale_f32 v125, vcc, v110, v109, v110
	v_mul_f32_e32 v126, v125, v124
	v_fma_f32 v127, -v116, v126, v125
	v_fmac_f32_e32 v126, v127, v124
	v_fma_f32 v116, -v116, v126, v125
	v_div_fmas_f32 v116, v116, v124, v126
	v_div_fixup_f32 v109, v116, v109, v110
	v_mul_f32_e32 v110, 0xbfb8aa3b, v111
	v_exp_f32_e32 v110, v110
	s_nop 0
	v_add_f32_e32 v110, 1.0, v110
	v_div_scale_f32 v116, s[0:1], v110, v110, v111
	v_rcp_f32_e32 v124, v116
	s_nop 0
	v_fma_f32 v125, -v116, v124, 1.0
	v_fmac_f32_e32 v124, v125, v124
	v_div_scale_f32 v125, vcc, v111, v110, v111
	v_mul_f32_e32 v126, v125, v124
	v_fma_f32 v127, -v116, v126, v125
	v_fmac_f32_e32 v126, v127, v124
	v_fma_f32 v116, -v116, v126, v125
	v_div_fmas_f32 v116, v116, v124, v126
	v_div_fixup_f32 v110, v116, v110, v111
	v_lshlrev_b32_e32 v111, 16, v117
	v_sub_f32_e32 v111, v111, v121
	v_mul_f32_e32 v111, v111, v120
	v_mul_f32_e32 v109, v109, v111
	v_and_b32_e32 v111, 0xffff0000, v117
	v_sub_f32_e32 v111, v111, v121
	v_mul_f32_e32 v111, v111, v120
	v_mul_f32_e32 v110, v110, v111
	v_cvt_pk_bf16_f32 v109, v109, v110
	v_mul_f32_e32 v110, 0xbfb8aa3b, v104
	v_exp_f32_e32 v110, v110
	s_nop 0
	v_add_f32_e32 v110, 1.0, v110
	v_div_scale_f32 v111, s[0:1], v110, v110, v104
	v_rcp_f32_e32 v116, v111
	s_nop 0
	v_fma_f32 v117, -v111, v116, 1.0
	v_fmac_f32_e32 v116, v117, v116
	v_div_scale_f32 v117, vcc, v104, v110, v104
	v_mul_f32_e32 v124, v117, v116
	v_fma_f32 v125, -v111, v124, v117
	v_fmac_f32_e32 v124, v125, v116
	v_fma_f32 v111, -v111, v124, v117
	v_div_fmas_f32 v111, v111, v116, v124
	v_div_fixup_f32 v104, v111, v110, v104
	v_mul_f32_e32 v110, 0xbfb8aa3b, v105
	v_exp_f32_e32 v110, v110
	s_nop 0
	v_add_f32_e32 v110, 1.0, v110
	v_div_scale_f32 v111, s[0:1], v110, v110, v105
	v_rcp_f32_e32 v116, v111
	s_nop 0
	v_fma_f32 v117, -v111, v116, 1.0
	v_fmac_f32_e32 v116, v117, v116
	v_div_scale_f32 v117, vcc, v105, v110, v105
	v_mul_f32_e32 v124, v117, v116
	v_fma_f32 v125, -v111, v124, v117
	v_fmac_f32_e32 v124, v125, v116
	v_fma_f32 v111, -v111, v124, v117
	v_div_fmas_f32 v111, v111, v116, v124
	v_div_fixup_f32 v105, v111, v110, v105
	v_lshlrev_b32_e32 v110, 16, v118
	v_sub_f32_e32 v110, v110, v121
	v_mul_f32_e32 v110, v110, v120
	v_mul_f32_e32 v104, v104, v110
	v_and_b32_e32 v110, 0xffff0000, v118
; __device__ __forceinline__ unsigned cvt_pk_bf16(float lo, float hi) { unsigned r; asm volatile("v_cvt_pk_bf16_f32 %0, %1, %2" : "=v"(r) : "v"(lo), "v"(hi)); return r; }
; __device__ __forceinline__ float bf_lo(unsigned w) { return __uint_as_float(w << 16); }
; __device__ __forceinline__ float bf_hi(unsigned w) { return __uint_as_float(w & 0xffff0000u); }
; __device__ __forceinline__ float silu_f(float v) { return v / (1.0f + __expf(-v)); }
;     __device__ __forceinline__ void operator()(const Acc& acc, const Unit& u, int wr, int wc, int fr, int fq) const {
;     ...
;                 for (int bj = 0; bj < 2; ++bj) { const u32x4 ov = bj == 0 ? o0 : o1; const unsigned ow[4] = {ov.x, ov.y, ov.z, ov.w}; unsigned r[4];
; #pragma unroll
;                     for (int p = 0; p < 4; ++p) { const f32x4 v = acc[ai][bj][m][p >> 1]; const float g0 = silu_f(v[(p & 1) * 2]), g1 = silu_f(v[(p & 1) * 2 + 1]);
;                         r[p] = cvt_pk_bf16(g0 * ((bf_lo(ow[p]) - mu) * rstd), g1 * ((bf_hi(ow[p]) - mu) * rstd)); }
;                     *(u32x4*)(U + off + bj * HALF) = (u32x4){r[0], r[1], r[2], r[3]}; }
	v_sub_f32_e32 v110, v110, v121
	v_mul_f32_e32 v110, v110, v120
	v_mul_f32_e32 v105, v105, v110
	v_cvt_pk_bf16_f32 v110, v104, v105
	v_mul_f32_e32 v104, 0xbfb8aa3b, v106
	v_exp_f32_e32 v104, v104
	s_nop 0
	v_add_f32_e32 v104, 1.0, v104
	v_div_scale_f32 v105, s[0:1], v104, v104, v106
	v_rcp_f32_e32 v111, v105
	s_nop 0
	v_fma_f32 v116, -v105, v111, 1.0
	v_fmac_f32_e32 v111, v116, v111
	v_div_scale_f32 v116, vcc, v106, v104, v106
	v_mul_f32_e32 v117, v116, v111
	v_fma_f32 v118, -v105, v117, v116
	v_fmac_f32_e32 v117, v118, v111
	v_fma_f32 v105, -v105, v117, v116
	v_div_fmas_f32 v105, v105, v111, v117
	v_div_fixup_f32 v104, v105, v104, v106
	v_mul_f32_e32 v105, 0xbfb8aa3b, v107
	v_exp_f32_e32 v105, v105
	s_nop 0
	v_add_f32_e32 v105, 1.0, v105
	v_div_scale_f32 v106, s[0:1], v105, v105, v107
	v_rcp_f32_e32 v111, v106
	s_nop 0
	v_fma_f32 v116, -v106, v111, 1.0
	v_fmac_f32_e32 v111, v116, v111
	v_div_scale_f32 v116, vcc, v107, v105, v107
	v_mul_f32_e32 v117, v116, v111
	v_fma_f32 v118, -v106, v117, v116
	v_fmac_f32_e32 v117, v118, v111
	v_fma_f32 v106, -v106, v117, v116
	v_div_fmas_f32 v106, v106, v111, v117
	v_div_fixup_f32 v105, v106, v105, v107
	v_lshlrev_b32_e32 v106, 16, v119
	v_sub_f32_e32 v106, v106, v121
	v_mul_f32_e32 v106, v106, v120
	v_mul_f32_e32 v104, v104, v106
	v_and_b32_e32 v106, 0xffff0000, v119
	v_sub_f32_e32 v106, v106, v121
	v_mul_f32_e32 v106, v106, v120
	v_mul_f32_e32 v105, v105, v106
	v_mul_f32_e32 v106, 0xbfb8aa3b, v100
	v_exp_f32_e32 v106, v106
	v_cvt_pk_bf16_f32 v111, v104, v105
	v_lshl_add_u64 v[104:105], s[6:7], 0, v[122:123]
	global_store_dwordx4 v[104:105], v[108:111], off
	v_add_f32_e32 v106, 1.0, v106
	v_div_scale_f32 v107, s[0:1], v106, v106, v100
	v_rcp_f32_e32 v108, v107
	s_nop 0
	v_fma_f32 v109, -v107, v108, 1.0
	v_fmac_f32_e32 v108, v109, v108
	v_div_scale_f32 v109, vcc, v100, v106, v100
	v_mul_f32_e32 v110, v109, v108
	v_fma_f32 v111, -v107, v110, v109
	v_fmac_f32_e32 v110, v111, v108
	v_fma_f32 v107, -v107, v110, v109
	v_div_fmas_f32 v107, v107, v108, v110
	v_div_fixup_f32 v100, v107, v106, v100
	v_mul_f32_e32 v106, 0xbfb8aa3b, v101
	v_exp_f32_e32 v106, v106
	s_nop 0
	v_add_f32_e32 v106, 1.0, v106
	v_div_scale_f32 v107, s[0:1], v106, v106, v101
	v_rcp_f32_e32 v108, v107
	s_nop 0
	v_fma_f32 v109, -v107, v108, 1.0
	v_fmac_f32_e32 v108, v109, v108
	v_div_scale_f32 v109, vcc, v101, v106, v101
	v_mul_f32_e32 v110, v109, v108
	v_fma_f32 v111, -v107, v110, v109
	v_fmac_f32_e32 v110, v111, v108
	v_fma_f32 v107, -v107, v110, v109
	v_div_fmas_f32 v107, v107, v108, v110
	v_div_fixup_f32 v101, v107, v106, v101
	v_lshlrev_b32_e32 v106, 16, v112
	v_sub_f32_e32 v106, v106, v121
	v_mul_f32_e32 v106, v106, v120
	v_mul_f32_e32 v100, v100, v106
	v_and_b32_e32 v106, 0xffff0000, v112
	v_sub_f32_e32 v106, v106, v121
	v_mul_f32_e32 v106, v106, v120
	v_mul_f32_e32 v101, v101, v106
	v_cvt_pk_bf16_f32 v100, v100, v101
	v_mul_f32_e32 v101, 0xbfb8aa3b, v102
	v_exp_f32_e32 v101, v101
	s_nop 0
	v_add_f32_e32 v101, 1.0, v101
	v_div_scale_f32 v106, s[0:1], v101, v101, v102
	v_rcp_f32_e32 v107, v106
	s_nop 0
	v_fma_f32 v108, -v106, v107, 1.0
	v_fmac_f32_e32 v107, v108, v107
	v_div_scale_f32 v108, vcc, v102, v101, v102
	v_mul_f32_e32 v109, v108, v107
	v_fma_f32 v110, -v106, v109, v108
	v_fmac_f32_e32 v109, v110, v107
	v_fma_f32 v106, -v106, v109, v108
	v_div_fmas_f32 v106, v106, v107, v109
	v_div_fixup_f32 v101, v106, v101, v102
	v_mul_f32_e32 v102, 0xbfb8aa3b, v103
	v_exp_f32_e32 v102, v102
	s_nop 0
	v_add_f32_e32 v102, 1.0, v102
	v_div_scale_f32 v106, s[0:1], v102, v102, v103
	v_rcp_f32_e32 v107, v106
	s_nop 0
	v_fma_f32 v108, -v106, v107, 1.0
	v_fmac_f32_e32 v107, v108, v107
	v_div_scale_f32 v108, vcc, v103, v102, v103
	v_mul_f32_e32 v109, v108, v107
	v_fma_f32 v110, -v106, v109, v108
	v_fmac_f32_e32 v109, v110, v107
	v_fma_f32 v106, -v106, v109, v108
	v_div_fmas_f32 v106, v106, v107, v109
	v_div_fixup_f32 v102, v106, v102, v103
	v_lshlrev_b32_e32 v103, 16, v113
	v_sub_f32_e32 v103, v103, v121
	v_mul_f32_e32 v103, v103, v120
	v_mul_f32_e32 v101, v101, v103
	v_and_b32_e32 v103, 0xffff0000, v113
	v_sub_f32_e32 v103, v103, v121
	v_mul_f32_e32 v103, v103, v120
	v_mul_f32_e32 v102, v102, v103
	v_cvt_pk_bf16_f32 v101, v101, v102
	v_mul_f32_e32 v102, 0xbfb8aa3b, v96
	v_exp_f32_e32 v102, v102
	s_nop 0
	v_add_f32_e32 v102, 1.0, v102
	v_div_scale_f32 v103, s[0:1], v102, v102, v96
	v_rcp_f32_e32 v106, v103
	s_nop 0
	v_fma_f32 v107, -v103, v106, 1.0
	v_fmac_f32_e32 v106, v107, v106
	v_div_scale_f32 v107, vcc, v96, v102, v96
	v_mul_f32_e32 v108, v107, v106
	v_fma_f32 v109, -v103, v108, v107
	v_fmac_f32_e32 v108, v109, v106
	v_fma_f32 v103, -v103, v108, v107
	v_div_fmas_f32 v103, v103, v106, v108
	v_div_fixup_f32 v96, v103, v102, v96
	v_mul_f32_e32 v102, 0xbfb8aa3b, v97
	v_exp_f32_e32 v102, v102
	s_nop 0
	v_add_f32_e32 v102, 1.0, v102
	v_div_scale_f32 v103, s[0:1], v102, v102, v97
	v_rcp_f32_e32 v106, v103
	s_nop 0
	v_fma_f32 v107, -v103, v106, 1.0
	v_fmac_f32_e32 v106, v107, v106
	v_div_scale_f32 v107, vcc, v97, v102, v97
	v_mul_f32_e32 v108, v107, v106
	v_fma_f32 v109, -v103, v108, v107
	v_fmac_f32_e32 v108, v109, v106
	v_fma_f32 v103, -v103, v108, v107
	v_div_fmas_f32 v103, v103, v106, v108
	v_div_fixup_f32 v97, v103, v102, v97
	v_lshlrev_b32_e32 v102, 16, v114
	v_sub_f32_e32 v102, v102, v121
	v_mul_f32_e32 v102, v102, v120
	v_mul_f32_e32 v96, v96, v102
	v_and_b32_e32 v102, 0xffff0000, v114
	v_sub_f32_e32 v102, v102, v121
	v_mul_f32_e32 v102, v102, v120
	v_mul_f32_e32 v97, v97, v102
	v_cvt_pk_bf16_f32 v102, v96, v97
	v_mul_f32_e32 v96, 0xbfb8aa3b, v98
	v_exp_f32_e32 v96, v96
	s_nop 0
	v_add_f32_e32 v96, 1.0, v96
	v_div_scale_f32 v97, s[0:1], v96, v96, v98
; __device__ __forceinline__ unsigned cvt_pk_bf16(float lo, float hi) { unsigned r; asm volatile("v_cvt_pk_bf16_f32 %0, %1, %2" : "=v"(r) : "v"(lo), "v"(hi)); return r; }
; template <class Epi, class Map>
; __device__ __forceinline__ void gemm_phase(LAS unsigned char* lds, const Gemm g, const Sched<Map>& S, const Epi& E) {
;     ...
;         if (wr == 0) PG8_BAR;
;     __device__ __forceinline__ void operator()(const Acc& acc, const Unit& u, int wr, int wc, int fr, int fq) const {
;     ...
;             for (int m = 0; m < 4; ++m) {
;                 const int row_in = ai * HALF + wr * 64 + m * 16 + fr, s = u.pm * BM + row_in;
;                 const f32x4 tq = ((const f32x4*)(stats + ((size_t)s * 8 + h) * 8))[fq];
;                 const size_t off = (size_t)s * RV + u.pn * BM + wc * 32 + 8 * fq;
;                 const u32x4 o0 = *(const u32x4*)(O + off), o1 = *(const u32x4*)(O + off + HALF);
;                 float s1 = tq[0] + tq[2], s2 = tq[1] + tq[3];
;                 { const auto r1 = __builtin_amdgcn_permlane16_swap(__float_as_uint(s1), __float_as_uint(s1), false, false); s1 = __uint_as_float(r1[0]) + __uint_as_float(r1[1]);
;                   const auto r2 = __builtin_amdgcn_permlane16_swap(__float_as_uint(s2), __float_as_uint(s2), false, false); s2 = __uint_as_float(r2[0]) + __uint_as_float(r2[1]);
;                   const auto r3 = __builtin_amdgcn_permlane32_swap(__float_as_uint(s1), __float_as_uint(s1), false, false); s1 = __uint_as_float(r3[0]) + __uint_as_float(r3[1]);
;                   const auto r4 = __builtin_amdgcn_permlane32_swap(__float_as_uint(s2), __float_as_uint(s2), false, false); s2 = __uint_as_float(r4[0]) + __uint_as_float(r4[1]); }
;                 const float mu = s1 * (1.0f / 512.0f), var = fmaxf(s2 * (1.0f / 512.0f) - mu * mu, 0.f), rstd = rsqrtf(var + EPS);
; #pragma unroll
;                 for (int bj = 0; bj < 2; ++bj) { const u32x4 ov = bj == 0 ? o0 : o1; const unsigned ow[4] = {ov.x, ov.y, ov.z, ov.w}; unsigned r[4];
; #pragma unroll
;                     for (int p = 0; p < 4; ++p) { const f32x4 v = acc[ai][bj][m][p >> 1]; const float g0 = silu_f(v[(p & 1) * 2]), g1 = silu_f(v[(p & 1) * 2 + 1]);
;                         r[p] = cvt_pk_bf16(g0 * ((bf_lo(ow[p]) - mu) * rstd), g1 * ((bf_hi(ow[p]) - mu) * rstd)); }
;                     *(u32x4*)(U + off + bj * HALF) = (u32x4){r[0], r[1], r[2], r[3]}; }
	v_rcp_f32_e32 v103, v97
	s_nop 0
	v_fma_f32 v106, -v97, v103, 1.0
	v_fmac_f32_e32 v103, v106, v103
	v_div_scale_f32 v106, vcc, v98, v96, v98
	v_mul_f32_e32 v107, v106, v103
	v_fma_f32 v108, -v97, v107, v106
	v_fmac_f32_e32 v107, v108, v103
	v_fma_f32 v97, -v97, v107, v106
	v_div_fmas_f32 v97, v97, v103, v107
	v_div_fixup_f32 v96, v97, v96, v98
	v_mul_f32_e32 v97, 0xbfb8aa3b, v99
	v_exp_f32_e32 v97, v97
	s_nop 0
	v_add_f32_e32 v97, 1.0, v97
	v_div_scale_f32 v98, s[0:1], v97, v97, v99
	v_rcp_f32_e32 v103, v98
	s_nop 0
	v_fma_f32 v106, -v98, v103, 1.0
	v_fmac_f32_e32 v103, v106, v103
	v_div_scale_f32 v106, vcc, v99, v97, v99
	v_mul_f32_e32 v107, v106, v103
	v_fma_f32 v108, -v98, v107, v106
	v_fmac_f32_e32 v107, v108, v103
	v_fma_f32 v98, -v98, v107, v106
	v_div_fmas_f32 v98, v98, v103, v107
	v_div_fixup_f32 v97, v98, v97, v99
	v_lshlrev_b32_e32 v98, 16, v115
	v_sub_f32_e32 v98, v98, v121
	v_mul_f32_e32 v98, v98, v120
	v_mul_f32_e32 v96, v96, v98
	v_and_b32_e32 v98, 0xffff0000, v115
	v_sub_f32_e32 v98, v98, v121
	v_mul_f32_e32 v98, v98, v120
	v_mul_f32_e32 v97, v97, v98
	v_cvt_pk_bf16_f32 v103, v96, v97
	v_add_u32_e32 v96, 32, v162
	v_ashrrev_i32_e32 v97, 31, v96
	v_lshlrev_b64 v[98:99], 9, v[96:97]
	v_lshl_add_u64 v[98:99], s[2:3], 0, v[98:99]
	v_lshl_add_u64 v[98:99], v[98:99], 0, s[48:49]
	global_store_dwordx4 v[104:105], v[100:103], off offset:256
	s_cmp_lg_u64 s[44:45], 0
	s_cbranch_scc0 .Llate_align_8
	s_barrier
.Llate_align_8:
	v_lshl_add_u64 v[98:99], v[98:99], 0, v[166:167]
	v_lshlrev_b64 v[96:97], 12, v[96:97]
	v_lshl_add_u64 v[96:97], v[96:97], 0, v[164:165]
	v_lshlrev_b64 v[106:107], 1, v[96:97]
	v_lshl_add_u64 v[96:97], s[4:5], 0, v[106:107]
	s_waitcnt vmcnt(2)
	v_mov_b32_e32 v108, v192
	v_mov_b32_e32 v109, v193
	v_mov_b32_e32 v110, v194
	v_mov_b32_e32 v111, v195
	v_mov_b32_e32 v100, v196
	v_mov_b32_e32 v101, v197
	v_mov_b32_e32 v102, v198
	v_mov_b32_e32 v103, v199
	v_mov_b32_e32 v96, v200
	v_mov_b32_e32 v97, v201
	v_mov_b32_e32 v98, v202
	v_mov_b32_e32 v99, v203
	v_add_u32_e32 v216, 48, v162
	v_ashrrev_i32_e32 v217, 31, v216
	v_lshlrev_b64 v[218:219], 9, v[216:217]
	v_lshl_add_u64 v[218:219], s[2:3], 0, v[218:219]
	v_lshl_add_u64 v[218:219], v[218:219], 0, s[48:49]
	v_lshl_add_u64 v[218:219], v[218:219], 0, v[166:167]
	global_load_dwordx4 v[204:207], v[218:219], off
	v_lshlrev_b64 v[216:217], 12, v[216:217]
	v_lshl_add_u64 v[216:217], v[216:217], 0, v[164:165]
	v_lshlrev_b64 v[216:217], 1, v[216:217]
	v_lshl_add_u64 v[216:217], s[4:5], 0, v[216:217]
	global_load_dwordx4 v[208:211], v[216:217], off
	global_load_dwordx4 v[212:215], v[216:217], off offset:256
	v_add_f32_e32 v104, v108, v110
	v_mov_b32_e32 v105, v104
	v_add_f32_e32 v108, v109, v111
	s_nop 0
	v_permlane16_swap_b32_e32 v104, v105
	v_add_f32_e32 v105, v104, v105
	v_mov_b32_e32 v104, v108
	s_nop 1
	v_permlane16_swap_b32_e32 v108, v104
	v_add_f32_e32 v104, v108, v104
	v_mov_b32_e32 v109, v105
	v_mov_b32_e32 v108, v104
	s_nop 0
	v_permlane32_swap_b32_e32 v105, v109
	v_permlane32_swap_b32_e32 v104, v108
	v_pk_add_f32 v[104:105], v[104:105], v[108:109]
	s_nop 0
	v_pk_mul_f32 v[104:105], v[104:105], s[8:9] op_sel_hi:[1,0]
	s_nop 0
	v_fma_f32 v104, -v105, v105, v104
	v_max_f32_e32 v104, 0, v104
	v_add_f32_e32 v104, 0x358637bd, v104
	v_cmp_gt_f32_e32 vcc, s73, v104
	v_mul_f32_e32 v108, 0x4b800000, v104
	s_nop 0
	v_cndmask_b32_e32 v104, v104, v108, vcc
	v_rsq_f32_e32 v104, v104
	s_nop 0
	v_mul_f32_e32 v108, 0x45800000, v104
	v_cndmask_b32_e32 v104, v104, v108, vcc
	v_mul_f32_e32 v108, 0xbfb8aa3b, v92
	v_exp_f32_e32 v108, v108
	s_nop 0
	v_add_f32_e32 v108, 1.0, v108
	v_div_scale_f32 v109, s[0:1], v108, v108, v92
	v_rcp_f32_e32 v110, v109
	s_nop 0
	v_fma_f32 v111, -v109, v110, 1.0
	v_fmac_f32_e32 v110, v111, v110
	v_div_scale_f32 v111, vcc, v92, v108, v92
	v_mul_f32_e32 v112, v111, v110
	v_fma_f32 v113, -v109, v112, v111
	v_fmac_f32_e32 v112, v113, v110
	v_fma_f32 v109, -v109, v112, v111
	v_div_fmas_f32 v109, v109, v110, v112
	v_div_fixup_f32 v92, v109, v108, v92
	v_mul_f32_e32 v108, 0xbfb8aa3b, v93
	v_exp_f32_e32 v108, v108
	s_nop 0
	v_add_f32_e32 v108, 1.0, v108
	v_div_scale_f32 v109, s[0:1], v108, v108, v93
	v_rcp_f32_e32 v110, v109
	s_nop 0
	v_fma_f32 v111, -v109, v110, 1.0
	v_fmac_f32_e32 v110, v111, v110
	v_div_scale_f32 v111, vcc, v93, v108, v93
	v_mul_f32_e32 v112, v111, v110
	v_fma_f32 v113, -v109, v112, v111
	v_fmac_f32_e32 v112, v113, v110
	v_fma_f32 v109, -v109, v112, v111
	v_div_fmas_f32 v109, v109, v110, v112
	v_div_fixup_f32 v93, v109, v108, v93
	v_lshlrev_b32_e32 v108, 16, v100
	v_and_b32_e32 v100, 0xffff0000, v100
	v_sub_f32_e32 v108, v108, v105
	v_sub_f32_e32 v100, v100, v105
	v_mul_f32_e32 v108, v108, v104
	v_mul_f32_e32 v100, v100, v104
	v_mul_f32_e32 v92, v92, v108
	v_mul_f32_e32 v93, v93, v100
	v_cvt_pk_bf16_f32 v92, v92, v93
	v_mul_f32_e32 v93, 0xbfb8aa3b, v94
	v_exp_f32_e32 v93, v93
	s_nop 0
	v_add_f32_e32 v93, 1.0, v93
	v_div_scale_f32 v100, s[0:1], v93, v93, v94
	v_rcp_f32_e32 v108, v100
	s_nop 0
	v_fma_f32 v109, -v100, v108, 1.0
	v_fmac_f32_e32 v108, v109, v108
	v_div_scale_f32 v109, vcc, v94, v93, v94
	v_mul_f32_e32 v110, v109, v108
	v_fma_f32 v111, -v100, v110, v109
	v_fmac_f32_e32 v110, v111, v108
	v_fma_f32 v100, -v100, v110, v109
	v_div_fmas_f32 v100, v100, v108, v110
	v_div_fixup_f32 v93, v100, v93, v94
	v_mul_f32_e32 v94, 0xbfb8aa3b, v95
	v_exp_f32_e32 v94, v94
	s_nop 0
	v_add_f32_e32 v94, 1.0, v94
	v_div_scale_f32 v100, s[0:1], v94, v94, v95
	v_rcp_f32_e32 v108, v100
	s_nop 0
	v_fma_f32 v109, -v100, v108, 1.0
	v_fmac_f32_e32 v108, v109, v108
	v_div_scale_f32 v109, vcc, v95, v94, v95
	v_mul_f32_e32 v110, v109, v108
	v_fma_f32 v111, -v100, v110, v109
; __device__ __forceinline__ unsigned cvt_pk_bf16(float lo, float hi) { unsigned r; asm volatile("v_cvt_pk_bf16_f32 %0, %1, %2" : "=v"(r) : "v"(lo), "v"(hi)); return r; }
; __device__ __forceinline__ float bf_lo(unsigned w) { return __uint_as_float(w << 16); }
; __device__ __forceinline__ float bf_hi(unsigned w) { return __uint_as_float(w & 0xffff0000u); }
; __device__ __forceinline__ float silu_f(float v) { return v / (1.0f + __expf(-v)); }
;     __device__ __forceinline__ void operator()(const Acc& acc, const Unit& u, int wr, int wc, int fr, int fq) const {
;     ...
;                 for (int bj = 0; bj < 2; ++bj) { const u32x4 ov = bj == 0 ? o0 : o1; const unsigned ow[4] = {ov.x, ov.y, ov.z, ov.w}; unsigned r[4];
; #pragma unroll
;                     for (int p = 0; p < 4; ++p) { const f32x4 v = acc[ai][bj][m][p >> 1]; const float g0 = silu_f(v[(p & 1) * 2]), g1 = silu_f(v[(p & 1) * 2 + 1]);
;                         r[p] = cvt_pk_bf16(g0 * ((bf_lo(ow[p]) - mu) * rstd), g1 * ((bf_hi(ow[p]) - mu) * rstd)); }
;                     *(u32x4*)(U + off + bj * HALF) = (u32x4){r[0], r[1], r[2], r[3]}; }
	v_fmac_f32_e32 v110, v111, v108
	v_fma_f32 v100, -v100, v110, v109
	v_div_fmas_f32 v100, v100, v108, v110
	v_div_fixup_f32 v94, v100, v94, v95
	v_lshlrev_b32_e32 v95, 16, v101
	v_sub_f32_e32 v95, v95, v105
	v_mul_f32_e32 v95, v95, v104
	v_mul_f32_e32 v93, v93, v95
	v_and_b32_e32 v95, 0xffff0000, v101
	v_sub_f32_e32 v95, v95, v105
	v_mul_f32_e32 v95, v95, v104
	v_mul_f32_e32 v94, v94, v95
	v_cvt_pk_bf16_f32 v93, v93, v94
	v_mul_f32_e32 v94, 0xbfb8aa3b, v88
	v_exp_f32_e32 v94, v94
	s_nop 0
	v_add_f32_e32 v94, 1.0, v94
	v_div_scale_f32 v95, s[0:1], v94, v94, v88
	v_rcp_f32_e32 v100, v95
	s_nop 0
	v_fma_f32 v101, -v95, v100, 1.0
	v_fmac_f32_e32 v100, v101, v100
	v_div_scale_f32 v101, vcc, v88, v94, v88
	v_mul_f32_e32 v108, v101, v100
	v_fma_f32 v109, -v95, v108, v101
	v_fmac_f32_e32 v108, v109, v100
	v_fma_f32 v95, -v95, v108, v101
	v_div_fmas_f32 v95, v95, v100, v108
	v_div_fixup_f32 v88, v95, v94, v88
	v_mul_f32_e32 v94, 0xbfb8aa3b, v89
	v_exp_f32_e32 v94, v94
	s_nop 0
	v_add_f32_e32 v94, 1.0, v94
	v_div_scale_f32 v95, s[0:1], v94, v94, v89
	v_rcp_f32_e32 v100, v95
	s_nop 0
	v_fma_f32 v101, -v95, v100, 1.0
	v_fmac_f32_e32 v100, v101, v100
	v_div_scale_f32 v101, vcc, v89, v94, v89
	v_mul_f32_e32 v108, v101, v100
	v_fma_f32 v109, -v95, v108, v101
	v_fmac_f32_e32 v108, v109, v100
	v_fma_f32 v95, -v95, v108, v101
	v_div_fmas_f32 v95, v95, v100, v108
	v_div_fixup_f32 v89, v95, v94, v89
	v_lshlrev_b32_e32 v94, 16, v102
	v_sub_f32_e32 v94, v94, v105
	v_mul_f32_e32 v94, v94, v104
	v_mul_f32_e32 v88, v88, v94
	v_and_b32_e32 v94, 0xffff0000, v102
	v_sub_f32_e32 v94, v94, v105
	v_mul_f32_e32 v94, v94, v104
	v_mul_f32_e32 v89, v89, v94
	v_cvt_pk_bf16_f32 v94, v88, v89
	v_mul_f32_e32 v88, 0xbfb8aa3b, v90
	v_exp_f32_e32 v88, v88
	s_nop 0
	v_add_f32_e32 v88, 1.0, v88
	v_div_scale_f32 v89, s[0:1], v88, v88, v90
	v_rcp_f32_e32 v95, v89
	s_nop 0
	v_fma_f32 v100, -v89, v95, 1.0
	v_fmac_f32_e32 v95, v100, v95
	v_div_scale_f32 v100, vcc, v90, v88, v90
	v_mul_f32_e32 v101, v100, v95
	v_fma_f32 v102, -v89, v101, v100
	v_fmac_f32_e32 v101, v102, v95
	v_fma_f32 v89, -v89, v101, v100
	v_div_fmas_f32 v89, v89, v95, v101
	v_div_fixup_f32 v88, v89, v88, v90
	v_mul_f32_e32 v89, 0xbfb8aa3b, v91
	v_exp_f32_e32 v89, v89
	s_nop 0
	v_add_f32_e32 v89, 1.0, v89
	v_div_scale_f32 v90, s[0:1], v89, v89, v91
	v_rcp_f32_e32 v95, v90
	s_nop 0
	v_fma_f32 v100, -v90, v95, 1.0
	v_fmac_f32_e32 v95, v100, v95
	v_div_scale_f32 v100, vcc, v91, v89, v91
	v_mul_f32_e32 v101, v100, v95
	v_fma_f32 v102, -v90, v101, v100
	v_fmac_f32_e32 v101, v102, v95
	v_fma_f32 v90, -v90, v101, v100
	v_div_fmas_f32 v90, v90, v95, v101
	v_div_fixup_f32 v89, v90, v89, v91
	v_lshlrev_b32_e32 v90, 16, v103
	v_sub_f32_e32 v90, v90, v105
	v_mul_f32_e32 v90, v90, v104
	v_mul_f32_e32 v88, v88, v90
	v_and_b32_e32 v90, 0xffff0000, v103
	v_sub_f32_e32 v90, v90, v105
	v_mul_f32_e32 v90, v90, v104
	v_mul_f32_e32 v89, v89, v90
	v_mul_f32_e32 v90, 0xbfb8aa3b, v84
	v_exp_f32_e32 v90, v90
	v_cvt_pk_bf16_f32 v95, v88, v89
	v_lshl_add_u64 v[88:89], s[6:7], 0, v[106:107]
	global_store_dwordx4 v[88:89], v[92:95], off
	v_add_f32_e32 v90, 1.0, v90
	v_div_scale_f32 v91, s[0:1], v90, v90, v84
	v_rcp_f32_e32 v92, v91
	s_nop 0
	v_fma_f32 v93, -v91, v92, 1.0
	v_fmac_f32_e32 v92, v93, v92
	v_div_scale_f32 v93, vcc, v84, v90, v84
	v_mul_f32_e32 v94, v93, v92
	v_fma_f32 v95, -v91, v94, v93
	v_fmac_f32_e32 v94, v95, v92
	v_fma_f32 v91, -v91, v94, v93
	v_div_fmas_f32 v91, v91, v92, v94
	v_div_fixup_f32 v84, v91, v90, v84
	v_mul_f32_e32 v90, 0xbfb8aa3b, v85
	v_exp_f32_e32 v90, v90
	s_nop 0
	v_add_f32_e32 v90, 1.0, v90
	v_div_scale_f32 v91, s[0:1], v90, v90, v85
	v_rcp_f32_e32 v92, v91
	s_nop 0
	v_fma_f32 v93, -v91, v92, 1.0
	v_fmac_f32_e32 v92, v93, v92
	v_div_scale_f32 v93, vcc, v85, v90, v85
	v_mul_f32_e32 v94, v93, v92
	v_fma_f32 v95, -v91, v94, v93
	v_fmac_f32_e32 v94, v95, v92
	v_fma_f32 v91, -v91, v94, v93
	v_div_fmas_f32 v91, v91, v92, v94
	v_div_fixup_f32 v85, v91, v90, v85
	v_lshlrev_b32_e32 v90, 16, v96
	v_sub_f32_e32 v90, v90, v105
	v_mul_f32_e32 v90, v90, v104
	v_mul_f32_e32 v84, v84, v90
	v_and_b32_e32 v90, 0xffff0000, v96
	v_sub_f32_e32 v90, v90, v105
	v_mul_f32_e32 v90, v90, v104
	v_mul_f32_e32 v85, v85, v90
	v_cvt_pk_bf16_f32 v84, v84, v85
	v_mul_f32_e32 v85, 0xbfb8aa3b, v86
	v_exp_f32_e32 v85, v85
	s_nop 0
	v_add_f32_e32 v85, 1.0, v85
	v_div_scale_f32 v90, s[0:1], v85, v85, v86
	v_rcp_f32_e32 v91, v90
	s_nop 0
	v_fma_f32 v92, -v90, v91, 1.0
	v_fmac_f32_e32 v91, v92, v91
	v_div_scale_f32 v92, vcc, v86, v85, v86
	v_mul_f32_e32 v93, v92, v91
	v_fma_f32 v94, -v90, v93, v92
	v_fmac_f32_e32 v93, v94, v91
	v_fma_f32 v90, -v90, v93, v92
	v_div_fmas_f32 v90, v90, v91, v93
	v_div_fixup_f32 v85, v90, v85, v86
	v_mul_f32_e32 v86, 0xbfb8aa3b, v87
	v_exp_f32_e32 v86, v86
	s_nop 0
	v_add_f32_e32 v86, 1.0, v86
	v_div_scale_f32 v90, s[0:1], v86, v86, v87
	v_rcp_f32_e32 v91, v90
	s_nop 0
	v_fma_f32 v92, -v90, v91, 1.0
	v_fmac_f32_e32 v91, v92, v91
	v_div_scale_f32 v92, vcc, v87, v86, v87
	v_mul_f32_e32 v93, v92, v91
	v_fma_f32 v94, -v90, v93, v92
	v_fmac_f32_e32 v93, v94, v91
	v_fma_f32 v90, -v90, v93, v92
	v_div_fmas_f32 v90, v90, v91, v93
	v_div_fixup_f32 v86, v90, v86, v87
	v_lshlrev_b32_e32 v87, 16, v97
	v_sub_f32_e32 v87, v87, v105
	v_mul_f32_e32 v87, v87, v104
	v_mul_f32_e32 v85, v85, v87
	v_and_b32_e32 v87, 0xffff0000, v97
	v_sub_f32_e32 v87, v87, v105
	v_mul_f32_e32 v87, v87, v104
	v_mul_f32_e32 v86, v86, v87
	v_cvt_pk_bf16_f32 v85, v85, v86
	v_mul_f32_e32 v86, 0xbfb8aa3b, v80
	v_exp_f32_e32 v86, v86
	s_nop 0
	v_add_f32_e32 v86, 1.0, v86
	v_div_scale_f32 v87, s[0:1], v86, v86, v80
	v_rcp_f32_e32 v90, v87
	s_nop 0
	v_fma_f32 v91, -v87, v90, 1.0
; __device__ __forceinline__ unsigned cvt_pk_bf16(float lo, float hi) { unsigned r; asm volatile("v_cvt_pk_bf16_f32 %0, %1, %2" : "=v"(r) : "v"(lo), "v"(hi)); return r; }
; __device__ __forceinline__ float bf_lo(unsigned w) { return __uint_as_float(w << 16); }
; __device__ __forceinline__ float bf_hi(unsigned w) { return __uint_as_float(w & 0xffff0000u); }
;     __device__ __forceinline__ void operator()(const Acc& acc, const Unit& u, int wr, int wc, int fr, int fq) const {
;     ...
;             for (int m = 0; m < 4; ++m) {
;                 const int row_in = ai * HALF + wr * 64 + m * 16 + fr, s = u.pm * BM + row_in;
;                 const f32x4 tq = ((const f32x4*)(stats + ((size_t)s * 8 + h) * 8))[fq];
;                 const size_t off = (size_t)s * RV + u.pn * BM + wc * 32 + 8 * fq;
;                 const u32x4 o0 = *(const u32x4*)(O + off), o1 = *(const u32x4*)(O + off + HALF);
;                 float s1 = tq[0] + tq[2], s2 = tq[1] + tq[3];
;                 { const auto r1 = __builtin_amdgcn_permlane16_swap(__float_as_uint(s1), __float_as_uint(s1), false, false); s1 = __uint_as_float(r1[0]) + __uint_as_float(r1[1]);
;                   const auto r2 = __builtin_amdgcn_permlane16_swap(__float_as_uint(s2), __float_as_uint(s2), false, false); s2 = __uint_as_float(r2[0]) + __uint_as_float(r2[1]);
;                   const auto r3 = __builtin_amdgcn_permlane32_swap(__float_as_uint(s1), __float_as_uint(s1), false, false); s1 = __uint_as_float(r3[0]) + __uint_as_float(r3[1]);
;                   const auto r4 = __builtin_amdgcn_permlane32_swap(__float_as_uint(s2), __float_as_uint(s2), false, false); s2 = __uint_as_float(r4[0]) + __uint_as_float(r4[1]); }
;                 const float mu = s1 * (1.0f / 512.0f), var = fmaxf(s2 * (1.0f / 512.0f) - mu * mu, 0.f), rstd = rsqrtf(var + EPS);
; #pragma unroll
;                 for (int bj = 0; bj < 2; ++bj) { const u32x4 ov = bj == 0 ? o0 : o1; const unsigned ow[4] = {ov.x, ov.y, ov.z, ov.w}; unsigned r[4];
; #pragma unroll
;                     for (int p = 0; p < 4; ++p) { const f32x4 v = acc[ai][bj][m][p >> 1]; const float g0 = silu_f(v[(p & 1) * 2]), g1 = silu_f(v[(p & 1) * 2 + 1]);
;                         r[p] = cvt_pk_bf16(g0 * ((bf_lo(ow[p]) - mu) * rstd), g1 * ((bf_hi(ow[p]) - mu) * rstd)); }
;                     *(u32x4*)(U + off + bj * HALF) = (u32x4){r[0], r[1], r[2], r[3]}; }
	v_fmac_f32_e32 v90, v91, v90
	v_div_scale_f32 v91, vcc, v80, v86, v80
	v_mul_f32_e32 v92, v91, v90
	v_fma_f32 v93, -v87, v92, v91
	v_fmac_f32_e32 v92, v93, v90
	v_fma_f32 v87, -v87, v92, v91
	v_div_fmas_f32 v87, v87, v90, v92
	v_div_fixup_f32 v80, v87, v86, v80
	v_mul_f32_e32 v86, 0xbfb8aa3b, v81
	v_exp_f32_e32 v86, v86
	s_nop 0
	v_add_f32_e32 v86, 1.0, v86
	v_div_scale_f32 v87, s[0:1], v86, v86, v81
	v_rcp_f32_e32 v90, v87
	s_nop 0
	v_fma_f32 v91, -v87, v90, 1.0
	v_fmac_f32_e32 v90, v91, v90
	v_div_scale_f32 v91, vcc, v81, v86, v81
	v_mul_f32_e32 v92, v91, v90
	v_fma_f32 v93, -v87, v92, v91
	v_fmac_f32_e32 v92, v93, v90
	v_fma_f32 v87, -v87, v92, v91
	v_div_fmas_f32 v87, v87, v90, v92
	v_div_fixup_f32 v81, v87, v86, v81
	v_lshlrev_b32_e32 v86, 16, v98
	v_sub_f32_e32 v86, v86, v105
	v_mul_f32_e32 v86, v86, v104
	v_mul_f32_e32 v80, v80, v86
	v_and_b32_e32 v86, 0xffff0000, v98
	v_sub_f32_e32 v86, v86, v105
	v_mul_f32_e32 v86, v86, v104
	v_mul_f32_e32 v81, v81, v86
	v_cvt_pk_bf16_f32 v86, v80, v81
	v_mul_f32_e32 v80, 0xbfb8aa3b, v82
	v_exp_f32_e32 v80, v80
	s_nop 0
	v_add_f32_e32 v80, 1.0, v80
	v_div_scale_f32 v81, s[0:1], v80, v80, v82
	v_rcp_f32_e32 v87, v81
	s_nop 0
	v_fma_f32 v90, -v81, v87, 1.0
	v_fmac_f32_e32 v87, v90, v87
	v_div_scale_f32 v90, vcc, v82, v80, v82
	v_mul_f32_e32 v91, v90, v87
	v_fma_f32 v92, -v81, v91, v90
	v_fmac_f32_e32 v91, v92, v87
	v_fma_f32 v81, -v81, v91, v90
	v_div_fmas_f32 v81, v81, v87, v91
	v_div_fixup_f32 v80, v81, v80, v82
	v_mul_f32_e32 v81, 0xbfb8aa3b, v83
	v_exp_f32_e32 v81, v81
	s_nop 0
	v_add_f32_e32 v81, 1.0, v81
	v_div_scale_f32 v82, s[0:1], v81, v81, v83
	v_rcp_f32_e32 v87, v82
	s_nop 0
	v_fma_f32 v90, -v82, v87, 1.0
	v_fmac_f32_e32 v87, v90, v87
	v_div_scale_f32 v90, vcc, v83, v81, v83
	v_mul_f32_e32 v91, v90, v87
	v_fma_f32 v92, -v82, v91, v90
	v_fmac_f32_e32 v91, v92, v87
	v_fma_f32 v82, -v82, v91, v90
	v_div_fmas_f32 v82, v82, v87, v91
	v_div_fixup_f32 v81, v82, v81, v83
	v_lshlrev_b32_e32 v82, 16, v99
	v_sub_f32_e32 v82, v82, v105
	v_mul_f32_e32 v82, v82, v104
	v_mul_f32_e32 v80, v80, v82
	v_and_b32_e32 v82, 0xffff0000, v99
	v_sub_f32_e32 v82, v82, v105
	v_mul_f32_e32 v82, v82, v104
	v_mul_f32_e32 v81, v81, v82
	v_cvt_pk_bf16_f32 v87, v80, v81
	v_add_u32_e32 v80, 48, v162
	v_ashrrev_i32_e32 v81, 31, v80
	v_lshlrev_b64 v[82:83], 9, v[80:81]
	v_lshl_add_u64 v[82:83], s[2:3], 0, v[82:83]
	v_lshl_add_u64 v[82:83], v[82:83], 0, s[48:49]
	global_store_dwordx4 v[88:89], v[84:87], off offset:256
	v_lshl_add_u64 v[82:83], v[82:83], 0, v[166:167]
	v_lshlrev_b64 v[80:81], 12, v[80:81]
	v_lshl_add_u64 v[80:81], v[80:81], 0, v[164:165]
	v_lshlrev_b64 v[90:91], 1, v[80:81]
	v_lshl_add_u64 v[80:81], s[4:5], 0, v[90:91]
	s_waitcnt vmcnt(2)
	v_mov_b32_e32 v92, v204
	v_mov_b32_e32 v93, v205
	v_mov_b32_e32 v94, v206
	v_mov_b32_e32 v95, v207
	v_mov_b32_e32 v84, v208
	v_mov_b32_e32 v85, v209
	v_mov_b32_e32 v86, v210
	v_mov_b32_e32 v87, v211
	v_mov_b32_e32 v80, v212
	v_mov_b32_e32 v81, v213
	v_mov_b32_e32 v82, v214
	v_mov_b32_e32 v83, v215
	v_add_u32_e32 v216, 0x80, v162
	v_ashrrev_i32_e32 v217, 31, v216
	v_lshlrev_b64 v[218:219], 9, v[216:217]
	v_lshl_add_u64 v[218:219], s[2:3], 0, v[218:219]
	v_lshl_add_u64 v[218:219], v[218:219], 0, s[48:49]
	v_lshl_add_u64 v[218:219], v[218:219], 0, v[166:167]
	global_load_dwordx4 v[192:195], v[218:219], off
	v_lshlrev_b64 v[216:217], 12, v[216:217]
	v_lshl_add_u64 v[216:217], v[216:217], 0, v[164:165]
	v_lshlrev_b64 v[216:217], 1, v[216:217]
	v_lshl_add_u64 v[216:217], s[4:5], 0, v[216:217]
	global_load_dwordx4 v[196:199], v[216:217], off
	global_load_dwordx4 v[200:203], v[216:217], off offset:256
	v_add_f32_e32 v88, v92, v94
	v_mov_b32_e32 v89, v88
	v_add_f32_e32 v92, v93, v95
	s_nop 0
	v_permlane16_swap_b32_e32 v88, v89
	v_add_f32_e32 v89, v88, v89
	v_mov_b32_e32 v88, v92
	s_nop 1
	v_permlane16_swap_b32_e32 v92, v88
	v_add_f32_e32 v88, v92, v88
	v_mov_b32_e32 v93, v89
	v_mov_b32_e32 v92, v88
	s_nop 0
	v_permlane32_swap_b32_e32 v89, v93
	v_permlane32_swap_b32_e32 v88, v92
	v_pk_add_f32 v[88:89], v[88:89], v[92:93]
	s_nop 0
	v_pk_mul_f32 v[88:89], v[88:89], s[8:9] op_sel_hi:[1,0]
	s_nop 0
	v_fma_f32 v88, -v89, v89, v88
	v_max_f32_e32 v88, 0, v88
	v_add_f32_e32 v88, 0x358637bd, v88
	v_cmp_gt_f32_e32 vcc, s73, v88
	v_mul_f32_e32 v92, 0x4b800000, v88
	s_nop 0
	v_cndmask_b32_e32 v88, v88, v92, vcc
	v_rsq_f32_e32 v88, v88
	s_nop 0
	v_mul_f32_e32 v92, 0x45800000, v88
	v_cndmask_b32_e32 v88, v88, v92, vcc
	v_mul_f32_e32 v92, 0xbfb8aa3b, v76
	v_exp_f32_e32 v92, v92
	s_nop 0
	v_add_f32_e32 v92, 1.0, v92
	v_div_scale_f32 v93, s[0:1], v92, v92, v76
	v_rcp_f32_e32 v94, v93
	s_nop 0
	v_fma_f32 v95, -v93, v94, 1.0
	v_fmac_f32_e32 v94, v95, v94
	v_div_scale_f32 v95, vcc, v76, v92, v76
	v_mul_f32_e32 v96, v95, v94
	v_fma_f32 v97, -v93, v96, v95
	v_fmac_f32_e32 v96, v97, v94
	v_fma_f32 v93, -v93, v96, v95
	v_div_fmas_f32 v93, v93, v94, v96
	v_div_fixup_f32 v76, v93, v92, v76
	v_mul_f32_e32 v92, 0xbfb8aa3b, v77
	v_exp_f32_e32 v92, v92
	s_nop 0
	v_add_f32_e32 v92, 1.0, v92
	v_div_scale_f32 v93, s[0:1], v92, v92, v77
	v_rcp_f32_e32 v94, v93
	s_nop 0
	v_fma_f32 v95, -v93, v94, 1.0
	v_fmac_f32_e32 v94, v95, v94
	v_div_scale_f32 v95, vcc, v77, v92, v77
	v_mul_f32_e32 v96, v95, v94
	v_fma_f32 v97, -v93, v96, v95
	v_fmac_f32_e32 v96, v97, v94
	v_fma_f32 v93, -v93, v96, v95
	v_div_fmas_f32 v93, v93, v94, v96
	v_div_fixup_f32 v77, v93, v92, v77
	v_lshlrev_b32_e32 v92, 16, v84
	v_and_b32_e32 v84, 0xffff0000, v84
	v_sub_f32_e32 v92, v92, v89
	v_sub_f32_e32 v84, v84, v89
	v_mul_f32_e32 v92, v92, v88
	v_mul_f32_e32 v84, v84, v88
	v_mul_f32_e32 v76, v76, v92
	v_mul_f32_e32 v77, v77, v84
	v_cvt_pk_bf16_f32 v76, v76, v77
; __device__ __forceinline__ unsigned cvt_pk_bf16(float lo, float hi) { unsigned r; asm volatile("v_cvt_pk_bf16_f32 %0, %1, %2" : "=v"(r) : "v"(lo), "v"(hi)); return r; }
; __device__ __forceinline__ float bf_lo(unsigned w) { return __uint_as_float(w << 16); }
; __device__ __forceinline__ float bf_hi(unsigned w) { return __uint_as_float(w & 0xffff0000u); }
; __device__ __forceinline__ float silu_f(float v) { return v / (1.0f + __expf(-v)); }
;     __device__ __forceinline__ void operator()(const Acc& acc, const Unit& u, int wr, int wc, int fr, int fq) const {
;     ...
;                 for (int bj = 0; bj < 2; ++bj) { const u32x4 ov = bj == 0 ? o0 : o1; const unsigned ow[4] = {ov.x, ov.y, ov.z, ov.w}; unsigned r[4];
; #pragma unroll
;                     for (int p = 0; p < 4; ++p) { const f32x4 v = acc[ai][bj][m][p >> 1]; const float g0 = silu_f(v[(p & 1) * 2]), g1 = silu_f(v[(p & 1) * 2 + 1]);
;                         r[p] = cvt_pk_bf16(g0 * ((bf_lo(ow[p]) - mu) * rstd), g1 * ((bf_hi(ow[p]) - mu) * rstd)); }
;                     *(u32x4*)(U + off + bj * HALF) = (u32x4){r[0], r[1], r[2], r[3]}; }
	v_mul_f32_e32 v77, 0xbfb8aa3b, v78
	v_exp_f32_e32 v77, v77
	s_nop 0
	v_add_f32_e32 v77, 1.0, v77
	v_div_scale_f32 v84, s[0:1], v77, v77, v78
	v_rcp_f32_e32 v92, v84
	s_nop 0
	v_fma_f32 v93, -v84, v92, 1.0
	v_fmac_f32_e32 v92, v93, v92
	v_div_scale_f32 v93, vcc, v78, v77, v78
	v_mul_f32_e32 v94, v93, v92
	v_fma_f32 v95, -v84, v94, v93
	v_fmac_f32_e32 v94, v95, v92
	v_fma_f32 v84, -v84, v94, v93
	v_div_fmas_f32 v84, v84, v92, v94
	v_div_fixup_f32 v77, v84, v77, v78
	v_mul_f32_e32 v78, 0xbfb8aa3b, v79
	v_exp_f32_e32 v78, v78
	s_nop 0
	v_add_f32_e32 v78, 1.0, v78
	v_div_scale_f32 v84, s[0:1], v78, v78, v79
	v_rcp_f32_e32 v92, v84
	s_nop 0
	v_fma_f32 v93, -v84, v92, 1.0
	v_fmac_f32_e32 v92, v93, v92
	v_div_scale_f32 v93, vcc, v79, v78, v79
	v_mul_f32_e32 v94, v93, v92
	v_fma_f32 v95, -v84, v94, v93
	v_fmac_f32_e32 v94, v95, v92
	v_fma_f32 v84, -v84, v94, v93
	v_div_fmas_f32 v84, v84, v92, v94
	v_div_fixup_f32 v78, v84, v78, v79
	v_lshlrev_b32_e32 v79, 16, v85
	v_sub_f32_e32 v79, v79, v89
	v_mul_f32_e32 v79, v79, v88
	v_mul_f32_e32 v77, v77, v79
	v_and_b32_e32 v79, 0xffff0000, v85
	v_sub_f32_e32 v79, v79, v89
	v_mul_f32_e32 v79, v79, v88
	v_mul_f32_e32 v78, v78, v79
	v_cvt_pk_bf16_f32 v77, v77, v78
	v_mul_f32_e32 v78, 0xbfb8aa3b, v72
	v_exp_f32_e32 v78, v78
	s_nop 0
	v_add_f32_e32 v78, 1.0, v78
	v_div_scale_f32 v79, s[0:1], v78, v78, v72
	v_rcp_f32_e32 v84, v79
	s_nop 0
	v_fma_f32 v85, -v79, v84, 1.0
	v_fmac_f32_e32 v84, v85, v84
	v_div_scale_f32 v85, vcc, v72, v78, v72
	v_mul_f32_e32 v92, v85, v84
	v_fma_f32 v93, -v79, v92, v85
	v_fmac_f32_e32 v92, v93, v84
	v_fma_f32 v79, -v79, v92, v85
	v_div_fmas_f32 v79, v79, v84, v92
	v_div_fixup_f32 v72, v79, v78, v72
	v_mul_f32_e32 v78, 0xbfb8aa3b, v73
	v_exp_f32_e32 v78, v78
	s_nop 0
	v_add_f32_e32 v78, 1.0, v78
	v_div_scale_f32 v79, s[0:1], v78, v78, v73
	v_rcp_f32_e32 v84, v79
	s_nop 0
	v_fma_f32 v85, -v79, v84, 1.0
	v_fmac_f32_e32 v84, v85, v84
	v_div_scale_f32 v85, vcc, v73, v78, v73
	v_mul_f32_e32 v92, v85, v84
	v_fma_f32 v93, -v79, v92, v85
	v_fmac_f32_e32 v92, v93, v84
	v_fma_f32 v79, -v79, v92, v85
	v_div_fmas_f32 v79, v79, v84, v92
	v_div_fixup_f32 v73, v79, v78, v73
	v_lshlrev_b32_e32 v78, 16, v86
	v_sub_f32_e32 v78, v78, v89
	v_mul_f32_e32 v78, v78, v88
	v_mul_f32_e32 v72, v72, v78
	v_and_b32_e32 v78, 0xffff0000, v86
	v_sub_f32_e32 v78, v78, v89
	v_mul_f32_e32 v78, v78, v88
	v_mul_f32_e32 v73, v73, v78
	v_cvt_pk_bf16_f32 v78, v72, v73
	v_mul_f32_e32 v72, 0xbfb8aa3b, v74
	v_exp_f32_e32 v72, v72
	s_nop 0
	v_add_f32_e32 v72, 1.0, v72
	v_div_scale_f32 v73, s[0:1], v72, v72, v74
	v_rcp_f32_e32 v79, v73
	s_nop 0
	v_fma_f32 v84, -v73, v79, 1.0
	v_fmac_f32_e32 v79, v84, v79
	v_div_scale_f32 v84, vcc, v74, v72, v74
	v_mul_f32_e32 v85, v84, v79
	v_fma_f32 v86, -v73, v85, v84
	v_fmac_f32_e32 v85, v86, v79
	v_fma_f32 v73, -v73, v85, v84
	v_div_fmas_f32 v73, v73, v79, v85
	v_div_fixup_f32 v72, v73, v72, v74
	v_mul_f32_e32 v73, 0xbfb8aa3b, v75
	v_exp_f32_e32 v73, v73
	s_nop 0
	v_add_f32_e32 v73, 1.0, v73
	v_div_scale_f32 v74, s[0:1], v73, v73, v75
	v_rcp_f32_e32 v79, v74
	s_nop 0
	v_fma_f32 v84, -v74, v79, 1.0
	v_fmac_f32_e32 v79, v84, v79
	v_div_scale_f32 v84, vcc, v75, v73, v75
	v_mul_f32_e32 v85, v84, v79
	v_fma_f32 v86, -v74, v85, v84
	v_fmac_f32_e32 v85, v86, v79
	v_fma_f32 v74, -v74, v85, v84
	v_div_fmas_f32 v74, v74, v79, v85
	v_div_fixup_f32 v73, v74, v73, v75
	v_lshlrev_b32_e32 v74, 16, v87
	v_sub_f32_e32 v74, v74, v89
	v_mul_f32_e32 v74, v74, v88
	v_mul_f32_e32 v72, v72, v74
	v_and_b32_e32 v74, 0xffff0000, v87
	v_sub_f32_e32 v74, v74, v89
	v_mul_f32_e32 v74, v74, v88
	v_mul_f32_e32 v73, v73, v74
	v_mul_f32_e32 v74, 0xbfb8aa3b, v68
	v_exp_f32_e32 v74, v74
	v_cvt_pk_bf16_f32 v79, v72, v73
	v_lshl_add_u64 v[72:73], s[6:7], 0, v[90:91]
	global_store_dwordx4 v[72:73], v[76:79], off
	v_add_f32_e32 v74, 1.0, v74
	v_div_scale_f32 v75, s[0:1], v74, v74, v68
	v_rcp_f32_e32 v76, v75
	s_nop 0
	v_fma_f32 v77, -v75, v76, 1.0
	v_fmac_f32_e32 v76, v77, v76
	v_div_scale_f32 v77, vcc, v68, v74, v68
	v_mul_f32_e32 v78, v77, v76
	v_fma_f32 v79, -v75, v78, v77
	v_fmac_f32_e32 v78, v79, v76
	v_fma_f32 v75, -v75, v78, v77
	v_div_fmas_f32 v75, v75, v76, v78
	v_div_fixup_f32 v68, v75, v74, v68
	v_mul_f32_e32 v74, 0xbfb8aa3b, v69
	v_exp_f32_e32 v74, v74
	s_nop 0
	v_add_f32_e32 v74, 1.0, v74
	v_div_scale_f32 v75, s[0:1], v74, v74, v69
	v_rcp_f32_e32 v76, v75
	s_nop 0
	v_fma_f32 v77, -v75, v76, 1.0
	v_fmac_f32_e32 v76, v77, v76
	v_div_scale_f32 v77, vcc, v69, v74, v69
	v_mul_f32_e32 v78, v77, v76
	v_fma_f32 v79, -v75, v78, v77
	v_fmac_f32_e32 v78, v79, v76
	v_fma_f32 v75, -v75, v78, v77
	v_div_fmas_f32 v75, v75, v76, v78
	v_div_fixup_f32 v69, v75, v74, v69
	v_lshlrev_b32_e32 v74, 16, v80
	v_sub_f32_e32 v74, v74, v89
	v_mul_f32_e32 v74, v74, v88
	v_mul_f32_e32 v68, v68, v74
	v_and_b32_e32 v74, 0xffff0000, v80
	v_sub_f32_e32 v74, v74, v89
	v_mul_f32_e32 v74, v74, v88
	v_mul_f32_e32 v69, v69, v74
	v_cvt_pk_bf16_f32 v68, v68, v69
	v_mul_f32_e32 v69, 0xbfb8aa3b, v70
	v_exp_f32_e32 v69, v69
	s_nop 0
	v_add_f32_e32 v69, 1.0, v69
	v_div_scale_f32 v74, s[0:1], v69, v69, v70
	v_rcp_f32_e32 v75, v74
	s_nop 0
	v_fma_f32 v76, -v74, v75, 1.0
	v_fmac_f32_e32 v75, v76, v75
	v_div_scale_f32 v76, vcc, v70, v69, v70
	v_mul_f32_e32 v77, v76, v75
	v_fma_f32 v78, -v74, v77, v76
	v_fmac_f32_e32 v77, v78, v75
	v_fma_f32 v74, -v74, v77, v76
	v_div_fmas_f32 v74, v74, v75, v77
	v_div_fixup_f32 v69, v74, v69, v70
	v_mul_f32_e32 v70, 0xbfb8aa3b, v71
	v_exp_f32_e32 v70, v70
	s_nop 0
	v_add_f32_e32 v70, 1.0, v70
	v_div_scale_f32 v74, s[0:1], v70, v70, v71
	v_rcp_f32_e32 v75, v74
	s_nop 0
	v_fma_f32 v76, -v74, v75, 1.0
	v_fmac_f32_e32 v75, v76, v75
; __device__ __forceinline__ unsigned cvt_pk_bf16(float lo, float hi) { unsigned r; asm volatile("v_cvt_pk_bf16_f32 %0, %1, %2" : "=v"(r) : "v"(lo), "v"(hi)); return r; }
; __device__ __forceinline__ float bf_lo(unsigned w) { return __uint_as_float(w << 16); }
; __device__ __forceinline__ float bf_hi(unsigned w) { return __uint_as_float(w & 0xffff0000u); }
;     __device__ __forceinline__ void operator()(const Acc& acc, const Unit& u, int wr, int wc, int fr, int fq) const {
;     ...
;             for (int m = 0; m < 4; ++m) {
;                 const int row_in = ai * HALF + wr * 64 + m * 16 + fr, s = u.pm * BM + row_in;
;                 const f32x4 tq = ((const f32x4*)(stats + ((size_t)s * 8 + h) * 8))[fq];
;                 const size_t off = (size_t)s * RV + u.pn * BM + wc * 32 + 8 * fq;
;                 const u32x4 o0 = *(const u32x4*)(O + off), o1 = *(const u32x4*)(O + off + HALF);
;                 float s1 = tq[0] + tq[2], s2 = tq[1] + tq[3];
;                 { const auto r1 = __builtin_amdgcn_permlane16_swap(__float_as_uint(s1), __float_as_uint(s1), false, false); s1 = __uint_as_float(r1[0]) + __uint_as_float(r1[1]);
;                   const auto r2 = __builtin_amdgcn_permlane16_swap(__float_as_uint(s2), __float_as_uint(s2), false, false); s2 = __uint_as_float(r2[0]) + __uint_as_float(r2[1]);
;                   const auto r3 = __builtin_amdgcn_permlane32_swap(__float_as_uint(s1), __float_as_uint(s1), false, false); s1 = __uint_as_float(r3[0]) + __uint_as_float(r3[1]);
;                   const auto r4 = __builtin_amdgcn_permlane32_swap(__float_as_uint(s2), __float_as_uint(s2), false, false); s2 = __uint_as_float(r4[0]) + __uint_as_float(r4[1]); }
;                 const float mu = s1 * (1.0f / 512.0f), var = fmaxf(s2 * (1.0f / 512.0f) - mu * mu, 0.f), rstd = rsqrtf(var + EPS);
; #pragma unroll
;                 for (int bj = 0; bj < 2; ++bj) { const u32x4 ov = bj == 0 ? o0 : o1; const unsigned ow[4] = {ov.x, ov.y, ov.z, ov.w}; unsigned r[4];
; #pragma unroll
;                     for (int p = 0; p < 4; ++p) { const f32x4 v = acc[ai][bj][m][p >> 1]; const float g0 = silu_f(v[(p & 1) * 2]), g1 = silu_f(v[(p & 1) * 2 + 1]);
;                         r[p] = cvt_pk_bf16(g0 * ((bf_lo(ow[p]) - mu) * rstd), g1 * ((bf_hi(ow[p]) - mu) * rstd)); }
;                     *(u32x4*)(U + off + bj * HALF) = (u32x4){r[0], r[1], r[2], r[3]}; }
	v_div_scale_f32 v76, vcc, v71, v70, v71
	v_mul_f32_e32 v77, v76, v75
	v_fma_f32 v78, -v74, v77, v76
	v_fmac_f32_e32 v77, v78, v75
	v_fma_f32 v74, -v74, v77, v76
	v_div_fmas_f32 v74, v74, v75, v77
	v_div_fixup_f32 v70, v74, v70, v71
	v_lshlrev_b32_e32 v71, 16, v81
	v_sub_f32_e32 v71, v71, v89
	v_mul_f32_e32 v71, v71, v88
	v_mul_f32_e32 v69, v69, v71
	v_and_b32_e32 v71, 0xffff0000, v81
	v_sub_f32_e32 v71, v71, v89
	v_mul_f32_e32 v71, v71, v88
	v_mul_f32_e32 v70, v70, v71
	v_cvt_pk_bf16_f32 v69, v69, v70
	v_mul_f32_e32 v70, 0xbfb8aa3b, v64
	v_exp_f32_e32 v70, v70
	s_nop 0
	v_add_f32_e32 v70, 1.0, v70
	v_div_scale_f32 v71, s[0:1], v70, v70, v64
	v_rcp_f32_e32 v74, v71
	s_nop 0
	v_fma_f32 v75, -v71, v74, 1.0
	v_fmac_f32_e32 v74, v75, v74
	v_div_scale_f32 v75, vcc, v64, v70, v64
	v_mul_f32_e32 v76, v75, v74
	v_fma_f32 v77, -v71, v76, v75
	v_fmac_f32_e32 v76, v77, v74
	v_fma_f32 v71, -v71, v76, v75
	v_div_fmas_f32 v71, v71, v74, v76
	v_div_fixup_f32 v64, v71, v70, v64
	v_mul_f32_e32 v70, 0xbfb8aa3b, v65
	v_exp_f32_e32 v70, v70
	s_nop 0
	v_add_f32_e32 v70, 1.0, v70
	v_div_scale_f32 v71, s[0:1], v70, v70, v65
	v_rcp_f32_e32 v74, v71
	s_nop 0
	v_fma_f32 v75, -v71, v74, 1.0
	v_fmac_f32_e32 v74, v75, v74
	v_div_scale_f32 v75, vcc, v65, v70, v65
	v_mul_f32_e32 v76, v75, v74
	v_fma_f32 v77, -v71, v76, v75
	v_fmac_f32_e32 v76, v77, v74
	v_fma_f32 v71, -v71, v76, v75
	v_div_fmas_f32 v71, v71, v74, v76
	v_div_fixup_f32 v65, v71, v70, v65
	v_lshlrev_b32_e32 v70, 16, v82
	v_sub_f32_e32 v70, v70, v89
	v_mul_f32_e32 v70, v70, v88
	v_mul_f32_e32 v64, v64, v70
	v_and_b32_e32 v70, 0xffff0000, v82
	v_sub_f32_e32 v70, v70, v89
	v_mul_f32_e32 v70, v70, v88
	v_mul_f32_e32 v65, v65, v70
	v_cvt_pk_bf16_f32 v70, v64, v65
	v_mul_f32_e32 v64, 0xbfb8aa3b, v66
	v_exp_f32_e32 v64, v64
	s_nop 0
	v_add_f32_e32 v64, 1.0, v64
	v_div_scale_f32 v65, s[0:1], v64, v64, v66
	v_rcp_f32_e32 v71, v65
	s_nop 0
	v_fma_f32 v74, -v65, v71, 1.0
	v_fmac_f32_e32 v71, v74, v71
	v_div_scale_f32 v74, vcc, v66, v64, v66
	v_mul_f32_e32 v75, v74, v71
	v_fma_f32 v76, -v65, v75, v74
	v_fmac_f32_e32 v75, v76, v71
	v_fma_f32 v65, -v65, v75, v74
	v_div_fmas_f32 v65, v65, v71, v75
	v_div_fixup_f32 v64, v65, v64, v66
	v_mul_f32_e32 v65, 0xbfb8aa3b, v67
	v_exp_f32_e32 v65, v65
	s_nop 0
	v_add_f32_e32 v65, 1.0, v65
	v_div_scale_f32 v66, s[0:1], v65, v65, v67
	v_rcp_f32_e32 v71, v66
	s_nop 0
	v_fma_f32 v74, -v66, v71, 1.0
	v_fmac_f32_e32 v71, v74, v71
	v_div_scale_f32 v74, vcc, v67, v65, v67
	v_mul_f32_e32 v75, v74, v71
	v_fma_f32 v76, -v66, v75, v74
	v_fmac_f32_e32 v75, v76, v71
	v_fma_f32 v66, -v66, v75, v74
	v_div_fmas_f32 v66, v66, v71, v75
	v_div_fixup_f32 v65, v66, v65, v67
	v_lshlrev_b32_e32 v66, 16, v83
	v_sub_f32_e32 v66, v66, v89
	v_mul_f32_e32 v66, v66, v88
	v_mul_f32_e32 v64, v64, v66
	v_and_b32_e32 v66, 0xffff0000, v83
	v_sub_f32_e32 v66, v66, v89
	v_mul_f32_e32 v66, v66, v88
	v_mul_f32_e32 v65, v65, v66
	v_cvt_pk_bf16_f32 v71, v64, v65
	v_add_u32_e32 v64, 0x80, v162
	v_ashrrev_i32_e32 v65, 31, v64
	v_lshlrev_b64 v[66:67], 9, v[64:65]
	v_lshl_add_u64 v[66:67], s[2:3], 0, v[66:67]
	v_lshl_add_u64 v[66:67], v[66:67], 0, s[48:49]
	global_store_dwordx4 v[72:73], v[68:71], off offset:256
	v_lshl_add_u64 v[66:67], v[66:67], 0, v[166:167]
	v_lshlrev_b64 v[64:65], 12, v[64:65]
	v_lshl_add_u64 v[64:65], v[64:65], 0, v[164:165]
	v_lshlrev_b64 v[74:75], 1, v[64:65]
	v_lshl_add_u64 v[64:65], s[4:5], 0, v[74:75]
	s_waitcnt vmcnt(2)
	v_mov_b32_e32 v76, v192
	v_mov_b32_e32 v77, v193
	v_mov_b32_e32 v78, v194
	v_mov_b32_e32 v79, v195
	v_mov_b32_e32 v68, v196
	v_mov_b32_e32 v69, v197
	v_mov_b32_e32 v70, v198
	v_mov_b32_e32 v71, v199
	v_mov_b32_e32 v64, v200
	v_mov_b32_e32 v65, v201
	v_mov_b32_e32 v66, v202
	v_mov_b32_e32 v67, v203
	v_add_u32_e32 v216, 0x90, v162
	v_ashrrev_i32_e32 v217, 31, v216
	v_lshlrev_b64 v[218:219], 9, v[216:217]
	v_lshl_add_u64 v[218:219], s[2:3], 0, v[218:219]
	v_lshl_add_u64 v[218:219], v[218:219], 0, s[48:49]
	v_lshl_add_u64 v[218:219], v[218:219], 0, v[166:167]
	global_load_dwordx4 v[204:207], v[218:219], off
	v_lshlrev_b64 v[216:217], 12, v[216:217]
	v_lshl_add_u64 v[216:217], v[216:217], 0, v[164:165]
	v_lshlrev_b64 v[216:217], 1, v[216:217]
	v_lshl_add_u64 v[216:217], s[4:5], 0, v[216:217]
	global_load_dwordx4 v[208:211], v[216:217], off
	global_load_dwordx4 v[212:215], v[216:217], off offset:256
	v_add_f32_e32 v72, v76, v78
	v_mov_b32_e32 v73, v72
	v_add_f32_e32 v76, v77, v79
	s_nop 0
	v_permlane16_swap_b32_e32 v72, v73
	v_add_f32_e32 v73, v72, v73
	v_mov_b32_e32 v72, v76
	s_nop 1
	v_permlane16_swap_b32_e32 v76, v72
	v_add_f32_e32 v72, v76, v72
	v_mov_b32_e32 v77, v73
	v_mov_b32_e32 v76, v72
	s_nop 0
	v_permlane32_swap_b32_e32 v73, v77
	v_permlane32_swap_b32_e32 v72, v76
	v_pk_add_f32 v[72:73], v[72:73], v[76:77]
	s_nop 0
	v_pk_mul_f32 v[72:73], v[72:73], s[8:9] op_sel_hi:[1,0]
	s_nop 0
	v_fma_f32 v72, -v73, v73, v72
	v_max_f32_e32 v72, 0, v72
	v_add_f32_e32 v72, 0x358637bd, v72
	v_cmp_gt_f32_e32 vcc, s73, v72
	v_mul_f32_e32 v76, 0x4b800000, v72
	s_nop 0
	v_cndmask_b32_e32 v72, v72, v76, vcc
	v_rsq_f32_e32 v72, v72
	s_nop 0
	v_mul_f32_e32 v76, 0x45800000, v72
	v_cndmask_b32_e32 v72, v72, v76, vcc
	v_mul_f32_e32 v76, 0xbfb8aa3b, v60
	v_exp_f32_e32 v76, v76
	s_nop 0
	v_add_f32_e32 v76, 1.0, v76
	v_div_scale_f32 v77, s[0:1], v76, v76, v60
	v_rcp_f32_e32 v78, v77
	s_nop 0
	v_fma_f32 v79, -v77, v78, 1.0
	v_fmac_f32_e32 v78, v79, v78
	v_div_scale_f32 v79, vcc, v60, v76, v60
	v_mul_f32_e32 v80, v79, v78
	v_fma_f32 v81, -v77, v80, v79
	v_fmac_f32_e32 v80, v81, v78
	v_fma_f32 v77, -v77, v80, v79
	v_div_fmas_f32 v77, v77, v78, v80
	v_div_fixup_f32 v60, v77, v76, v60
	v_mul_f32_e32 v76, 0xbfb8aa3b, v61
; __device__ __forceinline__ unsigned cvt_pk_bf16(float lo, float hi) { unsigned r; asm volatile("v_cvt_pk_bf16_f32 %0, %1, %2" : "=v"(r) : "v"(lo), "v"(hi)); return r; }
; __device__ __forceinline__ float bf_lo(unsigned w) { return __uint_as_float(w << 16); }
; __device__ __forceinline__ float bf_hi(unsigned w) { return __uint_as_float(w & 0xffff0000u); }
; __device__ __forceinline__ float silu_f(float v) { return v / (1.0f + __expf(-v)); }
;     __device__ __forceinline__ void operator()(const Acc& acc, const Unit& u, int wr, int wc, int fr, int fq) const {
;     ...
;                 for (int bj = 0; bj < 2; ++bj) { const u32x4 ov = bj == 0 ? o0 : o1; const unsigned ow[4] = {ov.x, ov.y, ov.z, ov.w}; unsigned r[4];
; #pragma unroll
;                     for (int p = 0; p < 4; ++p) { const f32x4 v = acc[ai][bj][m][p >> 1]; const float g0 = silu_f(v[(p & 1) * 2]), g1 = silu_f(v[(p & 1) * 2 + 1]);
;                         r[p] = cvt_pk_bf16(g0 * ((bf_lo(ow[p]) - mu) * rstd), g1 * ((bf_hi(ow[p]) - mu) * rstd)); }
;                     *(u32x4*)(U + off + bj * HALF) = (u32x4){r[0], r[1], r[2], r[3]}; }
	v_exp_f32_e32 v76, v76
	s_nop 0
	v_add_f32_e32 v76, 1.0, v76
	v_div_scale_f32 v77, s[0:1], v76, v76, v61
	v_rcp_f32_e32 v78, v77
	s_nop 0
	v_fma_f32 v79, -v77, v78, 1.0
	v_fmac_f32_e32 v78, v79, v78
	v_div_scale_f32 v79, vcc, v61, v76, v61
	v_mul_f32_e32 v80, v79, v78
	v_fma_f32 v81, -v77, v80, v79
	v_fmac_f32_e32 v80, v81, v78
	v_fma_f32 v77, -v77, v80, v79
	v_div_fmas_f32 v77, v77, v78, v80
	v_div_fixup_f32 v61, v77, v76, v61
	v_lshlrev_b32_e32 v76, 16, v68
	v_and_b32_e32 v68, 0xffff0000, v68
	v_sub_f32_e32 v76, v76, v73
	v_sub_f32_e32 v68, v68, v73
	v_mul_f32_e32 v76, v76, v72
	v_mul_f32_e32 v68, v68, v72
	v_mul_f32_e32 v60, v60, v76
	v_mul_f32_e32 v61, v61, v68
	v_cvt_pk_bf16_f32 v60, v60, v61
	v_mul_f32_e32 v61, 0xbfb8aa3b, v62
	v_exp_f32_e32 v61, v61
	s_nop 0
	v_add_f32_e32 v61, 1.0, v61
	v_div_scale_f32 v68, s[0:1], v61, v61, v62
	v_rcp_f32_e32 v76, v68
	s_nop 0
	v_fma_f32 v77, -v68, v76, 1.0
	v_fmac_f32_e32 v76, v77, v76
	v_div_scale_f32 v77, vcc, v62, v61, v62
	v_mul_f32_e32 v78, v77, v76
	v_fma_f32 v79, -v68, v78, v77
	v_fmac_f32_e32 v78, v79, v76
	v_fma_f32 v68, -v68, v78, v77
	v_div_fmas_f32 v68, v68, v76, v78
	v_div_fixup_f32 v61, v68, v61, v62
	v_mul_f32_e32 v62, 0xbfb8aa3b, v63
	v_exp_f32_e32 v62, v62
	s_nop 0
	v_add_f32_e32 v62, 1.0, v62
	v_div_scale_f32 v68, s[0:1], v62, v62, v63
	v_rcp_f32_e32 v76, v68
	s_nop 0
	v_fma_f32 v77, -v68, v76, 1.0
	v_fmac_f32_e32 v76, v77, v76
	v_div_scale_f32 v77, vcc, v63, v62, v63
	v_mul_f32_e32 v78, v77, v76
	v_fma_f32 v79, -v68, v78, v77
	v_fmac_f32_e32 v78, v79, v76
	v_fma_f32 v68, -v68, v78, v77
	v_div_fmas_f32 v68, v68, v76, v78
	v_div_fixup_f32 v62, v68, v62, v63
	v_lshlrev_b32_e32 v63, 16, v69
	v_sub_f32_e32 v63, v63, v73
	v_mul_f32_e32 v63, v63, v72
	v_mul_f32_e32 v61, v61, v63
	v_and_b32_e32 v63, 0xffff0000, v69
	v_sub_f32_e32 v63, v63, v73
	v_mul_f32_e32 v63, v63, v72
	v_mul_f32_e32 v62, v62, v63
	v_cvt_pk_bf16_f32 v61, v61, v62
	v_mul_f32_e32 v62, 0xbfb8aa3b, v56
	v_exp_f32_e32 v62, v62
	s_nop 0
	v_add_f32_e32 v62, 1.0, v62
	v_div_scale_f32 v63, s[0:1], v62, v62, v56
	v_rcp_f32_e32 v68, v63
	s_nop 0
	v_fma_f32 v69, -v63, v68, 1.0
	v_fmac_f32_e32 v68, v69, v68
	v_div_scale_f32 v69, vcc, v56, v62, v56
	v_mul_f32_e32 v76, v69, v68
	v_fma_f32 v77, -v63, v76, v69
	v_fmac_f32_e32 v76, v77, v68
	v_fma_f32 v63, -v63, v76, v69
	v_div_fmas_f32 v63, v63, v68, v76
	v_div_fixup_f32 v56, v63, v62, v56
	v_mul_f32_e32 v62, 0xbfb8aa3b, v57
	v_exp_f32_e32 v62, v62
	s_nop 0
	v_add_f32_e32 v62, 1.0, v62
	v_div_scale_f32 v63, s[0:1], v62, v62, v57
	v_rcp_f32_e32 v68, v63
	s_nop 0
	v_fma_f32 v69, -v63, v68, 1.0
	v_fmac_f32_e32 v68, v69, v68
	v_div_scale_f32 v69, vcc, v57, v62, v57
	v_mul_f32_e32 v76, v69, v68
	v_fma_f32 v77, -v63, v76, v69
	v_fmac_f32_e32 v76, v77, v68
	v_fma_f32 v63, -v63, v76, v69
	v_div_fmas_f32 v63, v63, v68, v76
	v_div_fixup_f32 v57, v63, v62, v57
	v_lshlrev_b32_e32 v62, 16, v70
	v_sub_f32_e32 v62, v62, v73
	v_mul_f32_e32 v62, v62, v72
	v_mul_f32_e32 v56, v56, v62
	v_and_b32_e32 v62, 0xffff0000, v70
	v_sub_f32_e32 v62, v62, v73
	v_mul_f32_e32 v62, v62, v72
	v_mul_f32_e32 v57, v57, v62
	v_cvt_pk_bf16_f32 v62, v56, v57
	v_mul_f32_e32 v56, 0xbfb8aa3b, v58
	v_exp_f32_e32 v56, v56
	s_nop 0
	v_add_f32_e32 v56, 1.0, v56
	v_div_scale_f32 v57, s[0:1], v56, v56, v58
	v_rcp_f32_e32 v63, v57
	s_nop 0
	v_fma_f32 v68, -v57, v63, 1.0
	v_fmac_f32_e32 v63, v68, v63
	v_div_scale_f32 v68, vcc, v58, v56, v58
	v_mul_f32_e32 v69, v68, v63
	v_fma_f32 v70, -v57, v69, v68
	v_fmac_f32_e32 v69, v70, v63
	v_fma_f32 v57, -v57, v69, v68
	v_div_fmas_f32 v57, v57, v63, v69
	v_div_fixup_f32 v56, v57, v56, v58
	v_mul_f32_e32 v57, 0xbfb8aa3b, v59
	v_exp_f32_e32 v57, v57
	s_nop 0
	v_add_f32_e32 v57, 1.0, v57
	v_div_scale_f32 v58, s[0:1], v57, v57, v59
	v_rcp_f32_e32 v63, v58
	s_nop 0
	v_fma_f32 v68, -v58, v63, 1.0
	v_fmac_f32_e32 v63, v68, v63
	v_div_scale_f32 v68, vcc, v59, v57, v59
	v_mul_f32_e32 v69, v68, v63
	v_fma_f32 v70, -v58, v69, v68
	v_fmac_f32_e32 v69, v70, v63
	v_fma_f32 v58, -v58, v69, v68
	v_div_fmas_f32 v58, v58, v63, v69
	v_div_fixup_f32 v57, v58, v57, v59
	v_lshlrev_b32_e32 v58, 16, v71
	v_sub_f32_e32 v58, v58, v73
	v_mul_f32_e32 v58, v58, v72
	v_mul_f32_e32 v56, v56, v58
	v_and_b32_e32 v58, 0xffff0000, v71
	v_sub_f32_e32 v58, v58, v73
	v_mul_f32_e32 v58, v58, v72
	v_mul_f32_e32 v57, v57, v58
	v_mul_f32_e32 v58, 0xbfb8aa3b, v52
	v_exp_f32_e32 v58, v58
	v_cvt_pk_bf16_f32 v63, v56, v57
	v_lshl_add_u64 v[56:57], s[6:7], 0, v[74:75]
	global_store_dwordx4 v[56:57], v[60:63], off
	v_add_f32_e32 v58, 1.0, v58
	v_div_scale_f32 v59, s[0:1], v58, v58, v52
	v_rcp_f32_e32 v60, v59
	s_nop 0
	v_fma_f32 v61, -v59, v60, 1.0
	v_fmac_f32_e32 v60, v61, v60
	v_div_scale_f32 v61, vcc, v52, v58, v52
	v_mul_f32_e32 v62, v61, v60
	v_fma_f32 v63, -v59, v62, v61
	v_fmac_f32_e32 v62, v63, v60
	v_fma_f32 v59, -v59, v62, v61
	v_div_fmas_f32 v59, v59, v60, v62
	v_div_fixup_f32 v52, v59, v58, v52
	v_mul_f32_e32 v58, 0xbfb8aa3b, v53
	v_exp_f32_e32 v58, v58
	s_nop 0
	v_add_f32_e32 v58, 1.0, v58
	v_div_scale_f32 v59, s[0:1], v58, v58, v53
	v_rcp_f32_e32 v60, v59
	s_nop 0
	v_fma_f32 v61, -v59, v60, 1.0
	v_fmac_f32_e32 v60, v61, v60
	v_div_scale_f32 v61, vcc, v53, v58, v53
	v_mul_f32_e32 v62, v61, v60
	v_fma_f32 v63, -v59, v62, v61
	v_fmac_f32_e32 v62, v63, v60
	v_fma_f32 v59, -v59, v62, v61
	v_div_fmas_f32 v59, v59, v60, v62
	v_div_fixup_f32 v53, v59, v58, v53
	v_lshlrev_b32_e32 v58, 16, v64
	v_sub_f32_e32 v58, v58, v73
	v_mul_f32_e32 v58, v58, v72
	v_mul_f32_e32 v52, v52, v58
	v_and_b32_e32 v58, 0xffff0000, v64
	v_sub_f32_e32 v58, v58, v73
	v_mul_f32_e32 v58, v58, v72
	v_mul_f32_e32 v53, v53, v58
	v_cvt_pk_bf16_f32 v52, v52, v53
; __device__ __forceinline__ unsigned cvt_pk_bf16(float lo, float hi) { unsigned r; asm volatile("v_cvt_pk_bf16_f32 %0, %1, %2" : "=v"(r) : "v"(lo), "v"(hi)); return r; }
; __device__ __forceinline__ float bf_lo(unsigned w) { return __uint_as_float(w << 16); }
; __device__ __forceinline__ float bf_hi(unsigned w) { return __uint_as_float(w & 0xffff0000u); }
;     __device__ __forceinline__ void operator()(const Acc& acc, const Unit& u, int wr, int wc, int fr, int fq) const {
;     ...
;             for (int m = 0; m < 4; ++m) {
;                 const int row_in = ai * HALF + wr * 64 + m * 16 + fr, s = u.pm * BM + row_in;
;                 const f32x4 tq = ((const f32x4*)(stats + ((size_t)s * 8 + h) * 8))[fq];
;                 const size_t off = (size_t)s * RV + u.pn * BM + wc * 32 + 8 * fq;
;                 const u32x4 o0 = *(const u32x4*)(O + off), o1 = *(const u32x4*)(O + off + HALF);
;                 float s1 = tq[0] + tq[2], s2 = tq[1] + tq[3];
;                 { const auto r1 = __builtin_amdgcn_permlane16_swap(__float_as_uint(s1), __float_as_uint(s1), false, false); s1 = __uint_as_float(r1[0]) + __uint_as_float(r1[1]);
;                   const auto r2 = __builtin_amdgcn_permlane16_swap(__float_as_uint(s2), __float_as_uint(s2), false, false); s2 = __uint_as_float(r2[0]) + __uint_as_float(r2[1]);
;                   const auto r3 = __builtin_amdgcn_permlane32_swap(__float_as_uint(s1), __float_as_uint(s1), false, false); s1 = __uint_as_float(r3[0]) + __uint_as_float(r3[1]);
;                   const auto r4 = __builtin_amdgcn_permlane32_swap(__float_as_uint(s2), __float_as_uint(s2), false, false); s2 = __uint_as_float(r4[0]) + __uint_as_float(r4[1]); }
;                 const float mu = s1 * (1.0f / 512.0f), var = fmaxf(s2 * (1.0f / 512.0f) - mu * mu, 0.f), rstd = rsqrtf(var + EPS);
; #pragma unroll
;                 for (int bj = 0; bj < 2; ++bj) { const u32x4 ov = bj == 0 ? o0 : o1; const unsigned ow[4] = {ov.x, ov.y, ov.z, ov.w}; unsigned r[4];
; #pragma unroll
;                     for (int p = 0; p < 4; ++p) { const f32x4 v = acc[ai][bj][m][p >> 1]; const float g0 = silu_f(v[(p & 1) * 2]), g1 = silu_f(v[(p & 1) * 2 + 1]);
;                         r[p] = cvt_pk_bf16(g0 * ((bf_lo(ow[p]) - mu) * rstd), g1 * ((bf_hi(ow[p]) - mu) * rstd)); }
;                     *(u32x4*)(U + off + bj * HALF) = (u32x4){r[0], r[1], r[2], r[3]}; }
	v_mul_f32_e32 v53, 0xbfb8aa3b, v54
	v_exp_f32_e32 v53, v53
	s_nop 0
	v_add_f32_e32 v53, 1.0, v53
	v_div_scale_f32 v58, s[0:1], v53, v53, v54
	v_rcp_f32_e32 v59, v58
	s_nop 0
	v_fma_f32 v60, -v58, v59, 1.0
	v_fmac_f32_e32 v59, v60, v59
	v_div_scale_f32 v60, vcc, v54, v53, v54
	v_mul_f32_e32 v61, v60, v59
	v_fma_f32 v62, -v58, v61, v60
	v_fmac_f32_e32 v61, v62, v59
	v_fma_f32 v58, -v58, v61, v60
	v_div_fmas_f32 v58, v58, v59, v61
	v_div_fixup_f32 v53, v58, v53, v54
	v_mul_f32_e32 v54, 0xbfb8aa3b, v55
	v_exp_f32_e32 v54, v54
	s_nop 0
	v_add_f32_e32 v54, 1.0, v54
	v_div_scale_f32 v58, s[0:1], v54, v54, v55
	v_rcp_f32_e32 v59, v58
	s_nop 0
	v_fma_f32 v60, -v58, v59, 1.0
	v_fmac_f32_e32 v59, v60, v59
	v_div_scale_f32 v60, vcc, v55, v54, v55
	v_mul_f32_e32 v61, v60, v59
	v_fma_f32 v62, -v58, v61, v60
	v_fmac_f32_e32 v61, v62, v59
	v_fma_f32 v58, -v58, v61, v60
	v_div_fmas_f32 v58, v58, v59, v61
	v_div_fixup_f32 v54, v58, v54, v55
	v_lshlrev_b32_e32 v55, 16, v65
	v_sub_f32_e32 v55, v55, v73
	v_mul_f32_e32 v55, v55, v72
	v_mul_f32_e32 v53, v53, v55
	v_and_b32_e32 v55, 0xffff0000, v65
	v_sub_f32_e32 v55, v55, v73
	v_mul_f32_e32 v55, v55, v72
	v_mul_f32_e32 v54, v54, v55
	v_cvt_pk_bf16_f32 v53, v53, v54
	v_mul_f32_e32 v54, 0xbfb8aa3b, v48
	v_exp_f32_e32 v54, v54
	s_nop 0
	v_add_f32_e32 v54, 1.0, v54
	v_div_scale_f32 v55, s[0:1], v54, v54, v48
	v_rcp_f32_e32 v58, v55
	s_nop 0
	v_fma_f32 v59, -v55, v58, 1.0
	v_fmac_f32_e32 v58, v59, v58
	v_div_scale_f32 v59, vcc, v48, v54, v48
	v_mul_f32_e32 v60, v59, v58
	v_fma_f32 v61, -v55, v60, v59
	v_fmac_f32_e32 v60, v61, v58
	v_fma_f32 v55, -v55, v60, v59
	v_div_fmas_f32 v55, v55, v58, v60
	v_div_fixup_f32 v48, v55, v54, v48
	v_mul_f32_e32 v54, 0xbfb8aa3b, v49
	v_exp_f32_e32 v54, v54
	s_nop 0
	v_add_f32_e32 v54, 1.0, v54
	v_div_scale_f32 v55, s[0:1], v54, v54, v49
	v_rcp_f32_e32 v58, v55
	s_nop 0
	v_fma_f32 v59, -v55, v58, 1.0
	v_fmac_f32_e32 v58, v59, v58
	v_div_scale_f32 v59, vcc, v49, v54, v49
	v_mul_f32_e32 v60, v59, v58
	v_fma_f32 v61, -v55, v60, v59
	v_fmac_f32_e32 v60, v61, v58
	v_fma_f32 v55, -v55, v60, v59
	v_div_fmas_f32 v55, v55, v58, v60
	v_div_fixup_f32 v49, v55, v54, v49
	v_lshlrev_b32_e32 v54, 16, v66
	v_sub_f32_e32 v54, v54, v73
	v_mul_f32_e32 v54, v54, v72
	v_mul_f32_e32 v48, v48, v54
	v_and_b32_e32 v54, 0xffff0000, v66
	v_sub_f32_e32 v54, v54, v73
	v_mul_f32_e32 v54, v54, v72
	v_mul_f32_e32 v49, v49, v54
	v_cvt_pk_bf16_f32 v54, v48, v49
	v_mul_f32_e32 v48, 0xbfb8aa3b, v50
	v_exp_f32_e32 v48, v48
	s_nop 0
	v_add_f32_e32 v48, 1.0, v48
	v_div_scale_f32 v49, s[0:1], v48, v48, v50
	v_rcp_f32_e32 v55, v49
	s_nop 0
	v_fma_f32 v58, -v49, v55, 1.0
	v_fmac_f32_e32 v55, v58, v55
	v_div_scale_f32 v58, vcc, v50, v48, v50
	v_mul_f32_e32 v59, v58, v55
	v_fma_f32 v60, -v49, v59, v58
	v_fmac_f32_e32 v59, v60, v55
	v_fma_f32 v49, -v49, v59, v58
	v_div_fmas_f32 v49, v49, v55, v59
	v_div_fixup_f32 v48, v49, v48, v50
	v_mul_f32_e32 v49, 0xbfb8aa3b, v51
	v_exp_f32_e32 v49, v49
	s_nop 0
	v_add_f32_e32 v49, 1.0, v49
	v_div_scale_f32 v50, s[0:1], v49, v49, v51
	v_rcp_f32_e32 v55, v50
	s_nop 0
	v_fma_f32 v58, -v50, v55, 1.0
	v_fmac_f32_e32 v55, v58, v55
	v_div_scale_f32 v58, vcc, v51, v49, v51
	v_mul_f32_e32 v59, v58, v55
	v_fma_f32 v60, -v50, v59, v58
	v_fmac_f32_e32 v59, v60, v55
	v_fma_f32 v50, -v50, v59, v58
	v_div_fmas_f32 v50, v50, v55, v59
	v_div_fixup_f32 v49, v50, v49, v51
	v_lshlrev_b32_e32 v50, 16, v67
	v_sub_f32_e32 v50, v50, v73
	v_mul_f32_e32 v50, v50, v72
	v_mul_f32_e32 v48, v48, v50
	v_and_b32_e32 v50, 0xffff0000, v67
	v_sub_f32_e32 v50, v50, v73
	v_mul_f32_e32 v50, v50, v72
	v_mul_f32_e32 v49, v49, v50
	v_cvt_pk_bf16_f32 v55, v48, v49
	v_add_u32_e32 v48, 0x90, v162
	v_ashrrev_i32_e32 v49, 31, v48
	v_lshlrev_b64 v[50:51], 9, v[48:49]
	v_lshl_add_u64 v[50:51], s[2:3], 0, v[50:51]
	v_lshl_add_u64 v[50:51], v[50:51], 0, s[48:49]
	global_store_dwordx4 v[56:57], v[52:55], off offset:256
	v_lshl_add_u64 v[50:51], v[50:51], 0, v[166:167]
	v_lshlrev_b64 v[48:49], 12, v[48:49]
	v_lshl_add_u64 v[48:49], v[48:49], 0, v[164:165]
	v_lshlrev_b64 v[58:59], 1, v[48:49]
	v_lshl_add_u64 v[48:49], s[4:5], 0, v[58:59]
	s_waitcnt vmcnt(2)
	v_mov_b32_e32 v60, v204
	v_mov_b32_e32 v61, v205
	v_mov_b32_e32 v62, v206
	v_mov_b32_e32 v63, v207
	v_mov_b32_e32 v52, v208
	v_mov_b32_e32 v53, v209
	v_mov_b32_e32 v54, v210
	v_mov_b32_e32 v55, v211
	v_mov_b32_e32 v48, v212
	v_mov_b32_e32 v49, v213
	v_mov_b32_e32 v50, v214
	v_mov_b32_e32 v51, v215
	v_add_u32_e32 v216, 0xa0, v162
	v_ashrrev_i32_e32 v217, 31, v216
	v_lshlrev_b64 v[218:219], 9, v[216:217]
	v_lshl_add_u64 v[218:219], s[2:3], 0, v[218:219]
	v_lshl_add_u64 v[218:219], v[218:219], 0, s[48:49]
	v_lshl_add_u64 v[218:219], v[218:219], 0, v[166:167]
	global_load_dwordx4 v[192:195], v[218:219], off
	v_lshlrev_b64 v[216:217], 12, v[216:217]
	v_lshl_add_u64 v[216:217], v[216:217], 0, v[164:165]
	v_lshlrev_b64 v[216:217], 1, v[216:217]
	v_lshl_add_u64 v[216:217], s[4:5], 0, v[216:217]
	global_load_dwordx4 v[196:199], v[216:217], off
	global_load_dwordx4 v[200:203], v[216:217], off offset:256
	v_add_f32_e32 v56, v60, v62
	v_mov_b32_e32 v57, v56
	v_add_f32_e32 v60, v61, v63
	s_nop 0
	v_permlane16_swap_b32_e32 v56, v57
	v_add_f32_e32 v57, v56, v57
	v_mov_b32_e32 v56, v60
	s_nop 1
	v_permlane16_swap_b32_e32 v60, v56
	v_add_f32_e32 v56, v60, v56
	v_mov_b32_e32 v61, v57
	v_mov_b32_e32 v60, v56
	s_nop 0
	v_permlane32_swap_b32_e32 v57, v61
	v_permlane32_swap_b32_e32 v56, v60
	v_pk_add_f32 v[56:57], v[56:57], v[60:61]
	s_nop 0
	v_pk_mul_f32 v[56:57], v[56:57], s[8:9] op_sel_hi:[1,0]
	s_nop 0
	v_fma_f32 v56, -v57, v57, v56
	v_max_f32_e32 v56, 0, v56
	v_add_f32_e32 v56, 0x358637bd, v56
; __device__ __forceinline__ unsigned cvt_pk_bf16(float lo, float hi) { unsigned r; asm volatile("v_cvt_pk_bf16_f32 %0, %1, %2" : "=v"(r) : "v"(lo), "v"(hi)); return r; }
; __device__ __forceinline__ float bf_lo(unsigned w) { return __uint_as_float(w << 16); }
; __device__ __forceinline__ float bf_hi(unsigned w) { return __uint_as_float(w & 0xffff0000u); }
; __device__ __forceinline__ float silu_f(float v) { return v / (1.0f + __expf(-v)); }
;     __device__ __forceinline__ void operator()(const Acc& acc, const Unit& u, int wr, int wc, int fr, int fq) const {
;     ...
;                 for (int bj = 0; bj < 2; ++bj) { const u32x4 ov = bj == 0 ? o0 : o1; const unsigned ow[4] = {ov.x, ov.y, ov.z, ov.w}; unsigned r[4];
; #pragma unroll
;                     for (int p = 0; p < 4; ++p) { const f32x4 v = acc[ai][bj][m][p >> 1]; const float g0 = silu_f(v[(p & 1) * 2]), g1 = silu_f(v[(p & 1) * 2 + 1]);
;                         r[p] = cvt_pk_bf16(g0 * ((bf_lo(ow[p]) - mu) * rstd), g1 * ((bf_hi(ow[p]) - mu) * rstd)); }
;                     *(u32x4*)(U + off + bj * HALF) = (u32x4){r[0], r[1], r[2], r[3]}; }
	v_cmp_gt_f32_e32 vcc, s73, v56
	v_mul_f32_e32 v60, 0x4b800000, v56
	s_nop 0
	v_cndmask_b32_e32 v56, v56, v60, vcc
	v_rsq_f32_e32 v56, v56
	s_nop 0
	v_mul_f32_e32 v60, 0x45800000, v56
	v_cndmask_b32_e32 v56, v56, v60, vcc
	v_mul_f32_e32 v60, 0xbfb8aa3b, v44
	v_exp_f32_e32 v60, v60
	s_nop 0
	v_add_f32_e32 v60, 1.0, v60
	v_div_scale_f32 v61, s[0:1], v60, v60, v44
	v_rcp_f32_e32 v62, v61
	s_nop 0
	v_fma_f32 v63, -v61, v62, 1.0
	v_fmac_f32_e32 v62, v63, v62
	v_div_scale_f32 v63, vcc, v44, v60, v44
	v_mul_f32_e32 v64, v63, v62
	v_fma_f32 v65, -v61, v64, v63
	v_fmac_f32_e32 v64, v65, v62
	v_fma_f32 v61, -v61, v64, v63
	v_div_fmas_f32 v61, v61, v62, v64
	v_div_fixup_f32 v44, v61, v60, v44
	v_mul_f32_e32 v60, 0xbfb8aa3b, v45
	v_exp_f32_e32 v60, v60
	s_nop 0
	v_add_f32_e32 v60, 1.0, v60
	v_div_scale_f32 v61, s[0:1], v60, v60, v45
	v_rcp_f32_e32 v62, v61
	s_nop 0
	v_fma_f32 v63, -v61, v62, 1.0
	v_fmac_f32_e32 v62, v63, v62
	v_div_scale_f32 v63, vcc, v45, v60, v45
	v_mul_f32_e32 v64, v63, v62
	v_fma_f32 v65, -v61, v64, v63
	v_fmac_f32_e32 v64, v65, v62
	v_fma_f32 v61, -v61, v64, v63
	v_div_fmas_f32 v61, v61, v62, v64
	v_div_fixup_f32 v45, v61, v60, v45
	v_lshlrev_b32_e32 v60, 16, v52
	v_and_b32_e32 v52, 0xffff0000, v52
	v_sub_f32_e32 v60, v60, v57
	v_sub_f32_e32 v52, v52, v57
	v_mul_f32_e32 v60, v60, v56
	v_mul_f32_e32 v52, v52, v56
	v_mul_f32_e32 v44, v44, v60
	v_mul_f32_e32 v45, v45, v52
	v_cvt_pk_bf16_f32 v44, v44, v45
	v_mul_f32_e32 v45, 0xbfb8aa3b, v46
	v_exp_f32_e32 v45, v45
	s_nop 0
	v_add_f32_e32 v45, 1.0, v45
	v_div_scale_f32 v52, s[0:1], v45, v45, v46
	v_rcp_f32_e32 v60, v52
	s_nop 0
	v_fma_f32 v61, -v52, v60, 1.0
	v_fmac_f32_e32 v60, v61, v60
	v_div_scale_f32 v61, vcc, v46, v45, v46
	v_mul_f32_e32 v62, v61, v60
	v_fma_f32 v63, -v52, v62, v61
	v_fmac_f32_e32 v62, v63, v60
	v_fma_f32 v52, -v52, v62, v61
	v_div_fmas_f32 v52, v52, v60, v62
	v_div_fixup_f32 v45, v52, v45, v46
	v_mul_f32_e32 v46, 0xbfb8aa3b, v47
	v_exp_f32_e32 v46, v46
	s_nop 0
	v_add_f32_e32 v46, 1.0, v46
	v_div_scale_f32 v52, s[0:1], v46, v46, v47
	v_rcp_f32_e32 v60, v52
	s_nop 0
	v_fma_f32 v61, -v52, v60, 1.0
	v_fmac_f32_e32 v60, v61, v60
	v_div_scale_f32 v61, vcc, v47, v46, v47
	v_mul_f32_e32 v62, v61, v60
	v_fma_f32 v63, -v52, v62, v61
	v_fmac_f32_e32 v62, v63, v60
	v_fma_f32 v52, -v52, v62, v61
	v_div_fmas_f32 v52, v52, v60, v62
	v_div_fixup_f32 v46, v52, v46, v47
	v_lshlrev_b32_e32 v47, 16, v53
	v_sub_f32_e32 v47, v47, v57
	v_mul_f32_e32 v47, v47, v56
	v_mul_f32_e32 v45, v45, v47
	v_and_b32_e32 v47, 0xffff0000, v53
	v_sub_f32_e32 v47, v47, v57
	v_mul_f32_e32 v47, v47, v56
	v_mul_f32_e32 v46, v46, v47
	v_cvt_pk_bf16_f32 v45, v45, v46
	v_mul_f32_e32 v46, 0xbfb8aa3b, v40
	v_exp_f32_e32 v46, v46
	s_nop 0
	v_add_f32_e32 v46, 1.0, v46
	v_div_scale_f32 v47, s[0:1], v46, v46, v40
	v_rcp_f32_e32 v52, v47
	s_nop 0
	v_fma_f32 v53, -v47, v52, 1.0
	v_fmac_f32_e32 v52, v53, v52
	v_div_scale_f32 v53, vcc, v40, v46, v40
	v_mul_f32_e32 v60, v53, v52
	v_fma_f32 v61, -v47, v60, v53
	v_fmac_f32_e32 v60, v61, v52
	v_fma_f32 v47, -v47, v60, v53
	v_div_fmas_f32 v47, v47, v52, v60
	v_div_fixup_f32 v40, v47, v46, v40
	v_mul_f32_e32 v46, 0xbfb8aa3b, v41
	v_exp_f32_e32 v46, v46
	s_nop 0
	v_add_f32_e32 v46, 1.0, v46
	v_div_scale_f32 v47, s[0:1], v46, v46, v41
	v_rcp_f32_e32 v52, v47
	s_nop 0
	v_fma_f32 v53, -v47, v52, 1.0
	v_fmac_f32_e32 v52, v53, v52
	v_div_scale_f32 v53, vcc, v41, v46, v41
	v_mul_f32_e32 v60, v53, v52
	v_fma_f32 v61, -v47, v60, v53
	v_fmac_f32_e32 v60, v61, v52
	v_fma_f32 v47, -v47, v60, v53
	v_div_fmas_f32 v47, v47, v52, v60
	v_div_fixup_f32 v41, v47, v46, v41
	v_lshlrev_b32_e32 v46, 16, v54
	v_sub_f32_e32 v46, v46, v57
	v_mul_f32_e32 v46, v46, v56
	v_mul_f32_e32 v40, v40, v46
	v_and_b32_e32 v46, 0xffff0000, v54
	v_sub_f32_e32 v46, v46, v57
	v_mul_f32_e32 v46, v46, v56
	v_mul_f32_e32 v41, v41, v46
	v_cvt_pk_bf16_f32 v46, v40, v41
	v_mul_f32_e32 v40, 0xbfb8aa3b, v42
	v_exp_f32_e32 v40, v40
	s_nop 0
	v_add_f32_e32 v40, 1.0, v40
	v_div_scale_f32 v41, s[0:1], v40, v40, v42
	v_rcp_f32_e32 v47, v41
	s_nop 0
	v_fma_f32 v52, -v41, v47, 1.0
	v_fmac_f32_e32 v47, v52, v47
	v_div_scale_f32 v52, vcc, v42, v40, v42
	v_mul_f32_e32 v53, v52, v47
	v_fma_f32 v54, -v41, v53, v52
	v_fmac_f32_e32 v53, v54, v47
	v_fma_f32 v41, -v41, v53, v52
	v_div_fmas_f32 v41, v41, v47, v53
	v_div_fixup_f32 v40, v41, v40, v42
	v_mul_f32_e32 v41, 0xbfb8aa3b, v43
	v_exp_f32_e32 v41, v41
	s_nop 0
	v_add_f32_e32 v41, 1.0, v41
	v_div_scale_f32 v42, s[0:1], v41, v41, v43
	v_rcp_f32_e32 v47, v42
	s_nop 0
	v_fma_f32 v52, -v42, v47, 1.0
	v_fmac_f32_e32 v47, v52, v47
	v_div_scale_f32 v52, vcc, v43, v41, v43
	v_mul_f32_e32 v53, v52, v47
	v_fma_f32 v54, -v42, v53, v52
	v_fmac_f32_e32 v53, v54, v47
	v_fma_f32 v42, -v42, v53, v52
	v_div_fmas_f32 v42, v42, v47, v53
	v_div_fixup_f32 v41, v42, v41, v43
	v_lshlrev_b32_e32 v42, 16, v55
	v_sub_f32_e32 v42, v42, v57
	v_mul_f32_e32 v42, v42, v56
	v_mul_f32_e32 v40, v40, v42
	v_and_b32_e32 v42, 0xffff0000, v55
	v_sub_f32_e32 v42, v42, v57
	v_mul_f32_e32 v42, v42, v56
	v_mul_f32_e32 v41, v41, v42
	v_mul_f32_e32 v42, 0xbfb8aa3b, v36
	v_exp_f32_e32 v42, v42
	v_cvt_pk_bf16_f32 v47, v40, v41
	v_lshl_add_u64 v[40:41], s[6:7], 0, v[58:59]
	global_store_dwordx4 v[40:41], v[44:47], off
	v_add_f32_e32 v42, 1.0, v42
	v_div_scale_f32 v43, s[0:1], v42, v42, v36
	v_rcp_f32_e32 v44, v43
	s_nop 0
	v_fma_f32 v45, -v43, v44, 1.0
	v_fmac_f32_e32 v44, v45, v44
	v_div_scale_f32 v45, vcc, v36, v42, v36
	v_mul_f32_e32 v46, v45, v44
	v_fma_f32 v47, -v43, v46, v45
	v_fmac_f32_e32 v46, v47, v44
	v_fma_f32 v43, -v43, v46, v45
	v_div_fmas_f32 v43, v43, v44, v46
	v_div_fixup_f32 v36, v43, v42, v36
; __device__ __forceinline__ unsigned cvt_pk_bf16(float lo, float hi) { unsigned r; asm volatile("v_cvt_pk_bf16_f32 %0, %1, %2" : "=v"(r) : "v"(lo), "v"(hi)); return r; }
; __device__ __forceinline__ float bf_lo(unsigned w) { return __uint_as_float(w << 16); }
; __device__ __forceinline__ float bf_hi(unsigned w) { return __uint_as_float(w & 0xffff0000u); }
; __device__ __forceinline__ float silu_f(float v) { return v / (1.0f + __expf(-v)); }
;     __device__ __forceinline__ void operator()(const Acc& acc, const Unit& u, int wr, int wc, int fr, int fq) const {
;     ...
;                 for (int bj = 0; bj < 2; ++bj) { const u32x4 ov = bj == 0 ? o0 : o1; const unsigned ow[4] = {ov.x, ov.y, ov.z, ov.w}; unsigned r[4];
; #pragma unroll
;                     for (int p = 0; p < 4; ++p) { const f32x4 v = acc[ai][bj][m][p >> 1]; const float g0 = silu_f(v[(p & 1) * 2]), g1 = silu_f(v[(p & 1) * 2 + 1]);
;                         r[p] = cvt_pk_bf16(g0 * ((bf_lo(ow[p]) - mu) * rstd), g1 * ((bf_hi(ow[p]) - mu) * rstd)); }
;                     *(u32x4*)(U + off + bj * HALF) = (u32x4){r[0], r[1], r[2], r[3]}; }
	v_mul_f32_e32 v42, 0xbfb8aa3b, v37
	v_exp_f32_e32 v42, v42
	s_nop 0
	v_add_f32_e32 v42, 1.0, v42
	v_div_scale_f32 v43, s[0:1], v42, v42, v37
	v_rcp_f32_e32 v44, v43
	s_nop 0
	v_fma_f32 v45, -v43, v44, 1.0
	v_fmac_f32_e32 v44, v45, v44
	v_div_scale_f32 v45, vcc, v37, v42, v37
	v_mul_f32_e32 v46, v45, v44
	v_fma_f32 v47, -v43, v46, v45
	v_fmac_f32_e32 v46, v47, v44
	v_fma_f32 v43, -v43, v46, v45
	v_div_fmas_f32 v43, v43, v44, v46
	v_div_fixup_f32 v37, v43, v42, v37
	v_lshlrev_b32_e32 v42, 16, v48
	v_sub_f32_e32 v42, v42, v57
	v_mul_f32_e32 v42, v42, v56
	v_mul_f32_e32 v36, v36, v42
	v_and_b32_e32 v42, 0xffff0000, v48
	v_sub_f32_e32 v42, v42, v57
	v_mul_f32_e32 v42, v42, v56
	v_mul_f32_e32 v37, v37, v42
	v_cvt_pk_bf16_f32 v36, v36, v37
	v_mul_f32_e32 v37, 0xbfb8aa3b, v38
	v_exp_f32_e32 v37, v37
	s_nop 0
	v_add_f32_e32 v37, 1.0, v37
	v_div_scale_f32 v42, s[0:1], v37, v37, v38
	v_rcp_f32_e32 v43, v42
	s_nop 0
	v_fma_f32 v44, -v42, v43, 1.0
	v_fmac_f32_e32 v43, v44, v43
	v_div_scale_f32 v44, vcc, v38, v37, v38
	v_mul_f32_e32 v45, v44, v43
	v_fma_f32 v46, -v42, v45, v44
	v_fmac_f32_e32 v45, v46, v43
	v_fma_f32 v42, -v42, v45, v44
	v_div_fmas_f32 v42, v42, v43, v45
	v_div_fixup_f32 v37, v42, v37, v38
	v_mul_f32_e32 v38, 0xbfb8aa3b, v39
	v_exp_f32_e32 v38, v38
	s_nop 0
	v_add_f32_e32 v38, 1.0, v38
	v_div_scale_f32 v42, s[0:1], v38, v38, v39
	v_rcp_f32_e32 v43, v42
	s_nop 0
	v_fma_f32 v44, -v42, v43, 1.0
	v_fmac_f32_e32 v43, v44, v43
	v_div_scale_f32 v44, vcc, v39, v38, v39
	v_mul_f32_e32 v45, v44, v43
	v_fma_f32 v46, -v42, v45, v44
	v_fmac_f32_e32 v45, v46, v43
	v_fma_f32 v42, -v42, v45, v44
	v_div_fmas_f32 v42, v42, v43, v45
	v_div_fixup_f32 v38, v42, v38, v39
	v_lshlrev_b32_e32 v39, 16, v49
	v_sub_f32_e32 v39, v39, v57
	v_mul_f32_e32 v39, v39, v56
	v_mul_f32_e32 v37, v37, v39
	v_and_b32_e32 v39, 0xffff0000, v49
	v_sub_f32_e32 v39, v39, v57
	v_mul_f32_e32 v39, v39, v56
	v_mul_f32_e32 v38, v38, v39
	v_cvt_pk_bf16_f32 v37, v37, v38
	v_mul_f32_e32 v38, 0xbfb8aa3b, v32
	v_exp_f32_e32 v38, v38
	s_nop 0
	v_add_f32_e32 v38, 1.0, v38
	v_div_scale_f32 v39, s[0:1], v38, v38, v32
	v_rcp_f32_e32 v42, v39
	s_nop 0
	v_fma_f32 v43, -v39, v42, 1.0
	v_fmac_f32_e32 v42, v43, v42
	v_div_scale_f32 v43, vcc, v32, v38, v32
	v_mul_f32_e32 v44, v43, v42
	v_fma_f32 v45, -v39, v44, v43
	v_fmac_f32_e32 v44, v45, v42
	v_fma_f32 v39, -v39, v44, v43
	v_div_fmas_f32 v39, v39, v42, v44
	v_div_fixup_f32 v32, v39, v38, v32
	v_mul_f32_e32 v38, 0xbfb8aa3b, v33
	v_exp_f32_e32 v38, v38
	s_nop 0
	v_add_f32_e32 v38, 1.0, v38
	v_div_scale_f32 v39, s[0:1], v38, v38, v33
	v_rcp_f32_e32 v42, v39
	s_nop 0
	v_fma_f32 v43, -v39, v42, 1.0
	v_fmac_f32_e32 v42, v43, v42
	v_div_scale_f32 v43, vcc, v33, v38, v33
	v_mul_f32_e32 v44, v43, v42
	v_fma_f32 v45, -v39, v44, v43
	v_fmac_f32_e32 v44, v45, v42
	v_fma_f32 v39, -v39, v44, v43
	v_div_fmas_f32 v39, v39, v42, v44
	v_div_fixup_f32 v33, v39, v38, v33
	v_lshlrev_b32_e32 v38, 16, v50
	v_sub_f32_e32 v38, v38, v57
	v_mul_f32_e32 v38, v38, v56
	v_mul_f32_e32 v32, v32, v38
	v_and_b32_e32 v38, 0xffff0000, v50
	v_sub_f32_e32 v38, v38, v57
	v_mul_f32_e32 v38, v38, v56
	v_mul_f32_e32 v33, v33, v38
	v_cvt_pk_bf16_f32 v38, v32, v33
	v_mul_f32_e32 v32, 0xbfb8aa3b, v34
	v_exp_f32_e32 v32, v32
	s_nop 0
	v_add_f32_e32 v32, 1.0, v32
	v_div_scale_f32 v33, s[0:1], v32, v32, v34
	v_rcp_f32_e32 v39, v33
	s_nop 0
	v_fma_f32 v42, -v33, v39, 1.0
	v_fmac_f32_e32 v39, v42, v39
	v_div_scale_f32 v42, vcc, v34, v32, v34
	v_mul_f32_e32 v43, v42, v39
	v_fma_f32 v44, -v33, v43, v42
	v_fmac_f32_e32 v43, v44, v39
	v_fma_f32 v33, -v33, v43, v42
	v_div_fmas_f32 v33, v33, v39, v43
	v_div_fixup_f32 v32, v33, v32, v34
	v_mul_f32_e32 v33, 0xbfb8aa3b, v35
	v_exp_f32_e32 v33, v33
	s_nop 0
	v_add_f32_e32 v33, 1.0, v33
	v_div_scale_f32 v34, s[0:1], v33, v33, v35
	v_rcp_f32_e32 v39, v34
	s_nop 0
	v_fma_f32 v42, -v34, v39, 1.0
	v_fmac_f32_e32 v39, v42, v39
	v_div_scale_f32 v42, vcc, v35, v33, v35
	v_mul_f32_e32 v43, v42, v39
	v_fma_f32 v44, -v34, v43, v42
	v_fmac_f32_e32 v43, v44, v39
	v_fma_f32 v34, -v34, v43, v42
	v_div_fmas_f32 v34, v34, v39, v43
	v_div_fixup_f32 v33, v34, v33, v35
	v_lshlrev_b32_e32 v34, 16, v51
	v_sub_f32_e32 v34, v34, v57
	v_mul_f32_e32 v34, v34, v56
	v_mul_f32_e32 v32, v32, v34
	v_and_b32_e32 v34, 0xffff0000, v51
	v_sub_f32_e32 v34, v34, v57
	v_mul_f32_e32 v34, v34, v56
	v_mul_f32_e32 v33, v33, v34
	v_cvt_pk_bf16_f32 v39, v32, v33
	v_add_u32_e32 v32, 0xa0, v162
	v_ashrrev_i32_e32 v33, 31, v32
	v_lshlrev_b64 v[34:35], 9, v[32:33]
	v_lshl_add_u64 v[34:35], s[2:3], 0, v[34:35]
	v_lshl_add_u64 v[34:35], v[34:35], 0, s[48:49]
	global_store_dwordx4 v[40:41], v[36:39], off offset:256
	v_lshl_add_u64 v[34:35], v[34:35], 0, v[166:167]
	v_lshlrev_b64 v[32:33], 12, v[32:33]
	v_lshl_add_u64 v[32:33], v[32:33], 0, v[164:165]
	v_lshlrev_b64 v[42:43], 1, v[32:33]
	v_lshl_add_u64 v[32:33], s[4:5], 0, v[42:43]
	s_waitcnt vmcnt(2)
; __device__ __forceinline__ unsigned cvt_pk_bf16(float lo, float hi) { unsigned r; asm volatile("v_cvt_pk_bf16_f32 %0, %1, %2" : "=v"(r) : "v"(lo), "v"(hi)); return r; }
; __device__ __forceinline__ float bf_lo(unsigned w) { return __uint_as_float(w << 16); }
; __device__ __forceinline__ float bf_hi(unsigned w) { return __uint_as_float(w & 0xffff0000u); }
; __device__ __forceinline__ float silu_f(float v) { return v / (1.0f + __expf(-v)); }
;     __device__ __forceinline__ void operator()(const Acc& acc, const Unit& u, int wr, int wc, int fr, int fq) const {
;     ...
;             for (int m = 0; m < 4; ++m) {
;                 const int row_in = ai * HALF + wr * 64 + m * 16 + fr, s = u.pm * BM + row_in;
;                 const f32x4 tq = ((const f32x4*)(stats + ((size_t)s * 8 + h) * 8))[fq];
;                 const size_t off = (size_t)s * RV + u.pn * BM + wc * 32 + 8 * fq;
;                 const u32x4 o0 = *(const u32x4*)(O + off), o1 = *(const u32x4*)(O + off + HALF);
;                 float s1 = tq[0] + tq[2], s2 = tq[1] + tq[3];
;                 { const auto r1 = __builtin_amdgcn_permlane16_swap(__float_as_uint(s1), __float_as_uint(s1), false, false); s1 = __uint_as_float(r1[0]) + __uint_as_float(r1[1]);
;                   const auto r2 = __builtin_amdgcn_permlane16_swap(__float_as_uint(s2), __float_as_uint(s2), false, false); s2 = __uint_as_float(r2[0]) + __uint_as_float(r2[1]);
;                   const auto r3 = __builtin_amdgcn_permlane32_swap(__float_as_uint(s1), __float_as_uint(s1), false, false); s1 = __uint_as_float(r3[0]) + __uint_as_float(r3[1]);
;                   const auto r4 = __builtin_amdgcn_permlane32_swap(__float_as_uint(s2), __float_as_uint(s2), false, false); s2 = __uint_as_float(r4[0]) + __uint_as_float(r4[1]); }
;                 const float mu = s1 * (1.0f / 512.0f), var = fmaxf(s2 * (1.0f / 512.0f) - mu * mu, 0.f), rstd = rsqrtf(var + EPS);
; #pragma unroll
;                 for (int bj = 0; bj < 2; ++bj) { const u32x4 ov = bj == 0 ? o0 : o1; const unsigned ow[4] = {ov.x, ov.y, ov.z, ov.w}; unsigned r[4];
; #pragma unroll
;                     for (int p = 0; p < 4; ++p) { const f32x4 v = acc[ai][bj][m][p >> 1]; const float g0 = silu_f(v[(p & 1) * 2]), g1 = silu_f(v[(p & 1) * 2 + 1]);
;                         r[p] = cvt_pk_bf16(g0 * ((bf_lo(ow[p]) - mu) * rstd), g1 * ((bf_hi(ow[p]) - mu) * rstd)); }
	v_mov_b32_e32 v44, v192
	v_mov_b32_e32 v45, v193
	v_mov_b32_e32 v46, v194
	v_mov_b32_e32 v47, v195
	v_mov_b32_e32 v36, v196
	v_mov_b32_e32 v37, v197
	v_mov_b32_e32 v38, v198
	v_mov_b32_e32 v39, v199
	v_mov_b32_e32 v32, v200
	v_mov_b32_e32 v33, v201
	v_mov_b32_e32 v34, v202
	v_mov_b32_e32 v35, v203
	v_add_u32_e32 v216, 0xb0, v162
	v_ashrrev_i32_e32 v217, 31, v216
	v_lshlrev_b64 v[218:219], 9, v[216:217]
	v_lshl_add_u64 v[218:219], s[2:3], 0, v[218:219]
	v_lshl_add_u64 v[218:219], v[218:219], 0, s[48:49]
	v_lshl_add_u64 v[218:219], v[218:219], 0, v[166:167]
	global_load_dwordx4 v[204:207], v[218:219], off
	v_lshlrev_b64 v[216:217], 12, v[216:217]
	v_lshl_add_u64 v[216:217], v[216:217], 0, v[164:165]
	v_lshlrev_b64 v[216:217], 1, v[216:217]
	v_lshl_add_u64 v[216:217], s[4:5], 0, v[216:217]
	global_load_dwordx4 v[208:211], v[216:217], off
	global_load_dwordx4 v[212:215], v[216:217], off offset:256
	v_add_f32_e32 v40, v44, v46
	v_mov_b32_e32 v41, v40
	v_add_f32_e32 v44, v45, v47
	s_nop 0
	v_permlane16_swap_b32_e32 v40, v41
	v_add_f32_e32 v41, v40, v41
	v_mov_b32_e32 v40, v44
	s_nop 1
	v_permlane16_swap_b32_e32 v44, v40
	v_add_f32_e32 v40, v44, v40
	v_mov_b32_e32 v45, v41
	v_mov_b32_e32 v44, v40
	s_nop 0
	v_permlane32_swap_b32_e32 v41, v45
	v_permlane32_swap_b32_e32 v40, v44
	v_pk_add_f32 v[40:41], v[40:41], v[44:45]
	s_nop 0
	v_pk_mul_f32 v[40:41], v[40:41], s[8:9] op_sel_hi:[1,0]
	s_nop 0
	v_fma_f32 v40, -v41, v41, v40
	v_max_f32_e32 v40, 0, v40
	v_add_f32_e32 v40, 0x358637bd, v40
	v_cmp_gt_f32_e32 vcc, s73, v40
	v_mul_f32_e32 v44, 0x4b800000, v40
	s_nop 0
	v_cndmask_b32_e32 v40, v40, v44, vcc
	v_rsq_f32_e32 v40, v40
	s_nop 0
	v_mul_f32_e32 v44, 0x45800000, v40
	v_cndmask_b32_e32 v40, v40, v44, vcc
	v_mul_f32_e32 v44, 0xbfb8aa3b, v28
	v_exp_f32_e32 v44, v44
	s_nop 0
	v_add_f32_e32 v44, 1.0, v44
	v_div_scale_f32 v45, s[0:1], v44, v44, v28
	v_rcp_f32_e32 v46, v45
	s_nop 0
	v_fma_f32 v47, -v45, v46, 1.0
	v_fmac_f32_e32 v46, v47, v46
	v_div_scale_f32 v47, vcc, v28, v44, v28
	v_mul_f32_e32 v48, v47, v46
	v_fma_f32 v49, -v45, v48, v47
	v_fmac_f32_e32 v48, v49, v46
	v_fma_f32 v45, -v45, v48, v47
	v_div_fmas_f32 v45, v45, v46, v48
	v_div_fixup_f32 v28, v45, v44, v28
	v_mul_f32_e32 v44, 0xbfb8aa3b, v29
	v_exp_f32_e32 v44, v44
	s_nop 0
	v_add_f32_e32 v44, 1.0, v44
	v_div_scale_f32 v45, s[0:1], v44, v44, v29
	v_rcp_f32_e32 v46, v45
	s_nop 0
	v_fma_f32 v47, -v45, v46, 1.0
	v_fmac_f32_e32 v46, v47, v46
	v_div_scale_f32 v47, vcc, v29, v44, v29
	v_mul_f32_e32 v48, v47, v46
	v_fma_f32 v49, -v45, v48, v47
	v_fmac_f32_e32 v48, v49, v46
	v_fma_f32 v45, -v45, v48, v47
	v_div_fmas_f32 v45, v45, v46, v48
	v_div_fixup_f32 v29, v45, v44, v29
	v_lshlrev_b32_e32 v44, 16, v36
	v_and_b32_e32 v36, 0xffff0000, v36
	v_sub_f32_e32 v44, v44, v41
	v_sub_f32_e32 v36, v36, v41
	v_mul_f32_e32 v44, v44, v40
	v_mul_f32_e32 v36, v36, v40
	v_mul_f32_e32 v28, v28, v44
	v_mul_f32_e32 v29, v29, v36
	v_cvt_pk_bf16_f32 v28, v28, v29
	v_mul_f32_e32 v29, 0xbfb8aa3b, v30
	v_exp_f32_e32 v29, v29
	s_nop 0
	v_add_f32_e32 v29, 1.0, v29
	v_div_scale_f32 v36, s[0:1], v29, v29, v30
	v_rcp_f32_e32 v44, v36
	s_nop 0
	v_fma_f32 v45, -v36, v44, 1.0
	v_fmac_f32_e32 v44, v45, v44
	v_div_scale_f32 v45, vcc, v30, v29, v30
	v_mul_f32_e32 v46, v45, v44
	v_fma_f32 v47, -v36, v46, v45
	v_fmac_f32_e32 v46, v47, v44
	v_fma_f32 v36, -v36, v46, v45
	v_div_fmas_f32 v36, v36, v44, v46
	v_div_fixup_f32 v29, v36, v29, v30
	v_mul_f32_e32 v30, 0xbfb8aa3b, v31
	v_exp_f32_e32 v30, v30
	s_nop 0
	v_add_f32_e32 v30, 1.0, v30
	v_div_scale_f32 v36, s[0:1], v30, v30, v31
	v_rcp_f32_e32 v44, v36
	s_nop 0
	v_fma_f32 v45, -v36, v44, 1.0
	v_fmac_f32_e32 v44, v45, v44
	v_div_scale_f32 v45, vcc, v31, v30, v31
	v_mul_f32_e32 v46, v45, v44
	v_fma_f32 v47, -v36, v46, v45
	v_fmac_f32_e32 v46, v47, v44
	v_fma_f32 v36, -v36, v46, v45
	v_div_fmas_f32 v36, v36, v44, v46
	v_div_fixup_f32 v30, v36, v30, v31
	v_lshlrev_b32_e32 v31, 16, v37
	v_sub_f32_e32 v31, v31, v41
	v_mul_f32_e32 v31, v31, v40
	v_mul_f32_e32 v29, v29, v31
	v_and_b32_e32 v31, 0xffff0000, v37
	v_sub_f32_e32 v31, v31, v41
	v_mul_f32_e32 v31, v31, v40
	v_mul_f32_e32 v30, v30, v31
	v_cvt_pk_bf16_f32 v29, v29, v30
	v_mul_f32_e32 v30, 0xbfb8aa3b, v24
	v_exp_f32_e32 v30, v30
	s_nop 0
	v_add_f32_e32 v30, 1.0, v30
	v_div_scale_f32 v31, s[0:1], v30, v30, v24
	v_rcp_f32_e32 v36, v31
	s_nop 0
	v_fma_f32 v37, -v31, v36, 1.0
	v_fmac_f32_e32 v36, v37, v36
	v_div_scale_f32 v37, vcc, v24, v30, v24
	v_mul_f32_e32 v44, v37, v36
	v_fma_f32 v45, -v31, v44, v37
	v_fmac_f32_e32 v44, v45, v36
	v_fma_f32 v31, -v31, v44, v37
	v_div_fmas_f32 v31, v31, v36, v44
	v_div_fixup_f32 v24, v31, v30, v24
	v_mul_f32_e32 v30, 0xbfb8aa3b, v25
	v_exp_f32_e32 v30, v30
	s_nop 0
	v_add_f32_e32 v30, 1.0, v30
	v_div_scale_f32 v31, s[0:1], v30, v30, v25
	v_rcp_f32_e32 v36, v31
	s_nop 0
	v_fma_f32 v37, -v31, v36, 1.0
	v_fmac_f32_e32 v36, v37, v36
	v_div_scale_f32 v37, vcc, v25, v30, v25
	v_mul_f32_e32 v44, v37, v36
	v_fma_f32 v45, -v31, v44, v37
	v_fmac_f32_e32 v44, v45, v36
	v_fma_f32 v31, -v31, v44, v37
	v_div_fmas_f32 v31, v31, v36, v44
	v_div_fixup_f32 v25, v31, v30, v25
	v_lshlrev_b32_e32 v30, 16, v38
	v_sub_f32_e32 v30, v30, v41
	v_mul_f32_e32 v30, v30, v40
	v_mul_f32_e32 v24, v24, v30
	v_and_b32_e32 v30, 0xffff0000, v38
	v_sub_f32_e32 v30, v30, v41
	v_mul_f32_e32 v30, v30, v40
	v_mul_f32_e32 v25, v25, v30
	v_cvt_pk_bf16_f32 v30, v24, v25
	v_mul_f32_e32 v24, 0xbfb8aa3b, v26
	v_exp_f32_e32 v24, v24
	s_nop 0
	v_add_f32_e32 v24, 1.0, v24
	v_div_scale_f32 v25, s[0:1], v24, v24, v26
	v_rcp_f32_e32 v31, v25
	s_nop 0
	v_fma_f32 v36, -v25, v31, 1.0
	v_fmac_f32_e32 v31, v36, v31
	v_div_scale_f32 v36, vcc, v26, v24, v26
; __device__ __forceinline__ unsigned cvt_pk_bf16(float lo, float hi) { unsigned r; asm volatile("v_cvt_pk_bf16_f32 %0, %1, %2" : "=v"(r) : "v"(lo), "v"(hi)); return r; }
; __device__ __forceinline__ float bf_lo(unsigned w) { return __uint_as_float(w << 16); }
; __device__ __forceinline__ float bf_hi(unsigned w) { return __uint_as_float(w & 0xffff0000u); }
; __device__ __forceinline__ float silu_f(float v) { return v / (1.0f + __expf(-v)); }
;     __device__ __forceinline__ void operator()(const Acc& acc, const Unit& u, int wr, int wc, int fr, int fq) const {
;     ...
;                 for (int bj = 0; bj < 2; ++bj) { const u32x4 ov = bj == 0 ? o0 : o1; const unsigned ow[4] = {ov.x, ov.y, ov.z, ov.w}; unsigned r[4];
; #pragma unroll
;                     for (int p = 0; p < 4; ++p) { const f32x4 v = acc[ai][bj][m][p >> 1]; const float g0 = silu_f(v[(p & 1) * 2]), g1 = silu_f(v[(p & 1) * 2 + 1]);
;                         r[p] = cvt_pk_bf16(g0 * ((bf_lo(ow[p]) - mu) * rstd), g1 * ((bf_hi(ow[p]) - mu) * rstd)); }
;                     *(u32x4*)(U + off + bj * HALF) = (u32x4){r[0], r[1], r[2], r[3]}; }
	v_mul_f32_e32 v37, v36, v31
	v_fma_f32 v38, -v25, v37, v36
	v_fmac_f32_e32 v37, v38, v31
	v_fma_f32 v25, -v25, v37, v36
	v_div_fmas_f32 v25, v25, v31, v37
	v_div_fixup_f32 v24, v25, v24, v26
	v_mul_f32_e32 v25, 0xbfb8aa3b, v27
	v_exp_f32_e32 v25, v25
	s_nop 0
	v_add_f32_e32 v25, 1.0, v25
	v_div_scale_f32 v26, s[0:1], v25, v25, v27
	v_rcp_f32_e32 v31, v26
	s_nop 0
	v_fma_f32 v36, -v26, v31, 1.0
	v_fmac_f32_e32 v31, v36, v31
	v_div_scale_f32 v36, vcc, v27, v25, v27
	v_mul_f32_e32 v37, v36, v31
	v_fma_f32 v38, -v26, v37, v36
	v_fmac_f32_e32 v37, v38, v31
	v_fma_f32 v26, -v26, v37, v36
	v_div_fmas_f32 v26, v26, v31, v37
	v_div_fixup_f32 v25, v26, v25, v27
	v_lshlrev_b32_e32 v26, 16, v39
	v_sub_f32_e32 v26, v26, v41
	v_mul_f32_e32 v26, v26, v40
	v_mul_f32_e32 v24, v24, v26
	v_and_b32_e32 v26, 0xffff0000, v39
	v_sub_f32_e32 v26, v26, v41
	v_mul_f32_e32 v26, v26, v40
	v_mul_f32_e32 v25, v25, v26
	v_mul_f32_e32 v26, 0xbfb8aa3b, v20
	v_exp_f32_e32 v26, v26
	v_cvt_pk_bf16_f32 v31, v24, v25
	v_lshl_add_u64 v[24:25], s[6:7], 0, v[42:43]
	global_store_dwordx4 v[24:25], v[28:31], off
	v_add_f32_e32 v26, 1.0, v26
	v_div_scale_f32 v27, s[0:1], v26, v26, v20
	v_rcp_f32_e32 v28, v27
	s_nop 0
	v_fma_f32 v29, -v27, v28, 1.0
	v_fmac_f32_e32 v28, v29, v28
	v_div_scale_f32 v29, vcc, v20, v26, v20
	v_mul_f32_e32 v30, v29, v28
	v_fma_f32 v31, -v27, v30, v29
	v_fmac_f32_e32 v30, v31, v28
	v_fma_f32 v27, -v27, v30, v29
	v_div_fmas_f32 v27, v27, v28, v30
	v_div_fixup_f32 v20, v27, v26, v20
	v_mul_f32_e32 v26, 0xbfb8aa3b, v21
	v_exp_f32_e32 v26, v26
	s_nop 0
	v_add_f32_e32 v26, 1.0, v26
	v_div_scale_f32 v27, s[0:1], v26, v26, v21
	v_rcp_f32_e32 v28, v27
	s_nop 0
	v_fma_f32 v29, -v27, v28, 1.0
	v_fmac_f32_e32 v28, v29, v28
	v_div_scale_f32 v29, vcc, v21, v26, v21
	v_mul_f32_e32 v30, v29, v28
	v_fma_f32 v31, -v27, v30, v29
	v_fmac_f32_e32 v30, v31, v28
	v_fma_f32 v27, -v27, v30, v29
	v_div_fmas_f32 v27, v27, v28, v30
	v_div_fixup_f32 v21, v27, v26, v21
	v_lshlrev_b32_e32 v26, 16, v32
	v_sub_f32_e32 v26, v26, v41
	v_mul_f32_e32 v26, v26, v40
	v_mul_f32_e32 v20, v20, v26
	v_and_b32_e32 v26, 0xffff0000, v32
	v_sub_f32_e32 v26, v26, v41
	v_mul_f32_e32 v26, v26, v40
	v_mul_f32_e32 v21, v21, v26
	v_cvt_pk_bf16_f32 v20, v20, v21
	v_mul_f32_e32 v21, 0xbfb8aa3b, v22
	v_exp_f32_e32 v21, v21
	s_nop 0
	v_add_f32_e32 v21, 1.0, v21
	v_div_scale_f32 v26, s[0:1], v21, v21, v22
	v_rcp_f32_e32 v27, v26
	s_nop 0
	v_fma_f32 v28, -v26, v27, 1.0
	v_fmac_f32_e32 v27, v28, v27
	v_div_scale_f32 v28, vcc, v22, v21, v22
	v_mul_f32_e32 v29, v28, v27
	v_fma_f32 v30, -v26, v29, v28
	v_fmac_f32_e32 v29, v30, v27
	v_fma_f32 v26, -v26, v29, v28
	v_div_fmas_f32 v26, v26, v27, v29
	v_div_fixup_f32 v21, v26, v21, v22
	v_mul_f32_e32 v22, 0xbfb8aa3b, v23
	v_exp_f32_e32 v22, v22
	s_nop 0
	v_add_f32_e32 v22, 1.0, v22
	v_div_scale_f32 v26, s[0:1], v22, v22, v23
	v_rcp_f32_e32 v27, v26
	s_nop 0
	v_fma_f32 v28, -v26, v27, 1.0
	v_fmac_f32_e32 v27, v28, v27
	v_div_scale_f32 v28, vcc, v23, v22, v23
	v_mul_f32_e32 v29, v28, v27
	v_fma_f32 v30, -v26, v29, v28
	v_fmac_f32_e32 v29, v30, v27
	v_fma_f32 v26, -v26, v29, v28
	v_div_fmas_f32 v26, v26, v27, v29
	v_div_fixup_f32 v22, v26, v22, v23
	v_lshlrev_b32_e32 v23, 16, v33
	v_sub_f32_e32 v23, v23, v41
	v_mul_f32_e32 v23, v23, v40
	v_mul_f32_e32 v21, v21, v23
	v_and_b32_e32 v23, 0xffff0000, v33
	v_sub_f32_e32 v23, v23, v41
	v_mul_f32_e32 v23, v23, v40
	v_mul_f32_e32 v22, v22, v23
	v_cvt_pk_bf16_f32 v21, v21, v22
	v_mul_f32_e32 v22, 0xbfb8aa3b, v16
	v_exp_f32_e32 v22, v22
	s_nop 0
	v_add_f32_e32 v22, 1.0, v22
	v_div_scale_f32 v23, s[0:1], v22, v22, v16
	v_rcp_f32_e32 v26, v23
	s_nop 0
	v_fma_f32 v27, -v23, v26, 1.0
	v_fmac_f32_e32 v26, v27, v26
	v_div_scale_f32 v27, vcc, v16, v22, v16
	v_mul_f32_e32 v28, v27, v26
	v_fma_f32 v29, -v23, v28, v27
	v_fmac_f32_e32 v28, v29, v26
	v_fma_f32 v23, -v23, v28, v27
	v_div_fmas_f32 v23, v23, v26, v28
	v_div_fixup_f32 v16, v23, v22, v16
	v_mul_f32_e32 v22, 0xbfb8aa3b, v17
	v_exp_f32_e32 v22, v22
	s_nop 0
	v_add_f32_e32 v22, 1.0, v22
	v_div_scale_f32 v23, s[0:1], v22, v22, v17
	v_rcp_f32_e32 v26, v23
	s_nop 0
	v_fma_f32 v27, -v23, v26, 1.0
	v_fmac_f32_e32 v26, v27, v26
	v_div_scale_f32 v27, vcc, v17, v22, v17
	v_mul_f32_e32 v28, v27, v26
	v_fma_f32 v29, -v23, v28, v27
	v_fmac_f32_e32 v28, v29, v26
	v_fma_f32 v23, -v23, v28, v27
	v_div_fmas_f32 v23, v23, v26, v28
	v_div_fixup_f32 v17, v23, v22, v17
	v_lshlrev_b32_e32 v22, 16, v34
	v_sub_f32_e32 v22, v22, v41
	v_mul_f32_e32 v22, v22, v40
	v_mul_f32_e32 v16, v16, v22
	v_and_b32_e32 v22, 0xffff0000, v34
	v_sub_f32_e32 v22, v22, v41
	v_mul_f32_e32 v22, v22, v40
	v_mul_f32_e32 v17, v17, v22
	v_cvt_pk_bf16_f32 v22, v16, v17
	v_mul_f32_e32 v16, 0xbfb8aa3b, v18
	v_exp_f32_e32 v16, v16
	s_nop 0
	v_add_f32_e32 v16, 1.0, v16
	v_div_scale_f32 v17, s[0:1], v16, v16, v18
	v_rcp_f32_e32 v23, v17
	s_nop 0
	v_fma_f32 v26, -v17, v23, 1.0
	v_fmac_f32_e32 v23, v26, v23
	v_div_scale_f32 v26, vcc, v18, v16, v18
	v_mul_f32_e32 v27, v26, v23
	v_fma_f32 v28, -v17, v27, v26
	v_fmac_f32_e32 v27, v28, v23
	v_fma_f32 v17, -v17, v27, v26
	v_div_fmas_f32 v17, v17, v23, v27
	v_div_fixup_f32 v16, v17, v16, v18
	v_mul_f32_e32 v17, 0xbfb8aa3b, v19
	v_exp_f32_e32 v17, v17
	s_nop 0
	v_add_f32_e32 v17, 1.0, v17
	v_div_scale_f32 v18, s[0:1], v17, v17, v19
	v_rcp_f32_e32 v23, v18
	s_nop 0
	v_fma_f32 v26, -v18, v23, 1.0
	v_fmac_f32_e32 v23, v26, v23
	v_div_scale_f32 v26, vcc, v19, v17, v19
	v_mul_f32_e32 v27, v26, v23
	v_fma_f32 v28, -v18, v27, v26
	v_fmac_f32_e32 v27, v28, v23
	v_fma_f32 v18, -v18, v27, v26
	v_div_fmas_f32 v18, v18, v23, v27
	v_div_fixup_f32 v17, v18, v17, v19
	v_lshlrev_b32_e32 v18, 16, v35
	v_sub_f32_e32 v18, v18, v41
	v_mul_f32_e32 v18, v18, v40
	v_mul_f32_e32 v16, v16, v18
	v_and_b32_e32 v18, 0xffff0000, v35
	v_sub_f32_e32 v18, v18, v41
	v_mul_f32_e32 v18, v18, v40
	v_mul_f32_e32 v17, v17, v18
	v_cvt_pk_bf16_f32 v23, v16, v17
	v_add_u32_e32 v16, 0xb0, v162
	v_ashrrev_i32_e32 v17, 31, v16
	v_lshlrev_b64 v[18:19], 9, v[16:17]
	v_lshl_add_u64 v[18:19], s[2:3], 0, v[18:19]
	v_lshl_add_u64 v[18:19], v[18:19], 0, s[48:49]
	global_store_dwordx4 v[24:25], v[20:23], off offset:256
	v_lshl_add_u64 v[18:19], v[18:19], 0, v[166:167]
	v_lshlrev_b64 v[16:17], 12, v[16:17]
	v_lshl_add_u64 v[16:17], v[16:17], 0, v[164:165]
	v_lshlrev_b64 v[26:27], 1, v[16:17]
	v_lshl_add_u64 v[16:17], s[4:5], 0, v[26:27]
	s_waitcnt vmcnt(2)
; __device__ __forceinline__ unsigned cvt_pk_bf16(float lo, float hi) { unsigned r; asm volatile("v_cvt_pk_bf16_f32 %0, %1, %2" : "=v"(r) : "v"(lo), "v"(hi)); return r; }
; __device__ __forceinline__ float bf_lo(unsigned w) { return __uint_as_float(w << 16); }
; __device__ __forceinline__ float bf_hi(unsigned w) { return __uint_as_float(w & 0xffff0000u); }
; __device__ __forceinline__ float silu_f(float v) { return v / (1.0f + __expf(-v)); }
;     __device__ __forceinline__ void operator()(const Acc& acc, const Unit& u, int wr, int wc, int fr, int fq) const {
;     ...
;             for (int m = 0; m < 4; ++m) {
;                 const int row_in = ai * HALF + wr * 64 + m * 16 + fr, s = u.pm * BM + row_in;
;                 const f32x4 tq = ((const f32x4*)(stats + ((size_t)s * 8 + h) * 8))[fq];
;                 const size_t off = (size_t)s * RV + u.pn * BM + wc * 32 + 8 * fq;
;                 const u32x4 o0 = *(const u32x4*)(O + off), o1 = *(const u32x4*)(O + off + HALF);
;                 float s1 = tq[0] + tq[2], s2 = tq[1] + tq[3];
;                 { const auto r1 = __builtin_amdgcn_permlane16_swap(__float_as_uint(s1), __float_as_uint(s1), false, false); s1 = __uint_as_float(r1[0]) + __uint_as_float(r1[1]);
;                   const auto r2 = __builtin_amdgcn_permlane16_swap(__float_as_uint(s2), __float_as_uint(s2), false, false); s2 = __uint_as_float(r2[0]) + __uint_as_float(r2[1]);
;                   const auto r3 = __builtin_amdgcn_permlane32_swap(__float_as_uint(s1), __float_as_uint(s1), false, false); s1 = __uint_as_float(r3[0]) + __uint_as_float(r3[1]);
;                   const auto r4 = __builtin_amdgcn_permlane32_swap(__float_as_uint(s2), __float_as_uint(s2), false, false); s2 = __uint_as_float(r4[0]) + __uint_as_float(r4[1]); }
;                 const float mu = s1 * (1.0f / 512.0f), var = fmaxf(s2 * (1.0f / 512.0f) - mu * mu, 0.f), rstd = rsqrtf(var + EPS);
; #pragma unroll
;                 for (int bj = 0; bj < 2; ++bj) { const u32x4 ov = bj == 0 ? o0 : o1; const unsigned ow[4] = {ov.x, ov.y, ov.z, ov.w}; unsigned r[4];
; #pragma unroll
;                     for (int p = 0; p < 4; ++p) { const f32x4 v = acc[ai][bj][m][p >> 1]; const float g0 = silu_f(v[(p & 1) * 2]), g1 = silu_f(v[(p & 1) * 2 + 1]);
;                         r[p] = cvt_pk_bf16(g0 * ((bf_lo(ow[p]) - mu) * rstd), g1 * ((bf_hi(ow[p]) - mu) * rstd)); }
	v_mov_b32_e32 v28, v204
	v_mov_b32_e32 v29, v205
	v_mov_b32_e32 v30, v206
	v_mov_b32_e32 v31, v207
	v_mov_b32_e32 v20, v208
	v_mov_b32_e32 v21, v209
	v_mov_b32_e32 v22, v210
	v_mov_b32_e32 v23, v211
	v_mov_b32_e32 v16, v212
	v_mov_b32_e32 v17, v213
	v_mov_b32_e32 v18, v214
	v_mov_b32_e32 v19, v215
	v_add_f32_e32 v24, v28, v30
	v_mov_b32_e32 v25, v24
	v_add_f32_e32 v28, v29, v31
	s_nop 0
	v_permlane16_swap_b32_e32 v24, v25
	v_add_f32_e32 v25, v24, v25
	v_mov_b32_e32 v24, v28
	s_nop 1
	v_permlane16_swap_b32_e32 v28, v24
	v_add_f32_e32 v24, v28, v24
	v_mov_b32_e32 v29, v25
	v_mov_b32_e32 v28, v24
	s_nop 0
	v_permlane32_swap_b32_e32 v25, v29
	v_permlane32_swap_b32_e32 v24, v28
	v_pk_add_f32 v[24:25], v[24:25], v[28:29]
	s_nop 0
	v_pk_mul_f32 v[24:25], v[24:25], s[8:9] op_sel_hi:[1,0]
	s_nop 0
	v_fma_f32 v24, -v25, v25, v24
	v_max_f32_e32 v24, 0, v24
	v_add_f32_e32 v24, 0x358637bd, v24
	v_cmp_gt_f32_e32 vcc, s73, v24
	v_mul_f32_e32 v28, 0x4b800000, v24
	s_nop 0
	v_cndmask_b32_e32 v24, v24, v28, vcc
	v_rsq_f32_e32 v24, v24
	s_nop 0
	v_mul_f32_e32 v28, 0x45800000, v24
	v_cndmask_b32_e32 v24, v24, v28, vcc
	v_mul_f32_e32 v28, 0xbfb8aa3b, v12
	v_exp_f32_e32 v28, v28
	s_nop 0
	v_add_f32_e32 v28, 1.0, v28
	v_div_scale_f32 v29, s[0:1], v28, v28, v12
	v_rcp_f32_e32 v30, v29
	s_nop 0
	v_fma_f32 v31, -v29, v30, 1.0
	v_fmac_f32_e32 v30, v31, v30
	v_div_scale_f32 v31, vcc, v12, v28, v12
	v_mul_f32_e32 v32, v31, v30
	v_fma_f32 v33, -v29, v32, v31
	v_fmac_f32_e32 v32, v33, v30
	v_fma_f32 v29, -v29, v32, v31
	v_div_fmas_f32 v29, v29, v30, v32
	v_div_fixup_f32 v12, v29, v28, v12
	v_mul_f32_e32 v28, 0xbfb8aa3b, v13
	v_exp_f32_e32 v28, v28
	s_nop 0
	v_add_f32_e32 v28, 1.0, v28
	v_div_scale_f32 v29, s[0:1], v28, v28, v13
	v_rcp_f32_e32 v30, v29
	s_nop 0
	v_fma_f32 v31, -v29, v30, 1.0
	v_fmac_f32_e32 v30, v31, v30
	v_div_scale_f32 v31, vcc, v13, v28, v13
	v_mul_f32_e32 v32, v31, v30
	v_fma_f32 v33, -v29, v32, v31
	v_fmac_f32_e32 v32, v33, v30
	v_fma_f32 v29, -v29, v32, v31
	v_div_fmas_f32 v29, v29, v30, v32
	v_div_fixup_f32 v13, v29, v28, v13
	v_lshlrev_b32_e32 v28, 16, v20
	v_and_b32_e32 v20, 0xffff0000, v20
	v_sub_f32_e32 v28, v28, v25
	v_sub_f32_e32 v20, v20, v25
	v_mul_f32_e32 v28, v28, v24
	v_mul_f32_e32 v20, v20, v24
	v_mul_f32_e32 v12, v12, v28
	v_mul_f32_e32 v13, v13, v20
	v_cvt_pk_bf16_f32 v12, v12, v13
	v_mul_f32_e32 v13, 0xbfb8aa3b, v14
	v_exp_f32_e32 v13, v13
	s_nop 0
	v_add_f32_e32 v13, 1.0, v13
	v_div_scale_f32 v20, s[0:1], v13, v13, v14
	v_rcp_f32_e32 v28, v20
	s_nop 0
	v_fma_f32 v29, -v20, v28, 1.0
	v_fmac_f32_e32 v28, v29, v28
	v_div_scale_f32 v29, vcc, v14, v13, v14
	v_mul_f32_e32 v30, v29, v28
	v_fma_f32 v31, -v20, v30, v29
	v_fmac_f32_e32 v30, v31, v28
	v_fma_f32 v20, -v20, v30, v29
	v_div_fmas_f32 v20, v20, v28, v30
	v_div_fixup_f32 v13, v20, v13, v14
	v_mul_f32_e32 v14, 0xbfb8aa3b, v15
	v_exp_f32_e32 v14, v14
	s_nop 0
	v_add_f32_e32 v14, 1.0, v14
	v_div_scale_f32 v20, s[0:1], v14, v14, v15
	v_rcp_f32_e32 v28, v20
	s_nop 0
	v_fma_f32 v29, -v20, v28, 1.0
	v_fmac_f32_e32 v28, v29, v28
	v_div_scale_f32 v29, vcc, v15, v14, v15
	v_mul_f32_e32 v30, v29, v28
	v_fma_f32 v31, -v20, v30, v29
	v_fmac_f32_e32 v30, v31, v28
	v_fma_f32 v20, -v20, v30, v29
	v_div_fmas_f32 v20, v20, v28, v30
	v_div_fixup_f32 v14, v20, v14, v15
	v_lshlrev_b32_e32 v15, 16, v21
	v_sub_f32_e32 v15, v15, v25
	v_mul_f32_e32 v15, v15, v24
	v_mul_f32_e32 v13, v13, v15
	v_and_b32_e32 v15, 0xffff0000, v21
	v_sub_f32_e32 v15, v15, v25
	v_mul_f32_e32 v15, v15, v24
	v_mul_f32_e32 v14, v14, v15
	v_cvt_pk_bf16_f32 v13, v13, v14
	v_mul_f32_e32 v14, 0xbfb8aa3b, v8
	v_exp_f32_e32 v14, v14
	s_nop 0
	v_add_f32_e32 v14, 1.0, v14
	v_div_scale_f32 v15, s[0:1], v14, v14, v8
	v_rcp_f32_e32 v20, v15
	s_nop 0
	v_fma_f32 v21, -v15, v20, 1.0
	v_fmac_f32_e32 v20, v21, v20
	v_div_scale_f32 v21, vcc, v8, v14, v8
	v_mul_f32_e32 v28, v21, v20
	v_fma_f32 v29, -v15, v28, v21
	v_fmac_f32_e32 v28, v29, v20
	v_fma_f32 v15, -v15, v28, v21
	v_div_fmas_f32 v15, v15, v20, v28
	v_div_fixup_f32 v8, v15, v14, v8
	v_mul_f32_e32 v14, 0xbfb8aa3b, v9
	v_exp_f32_e32 v14, v14
	s_nop 0
	v_add_f32_e32 v14, 1.0, v14
	v_div_scale_f32 v15, s[0:1], v14, v14, v9
	v_rcp_f32_e32 v20, v15
	s_nop 0
	v_fma_f32 v21, -v15, v20, 1.0
	v_fmac_f32_e32 v20, v21, v20
	v_div_scale_f32 v21, vcc, v9, v14, v9
	v_mul_f32_e32 v28, v21, v20
	v_fma_f32 v29, -v15, v28, v21
	v_fmac_f32_e32 v28, v29, v20
	v_fma_f32 v15, -v15, v28, v21
	v_div_fmas_f32 v15, v15, v20, v28
	v_div_fixup_f32 v9, v15, v14, v9
	v_lshlrev_b32_e32 v14, 16, v22
	v_sub_f32_e32 v14, v14, v25
	v_mul_f32_e32 v14, v14, v24
	v_mul_f32_e32 v8, v8, v14
	v_and_b32_e32 v14, 0xffff0000, v22
	v_sub_f32_e32 v14, v14, v25
	v_mul_f32_e32 v14, v14, v24
	v_mul_f32_e32 v9, v9, v14
	v_cvt_pk_bf16_f32 v14, v8, v9
	v_mul_f32_e32 v8, 0xbfb8aa3b, v10
	v_exp_f32_e32 v8, v8
	s_nop 0
	v_add_f32_e32 v8, 1.0, v8
	v_div_scale_f32 v9, s[0:1], v8, v8, v10
	v_rcp_f32_e32 v15, v9
	s_nop 0
	v_fma_f32 v20, -v9, v15, 1.0
	v_fmac_f32_e32 v15, v20, v15
	v_div_scale_f32 v20, vcc, v10, v8, v10
	v_mul_f32_e32 v21, v20, v15
	v_fma_f32 v22, -v9, v21, v20
	v_fmac_f32_e32 v21, v22, v15
	v_fma_f32 v9, -v9, v21, v20
	v_div_fmas_f32 v9, v9, v15, v21
	v_div_fixup_f32 v8, v9, v8, v10
	v_mul_f32_e32 v9, 0xbfb8aa3b, v11
	v_exp_f32_e32 v9, v9
	s_nop 0
	v_add_f32_e32 v9, 1.0, v9
	v_div_scale_f32 v10, s[0:1], v9, v9, v11
	v_rcp_f32_e32 v15, v10
	s_nop 0
	v_fma_f32 v20, -v10, v15, 1.0
	v_fmac_f32_e32 v15, v20, v15
; __device__ __forceinline__ unsigned cvt_pk_bf16(float lo, float hi) { unsigned r; asm volatile("v_cvt_pk_bf16_f32 %0, %1, %2" : "=v"(r) : "v"(lo), "v"(hi)); return r; }
; __device__ __forceinline__ float bf_lo(unsigned w) { return __uint_as_float(w << 16); }
; __device__ __forceinline__ float bf_hi(unsigned w) { return __uint_as_float(w & 0xffff0000u); }
; __device__ __forceinline__ float silu_f(float v) { return v / (1.0f + __expf(-v)); }
; #define PG8_BAR __builtin_amdgcn_s_barrier()
; template <class Epi, class Map>
; __device__ __forceinline__ void gemm_phase(LAS unsigned char* lds, const Gemm g, const Sched<Map>& S, const Epi& E) {
;     ...
;         if (!has_next) break;
; #pragma unroll
;         for (int a = 0; a < 2; ++a)
; #pragma unroll
;             for (int b = 0; b < 2; ++b)
; #pragma unroll
;                 for (int m = 0; m < 4; ++m)
; #pragma unroll
;                     for (int n = 0; n < 2; ++n) acc[a][b][m][n] = (f32x4){0.f, 0.f, 0.f, 0.f};
;         cur = nxt; cA = nA; cB = nB; ++ui;
;         if (wr == 1) PG8_BAR;
;     __device__ __forceinline__ void operator()(const Acc& acc, const Unit& u, int wr, int wc, int fr, int fq) const {
;     ...
;                 for (int bj = 0; bj < 2; ++bj) { const u32x4 ov = bj == 0 ? o0 : o1; const unsigned ow[4] = {ov.x, ov.y, ov.z, ov.w}; unsigned r[4];
; #pragma unroll
;                     for (int p = 0; p < 4; ++p) { const f32x4 v = acc[ai][bj][m][p >> 1]; const float g0 = silu_f(v[(p & 1) * 2]), g1 = silu_f(v[(p & 1) * 2 + 1]);
;                         r[p] = cvt_pk_bf16(g0 * ((bf_lo(ow[p]) - mu) * rstd), g1 * ((bf_hi(ow[p]) - mu) * rstd)); }
;                     *(u32x4*)(U + off + bj * HALF) = (u32x4){r[0], r[1], r[2], r[3]}; }
	v_div_scale_f32 v20, vcc, v11, v9, v11
	v_mul_f32_e32 v21, v20, v15
	v_fma_f32 v22, -v10, v21, v20
	v_fmac_f32_e32 v21, v22, v15
	v_fma_f32 v10, -v10, v21, v20
	v_div_fmas_f32 v10, v10, v15, v21
	v_div_fixup_f32 v9, v10, v9, v11
	v_lshlrev_b32_e32 v10, 16, v23
	v_sub_f32_e32 v10, v10, v25
	v_mul_f32_e32 v10, v10, v24
	v_mul_f32_e32 v8, v8, v10
	v_and_b32_e32 v10, 0xffff0000, v23
	v_sub_f32_e32 v10, v10, v25
	v_mul_f32_e32 v10, v10, v24
	v_mul_f32_e32 v9, v9, v10
	v_mul_f32_e32 v10, 0xbfb8aa3b, v4
	v_exp_f32_e32 v10, v10
	v_cvt_pk_bf16_f32 v15, v8, v9
	v_lshl_add_u64 v[8:9], s[6:7], 0, v[26:27]
	global_store_dwordx4 v[8:9], v[12:15], off
	v_add_f32_e32 v10, 1.0, v10
	v_div_scale_f32 v11, s[0:1], v10, v10, v4
	v_rcp_f32_e32 v12, v11
	s_nop 0
	v_fma_f32 v13, -v11, v12, 1.0
	v_fmac_f32_e32 v12, v13, v12
	v_div_scale_f32 v13, vcc, v4, v10, v4
	v_mul_f32_e32 v14, v13, v12
	v_fma_f32 v15, -v11, v14, v13
	v_fmac_f32_e32 v14, v15, v12
	v_fma_f32 v11, -v11, v14, v13
	v_div_fmas_f32 v11, v11, v12, v14
	v_div_fixup_f32 v4, v11, v10, v4
	v_mul_f32_e32 v10, 0xbfb8aa3b, v5
	v_exp_f32_e32 v10, v10
	s_nop 0
	v_add_f32_e32 v10, 1.0, v10
	v_div_scale_f32 v11, s[0:1], v10, v10, v5
	v_rcp_f32_e32 v12, v11
	s_nop 0
	v_fma_f32 v13, -v11, v12, 1.0
	v_fmac_f32_e32 v12, v13, v12
	v_div_scale_f32 v13, vcc, v5, v10, v5
	v_mul_f32_e32 v14, v13, v12
	v_fma_f32 v15, -v11, v14, v13
	v_fmac_f32_e32 v14, v15, v12
	v_fma_f32 v11, -v11, v14, v13
	v_div_fmas_f32 v11, v11, v12, v14
	v_div_fixup_f32 v5, v11, v10, v5
	v_lshlrev_b32_e32 v10, 16, v16
	v_sub_f32_e32 v10, v10, v25
	v_mul_f32_e32 v10, v10, v24
	v_mul_f32_e32 v4, v4, v10
	v_and_b32_e32 v10, 0xffff0000, v16
	v_sub_f32_e32 v10, v10, v25
	v_mul_f32_e32 v10, v10, v24
	v_mul_f32_e32 v5, v5, v10
	v_cvt_pk_bf16_f32 v4, v4, v5
	v_mul_f32_e32 v5, 0xbfb8aa3b, v6
	v_exp_f32_e32 v5, v5
	s_nop 0
	v_add_f32_e32 v5, 1.0, v5
	v_div_scale_f32 v10, s[0:1], v5, v5, v6
	v_rcp_f32_e32 v11, v10
	s_nop 0
	v_fma_f32 v12, -v10, v11, 1.0
	v_fmac_f32_e32 v11, v12, v11
	v_div_scale_f32 v12, vcc, v6, v5, v6
	v_mul_f32_e32 v13, v12, v11
	v_fma_f32 v14, -v10, v13, v12
	v_fmac_f32_e32 v13, v14, v11
	v_fma_f32 v10, -v10, v13, v12
	v_div_fmas_f32 v10, v10, v11, v13
	v_div_fixup_f32 v5, v10, v5, v6
	v_mul_f32_e32 v6, 0xbfb8aa3b, v7
	v_exp_f32_e32 v6, v6
	s_nop 0
	v_add_f32_e32 v6, 1.0, v6
	v_div_scale_f32 v10, s[0:1], v6, v6, v7
	v_rcp_f32_e32 v11, v10
	s_nop 0
	v_fma_f32 v12, -v10, v11, 1.0
	v_fmac_f32_e32 v11, v12, v11
	v_div_scale_f32 v12, vcc, v7, v6, v7
	v_mul_f32_e32 v13, v12, v11
	v_fma_f32 v14, -v10, v13, v12
	v_fmac_f32_e32 v13, v14, v11
	v_fma_f32 v10, -v10, v13, v12
	v_div_fmas_f32 v10, v10, v11, v13
	v_div_fixup_f32 v6, v10, v6, v7
	v_lshlrev_b32_e32 v7, 16, v17
	v_sub_f32_e32 v7, v7, v25
	v_mul_f32_e32 v7, v7, v24
	v_mul_f32_e32 v5, v5, v7
	v_and_b32_e32 v7, 0xffff0000, v17
	v_sub_f32_e32 v7, v7, v25
	v_mul_f32_e32 v7, v7, v24
	v_mul_f32_e32 v6, v6, v7
	v_cvt_pk_bf16_f32 v5, v5, v6
	v_mul_f32_e32 v6, 0xbfb8aa3b, v0
	v_exp_f32_e32 v6, v6
	s_nop 0
	v_add_f32_e32 v6, 1.0, v6
	v_div_scale_f32 v7, s[0:1], v6, v6, v0
	v_rcp_f32_e32 v10, v7
	s_nop 0
	v_fma_f32 v11, -v7, v10, 1.0
	v_fmac_f32_e32 v10, v11, v10
	v_div_scale_f32 v11, vcc, v0, v6, v0
	v_mul_f32_e32 v12, v11, v10
	v_fma_f32 v13, -v7, v12, v11
	v_fmac_f32_e32 v12, v13, v10
	v_fma_f32 v7, -v7, v12, v11
	v_div_fmas_f32 v7, v7, v10, v12
	v_div_fixup_f32 v0, v7, v6, v0
	v_mul_f32_e32 v6, 0xbfb8aa3b, v1
	v_exp_f32_e32 v6, v6
	s_nop 0
	v_add_f32_e32 v6, 1.0, v6
	v_div_scale_f32 v7, s[0:1], v6, v6, v1
	v_rcp_f32_e32 v10, v7
	s_nop 0
	v_fma_f32 v11, -v7, v10, 1.0
	v_fmac_f32_e32 v10, v11, v10
	v_div_scale_f32 v11, vcc, v1, v6, v1
	v_mul_f32_e32 v12, v11, v10
	v_fma_f32 v13, -v7, v12, v11
	v_fmac_f32_e32 v12, v13, v10
	v_fma_f32 v7, -v7, v12, v11
	v_div_fmas_f32 v7, v7, v10, v12
	v_div_fixup_f32 v1, v7, v6, v1
	v_lshlrev_b32_e32 v6, 16, v18
	v_sub_f32_e32 v6, v6, v25
	v_mul_f32_e32 v6, v6, v24
	v_mul_f32_e32 v0, v0, v6
	v_and_b32_e32 v6, 0xffff0000, v18
	v_sub_f32_e32 v6, v6, v25
	v_mul_f32_e32 v6, v6, v24
	v_mul_f32_e32 v1, v1, v6
	v_cvt_pk_bf16_f32 v6, v0, v1
	v_mul_f32_e32 v0, 0xbfb8aa3b, v2
	v_exp_f32_e32 v0, v0
	s_nop 0
	v_add_f32_e32 v0, 1.0, v0
	v_div_scale_f32 v1, s[0:1], v0, v0, v2
	v_rcp_f32_e32 v7, v1
	s_nop 0
	v_fma_f32 v10, -v1, v7, 1.0
	v_fmac_f32_e32 v7, v10, v7
	v_div_scale_f32 v10, vcc, v2, v0, v2
	v_mul_f32_e32 v11, v10, v7
	v_fma_f32 v12, -v1, v11, v10
	v_fmac_f32_e32 v11, v12, v7
	v_fma_f32 v1, -v1, v11, v10
	v_div_fmas_f32 v1, v1, v7, v11
	v_div_fixup_f32 v0, v1, v0, v2
	v_mul_f32_e32 v1, 0xbfb8aa3b, v3
	v_exp_f32_e32 v1, v1
	s_nop 0
	v_add_f32_e32 v1, 1.0, v1
	v_div_scale_f32 v2, s[0:1], v1, v1, v3
	v_rcp_f32_e32 v7, v2
	s_nop 0
	v_fma_f32 v10, -v2, v7, 1.0
	v_fmac_f32_e32 v7, v10, v7
	v_div_scale_f32 v10, vcc, v3, v1, v3
	v_mul_f32_e32 v11, v10, v7
	v_fma_f32 v12, -v2, v11, v10
	v_fmac_f32_e32 v11, v12, v7
	v_fma_f32 v2, -v2, v11, v10
	v_div_fmas_f32 v2, v2, v7, v11
	v_div_fixup_f32 v1, v2, v1, v3
	v_lshlrev_b32_e32 v2, 16, v19
	v_sub_f32_e32 v2, v2, v25
	v_mul_f32_e32 v2, v2, v24
	v_mul_f32_e32 v0, v0, v2
	v_and_b32_e32 v2, 0xffff0000, v19
	v_sub_f32_e32 v2, v2, v25
	v_mul_f32_e32 v2, v2, v24
	s_andn2_b64 vcc, exec, s[40:41]
	v_mul_f32_e32 v1, v1, v2
	v_cvt_pk_bf16_f32 v7, v0, v1
	global_store_dwordx4 v[8:9], v[4:7], off offset:256
	s_cbranch_vccnz .LBB0_872
	s_andn2_b64 vcc, exec, s[42:43]
	s_cbranch_vccnz .LBB0_871
	s_barrier
	s_branch .LBB0_871

; #define PG8_STAGE(bufoff, gbase, voff) do { _Pragma("unroll") for (int _i = 0; _i < 2; ++_i) \
;         __builtin_amdgcn_global_load_lds((const unsigned*)((const char*)(gbase) + (voff)[_i]), (LAS unsigned*)(lds + (bufoff) + ldsw + _i * 8192), 16, 0, 0); } while (0)
; #define PG8_LDA(dst, b, h) do { _Pragma("unroll") for (int m = 0; m < 4; ++m) _Pragma("unroll") for (int k = 0; k < 2; ++k) dst[m][k] = *(const LAS bf16x8*)(lds + PG8_SA(b, h) + aoff + m * 2048 + k * 1024); } while (0)
; #define PG8_LDB(dst, b, h) do { _Pragma("unroll") for (int n = 0; n < 2; ++n) _Pragma("unroll") for (int k = 0; k < 2; ++k) dst[n][k] = *(const LAS bf16x8*)(lds + PG8_SB(b, h) + boff + n * 2048 + k * 1024); } while (0)
; #define PG8_MMA(ai, bj, At, Bt) do { __builtin_amdgcn_s_setprio(1); _Pragma("unroll") for (int m = 0; m < 4; ++m) _Pragma("unroll") for (int n = 0; n < 2; ++n) _Pragma("unroll") for (int k = 0; k < 2; ++k) \
;         acc[ai][bj][m][n] = __builtin_amdgcn_mfma_f32_16x16x32_bf16(Bt[n][k], At[m][k], acc[ai][bj][m][n], 0, 0, 0); __builtin_amdgcn_s_setprio(0); } while (0)
; #define PG8_WAIT_V(n) asm volatile("s_waitcnt vmcnt(" #n ")" ::: "memory")
; #define PG8_WAIT_L(n) asm volatile("s_waitcnt lgkmcnt(" #n ")" ::: "memory")
; #define PG8_BAR __builtin_amdgcn_s_barrier()
; template <class Epi, class Map>
; __device__ __forceinline__ void gemm_phase(LAS unsigned char* lds, const Gemm g, const Sched<Map>& S, const Epi& E) {
;     ...
;         for (int t = 0; t < nt; t += 2) {
;             const bool last = (t == nt - 2);
;             const char* a1 = cA + (size_t)(t + 1) * kstep;
;             const char* a2 = last ? nA : cA + (size_t)(t + 2) * kstep; const char* b2 = last ? nB : cB + (size_t)(t + 2) * kstep;
;             const char* a3 = a2 + kstep; const char* b3 = b2 + kstep;
;             PG8_LDB(B0, 0, 0); PG8_LDB(B1, 0, 1); PG8_SCHED; PG8_LDA(At, 0, 0); PG8_STAGE(PG8_SA(1, 1), a1 + hstepA, voffA);
;             PG8_WAIT_V(8); PG8_WAIT_L(0); PG8_BAR; PG8_MMA(0, 0, At, B0); PG8_MMA(0, 1, At, B1); PG8_BAR; PG8_SCHED;
;     ...
;         for (int a = 0; a < 2; ++a)
; #pragma unroll
;             for (int b = 0; b < 2; ++b)
; #pragma unroll
;                 for (int m = 0; m < 4; ++m)
; #pragma unroll
;                     for (int n = 0; n < 2; ++n) acc[a][b][m][n] = (f32x4){0.f, 0.f, 0.f, 0.f};
;         cur = nxt; cA = nA; cB = nB; ++ui;
.LBB0_951:
	v_readlane_b32 s30, v245, 8
	v_readlane_b32 s31, v245, 9
	s_add_u32 s30, s30, s13
	s_addc_u32 s31, s31, 0
	s_and_b64 s[34:35], s[38:39], exec
	v_readlane_b32 s34, v245, 4
	s_cselect_b32 s33, s31, s37
	s_cselect_b32 s44, s30, s36
	s_add_u32 s34, s34, s12
	v_readlane_b32 s35, v245, 5
	s_addc_u32 s35, s35, 0
	s_and_b64 s[42:43], s[38:39], exec
	s_cselect_b32 s45, s35, s41
	s_cselect_b32 s46, s34, s40
	s_add_u32 s36, s36, 0x100080
	s_addc_u32 s37, s37, 0
	s_add_u32 s47, s40, 0x100
	v_mov_b32_e32 v0, 0
	s_addc_u32 s48, s41, 0
	s_mov_b32 s49, -2
	v_mov_b32_e32 v1, v0
	v_mov_b32_e32 v2, v0
	v_mov_b32_e32 v3, v0
	v_mov_b32_e32 v4, v0
	v_mov_b32_e32 v5, v0
	v_mov_b32_e32 v6, v0
	v_mov_b32_e32 v7, v0
	v_mov_b32_e32 v12, v0
	v_mov_b32_e32 v13, v0
	v_mov_b32_e32 v14, v0
	v_mov_b32_e32 v15, v0
	v_mov_b32_e32 v16, v0
	v_mov_b32_e32 v17, v0
	v_mov_b32_e32 v18, v0
	v_mov_b32_e32 v19, v0
	v_mov_b32_e32 v32, v0
	v_mov_b32_e32 v33, v0
	v_mov_b32_e32 v34, v0
	v_mov_b32_e32 v35, v0
	v_mov_b32_e32 v36, v0
	v_mov_b32_e32 v37, v0
	v_mov_b32_e32 v38, v0
	v_mov_b32_e32 v39, v0
	v_mov_b32_e32 v40, v0
	v_mov_b32_e32 v41, v0
	v_mov_b32_e32 v42, v0
	v_mov_b32_e32 v43, v0
	v_mov_b32_e32 v44, v0
	v_mov_b32_e32 v45, v0
	v_mov_b32_e32 v46, v0
	v_mov_b32_e32 v47, v0
	v_mov_b32_e32 v8, v0
	v_mov_b32_e32 v9, v0
	v_mov_b32_e32 v10, v0
	v_mov_b32_e32 v11, v0
	v_mov_b32_e32 v20, v0
	v_mov_b32_e32 v21, v0
	v_mov_b32_e32 v22, v0
	v_mov_b32_e32 v23, v0
	v_mov_b32_e32 v24, v0
	v_mov_b32_e32 v25, v0
	v_mov_b32_e32 v26, v0
	v_mov_b32_e32 v27, v0
	v_mov_b32_e32 v28, v0
	v_mov_b32_e32 v29, v0
	v_mov_b32_e32 v30, v0
	v_mov_b32_e32 v31, v0
	v_mov_b32_e32 v48, v0
	v_mov_b32_e32 v49, v0
	v_mov_b32_e32 v50, v0
	v_mov_b32_e32 v51, v0
	v_mov_b32_e32 v52, v0
	v_mov_b32_e32 v53, v0
	v_mov_b32_e32 v54, v0
	v_mov_b32_e32 v55, v0
	v_mov_b32_e32 v56, v0
	v_mov_b32_e32 v57, v0
	v_mov_b32_e32 v58, v0
	v_mov_b32_e32 v59, v0
	v_mov_b32_e32 v60, v0
	v_mov_b32_e32 v61, v0
	v_mov_b32_e32 v62, v0
	v_mov_b32_e32 v63, v0
	v_mov_b32_e32 v76, v0
	v_mov_b32_e32 v77, v0
	v_mov_b32_e32 v78, v0
	v_mov_b32_e32 v79, v0
	v_mov_b32_e32 v80, v0
	v_mov_b32_e32 v81, v0
	v_mov_b32_e32 v82, v0
	v_mov_b32_e32 v83, v0
	v_mov_b32_e32 v84, v0
	v_mov_b32_e32 v85, v0
	v_mov_b32_e32 v86, v0
	v_mov_b32_e32 v87, v0
	v_mov_b32_e32 v88, v0
	v_mov_b32_e32 v89, v0
	v_mov_b32_e32 v90, v0
	v_mov_b32_e32 v91, v0
	v_mov_b32_e32 v112, v0
	v_mov_b32_e32 v113, v0
	v_mov_b32_e32 v114, v0
	v_mov_b32_e32 v115, v0
	v_mov_b32_e32 v116, v0
	v_mov_b32_e32 v117, v0
	v_mov_b32_e32 v118, v0
	v_mov_b32_e32 v119, v0
	v_mov_b32_e32 v120, v0
	v_mov_b32_e32 v121, v0
	v_mov_b32_e32 v122, v0
	v_mov_b32_e32 v123, v0
	v_mov_b32_e32 v124, v0
	v_mov_b32_e32 v125, v0
	v_mov_b32_e32 v126, v0
	v_mov_b32_e32 v127, v0
	v_mov_b32_e32 v92, v0
	v_mov_b32_e32 v93, v0
	v_mov_b32_e32 v94, v0
	v_mov_b32_e32 v95, v0
	v_mov_b32_e32 v96, v0
	v_mov_b32_e32 v97, v0
	v_mov_b32_e32 v98, v0
	v_mov_b32_e32 v99, v0
	v_mov_b32_e32 v100, v0
	v_mov_b32_e32 v101, v0
	v_mov_b32_e32 v102, v0
	v_mov_b32_e32 v103, v0
	v_mov_b32_e32 v104, v0
	v_mov_b32_e32 v105, v0
	v_mov_b32_e32 v106, v0
	v_mov_b32_e32 v107, v0
	v_mov_b32_e32 v128, v0
	v_mov_b32_e32 v129, v0
	v_mov_b32_e32 v130, v0
	v_mov_b32_e32 v131, v0
	v_mov_b32_e32 v132, v0
	v_mov_b32_e32 v133, v0
	v_mov_b32_e32 v134, v0
	v_mov_b32_e32 v135, v0
	v_mov_b32_e32 v136, v0
	v_mov_b32_e32 v137, v0
	v_mov_b32_e32 v138, v0
	v_mov_b32_e32 v139, v0
	v_mov_b32_e32 v140, v0
	v_mov_b32_e32 v141, v0
	v_mov_b32_e32 v142, v0
	v_mov_b32_e32 v143, v0
.LBB0_952:
	s_add_u32 s40, s36, 0xfff00080
	s_addc_u32 s41, s37, -1
	s_add_i32 s50, 0, 0x10000
	s_cmp_eq_u32 s49, 60
	s_cselect_b32 s43, s33, s41
	s_cselect_b32 s42, s44, s40
	s_cselect_b32 s41, s45, s48
	s_cselect_b32 s40, s46, s47
	s_add_i32 s52, 0, 0x14000
	v_add_u32_e32 v108, s50, v173
	v_add_u32_e32 v170, s52, v173
	ds_read_b128 v[64:67], v108
	ds_read_b128 v[68:71], v108 offset:1024
	ds_read_b128 v[72:75], v108 offset:2048
	ds_read_b128 v[108:111], v108 offset:3072
	ds_read_b128 v[166:169], v170
	ds_read_b128 v[176:179], v170 offset:1024
	ds_read_b128 v[192:195], v170 offset:2048
	ds_read_b128 v[196:199], v170 offset:3072
	v_lshl_add_u64 v[170:171], s[36:37], 0, v[162:163]
	s_add_i32 m0, s1, 0xc000
	ds_read_b128 v[200:203], v174
	ds_read_b128 v[204:207], v174 offset:1024
	ds_read_b128 v[208:211], v174 offset:2048
	ds_read_b128 v[212:215], v174 offset:3072
	ds_read_b128 v[216:219], v174 offset:4096
	ds_read_b128 v[220:223], v174 offset:5120
	ds_read_b128 v[224:227], v174 offset:6144
	ds_read_b128 v[228:231], v174 offset:7168
	global_load_lds_dwordx4 v[170:171], off
	v_lshl_add_u64 v[170:171], s[36:37], 0, v[164:165]
	s_add_i32 m0, s1, 0xe000
	s_nop 0
	global_load_lds_dwordx4 v[170:171], off
	s_waitcnt vmcnt(8)
	s_waitcnt lgkmcnt(0)
	s_barrier
; #define PG8_STAGE(bufoff, gbase, voff) do { _Pragma("unroll") for (int _i = 0; _i < 2; ++_i) \
;         __builtin_amdgcn_global_load_lds((const unsigned*)((const char*)(gbase) + (voff)[_i]), (LAS unsigned*)(lds + (bufoff) + ldsw + _i * 8192), 16, 0, 0); } while (0)
; #define PG8_LDA(dst, b, h) do { _Pragma("unroll") for (int m = 0; m < 4; ++m) _Pragma("unroll") for (int k = 0; k < 2; ++k) dst[m][k] = *(const LAS bf16x8*)(lds + PG8_SA(b, h) + aoff + m * 2048 + k * 1024); } while (0)
; #define PG8_MMA(ai, bj, At, Bt) do { __builtin_amdgcn_s_setprio(1); _Pragma("unroll") for (int m = 0; m < 4; ++m) _Pragma("unroll") for (int n = 0; n < 2; ++n) _Pragma("unroll") for (int k = 0; k < 2; ++k) \
;         acc[ai][bj][m][n] = __builtin_amdgcn_mfma_f32_16x16x32_bf16(Bt[n][k], At[m][k], acc[ai][bj][m][n], 0, 0, 0); __builtin_amdgcn_s_setprio(0); } while (0)
; #define PG8_WAIT_V(n) asm volatile("s_waitcnt vmcnt(" #n ")" ::: "memory")
; #define PG8_WAIT_L(n) asm volatile("s_waitcnt lgkmcnt(" #n ")" ::: "memory")
; #define PG8_BAR __builtin_amdgcn_s_barrier()
; #define PG8_SCHED __builtin_amdgcn_sched_barrier(0)
; template <class Epi, class Map>
; __device__ __forceinline__ void gemm_phase(LAS unsigned char* lds, const Gemm g, const Sched<Map>& S, const Epi& E) {
;     ...
;             PG8_WAIT_V(8); PG8_WAIT_L(0); PG8_BAR; PG8_MMA(0, 0, At, B0); PG8_MMA(0, 1, At, B1); PG8_BAR; PG8_SCHED;
;             PG8_LDA(At, 0, 1); PG8_STAGE(PG8_SB(0, 0), b2, voffB); PG8_STAGE(PG8_SB(0, 1), b2 + hstepB, voffB); PG8_STAGE(PG8_SA(0, 0), a2, voffA);
;             PG8_WAIT_V(8); PG8_WAIT_L(0); PG8_BAR; PG8_MMA(1, 0, At, B0); PG8_MMA(1, 1, At, B1); PG8_BAR; PG8_SCHED;
	s_waitcnt lgkmcnt(0)
	v_mfma_f32_16x16x32_bf16 v[140:143], v[64:67], v[200:203], v[140:143]
	v_mfma_f32_16x16x32_bf16 v[136:139], v[72:75], v[200:203], v[136:139]
	v_mfma_f32_16x16x32_bf16 v[132:135], v[64:67], v[208:211], v[132:135]
	v_mfma_f32_16x16x32_bf16 v[128:131], v[72:75], v[208:211], v[128:131]
	v_mfma_f32_16x16x32_bf16 v[104:107], v[64:67], v[216:219], v[104:107]
	v_mfma_f32_16x16x32_bf16 v[100:103], v[72:75], v[216:219], v[100:103]
	v_mfma_f32_16x16x32_bf16 v[96:99], v[64:67], v[224:227], v[96:99]
	v_mfma_f32_16x16x32_bf16 v[92:95], v[72:75], v[224:227], v[92:95]
	v_mfma_f32_16x16x32_bf16 v[140:143], v[68:71], v[204:207], v[140:143]
	v_mfma_f32_16x16x32_bf16 v[136:139], v[108:111], v[204:207], v[136:139]
	v_mfma_f32_16x16x32_bf16 v[132:135], v[68:71], v[212:215], v[132:135]
	v_mfma_f32_16x16x32_bf16 v[128:131], v[108:111], v[212:215], v[128:131]
	v_mfma_f32_16x16x32_bf16 v[104:107], v[68:71], v[220:223], v[104:107]
	v_mfma_f32_16x16x32_bf16 v[100:103], v[108:111], v[220:223], v[100:103]
	v_mfma_f32_16x16x32_bf16 v[96:99], v[68:71], v[228:231], v[96:99]
	v_mfma_f32_16x16x32_bf16 v[92:95], v[108:111], v[228:231], v[92:95]
	v_mfma_f32_16x16x32_bf16 v[124:127], v[166:169], v[200:203], v[124:127]
	v_mfma_f32_16x16x32_bf16 v[120:123], v[192:195], v[200:203], v[120:123]
	v_mfma_f32_16x16x32_bf16 v[116:119], v[166:169], v[208:211], v[116:119]
	v_mfma_f32_16x16x32_bf16 v[112:115], v[192:195], v[208:211], v[112:115]
	v_mfma_f32_16x16x32_bf16 v[88:91], v[166:169], v[216:219], v[88:91]
	v_mfma_f32_16x16x32_bf16 v[84:87], v[192:195], v[216:219], v[84:87]
	v_mfma_f32_16x16x32_bf16 v[80:83], v[166:169], v[224:227], v[80:83]
	v_mfma_f32_16x16x32_bf16 v[76:79], v[192:195], v[224:227], v[76:79]
	v_mfma_f32_16x16x32_bf16 v[124:127], v[176:179], v[204:207], v[124:127]
	v_mfma_f32_16x16x32_bf16 v[120:123], v[196:199], v[204:207], v[120:123]
	v_mfma_f32_16x16x32_bf16 v[116:119], v[176:179], v[212:215], v[116:119]
	v_mfma_f32_16x16x32_bf16 v[112:115], v[196:199], v[212:215], v[112:115]
	v_mfma_f32_16x16x32_bf16 v[88:91], v[176:179], v[220:223], v[88:91]
	v_mfma_f32_16x16x32_bf16 v[84:87], v[196:199], v[220:223], v[84:87]
	v_mfma_f32_16x16x32_bf16 v[80:83], v[176:179], v[228:231], v[80:83]
	v_mfma_f32_16x16x32_bf16 v[76:79], v[196:199], v[228:231], v[76:79]
	s_barrier
	s_add_i32 s50, s50, s0
	v_lshl_add_u64 v[170:171], s[40:41], 0, v[144:145]
	s_mov_b32 m0, s50
	ds_read_b128 v[200:203], v174 offset:16384
	ds_read_b128 v[204:207], v174 offset:17408
	ds_read_b128 v[208:211], v174 offset:18432
	ds_read_b128 v[212:215], v174 offset:19456
	ds_read_b128 v[216:219], v174 offset:20480
	ds_read_b128 v[220:223], v174 offset:21504
	ds_read_b128 v[224:227], v174 offset:22528
	ds_read_b128 v[228:231], v174 offset:23552
	global_load_lds_dwordx4 v[170:171], off
	s_add_i32 m0, s50, 0x2000
	s_add_u32 s50, s40, 0x100000
	v_lshl_add_u64 v[180:181], s[40:41], 0, v[160:161]
	s_addc_u32 s51, s41, 0
	s_add_i32 s52, s52, s0
	global_load_lds_dwordx4 v[180:181], off
	v_lshl_add_u64 v[232:233], s[50:51], 0, v[144:145]
	s_mov_b32 m0, s52
	v_lshl_add_u64 v[234:235], s[42:43], 0, v[160:161]
	global_load_lds_dwordx4 v[232:233], off
	v_lshl_add_u64 v[232:233], s[50:51], 0, v[160:161]
	s_add_i32 m0, s52, 0x2000
	s_nop 0
	global_load_lds_dwordx4 v[232:233], off
	v_lshl_add_u64 v[232:233], s[42:43], 0, v[144:145]
	s_mov_b32 m0, s1
	s_nop 0
	global_load_lds_dwordx4 v[232:233], off
	s_mov_b32 m0, s2
	s_nop 0
	global_load_lds_dwordx4 v[234:235], off
	s_waitcnt vmcnt(8)
	s_waitcnt lgkmcnt(0)
	s_barrier
	s_waitcnt lgkmcnt(0)
	v_mfma_f32_16x16x32_bf16 v[60:63], v[64:67], v[200:203], v[60:63]
	v_mfma_f32_16x16x32_bf16 v[56:59], v[72:75], v[200:203], v[56:59]
	v_mfma_f32_16x16x32_bf16 v[52:55], v[64:67], v[208:211], v[52:55]
	v_mfma_f32_16x16x32_bf16 v[48:51], v[72:75], v[208:211], v[48:51]
	v_mfma_f32_16x16x32_bf16 v[28:31], v[64:67], v[216:219], v[28:31]
	v_mfma_f32_16x16x32_bf16 v[24:27], v[72:75], v[216:219], v[24:27]
	v_mfma_f32_16x16x32_bf16 v[20:23], v[64:67], v[224:227], v[20:23]
	v_mfma_f32_16x16x32_bf16 v[8:11], v[72:75], v[224:227], v[8:11]
	v_mfma_f32_16x16x32_bf16 v[60:63], v[68:71], v[204:207], v[60:63]
	v_mfma_f32_16x16x32_bf16 v[56:59], v[108:111], v[204:207], v[56:59]
	v_mfma_f32_16x16x32_bf16 v[52:55], v[68:71], v[212:215], v[52:55]
	v_mfma_f32_16x16x32_bf16 v[48:51], v[108:111], v[212:215], v[48:51]
	v_mfma_f32_16x16x32_bf16 v[28:31], v[68:71], v[220:223], v[28:31]
	v_mfma_f32_16x16x32_bf16 v[24:27], v[108:111], v[220:223], v[24:27]
	v_mfma_f32_16x16x32_bf16 v[20:23], v[68:71], v[228:231], v[20:23]
	v_mfma_f32_16x16x32_bf16 v[8:11], v[108:111], v[228:231], v[8:11]
	v_mfma_f32_16x16x32_bf16 v[44:47], v[166:169], v[200:203], v[44:47]
	v_mfma_f32_16x16x32_bf16 v[40:43], v[192:195], v[200:203], v[40:43]
	v_mfma_f32_16x16x32_bf16 v[36:39], v[166:169], v[208:211], v[36:39]
	v_mfma_f32_16x16x32_bf16 v[32:35], v[192:195], v[208:211], v[32:35]
	v_mfma_f32_16x16x32_bf16 v[16:19], v[166:169], v[216:219], v[16:19]
	v_mfma_f32_16x16x32_bf16 v[12:15], v[192:195], v[216:219], v[12:15]
	v_mfma_f32_16x16x32_bf16 v[4:7], v[166:169], v[224:227], v[4:7]
	v_mfma_f32_16x16x32_bf16 v[0:3], v[192:195], v[224:227], v[0:3]
	v_mfma_f32_16x16x32_bf16 v[44:47], v[176:179], v[204:207], v[44:47]
	v_mfma_f32_16x16x32_bf16 v[40:43], v[196:199], v[204:207], v[40:43]
	v_mfma_f32_16x16x32_bf16 v[36:39], v[176:179], v[212:215], v[36:39]
	v_mfma_f32_16x16x32_bf16 v[32:35], v[196:199], v[212:215], v[32:35]
	v_mfma_f32_16x16x32_bf16 v[16:19], v[176:179], v[220:223], v[16:19]
	v_mfma_f32_16x16x32_bf16 v[12:15], v[196:199], v[220:223], v[12:15]
	v_mfma_f32_16x16x32_bf16 v[4:7], v[176:179], v[228:231], v[4:7]
	v_mfma_f32_16x16x32_bf16 v[0:3], v[196:199], v[228:231], v[0:3]
	s_barrier
; #define PG8_STAGE(bufoff, gbase, voff) do { _Pragma("unroll") for (int _i = 0; _i < 2; ++_i) \
;         __builtin_amdgcn_global_load_lds((const unsigned*)((const char*)(gbase) + (voff)[_i]), (LAS unsigned*)(lds + (bufoff) + ldsw + _i * 8192), 16, 0, 0); } while (0)
; #define PG8_LDA(dst, b, h) do { _Pragma("unroll") for (int m = 0; m < 4; ++m) _Pragma("unroll") for (int k = 0; k < 2; ++k) dst[m][k] = *(const LAS bf16x8*)(lds + PG8_SA(b, h) + aoff + m * 2048 + k * 1024); } while (0)
; #define PG8_LDB(dst, b, h) do { _Pragma("unroll") for (int n = 0; n < 2; ++n) _Pragma("unroll") for (int k = 0; k < 2; ++k) dst[n][k] = *(const LAS bf16x8*)(lds + PG8_SB(b, h) + boff + n * 2048 + k * 1024); } while (0)
; #define PG8_MMA(ai, bj, At, Bt) do { __builtin_amdgcn_s_setprio(1); _Pragma("unroll") for (int m = 0; m < 4; ++m) _Pragma("unroll") for (int n = 0; n < 2; ++n) _Pragma("unroll") for (int k = 0; k < 2; ++k) \
;         acc[ai][bj][m][n] = __builtin_amdgcn_mfma_f32_16x16x32_bf16(Bt[n][k], At[m][k], acc[ai][bj][m][n], 0, 0, 0); __builtin_amdgcn_s_setprio(0); } while (0)
; #define PG8_WAIT_V(n) asm volatile("s_waitcnt vmcnt(" #n ")" ::: "memory")
; #define PG8_WAIT_L(n) asm volatile("s_waitcnt lgkmcnt(" #n ")" ::: "memory")
; #define PG8_BAR __builtin_amdgcn_s_barrier()
; #define PG8_SCHED __builtin_amdgcn_sched_barrier(0)
; template <class Epi, class Map>
; __device__ __forceinline__ void gemm_phase(LAS unsigned char* lds, const Gemm g, const Sched<Map>& S, const Epi& E) {
;     ...
;             PG8_LDB(B0, 1, 0); PG8_LDB(B1, 1, 1); PG8_SCHED; PG8_LDA(At, 1, 0); PG8_STAGE(PG8_SA(0, 1), a2 + hstepA, voffA);
;             PG8_WAIT_V(8); PG8_WAIT_L(0); PG8_BAR; PG8_MMA(0, 0, At, B0); PG8_MMA(0, 1, At, B1); PG8_BAR; PG8_SCHED;
;             PG8_LDA(At, 1, 1); PG8_STAGE(PG8_SB(1, 0), b3, voffB); PG8_STAGE(PG8_SB(1, 1), b3 + hstepB, voffB); PG8_STAGE(PG8_SA(1, 0), a3, voffA);
;             PG8_WAIT_V(8); PG8_WAIT_L(0); PG8_BAR; PG8_MMA(1, 0, At, B0); PG8_MMA(1, 1, At, B1); PG8_BAR; PG8_SCHED;
	s_add_i32 s50, 0, 0x18000
	s_add_i32 s51, 0, 0x1c000
	v_add_u32_e32 v108, s50, v173
	v_add_u32_e32 v175, s51, v173
	ds_read_b128 v[64:67], v108
	ds_read_b128 v[68:71], v108 offset:1024
	ds_read_b128 v[72:75], v108 offset:2048
	ds_read_b128 v[108:111], v108 offset:3072
	ds_read_b128 v[166:169], v175
	ds_read_b128 v[176:179], v175 offset:1024
	ds_read_b128 v[192:195], v175 offset:2048
	ds_read_b128 v[196:199], v175 offset:3072
	s_add_u32 s42, s42, 0x100000
	s_addc_u32 s43, s43, 0
	s_mov_b32 m0, s3
	v_lshl_add_u64 v[236:237], s[42:43], 0, v[144:145]
	ds_read_b128 v[200:203], v174 offset:32768
	ds_read_b128 v[204:207], v174 offset:33792
	ds_read_b128 v[208:211], v174 offset:34816
	ds_read_b128 v[212:215], v174 offset:35840
	ds_read_b128 v[216:219], v174 offset:36864
	ds_read_b128 v[220:223], v174 offset:37888
	ds_read_b128 v[224:227], v174 offset:38912
	ds_read_b128 v[228:231], v174 offset:39936
	global_load_lds_dwordx4 v[236:237], off
	v_lshl_add_u64 v[236:237], s[42:43], 0, v[160:161]
	s_mov_b32 m0, s4
	s_nop 0
	global_load_lds_dwordx4 v[236:237], off
	s_waitcnt vmcnt(8)
	s_waitcnt lgkmcnt(0)
	s_barrier
	s_waitcnt lgkmcnt(0)
	v_mfma_f32_16x16x32_bf16 v[140:143], v[64:67], v[200:203], v[140:143]
	v_mfma_f32_16x16x32_bf16 v[136:139], v[72:75], v[200:203], v[136:139]
	v_mfma_f32_16x16x32_bf16 v[132:135], v[64:67], v[208:211], v[132:135]
	v_mfma_f32_16x16x32_bf16 v[128:131], v[72:75], v[208:211], v[128:131]
	v_mfma_f32_16x16x32_bf16 v[104:107], v[64:67], v[216:219], v[104:107]
	v_mfma_f32_16x16x32_bf16 v[100:103], v[72:75], v[216:219], v[100:103]
	v_mfma_f32_16x16x32_bf16 v[96:99], v[64:67], v[224:227], v[96:99]
	v_mfma_f32_16x16x32_bf16 v[92:95], v[72:75], v[224:227], v[92:95]
	v_mfma_f32_16x16x32_bf16 v[140:143], v[68:71], v[204:207], v[140:143]
	v_mfma_f32_16x16x32_bf16 v[136:139], v[108:111], v[204:207], v[136:139]
	v_mfma_f32_16x16x32_bf16 v[132:135], v[68:71], v[212:215], v[132:135]
	v_mfma_f32_16x16x32_bf16 v[128:131], v[108:111], v[212:215], v[128:131]
	v_mfma_f32_16x16x32_bf16 v[104:107], v[68:71], v[220:223], v[104:107]
	v_mfma_f32_16x16x32_bf16 v[100:103], v[108:111], v[220:223], v[100:103]
	v_mfma_f32_16x16x32_bf16 v[96:99], v[68:71], v[228:231], v[96:99]
	v_mfma_f32_16x16x32_bf16 v[92:95], v[108:111], v[228:231], v[92:95]
	v_mfma_f32_16x16x32_bf16 v[124:127], v[166:169], v[200:203], v[124:127]
	v_mfma_f32_16x16x32_bf16 v[120:123], v[192:195], v[200:203], v[120:123]
	v_mfma_f32_16x16x32_bf16 v[116:119], v[166:169], v[208:211], v[116:119]
	v_mfma_f32_16x16x32_bf16 v[112:115], v[192:195], v[208:211], v[112:115]
	v_mfma_f32_16x16x32_bf16 v[88:91], v[166:169], v[216:219], v[88:91]
	v_mfma_f32_16x16x32_bf16 v[84:87], v[192:195], v[216:219], v[84:87]
	v_mfma_f32_16x16x32_bf16 v[80:83], v[166:169], v[224:227], v[80:83]
	v_mfma_f32_16x16x32_bf16 v[76:79], v[192:195], v[224:227], v[76:79]
	v_mfma_f32_16x16x32_bf16 v[124:127], v[176:179], v[204:207], v[124:127]
	v_mfma_f32_16x16x32_bf16 v[120:123], v[196:199], v[204:207], v[120:123]
	v_mfma_f32_16x16x32_bf16 v[116:119], v[176:179], v[212:215], v[116:119]
	v_mfma_f32_16x16x32_bf16 v[112:115], v[196:199], v[212:215], v[112:115]
	v_mfma_f32_16x16x32_bf16 v[88:91], v[176:179], v[220:223], v[88:91]
	v_mfma_f32_16x16x32_bf16 v[84:87], v[196:199], v[220:223], v[84:87]
	v_mfma_f32_16x16x32_bf16 v[80:83], v[176:179], v[228:231], v[80:83]
	v_mfma_f32_16x16x32_bf16 v[76:79], v[196:199], v[228:231], v[76:79]
	s_barrier
	s_add_i32 s42, s50, s0
	v_lshl_add_u64 v[170:171], v[170:171], 0, s[82:83]
	s_mov_b32 m0, s42
	ds_read_b128 v[200:203], v174 offset:49152
	ds_read_b128 v[204:207], v174 offset:50176
	ds_read_b128 v[208:211], v174 offset:51200
	ds_read_b128 v[212:215], v174 offset:52224
	ds_read_b128 v[216:219], v174 offset:53248
	ds_read_b128 v[220:223], v174 offset:54272
	ds_read_b128 v[224:227], v174 offset:55296
	ds_read_b128 v[228:231], v174 offset:56320
	global_load_lds_dwordx4 v[170:171], off
	s_add_i32 m0, s42, 0x2000
	s_add_u32 s40, s40, 0x100080
	v_lshl_add_u64 v[170:171], v[180:181], 0, s[82:83]
	s_addc_u32 s41, s41, 0
	s_add_i32 s42, s51, s0
	global_load_lds_dwordx4 v[170:171], off
	v_lshl_add_u64 v[170:171], s[40:41], 0, v[144:145]
	s_mov_b32 m0, s42
	s_nop 0
	global_load_lds_dwordx4 v[170:171], off
	v_lshl_add_u64 v[170:171], s[40:41], 0, v[160:161]
	s_add_i32 m0, s42, 0x2000
	s_nop 0
	global_load_lds_dwordx4 v[170:171], off
	v_lshl_add_u64 v[170:171], v[232:233], 0, s[82:83]
	s_mov_b32 m0, s7
	s_nop 0
	global_load_lds_dwordx4 v[170:171], off
	v_lshl_add_u64 v[170:171], v[234:235], 0, s[82:83]
	s_mov_b32 m0, s8
	s_nop 0
	global_load_lds_dwordx4 v[170:171], off
	s_waitcnt vmcnt(8)
	s_waitcnt lgkmcnt(0)
	s_barrier
; #define PG8_MMA(ai, bj, At, Bt) do { __builtin_amdgcn_s_setprio(1); _Pragma("unroll") for (int m = 0; m < 4; ++m) _Pragma("unroll") for (int n = 0; n < 2; ++n) _Pragma("unroll") for (int k = 0; k < 2; ++k) \
;         acc[ai][bj][m][n] = __builtin_amdgcn_mfma_f32_16x16x32_bf16(Bt[n][k], At[m][k], acc[ai][bj][m][n], 0, 0, 0); __builtin_amdgcn_s_setprio(0); } while (0)
; #define PG8_WAIT_V(n) asm volatile("s_waitcnt vmcnt(" #n ")" ::: "memory")
; #define PG8_WAIT_L(n) asm volatile("s_waitcnt lgkmcnt(" #n ")" ::: "memory")
; #define PG8_BAR __builtin_amdgcn_s_barrier()
; #define PG8_SCHED __builtin_amdgcn_sched_barrier(0)
; template <class Epi, class Map>
; __device__ __forceinline__ void gemm_phase(LAS unsigned char* lds, const Gemm g, const Sched<Map>& S, const Epi& E) {
;     ...
;             PG8_WAIT_V(8); PG8_WAIT_L(0); PG8_BAR; PG8_MMA(1, 0, At, B0); PG8_MMA(1, 1, At, B1); PG8_BAR; PG8_SCHED;
;         }
;         if (wr == 0) PG8_BAR;
;     __device__ __forceinline__ void operator()(const Acc& acc, const Unit& u, int wr, int wc, int fr, int fq) const {
;         asm volatile("" : "+v"(fr), "+v"(fq));
;         const int row0 = u.pm * BM + wr * 64 + fr, col0 = u.pn * BM + wc * 32 + 4 * fq;
;         const float* gp = gate + (size_t)(u.pm >> 6) * gate_bstride + col0;
;         f32x4 gv[2][2];
; #pragma unroll
;         for (int bj = 0; bj < 2; ++bj)
; #pragma unroll
;             for (int n = 0; n < 2; ++n) gv[bj][n] = *(const f32x4*)(gp + bj * HALF + n * 16);
; #pragma unroll
;         for (int aim = 0; aim < 4; ++aim) { const int ai = aim >> 1, m0 = (aim & 1) * 2;
;             f32x4 bs[2][2][2];
; #pragma unroll
;             for (int mm = 0; mm < 2; ++mm) { const size_t off = (size_t)(row0 + ai * HALF + (m0 + mm) * 16) * D + col0;
; #pragma unroll
;                 for (int bj = 0; bj < 2; ++bj)
; #pragma unroll
;                     for (int n = 0; n < 2; ++n) bs[mm][bj][n] = *(const f32x4*)(base + off + bj * HALF + n * 16); }
; #pragma unroll
;             for (int mm = 0; mm < 2; ++mm) { const size_t off = (size_t)(row0 + ai * HALF + (m0 + mm) * 16) * D + col0;
; #pragma unroll
;                 for (int bj = 0; bj < 2; ++bj)
; #pragma unroll
;                     for (int n = 0; n < 2; ++n) *(f32x4*)(out + off + bj * HALF + n * 16) = bs[mm][bj][n] + gv[bj][n] * acc[ai][bj][m0 + mm][n]; }
	s_waitcnt lgkmcnt(0)
	v_mfma_f32_16x16x32_bf16 v[60:63], v[64:67], v[200:203], v[60:63]
	v_mfma_f32_16x16x32_bf16 v[56:59], v[72:75], v[200:203], v[56:59]
	v_mfma_f32_16x16x32_bf16 v[52:55], v[64:67], v[208:211], v[52:55]
	v_mfma_f32_16x16x32_bf16 v[48:51], v[72:75], v[208:211], v[48:51]
	v_mfma_f32_16x16x32_bf16 v[28:31], v[64:67], v[216:219], v[28:31]
	v_mfma_f32_16x16x32_bf16 v[24:27], v[72:75], v[216:219], v[24:27]
	v_mfma_f32_16x16x32_bf16 v[20:23], v[64:67], v[224:227], v[20:23]
	v_mfma_f32_16x16x32_bf16 v[8:11], v[72:75], v[224:227], v[8:11]
	v_mfma_f32_16x16x32_bf16 v[60:63], v[68:71], v[204:207], v[60:63]
	v_mfma_f32_16x16x32_bf16 v[56:59], v[108:111], v[204:207], v[56:59]
	v_mfma_f32_16x16x32_bf16 v[52:55], v[68:71], v[212:215], v[52:55]
	v_mfma_f32_16x16x32_bf16 v[48:51], v[108:111], v[212:215], v[48:51]
	v_mfma_f32_16x16x32_bf16 v[28:31], v[68:71], v[220:223], v[28:31]
	v_mfma_f32_16x16x32_bf16 v[24:27], v[108:111], v[220:223], v[24:27]
	v_mfma_f32_16x16x32_bf16 v[20:23], v[68:71], v[228:231], v[20:23]
	v_mfma_f32_16x16x32_bf16 v[8:11], v[108:111], v[228:231], v[8:11]
	v_mfma_f32_16x16x32_bf16 v[44:47], v[166:169], v[200:203], v[44:47]
	v_mfma_f32_16x16x32_bf16 v[40:43], v[192:195], v[200:203], v[40:43]
	v_mfma_f32_16x16x32_bf16 v[36:39], v[166:169], v[208:211], v[36:39]
	v_mfma_f32_16x16x32_bf16 v[32:35], v[192:195], v[208:211], v[32:35]
	v_mfma_f32_16x16x32_bf16 v[16:19], v[166:169], v[216:219], v[16:19]
	v_mfma_f32_16x16x32_bf16 v[12:15], v[192:195], v[216:219], v[12:15]
	v_mfma_f32_16x16x32_bf16 v[4:7], v[166:169], v[224:227], v[4:7]
	v_mfma_f32_16x16x32_bf16 v[0:3], v[192:195], v[224:227], v[0:3]
	v_mfma_f32_16x16x32_bf16 v[44:47], v[176:179], v[204:207], v[44:47]
	v_mfma_f32_16x16x32_bf16 v[40:43], v[196:199], v[204:207], v[40:43]
	v_mfma_f32_16x16x32_bf16 v[36:39], v[176:179], v[212:215], v[36:39]
	v_mfma_f32_16x16x32_bf16 v[32:35], v[196:199], v[212:215], v[32:35]
	v_mfma_f32_16x16x32_bf16 v[16:19], v[176:179], v[220:223], v[16:19]
	v_mfma_f32_16x16x32_bf16 v[12:15], v[196:199], v[220:223], v[12:15]
	v_mfma_f32_16x16x32_bf16 v[4:7], v[176:179], v[228:231], v[4:7]
	v_mfma_f32_16x16x32_bf16 v[0:3], v[196:199], v[228:231], v[0:3]
	s_barrier
	s_add_i32 s49, s49, 2
	s_add_u32 s36, s36, 0x100
	s_addc_u32 s37, s37, 0
	s_add_u32 s47, s47, 0x100
	s_addc_u32 s48, s48, 0
	s_cmp_gt_u32 s49, 61
	s_cbranch_scc0 .LBB0_952
	s_and_b64 vcc, exec, s[28:29]
	s_cbranch_vccz .LBB0_955
.LBB0_955:
	v_mov_b32_e32 v168, v159
	v_mov_b32_e32 v64, v172
	s_lshl_b32 s15, s15, 8
	s_or_b32 s15, s15, s6
	s_lshl_b32 s14, s14, 8
	v_lshl_add_u32 v64, v64, 2, s15
	s_add_i32 s14, s14, s5
	v_ashrrev_i32_e32 v65, 31, v64
	v_add_u32_e32 v170, s14, v168
	v_lshlrev_b64 v[166:167], 2, v[64:65]
	v_ashrrev_i32_e32 v171, 31, v170
	v_lshl_add_u64 v[168:169], s[18:19], 0, v[166:167]
	v_lshlrev_b64 v[170:171], 13, v[170:171]
	v_lshl_add_u64 v[64:65], s[24:25], 0, v[166:167]
	v_lshl_add_u64 v[180:181], v[168:169], 0, v[170:171]
	s_mov_b64 s[14:15], 0x20000
	global_load_dwordx4 v[108:111], v[64:65], off
	global_load_dwordx4 v[72:75], v[64:65], off offset:64
	global_load_dwordx4 v[68:71], v[64:65], off offset:512
	s_nop 0
	global_load_dwordx4 v[64:67], v[64:65], off offset:576
	s_nop 0
	global_load_dwordx4 v[176:179], v[180:181], off
	global_load_dwordx4 v[192:195], v[180:181], off offset:64
	global_load_dwordx4 v[196:199], v[180:181], off offset:512
	global_load_dwordx4 v[200:203], v[180:181], off offset:576
	v_lshl_add_u64 v[180:181], v[170:171], 0, s[14:15]
	v_lshl_add_u64 v[216:217], v[168:169], 0, v[180:181]
	global_load_dwordx4 v[204:207], v[216:217], off
	global_load_dwordx4 v[208:211], v[216:217], off offset:64
	global_load_dwordx4 v[212:215], v[216:217], off offset:512
	s_nop 0
	global_load_dwordx4 v[216:219], v[216:217], off offset:576
	s_mov_b64 s[14:15], 0x40000
	s_mov_b64 s[36:37], -1
	s_andn2_b64 vcc, exec, s[38:39]
	s_waitcnt vmcnt(0)
	v_pk_fma_f32 v[140:141], v[140:141], v[108:109], v[176:177]
	v_lshl_add_u64 v[176:177], s[20:21], 0, v[170:171]
	v_lshl_add_u64 v[176:177], v[176:177], 0, v[166:167]
	v_pk_fma_f32 v[126:127], v[126:127], v[70:71], v[198:199]
	v_pk_fma_f32 v[124:125], v[124:125], v[68:69], v[196:197]
	global_store_dwordx4 v[176:177], v[124:127], off offset:512
	v_pk_fma_f32 v[122:123], v[122:123], v[66:67], v[202:203]
	v_pk_fma_f32 v[120:121], v[120:121], v[64:65], v[200:201]
	v_lshl_add_u64 v[124:125], s[20:21], 0, v[180:181]
	global_store_dwordx4 v[176:177], v[120:123], off offset:576
	v_lshl_add_u64 v[124:125], v[124:125], 0, v[166:167]
	v_pk_fma_f32 v[142:143], v[142:143], v[110:111], v[178:179]
	v_pk_fma_f32 v[122:123], v[134:135], v[110:111], v[206:207]
	v_pk_fma_f32 v[120:121], v[132:133], v[108:109], v[204:205]
	v_pk_fma_f32 v[138:139], v[138:139], v[74:75], v[194:195]
	v_pk_fma_f32 v[136:137], v[136:137], v[72:73], v[192:193]
	global_store_dwordx4 v[124:125], v[120:123], off
	v_pk_fma_f32 v[118:119], v[118:119], v[70:71], v[214:215]
	v_pk_fma_f32 v[116:117], v[116:117], v[68:69], v[212:213]
	v_pk_fma_f32 v[122:123], v[130:131], v[74:75], v[210:211]
	v_pk_fma_f32 v[120:121], v[128:129], v[72:73], v[208:209]
	v_pk_fma_f32 v[114:115], v[114:115], v[66:67], v[218:219]
	v_pk_fma_f32 v[112:113], v[112:113], v[64:65], v[216:217]
	global_store_dwordx4 v[176:177], v[140:143], off
	s_cmp_lg_u64 s[28:29], 0
	s_cbranch_scc0 .Llate_align_9
	s_barrier
;     __device__ __forceinline__ void operator()(const Acc& acc, const Unit& u, int wr, int wc, int fr, int fq) const {
;     ...
;         for (int aim = 0; aim < 4; ++aim) { const int ai = aim >> 1, m0 = (aim & 1) * 2;
;             f32x4 bs[2][2][2];
; #pragma unroll
;             for (int mm = 0; mm < 2; ++mm) { const size_t off = (size_t)(row0 + ai * HALF + (m0 + mm) * 16) * D + col0;
; #pragma unroll
;                 for (int bj = 0; bj < 2; ++bj)
; #pragma unroll
;                     for (int n = 0; n < 2; ++n) bs[mm][bj][n] = *(const f32x4*)(base + off + bj * HALF + n * 16); }
; #pragma unroll
;             for (int mm = 0; mm < 2; ++mm) { const size_t off = (size_t)(row0 + ai * HALF + (m0 + mm) * 16) * D + col0;
; #pragma unroll
;                 for (int bj = 0; bj < 2; ++bj)
; #pragma unroll
;                     for (int n = 0; n < 2; ++n) *(f32x4*)(out + off + bj * HALF + n * 16) = bs[mm][bj][n] + gv[bj][n] * acc[ai][bj][m0 + mm][n]; }
;             asm volatile("" ::: "memory"); }
.Llate_align_9:
	global_store_dwordx4 v[176:177], v[136:139], off offset:64
	global_store_dwordx4 v[124:125], v[120:123], off offset:64
	global_store_dwordx4 v[124:125], v[116:119], off offset:512
	global_store_dwordx4 v[124:125], v[112:115], off offset:576
	v_lshl_add_u64 v[176:177], v[170:171], 0, s[14:15]
	v_lshl_add_u64 v[124:125], v[168:169], 0, v[176:177]
	s_mov_b64 s[14:15], 0x60000
	global_load_dwordx4 v[112:115], v[124:125], off
	global_load_dwordx4 v[116:119], v[124:125], off offset:64
	global_load_dwordx4 v[120:123], v[124:125], off offset:512
	s_nop 0
	global_load_dwordx4 v[124:127], v[124:125], off offset:576
	v_lshl_add_u64 v[178:179], v[170:171], 0, s[14:15]
	v_lshl_add_u64 v[140:141], v[168:169], 0, v[178:179]
	global_load_dwordx4 v[128:131], v[140:141], off
	global_load_dwordx4 v[132:135], v[140:141], off offset:64
	global_load_dwordx4 v[136:139], v[140:141], off offset:512
	s_nop 0
	global_load_dwordx4 v[140:143], v[140:141], off offset:576
	s_mov_b64 s[14:15], 0x100000
	s_waitcnt vmcnt(7)
	v_pk_fma_f32 v[104:105], v[104:105], v[108:109], v[112:113]
	v_lshl_add_u64 v[112:113], s[20:21], 0, v[176:177]
	v_lshl_add_u64 v[112:113], v[112:113], 0, v[166:167]
	s_waitcnt vmcnt(5)
	v_pk_fma_f32 v[90:91], v[90:91], v[70:71], v[122:123]
	v_pk_fma_f32 v[88:89], v[88:89], v[68:69], v[120:121]
	global_store_dwordx4 v[112:113], v[88:91], off offset:512
	s_waitcnt vmcnt(5)
	v_pk_fma_f32 v[86:87], v[86:87], v[66:67], v[126:127]
	v_pk_fma_f32 v[84:85], v[84:85], v[64:65], v[124:125]
	v_lshl_add_u64 v[88:89], s[20:21], 0, v[178:179]
	global_store_dwordx4 v[112:113], v[84:87], off offset:576
	v_lshl_add_u64 v[88:89], v[88:89], 0, v[166:167]
	v_pk_fma_f32 v[106:107], v[106:107], v[110:111], v[114:115]
	s_waitcnt vmcnt(5)
	v_pk_fma_f32 v[86:87], v[98:99], v[110:111], v[130:131]
	v_pk_fma_f32 v[84:85], v[96:97], v[108:109], v[128:129]
	v_pk_fma_f32 v[102:103], v[102:103], v[74:75], v[118:119]
	v_pk_fma_f32 v[100:101], v[100:101], v[72:73], v[116:117]
	global_store_dwordx4 v[88:89], v[84:87], off
	s_waitcnt vmcnt(4)
	v_pk_fma_f32 v[82:83], v[82:83], v[70:71], v[138:139]
	v_pk_fma_f32 v[80:81], v[80:81], v[68:69], v[136:137]
	v_pk_fma_f32 v[86:87], v[94:95], v[74:75], v[134:135]
	v_pk_fma_f32 v[84:85], v[92:93], v[72:73], v[132:133]
	s_waitcnt vmcnt(3)
	v_pk_fma_f32 v[78:79], v[78:79], v[66:67], v[142:143]
	v_pk_fma_f32 v[76:77], v[76:77], v[64:65], v[140:141]
	global_store_dwordx4 v[112:113], v[104:107], off
	global_store_dwordx4 v[112:113], v[100:103], off offset:64
	global_store_dwordx4 v[88:89], v[84:87], off offset:64
	global_store_dwordx4 v[88:89], v[80:83], off offset:512
	global_store_dwordx4 v[88:89], v[76:79], off offset:576
	v_lshl_add_u64 v[112:113], v[170:171], 0, s[14:15]
	v_lshl_add_u64 v[88:89], v[168:169], 0, v[112:113]
	s_mov_b64 s[14:15], 0x120000
	global_load_dwordx4 v[76:79], v[88:89], off
	global_load_dwordx4 v[80:83], v[88:89], off offset:64
	global_load_dwordx4 v[84:87], v[88:89], off offset:512
	s_nop 0
	global_load_dwordx4 v[88:91], v[88:89], off offset:576
	v_lshl_add_u64 v[114:115], v[170:171], 0, s[14:15]
	v_lshl_add_u64 v[104:105], v[168:169], 0, v[114:115]
	global_load_dwordx4 v[92:95], v[104:105], off
	global_load_dwordx4 v[96:99], v[104:105], off offset:64
	global_load_dwordx4 v[100:103], v[104:105], off offset:512
	s_nop 0
	global_load_dwordx4 v[104:107], v[104:105], off offset:576
	s_mov_b64 s[14:15], 0x140000
	s_waitcnt vmcnt(7)
	v_pk_fma_f32 v[60:61], v[60:61], v[108:109], v[76:77]
	v_lshl_add_u64 v[76:77], s[20:21], 0, v[112:113]
	v_lshl_add_u64 v[76:77], v[76:77], 0, v[166:167]
	s_waitcnt vmcnt(5)
	v_pk_fma_f32 v[46:47], v[46:47], v[70:71], v[86:87]
	v_pk_fma_f32 v[44:45], v[44:45], v[68:69], v[84:85]
	global_store_dwordx4 v[76:77], v[44:47], off offset:512
	s_waitcnt vmcnt(5)
; #define PG8_BAR __builtin_amdgcn_s_barrier()
; template <class Epi, class Map>
; __device__ __forceinline__ void gemm_phase(LAS unsigned char* lds, const Gemm g, const Sched<Map>& S, const Epi& E) {
;     ...
;         if (!has_next) break;
; #pragma unroll
;         for (int a = 0; a < 2; ++a)
; #pragma unroll
;             for (int b = 0; b < 2; ++b)
; #pragma unroll
;                 for (int m = 0; m < 4; ++m)
; #pragma unroll
;                     for (int n = 0; n < 2; ++n) acc[a][b][m][n] = (f32x4){0.f, 0.f, 0.f, 0.f};
;         cur = nxt; cA = nA; cB = nB; ++ui;
;         if (wr == 1) PG8_BAR;
;     __device__ __forceinline__ void operator()(const Acc& acc, const Unit& u, int wr, int wc, int fr, int fq) const {
;     ...
;         for (int aim = 0; aim < 4; ++aim) { const int ai = aim >> 1, m0 = (aim & 1) * 2;
;             f32x4 bs[2][2][2];
; #pragma unroll
;             for (int mm = 0; mm < 2; ++mm) { const size_t off = (size_t)(row0 + ai * HALF + (m0 + mm) * 16) * D + col0;
; #pragma unroll
;                 for (int bj = 0; bj < 2; ++bj)
; #pragma unroll
;                     for (int n = 0; n < 2; ++n) bs[mm][bj][n] = *(const f32x4*)(base + off + bj * HALF + n * 16); }
; #pragma unroll
;             for (int mm = 0; mm < 2; ++mm) { const size_t off = (size_t)(row0 + ai * HALF + (m0 + mm) * 16) * D + col0;
; #pragma unroll
;                 for (int bj = 0; bj < 2; ++bj)
; #pragma unroll
;                     for (int n = 0; n < 2; ++n) *(f32x4*)(out + off + bj * HALF + n * 16) = bs[mm][bj][n] + gv[bj][n] * acc[ai][bj][m0 + mm][n]; }
;             asm volatile("" ::: "memory"); }
	v_pk_fma_f32 v[42:43], v[42:43], v[66:67], v[90:91]
	v_pk_fma_f32 v[40:41], v[40:41], v[64:65], v[88:89]
	v_lshl_add_u64 v[44:45], s[20:21], 0, v[114:115]
	global_store_dwordx4 v[76:77], v[40:43], off offset:576
	v_lshl_add_u64 v[44:45], v[44:45], 0, v[166:167]
	v_pk_fma_f32 v[62:63], v[62:63], v[110:111], v[78:79]
	s_waitcnt vmcnt(5)
	v_pk_fma_f32 v[42:43], v[54:55], v[110:111], v[94:95]
	v_pk_fma_f32 v[40:41], v[52:53], v[108:109], v[92:93]
	v_pk_fma_f32 v[58:59], v[58:59], v[74:75], v[82:83]
	v_pk_fma_f32 v[56:57], v[56:57], v[72:73], v[80:81]
	global_store_dwordx4 v[44:45], v[40:43], off
	s_waitcnt vmcnt(4)
	v_pk_fma_f32 v[38:39], v[38:39], v[70:71], v[102:103]
	v_pk_fma_f32 v[36:37], v[36:37], v[68:69], v[100:101]
	v_pk_fma_f32 v[42:43], v[50:51], v[74:75], v[98:99]
	v_pk_fma_f32 v[40:41], v[48:49], v[72:73], v[96:97]
	s_waitcnt vmcnt(3)
	v_pk_fma_f32 v[34:35], v[34:35], v[66:67], v[106:107]
	v_pk_fma_f32 v[32:33], v[32:33], v[64:65], v[104:105]
	global_store_dwordx4 v[76:77], v[60:63], off
	global_store_dwordx4 v[76:77], v[56:59], off offset:64
	global_store_dwordx4 v[44:45], v[40:43], off offset:64
	global_store_dwordx4 v[44:45], v[36:39], off offset:512
	global_store_dwordx4 v[44:45], v[32:35], off offset:576
	v_lshl_add_u64 v[76:77], v[170:171], 0, s[14:15]
	s_mov_b64 s[14:15], 0x160000
	v_lshl_add_u64 v[44:45], v[168:169], 0, v[76:77]
	v_lshl_add_u64 v[78:79], v[170:171], 0, s[14:15]
	global_load_dwordx4 v[32:35], v[44:45], off
	global_load_dwordx4 v[36:39], v[44:45], off offset:64
	global_load_dwordx4 v[40:43], v[44:45], off offset:512
	s_nop 0
	global_load_dwordx4 v[44:47], v[44:45], off offset:576
	v_lshl_add_u64 v[60:61], v[168:169], 0, v[78:79]
	global_load_dwordx4 v[48:51], v[60:61], off
	global_load_dwordx4 v[52:55], v[60:61], off offset:64
	global_load_dwordx4 v[56:59], v[60:61], off offset:512
	s_nop 0
	global_load_dwordx4 v[60:63], v[60:61], off offset:576
	s_waitcnt vmcnt(7)
	v_pk_fma_f32 v[28:29], v[28:29], v[108:109], v[32:33]
	v_lshl_add_u64 v[32:33], s[20:21], 0, v[76:77]
	v_lshl_add_u64 v[32:33], v[32:33], 0, v[166:167]
	s_waitcnt vmcnt(5)
	v_pk_fma_f32 v[18:19], v[18:19], v[70:71], v[42:43]
	v_pk_fma_f32 v[16:17], v[16:17], v[68:69], v[40:41]
	global_store_dwordx4 v[32:33], v[16:19], off offset:512
	s_waitcnt vmcnt(5)
	v_pk_fma_f32 v[14:15], v[14:15], v[66:67], v[46:47]
	v_pk_fma_f32 v[12:13], v[12:13], v[64:65], v[44:45]
	v_lshl_add_u64 v[16:17], s[20:21], 0, v[78:79]
	v_pk_fma_f32 v[30:31], v[30:31], v[110:111], v[34:35]
	v_pk_fma_f32 v[26:27], v[26:27], v[74:75], v[38:39]
	v_pk_fma_f32 v[24:25], v[24:25], v[72:73], v[36:37]
	global_store_dwordx4 v[32:33], v[12:15], off offset:576
	v_lshl_add_u64 v[16:17], v[16:17], 0, v[166:167]
	s_waitcnt vmcnt(4)
	v_pk_fma_f32 v[10:11], v[10:11], v[74:75], v[54:55]
	v_pk_fma_f32 v[14:15], v[22:23], v[110:111], v[50:51]
	v_pk_fma_f32 v[12:13], v[20:21], v[108:109], v[48:49]
	v_pk_fma_f32 v[8:9], v[8:9], v[72:73], v[52:53]
	s_waitcnt vmcnt(3)
	v_pk_fma_f32 v[6:7], v[6:7], v[70:71], v[58:59]
	v_pk_fma_f32 v[4:5], v[4:5], v[68:69], v[56:57]
	s_waitcnt vmcnt(2)
	v_pk_fma_f32 v[2:3], v[2:3], v[66:67], v[62:63]
	v_pk_fma_f32 v[0:1], v[0:1], v[64:65], v[60:61]
	global_store_dwordx4 v[32:33], v[28:31], off
	global_store_dwordx4 v[32:33], v[24:27], off offset:64
	global_store_dwordx4 v[16:17], v[12:15], off
	global_store_dwordx4 v[16:17], v[8:11], off offset:64
	global_store_dwordx4 v[16:17], v[4:7], off offset:512
	global_store_dwordx4 v[16:17], v[0:3], off offset:576
	s_cbranch_vccnz .LBB0_944
	s_andn2_b64 vcc, exec, s[16:17]
	s_cbranch_vccnz .LBB0_943
	s_barrier
	s_branch .LBB0_943

; #define PG8_STAGE(bufoff, gbase, voff) do { _Pragma("unroll") for (int _i = 0; _i < 2; ++_i) \
;         __builtin_amdgcn_global_load_lds((const unsigned*)((const char*)(gbase) + (voff)[_i]), (LAS unsigned*)(lds + (bufoff) + ldsw + _i * 8192), 16, 0, 0); } while (0)
; #define PG8_LDA(dst, b, h) do { _Pragma("unroll") for (int m = 0; m < 4; ++m) _Pragma("unroll") for (int k = 0; k < 2; ++k) dst[m][k] = *(const LAS bf16x8*)(lds + PG8_SA(b, h) + aoff + m * 2048 + k * 1024); } while (0)
; #define PG8_LDB(dst, b, h) do { _Pragma("unroll") for (int n = 0; n < 2; ++n) _Pragma("unroll") for (int k = 0; k < 2; ++k) dst[n][k] = *(const LAS bf16x8*)(lds + PG8_SB(b, h) + boff + n * 2048 + k * 1024); } while (0)
; #define PG8_MMA(ai, bj, At, Bt) do { __builtin_amdgcn_s_setprio(1); _Pragma("unroll") for (int m = 0; m < 4; ++m) _Pragma("unroll") for (int n = 0; n < 2; ++n) _Pragma("unroll") for (int k = 0; k < 2; ++k) \
;         acc[ai][bj][m][n] = __builtin_amdgcn_mfma_f32_16x16x32_bf16(Bt[n][k], At[m][k], acc[ai][bj][m][n], 0, 0, 0); __builtin_amdgcn_s_setprio(0); } while (0)
; #define PG8_WAIT_V(n) asm volatile("s_waitcnt vmcnt(" #n ")" ::: "memory")
; #define PG8_WAIT_L(n) asm volatile("s_waitcnt lgkmcnt(" #n ")" ::: "memory")
; #define PG8_BAR __builtin_amdgcn_s_barrier()
; template <class Epi, class Map>
; __device__ __forceinline__ void gemm_phase(LAS unsigned char* lds, const Gemm g, const Sched<Map>& S, const Epi& E) {
;     ...
;         for (int t = 0; t < nt; t += 2) {
;             const bool last = (t == nt - 2);
;             const char* a1 = cA + (size_t)(t + 1) * kstep;
;             const char* a2 = last ? nA : cA + (size_t)(t + 2) * kstep; const char* b2 = last ? nB : cB + (size_t)(t + 2) * kstep;
;             const char* a3 = a2 + kstep; const char* b3 = b2 + kstep;
;             PG8_LDB(B0, 0, 0); PG8_LDB(B1, 0, 1); PG8_SCHED; PG8_LDA(At, 0, 0); PG8_STAGE(PG8_SA(1, 1), a1 + hstepA, voffA);
;             PG8_WAIT_V(8); PG8_WAIT_L(0); PG8_BAR; PG8_MMA(0, 0, At, B0); PG8_MMA(0, 1, At, B1); PG8_BAR; PG8_SCHED;
;     ...
;         for (int a = 0; a < 2; ++a)
; #pragma unroll
;             for (int b = 0; b < 2; ++b)
; #pragma unroll
;                 for (int m = 0; m < 4; ++m)
; #pragma unroll
;                     for (int n = 0; n < 2; ++n) acc[a][b][m][n] = (f32x4){0.f, 0.f, 0.f, 0.f};
;         cur = nxt; cA = nA; cB = nB; ++ui;
.LBB0_1087:
	v_readlane_b32 s12, v245, 21
	v_readlane_b32 s13, v245, 22
	s_add_u32 s24, s12, s10
	s_addc_u32 s25, s13, 0
	s_and_b64 s[12:13], s[38:39], exec
	v_readlane_b32 s14, v244, 20
	s_cselect_b32 s12, s25, s31
	s_cselect_b32 s13, s24, s30
	s_add_u32 s28, s14, s9
	v_readlane_b32 s14, v244, 21
	s_addc_u32 s29, s14, 0
	s_and_b64 s[14:15], s[38:39], exec
	s_cselect_b32 s14, s29, s35
	s_cselect_b32 s15, s28, s34
	s_add_u32 s30, s30, 0x80080
	s_addc_u32 s31, s31, 0
	s_add_u32 s21, s34, 0x100
	v_mov_b32_e32 v0, 0
	s_addc_u32 s33, s35, 0
	s_mov_b32 s40, -2
	v_mov_b32_e32 v1, v0
	v_mov_b32_e32 v2, v0
	v_mov_b32_e32 v3, v0
	v_mov_b32_e32 v4, v0
	v_mov_b32_e32 v5, v0
	v_mov_b32_e32 v6, v0
	v_mov_b32_e32 v7, v0
	v_mov_b32_e32 v16, v0
	v_mov_b32_e32 v17, v0
	v_mov_b32_e32 v18, v0
	v_mov_b32_e32 v19, v0
	v_mov_b32_e32 v20, v0
	v_mov_b32_e32 v21, v0
	v_mov_b32_e32 v22, v0
	v_mov_b32_e32 v23, v0
	v_mov_b32_e32 v32, v0
	v_mov_b32_e32 v33, v0
	v_mov_b32_e32 v34, v0
	v_mov_b32_e32 v35, v0
	v_mov_b32_e32 v36, v0
	v_mov_b32_e32 v37, v0
	v_mov_b32_e32 v38, v0
	v_mov_b32_e32 v39, v0
	v_mov_b32_e32 v48, v0
	v_mov_b32_e32 v49, v0
	v_mov_b32_e32 v50, v0
	v_mov_b32_e32 v51, v0
	v_mov_b32_e32 v52, v0
	v_mov_b32_e32 v53, v0
	v_mov_b32_e32 v54, v0
	v_mov_b32_e32 v55, v0
	v_mov_b32_e32 v8, v0
	v_mov_b32_e32 v9, v0
	v_mov_b32_e32 v10, v0
	v_mov_b32_e32 v11, v0
	v_mov_b32_e32 v12, v0
	v_mov_b32_e32 v13, v0
	v_mov_b32_e32 v14, v0
	v_mov_b32_e32 v15, v0
	v_mov_b32_e32 v24, v0
	v_mov_b32_e32 v25, v0
	v_mov_b32_e32 v26, v0
	v_mov_b32_e32 v27, v0
	v_mov_b32_e32 v28, v0
	v_mov_b32_e32 v29, v0
	v_mov_b32_e32 v30, v0
	v_mov_b32_e32 v31, v0
	v_mov_b32_e32 v40, v0
	v_mov_b32_e32 v41, v0
	v_mov_b32_e32 v42, v0
	v_mov_b32_e32 v43, v0
	v_mov_b32_e32 v44, v0
	v_mov_b32_e32 v45, v0
	v_mov_b32_e32 v46, v0
	v_mov_b32_e32 v47, v0
	v_mov_b32_e32 v56, v0
	v_mov_b32_e32 v57, v0
	v_mov_b32_e32 v58, v0
	v_mov_b32_e32 v59, v0
	v_mov_b32_e32 v60, v0
	v_mov_b32_e32 v61, v0
	v_mov_b32_e32 v62, v0
	v_mov_b32_e32 v63, v0
	v_mov_b32_e32 v64, v0
	v_mov_b32_e32 v65, v0
	v_mov_b32_e32 v66, v0
	v_mov_b32_e32 v67, v0
	v_mov_b32_e32 v68, v0
	v_mov_b32_e32 v69, v0
	v_mov_b32_e32 v70, v0
	v_mov_b32_e32 v71, v0
	v_mov_b32_e32 v80, v0
	v_mov_b32_e32 v81, v0
	v_mov_b32_e32 v82, v0
	v_mov_b32_e32 v83, v0
	v_mov_b32_e32 v84, v0
	v_mov_b32_e32 v85, v0
	v_mov_b32_e32 v86, v0
	v_mov_b32_e32 v87, v0
	v_mov_b32_e32 v96, v0
	v_mov_b32_e32 v97, v0
	v_mov_b32_e32 v98, v0
	v_mov_b32_e32 v99, v0
	v_mov_b32_e32 v100, v0
	v_mov_b32_e32 v101, v0
	v_mov_b32_e32 v102, v0
	v_mov_b32_e32 v103, v0
	v_mov_b32_e32 v112, v0
	v_mov_b32_e32 v113, v0
	v_mov_b32_e32 v114, v0
	v_mov_b32_e32 v115, v0
	v_mov_b32_e32 v116, v0
	v_mov_b32_e32 v117, v0
	v_mov_b32_e32 v118, v0
	v_mov_b32_e32 v119, v0
	v_mov_b32_e32 v72, v0
	v_mov_b32_e32 v73, v0
	v_mov_b32_e32 v74, v0
	v_mov_b32_e32 v75, v0
	v_mov_b32_e32 v76, v0
	v_mov_b32_e32 v77, v0
	v_mov_b32_e32 v78, v0
	v_mov_b32_e32 v79, v0
	v_mov_b32_e32 v88, v0
	v_mov_b32_e32 v89, v0
	v_mov_b32_e32 v90, v0
	v_mov_b32_e32 v91, v0
	v_mov_b32_e32 v92, v0
	v_mov_b32_e32 v93, v0
	v_mov_b32_e32 v94, v0
	v_mov_b32_e32 v95, v0
	v_mov_b32_e32 v104, v0
	v_mov_b32_e32 v105, v0
	v_mov_b32_e32 v106, v0
	v_mov_b32_e32 v107, v0
	v_mov_b32_e32 v108, v0
	v_mov_b32_e32 v109, v0
	v_mov_b32_e32 v110, v0
	v_mov_b32_e32 v111, v0
	v_mov_b32_e32 v120, v0
	v_mov_b32_e32 v121, v0
	v_mov_b32_e32 v122, v0
	v_mov_b32_e32 v123, v0
	v_mov_b32_e32 v124, v0
	v_mov_b32_e32 v125, v0
	v_mov_b32_e32 v126, v0
	v_mov_b32_e32 v127, v0
.LBB0_1088:
	s_add_u32 s34, s30, 0xfff80080
	s_addc_u32 s35, s31, -1
	s_add_i32 s41, 0, 0x10000
	s_cmp_eq_u32 s40, 28
	s_cselect_b32 s37, s12, s35
	s_cselect_b32 s36, s13, s34
	v_add_u32_e32 v138, s41, v142
	s_cselect_b32 s35, s14, s33
	s_cselect_b32 s34, s15, s21
	s_add_i32 s46, 0, 0x14000
	ds_read_b128 v[160:163], v138
	ds_read_b128 v[164:167], v138 offset:1024
	ds_read_b128 v[168:171], v138 offset:2048
	ds_read_b128 v[172:175], v138 offset:3072
	v_add_u32_e32 v138, s46, v142
	ds_read_b128 v[176:179], v138
	ds_read_b128 v[192:195], v138 offset:1024
	ds_read_b128 v[196:199], v138 offset:2048
	ds_read_b128 v[200:203], v138 offset:3072
	v_lshl_add_u64 v[138:139], s[30:31], 0, v[134:135]
	s_add_i32 m0, s1, 0xc000
	ds_read_b128 v[204:207], v143
	ds_read_b128 v[208:211], v143 offset:1024
	ds_read_b128 v[212:215], v143 offset:2048
	ds_read_b128 v[216:219], v143 offset:3072
	ds_read_b128 v[220:223], v143 offset:4096
	ds_read_b128 v[224:227], v143 offset:5120
	ds_read_b128 v[228:231], v143 offset:6144
	ds_read_b128 v[232:235], v143 offset:7168
	global_load_lds_dwordx4 v[138:139], off
	v_lshl_add_u64 v[138:139], s[30:31], 0, v[136:137]
	s_add_i32 m0, s1, 0xe000
	s_nop 0
	global_load_lds_dwordx4 v[138:139], off
	s_waitcnt vmcnt(8)
	s_waitcnt lgkmcnt(0)
	s_barrier
; #define PG8_STAGE(bufoff, gbase, voff) do { _Pragma("unroll") for (int _i = 0; _i < 2; ++_i) \
;         __builtin_amdgcn_global_load_lds((const unsigned*)((const char*)(gbase) + (voff)[_i]), (LAS unsigned*)(lds + (bufoff) + ldsw + _i * 8192), 16, 0, 0); } while (0)
; #define PG8_LDA(dst, b, h) do { _Pragma("unroll") for (int m = 0; m < 4; ++m) _Pragma("unroll") for (int k = 0; k < 2; ++k) dst[m][k] = *(const LAS bf16x8*)(lds + PG8_SA(b, h) + aoff + m * 2048 + k * 1024); } while (0)
; #define PG8_MMA(ai, bj, At, Bt) do { __builtin_amdgcn_s_setprio(1); _Pragma("unroll") for (int m = 0; m < 4; ++m) _Pragma("unroll") for (int n = 0; n < 2; ++n) _Pragma("unroll") for (int k = 0; k < 2; ++k) \
;         acc[ai][bj][m][n] = __builtin_amdgcn_mfma_f32_16x16x32_bf16(Bt[n][k], At[m][k], acc[ai][bj][m][n], 0, 0, 0); __builtin_amdgcn_s_setprio(0); } while (0)
; #define PG8_WAIT_V(n) asm volatile("s_waitcnt vmcnt(" #n ")" ::: "memory")
; #define PG8_WAIT_L(n) asm volatile("s_waitcnt lgkmcnt(" #n ")" ::: "memory")
; #define PG8_BAR __builtin_amdgcn_s_barrier()
; #define PG8_SCHED __builtin_amdgcn_sched_barrier(0)
; template <class Epi, class Map>
; __device__ __forceinline__ void gemm_phase(LAS unsigned char* lds, const Gemm g, const Sched<Map>& S, const Epi& E) {
;     ...
;             PG8_WAIT_V(8); PG8_WAIT_L(0); PG8_BAR; PG8_MMA(0, 0, At, B0); PG8_MMA(0, 1, At, B1); PG8_BAR; PG8_SCHED;
;             PG8_LDA(At, 0, 1); PG8_STAGE(PG8_SB(0, 0), b2, voffB); PG8_STAGE(PG8_SB(0, 1), b2 + hstepB, voffB); PG8_STAGE(PG8_SA(0, 0), a2, voffA);
;             PG8_WAIT_V(8); PG8_WAIT_L(0); PG8_BAR; PG8_MMA(1, 0, At, B0); PG8_MMA(1, 1, At, B1); PG8_BAR; PG8_SCHED;
	s_waitcnt lgkmcnt(0)
	v_mfma_f32_16x16x32_bf16 v[124:127], v[160:163], v[204:207], v[124:127]
	v_mfma_f32_16x16x32_bf16 v[120:123], v[168:171], v[204:207], v[120:123]
	v_mfma_f32_16x16x32_bf16 v[108:111], v[160:163], v[212:215], v[108:111]
	v_mfma_f32_16x16x32_bf16 v[104:107], v[168:171], v[212:215], v[104:107]
	v_mfma_f32_16x16x32_bf16 v[92:95], v[160:163], v[220:223], v[92:95]
	v_mfma_f32_16x16x32_bf16 v[88:91], v[168:171], v[220:223], v[88:91]
	v_mfma_f32_16x16x32_bf16 v[76:79], v[160:163], v[228:231], v[76:79]
	v_mfma_f32_16x16x32_bf16 v[72:75], v[168:171], v[228:231], v[72:75]
	v_mfma_f32_16x16x32_bf16 v[124:127], v[164:167], v[208:211], v[124:127]
	v_mfma_f32_16x16x32_bf16 v[120:123], v[172:175], v[208:211], v[120:123]
	v_mfma_f32_16x16x32_bf16 v[108:111], v[164:167], v[216:219], v[108:111]
	v_mfma_f32_16x16x32_bf16 v[104:107], v[172:175], v[216:219], v[104:107]
	v_mfma_f32_16x16x32_bf16 v[92:95], v[164:167], v[224:227], v[92:95]
	v_mfma_f32_16x16x32_bf16 v[88:91], v[172:175], v[224:227], v[88:91]
	v_mfma_f32_16x16x32_bf16 v[76:79], v[164:167], v[232:235], v[76:79]
	v_mfma_f32_16x16x32_bf16 v[72:75], v[172:175], v[232:235], v[72:75]
	v_mfma_f32_16x16x32_bf16 v[116:119], v[176:179], v[204:207], v[116:119]
	v_mfma_f32_16x16x32_bf16 v[112:115], v[196:199], v[204:207], v[112:115]
	v_mfma_f32_16x16x32_bf16 v[100:103], v[176:179], v[212:215], v[100:103]
	v_mfma_f32_16x16x32_bf16 v[96:99], v[196:199], v[212:215], v[96:99]
	v_mfma_f32_16x16x32_bf16 v[84:87], v[176:179], v[220:223], v[84:87]
	v_mfma_f32_16x16x32_bf16 v[80:83], v[196:199], v[220:223], v[80:83]
	v_mfma_f32_16x16x32_bf16 v[68:71], v[176:179], v[228:231], v[68:71]
	v_mfma_f32_16x16x32_bf16 v[64:67], v[196:199], v[228:231], v[64:67]
	v_mfma_f32_16x16x32_bf16 v[116:119], v[192:195], v[208:211], v[116:119]
	v_mfma_f32_16x16x32_bf16 v[112:115], v[200:203], v[208:211], v[112:115]
	v_mfma_f32_16x16x32_bf16 v[100:103], v[192:195], v[216:219], v[100:103]
	v_mfma_f32_16x16x32_bf16 v[96:99], v[200:203], v[216:219], v[96:99]
	v_mfma_f32_16x16x32_bf16 v[84:87], v[192:195], v[224:227], v[84:87]
	v_mfma_f32_16x16x32_bf16 v[80:83], v[200:203], v[224:227], v[80:83]
	v_mfma_f32_16x16x32_bf16 v[68:71], v[192:195], v[232:235], v[68:71]
	v_mfma_f32_16x16x32_bf16 v[64:67], v[200:203], v[232:235], v[64:67]
	s_barrier
	s_add_i32 s41, s41, s0
	v_lshl_add_u64 v[138:139], s[34:35], 0, v[144:145]
	s_mov_b32 m0, s41
	ds_read_b128 v[204:207], v143 offset:16384
	ds_read_b128 v[208:211], v143 offset:17408
	ds_read_b128 v[212:215], v143 offset:18432
	ds_read_b128 v[216:219], v143 offset:19456
	ds_read_b128 v[220:223], v143 offset:20480
	ds_read_b128 v[224:227], v143 offset:21504
	ds_read_b128 v[228:231], v143 offset:22528
	ds_read_b128 v[232:235], v143 offset:23552
	global_load_lds_dwordx4 v[138:139], off
	s_add_i32 m0, s41, 0x2000
	s_add_u32 s44, s34, 0x80000
	v_lshl_add_u64 v[180:181], s[34:35], 0, v[128:129]
	s_addc_u32 s45, s35, 0
	s_add_i32 s41, s46, s0
	global_load_lds_dwordx4 v[180:181], off
	v_lshl_add_u64 v[236:237], s[44:45], 0, v[144:145]
	s_mov_b32 m0, s41
	v_lshl_add_u64 v[238:239], s[36:37], 0, v[130:131]
	global_load_lds_dwordx4 v[236:237], off
	v_lshl_add_u64 v[236:237], s[44:45], 0, v[128:129]
	s_add_i32 m0, s41, 0x2000
	s_nop 0
	global_load_lds_dwordx4 v[236:237], off
	v_lshl_add_u64 v[236:237], s[36:37], 0, v[132:133]
	s_mov_b32 m0, s1
	s_nop 0
	global_load_lds_dwordx4 v[236:237], off
	s_mov_b32 m0, s2
	s_nop 0
	global_load_lds_dwordx4 v[238:239], off
	s_waitcnt vmcnt(8)
	s_waitcnt lgkmcnt(0)
	s_barrier
	s_waitcnt lgkmcnt(0)
	v_mfma_f32_16x16x32_bf16 v[60:63], v[160:163], v[204:207], v[60:63]
	v_mfma_f32_16x16x32_bf16 v[56:59], v[168:171], v[204:207], v[56:59]
	v_mfma_f32_16x16x32_bf16 v[44:47], v[160:163], v[212:215], v[44:47]
	v_mfma_f32_16x16x32_bf16 v[40:43], v[168:171], v[212:215], v[40:43]
	v_mfma_f32_16x16x32_bf16 v[28:31], v[160:163], v[220:223], v[28:31]
	v_mfma_f32_16x16x32_bf16 v[24:27], v[168:171], v[220:223], v[24:27]
	v_mfma_f32_16x16x32_bf16 v[12:15], v[160:163], v[228:231], v[12:15]
	v_mfma_f32_16x16x32_bf16 v[8:11], v[168:171], v[228:231], v[8:11]
	v_mfma_f32_16x16x32_bf16 v[60:63], v[164:167], v[208:211], v[60:63]
	v_mfma_f32_16x16x32_bf16 v[56:59], v[172:175], v[208:211], v[56:59]
	v_mfma_f32_16x16x32_bf16 v[44:47], v[164:167], v[216:219], v[44:47]
	v_mfma_f32_16x16x32_bf16 v[40:43], v[172:175], v[216:219], v[40:43]
	v_mfma_f32_16x16x32_bf16 v[28:31], v[164:167], v[224:227], v[28:31]
	v_mfma_f32_16x16x32_bf16 v[24:27], v[172:175], v[224:227], v[24:27]
	v_mfma_f32_16x16x32_bf16 v[12:15], v[164:167], v[232:235], v[12:15]
	v_mfma_f32_16x16x32_bf16 v[8:11], v[172:175], v[232:235], v[8:11]
	v_mfma_f32_16x16x32_bf16 v[52:55], v[176:179], v[204:207], v[52:55]
	v_mfma_f32_16x16x32_bf16 v[48:51], v[196:199], v[204:207], v[48:51]
	v_mfma_f32_16x16x32_bf16 v[36:39], v[176:179], v[212:215], v[36:39]
	v_mfma_f32_16x16x32_bf16 v[32:35], v[196:199], v[212:215], v[32:35]
	v_mfma_f32_16x16x32_bf16 v[20:23], v[176:179], v[220:223], v[20:23]
	v_mfma_f32_16x16x32_bf16 v[16:19], v[196:199], v[220:223], v[16:19]
	v_mfma_f32_16x16x32_bf16 v[4:7], v[176:179], v[228:231], v[4:7]
	v_mfma_f32_16x16x32_bf16 v[0:3], v[196:199], v[228:231], v[0:3]
	v_mfma_f32_16x16x32_bf16 v[52:55], v[192:195], v[208:211], v[52:55]
	v_mfma_f32_16x16x32_bf16 v[48:51], v[200:203], v[208:211], v[48:51]
	v_mfma_f32_16x16x32_bf16 v[36:39], v[192:195], v[216:219], v[36:39]
	v_mfma_f32_16x16x32_bf16 v[32:35], v[200:203], v[216:219], v[32:35]
	v_mfma_f32_16x16x32_bf16 v[20:23], v[192:195], v[224:227], v[20:23]
	v_mfma_f32_16x16x32_bf16 v[16:19], v[200:203], v[224:227], v[16:19]
	v_mfma_f32_16x16x32_bf16 v[4:7], v[192:195], v[232:235], v[4:7]
	v_mfma_f32_16x16x32_bf16 v[0:3], v[200:203], v[232:235], v[0:3]
	s_barrier
; #define PG8_STAGE(bufoff, gbase, voff) do { _Pragma("unroll") for (int _i = 0; _i < 2; ++_i) \
;         __builtin_amdgcn_global_load_lds((const unsigned*)((const char*)(gbase) + (voff)[_i]), (LAS unsigned*)(lds + (bufoff) + ldsw + _i * 8192), 16, 0, 0); } while (0)
; #define PG8_LDA(dst, b, h) do { _Pragma("unroll") for (int m = 0; m < 4; ++m) _Pragma("unroll") for (int k = 0; k < 2; ++k) dst[m][k] = *(const LAS bf16x8*)(lds + PG8_SA(b, h) + aoff + m * 2048 + k * 1024); } while (0)
; #define PG8_LDB(dst, b, h) do { _Pragma("unroll") for (int n = 0; n < 2; ++n) _Pragma("unroll") for (int k = 0; k < 2; ++k) dst[n][k] = *(const LAS bf16x8*)(lds + PG8_SB(b, h) + boff + n * 2048 + k * 1024); } while (0)
; #define PG8_MMA(ai, bj, At, Bt) do { __builtin_amdgcn_s_setprio(1); _Pragma("unroll") for (int m = 0; m < 4; ++m) _Pragma("unroll") for (int n = 0; n < 2; ++n) _Pragma("unroll") for (int k = 0; k < 2; ++k) \
;         acc[ai][bj][m][n] = __builtin_amdgcn_mfma_f32_16x16x32_bf16(Bt[n][k], At[m][k], acc[ai][bj][m][n], 0, 0, 0); __builtin_amdgcn_s_setprio(0); } while (0)
; #define PG8_WAIT_V(n) asm volatile("s_waitcnt vmcnt(" #n ")" ::: "memory")
; #define PG8_WAIT_L(n) asm volatile("s_waitcnt lgkmcnt(" #n ")" ::: "memory")
; #define PG8_BAR __builtin_amdgcn_s_barrier()
; #define PG8_SCHED __builtin_amdgcn_sched_barrier(0)
; template <class Epi, class Map>
; __device__ __forceinline__ void gemm_phase(LAS unsigned char* lds, const Gemm g, const Sched<Map>& S, const Epi& E) {
;     ...
;             PG8_LDB(B0, 1, 0); PG8_LDB(B1, 1, 1); PG8_SCHED; PG8_LDA(At, 1, 0); PG8_STAGE(PG8_SA(0, 1), a2 + hstepA, voffA);
;             PG8_WAIT_V(8); PG8_WAIT_L(0); PG8_BAR; PG8_MMA(0, 0, At, B0); PG8_MMA(0, 1, At, B1); PG8_BAR; PG8_SCHED;
;             PG8_LDA(At, 1, 1); PG8_STAGE(PG8_SB(1, 0), b3, voffB); PG8_STAGE(PG8_SB(1, 1), b3 + hstepB, voffB); PG8_STAGE(PG8_SA(1, 0), a3, voffA);
;             PG8_WAIT_V(8); PG8_WAIT_L(0); PG8_BAR; PG8_MMA(1, 0, At, B0); PG8_MMA(1, 1, At, B1); PG8_BAR; PG8_SCHED;
	s_add_i32 s41, 0, 0x18000
	v_add_u32_e32 v159, s41, v142
	s_add_i32 s44, 0, 0x1c000
	ds_read_b128 v[160:163], v159
	ds_read_b128 v[164:167], v159 offset:1024
	ds_read_b128 v[168:171], v159 offset:2048
	ds_read_b128 v[172:175], v159 offset:3072
	v_add_u32_e32 v159, s44, v142
	ds_read_b128 v[176:179], v159
	ds_read_b128 v[192:195], v159 offset:1024
	ds_read_b128 v[196:199], v159 offset:2048
	ds_read_b128 v[200:203], v159 offset:3072
	s_add_u32 s36, s36, 0x80000
	s_addc_u32 s37, s37, 0
	s_mov_b32 m0, s3
	v_lshl_add_u64 v[240:241], s[36:37], 0, v[132:133]
	ds_read_b128 v[204:207], v143 offset:32768
	ds_read_b128 v[208:211], v143 offset:33792
	ds_read_b128 v[212:215], v143 offset:34816
	ds_read_b128 v[216:219], v143 offset:35840
	ds_read_b128 v[220:223], v143 offset:36864
	ds_read_b128 v[224:227], v143 offset:37888
	ds_read_b128 v[228:231], v143 offset:38912
	ds_read_b128 v[232:235], v143 offset:39936
	global_load_lds_dwordx4 v[240:241], off
	v_lshl_add_u64 v[240:241], s[36:37], 0, v[130:131]
	s_mov_b32 m0, s4
	s_nop 0
	global_load_lds_dwordx4 v[240:241], off
	s_waitcnt vmcnt(8)
	s_waitcnt lgkmcnt(0)
	s_barrier
	s_waitcnt lgkmcnt(0)
	v_mfma_f32_16x16x32_bf16 v[124:127], v[160:163], v[204:207], v[124:127]
	v_mfma_f32_16x16x32_bf16 v[120:123], v[168:171], v[204:207], v[120:123]
	v_mfma_f32_16x16x32_bf16 v[108:111], v[160:163], v[212:215], v[108:111]
	v_mfma_f32_16x16x32_bf16 v[104:107], v[168:171], v[212:215], v[104:107]
	v_mfma_f32_16x16x32_bf16 v[92:95], v[160:163], v[220:223], v[92:95]
	v_mfma_f32_16x16x32_bf16 v[88:91], v[168:171], v[220:223], v[88:91]
	v_mfma_f32_16x16x32_bf16 v[76:79], v[160:163], v[228:231], v[76:79]
	v_mfma_f32_16x16x32_bf16 v[72:75], v[168:171], v[228:231], v[72:75]
	v_mfma_f32_16x16x32_bf16 v[124:127], v[164:167], v[208:211], v[124:127]
	v_mfma_f32_16x16x32_bf16 v[120:123], v[172:175], v[208:211], v[120:123]
	v_mfma_f32_16x16x32_bf16 v[108:111], v[164:167], v[216:219], v[108:111]
	v_mfma_f32_16x16x32_bf16 v[104:107], v[172:175], v[216:219], v[104:107]
	v_mfma_f32_16x16x32_bf16 v[92:95], v[164:167], v[224:227], v[92:95]
	v_mfma_f32_16x16x32_bf16 v[88:91], v[172:175], v[224:227], v[88:91]
	v_mfma_f32_16x16x32_bf16 v[76:79], v[164:167], v[232:235], v[76:79]
	v_mfma_f32_16x16x32_bf16 v[72:75], v[172:175], v[232:235], v[72:75]
	v_mfma_f32_16x16x32_bf16 v[116:119], v[176:179], v[204:207], v[116:119]
	v_mfma_f32_16x16x32_bf16 v[112:115], v[196:199], v[204:207], v[112:115]
	v_mfma_f32_16x16x32_bf16 v[100:103], v[176:179], v[212:215], v[100:103]
	v_mfma_f32_16x16x32_bf16 v[96:99], v[196:199], v[212:215], v[96:99]
	v_mfma_f32_16x16x32_bf16 v[84:87], v[176:179], v[220:223], v[84:87]
	v_mfma_f32_16x16x32_bf16 v[80:83], v[196:199], v[220:223], v[80:83]
	v_mfma_f32_16x16x32_bf16 v[68:71], v[176:179], v[228:231], v[68:71]
	v_mfma_f32_16x16x32_bf16 v[64:67], v[196:199], v[228:231], v[64:67]
	v_mfma_f32_16x16x32_bf16 v[116:119], v[192:195], v[208:211], v[116:119]
	v_mfma_f32_16x16x32_bf16 v[112:115], v[200:203], v[208:211], v[112:115]
	v_mfma_f32_16x16x32_bf16 v[100:103], v[192:195], v[216:219], v[100:103]
	v_mfma_f32_16x16x32_bf16 v[96:99], v[200:203], v[216:219], v[96:99]
	v_mfma_f32_16x16x32_bf16 v[84:87], v[192:195], v[224:227], v[84:87]
	v_mfma_f32_16x16x32_bf16 v[80:83], v[200:203], v[224:227], v[80:83]
	v_mfma_f32_16x16x32_bf16 v[68:71], v[192:195], v[232:235], v[68:71]
	v_mfma_f32_16x16x32_bf16 v[64:67], v[200:203], v[232:235], v[64:67]
	s_barrier
	s_add_i32 s36, s41, s0
	v_lshl_add_u64 v[138:139], v[138:139], 0, s[82:83]
	s_mov_b32 m0, s36
	ds_read_b128 v[204:207], v143 offset:49152
	ds_read_b128 v[208:211], v143 offset:50176
	ds_read_b128 v[212:215], v143 offset:51200
	ds_read_b128 v[216:219], v143 offset:52224
	ds_read_b128 v[220:223], v143 offset:53248
	ds_read_b128 v[224:227], v143 offset:54272
	ds_read_b128 v[228:231], v143 offset:55296
	ds_read_b128 v[232:235], v143 offset:56320
	global_load_lds_dwordx4 v[138:139], off
	s_add_i32 m0, s36, 0x2000
	s_add_u32 s34, s34, 0x80080
	v_lshl_add_u64 v[138:139], v[180:181], 0, s[82:83]
	s_addc_u32 s35, s35, 0
	s_add_i32 s36, s44, s0
	global_load_lds_dwordx4 v[138:139], off
	v_lshl_add_u64 v[138:139], s[34:35], 0, v[144:145]
	s_mov_b32 m0, s36
	s_nop 0
	global_load_lds_dwordx4 v[138:139], off
	v_lshl_add_u64 v[138:139], s[34:35], 0, v[128:129]
	s_add_i32 m0, s36, 0x2000
	s_nop 0
	global_load_lds_dwordx4 v[138:139], off
	v_lshl_add_u64 v[138:139], v[236:237], 0, s[82:83]
	s_mov_b32 m0, s6
	s_nop 0
	global_load_lds_dwordx4 v[138:139], off
	v_lshl_add_u64 v[138:139], v[238:239], 0, s[82:83]
	s_mov_b32 m0, s7
	s_nop 0
	global_load_lds_dwordx4 v[138:139], off
	s_waitcnt vmcnt(8)
	s_waitcnt lgkmcnt(0)
	s_barrier
; __device__ __forceinline__ unsigned cvt_pk_bf16(float lo, float hi) { unsigned r; asm volatile("v_cvt_pk_bf16_f32 %0, %1, %2" : "=v"(r) : "v"(lo), "v"(hi)); return r; }
; __device__ __forceinline__ float silu_f(float v) { return v / (1.0f + __expf(-v)); }
; #define PG8_MMA(ai, bj, At, Bt) do { __builtin_amdgcn_s_setprio(1); _Pragma("unroll") for (int m = 0; m < 4; ++m) _Pragma("unroll") for (int n = 0; n < 2; ++n) _Pragma("unroll") for (int k = 0; k < 2; ++k) \
;         acc[ai][bj][m][n] = __builtin_amdgcn_mfma_f32_16x16x32_bf16(Bt[n][k], At[m][k], acc[ai][bj][m][n], 0, 0, 0); __builtin_amdgcn_s_setprio(0); } while (0)
; #define PG8_WAIT_V(n) asm volatile("s_waitcnt vmcnt(" #n ")" ::: "memory")
; #define PG8_WAIT_L(n) asm volatile("s_waitcnt lgkmcnt(" #n ")" ::: "memory")
; #define PG8_BAR __builtin_amdgcn_s_barrier()
; #define PG8_SCHED __builtin_amdgcn_sched_barrier(0)
; template <class Epi, class Map>
; __device__ __forceinline__ void gemm_phase(LAS unsigned char* lds, const Gemm g, const Sched<Map>& S, const Epi& E) {
;     ...
;             PG8_WAIT_V(8); PG8_WAIT_L(0); PG8_BAR; PG8_MMA(1, 0, At, B0); PG8_MMA(1, 1, At, B1); PG8_BAR; PG8_SCHED;
;         }
;         if (wr == 0) PG8_BAR;
;     __device__ __forceinline__ void operator()(const Acc& acc, const Unit& u, int wr, int wc, int fr, int fq) const {
;         asm volatile("" : "+v"(fr), "+v"(fq));
;         bf16_t* base = O + u.coff + (size_t)(wr * 64 + fr) * ldc + wc * 32 + 8 * fq;
; #pragma unroll
;         for (int ai = 0; ai < 2; ++ai)
; #pragma unroll
;             for (int m = 0; m < 4; ++m) { bf16_t* rowp = base + (size_t)(ai * HALF + m * 16) * ldc;
; #pragma unroll
;                 for (int bj = 0; bj < 2; ++bj) { f32x4 v0 = acc[ai][bj][m][0], v1 = acc[ai][bj][m][1];
;                     if (ACT == 1) {
; #pragma unroll
;                         for (int j = 0; j < 4; ++j) { v0[j] = silu_f(v0[j]); v1[j] = silu_f(v1[j]); } }
;                     if (ACT == 2) {
; #pragma unroll
;                         for (int j = 0; j < 4; ++j) { const float a = fmaxf(v0[j], 0.f), b = fmaxf(v1[j], 0.f); v0[j] = a * a; v1[j] = b * b; } }
;                     u32x4 w; w.x = cvt_pk_bf16(v0[0], v0[1]); w.y = cvt_pk_bf16(v0[2], v0[3]); w.z = cvt_pk_bf16(v1[0], v1[1]); w.w = cvt_pk_bf16(v1[2], v1[3]);
;                     *(u32x4*)(rowp + bj * HALF) = w; } }
	s_waitcnt lgkmcnt(0)
	v_mfma_f32_16x16x32_bf16 v[60:63], v[160:163], v[204:207], v[60:63]
	v_mfma_f32_16x16x32_bf16 v[56:59], v[168:171], v[204:207], v[56:59]
	v_mfma_f32_16x16x32_bf16 v[44:47], v[160:163], v[212:215], v[44:47]
	v_mfma_f32_16x16x32_bf16 v[40:43], v[168:171], v[212:215], v[40:43]
	v_mfma_f32_16x16x32_bf16 v[28:31], v[160:163], v[220:223], v[28:31]
	v_mfma_f32_16x16x32_bf16 v[24:27], v[168:171], v[220:223], v[24:27]
	v_mfma_f32_16x16x32_bf16 v[12:15], v[160:163], v[228:231], v[12:15]
	v_mfma_f32_16x16x32_bf16 v[8:11], v[168:171], v[228:231], v[8:11]
	v_mfma_f32_16x16x32_bf16 v[60:63], v[164:167], v[208:211], v[60:63]
	v_mfma_f32_16x16x32_bf16 v[56:59], v[172:175], v[208:211], v[56:59]
	v_mfma_f32_16x16x32_bf16 v[44:47], v[164:167], v[216:219], v[44:47]
	v_mfma_f32_16x16x32_bf16 v[40:43], v[172:175], v[216:219], v[40:43]
	v_mfma_f32_16x16x32_bf16 v[28:31], v[164:167], v[224:227], v[28:31]
	v_mfma_f32_16x16x32_bf16 v[24:27], v[172:175], v[224:227], v[24:27]
	v_mfma_f32_16x16x32_bf16 v[12:15], v[164:167], v[232:235], v[12:15]
	v_mfma_f32_16x16x32_bf16 v[8:11], v[172:175], v[232:235], v[8:11]
	v_mfma_f32_16x16x32_bf16 v[52:55], v[176:179], v[204:207], v[52:55]
	v_mfma_f32_16x16x32_bf16 v[48:51], v[196:199], v[204:207], v[48:51]
	v_mfma_f32_16x16x32_bf16 v[36:39], v[176:179], v[212:215], v[36:39]
	v_mfma_f32_16x16x32_bf16 v[32:35], v[196:199], v[212:215], v[32:35]
	v_mfma_f32_16x16x32_bf16 v[20:23], v[176:179], v[220:223], v[20:23]
	v_mfma_f32_16x16x32_bf16 v[16:19], v[196:199], v[220:223], v[16:19]
	v_mfma_f32_16x16x32_bf16 v[4:7], v[176:179], v[228:231], v[4:7]
	v_mfma_f32_16x16x32_bf16 v[0:3], v[196:199], v[228:231], v[0:3]
	v_mfma_f32_16x16x32_bf16 v[52:55], v[192:195], v[208:211], v[52:55]
	v_mfma_f32_16x16x32_bf16 v[48:51], v[200:203], v[208:211], v[48:51]
	v_mfma_f32_16x16x32_bf16 v[36:39], v[192:195], v[216:219], v[36:39]
	v_mfma_f32_16x16x32_bf16 v[32:35], v[200:203], v[216:219], v[32:35]
	v_mfma_f32_16x16x32_bf16 v[20:23], v[192:195], v[224:227], v[20:23]
	v_mfma_f32_16x16x32_bf16 v[16:19], v[200:203], v[224:227], v[16:19]
	v_mfma_f32_16x16x32_bf16 v[4:7], v[192:195], v[232:235], v[4:7]
	v_mfma_f32_16x16x32_bf16 v[0:3], v[200:203], v[232:235], v[0:3]
	s_barrier
	s_add_i32 s40, s40, 2
	s_add_u32 s30, s30, 0x100
	s_addc_u32 s31, s31, 0
	s_add_u32 s21, s21, 0x100
	s_addc_u32 s33, s33, 0
	s_cmp_gt_u32 s40, 29
	s_cbranch_scc0 .LBB0_1088
	s_and_b64 vcc, exec, s[18:19]
	s_cbranch_vccz .LBB0_1091
.LBB0_1091:
	v_mov_b32_e32 v138, v140
	v_mov_b32_e32 v159, v141
	s_lshl_b64 s[12:13], s[60:61], 1
	v_readlane_b32 s14, v245, 30
	v_add_u32_e32 v138, s5, v138
	v_max_f32_e32 v120, v120, v120
	v_readlane_b32 s15, v245, 31
	s_add_u32 s12, s14, s12
	v_ashrrev_i32_e32 v139, 31, v138
	v_max_f32_e32 v120, 0, v120
	v_max_f32_e32 v121, v121, v121
	v_max_f32_e32 v122, v122, v122
	s_addc_u32 s13, s15, s13
	v_lshlrev_b64 v[138:139], 14, v[138:139]
	v_lshlrev_b32_e32 v160, 3, v159
	v_mul_f32_e32 v159, v120, v120
	v_max_f32_e32 v120, v125, v125
	v_max_f32_e32 v121, 0, v121
	v_max_f32_e32 v122, 0, v122
	v_lshl_add_u64 v[138:139], s[12:13], 0, v[138:139]
	s_mov_b32 s21, s61
	v_max_f32_e32 v124, v124, v124
	v_max_f32_e32 v120, 0, v120
	v_mul_f32_e32 v125, v121, v121
	v_max_f32_e32 v121, v126, v126
	v_mul_f32_e32 v126, v122, v122
	v_max_f32_e32 v122, v127, v127
	v_max_f32_e32 v123, v123, v123
	v_lshl_add_u64 v[138:139], v[138:139], 0, s[20:21]
	v_ashrrev_i32_e32 v161, 31, v160
	v_max_f32_e32 v124, 0, v124
	v_mul_f32_e32 v120, v120, v120
	v_max_f32_e32 v121, 0, v121
	v_max_f32_e32 v122, 0, v122
	v_max_f32_e32 v123, 0, v123
	v_max_f32_e32 v112, v112, v112
	v_lshl_add_u64 v[138:139], v[160:161], 1, v[138:139]
	v_mul_f32_e32 v124, v124, v124
	v_mul_f32_e32 v121, v121, v121
	v_mul_f32_e32 v122, v122, v122
	v_mul_f32_e32 v123, v123, v123
	v_cvt_pk_bf16_f32 v120, v124, v120
	v_max_f32_e32 v112, 0, v112
	v_max_f32_e32 v113, v113, v113
	v_max_f32_e32 v114, v114, v114
	v_cvt_pk_bf16_f32 v121, v121, v122
	v_cvt_pk_bf16_f32 v122, v159, v125
	v_cvt_pk_bf16_f32 v123, v126, v123
	global_store_dwordx4 v[138:139], v[120:123], off
	v_max_f32_e32 v113, 0, v113
	v_max_f32_e32 v114, 0, v114
	v_mul_f32_e32 v120, v112, v112
	v_max_f32_e32 v112, v117, v117
	v_max_f32_e32 v116, v116, v116
	v_max_f32_e32 v112, 0, v112
	v_mul_f32_e32 v117, v113, v113
	v_max_f32_e32 v113, v118, v118
	v_mul_f32_e32 v118, v114, v114
	v_max_f32_e32 v114, v119, v119
	v_max_f32_e32 v115, v115, v115
	v_max_f32_e32 v116, 0, v116
	v_mul_f32_e32 v112, v112, v112
	v_max_f32_e32 v113, 0, v113
	v_max_f32_e32 v114, 0, v114
	v_max_f32_e32 v115, 0, v115
	v_max_f32_e32 v104, v104, v104
	v_mul_f32_e32 v116, v116, v116
	v_mul_f32_e32 v113, v113, v113
	v_mul_f32_e32 v114, v114, v114
	v_mul_f32_e32 v115, v115, v115
	v_cvt_pk_bf16_f32 v112, v116, v112
	v_max_f32_e32 v104, 0, v104
	v_max_f32_e32 v105, v105, v105
	v_max_f32_e32 v106, v106, v106
	v_cvt_pk_bf16_f32 v113, v113, v114
	v_cvt_pk_bf16_f32 v114, v120, v117
	v_cvt_pk_bf16_f32 v115, v118, v115
	global_store_dwordx4 v[138:139], v[112:115], off offset:256
	v_max_f32_e32 v108, v108, v108
	v_max_f32_e32 v105, 0, v105
	v_mul_f32_e32 v112, v104, v104
	v_max_f32_e32 v104, v109, v109
	v_max_f32_e32 v106, 0, v106
	v_max_f32_e32 v108, 0, v108
	v_max_f32_e32 v104, 0, v104
	v_mul_f32_e32 v109, v105, v105
	v_max_f32_e32 v105, v110, v110
	v_mul_f32_e32 v110, v106, v106
	v_max_f32_e32 v106, v111, v111
	v_mul_f32_e32 v108, v108, v108
	v_mul_f32_e32 v104, v104, v104
	v_max_f32_e32 v105, 0, v105
	v_max_f32_e32 v106, 0, v106
	v_max_f32_e32 v107, v107, v107
	s_mov_b32 s12, 0x40000
	v_mul_f32_e32 v105, v105, v105
	v_max_f32_e32 v107, 0, v107
	v_mul_f32_e32 v106, v106, v106
	v_cvt_pk_bf16_f32 v104, v108, v104
	v_add_co_u32_e32 v108, vcc, s12, v138
	v_max_f32_e32 v96, v96, v96
	v_mul_f32_e32 v107, v107, v107
	v_cvt_pk_bf16_f32 v105, v105, v106
	v_cvt_pk_bf16_f32 v106, v112, v109
	v_addc_co_u32_e32 v109, vcc, 0, v139, vcc
	v_max_f32_e32 v96, 0, v96
	v_max_f32_e32 v97, v97, v97
	v_max_f32_e32 v98, v98, v98
	v_cvt_pk_bf16_f32 v107, v110, v107
	global_store_dwordx4 v[108:109], v[104:107], off
	v_max_f32_e32 v97, 0, v97
	v_max_f32_e32 v98, 0, v98
	v_mul_f32_e32 v104, v96, v96
	v_max_f32_e32 v96, v101, v101
	v_max_f32_e32 v100, v100, v100
	v_max_f32_e32 v96, 0, v96
	v_mul_f32_e32 v101, v97, v97
	v_max_f32_e32 v97, v102, v102
	v_mul_f32_e32 v102, v98, v98
	v_max_f32_e32 v98, v103, v103
	v_max_f32_e32 v99, v99, v99
	v_max_f32_e32 v100, 0, v100
	v_mul_f32_e32 v96, v96, v96
	v_max_f32_e32 v97, 0, v97
	v_max_f32_e32 v98, 0, v98
	v_max_f32_e32 v99, 0, v99
	v_max_f32_e32 v88, v88, v88
	v_mul_f32_e32 v100, v100, v100
	v_mul_f32_e32 v97, v97, v97
	v_mul_f32_e32 v98, v98, v98
	v_mul_f32_e32 v99, v99, v99
	v_cvt_pk_bf16_f32 v96, v100, v96
	v_max_f32_e32 v88, 0, v88
	v_max_f32_e32 v89, v89, v89
	v_max_f32_e32 v90, v90, v90
	v_cvt_pk_bf16_f32 v97, v97, v98
	v_cvt_pk_bf16_f32 v98, v104, v101
	v_cvt_pk_bf16_f32 v99, v102, v99
	global_store_dwordx4 v[108:109], v[96:99], off offset:256
	s_cmp_lg_u64 s[18:19], 0
	s_cbranch_scc0 .Llate_align_10
	s_barrier
; __device__ __forceinline__ unsigned cvt_pk_bf16(float lo, float hi) { unsigned r; asm volatile("v_cvt_pk_bf16_f32 %0, %1, %2" : "=v"(r) : "v"(lo), "v"(hi)); return r; }
; __device__ __forceinline__ float silu_f(float v) { return v / (1.0f + __expf(-v)); }
;     __device__ __forceinline__ void operator()(const Acc& acc, const Unit& u, int wr, int wc, int fr, int fq) const {
;         asm volatile("" : "+v"(fr), "+v"(fq));
;         bf16_t* base = O + u.coff + (size_t)(wr * 64 + fr) * ldc + wc * 32 + 8 * fq;
; #pragma unroll
;         for (int ai = 0; ai < 2; ++ai)
; #pragma unroll
;             for (int m = 0; m < 4; ++m) { bf16_t* rowp = base + (size_t)(ai * HALF + m * 16) * ldc;
; #pragma unroll
;                 for (int bj = 0; bj < 2; ++bj) { f32x4 v0 = acc[ai][bj][m][0], v1 = acc[ai][bj][m][1];
;                     if (ACT == 1) {
; #pragma unroll
;                         for (int j = 0; j < 4; ++j) { v0[j] = silu_f(v0[j]); v1[j] = silu_f(v1[j]); } }
;                     if (ACT == 2) {
; #pragma unroll
;                         for (int j = 0; j < 4; ++j) { const float a = fmaxf(v0[j], 0.f), b = fmaxf(v1[j], 0.f); v0[j] = a * a; v1[j] = b * b; } }
;                     u32x4 w; w.x = cvt_pk_bf16(v0[0], v0[1]); w.y = cvt_pk_bf16(v0[2], v0[3]); w.z = cvt_pk_bf16(v1[0], v1[1]); w.w = cvt_pk_bf16(v1[2], v1[3]);
;                     *(u32x4*)(rowp + bj * HALF) = w; } }
.Llate_align_10:
	v_max_f32_e32 v92, v92, v92
	v_max_f32_e32 v89, 0, v89
	v_mul_f32_e32 v96, v88, v88
	v_max_f32_e32 v88, v93, v93
	v_max_f32_e32 v90, 0, v90
	v_max_f32_e32 v92, 0, v92
	v_max_f32_e32 v88, 0, v88
	v_mul_f32_e32 v93, v89, v89
	v_max_f32_e32 v89, v94, v94
	v_mul_f32_e32 v94, v90, v90
	v_max_f32_e32 v90, v95, v95
	v_mul_f32_e32 v92, v92, v92
	v_mul_f32_e32 v88, v88, v88
	v_max_f32_e32 v89, 0, v89
	v_max_f32_e32 v90, 0, v90
	v_max_f32_e32 v91, v91, v91
	s_mov_b32 s12, 0x80000
	v_mul_f32_e32 v89, v89, v89
	v_max_f32_e32 v91, 0, v91
	v_mul_f32_e32 v90, v90, v90
	v_cvt_pk_bf16_f32 v88, v92, v88
	v_add_co_u32_e32 v92, vcc, s12, v138
	v_max_f32_e32 v80, v80, v80
	v_mul_f32_e32 v91, v91, v91
	v_cvt_pk_bf16_f32 v89, v89, v90
	v_cvt_pk_bf16_f32 v90, v96, v93
	v_addc_co_u32_e32 v93, vcc, 0, v139, vcc
	v_max_f32_e32 v80, 0, v80
	v_max_f32_e32 v81, v81, v81
	v_max_f32_e32 v82, v82, v82
	v_cvt_pk_bf16_f32 v91, v94, v91
	global_store_dwordx4 v[92:93], v[88:91], off
	v_max_f32_e32 v81, 0, v81
	v_max_f32_e32 v82, 0, v82
	v_mul_f32_e32 v88, v80, v80
	v_max_f32_e32 v80, v85, v85
	v_max_f32_e32 v84, v84, v84
	v_max_f32_e32 v80, 0, v80
	v_mul_f32_e32 v85, v81, v81
	v_max_f32_e32 v81, v86, v86
	v_mul_f32_e32 v86, v82, v82
	v_max_f32_e32 v82, v87, v87
	v_max_f32_e32 v83, v83, v83
	v_max_f32_e32 v84, 0, v84
	v_mul_f32_e32 v80, v80, v80
	v_max_f32_e32 v81, 0, v81
	v_max_f32_e32 v82, 0, v82
	v_max_f32_e32 v83, 0, v83
	v_max_f32_e32 v72, v72, v72
	v_mul_f32_e32 v84, v84, v84
	v_mul_f32_e32 v81, v81, v81
	v_mul_f32_e32 v82, v82, v82
	v_mul_f32_e32 v83, v83, v83
	v_cvt_pk_bf16_f32 v80, v84, v80
	v_max_f32_e32 v72, 0, v72
	v_max_f32_e32 v73, v73, v73
	v_max_f32_e32 v74, v74, v74
	v_cvt_pk_bf16_f32 v81, v81, v82
	v_cvt_pk_bf16_f32 v82, v88, v85
	v_cvt_pk_bf16_f32 v83, v86, v83
	global_store_dwordx4 v[92:93], v[80:83], off offset:256
	v_max_f32_e32 v76, v76, v76
	v_max_f32_e32 v73, 0, v73
	v_mul_f32_e32 v80, v72, v72
	v_max_f32_e32 v72, v77, v77
	v_max_f32_e32 v74, 0, v74
	v_max_f32_e32 v76, 0, v76
	v_max_f32_e32 v72, 0, v72
	v_mul_f32_e32 v77, v73, v73
	v_max_f32_e32 v73, v78, v78
	v_mul_f32_e32 v78, v74, v74
	v_max_f32_e32 v74, v79, v79
	v_mul_f32_e32 v76, v76, v76
	v_mul_f32_e32 v72, v72, v72
	v_max_f32_e32 v73, 0, v73
	v_max_f32_e32 v74, 0, v74
	v_max_f32_e32 v75, v75, v75
	s_mov_b32 s12, 0xc0000
	v_mul_f32_e32 v73, v73, v73
	v_max_f32_e32 v75, 0, v75
	v_mul_f32_e32 v74, v74, v74
	v_cvt_pk_bf16_f32 v72, v76, v72
	v_add_co_u32_e32 v76, vcc, s12, v138
	v_max_f32_e32 v64, v64, v64
	v_mul_f32_e32 v75, v75, v75
	v_cvt_pk_bf16_f32 v73, v73, v74
	v_cvt_pk_bf16_f32 v74, v80, v77
	v_addc_co_u32_e32 v77, vcc, 0, v139, vcc
	v_max_f32_e32 v64, 0, v64
	v_max_f32_e32 v65, v65, v65
	v_max_f32_e32 v66, v66, v66
	v_cvt_pk_bf16_f32 v75, v78, v75
	global_store_dwordx4 v[76:77], v[72:75], off
	v_max_f32_e32 v65, 0, v65
	v_max_f32_e32 v66, 0, v66
	v_mul_f32_e32 v72, v64, v64
	v_max_f32_e32 v64, v69, v69
	v_max_f32_e32 v68, v68, v68
	v_max_f32_e32 v64, 0, v64
	v_mul_f32_e32 v69, v65, v65
	v_max_f32_e32 v65, v70, v70
	v_mul_f32_e32 v70, v66, v66
	v_max_f32_e32 v66, v71, v71
	v_max_f32_e32 v67, v67, v67
	v_max_f32_e32 v68, 0, v68
	v_mul_f32_e32 v64, v64, v64
	v_max_f32_e32 v65, 0, v65
	v_max_f32_e32 v66, 0, v66
	v_max_f32_e32 v67, 0, v67
	v_max_f32_e32 v56, v56, v56
	v_mul_f32_e32 v68, v68, v68
	v_mul_f32_e32 v65, v65, v65
	v_mul_f32_e32 v66, v66, v66
	v_mul_f32_e32 v67, v67, v67
	v_cvt_pk_bf16_f32 v64, v68, v64
	v_max_f32_e32 v56, 0, v56
	v_max_f32_e32 v57, v57, v57
	v_max_f32_e32 v58, v58, v58
	v_cvt_pk_bf16_f32 v65, v65, v66
	v_cvt_pk_bf16_f32 v66, v72, v69
	v_cvt_pk_bf16_f32 v67, v70, v67
	global_store_dwordx4 v[76:77], v[64:67], off offset:256
	v_max_f32_e32 v60, v60, v60
	v_max_f32_e32 v57, 0, v57
	v_mul_f32_e32 v64, v56, v56
	v_max_f32_e32 v56, v61, v61
	v_max_f32_e32 v58, 0, v58
	v_max_f32_e32 v60, 0, v60
	v_max_f32_e32 v56, 0, v56
	v_mul_f32_e32 v61, v57, v57
	v_max_f32_e32 v57, v62, v62
	v_mul_f32_e32 v62, v58, v58
	v_max_f32_e32 v58, v63, v63
	v_mul_f32_e32 v60, v60, v60
	v_mul_f32_e32 v56, v56, v56
	v_max_f32_e32 v57, 0, v57
	v_max_f32_e32 v58, 0, v58
	v_max_f32_e32 v59, v59, v59
	s_mov_b32 s12, 0x200000
	v_mul_f32_e32 v57, v57, v57
	v_max_f32_e32 v59, 0, v59
	v_mul_f32_e32 v58, v58, v58
	v_cvt_pk_bf16_f32 v56, v60, v56
	v_add_co_u32_e32 v60, vcc, s12, v138
	v_max_f32_e32 v48, v48, v48
	v_mul_f32_e32 v59, v59, v59
	v_cvt_pk_bf16_f32 v57, v57, v58
	v_cvt_pk_bf16_f32 v58, v64, v61
	v_addc_co_u32_e32 v61, vcc, 0, v139, vcc
	v_max_f32_e32 v48, 0, v48
	v_max_f32_e32 v49, v49, v49
	v_max_f32_e32 v50, v50, v50
	v_cvt_pk_bf16_f32 v59, v62, v59
	global_store_dwordx4 v[60:61], v[56:59], off
	v_max_f32_e32 v49, 0, v49
	v_max_f32_e32 v50, 0, v50
	v_mul_f32_e32 v56, v48, v48
	v_max_f32_e32 v48, v53, v53
	v_max_f32_e32 v52, v52, v52
	v_max_f32_e32 v48, 0, v48
	v_mul_f32_e32 v53, v49, v49
	v_max_f32_e32 v49, v54, v54
	v_mul_f32_e32 v54, v50, v50
	v_max_f32_e32 v50, v55, v55
	v_max_f32_e32 v51, v51, v51
	v_max_f32_e32 v52, 0, v52
	v_mul_f32_e32 v48, v48, v48
	v_max_f32_e32 v49, 0, v49
	v_max_f32_e32 v50, 0, v50
	v_max_f32_e32 v51, 0, v51
	v_max_f32_e32 v40, v40, v40
	v_mul_f32_e32 v52, v52, v52
	v_mul_f32_e32 v49, v49, v49
	v_mul_f32_e32 v50, v50, v50
	v_mul_f32_e32 v51, v51, v51
	v_cvt_pk_bf16_f32 v48, v52, v48
	v_max_f32_e32 v40, 0, v40
	v_max_f32_e32 v41, v41, v41
	v_max_f32_e32 v42, v42, v42
	v_cvt_pk_bf16_f32 v49, v49, v50
	v_cvt_pk_bf16_f32 v50, v56, v53
	v_cvt_pk_bf16_f32 v51, v54, v51
; __device__ __forceinline__ unsigned cvt_pk_bf16(float lo, float hi) { unsigned r; asm volatile("v_cvt_pk_bf16_f32 %0, %1, %2" : "=v"(r) : "v"(lo), "v"(hi)); return r; }
; __device__ __forceinline__ float silu_f(float v) { return v / (1.0f + __expf(-v)); }
; #define PG8_BAR __builtin_amdgcn_s_barrier()
; template <class Epi, class Map>
; __device__ __forceinline__ void gemm_phase(LAS unsigned char* lds, const Gemm g, const Sched<Map>& S, const Epi& E) {
;     ...
;         if (!has_next) break;
; #pragma unroll
;         for (int a = 0; a < 2; ++a)
; #pragma unroll
;             for (int b = 0; b < 2; ++b)
; #pragma unroll
;                 for (int m = 0; m < 4; ++m)
; #pragma unroll
;                     for (int n = 0; n < 2; ++n) acc[a][b][m][n] = (f32x4){0.f, 0.f, 0.f, 0.f};
;         cur = nxt; cA = nA; cB = nB; ++ui;
;         if (wr == 1) PG8_BAR;
;     __device__ __forceinline__ void operator()(const Acc& acc, const Unit& u, int wr, int wc, int fr, int fq) const {
;         asm volatile("" : "+v"(fr), "+v"(fq));
;         bf16_t* base = O + u.coff + (size_t)(wr * 64 + fr) * ldc + wc * 32 + 8 * fq;
; #pragma unroll
;         for (int ai = 0; ai < 2; ++ai)
; #pragma unroll
;             for (int m = 0; m < 4; ++m) { bf16_t* rowp = base + (size_t)(ai * HALF + m * 16) * ldc;
; #pragma unroll
;                 for (int bj = 0; bj < 2; ++bj) { f32x4 v0 = acc[ai][bj][m][0], v1 = acc[ai][bj][m][1];
;                     if (ACT == 1) {
; #pragma unroll
;                         for (int j = 0; j < 4; ++j) { v0[j] = silu_f(v0[j]); v1[j] = silu_f(v1[j]); } }
;                     if (ACT == 2) {
; #pragma unroll
;                         for (int j = 0; j < 4; ++j) { const float a = fmaxf(v0[j], 0.f), b = fmaxf(v1[j], 0.f); v0[j] = a * a; v1[j] = b * b; } }
;                     u32x4 w; w.x = cvt_pk_bf16(v0[0], v0[1]); w.y = cvt_pk_bf16(v0[2], v0[3]); w.z = cvt_pk_bf16(v1[0], v1[1]); w.w = cvt_pk_bf16(v1[2], v1[3]);
;                     *(u32x4*)(rowp + bj * HALF) = w; } }
	global_store_dwordx4 v[60:61], v[48:51], off offset:256
	v_max_f32_e32 v44, v44, v44
	v_max_f32_e32 v41, 0, v41
	v_mul_f32_e32 v48, v40, v40
	v_max_f32_e32 v40, v45, v45
	v_max_f32_e32 v42, 0, v42
	v_max_f32_e32 v44, 0, v44
	v_max_f32_e32 v40, 0, v40
	v_mul_f32_e32 v45, v41, v41
	v_max_f32_e32 v41, v46, v46
	v_mul_f32_e32 v46, v42, v42
	v_max_f32_e32 v42, v47, v47
	v_mul_f32_e32 v44, v44, v44
	v_mul_f32_e32 v40, v40, v40
	v_max_f32_e32 v41, 0, v41
	v_max_f32_e32 v42, 0, v42
	v_max_f32_e32 v43, v43, v43
	s_mov_b32 s12, 0x240000
	v_mul_f32_e32 v41, v41, v41
	v_max_f32_e32 v43, 0, v43
	v_mul_f32_e32 v42, v42, v42
	v_cvt_pk_bf16_f32 v40, v44, v40
	v_add_co_u32_e32 v44, vcc, s12, v138
	v_max_f32_e32 v32, v32, v32
	v_mul_f32_e32 v43, v43, v43
	v_cvt_pk_bf16_f32 v41, v41, v42
	v_cvt_pk_bf16_f32 v42, v48, v45
	v_addc_co_u32_e32 v45, vcc, 0, v139, vcc
	v_max_f32_e32 v32, 0, v32
	v_max_f32_e32 v33, v33, v33
	v_max_f32_e32 v34, v34, v34
	v_cvt_pk_bf16_f32 v43, v46, v43
	global_store_dwordx4 v[44:45], v[40:43], off
	v_max_f32_e32 v33, 0, v33
	v_max_f32_e32 v34, 0, v34
	v_mul_f32_e32 v40, v32, v32
	v_max_f32_e32 v32, v37, v37
	v_max_f32_e32 v36, v36, v36
	v_max_f32_e32 v32, 0, v32
	v_mul_f32_e32 v37, v33, v33
	v_max_f32_e32 v33, v38, v38
	v_mul_f32_e32 v38, v34, v34
	v_max_f32_e32 v34, v39, v39
	v_max_f32_e32 v35, v35, v35
	v_max_f32_e32 v36, 0, v36
	v_mul_f32_e32 v32, v32, v32
	v_max_f32_e32 v33, 0, v33
	v_max_f32_e32 v34, 0, v34
	v_max_f32_e32 v35, 0, v35
	v_max_f32_e32 v24, v24, v24
	v_mul_f32_e32 v36, v36, v36
	v_mul_f32_e32 v33, v33, v33
	v_mul_f32_e32 v34, v34, v34
	v_mul_f32_e32 v35, v35, v35
	v_cvt_pk_bf16_f32 v32, v36, v32
	v_max_f32_e32 v24, 0, v24
	v_max_f32_e32 v25, v25, v25
	v_max_f32_e32 v26, v26, v26
	v_cvt_pk_bf16_f32 v33, v33, v34
	v_cvt_pk_bf16_f32 v34, v40, v37
	v_cvt_pk_bf16_f32 v35, v38, v35
	global_store_dwordx4 v[44:45], v[32:35], off offset:256
	v_max_f32_e32 v28, v28, v28
	v_max_f32_e32 v25, 0, v25
	v_mul_f32_e32 v32, v24, v24
	v_max_f32_e32 v24, v29, v29
	v_max_f32_e32 v26, 0, v26
	v_max_f32_e32 v28, 0, v28
	v_max_f32_e32 v24, 0, v24
	v_mul_f32_e32 v29, v25, v25
	v_max_f32_e32 v25, v30, v30
	v_mul_f32_e32 v30, v26, v26
	v_max_f32_e32 v26, v31, v31
	v_mul_f32_e32 v28, v28, v28
	v_mul_f32_e32 v24, v24, v24
	v_max_f32_e32 v25, 0, v25
	v_max_f32_e32 v26, 0, v26
	v_max_f32_e32 v27, v27, v27
	s_mov_b32 s12, 0x280000
	v_mul_f32_e32 v25, v25, v25
	v_max_f32_e32 v27, 0, v27
	v_mul_f32_e32 v26, v26, v26
	v_cvt_pk_bf16_f32 v24, v28, v24
	v_add_co_u32_e32 v28, vcc, s12, v138
	v_max_f32_e32 v16, v16, v16
	v_mul_f32_e32 v27, v27, v27
	v_cvt_pk_bf16_f32 v25, v25, v26
	v_cvt_pk_bf16_f32 v26, v32, v29
	v_addc_co_u32_e32 v29, vcc, 0, v139, vcc
	v_max_f32_e32 v16, 0, v16
	v_max_f32_e32 v17, v17, v17
	v_max_f32_e32 v18, v18, v18
	v_cvt_pk_bf16_f32 v27, v30, v27
	global_store_dwordx4 v[28:29], v[24:27], off
	v_max_f32_e32 v17, 0, v17
	v_max_f32_e32 v18, 0, v18
	v_mul_f32_e32 v24, v16, v16
	v_max_f32_e32 v16, v21, v21
	v_max_f32_e32 v20, v20, v20
	v_max_f32_e32 v16, 0, v16
	v_mul_f32_e32 v21, v17, v17
	v_max_f32_e32 v17, v22, v22
	v_mul_f32_e32 v22, v18, v18
	v_max_f32_e32 v18, v23, v23
	v_max_f32_e32 v19, v19, v19
	v_max_f32_e32 v20, 0, v20
	v_mul_f32_e32 v16, v16, v16
	v_max_f32_e32 v17, 0, v17
	v_max_f32_e32 v18, 0, v18
	v_max_f32_e32 v19, 0, v19
	v_max_f32_e32 v8, v8, v8
	v_mul_f32_e32 v20, v20, v20
	v_mul_f32_e32 v17, v17, v17
	v_mul_f32_e32 v18, v18, v18
	v_mul_f32_e32 v19, v19, v19
	v_cvt_pk_bf16_f32 v16, v20, v16
	v_max_f32_e32 v8, 0, v8
	v_max_f32_e32 v9, v9, v9
	v_max_f32_e32 v10, v10, v10
	v_cvt_pk_bf16_f32 v17, v17, v18
	v_cvt_pk_bf16_f32 v18, v24, v21
	v_cvt_pk_bf16_f32 v19, v22, v19
	global_store_dwordx4 v[28:29], v[16:19], off offset:256
	v_max_f32_e32 v12, v12, v12
	v_max_f32_e32 v9, 0, v9
	v_mul_f32_e32 v16, v8, v8
	v_max_f32_e32 v8, v13, v13
	v_max_f32_e32 v10, 0, v10
	v_max_f32_e32 v12, 0, v12
	v_max_f32_e32 v8, 0, v8
	v_mul_f32_e32 v13, v9, v9
	v_max_f32_e32 v9, v14, v14
	v_mul_f32_e32 v14, v10, v10
	v_max_f32_e32 v10, v15, v15
	v_mul_f32_e32 v12, v12, v12
	v_mul_f32_e32 v8, v8, v8
	v_max_f32_e32 v9, 0, v9
	v_max_f32_e32 v10, 0, v10
	v_max_f32_e32 v11, v11, v11
	s_mov_b32 s12, 0x2c0000
	v_mul_f32_e32 v9, v9, v9
	v_max_f32_e32 v11, 0, v11
	v_mul_f32_e32 v10, v10, v10
	v_cvt_pk_bf16_f32 v8, v12, v8
	v_add_co_u32_e32 v12, vcc, s12, v138
	v_max_f32_e32 v0, v0, v0
	v_max_f32_e32 v1, v1, v1
	v_max_f32_e32 v2, v2, v2
	v_mul_f32_e32 v11, v11, v11
	v_cvt_pk_bf16_f32 v9, v9, v10
	v_cvt_pk_bf16_f32 v10, v16, v13
	v_addc_co_u32_e32 v13, vcc, 0, v139, vcc
	v_max_f32_e32 v0, 0, v0
	v_max_f32_e32 v1, 0, v1
	v_max_f32_e32 v2, 0, v2
	v_cvt_pk_bf16_f32 v11, v14, v11
	global_store_dwordx4 v[12:13], v[8:11], off
	v_max_f32_e32 v3, v3, v3
	v_max_f32_e32 v4, v4, v4
	v_mul_f32_e32 v8, v0, v0
	v_max_f32_e32 v0, v5, v5
	v_mul_f32_e32 v5, v1, v1
	v_max_f32_e32 v1, v6, v6
	v_mul_f32_e32 v6, v2, v2
	v_max_f32_e32 v2, v7, v7
	v_max_f32_e32 v0, 0, v0
	v_max_f32_e32 v1, 0, v1
	v_max_f32_e32 v2, 0, v2
	v_max_f32_e32 v3, 0, v3
	v_max_f32_e32 v4, 0, v4
	v_mul_f32_e32 v0, v0, v0
	v_mul_f32_e32 v1, v1, v1
	v_mul_f32_e32 v2, v2, v2
	v_mul_f32_e32 v3, v3, v3
	s_andn2_b64 vcc, exec, s[38:39]
	s_mov_b64 s[30:31], -1
	v_mul_f32_e32 v4, v4, v4
	v_cvt_pk_bf16_f32 v0, v4, v0
	v_cvt_pk_bf16_f32 v1, v1, v2
	v_cvt_pk_bf16_f32 v2, v8, v5
	v_cvt_pk_bf16_f32 v3, v6, v3
	global_store_dwordx4 v[12:13], v[0:3], off offset:256
	s_cbranch_vccnz .LBB0_1080
	s_andn2_b64 vcc, exec, s[16:17]
	s_cbranch_vccnz .LBB0_1079
	s_barrier
	s_branch .LBB0_1079

; #define PG8_STAGE(bufoff, gbase, voff) do { _Pragma("unroll") for (int _i = 0; _i < 2; ++_i) \
;         __builtin_amdgcn_global_load_lds((const unsigned*)((const char*)(gbase) + (voff)[_i]), (LAS unsigned*)(lds + (bufoff) + ldsw + _i * 8192), 16, 0, 0); } while (0)
; #define PG8_LDA(dst, b, h) do { _Pragma("unroll") for (int m = 0; m < 4; ++m) _Pragma("unroll") for (int k = 0; k < 2; ++k) dst[m][k] = *(const LAS bf16x8*)(lds + PG8_SA(b, h) + aoff + m * 2048 + k * 1024); } while (0)
; #define PG8_LDB(dst, b, h) do { _Pragma("unroll") for (int n = 0; n < 2; ++n) _Pragma("unroll") for (int k = 0; k < 2; ++k) dst[n][k] = *(const LAS bf16x8*)(lds + PG8_SB(b, h) + boff + n * 2048 + k * 1024); } while (0)
; #define PG8_MMA(ai, bj, At, Bt) do { __builtin_amdgcn_s_setprio(1); _Pragma("unroll") for (int m = 0; m < 4; ++m) _Pragma("unroll") for (int n = 0; n < 2; ++n) _Pragma("unroll") for (int k = 0; k < 2; ++k) \
;         acc[ai][bj][m][n] = __builtin_amdgcn_mfma_f32_16x16x32_bf16(Bt[n][k], At[m][k], acc[ai][bj][m][n], 0, 0, 0); __builtin_amdgcn_s_setprio(0); } while (0)
; #define PG8_WAIT_V(n) asm volatile("s_waitcnt vmcnt(" #n ")" ::: "memory")
; #define PG8_WAIT_L(n) asm volatile("s_waitcnt lgkmcnt(" #n ")" ::: "memory")
; #define PG8_BAR __builtin_amdgcn_s_barrier()
; template <class Epi, class Map>
; __device__ __forceinline__ void gemm_phase(LAS unsigned char* lds, const Gemm g, const Sched<Map>& S, const Epi& E) {
;     ...
;         for (int t = 0; t < nt; t += 2) {
;             const bool last = (t == nt - 2);
;             const char* a1 = cA + (size_t)(t + 1) * kstep;
;             const char* a2 = last ? nA : cA + (size_t)(t + 2) * kstep; const char* b2 = last ? nB : cB + (size_t)(t + 2) * kstep;
;             const char* a3 = a2 + kstep; const char* b3 = b2 + kstep;
;             PG8_LDB(B0, 0, 0); PG8_LDB(B1, 0, 1); PG8_SCHED; PG8_LDA(At, 0, 0); PG8_STAGE(PG8_SA(1, 1), a1 + hstepA, voffA);
;             PG8_WAIT_V(8); PG8_WAIT_L(0); PG8_BAR; PG8_MMA(0, 0, At, B0); PG8_MMA(0, 1, At, B1); PG8_BAR; PG8_SCHED;
;     ...
;         for (int a = 0; a < 2; ++a)
; #pragma unroll
;             for (int b = 0; b < 2; ++b)
; #pragma unroll
;                 for (int m = 0; m < 4; ++m)
; #pragma unroll
;                     for (int n = 0; n < 2; ++n) acc[a][b][m][n] = (f32x4){0.f, 0.f, 0.f, 0.f};
;         cur = nxt; cA = nA; cB = nB; ++ui;
.LBB0_1160:
	v_readlane_b32 s20, v245, 30
	v_readlane_b32 s21, v245, 31
	s_add_u32 s20, s20, s15
	s_addc_u32 s21, s21, 0
	s_and_b64 s[24:25], s[40:41], exec
	v_readlane_b32 s24, v244, 22
	s_cselect_b32 s37, s21, s29
	s_cselect_b32 s44, s20, s28
	s_add_u32 s24, s24, s14
	v_readlane_b32 s25, v244, 23
	s_addc_u32 s25, s25, 0
	s_and_b64 s[34:35], s[40:41], exec
	s_cselect_b32 s45, s25, s31
	s_cselect_b32 s46, s24, s30
	s_add_u32 s28, s28, 0x200080
	s_addc_u32 s29, s29, 0
	s_add_u32 s47, s30, 0x100
	v_mov_b32_e32 v0, 0
	s_addc_u32 s48, s31, 0
	s_mov_b32 s49, -2
	v_mov_b32_e32 v1, v0
	v_mov_b32_e32 v2, v0
	v_mov_b32_e32 v3, v0
	v_mov_b32_e32 v4, v0
	v_mov_b32_e32 v5, v0
	v_mov_b32_e32 v6, v0
	v_mov_b32_e32 v7, v0
	v_mov_b32_e32 v12, v0
	v_mov_b32_e32 v13, v0
	v_mov_b32_e32 v14, v0
	v_mov_b32_e32 v15, v0
	v_mov_b32_e32 v20, v0
	v_mov_b32_e32 v21, v0
	v_mov_b32_e32 v22, v0
	v_mov_b32_e32 v23, v0
	v_mov_b32_e32 v28, v0
	v_mov_b32_e32 v29, v0
	v_mov_b32_e32 v30, v0
	v_mov_b32_e32 v31, v0
	v_mov_b32_e32 v36, v0
	v_mov_b32_e32 v37, v0
	v_mov_b32_e32 v38, v0
	v_mov_b32_e32 v39, v0
	v_mov_b32_e32 v44, v0
	v_mov_b32_e32 v45, v0
	v_mov_b32_e32 v46, v0
	v_mov_b32_e32 v47, v0
	v_mov_b32_e32 v52, v0
	v_mov_b32_e32 v53, v0
	v_mov_b32_e32 v54, v0
	v_mov_b32_e32 v55, v0
	v_mov_b32_e32 v8, v0
	v_mov_b32_e32 v9, v0
	v_mov_b32_e32 v10, v0
	v_mov_b32_e32 v11, v0
	v_mov_b32_e32 v16, v0
	v_mov_b32_e32 v17, v0
	v_mov_b32_e32 v18, v0
	v_mov_b32_e32 v19, v0
	v_mov_b32_e32 v24, v0
	v_mov_b32_e32 v25, v0
	v_mov_b32_e32 v26, v0
	v_mov_b32_e32 v27, v0
	v_mov_b32_e32 v32, v0
	v_mov_b32_e32 v33, v0
	v_mov_b32_e32 v34, v0
	v_mov_b32_e32 v35, v0
	v_mov_b32_e32 v40, v0
	v_mov_b32_e32 v41, v0
	v_mov_b32_e32 v42, v0
	v_mov_b32_e32 v43, v0
	v_mov_b32_e32 v48, v0
	v_mov_b32_e32 v49, v0
	v_mov_b32_e32 v50, v0
	v_mov_b32_e32 v51, v0
	v_mov_b32_e32 v56, v0
	v_mov_b32_e32 v57, v0
	v_mov_b32_e32 v58, v0
	v_mov_b32_e32 v59, v0
	v_mov_b32_e32 v60, v0
	v_mov_b32_e32 v61, v0
	v_mov_b32_e32 v62, v0
	v_mov_b32_e32 v63, v0
	v_mov_b32_e32 v64, v0
	v_mov_b32_e32 v65, v0
	v_mov_b32_e32 v66, v0
	v_mov_b32_e32 v67, v0
	v_mov_b32_e32 v68, v0
	v_mov_b32_e32 v69, v0
	v_mov_b32_e32 v70, v0
	v_mov_b32_e32 v71, v0
	v_mov_b32_e32 v80, v0
	v_mov_b32_e32 v81, v0
	v_mov_b32_e32 v82, v0
	v_mov_b32_e32 v83, v0
	v_mov_b32_e32 v84, v0
	v_mov_b32_e32 v85, v0
	v_mov_b32_e32 v86, v0
	v_mov_b32_e32 v87, v0
	v_mov_b32_e32 v88, v0
	v_mov_b32_e32 v89, v0
	v_mov_b32_e32 v90, v0
	v_mov_b32_e32 v91, v0
	v_mov_b32_e32 v92, v0
	v_mov_b32_e32 v93, v0
	v_mov_b32_e32 v94, v0
	v_mov_b32_e32 v95, v0
	v_mov_b32_e32 v120, v0
	v_mov_b32_e32 v121, v0
	v_mov_b32_e32 v122, v0
	v_mov_b32_e32 v123, v0
	v_mov_b32_e32 v124, v0
	v_mov_b32_e32 v125, v0
	v_mov_b32_e32 v126, v0
	v_mov_b32_e32 v127, v0
	v_mov_b32_e32 v72, v0
	v_mov_b32_e32 v73, v0
	v_mov_b32_e32 v74, v0
	v_mov_b32_e32 v75, v0
	v_mov_b32_e32 v76, v0
	v_mov_b32_e32 v77, v0
	v_mov_b32_e32 v78, v0
	v_mov_b32_e32 v79, v0
	v_mov_b32_e32 v96, v0
	v_mov_b32_e32 v97, v0
	v_mov_b32_e32 v98, v0
	v_mov_b32_e32 v99, v0
	v_mov_b32_e32 v100, v0
	v_mov_b32_e32 v101, v0
	v_mov_b32_e32 v102, v0
	v_mov_b32_e32 v103, v0
	v_mov_b32_e32 v128, v0
	v_mov_b32_e32 v129, v0
	v_mov_b32_e32 v130, v0
	v_mov_b32_e32 v131, v0
	v_mov_b32_e32 v132, v0
	v_mov_b32_e32 v133, v0
	v_mov_b32_e32 v134, v0
	v_mov_b32_e32 v135, v0
	v_mov_b32_e32 v136, v0
	v_mov_b32_e32 v137, v0
	v_mov_b32_e32 v138, v0
	v_mov_b32_e32 v139, v0
	v_mov_b32_e32 v140, v0
	v_mov_b32_e32 v141, v0
	v_mov_b32_e32 v142, v0
	v_mov_b32_e32 v143, v0
.LBB0_1161:
	s_add_u32 s30, s28, 0xffe00080
	s_addc_u32 s31, s29, -1
	s_add_i32 s50, 0, 0x10000
	s_cmpk_eq_i32 s49, 0x7c
	s_cselect_b32 s35, s37, s31
	s_cselect_b32 s34, s44, s30
	s_cselect_b32 s31, s45, s48
	s_cselect_b32 s30, s46, s47
	s_add_i32 s52, 0, 0x14000
	v_add_u32_e32 v116, s50, v173
	v_add_u32_e32 v170, s52, v173
	ds_read_b128 v[104:107], v116
	ds_read_b128 v[108:111], v116 offset:1024
	ds_read_b128 v[112:115], v116 offset:2048
	ds_read_b128 v[116:119], v116 offset:3072
	ds_read_b128 v[176:179], v170
	ds_read_b128 v[192:195], v170 offset:1024
	ds_read_b128 v[196:199], v170 offset:2048
	ds_read_b128 v[200:203], v170 offset:3072
	v_lshl_add_u64 v[170:171], s[28:29], 0, v[166:167]
	s_add_i32 m0, s3, 0xc000
	ds_read_b128 v[204:207], v174
	ds_read_b128 v[208:211], v174 offset:1024
	ds_read_b128 v[212:215], v174 offset:2048
	ds_read_b128 v[216:219], v174 offset:3072
	ds_read_b128 v[220:223], v174 offset:4096
	ds_read_b128 v[224:227], v174 offset:5120
	ds_read_b128 v[228:231], v174 offset:6144
	ds_read_b128 v[232:235], v174 offset:7168
	global_load_lds_dwordx4 v[170:171], off
	v_lshl_add_u64 v[170:171], s[28:29], 0, v[168:169]
	s_add_i32 m0, s3, 0xe000
	s_nop 0
	global_load_lds_dwordx4 v[170:171], off
	s_waitcnt vmcnt(8)
	s_waitcnt lgkmcnt(0)
	s_barrier
; #define PG8_STAGE(bufoff, gbase, voff) do { _Pragma("unroll") for (int _i = 0; _i < 2; ++_i) \
;         __builtin_amdgcn_global_load_lds((const unsigned*)((const char*)(gbase) + (voff)[_i]), (LAS unsigned*)(lds + (bufoff) + ldsw + _i * 8192), 16, 0, 0); } while (0)
; #define PG8_LDA(dst, b, h) do { _Pragma("unroll") for (int m = 0; m < 4; ++m) _Pragma("unroll") for (int k = 0; k < 2; ++k) dst[m][k] = *(const LAS bf16x8*)(lds + PG8_SA(b, h) + aoff + m * 2048 + k * 1024); } while (0)
; #define PG8_MMA(ai, bj, At, Bt) do { __builtin_amdgcn_s_setprio(1); _Pragma("unroll") for (int m = 0; m < 4; ++m) _Pragma("unroll") for (int n = 0; n < 2; ++n) _Pragma("unroll") for (int k = 0; k < 2; ++k) \
;         acc[ai][bj][m][n] = __builtin_amdgcn_mfma_f32_16x16x32_bf16(Bt[n][k], At[m][k], acc[ai][bj][m][n], 0, 0, 0); __builtin_amdgcn_s_setprio(0); } while (0)
; #define PG8_WAIT_V(n) asm volatile("s_waitcnt vmcnt(" #n ")" ::: "memory")
; #define PG8_WAIT_L(n) asm volatile("s_waitcnt lgkmcnt(" #n ")" ::: "memory")
; #define PG8_BAR __builtin_amdgcn_s_barrier()
; #define PG8_SCHED __builtin_amdgcn_sched_barrier(0)
; template <class Epi, class Map>
; __device__ __forceinline__ void gemm_phase(LAS unsigned char* lds, const Gemm g, const Sched<Map>& S, const Epi& E) {
;     ...
;             PG8_WAIT_V(8); PG8_WAIT_L(0); PG8_BAR; PG8_MMA(0, 0, At, B0); PG8_MMA(0, 1, At, B1); PG8_BAR; PG8_SCHED;
;             PG8_LDA(At, 0, 1); PG8_STAGE(PG8_SB(0, 0), b2, voffB); PG8_STAGE(PG8_SB(0, 1), b2 + hstepB, voffB); PG8_STAGE(PG8_SA(0, 0), a2, voffA);
;             PG8_WAIT_V(8); PG8_WAIT_L(0); PG8_BAR; PG8_MMA(1, 0, At, B0); PG8_MMA(1, 1, At, B1); PG8_BAR; PG8_SCHED;
	s_waitcnt lgkmcnt(0)
	v_mfma_f32_16x16x32_bf16 v[140:143], v[104:107], v[204:207], v[140:143]
	v_mfma_f32_16x16x32_bf16 v[136:139], v[112:115], v[204:207], v[136:139]
	v_mfma_f32_16x16x32_bf16 v[132:135], v[104:107], v[212:215], v[132:135]
	v_mfma_f32_16x16x32_bf16 v[128:131], v[112:115], v[212:215], v[128:131]
	v_mfma_f32_16x16x32_bf16 v[100:103], v[104:107], v[220:223], v[100:103]
	v_mfma_f32_16x16x32_bf16 v[96:99], v[112:115], v[220:223], v[96:99]
	v_mfma_f32_16x16x32_bf16 v[76:79], v[104:107], v[228:231], v[76:79]
	v_mfma_f32_16x16x32_bf16 v[72:75], v[112:115], v[228:231], v[72:75]
	v_mfma_f32_16x16x32_bf16 v[140:143], v[108:111], v[208:211], v[140:143]
	v_mfma_f32_16x16x32_bf16 v[136:139], v[116:119], v[208:211], v[136:139]
	v_mfma_f32_16x16x32_bf16 v[132:135], v[108:111], v[216:219], v[132:135]
	v_mfma_f32_16x16x32_bf16 v[128:131], v[116:119], v[216:219], v[128:131]
	v_mfma_f32_16x16x32_bf16 v[100:103], v[108:111], v[224:227], v[100:103]
	v_mfma_f32_16x16x32_bf16 v[96:99], v[116:119], v[224:227], v[96:99]
	v_mfma_f32_16x16x32_bf16 v[76:79], v[108:111], v[232:235], v[76:79]
	v_mfma_f32_16x16x32_bf16 v[72:75], v[116:119], v[232:235], v[72:75]
	v_mfma_f32_16x16x32_bf16 v[124:127], v[176:179], v[204:207], v[124:127]
	v_mfma_f32_16x16x32_bf16 v[120:123], v[196:199], v[204:207], v[120:123]
	v_mfma_f32_16x16x32_bf16 v[92:95], v[176:179], v[212:215], v[92:95]
	v_mfma_f32_16x16x32_bf16 v[88:91], v[196:199], v[212:215], v[88:91]
	v_mfma_f32_16x16x32_bf16 v[84:87], v[176:179], v[220:223], v[84:87]
	v_mfma_f32_16x16x32_bf16 v[80:83], v[196:199], v[220:223], v[80:83]
	v_mfma_f32_16x16x32_bf16 v[68:71], v[176:179], v[228:231], v[68:71]
	v_mfma_f32_16x16x32_bf16 v[64:67], v[196:199], v[228:231], v[64:67]
	v_mfma_f32_16x16x32_bf16 v[124:127], v[192:195], v[208:211], v[124:127]
	v_mfma_f32_16x16x32_bf16 v[120:123], v[200:203], v[208:211], v[120:123]
	v_mfma_f32_16x16x32_bf16 v[92:95], v[192:195], v[216:219], v[92:95]
	v_mfma_f32_16x16x32_bf16 v[88:91], v[200:203], v[216:219], v[88:91]
	v_mfma_f32_16x16x32_bf16 v[84:87], v[192:195], v[224:227], v[84:87]
	v_mfma_f32_16x16x32_bf16 v[80:83], v[200:203], v[224:227], v[80:83]
	v_mfma_f32_16x16x32_bf16 v[68:71], v[192:195], v[232:235], v[68:71]
	v_mfma_f32_16x16x32_bf16 v[64:67], v[200:203], v[232:235], v[64:67]
	s_barrier
	s_add_i32 s50, s50, s2
	v_lshl_add_u64 v[170:171], s[30:31], 0, v[144:145]
	s_mov_b32 m0, s50
	ds_read_b128 v[204:207], v174 offset:16384
	ds_read_b128 v[208:211], v174 offset:17408
	ds_read_b128 v[212:215], v174 offset:18432
	ds_read_b128 v[216:219], v174 offset:19456
	ds_read_b128 v[220:223], v174 offset:20480
	ds_read_b128 v[224:227], v174 offset:21504
	ds_read_b128 v[228:231], v174 offset:22528
	ds_read_b128 v[232:235], v174 offset:23552
	global_load_lds_dwordx4 v[170:171], off
	s_add_i32 m0, s50, 0x2000
	s_add_u32 s50, s30, 0x200000
	v_lshl_add_u64 v[180:181], s[30:31], 0, v[160:161]
	s_addc_u32 s51, s31, 0
	s_add_i32 s52, s52, s2
	global_load_lds_dwordx4 v[180:181], off
	v_lshl_add_u64 v[236:237], s[50:51], 0, v[144:145]
	s_mov_b32 m0, s52
	v_lshl_add_u64 v[238:239], s[34:35], 0, v[162:163]
	global_load_lds_dwordx4 v[236:237], off
	v_lshl_add_u64 v[236:237], s[50:51], 0, v[160:161]
	s_add_i32 m0, s52, 0x2000
	s_nop 0
	global_load_lds_dwordx4 v[236:237], off
	v_lshl_add_u64 v[236:237], s[34:35], 0, v[164:165]
	s_mov_b32 m0, s3
	s_nop 0
	global_load_lds_dwordx4 v[236:237], off
	s_mov_b32 m0, s4
	s_nop 0
	global_load_lds_dwordx4 v[238:239], off
	s_waitcnt vmcnt(8)
	s_waitcnt lgkmcnt(0)
	s_barrier
	s_waitcnt lgkmcnt(0)
	v_mfma_f32_16x16x32_bf16 v[60:63], v[104:107], v[204:207], v[60:63]
	v_mfma_f32_16x16x32_bf16 v[56:59], v[112:115], v[204:207], v[56:59]
	v_mfma_f32_16x16x32_bf16 v[48:51], v[104:107], v[212:215], v[48:51]
	v_mfma_f32_16x16x32_bf16 v[40:43], v[112:115], v[212:215], v[40:43]
	v_mfma_f32_16x16x32_bf16 v[32:35], v[104:107], v[220:223], v[32:35]
	v_mfma_f32_16x16x32_bf16 v[24:27], v[112:115], v[220:223], v[24:27]
	v_mfma_f32_16x16x32_bf16 v[16:19], v[104:107], v[228:231], v[16:19]
	v_mfma_f32_16x16x32_bf16 v[8:11], v[112:115], v[228:231], v[8:11]
	v_mfma_f32_16x16x32_bf16 v[60:63], v[108:111], v[208:211], v[60:63]
	v_mfma_f32_16x16x32_bf16 v[56:59], v[116:119], v[208:211], v[56:59]
	v_mfma_f32_16x16x32_bf16 v[48:51], v[108:111], v[216:219], v[48:51]
	v_mfma_f32_16x16x32_bf16 v[40:43], v[116:119], v[216:219], v[40:43]
	v_mfma_f32_16x16x32_bf16 v[32:35], v[108:111], v[224:227], v[32:35]
	v_mfma_f32_16x16x32_bf16 v[24:27], v[116:119], v[224:227], v[24:27]
	v_mfma_f32_16x16x32_bf16 v[16:19], v[108:111], v[232:235], v[16:19]
	v_mfma_f32_16x16x32_bf16 v[8:11], v[116:119], v[232:235], v[8:11]
	v_mfma_f32_16x16x32_bf16 v[52:55], v[176:179], v[204:207], v[52:55]
	v_mfma_f32_16x16x32_bf16 v[44:47], v[196:199], v[204:207], v[44:47]
	v_mfma_f32_16x16x32_bf16 v[36:39], v[176:179], v[212:215], v[36:39]
	v_mfma_f32_16x16x32_bf16 v[28:31], v[196:199], v[212:215], v[28:31]
	v_mfma_f32_16x16x32_bf16 v[20:23], v[176:179], v[220:223], v[20:23]
	v_mfma_f32_16x16x32_bf16 v[12:15], v[196:199], v[220:223], v[12:15]
	v_mfma_f32_16x16x32_bf16 v[4:7], v[176:179], v[228:231], v[4:7]
	v_mfma_f32_16x16x32_bf16 v[0:3], v[196:199], v[228:231], v[0:3]
	v_mfma_f32_16x16x32_bf16 v[52:55], v[192:195], v[208:211], v[52:55]
	v_mfma_f32_16x16x32_bf16 v[44:47], v[200:203], v[208:211], v[44:47]
	v_mfma_f32_16x16x32_bf16 v[36:39], v[192:195], v[216:219], v[36:39]
	v_mfma_f32_16x16x32_bf16 v[28:31], v[200:203], v[216:219], v[28:31]
	v_mfma_f32_16x16x32_bf16 v[20:23], v[192:195], v[224:227], v[20:23]
	v_mfma_f32_16x16x32_bf16 v[12:15], v[200:203], v[224:227], v[12:15]
	v_mfma_f32_16x16x32_bf16 v[4:7], v[192:195], v[232:235], v[4:7]
	v_mfma_f32_16x16x32_bf16 v[0:3], v[200:203], v[232:235], v[0:3]
	s_barrier
; #define PG8_STAGE(bufoff, gbase, voff) do { _Pragma("unroll") for (int _i = 0; _i < 2; ++_i) \
;         __builtin_amdgcn_global_load_lds((const unsigned*)((const char*)(gbase) + (voff)[_i]), (LAS unsigned*)(lds + (bufoff) + ldsw + _i * 8192), 16, 0, 0); } while (0)
; #define PG8_LDA(dst, b, h) do { _Pragma("unroll") for (int m = 0; m < 4; ++m) _Pragma("unroll") for (int k = 0; k < 2; ++k) dst[m][k] = *(const LAS bf16x8*)(lds + PG8_SA(b, h) + aoff + m * 2048 + k * 1024); } while (0)
; #define PG8_LDB(dst, b, h) do { _Pragma("unroll") for (int n = 0; n < 2; ++n) _Pragma("unroll") for (int k = 0; k < 2; ++k) dst[n][k] = *(const LAS bf16x8*)(lds + PG8_SB(b, h) + boff + n * 2048 + k * 1024); } while (0)
; #define PG8_MMA(ai, bj, At, Bt) do { __builtin_amdgcn_s_setprio(1); _Pragma("unroll") for (int m = 0; m < 4; ++m) _Pragma("unroll") for (int n = 0; n < 2; ++n) _Pragma("unroll") for (int k = 0; k < 2; ++k) \
;         acc[ai][bj][m][n] = __builtin_amdgcn_mfma_f32_16x16x32_bf16(Bt[n][k], At[m][k], acc[ai][bj][m][n], 0, 0, 0); __builtin_amdgcn_s_setprio(0); } while (0)
; #define PG8_WAIT_V(n) asm volatile("s_waitcnt vmcnt(" #n ")" ::: "memory")
; #define PG8_WAIT_L(n) asm volatile("s_waitcnt lgkmcnt(" #n ")" ::: "memory")
; #define PG8_BAR __builtin_amdgcn_s_barrier()
; #define PG8_SCHED __builtin_amdgcn_sched_barrier(0)
; template <class Epi, class Map>
; __device__ __forceinline__ void gemm_phase(LAS unsigned char* lds, const Gemm g, const Sched<Map>& S, const Epi& E) {
;     ...
;             PG8_LDB(B0, 1, 0); PG8_LDB(B1, 1, 1); PG8_SCHED; PG8_LDA(At, 1, 0); PG8_STAGE(PG8_SA(0, 1), a2 + hstepA, voffA);
;             PG8_WAIT_V(8); PG8_WAIT_L(0); PG8_BAR; PG8_MMA(0, 0, At, B0); PG8_MMA(0, 1, At, B1); PG8_BAR; PG8_SCHED;
;             PG8_LDA(At, 1, 1); PG8_STAGE(PG8_SB(1, 0), b3, voffB); PG8_STAGE(PG8_SB(1, 1), b3 + hstepB, voffB); PG8_STAGE(PG8_SA(1, 0), a3, voffA);
;             PG8_WAIT_V(8); PG8_WAIT_L(0); PG8_BAR; PG8_MMA(1, 0, At, B0); PG8_MMA(1, 1, At, B1); PG8_BAR; PG8_SCHED;
	s_add_i32 s50, 0, 0x18000
	s_add_i32 s51, 0, 0x1c000
	v_add_u32_e32 v116, s50, v173
	v_add_u32_e32 v175, s51, v173
	ds_read_b128 v[104:107], v116
	ds_read_b128 v[108:111], v116 offset:1024
	ds_read_b128 v[112:115], v116 offset:2048
	ds_read_b128 v[116:119], v116 offset:3072
	ds_read_b128 v[176:179], v175
	ds_read_b128 v[192:195], v175 offset:1024
	ds_read_b128 v[196:199], v175 offset:2048
	ds_read_b128 v[200:203], v175 offset:3072
	s_add_u32 s34, s34, 0x200000
	s_addc_u32 s35, s35, 0
	s_mov_b32 m0, s5
	v_lshl_add_u64 v[240:241], s[34:35], 0, v[164:165]
	ds_read_b128 v[204:207], v174 offset:32768
	ds_read_b128 v[208:211], v174 offset:33792
	ds_read_b128 v[212:215], v174 offset:34816
	ds_read_b128 v[216:219], v174 offset:35840
	ds_read_b128 v[220:223], v174 offset:36864
	ds_read_b128 v[224:227], v174 offset:37888
	ds_read_b128 v[228:231], v174 offset:38912
	ds_read_b128 v[232:235], v174 offset:39936
	global_load_lds_dwordx4 v[240:241], off
	v_lshl_add_u64 v[240:241], s[34:35], 0, v[162:163]
	s_mov_b32 m0, s6
	s_nop 0
	global_load_lds_dwordx4 v[240:241], off
	s_waitcnt vmcnt(8)
	s_waitcnt lgkmcnt(0)
	s_barrier
	s_waitcnt lgkmcnt(0)
	v_mfma_f32_16x16x32_bf16 v[140:143], v[104:107], v[204:207], v[140:143]
	v_mfma_f32_16x16x32_bf16 v[136:139], v[112:115], v[204:207], v[136:139]
	v_mfma_f32_16x16x32_bf16 v[132:135], v[104:107], v[212:215], v[132:135]
	v_mfma_f32_16x16x32_bf16 v[128:131], v[112:115], v[212:215], v[128:131]
	v_mfma_f32_16x16x32_bf16 v[100:103], v[104:107], v[220:223], v[100:103]
	v_mfma_f32_16x16x32_bf16 v[96:99], v[112:115], v[220:223], v[96:99]
	v_mfma_f32_16x16x32_bf16 v[76:79], v[104:107], v[228:231], v[76:79]
	v_mfma_f32_16x16x32_bf16 v[72:75], v[112:115], v[228:231], v[72:75]
	v_mfma_f32_16x16x32_bf16 v[140:143], v[108:111], v[208:211], v[140:143]
	v_mfma_f32_16x16x32_bf16 v[136:139], v[116:119], v[208:211], v[136:139]
	v_mfma_f32_16x16x32_bf16 v[132:135], v[108:111], v[216:219], v[132:135]
	v_mfma_f32_16x16x32_bf16 v[128:131], v[116:119], v[216:219], v[128:131]
	v_mfma_f32_16x16x32_bf16 v[100:103], v[108:111], v[224:227], v[100:103]
	v_mfma_f32_16x16x32_bf16 v[96:99], v[116:119], v[224:227], v[96:99]
	v_mfma_f32_16x16x32_bf16 v[76:79], v[108:111], v[232:235], v[76:79]
	v_mfma_f32_16x16x32_bf16 v[72:75], v[116:119], v[232:235], v[72:75]
	v_mfma_f32_16x16x32_bf16 v[124:127], v[176:179], v[204:207], v[124:127]
	v_mfma_f32_16x16x32_bf16 v[120:123], v[196:199], v[204:207], v[120:123]
	v_mfma_f32_16x16x32_bf16 v[92:95], v[176:179], v[212:215], v[92:95]
	v_mfma_f32_16x16x32_bf16 v[88:91], v[196:199], v[212:215], v[88:91]
	v_mfma_f32_16x16x32_bf16 v[84:87], v[176:179], v[220:223], v[84:87]
	v_mfma_f32_16x16x32_bf16 v[80:83], v[196:199], v[220:223], v[80:83]
	v_mfma_f32_16x16x32_bf16 v[68:71], v[176:179], v[228:231], v[68:71]
	v_mfma_f32_16x16x32_bf16 v[64:67], v[196:199], v[228:231], v[64:67]
	v_mfma_f32_16x16x32_bf16 v[124:127], v[192:195], v[208:211], v[124:127]
	v_mfma_f32_16x16x32_bf16 v[120:123], v[200:203], v[208:211], v[120:123]
	v_mfma_f32_16x16x32_bf16 v[92:95], v[192:195], v[216:219], v[92:95]
	v_mfma_f32_16x16x32_bf16 v[88:91], v[200:203], v[216:219], v[88:91]
	v_mfma_f32_16x16x32_bf16 v[84:87], v[192:195], v[224:227], v[84:87]
	v_mfma_f32_16x16x32_bf16 v[80:83], v[200:203], v[224:227], v[80:83]
	v_mfma_f32_16x16x32_bf16 v[68:71], v[192:195], v[232:235], v[68:71]
	v_mfma_f32_16x16x32_bf16 v[64:67], v[200:203], v[232:235], v[64:67]
	s_barrier
	s_add_i32 s34, s50, s2
	v_lshl_add_u64 v[170:171], v[170:171], 0, s[82:83]
	s_mov_b32 m0, s34
	ds_read_b128 v[204:207], v174 offset:49152
	ds_read_b128 v[208:211], v174 offset:50176
	ds_read_b128 v[212:215], v174 offset:51200
	ds_read_b128 v[216:219], v174 offset:52224
	ds_read_b128 v[220:223], v174 offset:53248
	ds_read_b128 v[224:227], v174 offset:54272
	ds_read_b128 v[228:231], v174 offset:55296
	ds_read_b128 v[232:235], v174 offset:56320
	global_load_lds_dwordx4 v[170:171], off
	s_add_i32 m0, s34, 0x2000
	s_add_u32 s30, s30, 0x200080
	v_lshl_add_u64 v[170:171], v[180:181], 0, s[82:83]
	s_addc_u32 s31, s31, 0
	s_add_i32 s34, s51, s2
	global_load_lds_dwordx4 v[170:171], off
	v_lshl_add_u64 v[170:171], s[30:31], 0, v[144:145]
	s_mov_b32 m0, s34
	s_nop 0
	global_load_lds_dwordx4 v[170:171], off
	v_lshl_add_u64 v[170:171], s[30:31], 0, v[160:161]
	s_add_i32 m0, s34, 0x2000
	s_nop 0
	global_load_lds_dwordx4 v[170:171], off
	v_lshl_add_u64 v[170:171], v[236:237], 0, s[82:83]
	s_mov_b32 m0, s9
	s_nop 0
	global_load_lds_dwordx4 v[170:171], off
	v_lshl_add_u64 v[170:171], v[238:239], 0, s[82:83]
	s_mov_b32 m0, s10
	s_nop 0
	global_load_lds_dwordx4 v[170:171], off
	s_waitcnt vmcnt(8)
	s_waitcnt lgkmcnt(0)
	s_barrier
; __device__ __forceinline__ unsigned cvt_pk_bf16(float lo, float hi) { unsigned r; asm volatile("v_cvt_pk_bf16_f32 %0, %1, %2" : "=v"(r) : "v"(lo), "v"(hi)); return r; }
; #define PG8_MMA(ai, bj, At, Bt) do { __builtin_amdgcn_s_setprio(1); _Pragma("unroll") for (int m = 0; m < 4; ++m) _Pragma("unroll") for (int n = 0; n < 2; ++n) _Pragma("unroll") for (int k = 0; k < 2; ++k) \
;         acc[ai][bj][m][n] = __builtin_amdgcn_mfma_f32_16x16x32_bf16(Bt[n][k], At[m][k], acc[ai][bj][m][n], 0, 0, 0); __builtin_amdgcn_s_setprio(0); } while (0)
; #define PG8_WAIT_V(n) asm volatile("s_waitcnt vmcnt(" #n ")" ::: "memory")
; #define PG8_WAIT_L(n) asm volatile("s_waitcnt lgkmcnt(" #n ")" ::: "memory")
; #define PG8_BAR __builtin_amdgcn_s_barrier()
; #define PG8_SCHED __builtin_amdgcn_sched_barrier(0)
; template <class Epi, class Map>
; __device__ __forceinline__ void gemm_phase(LAS unsigned char* lds, const Gemm g, const Sched<Map>& S, const Epi& E) {
;     ...
;             PG8_WAIT_V(8); PG8_WAIT_L(0); PG8_BAR; PG8_MMA(1, 0, At, B0); PG8_MMA(1, 1, At, B1); PG8_BAR; PG8_SCHED;
;         }
;         if (wr == 0) PG8_BAR;
;     __device__ __forceinline__ void operator()(const Acc& acc, const Unit& u, int wr, int wc, int fr, int fq) const {
;         asm volatile("" : "+v"(fr), "+v"(fq));
;         const int col0 = u.pn * BM + wc * 32 + 8 * fq;
;         const float* gp = gate + (size_t)(u.pm >> 6) * gate_bstride + col0;
;         f32x4 gv[2][2];
; #pragma unroll
;         for (int bj = 0; bj < 2; ++bj) { gv[bj][0] = *(const f32x4*)(gp + bj * HALF); gv[bj][1] = *(const f32x4*)(gp + bj * HALF + 4); }
;         bf16_t* base = Y + (size_t)(u.pm * BM + wr * 64 + fr) * D + col0;
; #pragma unroll
;         for (int ai = 0; ai < 2; ++ai)
; #pragma unroll
;             for (int m = 0; m < 4; ++m) { bf16_t* rowp = base + (size_t)(ai * HALF + m * 16) * D;
; #pragma unroll
;                 for (int bj = 0; bj < 2; ++bj) { const f32x4 v0 = acc[ai][bj][m][0] * gv[bj][0], v1 = acc[ai][bj][m][1] * gv[bj][1];
;                     u32x4 w; w.x = cvt_pk_bf16(v0[0], v0[1]); w.y = cvt_pk_bf16(v0[2], v0[3]); w.z = cvt_pk_bf16(v1[0], v1[1]); w.w = cvt_pk_bf16(v1[2], v1[3]);
;                     *(u32x4*)(rowp + bj * HALF) = w; } }
	s_waitcnt lgkmcnt(0)
	v_mfma_f32_16x16x32_bf16 v[60:63], v[104:107], v[204:207], v[60:63]
	v_mfma_f32_16x16x32_bf16 v[56:59], v[112:115], v[204:207], v[56:59]
	v_mfma_f32_16x16x32_bf16 v[48:51], v[104:107], v[212:215], v[48:51]
	v_mfma_f32_16x16x32_bf16 v[40:43], v[112:115], v[212:215], v[40:43]
	v_mfma_f32_16x16x32_bf16 v[32:35], v[104:107], v[220:223], v[32:35]
	v_mfma_f32_16x16x32_bf16 v[24:27], v[112:115], v[220:223], v[24:27]
	v_mfma_f32_16x16x32_bf16 v[16:19], v[104:107], v[228:231], v[16:19]
	v_mfma_f32_16x16x32_bf16 v[8:11], v[112:115], v[228:231], v[8:11]
	v_mfma_f32_16x16x32_bf16 v[60:63], v[108:111], v[208:211], v[60:63]
	v_mfma_f32_16x16x32_bf16 v[56:59], v[116:119], v[208:211], v[56:59]
	v_mfma_f32_16x16x32_bf16 v[48:51], v[108:111], v[216:219], v[48:51]
	v_mfma_f32_16x16x32_bf16 v[40:43], v[116:119], v[216:219], v[40:43]
	v_mfma_f32_16x16x32_bf16 v[32:35], v[108:111], v[224:227], v[32:35]
	v_mfma_f32_16x16x32_bf16 v[24:27], v[116:119], v[224:227], v[24:27]
	v_mfma_f32_16x16x32_bf16 v[16:19], v[108:111], v[232:235], v[16:19]
	v_mfma_f32_16x16x32_bf16 v[8:11], v[116:119], v[232:235], v[8:11]
	v_mfma_f32_16x16x32_bf16 v[52:55], v[176:179], v[204:207], v[52:55]
	v_mfma_f32_16x16x32_bf16 v[44:47], v[196:199], v[204:207], v[44:47]
	v_mfma_f32_16x16x32_bf16 v[36:39], v[176:179], v[212:215], v[36:39]
	v_mfma_f32_16x16x32_bf16 v[28:31], v[196:199], v[212:215], v[28:31]
	v_mfma_f32_16x16x32_bf16 v[20:23], v[176:179], v[220:223], v[20:23]
	v_mfma_f32_16x16x32_bf16 v[12:15], v[196:199], v[220:223], v[12:15]
	v_mfma_f32_16x16x32_bf16 v[4:7], v[176:179], v[228:231], v[4:7]
	v_mfma_f32_16x16x32_bf16 v[0:3], v[196:199], v[228:231], v[0:3]
	v_mfma_f32_16x16x32_bf16 v[52:55], v[192:195], v[208:211], v[52:55]
	v_mfma_f32_16x16x32_bf16 v[44:47], v[200:203], v[208:211], v[44:47]
	v_mfma_f32_16x16x32_bf16 v[36:39], v[192:195], v[216:219], v[36:39]
	v_mfma_f32_16x16x32_bf16 v[28:31], v[200:203], v[216:219], v[28:31]
	v_mfma_f32_16x16x32_bf16 v[20:23], v[192:195], v[224:227], v[20:23]
	v_mfma_f32_16x16x32_bf16 v[12:15], v[200:203], v[224:227], v[12:15]
	v_mfma_f32_16x16x32_bf16 v[4:7], v[192:195], v[232:235], v[4:7]
	v_mfma_f32_16x16x32_bf16 v[0:3], v[200:203], v[232:235], v[0:3]
	s_barrier
	s_add_i32 s49, s49, 2
	s_add_u32 s28, s28, 0x100
	s_addc_u32 s29, s29, 0
	s_add_u32 s47, s47, 0x100
	s_addc_u32 s48, s48, 0
	s_cmpk_gt_u32 s49, 0x7d
	s_cbranch_scc0 .LBB0_1161
	s_and_b64 vcc, exec, s[18:19]
	s_cbranch_vccz .LBB0_1164
.LBB0_1164:
	s_lshl_b32 s28, s36, 8
	v_mov_b32_e32 v175, v159
	v_mov_b32_e32 v104, v172
	s_or_b32 s28, s28, s8
	s_nop 0
	v_lshl_add_u32 v170, v104, 3, s28
	s_ashr_i32 s28, s33, 6
	s_mul_hi_i32 s29, s28, 0xc000
	s_mul_i32 s28, s28, 0xc000
	s_add_u32 s28, s0, s28
	s_addc_u32 s29, s1, s29
	v_ashrrev_i32_e32 v171, 31, v170
	v_lshl_add_u64 v[108:109], v[170:171], 2, s[28:29]
	global_load_dwordx4 v[112:115], v[108:109], off offset:16
	global_load_dwordx4 v[116:119], v[108:109], off
	global_load_dwordx4 v[104:107], v[108:109], off offset:528
	s_nop 0
	global_load_dwordx4 v[108:111], v[108:109], off offset:512
	s_lshl_b32 s28, s33, 8
	s_add_i32 s28, s28, s7
	v_add_u32_e32 v176, s28, v175
	v_ashrrev_i32_e32 v177, 31, v176
	v_readlane_b32 s28, v245, 21
	v_lshlrev_b64 v[176:177], 12, v[176:177]
	v_readlane_b32 s29, v245, 22
	s_waitcnt vmcnt(0)
	v_pk_mul_f32 v[142:143], v[142:143], v[118:119]
	v_lshl_add_u64 v[176:177], s[28:29], 0, v[176:177]
	v_lshl_add_u64 v[170:171], v[170:171], 1, v[176:177]
	v_pk_mul_f32 v[140:141], v[140:141], v[116:117]
	v_pk_mul_f32 v[176:177], v[138:139], v[114:115]
	v_pk_mul_f32 v[138:139], v[136:137], v[112:113]
	v_cvt_pk_bf16_f32 v136, v140, v141
	v_cvt_pk_bf16_f32 v137, v142, v143
	v_pk_mul_f32 v[126:127], v[126:127], v[110:111]
	v_cvt_pk_bf16_f32 v138, v138, v139
	v_cvt_pk_bf16_f32 v139, v176, v177
	global_store_dwordx4 v[170:171], v[136:139], off
	v_pk_mul_f32 v[124:125], v[124:125], v[108:109]
	s_mov_b32 s28, 0x10000
	v_pk_mul_f32 v[136:137], v[122:123], v[106:107]
	v_pk_mul_f32 v[122:123], v[120:121], v[104:105]
	v_cvt_pk_bf16_f32 v120, v124, v125
	v_cvt_pk_bf16_f32 v121, v126, v127
	v_pk_mul_f32 v[124:125], v[130:131], v[114:115]
	v_cvt_pk_bf16_f32 v122, v122, v123
	v_cvt_pk_bf16_f32 v123, v136, v137
	global_store_dwordx4 v[170:171], v[120:123], off offset:256
	v_pk_mul_f32 v[126:127], v[128:129], v[112:113]
	v_pk_mul_f32 v[94:95], v[94:95], v[110:111]
	v_pk_mul_f32 v[122:123], v[134:135], v[118:119]
	v_pk_mul_f32 v[120:121], v[132:133], v[116:117]
	v_pk_mul_f32 v[92:93], v[92:93], v[108:109]
	v_cvt_pk_bf16_f32 v120, v120, v121
	v_cvt_pk_bf16_f32 v121, v122, v123
	v_cvt_pk_bf16_f32 v122, v126, v127
	v_cvt_pk_bf16_f32 v123, v124, v125
	v_add_co_u32_e32 v124, vcc, s28, v170
	s_mov_b32 s28, 0x20000
	s_nop 0
	v_addc_co_u32_e32 v125, vcc, 0, v171, vcc
	global_store_dwordx4 v[124:125], v[120:123], off
	v_pk_mul_f32 v[86:87], v[86:87], v[110:111]
	v_pk_mul_f32 v[84:85], v[84:85], v[108:109]
	v_pk_mul_f32 v[120:121], v[90:91], v[106:107]
	v_pk_mul_f32 v[90:91], v[88:89], v[104:105]
	v_cvt_pk_bf16_f32 v88, v92, v93
	v_cvt_pk_bf16_f32 v89, v94, v95
	v_pk_mul_f32 v[92:93], v[98:99], v[114:115]
	v_cvt_pk_bf16_f32 v90, v90, v91
	v_cvt_pk_bf16_f32 v91, v120, v121
	global_store_dwordx4 v[124:125], v[88:91], off offset:256
	s_cmp_lg_u64 s[18:19], 0
	s_cbranch_scc0 .Llate_align_11
	s_barrier
; __device__ __forceinline__ unsigned cvt_pk_bf16(float lo, float hi) { unsigned r; asm volatile("v_cvt_pk_bf16_f32 %0, %1, %2" : "=v"(r) : "v"(lo), "v"(hi)); return r; }
; #define PG8_BAR __builtin_amdgcn_s_barrier()
; template <class Epi, class Map>
; __device__ __forceinline__ void gemm_phase(LAS unsigned char* lds, const Gemm g, const Sched<Map>& S, const Epi& E) {
;     ...
;         if (!has_next) break;
; #pragma unroll
;         for (int a = 0; a < 2; ++a)
; #pragma unroll
;             for (int b = 0; b < 2; ++b)
; #pragma unroll
;                 for (int m = 0; m < 4; ++m)
; #pragma unroll
;                     for (int n = 0; n < 2; ++n) acc[a][b][m][n] = (f32x4){0.f, 0.f, 0.f, 0.f};
;         cur = nxt; cA = nA; cB = nB; ++ui;
;         if (wr == 1) PG8_BAR;
;     __device__ __forceinline__ void operator()(const Acc& acc, const Unit& u, int wr, int wc, int fr, int fq) const {
;         asm volatile("" : "+v"(fr), "+v"(fq));
;         const int col0 = u.pn * BM + wc * 32 + 8 * fq;
;         const float* gp = gate + (size_t)(u.pm >> 6) * gate_bstride + col0;
;         f32x4 gv[2][2];
; #pragma unroll
;         for (int bj = 0; bj < 2; ++bj) { gv[bj][0] = *(const f32x4*)(gp + bj * HALF); gv[bj][1] = *(const f32x4*)(gp + bj * HALF + 4); }
;         bf16_t* base = Y + (size_t)(u.pm * BM + wr * 64 + fr) * D + col0;
; #pragma unroll
;         for (int ai = 0; ai < 2; ++ai)
; #pragma unroll
;             for (int m = 0; m < 4; ++m) { bf16_t* rowp = base + (size_t)(ai * HALF + m * 16) * D;
; #pragma unroll
;                 for (int bj = 0; bj < 2; ++bj) { const f32x4 v0 = acc[ai][bj][m][0] * gv[bj][0], v1 = acc[ai][bj][m][1] * gv[bj][1];
;                     u32x4 w; w.x = cvt_pk_bf16(v0[0], v0[1]); w.y = cvt_pk_bf16(v0[2], v0[3]); w.z = cvt_pk_bf16(v1[0], v1[1]); w.w = cvt_pk_bf16(v1[2], v1[3]);
;                     *(u32x4*)(rowp + bj * HALF) = w; } }
.Llate_align_11:
	v_pk_mul_f32 v[94:95], v[96:97], v[112:113]
	v_pk_mul_f32 v[76:77], v[76:77], v[116:117]
	v_pk_mul_f32 v[90:91], v[102:103], v[118:119]
	v_pk_mul_f32 v[88:89], v[100:101], v[116:117]
	v_pk_mul_f32 v[78:79], v[78:79], v[118:119]
	v_cvt_pk_bf16_f32 v88, v88, v89
	v_cvt_pk_bf16_f32 v89, v90, v91
	v_cvt_pk_bf16_f32 v90, v94, v95
	v_cvt_pk_bf16_f32 v91, v92, v93
	v_add_co_u32_e32 v92, vcc, s28, v170
	s_mov_b32 s28, 0x30000
	s_nop 0
	v_addc_co_u32_e32 v93, vcc, 0, v171, vcc
	global_store_dwordx4 v[92:93], v[88:91], off
	v_pk_mul_f32 v[70:71], v[70:71], v[110:111]
	v_pk_mul_f32 v[68:69], v[68:69], v[108:109]
	v_pk_mul_f32 v[88:89], v[82:83], v[106:107]
	v_pk_mul_f32 v[82:83], v[80:81], v[104:105]
	v_cvt_pk_bf16_f32 v80, v84, v85
	v_cvt_pk_bf16_f32 v81, v86, v87
	v_pk_mul_f32 v[60:61], v[60:61], v[116:117]
	v_cvt_pk_bf16_f32 v82, v82, v83
	v_cvt_pk_bf16_f32 v83, v88, v89
	global_store_dwordx4 v[92:93], v[80:83], off offset:256
	v_pk_mul_f32 v[62:63], v[62:63], v[118:119]
	v_pk_mul_f32 v[54:55], v[54:55], v[110:111]
	v_pk_mul_f32 v[80:81], v[74:75], v[114:115]
	v_pk_mul_f32 v[74:75], v[72:73], v[112:113]
	v_cvt_pk_bf16_f32 v72, v76, v77
	v_add_co_u32_e32 v76, vcc, s28, v170
	v_cvt_pk_bf16_f32 v73, v78, v79
	v_cvt_pk_bf16_f32 v74, v74, v75
	v_cvt_pk_bf16_f32 v75, v80, v81
	s_mov_b32 s28, 0x80000
	s_nop 0
	v_addc_co_u32_e32 v77, vcc, 0, v171, vcc
	global_store_dwordx4 v[76:77], v[72:75], off
	v_pk_mul_f32 v[52:53], v[52:53], v[108:109]
	v_pk_mul_f32 v[38:39], v[38:39], v[110:111]
	v_pk_mul_f32 v[72:73], v[66:67], v[106:107]
	v_pk_mul_f32 v[66:67], v[64:65], v[104:105]
	v_cvt_pk_bf16_f32 v64, v68, v69
	v_cvt_pk_bf16_f32 v65, v70, v71
	v_pk_mul_f32 v[36:37], v[36:37], v[108:109]
	v_cvt_pk_bf16_f32 v66, v66, v67
	v_cvt_pk_bf16_f32 v67, v72, v73
	global_store_dwordx4 v[76:77], v[64:67], off offset:256
	v_pk_mul_f32 v[22:23], v[22:23], v[110:111]
	v_pk_mul_f32 v[20:21], v[20:21], v[108:109]
	v_pk_mul_f32 v[64:65], v[58:59], v[114:115]
	v_pk_mul_f32 v[58:59], v[56:57], v[112:113]
	v_cvt_pk_bf16_f32 v56, v60, v61
	v_add_co_u32_e32 v60, vcc, s28, v170
	v_cvt_pk_bf16_f32 v57, v62, v63
	v_cvt_pk_bf16_f32 v58, v58, v59
	v_cvt_pk_bf16_f32 v59, v64, v65
	s_mov_b32 s28, 0x90000
	s_nop 0
	v_addc_co_u32_e32 v61, vcc, 0, v171, vcc
	global_store_dwordx4 v[60:61], v[56:59], off
	v_pk_mul_f32 v[6:7], v[6:7], v[110:111]
	v_pk_mul_f32 v[4:5], v[4:5], v[108:109]
	v_pk_mul_f32 v[56:57], v[46:47], v[106:107]
	v_pk_mul_f32 v[46:47], v[44:45], v[104:105]
	v_cvt_pk_bf16_f32 v44, v52, v53
	v_cvt_pk_bf16_f32 v45, v54, v55
	s_nop 0
	v_cvt_pk_bf16_f32 v46, v46, v47
	v_cvt_pk_bf16_f32 v47, v56, v57
	global_store_dwordx4 v[60:61], v[44:47], off offset:256
	s_nop 1
	v_pk_mul_f32 v[44:45], v[50:51], v[118:119]
	v_pk_mul_f32 v[46:47], v[48:49], v[116:117]
	v_pk_mul_f32 v[48:49], v[42:43], v[114:115]
	v_pk_mul_f32 v[42:43], v[40:41], v[112:113]
	v_cvt_pk_bf16_f32 v40, v46, v47
	v_cvt_pk_bf16_f32 v41, v44, v45
	v_add_co_u32_e32 v44, vcc, s28, v170
	v_cvt_pk_bf16_f32 v42, v42, v43
	v_cvt_pk_bf16_f32 v43, v48, v49
	s_mov_b32 s28, 0xa0000
	s_nop 0
	v_addc_co_u32_e32 v45, vcc, 0, v171, vcc
	global_store_dwordx4 v[44:45], v[40:43], off
	s_nop 1
	v_pk_mul_f32 v[40:41], v[30:31], v[106:107]
	v_pk_mul_f32 v[30:31], v[28:29], v[104:105]
	v_cvt_pk_bf16_f32 v28, v36, v37
	v_cvt_pk_bf16_f32 v29, v38, v39
	s_nop 0
	v_cvt_pk_bf16_f32 v30, v30, v31
	v_cvt_pk_bf16_f32 v31, v40, v41
	global_store_dwordx4 v[44:45], v[28:31], off offset:256
	s_nop 1
	v_pk_mul_f32 v[28:29], v[34:35], v[118:119]
	v_pk_mul_f32 v[30:31], v[32:33], v[116:117]
	v_pk_mul_f32 v[32:33], v[26:27], v[114:115]
	v_pk_mul_f32 v[26:27], v[24:25], v[112:113]
	v_cvt_pk_bf16_f32 v24, v30, v31
	v_cvt_pk_bf16_f32 v25, v28, v29
	v_add_co_u32_e32 v28, vcc, s28, v170
	v_cvt_pk_bf16_f32 v26, v26, v27
	v_cvt_pk_bf16_f32 v27, v32, v33
	s_mov_b32 s28, 0xb0000
	s_nop 0
	v_addc_co_u32_e32 v29, vcc, 0, v171, vcc
	global_store_dwordx4 v[28:29], v[24:27], off
	s_nop 1
	v_pk_mul_f32 v[24:25], v[14:15], v[106:107]
	v_pk_mul_f32 v[14:15], v[12:13], v[104:105]
	v_cvt_pk_bf16_f32 v12, v20, v21
	v_cvt_pk_bf16_f32 v13, v22, v23
	s_nop 0
	v_cvt_pk_bf16_f32 v14, v14, v15
	v_cvt_pk_bf16_f32 v15, v24, v25
	global_store_dwordx4 v[28:29], v[12:15], off offset:256
	s_nop 1
	v_pk_mul_f32 v[12:13], v[18:19], v[118:119]
	v_pk_mul_f32 v[14:15], v[16:17], v[116:117]
	v_pk_mul_f32 v[16:17], v[10:11], v[114:115]
	v_pk_mul_f32 v[10:11], v[8:9], v[112:113]
	v_cvt_pk_bf16_f32 v8, v14, v15
	v_cvt_pk_bf16_f32 v9, v12, v13
	v_add_co_u32_e32 v12, vcc, s28, v170
	v_cvt_pk_bf16_f32 v10, v10, v11
	v_cvt_pk_bf16_f32 v11, v16, v17
	s_mov_b64 s[28:29], -1
	s_nop 0
	v_addc_co_u32_e32 v13, vcc, 0, v171, vcc
	global_store_dwordx4 v[12:13], v[8:11], off
	s_andn2_b64 vcc, exec, s[40:41]
	s_nop 0
	v_pk_mul_f32 v[8:9], v[2:3], v[106:107]
	v_pk_mul_f32 v[2:3], v[0:1], v[104:105]
	v_cvt_pk_bf16_f32 v0, v4, v5
	v_cvt_pk_bf16_f32 v1, v6, v7
	s_nop 0
	v_cvt_pk_bf16_f32 v2, v2, v3
	v_cvt_pk_bf16_f32 v3, v8, v9
	global_store_dwordx4 v[12:13], v[0:3], off offset:256
	s_cbranch_vccnz .LBB0_1153
	s_andn2_b64 vcc, exec, s[16:17]
	s_cbranch_vccnz .LBB0_1152
	s_barrier
	s_branch .LBB0_1152

; #define PG8_STAGE(bufoff, gbase, voff) do { _Pragma("unroll") for (int _i = 0; _i < 2; ++_i) \
;         __builtin_amdgcn_global_load_lds((const unsigned*)((const char*)(gbase) + (voff)[_i]), (LAS unsigned*)(lds + (bufoff) + ldsw + _i * 8192), 16, 0, 0); } while (0)
; #define PG8_LDA(dst, b, h) do { _Pragma("unroll") for (int m = 0; m < 4; ++m) _Pragma("unroll") for (int k = 0; k < 2; ++k) dst[m][k] = *(const LAS bf16x8*)(lds + PG8_SA(b, h) + aoff + m * 2048 + k * 1024); } while (0)
; #define PG8_LDB(dst, b, h) do { _Pragma("unroll") for (int n = 0; n < 2; ++n) _Pragma("unroll") for (int k = 0; k < 2; ++k) dst[n][k] = *(const LAS bf16x8*)(lds + PG8_SB(b, h) + boff + n * 2048 + k * 1024); } while (0)
; #define PG8_MMA(ai, bj, At, Bt) do { __builtin_amdgcn_s_setprio(1); _Pragma("unroll") for (int m = 0; m < 4; ++m) _Pragma("unroll") for (int n = 0; n < 2; ++n) _Pragma("unroll") for (int k = 0; k < 2; ++k) \
;         acc[ai][bj][m][n] = __builtin_amdgcn_mfma_f32_16x16x32_bf16(Bt[n][k], At[m][k], acc[ai][bj][m][n], 0, 0, 0); __builtin_amdgcn_s_setprio(0); } while (0)
; #define PG8_WAIT_V(n) asm volatile("s_waitcnt vmcnt(" #n ")" ::: "memory")
; #define PG8_WAIT_L(n) asm volatile("s_waitcnt lgkmcnt(" #n ")" ::: "memory")
; #define PG8_BAR __builtin_amdgcn_s_barrier()
; template <class Epi, class Map>
; __device__ __forceinline__ void gemm_phase(LAS unsigned char* lds, const Gemm g, const Sched<Map>& S, const Epi& E) {
;     ...
;         for (int t = 0; t < nt; t += 2) {
;             const bool last = (t == nt - 2);
;             const char* a1 = cA + (size_t)(t + 1) * kstep;
;             const char* a2 = last ? nA : cA + (size_t)(t + 2) * kstep; const char* b2 = last ? nB : cB + (size_t)(t + 2) * kstep;
;             const char* a3 = a2 + kstep; const char* b3 = b2 + kstep;
;             PG8_LDB(B0, 0, 0); PG8_LDB(B1, 0, 1); PG8_SCHED; PG8_LDA(At, 0, 0); PG8_STAGE(PG8_SA(1, 1), a1 + hstepA, voffA);
;             PG8_WAIT_V(8); PG8_WAIT_L(0); PG8_BAR; PG8_MMA(0, 0, At, B0); PG8_MMA(0, 1, At, B1); PG8_BAR; PG8_SCHED;
;     ...
;         for (int a = 0; a < 2; ++a)
; #pragma unroll
;             for (int b = 0; b < 2; ++b)
; #pragma unroll
;                 for (int m = 0; m < 4; ++m)
; #pragma unroll
;                     for (int n = 0; n < 2; ++n) acc[a][b][m][n] = (f32x4){0.f, 0.f, 0.f, 0.f};
;         cur = nxt; cA = nA; cB = nB; ++ui;
.LBB0_1182:
	v_readlane_b32 s20, v245, 30
	v_readlane_b32 s21, v245, 31
	s_add_u32 s20, s20, s15
	s_addc_u32 s21, s21, 0
	s_and_b64 s[24:25], s[38:39], exec
	v_readlane_b32 s24, v244, 22
	s_cselect_b32 s37, s21, s29
	s_cselect_b32 s40, s20, s28
	s_add_u32 s24, s24, s14
	v_readlane_b32 s25, v244, 23
	s_addc_u32 s25, s25, 0
	s_and_b64 s[34:35], s[38:39], exec
	s_cselect_b32 s41, s25, s31
	s_cselect_b32 s44, s24, s30
	s_add_u32 s28, s28, 0x200080
	s_addc_u32 s29, s29, 0
	s_add_u32 s45, s30, 0x100
	v_mov_b32_e32 v0, 0
	s_addc_u32 s46, s31, 0
	s_mov_b32 s47, -2
	v_mov_b32_e32 v1, v0
	v_mov_b32_e32 v2, v0
	v_mov_b32_e32 v3, v0
	v_mov_b32_e32 v4, v0
	v_mov_b32_e32 v5, v0
	v_mov_b32_e32 v6, v0
	v_mov_b32_e32 v7, v0
	v_mov_b32_e32 v12, v0
	v_mov_b32_e32 v13, v0
	v_mov_b32_e32 v14, v0
	v_mov_b32_e32 v15, v0
	v_mov_b32_e32 v16, v0
	v_mov_b32_e32 v17, v0
	v_mov_b32_e32 v18, v0
	v_mov_b32_e32 v19, v0
	v_mov_b32_e32 v32, v0
	v_mov_b32_e32 v33, v0
	v_mov_b32_e32 v34, v0
	v_mov_b32_e32 v35, v0
	v_mov_b32_e32 v36, v0
	v_mov_b32_e32 v37, v0
	v_mov_b32_e32 v38, v0
	v_mov_b32_e32 v39, v0
	v_mov_b32_e32 v40, v0
	v_mov_b32_e32 v41, v0
	v_mov_b32_e32 v42, v0
	v_mov_b32_e32 v43, v0
	v_mov_b32_e32 v44, v0
	v_mov_b32_e32 v45, v0
	v_mov_b32_e32 v46, v0
	v_mov_b32_e32 v47, v0
	v_mov_b32_e32 v8, v0
	v_mov_b32_e32 v9, v0
	v_mov_b32_e32 v10, v0
	v_mov_b32_e32 v11, v0
	v_mov_b32_e32 v20, v0
	v_mov_b32_e32 v21, v0
	v_mov_b32_e32 v22, v0
	v_mov_b32_e32 v23, v0
	v_mov_b32_e32 v24, v0
	v_mov_b32_e32 v25, v0
	v_mov_b32_e32 v26, v0
	v_mov_b32_e32 v27, v0
	v_mov_b32_e32 v28, v0
	v_mov_b32_e32 v29, v0
	v_mov_b32_e32 v30, v0
	v_mov_b32_e32 v31, v0
	v_mov_b32_e32 v48, v0
	v_mov_b32_e32 v49, v0
	v_mov_b32_e32 v50, v0
	v_mov_b32_e32 v51, v0
	v_mov_b32_e32 v52, v0
	v_mov_b32_e32 v53, v0
	v_mov_b32_e32 v54, v0
	v_mov_b32_e32 v55, v0
	v_mov_b32_e32 v56, v0
	v_mov_b32_e32 v57, v0
	v_mov_b32_e32 v58, v0
	v_mov_b32_e32 v59, v0
	v_mov_b32_e32 v60, v0
	v_mov_b32_e32 v61, v0
	v_mov_b32_e32 v62, v0
	v_mov_b32_e32 v63, v0
	v_mov_b32_e32 v76, v0
	v_mov_b32_e32 v77, v0
	v_mov_b32_e32 v78, v0
	v_mov_b32_e32 v79, v0
	v_mov_b32_e32 v80, v0
	v_mov_b32_e32 v81, v0
	v_mov_b32_e32 v82, v0
	v_mov_b32_e32 v83, v0
	v_mov_b32_e32 v84, v0
	v_mov_b32_e32 v85, v0
	v_mov_b32_e32 v86, v0
	v_mov_b32_e32 v87, v0
	v_mov_b32_e32 v88, v0
	v_mov_b32_e32 v89, v0
	v_mov_b32_e32 v90, v0
	v_mov_b32_e32 v91, v0
	v_mov_b32_e32 v112, v0
	v_mov_b32_e32 v113, v0
	v_mov_b32_e32 v114, v0
	v_mov_b32_e32 v115, v0
	v_mov_b32_e32 v116, v0
	v_mov_b32_e32 v117, v0
	v_mov_b32_e32 v118, v0
	v_mov_b32_e32 v119, v0
	v_mov_b32_e32 v120, v0
	v_mov_b32_e32 v121, v0
	v_mov_b32_e32 v122, v0
	v_mov_b32_e32 v123, v0
	v_mov_b32_e32 v124, v0
	v_mov_b32_e32 v125, v0
	v_mov_b32_e32 v126, v0
	v_mov_b32_e32 v127, v0
	v_mov_b32_e32 v92, v0
	v_mov_b32_e32 v93, v0
	v_mov_b32_e32 v94, v0
	v_mov_b32_e32 v95, v0
	v_mov_b32_e32 v96, v0
	v_mov_b32_e32 v97, v0
	v_mov_b32_e32 v98, v0
	v_mov_b32_e32 v99, v0
	v_mov_b32_e32 v100, v0
	v_mov_b32_e32 v101, v0
	v_mov_b32_e32 v102, v0
	v_mov_b32_e32 v103, v0
	v_mov_b32_e32 v104, v0
	v_mov_b32_e32 v105, v0
	v_mov_b32_e32 v106, v0
	v_mov_b32_e32 v107, v0
	v_mov_b32_e32 v128, v0
	v_mov_b32_e32 v129, v0
	v_mov_b32_e32 v130, v0
	v_mov_b32_e32 v131, v0
	v_mov_b32_e32 v132, v0
	v_mov_b32_e32 v133, v0
	v_mov_b32_e32 v134, v0
	v_mov_b32_e32 v135, v0
	v_mov_b32_e32 v136, v0
	v_mov_b32_e32 v137, v0
	v_mov_b32_e32 v138, v0
	v_mov_b32_e32 v139, v0
	v_mov_b32_e32 v140, v0
	v_mov_b32_e32 v141, v0
	v_mov_b32_e32 v142, v0
	v_mov_b32_e32 v143, v0
.LBB0_1183:
	s_add_u32 s30, s28, 0xffe00080
	s_addc_u32 s31, s29, -1
	s_add_i32 s48, 0, 0x10000
	s_cmpk_eq_i32 s47, 0x7c
	s_cselect_b32 s35, s37, s31
	s_cselect_b32 s34, s40, s30
	s_cselect_b32 s31, s41, s46
	s_cselect_b32 s30, s44, s45
	s_add_i32 s50, 0, 0x14000
	v_add_u32_e32 v108, s48, v173
	v_add_u32_e32 v170, s50, v173
	ds_read_b128 v[64:67], v108
	ds_read_b128 v[68:71], v108 offset:1024
	ds_read_b128 v[72:75], v108 offset:2048
	ds_read_b128 v[108:111], v108 offset:3072
	ds_read_b128 v[166:169], v170
	ds_read_b128 v[176:179], v170 offset:1024
	ds_read_b128 v[192:195], v170 offset:2048
	ds_read_b128 v[196:199], v170 offset:3072
	v_lshl_add_u64 v[170:171], s[28:29], 0, v[162:163]
	s_add_i32 m0, s3, 0xc000
	ds_read_b128 v[200:203], v174
	ds_read_b128 v[204:207], v174 offset:1024
	ds_read_b128 v[208:211], v174 offset:2048
	ds_read_b128 v[212:215], v174 offset:3072
	ds_read_b128 v[216:219], v174 offset:4096
	ds_read_b128 v[220:223], v174 offset:5120
	ds_read_b128 v[224:227], v174 offset:6144
	ds_read_b128 v[228:231], v174 offset:7168
	global_load_lds_dwordx4 v[170:171], off
	v_lshl_add_u64 v[170:171], s[28:29], 0, v[164:165]
	s_add_i32 m0, s3, 0xe000
	s_nop 0
	global_load_lds_dwordx4 v[170:171], off
	s_waitcnt vmcnt(8)
	s_waitcnt lgkmcnt(0)
	s_barrier
; #define PG8_STAGE(bufoff, gbase, voff) do { _Pragma("unroll") for (int _i = 0; _i < 2; ++_i) \
;         __builtin_amdgcn_global_load_lds((const unsigned*)((const char*)(gbase) + (voff)[_i]), (LAS unsigned*)(lds + (bufoff) + ldsw + _i * 8192), 16, 0, 0); } while (0)
; #define PG8_LDA(dst, b, h) do { _Pragma("unroll") for (int m = 0; m < 4; ++m) _Pragma("unroll") for (int k = 0; k < 2; ++k) dst[m][k] = *(const LAS bf16x8*)(lds + PG8_SA(b, h) + aoff + m * 2048 + k * 1024); } while (0)
; #define PG8_MMA(ai, bj, At, Bt) do { __builtin_amdgcn_s_setprio(1); _Pragma("unroll") for (int m = 0; m < 4; ++m) _Pragma("unroll") for (int n = 0; n < 2; ++n) _Pragma("unroll") for (int k = 0; k < 2; ++k) \
;         acc[ai][bj][m][n] = __builtin_amdgcn_mfma_f32_16x16x32_bf16(Bt[n][k], At[m][k], acc[ai][bj][m][n], 0, 0, 0); __builtin_amdgcn_s_setprio(0); } while (0)
; #define PG8_WAIT_V(n) asm volatile("s_waitcnt vmcnt(" #n ")" ::: "memory")
; #define PG8_WAIT_L(n) asm volatile("s_waitcnt lgkmcnt(" #n ")" ::: "memory")
; #define PG8_BAR __builtin_amdgcn_s_barrier()
; #define PG8_SCHED __builtin_amdgcn_sched_barrier(0)
; template <class Epi, class Map>
; __device__ __forceinline__ void gemm_phase(LAS unsigned char* lds, const Gemm g, const Sched<Map>& S, const Epi& E) {
;     ...
;             PG8_WAIT_V(8); PG8_WAIT_L(0); PG8_BAR; PG8_MMA(0, 0, At, B0); PG8_MMA(0, 1, At, B1); PG8_BAR; PG8_SCHED;
;             PG8_LDA(At, 0, 1); PG8_STAGE(PG8_SB(0, 0), b2, voffB); PG8_STAGE(PG8_SB(0, 1), b2 + hstepB, voffB); PG8_STAGE(PG8_SA(0, 0), a2, voffA);
;             PG8_WAIT_V(8); PG8_WAIT_L(0); PG8_BAR; PG8_MMA(1, 0, At, B0); PG8_MMA(1, 1, At, B1); PG8_BAR; PG8_SCHED;
	s_waitcnt lgkmcnt(0)
	v_mfma_f32_16x16x32_bf16 v[140:143], v[64:67], v[200:203], v[140:143]
	v_mfma_f32_16x16x32_bf16 v[136:139], v[72:75], v[200:203], v[136:139]
	v_mfma_f32_16x16x32_bf16 v[132:135], v[64:67], v[208:211], v[132:135]
	v_mfma_f32_16x16x32_bf16 v[128:131], v[72:75], v[208:211], v[128:131]
	v_mfma_f32_16x16x32_bf16 v[104:107], v[64:67], v[216:219], v[104:107]
	v_mfma_f32_16x16x32_bf16 v[100:103], v[72:75], v[216:219], v[100:103]
	v_mfma_f32_16x16x32_bf16 v[96:99], v[64:67], v[224:227], v[96:99]
	v_mfma_f32_16x16x32_bf16 v[92:95], v[72:75], v[224:227], v[92:95]
	v_mfma_f32_16x16x32_bf16 v[140:143], v[68:71], v[204:207], v[140:143]
	v_mfma_f32_16x16x32_bf16 v[136:139], v[108:111], v[204:207], v[136:139]
	v_mfma_f32_16x16x32_bf16 v[132:135], v[68:71], v[212:215], v[132:135]
	v_mfma_f32_16x16x32_bf16 v[128:131], v[108:111], v[212:215], v[128:131]
	v_mfma_f32_16x16x32_bf16 v[104:107], v[68:71], v[220:223], v[104:107]
	v_mfma_f32_16x16x32_bf16 v[100:103], v[108:111], v[220:223], v[100:103]
	v_mfma_f32_16x16x32_bf16 v[96:99], v[68:71], v[228:231], v[96:99]
	v_mfma_f32_16x16x32_bf16 v[92:95], v[108:111], v[228:231], v[92:95]
	v_mfma_f32_16x16x32_bf16 v[124:127], v[166:169], v[200:203], v[124:127]
	v_mfma_f32_16x16x32_bf16 v[120:123], v[192:195], v[200:203], v[120:123]
	v_mfma_f32_16x16x32_bf16 v[116:119], v[166:169], v[208:211], v[116:119]
	v_mfma_f32_16x16x32_bf16 v[112:115], v[192:195], v[208:211], v[112:115]
	v_mfma_f32_16x16x32_bf16 v[88:91], v[166:169], v[216:219], v[88:91]
	v_mfma_f32_16x16x32_bf16 v[84:87], v[192:195], v[216:219], v[84:87]
	v_mfma_f32_16x16x32_bf16 v[80:83], v[166:169], v[224:227], v[80:83]
	v_mfma_f32_16x16x32_bf16 v[76:79], v[192:195], v[224:227], v[76:79]
	v_mfma_f32_16x16x32_bf16 v[124:127], v[176:179], v[204:207], v[124:127]
	v_mfma_f32_16x16x32_bf16 v[120:123], v[196:199], v[204:207], v[120:123]
	v_mfma_f32_16x16x32_bf16 v[116:119], v[176:179], v[212:215], v[116:119]
	v_mfma_f32_16x16x32_bf16 v[112:115], v[196:199], v[212:215], v[112:115]
	v_mfma_f32_16x16x32_bf16 v[88:91], v[176:179], v[220:223], v[88:91]
	v_mfma_f32_16x16x32_bf16 v[84:87], v[196:199], v[220:223], v[84:87]
	v_mfma_f32_16x16x32_bf16 v[80:83], v[176:179], v[228:231], v[80:83]
	v_mfma_f32_16x16x32_bf16 v[76:79], v[196:199], v[228:231], v[76:79]
	s_barrier
	s_add_i32 s48, s48, s2
	v_lshl_add_u64 v[170:171], s[30:31], 0, v[144:145]
	s_mov_b32 m0, s48
	ds_read_b128 v[200:203], v174 offset:16384
	ds_read_b128 v[204:207], v174 offset:17408
	ds_read_b128 v[208:211], v174 offset:18432
	ds_read_b128 v[212:215], v174 offset:19456
	ds_read_b128 v[216:219], v174 offset:20480
	ds_read_b128 v[220:223], v174 offset:21504
	ds_read_b128 v[224:227], v174 offset:22528
	ds_read_b128 v[228:231], v174 offset:23552
	global_load_lds_dwordx4 v[170:171], off
	s_add_i32 m0, s48, 0x2000
	s_add_u32 s48, s30, 0x200000
	v_lshl_add_u64 v[180:181], s[30:31], 0, v[160:161]
	s_addc_u32 s49, s31, 0
	s_add_i32 s50, s50, s2
	global_load_lds_dwordx4 v[180:181], off
	v_lshl_add_u64 v[232:233], s[48:49], 0, v[144:145]
	s_mov_b32 m0, s50
	v_lshl_add_u64 v[234:235], s[34:35], 0, v[160:161]
	global_load_lds_dwordx4 v[232:233], off
	v_lshl_add_u64 v[232:233], s[48:49], 0, v[160:161]
	s_add_i32 m0, s50, 0x2000
	s_nop 0
	global_load_lds_dwordx4 v[232:233], off
	v_lshl_add_u64 v[232:233], s[34:35], 0, v[144:145]
	s_mov_b32 m0, s3
	s_nop 0
	global_load_lds_dwordx4 v[232:233], off
	s_mov_b32 m0, s4
	s_nop 0
	global_load_lds_dwordx4 v[234:235], off
	s_waitcnt vmcnt(8)
	s_waitcnt lgkmcnt(0)
	s_barrier
	s_waitcnt lgkmcnt(0)
	v_mfma_f32_16x16x32_bf16 v[60:63], v[64:67], v[200:203], v[60:63]
	v_mfma_f32_16x16x32_bf16 v[56:59], v[72:75], v[200:203], v[56:59]
	v_mfma_f32_16x16x32_bf16 v[52:55], v[64:67], v[208:211], v[52:55]
	v_mfma_f32_16x16x32_bf16 v[48:51], v[72:75], v[208:211], v[48:51]
	v_mfma_f32_16x16x32_bf16 v[28:31], v[64:67], v[216:219], v[28:31]
	v_mfma_f32_16x16x32_bf16 v[24:27], v[72:75], v[216:219], v[24:27]
	v_mfma_f32_16x16x32_bf16 v[20:23], v[64:67], v[224:227], v[20:23]
	v_mfma_f32_16x16x32_bf16 v[8:11], v[72:75], v[224:227], v[8:11]
	v_mfma_f32_16x16x32_bf16 v[60:63], v[68:71], v[204:207], v[60:63]
	v_mfma_f32_16x16x32_bf16 v[56:59], v[108:111], v[204:207], v[56:59]
	v_mfma_f32_16x16x32_bf16 v[52:55], v[68:71], v[212:215], v[52:55]
	v_mfma_f32_16x16x32_bf16 v[48:51], v[108:111], v[212:215], v[48:51]
	v_mfma_f32_16x16x32_bf16 v[28:31], v[68:71], v[220:223], v[28:31]
	v_mfma_f32_16x16x32_bf16 v[24:27], v[108:111], v[220:223], v[24:27]
	v_mfma_f32_16x16x32_bf16 v[20:23], v[68:71], v[228:231], v[20:23]
	v_mfma_f32_16x16x32_bf16 v[8:11], v[108:111], v[228:231], v[8:11]
	v_mfma_f32_16x16x32_bf16 v[44:47], v[166:169], v[200:203], v[44:47]
	v_mfma_f32_16x16x32_bf16 v[40:43], v[192:195], v[200:203], v[40:43]
	v_mfma_f32_16x16x32_bf16 v[36:39], v[166:169], v[208:211], v[36:39]
	v_mfma_f32_16x16x32_bf16 v[32:35], v[192:195], v[208:211], v[32:35]
	v_mfma_f32_16x16x32_bf16 v[16:19], v[166:169], v[216:219], v[16:19]
	v_mfma_f32_16x16x32_bf16 v[12:15], v[192:195], v[216:219], v[12:15]
	v_mfma_f32_16x16x32_bf16 v[4:7], v[166:169], v[224:227], v[4:7]
	v_mfma_f32_16x16x32_bf16 v[0:3], v[192:195], v[224:227], v[0:3]
	v_mfma_f32_16x16x32_bf16 v[44:47], v[176:179], v[204:207], v[44:47]
	v_mfma_f32_16x16x32_bf16 v[40:43], v[196:199], v[204:207], v[40:43]
	v_mfma_f32_16x16x32_bf16 v[36:39], v[176:179], v[212:215], v[36:39]
	v_mfma_f32_16x16x32_bf16 v[32:35], v[196:199], v[212:215], v[32:35]
	v_mfma_f32_16x16x32_bf16 v[16:19], v[176:179], v[220:223], v[16:19]
	v_mfma_f32_16x16x32_bf16 v[12:15], v[196:199], v[220:223], v[12:15]
	v_mfma_f32_16x16x32_bf16 v[4:7], v[176:179], v[228:231], v[4:7]
	v_mfma_f32_16x16x32_bf16 v[0:3], v[196:199], v[228:231], v[0:3]
	s_barrier
; #define PG8_STAGE(bufoff, gbase, voff) do { _Pragma("unroll") for (int _i = 0; _i < 2; ++_i) \
;         __builtin_amdgcn_global_load_lds((const unsigned*)((const char*)(gbase) + (voff)[_i]), (LAS unsigned*)(lds + (bufoff) + ldsw + _i * 8192), 16, 0, 0); } while (0)
; #define PG8_LDA(dst, b, h) do { _Pragma("unroll") for (int m = 0; m < 4; ++m) _Pragma("unroll") for (int k = 0; k < 2; ++k) dst[m][k] = *(const LAS bf16x8*)(lds + PG8_SA(b, h) + aoff + m * 2048 + k * 1024); } while (0)
; #define PG8_LDB(dst, b, h) do { _Pragma("unroll") for (int n = 0; n < 2; ++n) _Pragma("unroll") for (int k = 0; k < 2; ++k) dst[n][k] = *(const LAS bf16x8*)(lds + PG8_SB(b, h) + boff + n * 2048 + k * 1024); } while (0)
; #define PG8_MMA(ai, bj, At, Bt) do { __builtin_amdgcn_s_setprio(1); _Pragma("unroll") for (int m = 0; m < 4; ++m) _Pragma("unroll") for (int n = 0; n < 2; ++n) _Pragma("unroll") for (int k = 0; k < 2; ++k) \
;         acc[ai][bj][m][n] = __builtin_amdgcn_mfma_f32_16x16x32_bf16(Bt[n][k], At[m][k], acc[ai][bj][m][n], 0, 0, 0); __builtin_amdgcn_s_setprio(0); } while (0)
; #define PG8_WAIT_V(n) asm volatile("s_waitcnt vmcnt(" #n ")" ::: "memory")
; #define PG8_WAIT_L(n) asm volatile("s_waitcnt lgkmcnt(" #n ")" ::: "memory")
; #define PG8_BAR __builtin_amdgcn_s_barrier()
; #define PG8_SCHED __builtin_amdgcn_sched_barrier(0)
; template <class Epi, class Map>
; __device__ __forceinline__ void gemm_phase(LAS unsigned char* lds, const Gemm g, const Sched<Map>& S, const Epi& E) {
;     ...
;             PG8_LDB(B0, 1, 0); PG8_LDB(B1, 1, 1); PG8_SCHED; PG8_LDA(At, 1, 0); PG8_STAGE(PG8_SA(0, 1), a2 + hstepA, voffA);
;             PG8_WAIT_V(8); PG8_WAIT_L(0); PG8_BAR; PG8_MMA(0, 0, At, B0); PG8_MMA(0, 1, At, B1); PG8_BAR; PG8_SCHED;
;             PG8_LDA(At, 1, 1); PG8_STAGE(PG8_SB(1, 0), b3, voffB); PG8_STAGE(PG8_SB(1, 1), b3 + hstepB, voffB); PG8_STAGE(PG8_SA(1, 0), a3, voffA);
;             PG8_WAIT_V(8); PG8_WAIT_L(0); PG8_BAR; PG8_MMA(1, 0, At, B0); PG8_MMA(1, 1, At, B1); PG8_BAR; PG8_SCHED;
	s_add_i32 s48, 0, 0x18000
	s_add_i32 s49, 0, 0x1c000
	v_add_u32_e32 v108, s48, v173
	v_add_u32_e32 v175, s49, v173
	ds_read_b128 v[64:67], v108
	ds_read_b128 v[68:71], v108 offset:1024
	ds_read_b128 v[72:75], v108 offset:2048
	ds_read_b128 v[108:111], v108 offset:3072
	ds_read_b128 v[166:169], v175
	ds_read_b128 v[176:179], v175 offset:1024
	ds_read_b128 v[192:195], v175 offset:2048
	ds_read_b128 v[196:199], v175 offset:3072
	s_add_u32 s34, s34, 0x200000
	s_addc_u32 s35, s35, 0
	s_mov_b32 m0, s5
	v_lshl_add_u64 v[236:237], s[34:35], 0, v[144:145]
	ds_read_b128 v[200:203], v174 offset:32768
	ds_read_b128 v[204:207], v174 offset:33792
	ds_read_b128 v[208:211], v174 offset:34816
	ds_read_b128 v[212:215], v174 offset:35840
	ds_read_b128 v[216:219], v174 offset:36864
	ds_read_b128 v[220:223], v174 offset:37888
	ds_read_b128 v[224:227], v174 offset:38912
	ds_read_b128 v[228:231], v174 offset:39936
	global_load_lds_dwordx4 v[236:237], off
	v_lshl_add_u64 v[236:237], s[34:35], 0, v[160:161]
	s_mov_b32 m0, s6
	s_nop 0
	global_load_lds_dwordx4 v[236:237], off
	s_waitcnt vmcnt(8)
	s_waitcnt lgkmcnt(0)
	s_barrier
	s_waitcnt lgkmcnt(0)
	v_mfma_f32_16x16x32_bf16 v[140:143], v[64:67], v[200:203], v[140:143]
	v_mfma_f32_16x16x32_bf16 v[136:139], v[72:75], v[200:203], v[136:139]
	v_mfma_f32_16x16x32_bf16 v[132:135], v[64:67], v[208:211], v[132:135]
	v_mfma_f32_16x16x32_bf16 v[128:131], v[72:75], v[208:211], v[128:131]
	v_mfma_f32_16x16x32_bf16 v[104:107], v[64:67], v[216:219], v[104:107]
	v_mfma_f32_16x16x32_bf16 v[100:103], v[72:75], v[216:219], v[100:103]
	v_mfma_f32_16x16x32_bf16 v[96:99], v[64:67], v[224:227], v[96:99]
	v_mfma_f32_16x16x32_bf16 v[92:95], v[72:75], v[224:227], v[92:95]
	v_mfma_f32_16x16x32_bf16 v[140:143], v[68:71], v[204:207], v[140:143]
	v_mfma_f32_16x16x32_bf16 v[136:139], v[108:111], v[204:207], v[136:139]
	v_mfma_f32_16x16x32_bf16 v[132:135], v[68:71], v[212:215], v[132:135]
	v_mfma_f32_16x16x32_bf16 v[128:131], v[108:111], v[212:215], v[128:131]
	v_mfma_f32_16x16x32_bf16 v[104:107], v[68:71], v[220:223], v[104:107]
	v_mfma_f32_16x16x32_bf16 v[100:103], v[108:111], v[220:223], v[100:103]
	v_mfma_f32_16x16x32_bf16 v[96:99], v[68:71], v[228:231], v[96:99]
	v_mfma_f32_16x16x32_bf16 v[92:95], v[108:111], v[228:231], v[92:95]
	v_mfma_f32_16x16x32_bf16 v[124:127], v[166:169], v[200:203], v[124:127]
	v_mfma_f32_16x16x32_bf16 v[120:123], v[192:195], v[200:203], v[120:123]
	v_mfma_f32_16x16x32_bf16 v[116:119], v[166:169], v[208:211], v[116:119]
	v_mfma_f32_16x16x32_bf16 v[112:115], v[192:195], v[208:211], v[112:115]
	v_mfma_f32_16x16x32_bf16 v[88:91], v[166:169], v[216:219], v[88:91]
	v_mfma_f32_16x16x32_bf16 v[84:87], v[192:195], v[216:219], v[84:87]
	v_mfma_f32_16x16x32_bf16 v[80:83], v[166:169], v[224:227], v[80:83]
	v_mfma_f32_16x16x32_bf16 v[76:79], v[192:195], v[224:227], v[76:79]
	v_mfma_f32_16x16x32_bf16 v[124:127], v[176:179], v[204:207], v[124:127]
	v_mfma_f32_16x16x32_bf16 v[120:123], v[196:199], v[204:207], v[120:123]
	v_mfma_f32_16x16x32_bf16 v[116:119], v[176:179], v[212:215], v[116:119]
	v_mfma_f32_16x16x32_bf16 v[112:115], v[196:199], v[212:215], v[112:115]
	v_mfma_f32_16x16x32_bf16 v[88:91], v[176:179], v[220:223], v[88:91]
	v_mfma_f32_16x16x32_bf16 v[84:87], v[196:199], v[220:223], v[84:87]
	v_mfma_f32_16x16x32_bf16 v[80:83], v[176:179], v[228:231], v[80:83]
	v_mfma_f32_16x16x32_bf16 v[76:79], v[196:199], v[228:231], v[76:79]
	s_barrier
	s_add_i32 s34, s48, s2
	v_lshl_add_u64 v[170:171], v[170:171], 0, s[82:83]
	s_mov_b32 m0, s34
	ds_read_b128 v[200:203], v174 offset:49152
	ds_read_b128 v[204:207], v174 offset:50176
	ds_read_b128 v[208:211], v174 offset:51200
	ds_read_b128 v[212:215], v174 offset:52224
	ds_read_b128 v[216:219], v174 offset:53248
	ds_read_b128 v[220:223], v174 offset:54272
	ds_read_b128 v[224:227], v174 offset:55296
	ds_read_b128 v[228:231], v174 offset:56320
	global_load_lds_dwordx4 v[170:171], off
	s_add_i32 m0, s34, 0x2000
	s_add_u32 s30, s30, 0x200080
	v_lshl_add_u64 v[170:171], v[180:181], 0, s[82:83]
	s_addc_u32 s31, s31, 0
	s_add_i32 s34, s49, s2
	global_load_lds_dwordx4 v[170:171], off
	v_lshl_add_u64 v[170:171], s[30:31], 0, v[144:145]
	s_mov_b32 m0, s34
	s_nop 0
	global_load_lds_dwordx4 v[170:171], off
	v_lshl_add_u64 v[170:171], s[30:31], 0, v[160:161]
	s_add_i32 m0, s34, 0x2000
	s_nop 0
	global_load_lds_dwordx4 v[170:171], off
	v_lshl_add_u64 v[170:171], v[232:233], 0, s[82:83]
	s_mov_b32 m0, s9
	s_nop 0
	global_load_lds_dwordx4 v[170:171], off
	v_lshl_add_u64 v[170:171], v[234:235], 0, s[82:83]
	s_mov_b32 m0, s10
	s_nop 0
	global_load_lds_dwordx4 v[170:171], off
	s_waitcnt vmcnt(8)
	s_waitcnt lgkmcnt(0)
	s_barrier
; #define PG8_MMA(ai, bj, At, Bt) do { __builtin_amdgcn_s_setprio(1); _Pragma("unroll") for (int m = 0; m < 4; ++m) _Pragma("unroll") for (int n = 0; n < 2; ++n) _Pragma("unroll") for (int k = 0; k < 2; ++k) \
;         acc[ai][bj][m][n] = __builtin_amdgcn_mfma_f32_16x16x32_bf16(Bt[n][k], At[m][k], acc[ai][bj][m][n], 0, 0, 0); __builtin_amdgcn_s_setprio(0); } while (0)
; #define PG8_WAIT_V(n) asm volatile("s_waitcnt vmcnt(" #n ")" ::: "memory")
; #define PG8_WAIT_L(n) asm volatile("s_waitcnt lgkmcnt(" #n ")" ::: "memory")
; #define PG8_BAR __builtin_amdgcn_s_barrier()
; #define PG8_SCHED __builtin_amdgcn_sched_barrier(0)
; template <class Epi, class Map>
; __device__ __forceinline__ void gemm_phase(LAS unsigned char* lds, const Gemm g, const Sched<Map>& S, const Epi& E) {
;     ...
;             PG8_WAIT_V(8); PG8_WAIT_L(0); PG8_BAR; PG8_MMA(1, 0, At, B0); PG8_MMA(1, 1, At, B1); PG8_BAR; PG8_SCHED;
;         }
;         if (wr == 0) PG8_BAR;
;     __device__ __forceinline__ void operator()(const Acc& acc, const Unit& u, int wr, int wc, int fr, int fq) const {
;         asm volatile("" : "+v"(fr), "+v"(fq));
;         const int row0 = u.pm * BM + wr * 64 + fr, col0 = u.pn * BM + wc * 32 + 4 * fq;
;         const float* gp = gate + (size_t)(u.pm >> 6) * gate_bstride + col0;
;         f32x4 gv[2][2];
; #pragma unroll
;         for (int bj = 0; bj < 2; ++bj)
; #pragma unroll
;             for (int n = 0; n < 2; ++n) gv[bj][n] = *(const f32x4*)(gp + bj * HALF + n * 16);
; #pragma unroll
;         for (int aim = 0; aim < 4; ++aim) { const int ai = aim >> 1, m0 = (aim & 1) * 2;
;             f32x4 bs[2][2][2];
; #pragma unroll
;             for (int mm = 0; mm < 2; ++mm) { const size_t off = (size_t)(row0 + ai * HALF + (m0 + mm) * 16) * D + col0;
; #pragma unroll
;                 for (int bj = 0; bj < 2; ++bj)
; #pragma unroll
;                     for (int n = 0; n < 2; ++n) bs[mm][bj][n] = *(const f32x4*)(base + off + bj * HALF + n * 16); }
; #pragma unroll
;             for (int mm = 0; mm < 2; ++mm) { const size_t off = (size_t)(row0 + ai * HALF + (m0 + mm) * 16) * D + col0;
; #pragma unroll
;                 for (int bj = 0; bj < 2; ++bj)
; #pragma unroll
;                     for (int n = 0; n < 2; ++n) *(f32x4*)(out + off + bj * HALF + n * 16) = bs[mm][bj][n] + gv[bj][n] * acc[ai][bj][m0 + mm][n]; }
	s_waitcnt lgkmcnt(0)
	v_mfma_f32_16x16x32_bf16 v[60:63], v[64:67], v[200:203], v[60:63]
	v_mfma_f32_16x16x32_bf16 v[56:59], v[72:75], v[200:203], v[56:59]
	v_mfma_f32_16x16x32_bf16 v[52:55], v[64:67], v[208:211], v[52:55]
	v_mfma_f32_16x16x32_bf16 v[48:51], v[72:75], v[208:211], v[48:51]
	v_mfma_f32_16x16x32_bf16 v[28:31], v[64:67], v[216:219], v[28:31]
	v_mfma_f32_16x16x32_bf16 v[24:27], v[72:75], v[216:219], v[24:27]
	v_mfma_f32_16x16x32_bf16 v[20:23], v[64:67], v[224:227], v[20:23]
	v_mfma_f32_16x16x32_bf16 v[8:11], v[72:75], v[224:227], v[8:11]
	v_mfma_f32_16x16x32_bf16 v[60:63], v[68:71], v[204:207], v[60:63]
	v_mfma_f32_16x16x32_bf16 v[56:59], v[108:111], v[204:207], v[56:59]
	v_mfma_f32_16x16x32_bf16 v[52:55], v[68:71], v[212:215], v[52:55]
	v_mfma_f32_16x16x32_bf16 v[48:51], v[108:111], v[212:215], v[48:51]
	v_mfma_f32_16x16x32_bf16 v[28:31], v[68:71], v[220:223], v[28:31]
	v_mfma_f32_16x16x32_bf16 v[24:27], v[108:111], v[220:223], v[24:27]
	v_mfma_f32_16x16x32_bf16 v[20:23], v[68:71], v[228:231], v[20:23]
	v_mfma_f32_16x16x32_bf16 v[8:11], v[108:111], v[228:231], v[8:11]
	v_mfma_f32_16x16x32_bf16 v[44:47], v[166:169], v[200:203], v[44:47]
	v_mfma_f32_16x16x32_bf16 v[40:43], v[192:195], v[200:203], v[40:43]
	v_mfma_f32_16x16x32_bf16 v[36:39], v[166:169], v[208:211], v[36:39]
	v_mfma_f32_16x16x32_bf16 v[32:35], v[192:195], v[208:211], v[32:35]
	v_mfma_f32_16x16x32_bf16 v[16:19], v[166:169], v[216:219], v[16:19]
	v_mfma_f32_16x16x32_bf16 v[12:15], v[192:195], v[216:219], v[12:15]
	v_mfma_f32_16x16x32_bf16 v[4:7], v[166:169], v[224:227], v[4:7]
	v_mfma_f32_16x16x32_bf16 v[0:3], v[192:195], v[224:227], v[0:3]
	v_mfma_f32_16x16x32_bf16 v[44:47], v[176:179], v[204:207], v[44:47]
	v_mfma_f32_16x16x32_bf16 v[40:43], v[196:199], v[204:207], v[40:43]
	v_mfma_f32_16x16x32_bf16 v[36:39], v[176:179], v[212:215], v[36:39]
	v_mfma_f32_16x16x32_bf16 v[32:35], v[196:199], v[212:215], v[32:35]
	v_mfma_f32_16x16x32_bf16 v[16:19], v[176:179], v[220:223], v[16:19]
	v_mfma_f32_16x16x32_bf16 v[12:15], v[196:199], v[220:223], v[12:15]
	v_mfma_f32_16x16x32_bf16 v[4:7], v[176:179], v[228:231], v[4:7]
	v_mfma_f32_16x16x32_bf16 v[0:3], v[196:199], v[228:231], v[0:3]
	s_barrier
	s_add_i32 s47, s47, 2
	s_add_u32 s28, s28, 0x100
	s_addc_u32 s29, s29, 0
	s_add_u32 s45, s45, 0x100
	s_addc_u32 s46, s46, 0
	s_cmpk_gt_u32 s47, 0x7d
	s_cbranch_scc0 .LBB0_1183
	s_and_b64 vcc, exec, s[18:19]
	s_cbranch_vccz .LBB0_1186
.LBB0_1186:
	v_mov_b32_e32 v168, v159
	v_mov_b32_e32 v64, v172
	s_lshl_b32 s28, s36, 8
	s_or_b32 s28, s28, s8
	v_lshl_add_u32 v64, v64, 2, s28
	s_ashr_i32 s28, s33, 6
	s_mul_hi_i32 s29, s28, 0xc000
	s_mul_i32 s28, s28, 0xc000
	s_add_u32 s28, s0, s28
	v_ashrrev_i32_e32 v65, 31, v64
	s_addc_u32 s29, s1, s29
	v_lshlrev_b64 v[166:167], 2, v[64:65]
	v_lshl_add_u64 v[64:65], s[28:29], 0, v[166:167]
	s_lshl_b32 s28, s33, 8
	s_add_i32 s28, s28, s7
	v_add_u32_e32 v170, s28, v168
	v_readlane_b32 s28, v245, 51
	v_readlane_b32 s29, v245, 52
	v_ashrrev_i32_e32 v171, 31, v170
	v_lshlrev_b64 v[170:171], 13, v[170:171]
	v_lshl_add_u64 v[168:169], s[28:29], 0, v[166:167]
	v_lshl_add_u64 v[180:181], v[168:169], 0, v[170:171]
	s_mov_b64 s[30:31], 0x20000
	global_load_dwordx4 v[108:111], v[64:65], off
	global_load_dwordx4 v[72:75], v[64:65], off offset:64
	global_load_dwordx4 v[68:71], v[64:65], off offset:512
	s_nop 0
	global_load_dwordx4 v[64:67], v[64:65], off offset:576
	s_nop 0
	global_load_dwordx4 v[176:179], v[180:181], off
	global_load_dwordx4 v[192:195], v[180:181], off offset:64
	global_load_dwordx4 v[196:199], v[180:181], off offset:512
	global_load_dwordx4 v[200:203], v[180:181], off offset:576
	v_lshl_add_u64 v[180:181], v[170:171], 0, s[30:31]
	v_lshl_add_u64 v[216:217], v[168:169], 0, v[180:181]
	global_load_dwordx4 v[204:207], v[216:217], off
	global_load_dwordx4 v[208:211], v[216:217], off offset:64
	global_load_dwordx4 v[212:215], v[216:217], off offset:512
	s_nop 0
	global_load_dwordx4 v[216:219], v[216:217], off offset:576
	s_mov_b64 s[30:31], 0x40000
	s_andn2_b64 vcc, exec, s[38:39]
	s_waitcnt vmcnt(0)
	v_pk_fma_f32 v[140:141], v[140:141], v[108:109], v[176:177]
	v_lshl_add_u64 v[176:177], s[28:29], 0, v[170:171]
	v_lshl_add_u64 v[176:177], v[176:177], 0, v[166:167]
	v_pk_fma_f32 v[126:127], v[126:127], v[70:71], v[198:199]
	v_pk_fma_f32 v[124:125], v[124:125], v[68:69], v[196:197]
	global_store_dwordx4 v[176:177], v[124:127], off offset:512
	v_pk_fma_f32 v[122:123], v[122:123], v[66:67], v[202:203]
	v_pk_fma_f32 v[120:121], v[120:121], v[64:65], v[200:201]
	v_lshl_add_u64 v[124:125], s[28:29], 0, v[180:181]
	global_store_dwordx4 v[176:177], v[120:123], off offset:576
	v_lshl_add_u64 v[124:125], v[124:125], 0, v[166:167]
	v_pk_fma_f32 v[142:143], v[142:143], v[110:111], v[178:179]
	v_pk_fma_f32 v[122:123], v[134:135], v[110:111], v[206:207]
	v_pk_fma_f32 v[120:121], v[132:133], v[108:109], v[204:205]
	v_pk_fma_f32 v[138:139], v[138:139], v[74:75], v[194:195]
	v_pk_fma_f32 v[136:137], v[136:137], v[72:73], v[192:193]
	global_store_dwordx4 v[124:125], v[120:123], off
	v_pk_fma_f32 v[118:119], v[118:119], v[70:71], v[214:215]
	v_pk_fma_f32 v[116:117], v[116:117], v[68:69], v[212:213]
	v_pk_fma_f32 v[122:123], v[130:131], v[74:75], v[210:211]
	v_pk_fma_f32 v[120:121], v[128:129], v[72:73], v[208:209]
	v_pk_fma_f32 v[114:115], v[114:115], v[66:67], v[218:219]
	v_pk_fma_f32 v[112:113], v[112:113], v[64:65], v[216:217]
	global_store_dwordx4 v[176:177], v[140:143], off
	s_cmp_lg_u64 s[18:19], 0
	s_cbranch_scc0 .Llate_align_12
	s_barrier
